# row phases: 4 rotating register sets per wave instead of 3 (deeper row pipelining), on LRU hoist
# baseline (speedup 1.0000x reference)
; __device__ __forceinline__ void row_phase(const Params& P, int glayer, int layer, int xsrc, bool hasY, int gate_idx, const float* gpost,
;                           int xdst, bool doH, const float* gpre, int sh_idx, int nrows) {
;     ...
;     for (int u = 0; u < 4; ++u) {
;       const int R = rb + u * stride;
;       if (R < nrows) {
;         if (xsrc != 0 && R < N_X) {
;           const u16* xs_ = ((xsrc == 1) ? resA : P.zf) + (long)R * 1024;
; #pragma unroll
;           for (int i = 0; i < 4; ++i) {
;             const uint2 t2 = *reinterpret_cast<const uint2*>(xs_ + (i * 64 + lane) * 4);
;             xr[u][i].x = t2.x; xr[u][i].y = t2.y;
;           }
;         } else {
;           const float* xin_;
;           if (xsrc == 0) xin_ = R < N_X ? P.x + (long)R * 1024 : P.ctx + (long)(R - N_X) * 1024;
;           else           xin_ = P.xc + (long)(R - N_X) * 1024;
; #pragma unroll
;           for (int i = 0; i < 4; ++i) xr[u][i] = *reinterpret_cast<const uint4*>(xin_ + (i * 64 + lane) * 4);
;     ...
;         if (doH) {
;           float ss = 0.f;
; #pragma unroll
;           for (int i = 0; i < 4; ++i) ss += xv[i].x * xv[i].x + xv[i].y * xv[i].y + xv[i].z * xv[i].z + xv[i].w * xv[i].w;
;           ss = wave_sum(ss);
;           const float rstd = __builtin_amdgcn_rsqf(ss * (1.f / 1024.f) + EPSF);
;           u16* h = P.hy + (long)row * 1024;
; #pragma unroll
;           for (int i = 0; i < 4; ++i) {
;             const int col = (i * 64 + lane) * 4;
;             const float4 g = *reinterpret_cast<const float4*>(gpre + col);
;             const float4 sh = *reinterpret_cast<const float4*>(modp + sh_idx * 1024 + col);
;             const float4 sc = *reinterpret_cast<const float4*>(modp + (sh_idx + 1) * 1024 + col);
;             const unsigned h0 = f2bf(xv[i].x * rstd * g.x * (1.f + sc.x) + sh.x);
;             const unsigned h1 = f2bf(xv[i].y * rstd * g.y * (1.f + sc.y) + sh.y);
;             const unsigned h2 = f2bf(xv[i].z * rstd * g.z * (1.f + sc.z) + sh.z);
;             const unsigned h3 = f2bf(xv[i].w * rstd * g.w * (1.f + sc.w) + sh.w);
;             *reinterpret_cast<uint2*>(h + col) = make_uint2(h0 | (h1 << 16), h2 | (h3 << 16));
;           }
.LBB0_93:
	s_cmp_gt_i32 s6, 1
	s_cselect_b64 s[0:1], -1, 0
	s_cmp_lt_i32 s7, 2
	s_cselect_b64 s[4:5], -1, 0
	s_or_b64 s[0:1], s[0:1], s[4:5]
	v_readlane_b32 s66, v252, 18
	s_and_b64 vcc, exec, s[0:1]
	v_lshrrev_b32_e32 v204, 6, v152
	v_readlane_b32 s67, v252, 19
	s_mov_b64 s[34:35], s[6:7]
	s_cbranch_vccnz .LBB0_163
	v_lshl_add_u32 v64, s2, 3, v204
	s_mov_b32 s3, 0x8400
	v_mov_b32_e32 v0, v153
	v_cmp_gt_i32_e32 vcc, s3, v64
	s_and_saveexec_b64 s[8:9], vcc
	s_cbranch_execz .LBB0_109
	v_readlane_b32 s4, v252, 0
	v_readlane_b32 s5, v252, 1
	v_readfirstlane_b32 s19, v204
	s_nop 3
	s_sub_u32 s4, s4, 0x170
	s_subb_u32 s5, s5, 0
	s_load_dwordx2 s[12:13], s[4:5], 0x0
	s_load_dwordx2 s[14:15], s[4:5], 0x140
	s_load_dwordx2 s[20:21], s[4:5], 0x100
	s_lshl_b32 s98, s2, 3
	s_add_u32 s19, s98, s19
	v_and_b32_e32 v136, 63, v152
	v_lshlrev_b32_e32 v137, 3, v136
	v_lshlrev_b32_e32 v136, 4, v136
	s_waitcnt lgkmcnt(0)
	s_lshl_b32 vcc_lo, s19, 12
	s_add_u32 s100, s12, vcc_lo
	s_addc_u32 s101, s13, 0
	global_load_dwordx4 v[0:3], v136, s[100:101] offset:0
	global_load_dwordx4 v[4:7], v136, s[100:101] offset:1024
	global_load_dwordx4 v[8:11], v136, s[100:101] offset:2048
	global_load_dwordx4 v[12:15], v136, s[100:101] offset:3072
	s_lshl_b32 vcc_lo, s19, 12
	s_add_u32 vcc_lo, vcc_lo, 0x800000
	s_add_u32 s100, s12, vcc_lo
	s_addc_u32 s101, s13, 0
	global_load_dwordx4 v[16:19], v136, s[100:101] offset:0
	global_load_dwordx4 v[20:23], v136, s[100:101] offset:1024
	global_load_dwordx4 v[24:27], v136, s[100:101] offset:2048
	global_load_dwordx4 v[28:31], v136, s[100:101] offset:3072
	s_lshl_b32 vcc_lo, s19, 12
	s_add_u32 vcc_lo, vcc_lo, 0x1000000
	s_add_u32 s100, s12, vcc_lo
	s_addc_u32 s101, s13, 0
	global_load_dwordx4 v[32:35], v136, s[100:101] offset:0
	global_load_dwordx4 v[36:39], v136, s[100:101] offset:1024
	global_load_dwordx4 v[40:43], v136, s[100:101] offset:2048
	global_load_dwordx4 v[44:47], v136, s[100:101] offset:3072
	s_add_u32 s100, s20, 0x0
	s_addc_u32 s101, s21, 0
	global_load_dwordx4 v[104:107], v136, s[100:101] offset:0
	global_load_dwordx4 v[108:111], v136, s[100:101] offset:1024
	global_load_dwordx4 v[112:115], v136, s[100:101] offset:2048
	global_load_dwordx4 v[116:119], v136, s[100:101] offset:3072
	s_add_u32 s100, s100, 0x1000
	s_addc_u32 s101, s101, 0
	global_load_dwordx4 v[166:169], v136, s[100:101] offset:0
	global_load_dwordx4 v[170:173], v136, s[100:101] offset:1024
	global_load_dwordx4 v[174:177], v136, s[100:101] offset:2048
	global_load_dwordx4 v[178:181], v136, s[100:101] offset:3072
	s_load_dwordx2 s[98:99], s[4:5], 0x30
	s_waitcnt lgkmcnt(0)
	global_load_dwordx4 v[88:91], v136, s[98:99] offset:0
	global_load_dwordx4 v[92:95], v136, s[98:99] offset:1024
	global_load_dwordx4 v[96:99], v136, s[98:99] offset:2048
	global_load_dwordx4 v[100:103], v136, s[98:99] offset:3072
	s_waitcnt vmcnt(0)
	v_fma_f32 v88, v88, v166, v88
	v_fma_f32 v89, v89, v167, v89
	v_fma_f32 v90, v90, v168, v90
	v_fma_f32 v91, v91, v169, v91
	v_fma_f32 v92, v92, v170, v92
	v_fma_f32 v93, v93, v171, v93
	v_fma_f32 v94, v94, v172, v94
	v_fma_f32 v95, v95, v173, v95
	v_fma_f32 v96, v96, v174, v96
	v_fma_f32 v97, v97, v175, v97
	v_fma_f32 v98, v98, v176, v98
	v_fma_f32 v99, v99, v177, v99
	v_fma_f32 v100, v100, v178, v100
	v_fma_f32 v101, v101, v179, v101
	v_fma_f32 v102, v102, v180, v102
	v_fma_f32 v103, v103, v181, v103
	s_lshl_b32 vcc_lo, s19, 12
	s_add_u32 vcc_lo, vcc_lo, 0x1800000
	s_add_u32 s100, s12, vcc_lo
	s_addc_u32 s101, s13, 0
	global_load_dwordx4 v[166:169], v136, s[100:101] offset:0
	global_load_dwordx4 v[170:173], v136, s[100:101] offset:1024
	global_load_dwordx4 v[174:177], v136, s[100:101] offset:2048
	global_load_dwordx4 v[178:181], v136, s[100:101] offset:3072
	v_mul_f32_e32 v138, v0, v0
	v_mul_f32_e32 v149, v1, v1
	v_mul_f32_e32 v150, v2, v2
	v_mul_f32_e32 v154, v3, v3
	v_fma_f32 v138, v4, v4, v138
	v_fma_f32 v149, v5, v5, v149
	v_fma_f32 v150, v6, v6, v150
	v_fma_f32 v154, v7, v7, v154
	v_fma_f32 v138, v8, v8, v138
	v_fma_f32 v149, v9, v9, v149
	v_fma_f32 v150, v10, v10, v150
	v_fma_f32 v154, v11, v11, v154
	v_fma_f32 v138, v12, v12, v138
	v_fma_f32 v149, v13, v13, v149
	v_fma_f32 v150, v14, v14, v150
	v_fma_f32 v154, v15, v15, v154
	v_add_f32_e32 v138, v138, v149
	v_add_f32_e32 v150, v150, v154
	v_add_f32_e32 v138, v138, v150
	s_nop 1
	v_add_f32_dpp v138, v138, v138 quad_perm:[1,0,3,2] row_mask:0xf bank_mask:0xf
	s_nop 1
	v_add_f32_dpp v138, v138, v138 quad_perm:[2,3,0,1] row_mask:0xf bank_mask:0xf
	s_nop 1
	v_add_f32_dpp v138, v138, v138 row_half_mirror row_mask:0xf bank_mask:0xf
	s_nop 1
	v_add_f32_dpp v138, v138, v138 row_mirror row_mask:0xf bank_mask:0xf
	v_mov_b32_e32 v139, v138
	s_nop 1
	v_permlane16_swap_b32_e32 v138, v139
	v_add_f32_e32 v138, v138, v139
	v_mov_b32_e32 v139, v138
	s_nop 1
	v_permlane32_swap_b32_e32 v138, v139
	v_add_f32_e32 v138, v138, v139
	v_mul_f32_e32 v138, 0x3a800000, v138
	v_add_f32_e32 v138, 0x358637bd, v138
	v_rsq_f32_e32 v140, v138
	s_nop 0
	v_mul_f32_e32 v120, v0, v140
	v_mul_f32_e32 v121, v1, v140
	v_mul_f32_e32 v122, v2, v140
	v_mul_f32_e32 v123, v3, v140
	v_mul_f32_e32 v124, v4, v140
	v_mul_f32_e32 v125, v5, v140
	v_mul_f32_e32 v126, v6, v140
	v_mul_f32_e32 v127, v7, v140
	v_mul_f32_e32 v128, v8, v140
	v_mul_f32_e32 v129, v9, v140
	v_mul_f32_e32 v130, v10, v140
	v_mul_f32_e32 v131, v11, v140
	v_mul_f32_e32 v132, v12, v140
	v_mul_f32_e32 v133, v13, v140
	v_mul_f32_e32 v134, v14, v140
	v_mul_f32_e32 v135, v15, v140
	v_fma_f32 v120, v120, v88, v104
	v_fma_f32 v121, v121, v89, v105
	v_fma_f32 v122, v122, v90, v106
	v_fma_f32 v123, v123, v91, v107
	v_fma_f32 v124, v124, v92, v108
	v_fma_f32 v125, v125, v93, v109
; __device__ __forceinline__ void row_phase(const Params& P, int glayer, int layer, int xsrc, bool hasY, int gate_idx, const float* gpost,
;                           int xdst, bool doH, const float* gpre, int sh_idx, int nrows) {
;     ...
;           if (xsrc == 0) xin_ = R < N_X ? P.x + (long)R * 1024 : P.ctx + (long)(R - N_X) * 1024;
;           else           xin_ = P.xc + (long)(R - N_X) * 1024;
; #pragma unroll
;           for (int i = 0; i < 4; ++i) xr[u][i] = *reinterpret_cast<const uint4*>(xin_ + (i * 64 + lane) * 4);
;     ...
;         if (doH) {
;           float ss = 0.f;
; #pragma unroll
;           for (int i = 0; i < 4; ++i) ss += xv[i].x * xv[i].x + xv[i].y * xv[i].y + xv[i].z * xv[i].z + xv[i].w * xv[i].w;
;           ss = wave_sum(ss);
;           const float rstd = __builtin_amdgcn_rsqf(ss * (1.f / 1024.f) + EPSF);
;           u16* h = P.hy + (long)row * 1024;
; #pragma unroll
;           for (int i = 0; i < 4; ++i) {
;             const int col = (i * 64 + lane) * 4;
;             const float4 g = *reinterpret_cast<const float4*>(gpre + col);
;             const float4 sh = *reinterpret_cast<const float4*>(modp + sh_idx * 1024 + col);
;             const float4 sc = *reinterpret_cast<const float4*>(modp + (sh_idx + 1) * 1024 + col);
;             const unsigned h0 = f2bf(xv[i].x * rstd * g.x * (1.f + sc.x) + sh.x);
;             const unsigned h1 = f2bf(xv[i].y * rstd * g.y * (1.f + sc.y) + sh.y);
;             const unsigned h2 = f2bf(xv[i].z * rstd * g.z * (1.f + sc.z) + sh.z);
;             const unsigned h3 = f2bf(xv[i].w * rstd * g.w * (1.f + sc.w) + sh.w);
;             *reinterpret_cast<uint2*>(h + col) = make_uint2(h0 | (h1 << 16), h2 | (h3 << 16));
;           }
	v_fma_f32 v126, v126, v94, v110
	v_fma_f32 v127, v127, v95, v111
	v_fma_f32 v128, v128, v96, v112
	v_fma_f32 v129, v129, v97, v113
	v_fma_f32 v130, v130, v98, v114
	v_fma_f32 v131, v131, v99, v115
	v_fma_f32 v132, v132, v100, v116
	v_fma_f32 v133, v133, v101, v117
	v_fma_f32 v134, v134, v102, v118
	v_fma_f32 v135, v135, v103, v119
	v_cvt_pk_bf16_f32 v156, v120, v121
	v_cvt_pk_bf16_f32 v157, v122, v123
	v_cvt_pk_bf16_f32 v158, v124, v125
	v_cvt_pk_bf16_f32 v159, v126, v127
	v_cvt_pk_bf16_f32 v160, v128, v129
	v_cvt_pk_bf16_f32 v161, v130, v131
	v_cvt_pk_bf16_f32 v162, v132, v133
	v_cvt_pk_bf16_f32 v163, v134, v135
	s_lshl_b32 vcc_lo, s19, 11
	s_add_u32 s100, s14, vcc_lo
	s_addc_u32 s101, s15, 0
	global_store_dwordx2 v137, v[156:157], s[100:101] offset:0
	global_store_dwordx2 v137, v[158:159], s[100:101] offset:512
	global_store_dwordx2 v137, v[160:161], s[100:101] offset:1024
	global_store_dwordx2 v137, v[162:163], s[100:101] offset:1536
	s_lshl_b32 vcc_lo, s19, 12
	s_add_u32 vcc_lo, vcc_lo, 0x2000000
	s_add_u32 s100, s12, vcc_lo
	s_addc_u32 s101, s13, 0
	global_load_dwordx4 v[0:3], v136, s[100:101] offset:0
	global_load_dwordx4 v[4:7], v136, s[100:101] offset:1024
	global_load_dwordx4 v[8:11], v136, s[100:101] offset:2048
	global_load_dwordx4 v[12:15], v136, s[100:101] offset:3072
	v_mul_f32_e32 v138, v16, v16
	v_mul_f32_e32 v149, v17, v17
	v_mul_f32_e32 v150, v18, v18
	v_mul_f32_e32 v154, v19, v19
	v_fma_f32 v138, v20, v20, v138
	v_fma_f32 v149, v21, v21, v149
	v_fma_f32 v150, v22, v22, v150
	v_fma_f32 v154, v23, v23, v154
	v_fma_f32 v138, v24, v24, v138
	v_fma_f32 v149, v25, v25, v149
	v_fma_f32 v150, v26, v26, v150
	v_fma_f32 v154, v27, v27, v154
	v_fma_f32 v138, v28, v28, v138
	v_fma_f32 v149, v29, v29, v149
	v_fma_f32 v150, v30, v30, v150
	v_fma_f32 v154, v31, v31, v154
	v_add_f32_e32 v138, v138, v149
	v_add_f32_e32 v150, v150, v154
	v_add_f32_e32 v138, v138, v150
	s_nop 1
	v_add_f32_dpp v138, v138, v138 quad_perm:[1,0,3,2] row_mask:0xf bank_mask:0xf
	s_nop 1
	v_add_f32_dpp v138, v138, v138 quad_perm:[2,3,0,1] row_mask:0xf bank_mask:0xf
	s_nop 1
	v_add_f32_dpp v138, v138, v138 row_half_mirror row_mask:0xf bank_mask:0xf
	s_nop 1
	v_add_f32_dpp v138, v138, v138 row_mirror row_mask:0xf bank_mask:0xf
	v_mov_b32_e32 v139, v138
	s_nop 1
	v_permlane16_swap_b32_e32 v138, v139
	v_add_f32_e32 v138, v138, v139
	v_mov_b32_e32 v139, v138
	s_nop 1
	v_permlane32_swap_b32_e32 v138, v139
	v_add_f32_e32 v138, v138, v139
	v_mul_f32_e32 v138, 0x3a800000, v138
	v_add_f32_e32 v138, 0x358637bd, v138
	v_rsq_f32_e32 v140, v138
	s_nop 0
	v_mul_f32_e32 v120, v16, v140
	v_mul_f32_e32 v121, v17, v140
	v_mul_f32_e32 v122, v18, v140
	v_mul_f32_e32 v123, v19, v140
	v_mul_f32_e32 v124, v20, v140
	v_mul_f32_e32 v125, v21, v140
	v_mul_f32_e32 v126, v22, v140
	v_mul_f32_e32 v127, v23, v140
	v_mul_f32_e32 v128, v24, v140
	v_mul_f32_e32 v129, v25, v140
	v_mul_f32_e32 v130, v26, v140
	v_mul_f32_e32 v131, v27, v140
	v_mul_f32_e32 v132, v28, v140
	v_mul_f32_e32 v133, v29, v140
	v_mul_f32_e32 v134, v30, v140
	v_mul_f32_e32 v135, v31, v140
	v_fma_f32 v120, v120, v88, v104
	v_fma_f32 v121, v121, v89, v105
	v_fma_f32 v122, v122, v90, v106
	v_fma_f32 v123, v123, v91, v107
	v_fma_f32 v124, v124, v92, v108
	v_fma_f32 v125, v125, v93, v109
	v_fma_f32 v126, v126, v94, v110
	v_fma_f32 v127, v127, v95, v111
	v_fma_f32 v128, v128, v96, v112
	v_fma_f32 v129, v129, v97, v113
	v_fma_f32 v130, v130, v98, v114
	v_fma_f32 v131, v131, v99, v115
	v_fma_f32 v132, v132, v100, v116
	v_fma_f32 v133, v133, v101, v117
	v_fma_f32 v134, v134, v102, v118
	v_fma_f32 v135, v135, v103, v119
	v_cvt_pk_bf16_f32 v156, v120, v121
	v_cvt_pk_bf16_f32 v157, v122, v123
	v_cvt_pk_bf16_f32 v158, v124, v125
	v_cvt_pk_bf16_f32 v159, v126, v127
	v_cvt_pk_bf16_f32 v160, v128, v129
	v_cvt_pk_bf16_f32 v161, v130, v131
	v_cvt_pk_bf16_f32 v162, v132, v133
	v_cvt_pk_bf16_f32 v163, v134, v135
	s_lshl_b32 vcc_lo, s19, 11
	s_add_u32 vcc_lo, vcc_lo, 0x400000
	s_add_u32 s100, s14, vcc_lo
	s_addc_u32 s101, s15, 0
	global_store_dwordx2 v137, v[156:157], s[100:101] offset:0
	global_store_dwordx2 v137, v[158:159], s[100:101] offset:512
	global_store_dwordx2 v137, v[160:161], s[100:101] offset:1024
	global_store_dwordx2 v137, v[162:163], s[100:101] offset:1536
	s_lshl_b32 vcc_lo, s19, 12
	s_add_u32 vcc_lo, vcc_lo, 0x2800000
	s_add_u32 s100, s12, vcc_lo
	s_addc_u32 s101, s13, 0
	global_load_dwordx4 v[16:19], v136, s[100:101] offset:0
	global_load_dwordx4 v[20:23], v136, s[100:101] offset:1024
	global_load_dwordx4 v[24:27], v136, s[100:101] offset:2048
	global_load_dwordx4 v[28:31], v136, s[100:101] offset:3072
	v_mul_f32_e32 v138, v32, v32
	v_mul_f32_e32 v149, v33, v33
	v_mul_f32_e32 v150, v34, v34
	v_mul_f32_e32 v154, v35, v35
	v_fma_f32 v138, v36, v36, v138
	v_fma_f32 v149, v37, v37, v149
	v_fma_f32 v150, v38, v38, v150
	v_fma_f32 v154, v39, v39, v154
	v_fma_f32 v138, v40, v40, v138
	v_fma_f32 v149, v41, v41, v149
	v_fma_f32 v150, v42, v42, v150
	v_fma_f32 v154, v43, v43, v154
	v_fma_f32 v138, v44, v44, v138
	v_fma_f32 v149, v45, v45, v149
	v_fma_f32 v150, v46, v46, v150
	v_fma_f32 v154, v47, v47, v154
	v_add_f32_e32 v138, v138, v149
	v_add_f32_e32 v150, v150, v154
	v_add_f32_e32 v138, v138, v150
	s_nop 1
	v_add_f32_dpp v138, v138, v138 quad_perm:[1,0,3,2] row_mask:0xf bank_mask:0xf
	s_nop 1
	v_add_f32_dpp v138, v138, v138 quad_perm:[2,3,0,1] row_mask:0xf bank_mask:0xf
	s_nop 1
	v_add_f32_dpp v138, v138, v138 row_half_mirror row_mask:0xf bank_mask:0xf
	s_nop 1
	v_add_f32_dpp v138, v138, v138 row_mirror row_mask:0xf bank_mask:0xf
	v_mov_b32_e32 v139, v138
	s_nop 1
	v_permlane16_swap_b32_e32 v138, v139
	v_add_f32_e32 v138, v138, v139
; __device__ __forceinline__ void row_phase(const Params& P, int glayer, int layer, int xsrc, bool hasY, int gate_idx, const float* gpost,
;                           int xdst, bool doH, const float* gpre, int sh_idx, int nrows) {
;     ...
;           if (xsrc == 0) xin_ = R < N_X ? P.x + (long)R * 1024 : P.ctx + (long)(R - N_X) * 1024;
;           else           xin_ = P.xc + (long)(R - N_X) * 1024;
; #pragma unroll
;           for (int i = 0; i < 4; ++i) xr[u][i] = *reinterpret_cast<const uint4*>(xin_ + (i * 64 + lane) * 4);
;     ...
;         if (doH) {
;           float ss = 0.f;
; #pragma unroll
;           for (int i = 0; i < 4; ++i) ss += xv[i].x * xv[i].x + xv[i].y * xv[i].y + xv[i].z * xv[i].z + xv[i].w * xv[i].w;
;           ss = wave_sum(ss);
;           const float rstd = __builtin_amdgcn_rsqf(ss * (1.f / 1024.f) + EPSF);
;           u16* h = P.hy + (long)row * 1024;
; #pragma unroll
;           for (int i = 0; i < 4; ++i) {
;             const int col = (i * 64 + lane) * 4;
;             const float4 g = *reinterpret_cast<const float4*>(gpre + col);
;             const float4 sh = *reinterpret_cast<const float4*>(modp + sh_idx * 1024 + col);
;             const float4 sc = *reinterpret_cast<const float4*>(modp + (sh_idx + 1) * 1024 + col);
;             const unsigned h0 = f2bf(xv[i].x * rstd * g.x * (1.f + sc.x) + sh.x);
;             const unsigned h1 = f2bf(xv[i].y * rstd * g.y * (1.f + sc.y) + sh.y);
;             const unsigned h2 = f2bf(xv[i].z * rstd * g.z * (1.f + sc.z) + sh.z);
;             const unsigned h3 = f2bf(xv[i].w * rstd * g.w * (1.f + sc.w) + sh.w);
;             *reinterpret_cast<uint2*>(h + col) = make_uint2(h0 | (h1 << 16), h2 | (h3 << 16));
;           }
	v_mov_b32_e32 v139, v138
	s_nop 1
	v_permlane32_swap_b32_e32 v138, v139
	v_add_f32_e32 v138, v138, v139
	v_mul_f32_e32 v138, 0x3a800000, v138
	v_add_f32_e32 v138, 0x358637bd, v138
	v_rsq_f32_e32 v140, v138
	s_nop 0
	v_mul_f32_e32 v120, v32, v140
	v_mul_f32_e32 v121, v33, v140
	v_mul_f32_e32 v122, v34, v140
	v_mul_f32_e32 v123, v35, v140
	v_mul_f32_e32 v124, v36, v140
	v_mul_f32_e32 v125, v37, v140
	v_mul_f32_e32 v126, v38, v140
	v_mul_f32_e32 v127, v39, v140
	v_mul_f32_e32 v128, v40, v140
	v_mul_f32_e32 v129, v41, v140
	v_mul_f32_e32 v130, v42, v140
	v_mul_f32_e32 v131, v43, v140
	v_mul_f32_e32 v132, v44, v140
	v_mul_f32_e32 v133, v45, v140
	v_mul_f32_e32 v134, v46, v140
	v_mul_f32_e32 v135, v47, v140
	v_fma_f32 v120, v120, v88, v104
	v_fma_f32 v121, v121, v89, v105
	v_fma_f32 v122, v122, v90, v106
	v_fma_f32 v123, v123, v91, v107
	v_fma_f32 v124, v124, v92, v108
	v_fma_f32 v125, v125, v93, v109
	v_fma_f32 v126, v126, v94, v110
	v_fma_f32 v127, v127, v95, v111
	v_fma_f32 v128, v128, v96, v112
	v_fma_f32 v129, v129, v97, v113
	v_fma_f32 v130, v130, v98, v114
	v_fma_f32 v131, v131, v99, v115
	v_fma_f32 v132, v132, v100, v116
	v_fma_f32 v133, v133, v101, v117
	v_fma_f32 v134, v134, v102, v118
	v_fma_f32 v135, v135, v103, v119
	v_cvt_pk_bf16_f32 v156, v120, v121
	v_cvt_pk_bf16_f32 v157, v122, v123
	v_cvt_pk_bf16_f32 v158, v124, v125
	v_cvt_pk_bf16_f32 v159, v126, v127
	v_cvt_pk_bf16_f32 v160, v128, v129
	v_cvt_pk_bf16_f32 v161, v130, v131
	v_cvt_pk_bf16_f32 v162, v132, v133
	v_cvt_pk_bf16_f32 v163, v134, v135
	s_lshl_b32 vcc_lo, s19, 11
	s_add_u32 vcc_lo, vcc_lo, 0x800000
	s_add_u32 s100, s14, vcc_lo
	s_addc_u32 s101, s15, 0
	global_store_dwordx2 v137, v[156:157], s[100:101] offset:0
	global_store_dwordx2 v137, v[158:159], s[100:101] offset:512
	global_store_dwordx2 v137, v[160:161], s[100:101] offset:1024
	global_store_dwordx2 v137, v[162:163], s[100:101] offset:1536
	s_lshl_b32 vcc_lo, s19, 12
	s_add_u32 vcc_lo, vcc_lo, 0x3000000
	s_add_u32 s100, s12, vcc_lo
	s_addc_u32 s101, s13, 0
	global_load_dwordx4 v[32:35], v136, s[100:101] offset:0
	global_load_dwordx4 v[36:39], v136, s[100:101] offset:1024
	global_load_dwordx4 v[40:43], v136, s[100:101] offset:2048
	global_load_dwordx4 v[44:47], v136, s[100:101] offset:3072
	s_waitcnt vmcnt(24)
	v_mul_f32_e32 v138, v166, v166
	v_mul_f32_e32 v149, v167, v167
	v_mul_f32_e32 v150, v168, v168
	v_mul_f32_e32 v154, v169, v169
	v_fma_f32 v138, v170, v170, v138
	v_fma_f32 v149, v171, v171, v149
	v_fma_f32 v150, v172, v172, v150
	v_fma_f32 v154, v173, v173, v154
	v_fma_f32 v138, v174, v174, v138
	v_fma_f32 v149, v175, v175, v149
	v_fma_f32 v150, v176, v176, v150
	v_fma_f32 v154, v177, v177, v154
	v_fma_f32 v138, v178, v178, v138
	v_fma_f32 v149, v179, v179, v149
	v_fma_f32 v150, v180, v180, v150
	v_fma_f32 v154, v181, v181, v154
	v_add_f32_e32 v138, v138, v149
	v_add_f32_e32 v150, v150, v154
	v_add_f32_e32 v138, v138, v150
	s_nop 1
	v_add_f32_dpp v138, v138, v138 quad_perm:[1,0,3,2] row_mask:0xf bank_mask:0xf
	s_nop 1
	v_add_f32_dpp v138, v138, v138 quad_perm:[2,3,0,1] row_mask:0xf bank_mask:0xf
	s_nop 1
	v_add_f32_dpp v138, v138, v138 row_half_mirror row_mask:0xf bank_mask:0xf
	s_nop 1
	v_add_f32_dpp v138, v138, v138 row_mirror row_mask:0xf bank_mask:0xf
	v_mov_b32_e32 v139, v138
	s_nop 1
	v_permlane16_swap_b32_e32 v138, v139
	v_add_f32_e32 v138, v138, v139
	v_mov_b32_e32 v139, v138
	s_nop 1
	v_permlane32_swap_b32_e32 v138, v139
	v_add_f32_e32 v138, v138, v139
	v_mul_f32_e32 v138, 0x3a800000, v138
	v_add_f32_e32 v138, 0x358637bd, v138
	v_rsq_f32_e32 v140, v138
	s_nop 0
	v_mul_f32_e32 v120, v166, v140
	v_mul_f32_e32 v121, v167, v140
	v_mul_f32_e32 v122, v168, v140
	v_mul_f32_e32 v123, v169, v140
	v_mul_f32_e32 v124, v170, v140
	v_mul_f32_e32 v125, v171, v140
	v_mul_f32_e32 v126, v172, v140
	v_mul_f32_e32 v127, v173, v140
	v_mul_f32_e32 v128, v174, v140
	v_mul_f32_e32 v129, v175, v140
	v_mul_f32_e32 v130, v176, v140
	v_mul_f32_e32 v131, v177, v140
	v_mul_f32_e32 v132, v178, v140
	v_mul_f32_e32 v133, v179, v140
	v_mul_f32_e32 v134, v180, v140
	v_mul_f32_e32 v135, v181, v140
	v_fma_f32 v120, v120, v88, v104
	v_fma_f32 v121, v121, v89, v105
	v_fma_f32 v122, v122, v90, v106
	v_fma_f32 v123, v123, v91, v107
	v_fma_f32 v124, v124, v92, v108
	v_fma_f32 v125, v125, v93, v109
	v_fma_f32 v126, v126, v94, v110
	v_fma_f32 v127, v127, v95, v111
	v_fma_f32 v128, v128, v96, v112
	v_fma_f32 v129, v129, v97, v113
	v_fma_f32 v130, v130, v98, v114
	v_fma_f32 v131, v131, v99, v115
	v_fma_f32 v132, v132, v100, v116
	v_fma_f32 v133, v133, v101, v117
	v_fma_f32 v134, v134, v102, v118
	v_fma_f32 v135, v135, v103, v119
	v_cvt_pk_bf16_f32 v156, v120, v121
	v_cvt_pk_bf16_f32 v157, v122, v123
	v_cvt_pk_bf16_f32 v158, v124, v125
	v_cvt_pk_bf16_f32 v159, v126, v127
	v_cvt_pk_bf16_f32 v160, v128, v129
	v_cvt_pk_bf16_f32 v161, v130, v131
	v_cvt_pk_bf16_f32 v162, v132, v133
	v_cvt_pk_bf16_f32 v163, v134, v135
	s_lshl_b32 vcc_lo, s19, 11
	s_add_u32 vcc_lo, vcc_lo, 0xc00000
	s_add_u32 s100, s14, vcc_lo
	s_addc_u32 s101, s15, 0
	global_store_dwordx2 v137, v[156:157], s[100:101] offset:0
	global_store_dwordx2 v137, v[158:159], s[100:101] offset:512
	global_store_dwordx2 v137, v[160:161], s[100:101] offset:1024
	global_store_dwordx2 v137, v[162:163], s[100:101] offset:1536
	s_add_u32 s100, s20, 0x6000
	s_addc_u32 s101, s21, 0
	global_load_dwordx4 v[104:107], v136, s[100:101] offset:0
	global_load_dwordx4 v[108:111], v136, s[100:101] offset:1024
	global_load_dwordx4 v[112:115], v136, s[100:101] offset:2048
	global_load_dwordx4 v[116:119], v136, s[100:101] offset:3072
	s_add_u32 s100, s100, 0x1000
	s_addc_u32 s101, s101, 0
	global_load_dwordx4 v[166:169], v136, s[100:101] offset:0
	global_load_dwordx4 v[170:173], v136, s[100:101] offset:1024
	global_load_dwordx4 v[174:177], v136, s[100:101] offset:2048
	global_load_dwordx4 v[178:181], v136, s[100:101] offset:3072
	s_load_dwordx2 s[98:99], s[4:5], 0x30
	s_waitcnt lgkmcnt(0)
; __device__ __forceinline__ void row_phase(const Params& P, int glayer, int layer, int xsrc, bool hasY, int gate_idx, const float* gpost,
;                           int xdst, bool doH, const float* gpre, int sh_idx, int nrows) {
;     ...
;           if (xsrc == 0) xin_ = R < N_X ? P.x + (long)R * 1024 : P.ctx + (long)(R - N_X) * 1024;
;           else           xin_ = P.xc + (long)(R - N_X) * 1024;
; #pragma unroll
;           for (int i = 0; i < 4; ++i) xr[u][i] = *reinterpret_cast<const uint4*>(xin_ + (i * 64 + lane) * 4);
;     ...
;         if (doH) {
;           float ss = 0.f;
; #pragma unroll
;           for (int i = 0; i < 4; ++i) ss += xv[i].x * xv[i].x + xv[i].y * xv[i].y + xv[i].z * xv[i].z + xv[i].w * xv[i].w;
;           ss = wave_sum(ss);
;           const float rstd = __builtin_amdgcn_rsqf(ss * (1.f / 1024.f) + EPSF);
;           u16* h = P.hy + (long)row * 1024;
; #pragma unroll
;           for (int i = 0; i < 4; ++i) {
;             const int col = (i * 64 + lane) * 4;
;             const float4 g = *reinterpret_cast<const float4*>(gpre + col);
;             const float4 sh = *reinterpret_cast<const float4*>(modp + sh_idx * 1024 + col);
;             const float4 sc = *reinterpret_cast<const float4*>(modp + (sh_idx + 1) * 1024 + col);
;             const unsigned h0 = f2bf(xv[i].x * rstd * g.x * (1.f + sc.x) + sh.x);
;             const unsigned h1 = f2bf(xv[i].y * rstd * g.y * (1.f + sc.y) + sh.y);
;             const unsigned h2 = f2bf(xv[i].z * rstd * g.z * (1.f + sc.z) + sh.z);
;             const unsigned h3 = f2bf(xv[i].w * rstd * g.w * (1.f + sc.w) + sh.w);
;             *reinterpret_cast<uint2*>(h + col) = make_uint2(h0 | (h1 << 16), h2 | (h3 << 16));
;           }
	global_load_dwordx4 v[88:91], v136, s[98:99] offset:0
	global_load_dwordx4 v[92:95], v136, s[98:99] offset:1024
	global_load_dwordx4 v[96:99], v136, s[98:99] offset:2048
	global_load_dwordx4 v[100:103], v136, s[98:99] offset:3072
	s_waitcnt vmcnt(0)
	v_fma_f32 v88, v88, v166, v88
	v_fma_f32 v89, v89, v167, v89
	v_fma_f32 v90, v90, v168, v90
	v_fma_f32 v91, v91, v169, v91
	v_fma_f32 v92, v92, v170, v92
	v_fma_f32 v93, v93, v171, v93
	v_fma_f32 v94, v94, v172, v94
	v_fma_f32 v95, v95, v173, v95
	v_fma_f32 v96, v96, v174, v96
	v_fma_f32 v97, v97, v175, v97
	v_fma_f32 v98, v98, v176, v98
	v_fma_f32 v99, v99, v177, v99
	v_fma_f32 v100, v100, v178, v100
	v_fma_f32 v101, v101, v179, v101
	v_fma_f32 v102, v102, v180, v102
	v_fma_f32 v103, v103, v181, v103
	s_lshl_b32 vcc_lo, s19, 12
	s_add_u32 vcc_lo, vcc_lo, 0x3800000
	s_add_u32 s100, s12, vcc_lo
	s_addc_u32 s101, s13, 0
	global_load_dwordx4 v[166:169], v136, s[100:101] offset:0
	global_load_dwordx4 v[170:173], v136, s[100:101] offset:1024
	global_load_dwordx4 v[174:177], v136, s[100:101] offset:2048
	global_load_dwordx4 v[178:181], v136, s[100:101] offset:3072
	v_mul_f32_e32 v138, v0, v0
	v_mul_f32_e32 v149, v1, v1
	v_mul_f32_e32 v150, v2, v2
	v_mul_f32_e32 v154, v3, v3
	v_fma_f32 v138, v4, v4, v138
	v_fma_f32 v149, v5, v5, v149
	v_fma_f32 v150, v6, v6, v150
	v_fma_f32 v154, v7, v7, v154
	v_fma_f32 v138, v8, v8, v138
	v_fma_f32 v149, v9, v9, v149
	v_fma_f32 v150, v10, v10, v150
	v_fma_f32 v154, v11, v11, v154
	v_fma_f32 v138, v12, v12, v138
	v_fma_f32 v149, v13, v13, v149
	v_fma_f32 v150, v14, v14, v150
	v_fma_f32 v154, v15, v15, v154
	v_add_f32_e32 v138, v138, v149
	v_add_f32_e32 v150, v150, v154
	v_add_f32_e32 v138, v138, v150
	s_nop 1
	v_add_f32_dpp v138, v138, v138 quad_perm:[1,0,3,2] row_mask:0xf bank_mask:0xf
	s_nop 1
	v_add_f32_dpp v138, v138, v138 quad_perm:[2,3,0,1] row_mask:0xf bank_mask:0xf
	s_nop 1
	v_add_f32_dpp v138, v138, v138 row_half_mirror row_mask:0xf bank_mask:0xf
	s_nop 1
	v_add_f32_dpp v138, v138, v138 row_mirror row_mask:0xf bank_mask:0xf
	v_mov_b32_e32 v139, v138
	s_nop 1
	v_permlane16_swap_b32_e32 v138, v139
	v_add_f32_e32 v138, v138, v139
	v_mov_b32_e32 v139, v138
	s_nop 1
	v_permlane32_swap_b32_e32 v138, v139
	v_add_f32_e32 v138, v138, v139
	v_mul_f32_e32 v138, 0x3a800000, v138
	v_add_f32_e32 v138, 0x358637bd, v138
	v_rsq_f32_e32 v140, v138
	s_nop 0
	v_mul_f32_e32 v120, v0, v140
	v_mul_f32_e32 v121, v1, v140
	v_mul_f32_e32 v122, v2, v140
	v_mul_f32_e32 v123, v3, v140
	v_mul_f32_e32 v124, v4, v140
	v_mul_f32_e32 v125, v5, v140
	v_mul_f32_e32 v126, v6, v140
	v_mul_f32_e32 v127, v7, v140
	v_mul_f32_e32 v128, v8, v140
	v_mul_f32_e32 v129, v9, v140
	v_mul_f32_e32 v130, v10, v140
	v_mul_f32_e32 v131, v11, v140
	v_mul_f32_e32 v132, v12, v140
	v_mul_f32_e32 v133, v13, v140
	v_mul_f32_e32 v134, v14, v140
	v_mul_f32_e32 v135, v15, v140
	v_fma_f32 v120, v120, v88, v104
	v_fma_f32 v121, v121, v89, v105
	v_fma_f32 v122, v122, v90, v106
	v_fma_f32 v123, v123, v91, v107
	v_fma_f32 v124, v124, v92, v108
	v_fma_f32 v125, v125, v93, v109
	v_fma_f32 v126, v126, v94, v110
	v_fma_f32 v127, v127, v95, v111
	v_fma_f32 v128, v128, v96, v112
	v_fma_f32 v129, v129, v97, v113
	v_fma_f32 v130, v130, v98, v114
	v_fma_f32 v131, v131, v99, v115
	v_fma_f32 v132, v132, v100, v116
	v_fma_f32 v133, v133, v101, v117
	v_fma_f32 v134, v134, v102, v118
	v_fma_f32 v135, v135, v103, v119
	v_cvt_pk_bf16_f32 v156, v120, v121
	v_cvt_pk_bf16_f32 v157, v122, v123
	v_cvt_pk_bf16_f32 v158, v124, v125
	v_cvt_pk_bf16_f32 v159, v126, v127
	v_cvt_pk_bf16_f32 v160, v128, v129
	v_cvt_pk_bf16_f32 v161, v130, v131
	v_cvt_pk_bf16_f32 v162, v132, v133
	v_cvt_pk_bf16_f32 v163, v134, v135
	s_lshl_b32 vcc_lo, s19, 11
	s_add_u32 vcc_lo, vcc_lo, 0x1000000
	s_add_u32 s100, s14, vcc_lo
	s_addc_u32 s101, s15, 0
	global_store_dwordx2 v137, v[156:157], s[100:101] offset:0
	global_store_dwordx2 v137, v[158:159], s[100:101] offset:512
	global_store_dwordx2 v137, v[160:161], s[100:101] offset:1024
	global_store_dwordx2 v137, v[162:163], s[100:101] offset:1536
	s_lshl_b32 vcc_lo, s19, 12
	s_add_u32 vcc_lo, vcc_lo, 0x4000000
	s_add_u32 s100, s12, vcc_lo
	s_addc_u32 s101, s13, 0
	global_load_dwordx4 v[0:3], v136, s[100:101] offset:0
	global_load_dwordx4 v[4:7], v136, s[100:101] offset:1024
	global_load_dwordx4 v[8:11], v136, s[100:101] offset:2048
	global_load_dwordx4 v[12:15], v136, s[100:101] offset:3072
	v_mul_f32_e32 v138, v16, v16
	v_mul_f32_e32 v149, v17, v17
	v_mul_f32_e32 v150, v18, v18
	v_mul_f32_e32 v154, v19, v19
	v_fma_f32 v138, v20, v20, v138
	v_fma_f32 v149, v21, v21, v149
	v_fma_f32 v150, v22, v22, v150
	v_fma_f32 v154, v23, v23, v154
	v_fma_f32 v138, v24, v24, v138
	v_fma_f32 v149, v25, v25, v149
	v_fma_f32 v150, v26, v26, v150
	v_fma_f32 v154, v27, v27, v154
	v_fma_f32 v138, v28, v28, v138
	v_fma_f32 v149, v29, v29, v149
	v_fma_f32 v150, v30, v30, v150
	v_fma_f32 v154, v31, v31, v154
	v_add_f32_e32 v138, v138, v149
	v_add_f32_e32 v150, v150, v154
	v_add_f32_e32 v138, v138, v150
	s_nop 1
	v_add_f32_dpp v138, v138, v138 quad_perm:[1,0,3,2] row_mask:0xf bank_mask:0xf
	s_nop 1
	v_add_f32_dpp v138, v138, v138 quad_perm:[2,3,0,1] row_mask:0xf bank_mask:0xf
	s_nop 1
	v_add_f32_dpp v138, v138, v138 row_half_mirror row_mask:0xf bank_mask:0xf
	s_nop 1
	v_add_f32_dpp v138, v138, v138 row_mirror row_mask:0xf bank_mask:0xf
	v_mov_b32_e32 v139, v138
	s_nop 1
	v_permlane16_swap_b32_e32 v138, v139
	v_add_f32_e32 v138, v138, v139
	v_mov_b32_e32 v139, v138
	s_nop 1
	v_permlane32_swap_b32_e32 v138, v139
	v_add_f32_e32 v138, v138, v139
	v_mul_f32_e32 v138, 0x3a800000, v138
	v_add_f32_e32 v138, 0x358637bd, v138
	v_rsq_f32_e32 v140, v138
; __device__ __forceinline__ void row_phase(const Params& P, int glayer, int layer, int xsrc, bool hasY, int gate_idx, const float* gpost,
;                           int xdst, bool doH, const float* gpre, int sh_idx, int nrows) {
;     ...
;           if (xsrc == 0) xin_ = R < N_X ? P.x + (long)R * 1024 : P.ctx + (long)(R - N_X) * 1024;
;           else           xin_ = P.xc + (long)(R - N_X) * 1024;
; #pragma unroll
;           for (int i = 0; i < 4; ++i) xr[u][i] = *reinterpret_cast<const uint4*>(xin_ + (i * 64 + lane) * 4);
;     ...
;         if (doH) {
;           float ss = 0.f;
; #pragma unroll
;           for (int i = 0; i < 4; ++i) ss += xv[i].x * xv[i].x + xv[i].y * xv[i].y + xv[i].z * xv[i].z + xv[i].w * xv[i].w;
;           ss = wave_sum(ss);
;           const float rstd = __builtin_amdgcn_rsqf(ss * (1.f / 1024.f) + EPSF);
;           u16* h = P.hy + (long)row * 1024;
; #pragma unroll
;           for (int i = 0; i < 4; ++i) {
;             const int col = (i * 64 + lane) * 4;
;             const float4 g = *reinterpret_cast<const float4*>(gpre + col);
;             const float4 sh = *reinterpret_cast<const float4*>(modp + sh_idx * 1024 + col);
;             const float4 sc = *reinterpret_cast<const float4*>(modp + (sh_idx + 1) * 1024 + col);
;             const unsigned h0 = f2bf(xv[i].x * rstd * g.x * (1.f + sc.x) + sh.x);
;             const unsigned h1 = f2bf(xv[i].y * rstd * g.y * (1.f + sc.y) + sh.y);
;             const unsigned h2 = f2bf(xv[i].z * rstd * g.z * (1.f + sc.z) + sh.z);
;             const unsigned h3 = f2bf(xv[i].w * rstd * g.w * (1.f + sc.w) + sh.w);
;             *reinterpret_cast<uint2*>(h + col) = make_uint2(h0 | (h1 << 16), h2 | (h3 << 16));
;           }
	s_nop 0
	v_mul_f32_e32 v120, v16, v140
	v_mul_f32_e32 v121, v17, v140
	v_mul_f32_e32 v122, v18, v140
	v_mul_f32_e32 v123, v19, v140
	v_mul_f32_e32 v124, v20, v140
	v_mul_f32_e32 v125, v21, v140
	v_mul_f32_e32 v126, v22, v140
	v_mul_f32_e32 v127, v23, v140
	v_mul_f32_e32 v128, v24, v140
	v_mul_f32_e32 v129, v25, v140
	v_mul_f32_e32 v130, v26, v140
	v_mul_f32_e32 v131, v27, v140
	v_mul_f32_e32 v132, v28, v140
	v_mul_f32_e32 v133, v29, v140
	v_mul_f32_e32 v134, v30, v140
	v_mul_f32_e32 v135, v31, v140
	v_fma_f32 v120, v120, v88, v104
	v_fma_f32 v121, v121, v89, v105
	v_fma_f32 v122, v122, v90, v106
	v_fma_f32 v123, v123, v91, v107
	v_fma_f32 v124, v124, v92, v108
	v_fma_f32 v125, v125, v93, v109
	v_fma_f32 v126, v126, v94, v110
	v_fma_f32 v127, v127, v95, v111
	v_fma_f32 v128, v128, v96, v112
	v_fma_f32 v129, v129, v97, v113
	v_fma_f32 v130, v130, v98, v114
	v_fma_f32 v131, v131, v99, v115
	v_fma_f32 v132, v132, v100, v116
	v_fma_f32 v133, v133, v101, v117
	v_fma_f32 v134, v134, v102, v118
	v_fma_f32 v135, v135, v103, v119
	v_cvt_pk_bf16_f32 v156, v120, v121
	v_cvt_pk_bf16_f32 v157, v122, v123
	v_cvt_pk_bf16_f32 v158, v124, v125
	v_cvt_pk_bf16_f32 v159, v126, v127
	v_cvt_pk_bf16_f32 v160, v128, v129
	v_cvt_pk_bf16_f32 v161, v130, v131
	v_cvt_pk_bf16_f32 v162, v132, v133
	v_cvt_pk_bf16_f32 v163, v134, v135
	s_lshl_b32 vcc_lo, s19, 11
	s_add_u32 vcc_lo, vcc_lo, 0x1400000
	s_add_u32 s100, s14, vcc_lo
	s_addc_u32 s101, s15, 0
	global_store_dwordx2 v137, v[156:157], s[100:101] offset:0
	global_store_dwordx2 v137, v[158:159], s[100:101] offset:512
	global_store_dwordx2 v137, v[160:161], s[100:101] offset:1024
	global_store_dwordx2 v137, v[162:163], s[100:101] offset:1536
	s_lshl_b32 vcc_lo, s19, 12
	s_add_u32 vcc_lo, vcc_lo, 0x4800000
	s_add_u32 s100, s12, vcc_lo
	s_addc_u32 s101, s13, 0
	global_load_dwordx4 v[16:19], v136, s[100:101] offset:0
	global_load_dwordx4 v[20:23], v136, s[100:101] offset:1024
	global_load_dwordx4 v[24:27], v136, s[100:101] offset:2048
	global_load_dwordx4 v[28:31], v136, s[100:101] offset:3072
	v_mul_f32_e32 v138, v32, v32
	v_mul_f32_e32 v149, v33, v33
	v_mul_f32_e32 v150, v34, v34
	v_mul_f32_e32 v154, v35, v35
	v_fma_f32 v138, v36, v36, v138
	v_fma_f32 v149, v37, v37, v149
	v_fma_f32 v150, v38, v38, v150
	v_fma_f32 v154, v39, v39, v154
	v_fma_f32 v138, v40, v40, v138
	v_fma_f32 v149, v41, v41, v149
	v_fma_f32 v150, v42, v42, v150
	v_fma_f32 v154, v43, v43, v154
	v_fma_f32 v138, v44, v44, v138
	v_fma_f32 v149, v45, v45, v149
	v_fma_f32 v150, v46, v46, v150
	v_fma_f32 v154, v47, v47, v154
	v_add_f32_e32 v138, v138, v149
	v_add_f32_e32 v150, v150, v154
	v_add_f32_e32 v138, v138, v150
	s_nop 1
	v_add_f32_dpp v138, v138, v138 quad_perm:[1,0,3,2] row_mask:0xf bank_mask:0xf
	s_nop 1
	v_add_f32_dpp v138, v138, v138 quad_perm:[2,3,0,1] row_mask:0xf bank_mask:0xf
	s_nop 1
	v_add_f32_dpp v138, v138, v138 row_half_mirror row_mask:0xf bank_mask:0xf
	s_nop 1
	v_add_f32_dpp v138, v138, v138 row_mirror row_mask:0xf bank_mask:0xf
	v_mov_b32_e32 v139, v138
	s_nop 1
	v_permlane16_swap_b32_e32 v138, v139
	v_add_f32_e32 v138, v138, v139
	v_mov_b32_e32 v139, v138
	s_nop 1
	v_permlane32_swap_b32_e32 v138, v139
	v_add_f32_e32 v138, v138, v139
	v_mul_f32_e32 v138, 0x3a800000, v138
	v_add_f32_e32 v138, 0x358637bd, v138
	v_rsq_f32_e32 v140, v138
	s_nop 0
	v_mul_f32_e32 v120, v32, v140
	v_mul_f32_e32 v121, v33, v140
	v_mul_f32_e32 v122, v34, v140
	v_mul_f32_e32 v123, v35, v140
	v_mul_f32_e32 v124, v36, v140
	v_mul_f32_e32 v125, v37, v140
	v_mul_f32_e32 v126, v38, v140
	v_mul_f32_e32 v127, v39, v140
	v_mul_f32_e32 v128, v40, v140
	v_mul_f32_e32 v129, v41, v140
	v_mul_f32_e32 v130, v42, v140
	v_mul_f32_e32 v131, v43, v140
	v_mul_f32_e32 v132, v44, v140
	v_mul_f32_e32 v133, v45, v140
	v_mul_f32_e32 v134, v46, v140
	v_mul_f32_e32 v135, v47, v140
	v_fma_f32 v120, v120, v88, v104
	v_fma_f32 v121, v121, v89, v105
	v_fma_f32 v122, v122, v90, v106
	v_fma_f32 v123, v123, v91, v107
	v_fma_f32 v124, v124, v92, v108
	v_fma_f32 v125, v125, v93, v109
	v_fma_f32 v126, v126, v94, v110
	v_fma_f32 v127, v127, v95, v111
	v_fma_f32 v128, v128, v96, v112
	v_fma_f32 v129, v129, v97, v113
	v_fma_f32 v130, v130, v98, v114
	v_fma_f32 v131, v131, v99, v115
	v_fma_f32 v132, v132, v100, v116
	v_fma_f32 v133, v133, v101, v117
	v_fma_f32 v134, v134, v102, v118
	v_fma_f32 v135, v135, v103, v119
	v_cvt_pk_bf16_f32 v156, v120, v121
	v_cvt_pk_bf16_f32 v157, v122, v123
	v_cvt_pk_bf16_f32 v158, v124, v125
	v_cvt_pk_bf16_f32 v159, v126, v127
	v_cvt_pk_bf16_f32 v160, v128, v129
	v_cvt_pk_bf16_f32 v161, v130, v131
	v_cvt_pk_bf16_f32 v162, v132, v133
	v_cvt_pk_bf16_f32 v163, v134, v135
	s_lshl_b32 vcc_lo, s19, 11
	s_add_u32 vcc_lo, vcc_lo, 0x1800000
	s_add_u32 s100, s14, vcc_lo
	s_addc_u32 s101, s15, 0
	global_store_dwordx2 v137, v[156:157], s[100:101] offset:0
	global_store_dwordx2 v137, v[158:159], s[100:101] offset:512
	global_store_dwordx2 v137, v[160:161], s[100:101] offset:1024
	global_store_dwordx2 v137, v[162:163], s[100:101] offset:1536
	s_lshl_b32 vcc_lo, s19, 12
	s_add_u32 vcc_lo, vcc_lo, 0x5000000
	s_add_u32 s100, s12, vcc_lo
	s_addc_u32 s101, s13, 0
	global_load_dwordx4 v[32:35], v136, s[100:101] offset:0
	global_load_dwordx4 v[36:39], v136, s[100:101] offset:1024
	global_load_dwordx4 v[40:43], v136, s[100:101] offset:2048
	global_load_dwordx4 v[44:47], v136, s[100:101] offset:3072
	s_waitcnt vmcnt(24)
; __device__ __forceinline__ void row_phase(const Params& P, int glayer, int layer, int xsrc, bool hasY, int gate_idx, const float* gpost,
;                           int xdst, bool doH, const float* gpre, int sh_idx, int nrows) {
;     ...
;           if (xsrc == 0) xin_ = R < N_X ? P.x + (long)R * 1024 : P.ctx + (long)(R - N_X) * 1024;
;           else           xin_ = P.xc + (long)(R - N_X) * 1024;
; #pragma unroll
;           for (int i = 0; i < 4; ++i) xr[u][i] = *reinterpret_cast<const uint4*>(xin_ + (i * 64 + lane) * 4);
;     ...
;         if (doH) {
;           float ss = 0.f;
; #pragma unroll
;           for (int i = 0; i < 4; ++i) ss += xv[i].x * xv[i].x + xv[i].y * xv[i].y + xv[i].z * xv[i].z + xv[i].w * xv[i].w;
;           ss = wave_sum(ss);
;           const float rstd = __builtin_amdgcn_rsqf(ss * (1.f / 1024.f) + EPSF);
;           u16* h = P.hy + (long)row * 1024;
; #pragma unroll
;           for (int i = 0; i < 4; ++i) {
;             const int col = (i * 64 + lane) * 4;
;             const float4 g = *reinterpret_cast<const float4*>(gpre + col);
;             const float4 sh = *reinterpret_cast<const float4*>(modp + sh_idx * 1024 + col);
;             const float4 sc = *reinterpret_cast<const float4*>(modp + (sh_idx + 1) * 1024 + col);
;             const unsigned h0 = f2bf(xv[i].x * rstd * g.x * (1.f + sc.x) + sh.x);
;             const unsigned h1 = f2bf(xv[i].y * rstd * g.y * (1.f + sc.y) + sh.y);
;             const unsigned h2 = f2bf(xv[i].z * rstd * g.z * (1.f + sc.z) + sh.z);
;             const unsigned h3 = f2bf(xv[i].w * rstd * g.w * (1.f + sc.w) + sh.w);
;             *reinterpret_cast<uint2*>(h + col) = make_uint2(h0 | (h1 << 16), h2 | (h3 << 16));
;           }
	v_mul_f32_e32 v138, v166, v166
	v_mul_f32_e32 v149, v167, v167
	v_mul_f32_e32 v150, v168, v168
	v_mul_f32_e32 v154, v169, v169
	v_fma_f32 v138, v170, v170, v138
	v_fma_f32 v149, v171, v171, v149
	v_fma_f32 v150, v172, v172, v150
	v_fma_f32 v154, v173, v173, v154
	v_fma_f32 v138, v174, v174, v138
	v_fma_f32 v149, v175, v175, v149
	v_fma_f32 v150, v176, v176, v150
	v_fma_f32 v154, v177, v177, v154
	v_fma_f32 v138, v178, v178, v138
	v_fma_f32 v149, v179, v179, v149
	v_fma_f32 v150, v180, v180, v150
	v_fma_f32 v154, v181, v181, v154
	v_add_f32_e32 v138, v138, v149
	v_add_f32_e32 v150, v150, v154
	v_add_f32_e32 v138, v138, v150
	s_nop 1
	v_add_f32_dpp v138, v138, v138 quad_perm:[1,0,3,2] row_mask:0xf bank_mask:0xf
	s_nop 1
	v_add_f32_dpp v138, v138, v138 quad_perm:[2,3,0,1] row_mask:0xf bank_mask:0xf
	s_nop 1
	v_add_f32_dpp v138, v138, v138 row_half_mirror row_mask:0xf bank_mask:0xf
	s_nop 1
	v_add_f32_dpp v138, v138, v138 row_mirror row_mask:0xf bank_mask:0xf
	v_mov_b32_e32 v139, v138
	s_nop 1
	v_permlane16_swap_b32_e32 v138, v139
	v_add_f32_e32 v138, v138, v139
	v_mov_b32_e32 v139, v138
	s_nop 1
	v_permlane32_swap_b32_e32 v138, v139
	v_add_f32_e32 v138, v138, v139
	v_mul_f32_e32 v138, 0x3a800000, v138
	v_add_f32_e32 v138, 0x358637bd, v138
	v_rsq_f32_e32 v140, v138
	s_nop 0
	v_mul_f32_e32 v120, v166, v140
	v_mul_f32_e32 v121, v167, v140
	v_mul_f32_e32 v122, v168, v140
	v_mul_f32_e32 v123, v169, v140
	v_mul_f32_e32 v124, v170, v140
	v_mul_f32_e32 v125, v171, v140
	v_mul_f32_e32 v126, v172, v140
	v_mul_f32_e32 v127, v173, v140
	v_mul_f32_e32 v128, v174, v140
	v_mul_f32_e32 v129, v175, v140
	v_mul_f32_e32 v130, v176, v140
	v_mul_f32_e32 v131, v177, v140
	v_mul_f32_e32 v132, v178, v140
	v_mul_f32_e32 v133, v179, v140
	v_mul_f32_e32 v134, v180, v140
	v_mul_f32_e32 v135, v181, v140
	v_fma_f32 v120, v120, v88, v104
	v_fma_f32 v121, v121, v89, v105
	v_fma_f32 v122, v122, v90, v106
	v_fma_f32 v123, v123, v91, v107
	v_fma_f32 v124, v124, v92, v108
	v_fma_f32 v125, v125, v93, v109
	v_fma_f32 v126, v126, v94, v110
	v_fma_f32 v127, v127, v95, v111
	v_fma_f32 v128, v128, v96, v112
	v_fma_f32 v129, v129, v97, v113
	v_fma_f32 v130, v130, v98, v114
	v_fma_f32 v131, v131, v99, v115
	v_fma_f32 v132, v132, v100, v116
	v_fma_f32 v133, v133, v101, v117
	v_fma_f32 v134, v134, v102, v118
	v_fma_f32 v135, v135, v103, v119
	v_cvt_pk_bf16_f32 v156, v120, v121
	v_cvt_pk_bf16_f32 v157, v122, v123
	v_cvt_pk_bf16_f32 v158, v124, v125
	v_cvt_pk_bf16_f32 v159, v126, v127
	v_cvt_pk_bf16_f32 v160, v128, v129
	v_cvt_pk_bf16_f32 v161, v130, v131
	v_cvt_pk_bf16_f32 v162, v132, v133
	v_cvt_pk_bf16_f32 v163, v134, v135
	s_lshl_b32 vcc_lo, s19, 11
	s_add_u32 vcc_lo, vcc_lo, 0x1c00000
	s_add_u32 s100, s14, vcc_lo
	s_addc_u32 s101, s15, 0
	global_store_dwordx2 v137, v[156:157], s[100:101] offset:0
	global_store_dwordx2 v137, v[158:159], s[100:101] offset:512
	global_store_dwordx2 v137, v[160:161], s[100:101] offset:1024
	global_store_dwordx2 v137, v[162:163], s[100:101] offset:1536
	s_add_u32 s100, s20, 0xc000
	s_addc_u32 s101, s21, 0
	global_load_dwordx4 v[104:107], v136, s[100:101] offset:0
	global_load_dwordx4 v[108:111], v136, s[100:101] offset:1024
	global_load_dwordx4 v[112:115], v136, s[100:101] offset:2048
	global_load_dwordx4 v[116:119], v136, s[100:101] offset:3072
	s_add_u32 s100, s100, 0x1000
	s_addc_u32 s101, s101, 0
	global_load_dwordx4 v[166:169], v136, s[100:101] offset:0
	global_load_dwordx4 v[170:173], v136, s[100:101] offset:1024
	global_load_dwordx4 v[174:177], v136, s[100:101] offset:2048
	global_load_dwordx4 v[178:181], v136, s[100:101] offset:3072
	s_load_dwordx2 s[98:99], s[4:5], 0x30
	s_waitcnt lgkmcnt(0)
	global_load_dwordx4 v[88:91], v136, s[98:99] offset:0
	global_load_dwordx4 v[92:95], v136, s[98:99] offset:1024
	global_load_dwordx4 v[96:99], v136, s[98:99] offset:2048
	global_load_dwordx4 v[100:103], v136, s[98:99] offset:3072
	s_waitcnt vmcnt(0)
	v_fma_f32 v88, v88, v166, v88
	v_fma_f32 v89, v89, v167, v89
	v_fma_f32 v90, v90, v168, v90
	v_fma_f32 v91, v91, v169, v91
	v_fma_f32 v92, v92, v170, v92
	v_fma_f32 v93, v93, v171, v93
	v_fma_f32 v94, v94, v172, v94
	v_fma_f32 v95, v95, v173, v95
	v_fma_f32 v96, v96, v174, v96
	v_fma_f32 v97, v97, v175, v97
	v_fma_f32 v98, v98, v176, v98
	v_fma_f32 v99, v99, v177, v99
	v_fma_f32 v100, v100, v178, v100
	v_fma_f32 v101, v101, v179, v101
	v_fma_f32 v102, v102, v180, v102
	v_fma_f32 v103, v103, v181, v103
	s_lshl_b32 vcc_lo, s19, 12
	s_add_u32 vcc_lo, vcc_lo, 0x5800000
	s_add_u32 s100, s12, vcc_lo
	s_addc_u32 s101, s13, 0
	global_load_dwordx4 v[166:169], v136, s[100:101] offset:0
	global_load_dwordx4 v[170:173], v136, s[100:101] offset:1024
	global_load_dwordx4 v[174:177], v136, s[100:101] offset:2048
	global_load_dwordx4 v[178:181], v136, s[100:101] offset:3072
	v_mul_f32_e32 v138, v0, v0
	v_mul_f32_e32 v149, v1, v1
	v_mul_f32_e32 v150, v2, v2
	v_mul_f32_e32 v154, v3, v3
	v_fma_f32 v138, v4, v4, v138
	v_fma_f32 v149, v5, v5, v149
	v_fma_f32 v150, v6, v6, v150
	v_fma_f32 v154, v7, v7, v154
	v_fma_f32 v138, v8, v8, v138
	v_fma_f32 v149, v9, v9, v149
	v_fma_f32 v150, v10, v10, v150
	v_fma_f32 v154, v11, v11, v154
	v_fma_f32 v138, v12, v12, v138
	v_fma_f32 v149, v13, v13, v149
	v_fma_f32 v150, v14, v14, v150
	v_fma_f32 v154, v15, v15, v154
	v_add_f32_e32 v138, v138, v149
	v_add_f32_e32 v150, v150, v154
	v_add_f32_e32 v138, v138, v150
	s_nop 1
	v_add_f32_dpp v138, v138, v138 quad_perm:[1,0,3,2] row_mask:0xf bank_mask:0xf
	s_nop 1
	v_add_f32_dpp v138, v138, v138 quad_perm:[2,3,0,1] row_mask:0xf bank_mask:0xf
	s_nop 1
	v_add_f32_dpp v138, v138, v138 row_half_mirror row_mask:0xf bank_mask:0xf
	s_nop 1
; __device__ __forceinline__ void row_phase(const Params& P, int glayer, int layer, int xsrc, bool hasY, int gate_idx, const float* gpost,
;                           int xdst, bool doH, const float* gpre, int sh_idx, int nrows) {
;     ...
;           if (xsrc == 0) xin_ = R < N_X ? P.x + (long)R * 1024 : P.ctx + (long)(R - N_X) * 1024;
;           else           xin_ = P.xc + (long)(R - N_X) * 1024;
; #pragma unroll
;           for (int i = 0; i < 4; ++i) xr[u][i] = *reinterpret_cast<const uint4*>(xin_ + (i * 64 + lane) * 4);
;     ...
;         if (doH) {
;           float ss = 0.f;
; #pragma unroll
;           for (int i = 0; i < 4; ++i) ss += xv[i].x * xv[i].x + xv[i].y * xv[i].y + xv[i].z * xv[i].z + xv[i].w * xv[i].w;
;           ss = wave_sum(ss);
;           const float rstd = __builtin_amdgcn_rsqf(ss * (1.f / 1024.f) + EPSF);
;           u16* h = P.hy + (long)row * 1024;
; #pragma unroll
;           for (int i = 0; i < 4; ++i) {
;             const int col = (i * 64 + lane) * 4;
;             const float4 g = *reinterpret_cast<const float4*>(gpre + col);
;             const float4 sh = *reinterpret_cast<const float4*>(modp + sh_idx * 1024 + col);
;             const float4 sc = *reinterpret_cast<const float4*>(modp + (sh_idx + 1) * 1024 + col);
;             const unsigned h0 = f2bf(xv[i].x * rstd * g.x * (1.f + sc.x) + sh.x);
;             const unsigned h1 = f2bf(xv[i].y * rstd * g.y * (1.f + sc.y) + sh.y);
;             const unsigned h2 = f2bf(xv[i].z * rstd * g.z * (1.f + sc.z) + sh.z);
;             const unsigned h3 = f2bf(xv[i].w * rstd * g.w * (1.f + sc.w) + sh.w);
;             *reinterpret_cast<uint2*>(h + col) = make_uint2(h0 | (h1 << 16), h2 | (h3 << 16));
;           }
	v_add_f32_dpp v138, v138, v138 row_mirror row_mask:0xf bank_mask:0xf
	v_mov_b32_e32 v139, v138
	s_nop 1
	v_permlane16_swap_b32_e32 v138, v139
	v_add_f32_e32 v138, v138, v139
	v_mov_b32_e32 v139, v138
	s_nop 1
	v_permlane32_swap_b32_e32 v138, v139
	v_add_f32_e32 v138, v138, v139
	v_mul_f32_e32 v138, 0x3a800000, v138
	v_add_f32_e32 v138, 0x358637bd, v138
	v_rsq_f32_e32 v140, v138
	s_nop 0
	v_mul_f32_e32 v120, v0, v140
	v_mul_f32_e32 v121, v1, v140
	v_mul_f32_e32 v122, v2, v140
	v_mul_f32_e32 v123, v3, v140
	v_mul_f32_e32 v124, v4, v140
	v_mul_f32_e32 v125, v5, v140
	v_mul_f32_e32 v126, v6, v140
	v_mul_f32_e32 v127, v7, v140
	v_mul_f32_e32 v128, v8, v140
	v_mul_f32_e32 v129, v9, v140
	v_mul_f32_e32 v130, v10, v140
	v_mul_f32_e32 v131, v11, v140
	v_mul_f32_e32 v132, v12, v140
	v_mul_f32_e32 v133, v13, v140
	v_mul_f32_e32 v134, v14, v140
	v_mul_f32_e32 v135, v15, v140
	v_fma_f32 v120, v120, v88, v104
	v_fma_f32 v121, v121, v89, v105
	v_fma_f32 v122, v122, v90, v106
	v_fma_f32 v123, v123, v91, v107
	v_fma_f32 v124, v124, v92, v108
	v_fma_f32 v125, v125, v93, v109
	v_fma_f32 v126, v126, v94, v110
	v_fma_f32 v127, v127, v95, v111
	v_fma_f32 v128, v128, v96, v112
	v_fma_f32 v129, v129, v97, v113
	v_fma_f32 v130, v130, v98, v114
	v_fma_f32 v131, v131, v99, v115
	v_fma_f32 v132, v132, v100, v116
	v_fma_f32 v133, v133, v101, v117
	v_fma_f32 v134, v134, v102, v118
	v_fma_f32 v135, v135, v103, v119
	v_cvt_pk_bf16_f32 v156, v120, v121
	v_cvt_pk_bf16_f32 v157, v122, v123
	v_cvt_pk_bf16_f32 v158, v124, v125
	v_cvt_pk_bf16_f32 v159, v126, v127
	v_cvt_pk_bf16_f32 v160, v128, v129
	v_cvt_pk_bf16_f32 v161, v130, v131
	v_cvt_pk_bf16_f32 v162, v132, v133
	v_cvt_pk_bf16_f32 v163, v134, v135
	s_lshl_b32 vcc_lo, s19, 11
	s_add_u32 vcc_lo, vcc_lo, 0x2000000
	s_add_u32 s100, s14, vcc_lo
	s_addc_u32 s101, s15, 0
	global_store_dwordx2 v137, v[156:157], s[100:101] offset:0
	global_store_dwordx2 v137, v[158:159], s[100:101] offset:512
	global_store_dwordx2 v137, v[160:161], s[100:101] offset:1024
	global_store_dwordx2 v137, v[162:163], s[100:101] offset:1536
	s_lshl_b32 vcc_lo, s19, 12
	s_add_u32 vcc_lo, vcc_lo, 0x6000000
	s_add_u32 s100, s12, vcc_lo
	s_addc_u32 s101, s13, 0
	global_load_dwordx4 v[0:3], v136, s[100:101] offset:0
	global_load_dwordx4 v[4:7], v136, s[100:101] offset:1024
	global_load_dwordx4 v[8:11], v136, s[100:101] offset:2048
	global_load_dwordx4 v[12:15], v136, s[100:101] offset:3072
	v_mul_f32_e32 v138, v16, v16
	v_mul_f32_e32 v149, v17, v17
	v_mul_f32_e32 v150, v18, v18
	v_mul_f32_e32 v154, v19, v19
	v_fma_f32 v138, v20, v20, v138
	v_fma_f32 v149, v21, v21, v149
	v_fma_f32 v150, v22, v22, v150
	v_fma_f32 v154, v23, v23, v154
	v_fma_f32 v138, v24, v24, v138
	v_fma_f32 v149, v25, v25, v149
	v_fma_f32 v150, v26, v26, v150
	v_fma_f32 v154, v27, v27, v154
	v_fma_f32 v138, v28, v28, v138
	v_fma_f32 v149, v29, v29, v149
	v_fma_f32 v150, v30, v30, v150
	v_fma_f32 v154, v31, v31, v154
	v_add_f32_e32 v138, v138, v149
	v_add_f32_e32 v150, v150, v154
	v_add_f32_e32 v138, v138, v150
	s_nop 1
	v_add_f32_dpp v138, v138, v138 quad_perm:[1,0,3,2] row_mask:0xf bank_mask:0xf
	s_nop 1
	v_add_f32_dpp v138, v138, v138 quad_perm:[2,3,0,1] row_mask:0xf bank_mask:0xf
	s_nop 1
	v_add_f32_dpp v138, v138, v138 row_half_mirror row_mask:0xf bank_mask:0xf
	s_nop 1
	v_add_f32_dpp v138, v138, v138 row_mirror row_mask:0xf bank_mask:0xf
	v_mov_b32_e32 v139, v138
	s_nop 1
	v_permlane16_swap_b32_e32 v138, v139
	v_add_f32_e32 v138, v138, v139
	v_mov_b32_e32 v139, v138
	s_nop 1
	v_permlane32_swap_b32_e32 v138, v139
	v_add_f32_e32 v138, v138, v139
	v_mul_f32_e32 v138, 0x3a800000, v138
	v_add_f32_e32 v138, 0x358637bd, v138
	v_rsq_f32_e32 v140, v138
	s_nop 0
	v_mul_f32_e32 v120, v16, v140
	v_mul_f32_e32 v121, v17, v140
	v_mul_f32_e32 v122, v18, v140
	v_mul_f32_e32 v123, v19, v140
	v_mul_f32_e32 v124, v20, v140
	v_mul_f32_e32 v125, v21, v140
	v_mul_f32_e32 v126, v22, v140
	v_mul_f32_e32 v127, v23, v140
	v_mul_f32_e32 v128, v24, v140
	v_mul_f32_e32 v129, v25, v140
	v_mul_f32_e32 v130, v26, v140
	v_mul_f32_e32 v131, v27, v140
	v_mul_f32_e32 v132, v28, v140
	v_mul_f32_e32 v133, v29, v140
	v_mul_f32_e32 v134, v30, v140
	v_mul_f32_e32 v135, v31, v140
	v_fma_f32 v120, v120, v88, v104
	v_fma_f32 v121, v121, v89, v105
	v_fma_f32 v122, v122, v90, v106
	v_fma_f32 v123, v123, v91, v107
	v_fma_f32 v124, v124, v92, v108
	v_fma_f32 v125, v125, v93, v109
	v_fma_f32 v126, v126, v94, v110
	v_fma_f32 v127, v127, v95, v111
	v_fma_f32 v128, v128, v96, v112
	v_fma_f32 v129, v129, v97, v113
	v_fma_f32 v130, v130, v98, v114
	v_fma_f32 v131, v131, v99, v115
	v_fma_f32 v132, v132, v100, v116
	v_fma_f32 v133, v133, v101, v117
	v_fma_f32 v134, v134, v102, v118
	v_fma_f32 v135, v135, v103, v119
	v_cvt_pk_bf16_f32 v156, v120, v121
	v_cvt_pk_bf16_f32 v157, v122, v123
	v_cvt_pk_bf16_f32 v158, v124, v125
	v_cvt_pk_bf16_f32 v159, v126, v127
	v_cvt_pk_bf16_f32 v160, v128, v129
	v_cvt_pk_bf16_f32 v161, v130, v131
	v_cvt_pk_bf16_f32 v162, v132, v133
	v_cvt_pk_bf16_f32 v163, v134, v135
	s_lshl_b32 vcc_lo, s19, 11
	s_add_u32 vcc_lo, vcc_lo, 0x2400000
	s_add_u32 s100, s14, vcc_lo
	s_addc_u32 s101, s15, 0
	global_store_dwordx2 v137, v[156:157], s[100:101] offset:0
	global_store_dwordx2 v137, v[158:159], s[100:101] offset:512
	global_store_dwordx2 v137, v[160:161], s[100:101] offset:1024
	global_store_dwordx2 v137, v[162:163], s[100:101] offset:1536
	s_lshl_b32 vcc_lo, s19, 12
	s_add_u32 vcc_lo, vcc_lo, 0x6800000
	s_add_u32 s100, s12, vcc_lo
	s_addc_u32 s101, s13, 0
	global_load_dwordx4 v[16:19], v136, s[100:101] offset:0
	global_load_dwordx4 v[20:23], v136, s[100:101] offset:1024
	global_load_dwordx4 v[24:27], v136, s[100:101] offset:2048
; __device__ __forceinline__ void row_phase(const Params& P, int glayer, int layer, int xsrc, bool hasY, int gate_idx, const float* gpost,
;                           int xdst, bool doH, const float* gpre, int sh_idx, int nrows) {
;     ...
;           if (xsrc == 0) xin_ = R < N_X ? P.x + (long)R * 1024 : P.ctx + (long)(R - N_X) * 1024;
;           else           xin_ = P.xc + (long)(R - N_X) * 1024;
; #pragma unroll
;           for (int i = 0; i < 4; ++i) xr[u][i] = *reinterpret_cast<const uint4*>(xin_ + (i * 64 + lane) * 4);
;     ...
;         if (doH) {
;           float ss = 0.f;
; #pragma unroll
;           for (int i = 0; i < 4; ++i) ss += xv[i].x * xv[i].x + xv[i].y * xv[i].y + xv[i].z * xv[i].z + xv[i].w * xv[i].w;
;           ss = wave_sum(ss);
;           const float rstd = __builtin_amdgcn_rsqf(ss * (1.f / 1024.f) + EPSF);
;           u16* h = P.hy + (long)row * 1024;
; #pragma unroll
;           for (int i = 0; i < 4; ++i) {
;             const int col = (i * 64 + lane) * 4;
;             const float4 g = *reinterpret_cast<const float4*>(gpre + col);
;             const float4 sh = *reinterpret_cast<const float4*>(modp + sh_idx * 1024 + col);
;             const float4 sc = *reinterpret_cast<const float4*>(modp + (sh_idx + 1) * 1024 + col);
;             const unsigned h0 = f2bf(xv[i].x * rstd * g.x * (1.f + sc.x) + sh.x);
;             const unsigned h1 = f2bf(xv[i].y * rstd * g.y * (1.f + sc.y) + sh.y);
;             const unsigned h2 = f2bf(xv[i].z * rstd * g.z * (1.f + sc.z) + sh.z);
;             const unsigned h3 = f2bf(xv[i].w * rstd * g.w * (1.f + sc.w) + sh.w);
;             *reinterpret_cast<uint2*>(h + col) = make_uint2(h0 | (h1 << 16), h2 | (h3 << 16));
;           }
	global_load_dwordx4 v[28:31], v136, s[100:101] offset:3072
	v_mul_f32_e32 v138, v32, v32
	v_mul_f32_e32 v149, v33, v33
	v_mul_f32_e32 v150, v34, v34
	v_mul_f32_e32 v154, v35, v35
	v_fma_f32 v138, v36, v36, v138
	v_fma_f32 v149, v37, v37, v149
	v_fma_f32 v150, v38, v38, v150
	v_fma_f32 v154, v39, v39, v154
	v_fma_f32 v138, v40, v40, v138
	v_fma_f32 v149, v41, v41, v149
	v_fma_f32 v150, v42, v42, v150
	v_fma_f32 v154, v43, v43, v154
	v_fma_f32 v138, v44, v44, v138
	v_fma_f32 v149, v45, v45, v149
	v_fma_f32 v150, v46, v46, v150
	v_fma_f32 v154, v47, v47, v154
	v_add_f32_e32 v138, v138, v149
	v_add_f32_e32 v150, v150, v154
	v_add_f32_e32 v138, v138, v150
	s_nop 1
	v_add_f32_dpp v138, v138, v138 quad_perm:[1,0,3,2] row_mask:0xf bank_mask:0xf
	s_nop 1
	v_add_f32_dpp v138, v138, v138 quad_perm:[2,3,0,1] row_mask:0xf bank_mask:0xf
	s_nop 1
	v_add_f32_dpp v138, v138, v138 row_half_mirror row_mask:0xf bank_mask:0xf
	s_nop 1
	v_add_f32_dpp v138, v138, v138 row_mirror row_mask:0xf bank_mask:0xf
	v_mov_b32_e32 v139, v138
	s_nop 1
	v_permlane16_swap_b32_e32 v138, v139
	v_add_f32_e32 v138, v138, v139
	v_mov_b32_e32 v139, v138
	s_nop 1
	v_permlane32_swap_b32_e32 v138, v139
	v_add_f32_e32 v138, v138, v139
	v_mul_f32_e32 v138, 0x3a800000, v138
	v_add_f32_e32 v138, 0x358637bd, v138
	v_rsq_f32_e32 v140, v138
	s_nop 0
	v_mul_f32_e32 v120, v32, v140
	v_mul_f32_e32 v121, v33, v140
	v_mul_f32_e32 v122, v34, v140
	v_mul_f32_e32 v123, v35, v140
	v_mul_f32_e32 v124, v36, v140
	v_mul_f32_e32 v125, v37, v140
	v_mul_f32_e32 v126, v38, v140
	v_mul_f32_e32 v127, v39, v140
	v_mul_f32_e32 v128, v40, v140
	v_mul_f32_e32 v129, v41, v140
	v_mul_f32_e32 v130, v42, v140
	v_mul_f32_e32 v131, v43, v140
	v_mul_f32_e32 v132, v44, v140
	v_mul_f32_e32 v133, v45, v140
	v_mul_f32_e32 v134, v46, v140
	v_mul_f32_e32 v135, v47, v140
	v_fma_f32 v120, v120, v88, v104
	v_fma_f32 v121, v121, v89, v105
	v_fma_f32 v122, v122, v90, v106
	v_fma_f32 v123, v123, v91, v107
	v_fma_f32 v124, v124, v92, v108
	v_fma_f32 v125, v125, v93, v109
	v_fma_f32 v126, v126, v94, v110
	v_fma_f32 v127, v127, v95, v111
	v_fma_f32 v128, v128, v96, v112
	v_fma_f32 v129, v129, v97, v113
	v_fma_f32 v130, v130, v98, v114
	v_fma_f32 v131, v131, v99, v115
	v_fma_f32 v132, v132, v100, v116
	v_fma_f32 v133, v133, v101, v117
	v_fma_f32 v134, v134, v102, v118
	v_fma_f32 v135, v135, v103, v119
	v_cvt_pk_bf16_f32 v156, v120, v121
	v_cvt_pk_bf16_f32 v157, v122, v123
	v_cvt_pk_bf16_f32 v158, v124, v125
	v_cvt_pk_bf16_f32 v159, v126, v127
	v_cvt_pk_bf16_f32 v160, v128, v129
	v_cvt_pk_bf16_f32 v161, v130, v131
	v_cvt_pk_bf16_f32 v162, v132, v133
	v_cvt_pk_bf16_f32 v163, v134, v135
	s_lshl_b32 vcc_lo, s19, 11
	s_add_u32 vcc_lo, vcc_lo, 0x2800000
	s_add_u32 s100, s14, vcc_lo
	s_addc_u32 s101, s15, 0
	global_store_dwordx2 v137, v[156:157], s[100:101] offset:0
	global_store_dwordx2 v137, v[158:159], s[100:101] offset:512
	global_store_dwordx2 v137, v[160:161], s[100:101] offset:1024
	global_store_dwordx2 v137, v[162:163], s[100:101] offset:1536
	s_lshl_b32 vcc_lo, s19, 12
	s_add_u32 vcc_lo, vcc_lo, 0x7000000
	s_add_u32 s100, s12, vcc_lo
	s_addc_u32 s101, s13, 0
	global_load_dwordx4 v[32:35], v136, s[100:101] offset:0
	global_load_dwordx4 v[36:39], v136, s[100:101] offset:1024
	global_load_dwordx4 v[40:43], v136, s[100:101] offset:2048
	global_load_dwordx4 v[44:47], v136, s[100:101] offset:3072
	s_waitcnt vmcnt(24)
	v_mul_f32_e32 v138, v166, v166
	v_mul_f32_e32 v149, v167, v167
	v_mul_f32_e32 v150, v168, v168
	v_mul_f32_e32 v154, v169, v169
	v_fma_f32 v138, v170, v170, v138
	v_fma_f32 v149, v171, v171, v149
	v_fma_f32 v150, v172, v172, v150
	v_fma_f32 v154, v173, v173, v154
	v_fma_f32 v138, v174, v174, v138
	v_fma_f32 v149, v175, v175, v149
	v_fma_f32 v150, v176, v176, v150
	v_fma_f32 v154, v177, v177, v154
	v_fma_f32 v138, v178, v178, v138
	v_fma_f32 v149, v179, v179, v149
	v_fma_f32 v150, v180, v180, v150
	v_fma_f32 v154, v181, v181, v154
	v_add_f32_e32 v138, v138, v149
	v_add_f32_e32 v150, v150, v154
	v_add_f32_e32 v138, v138, v150
	s_nop 1
	v_add_f32_dpp v138, v138, v138 quad_perm:[1,0,3,2] row_mask:0xf bank_mask:0xf
	s_nop 1
	v_add_f32_dpp v138, v138, v138 quad_perm:[2,3,0,1] row_mask:0xf bank_mask:0xf
	s_nop 1
	v_add_f32_dpp v138, v138, v138 row_half_mirror row_mask:0xf bank_mask:0xf
	s_nop 1
	v_add_f32_dpp v138, v138, v138 row_mirror row_mask:0xf bank_mask:0xf
	v_mov_b32_e32 v139, v138
	s_nop 1
	v_permlane16_swap_b32_e32 v138, v139
	v_add_f32_e32 v138, v138, v139
	v_mov_b32_e32 v139, v138
	s_nop 1
	v_permlane32_swap_b32_e32 v138, v139
	v_add_f32_e32 v138, v138, v139
	v_mul_f32_e32 v138, 0x3a800000, v138
	v_add_f32_e32 v138, 0x358637bd, v138
	v_rsq_f32_e32 v140, v138
	s_nop 0
	v_mul_f32_e32 v120, v166, v140
	v_mul_f32_e32 v121, v167, v140
	v_mul_f32_e32 v122, v168, v140
	v_mul_f32_e32 v123, v169, v140
	v_mul_f32_e32 v124, v170, v140
	v_mul_f32_e32 v125, v171, v140
	v_mul_f32_e32 v126, v172, v140
	v_mul_f32_e32 v127, v173, v140
	v_mul_f32_e32 v128, v174, v140
	v_mul_f32_e32 v129, v175, v140
	v_mul_f32_e32 v130, v176, v140
	v_mul_f32_e32 v131, v177, v140
	v_mul_f32_e32 v132, v178, v140
	v_mul_f32_e32 v133, v179, v140
	v_mul_f32_e32 v134, v180, v140
	v_mul_f32_e32 v135, v181, v140
	v_fma_f32 v120, v120, v88, v104
	v_fma_f32 v121, v121, v89, v105
	v_fma_f32 v122, v122, v90, v106
	v_fma_f32 v123, v123, v91, v107
	v_fma_f32 v124, v124, v92, v108
	v_fma_f32 v125, v125, v93, v109
	v_fma_f32 v126, v126, v94, v110
	v_fma_f32 v127, v127, v95, v111
	v_fma_f32 v128, v128, v96, v112
	v_fma_f32 v129, v129, v97, v113
	v_fma_f32 v130, v130, v98, v114
	v_fma_f32 v131, v131, v99, v115
	v_fma_f32 v132, v132, v100, v116
	v_fma_f32 v133, v133, v101, v117
	v_fma_f32 v134, v134, v102, v118
	v_fma_f32 v135, v135, v103, v119
	v_cvt_pk_bf16_f32 v156, v120, v121
	v_cvt_pk_bf16_f32 v157, v122, v123
	v_cvt_pk_bf16_f32 v158, v124, v125
	v_cvt_pk_bf16_f32 v159, v126, v127
	v_cvt_pk_bf16_f32 v160, v128, v129
	v_cvt_pk_bf16_f32 v161, v130, v131
	v_cvt_pk_bf16_f32 v162, v132, v133
	v_cvt_pk_bf16_f32 v163, v134, v135
	s_lshl_b32 vcc_lo, s19, 11
	s_add_u32 vcc_lo, vcc_lo, 0x2c00000
	s_add_u32 s100, s14, vcc_lo
	s_addc_u32 s101, s15, 0
	global_store_dwordx2 v137, v[156:157], s[100:101] offset:0
	global_store_dwordx2 v137, v[158:159], s[100:101] offset:512
	global_store_dwordx2 v137, v[160:161], s[100:101] offset:1024
	global_store_dwordx2 v137, v[162:163], s[100:101] offset:1536
	s_add_u32 s100, s20, 0x12000
	s_addc_u32 s101, s21, 0
	global_load_dwordx4 v[104:107], v136, s[100:101] offset:0
	global_load_dwordx4 v[108:111], v136, s[100:101] offset:1024
	global_load_dwordx4 v[112:115], v136, s[100:101] offset:2048
	global_load_dwordx4 v[116:119], v136, s[100:101] offset:3072
	s_add_u32 s100, s100, 0x1000
	s_addc_u32 s101, s101, 0
	global_load_dwordx4 v[166:169], v136, s[100:101] offset:0
	global_load_dwordx4 v[170:173], v136, s[100:101] offset:1024
	global_load_dwordx4 v[174:177], v136, s[100:101] offset:2048
	global_load_dwordx4 v[178:181], v136, s[100:101] offset:3072
	s_load_dwordx2 s[98:99], s[4:5], 0x30
	s_waitcnt lgkmcnt(0)
; __device__ __forceinline__ void row_phase(const Params& P, int glayer, int layer, int xsrc, bool hasY, int gate_idx, const float* gpost,
;                           int xdst, bool doH, const float* gpre, int sh_idx, int nrows) {
;     ...
;           if (xsrc == 0) xin_ = R < N_X ? P.x + (long)R * 1024 : P.ctx + (long)(R - N_X) * 1024;
;           else           xin_ = P.xc + (long)(R - N_X) * 1024;
; #pragma unroll
;           for (int i = 0; i < 4; ++i) xr[u][i] = *reinterpret_cast<const uint4*>(xin_ + (i * 64 + lane) * 4);
;     ...
;         if (doH) {
;           float ss = 0.f;
; #pragma unroll
;           for (int i = 0; i < 4; ++i) ss += xv[i].x * xv[i].x + xv[i].y * xv[i].y + xv[i].z * xv[i].z + xv[i].w * xv[i].w;
;           ss = wave_sum(ss);
;           const float rstd = __builtin_amdgcn_rsqf(ss * (1.f / 1024.f) + EPSF);
;           u16* h = P.hy + (long)row * 1024;
; #pragma unroll
;           for (int i = 0; i < 4; ++i) {
;             const int col = (i * 64 + lane) * 4;
;             const float4 g = *reinterpret_cast<const float4*>(gpre + col);
;             const float4 sh = *reinterpret_cast<const float4*>(modp + sh_idx * 1024 + col);
;             const float4 sc = *reinterpret_cast<const float4*>(modp + (sh_idx + 1) * 1024 + col);
;             const unsigned h0 = f2bf(xv[i].x * rstd * g.x * (1.f + sc.x) + sh.x);
;             const unsigned h1 = f2bf(xv[i].y * rstd * g.y * (1.f + sc.y) + sh.y);
;             const unsigned h2 = f2bf(xv[i].z * rstd * g.z * (1.f + sc.z) + sh.z);
;             const unsigned h3 = f2bf(xv[i].w * rstd * g.w * (1.f + sc.w) + sh.w);
;             *reinterpret_cast<uint2*>(h + col) = make_uint2(h0 | (h1 << 16), h2 | (h3 << 16));
;           }
	global_load_dwordx4 v[88:91], v136, s[98:99] offset:0
	global_load_dwordx4 v[92:95], v136, s[98:99] offset:1024
	global_load_dwordx4 v[96:99], v136, s[98:99] offset:2048
	global_load_dwordx4 v[100:103], v136, s[98:99] offset:3072
	s_waitcnt vmcnt(0)
	v_fma_f32 v88, v88, v166, v88
	v_fma_f32 v89, v89, v167, v89
	v_fma_f32 v90, v90, v168, v90
	v_fma_f32 v91, v91, v169, v91
	v_fma_f32 v92, v92, v170, v92
	v_fma_f32 v93, v93, v171, v93
	v_fma_f32 v94, v94, v172, v94
	v_fma_f32 v95, v95, v173, v95
	v_fma_f32 v96, v96, v174, v96
	v_fma_f32 v97, v97, v175, v97
	v_fma_f32 v98, v98, v176, v98
	v_fma_f32 v99, v99, v177, v99
	v_fma_f32 v100, v100, v178, v100
	v_fma_f32 v101, v101, v179, v101
	v_fma_f32 v102, v102, v180, v102
	v_fma_f32 v103, v103, v181, v103
	s_lshl_b32 vcc_lo, s19, 12
	s_add_u32 vcc_lo, vcc_lo, 0x7800000
	s_add_u32 s100, s12, vcc_lo
	s_addc_u32 s101, s13, 0
	global_load_dwordx4 v[166:169], v136, s[100:101] offset:0
	global_load_dwordx4 v[170:173], v136, s[100:101] offset:1024
	global_load_dwordx4 v[174:177], v136, s[100:101] offset:2048
	global_load_dwordx4 v[178:181], v136, s[100:101] offset:3072
	v_mul_f32_e32 v138, v0, v0
	v_mul_f32_e32 v149, v1, v1
	v_mul_f32_e32 v150, v2, v2
	v_mul_f32_e32 v154, v3, v3
	v_fma_f32 v138, v4, v4, v138
	v_fma_f32 v149, v5, v5, v149
	v_fma_f32 v150, v6, v6, v150
	v_fma_f32 v154, v7, v7, v154
	v_fma_f32 v138, v8, v8, v138
	v_fma_f32 v149, v9, v9, v149
	v_fma_f32 v150, v10, v10, v150
	v_fma_f32 v154, v11, v11, v154
	v_fma_f32 v138, v12, v12, v138
	v_fma_f32 v149, v13, v13, v149
	v_fma_f32 v150, v14, v14, v150
	v_fma_f32 v154, v15, v15, v154
	v_add_f32_e32 v138, v138, v149
	v_add_f32_e32 v150, v150, v154
	v_add_f32_e32 v138, v138, v150
	s_nop 1
	v_add_f32_dpp v138, v138, v138 quad_perm:[1,0,3,2] row_mask:0xf bank_mask:0xf
	s_nop 1
	v_add_f32_dpp v138, v138, v138 quad_perm:[2,3,0,1] row_mask:0xf bank_mask:0xf
	s_nop 1
	v_add_f32_dpp v138, v138, v138 row_half_mirror row_mask:0xf bank_mask:0xf
	s_nop 1
	v_add_f32_dpp v138, v138, v138 row_mirror row_mask:0xf bank_mask:0xf
	v_mov_b32_e32 v139, v138
	s_nop 1
	v_permlane16_swap_b32_e32 v138, v139
	v_add_f32_e32 v138, v138, v139
	v_mov_b32_e32 v139, v138
	s_nop 1
	v_permlane32_swap_b32_e32 v138, v139
	v_add_f32_e32 v138, v138, v139
	v_mul_f32_e32 v138, 0x3a800000, v138
	v_add_f32_e32 v138, 0x358637bd, v138
	v_rsq_f32_e32 v140, v138
	s_nop 0
	v_mul_f32_e32 v120, v0, v140
	v_mul_f32_e32 v121, v1, v140
	v_mul_f32_e32 v122, v2, v140
	v_mul_f32_e32 v123, v3, v140
	v_mul_f32_e32 v124, v4, v140
	v_mul_f32_e32 v125, v5, v140
	v_mul_f32_e32 v126, v6, v140
	v_mul_f32_e32 v127, v7, v140
	v_mul_f32_e32 v128, v8, v140
	v_mul_f32_e32 v129, v9, v140
	v_mul_f32_e32 v130, v10, v140
	v_mul_f32_e32 v131, v11, v140
	v_mul_f32_e32 v132, v12, v140
	v_mul_f32_e32 v133, v13, v140
	v_mul_f32_e32 v134, v14, v140
	v_mul_f32_e32 v135, v15, v140
	v_fma_f32 v120, v120, v88, v104
	v_fma_f32 v121, v121, v89, v105
	v_fma_f32 v122, v122, v90, v106
	v_fma_f32 v123, v123, v91, v107
	v_fma_f32 v124, v124, v92, v108
	v_fma_f32 v125, v125, v93, v109
	v_fma_f32 v126, v126, v94, v110
	v_fma_f32 v127, v127, v95, v111
	v_fma_f32 v128, v128, v96, v112
	v_fma_f32 v129, v129, v97, v113
	v_fma_f32 v130, v130, v98, v114
	v_fma_f32 v131, v131, v99, v115
	v_fma_f32 v132, v132, v100, v116
	v_fma_f32 v133, v133, v101, v117
	v_fma_f32 v134, v134, v102, v118
	v_fma_f32 v135, v135, v103, v119
	v_cvt_pk_bf16_f32 v156, v120, v121
	v_cvt_pk_bf16_f32 v157, v122, v123
	v_cvt_pk_bf16_f32 v158, v124, v125
	v_cvt_pk_bf16_f32 v159, v126, v127
	v_cvt_pk_bf16_f32 v160, v128, v129
	v_cvt_pk_bf16_f32 v161, v130, v131
	v_cvt_pk_bf16_f32 v162, v132, v133
	v_cvt_pk_bf16_f32 v163, v134, v135
	s_lshl_b32 vcc_lo, s19, 11
	s_add_u32 vcc_lo, vcc_lo, 0x3000000
	s_add_u32 s100, s14, vcc_lo
	s_addc_u32 s101, s15, 0
	global_store_dwordx2 v137, v[156:157], s[100:101] offset:0
	global_store_dwordx2 v137, v[158:159], s[100:101] offset:512
	global_store_dwordx2 v137, v[160:161], s[100:101] offset:1024
	global_store_dwordx2 v137, v[162:163], s[100:101] offset:1536
	v_mul_f32_e32 v138, v16, v16
	v_mul_f32_e32 v149, v17, v17
	v_mul_f32_e32 v150, v18, v18
	v_mul_f32_e32 v154, v19, v19
	v_fma_f32 v138, v20, v20, v138
	v_fma_f32 v149, v21, v21, v149
	v_fma_f32 v150, v22, v22, v150
	v_fma_f32 v154, v23, v23, v154
	v_fma_f32 v138, v24, v24, v138
	v_fma_f32 v149, v25, v25, v149
	v_fma_f32 v150, v26, v26, v150
	v_fma_f32 v154, v27, v27, v154
	v_fma_f32 v138, v28, v28, v138
	v_fma_f32 v149, v29, v29, v149
	v_fma_f32 v150, v30, v30, v150
	v_fma_f32 v154, v31, v31, v154
	v_add_f32_e32 v138, v138, v149
	v_add_f32_e32 v150, v150, v154
	v_add_f32_e32 v138, v138, v150
	s_nop 1
	v_add_f32_dpp v138, v138, v138 quad_perm:[1,0,3,2] row_mask:0xf bank_mask:0xf
	s_nop 1
	v_add_f32_dpp v138, v138, v138 quad_perm:[2,3,0,1] row_mask:0xf bank_mask:0xf
	s_nop 1
	v_add_f32_dpp v138, v138, v138 row_half_mirror row_mask:0xf bank_mask:0xf
	s_nop 1
	v_add_f32_dpp v138, v138, v138 row_mirror row_mask:0xf bank_mask:0xf
	v_mov_b32_e32 v139, v138
	s_nop 1
	v_permlane16_swap_b32_e32 v138, v139
	v_add_f32_e32 v138, v138, v139
	v_mov_b32_e32 v139, v138
	s_nop 1
	v_permlane32_swap_b32_e32 v138, v139
	v_add_f32_e32 v138, v138, v139
	v_mul_f32_e32 v138, 0x3a800000, v138
	v_add_f32_e32 v138, 0x358637bd, v138
	v_rsq_f32_e32 v140, v138
	s_nop 0
	v_mul_f32_e32 v120, v16, v140
	v_mul_f32_e32 v121, v17, v140
	v_mul_f32_e32 v122, v18, v140
	v_mul_f32_e32 v123, v19, v140
	v_mul_f32_e32 v124, v20, v140
	v_mul_f32_e32 v125, v21, v140
	v_mul_f32_e32 v126, v22, v140
	v_mul_f32_e32 v127, v23, v140
	v_mul_f32_e32 v128, v24, v140
	v_mul_f32_e32 v129, v25, v140
	v_mul_f32_e32 v130, v26, v140
; __device__ __forceinline__ void row_phase(const Params& P, int glayer, int layer, int xsrc, bool hasY, int gate_idx, const float* gpost,
;                           int xdst, bool doH, const float* gpre, int sh_idx, int nrows) {
;     ...
;         if (doH) {
;           float ss = 0.f;
; #pragma unroll
;           for (int i = 0; i < 4; ++i) ss += xv[i].x * xv[i].x + xv[i].y * xv[i].y + xv[i].z * xv[i].z + xv[i].w * xv[i].w;
;           ss = wave_sum(ss);
;           const float rstd = __builtin_amdgcn_rsqf(ss * (1.f / 1024.f) + EPSF);
;           u16* h = P.hy + (long)row * 1024;
; #pragma unroll
;           for (int i = 0; i < 4; ++i) {
;             const int col = (i * 64 + lane) * 4;
;             const float4 g = *reinterpret_cast<const float4*>(gpre + col);
;             const float4 sh = *reinterpret_cast<const float4*>(modp + sh_idx * 1024 + col);
;             const float4 sc = *reinterpret_cast<const float4*>(modp + (sh_idx + 1) * 1024 + col);
;             const unsigned h0 = f2bf(xv[i].x * rstd * g.x * (1.f + sc.x) + sh.x);
;             const unsigned h1 = f2bf(xv[i].y * rstd * g.y * (1.f + sc.y) + sh.y);
;             const unsigned h2 = f2bf(xv[i].z * rstd * g.z * (1.f + sc.z) + sh.z);
;             const unsigned h3 = f2bf(xv[i].w * rstd * g.w * (1.f + sc.w) + sh.w);
;             *reinterpret_cast<uint2*>(h + col) = make_uint2(h0 | (h1 << 16), h2 | (h3 << 16));
;           }
	v_mul_f32_e32 v131, v27, v140
	v_mul_f32_e32 v132, v28, v140
	v_mul_f32_e32 v133, v29, v140
	v_mul_f32_e32 v134, v30, v140
	v_mul_f32_e32 v135, v31, v140
	v_fma_f32 v120, v120, v88, v104
	v_fma_f32 v121, v121, v89, v105
	v_fma_f32 v122, v122, v90, v106
	v_fma_f32 v123, v123, v91, v107
	v_fma_f32 v124, v124, v92, v108
	v_fma_f32 v125, v125, v93, v109
	v_fma_f32 v126, v126, v94, v110
	v_fma_f32 v127, v127, v95, v111
	v_fma_f32 v128, v128, v96, v112
	v_fma_f32 v129, v129, v97, v113
	v_fma_f32 v130, v130, v98, v114
	v_fma_f32 v131, v131, v99, v115
	v_fma_f32 v132, v132, v100, v116
	v_fma_f32 v133, v133, v101, v117
	v_fma_f32 v134, v134, v102, v118
	v_fma_f32 v135, v135, v103, v119
	v_cvt_pk_bf16_f32 v156, v120, v121
	v_cvt_pk_bf16_f32 v157, v122, v123
	v_cvt_pk_bf16_f32 v158, v124, v125
	v_cvt_pk_bf16_f32 v159, v126, v127
	v_cvt_pk_bf16_f32 v160, v128, v129
	v_cvt_pk_bf16_f32 v161, v130, v131
	v_cvt_pk_bf16_f32 v162, v132, v133
	v_cvt_pk_bf16_f32 v163, v134, v135
	s_lshl_b32 vcc_lo, s19, 11
	s_add_u32 vcc_lo, vcc_lo, 0x3400000
	s_add_u32 s100, s14, vcc_lo
	s_addc_u32 s101, s15, 0
	global_store_dwordx2 v137, v[156:157], s[100:101] offset:0
	global_store_dwordx2 v137, v[158:159], s[100:101] offset:512
	global_store_dwordx2 v137, v[160:161], s[100:101] offset:1024
	global_store_dwordx2 v137, v[162:163], s[100:101] offset:1536
	v_mul_f32_e32 v138, v32, v32
	v_mul_f32_e32 v149, v33, v33
	v_mul_f32_e32 v150, v34, v34
	v_mul_f32_e32 v154, v35, v35
	v_fma_f32 v138, v36, v36, v138
	v_fma_f32 v149, v37, v37, v149
	v_fma_f32 v150, v38, v38, v150
	v_fma_f32 v154, v39, v39, v154
	v_fma_f32 v138, v40, v40, v138
	v_fma_f32 v149, v41, v41, v149
	v_fma_f32 v150, v42, v42, v150
	v_fma_f32 v154, v43, v43, v154
	v_fma_f32 v138, v44, v44, v138
	v_fma_f32 v149, v45, v45, v149
	v_fma_f32 v150, v46, v46, v150
	v_fma_f32 v154, v47, v47, v154
	v_add_f32_e32 v138, v138, v149
	v_add_f32_e32 v150, v150, v154
	v_add_f32_e32 v138, v138, v150
	s_nop 1
	v_add_f32_dpp v138, v138, v138 quad_perm:[1,0,3,2] row_mask:0xf bank_mask:0xf
	s_nop 1
	v_add_f32_dpp v138, v138, v138 quad_perm:[2,3,0,1] row_mask:0xf bank_mask:0xf
	s_nop 1
	v_add_f32_dpp v138, v138, v138 row_half_mirror row_mask:0xf bank_mask:0xf
	s_nop 1
	v_add_f32_dpp v138, v138, v138 row_mirror row_mask:0xf bank_mask:0xf
	v_mov_b32_e32 v139, v138
	s_nop 1
	v_permlane16_swap_b32_e32 v138, v139
	v_add_f32_e32 v138, v138, v139
	v_mov_b32_e32 v139, v138
	s_nop 1
	v_permlane32_swap_b32_e32 v138, v139
	v_add_f32_e32 v138, v138, v139
	v_mul_f32_e32 v138, 0x3a800000, v138
	v_add_f32_e32 v138, 0x358637bd, v138
	v_rsq_f32_e32 v140, v138
	s_nop 0
	v_mul_f32_e32 v120, v32, v140
	v_mul_f32_e32 v121, v33, v140
	v_mul_f32_e32 v122, v34, v140
	v_mul_f32_e32 v123, v35, v140
	v_mul_f32_e32 v124, v36, v140
	v_mul_f32_e32 v125, v37, v140
	v_mul_f32_e32 v126, v38, v140
	v_mul_f32_e32 v127, v39, v140
	v_mul_f32_e32 v128, v40, v140
	v_mul_f32_e32 v129, v41, v140
	v_mul_f32_e32 v130, v42, v140
	v_mul_f32_e32 v131, v43, v140
	v_mul_f32_e32 v132, v44, v140
	v_mul_f32_e32 v133, v45, v140
	v_mul_f32_e32 v134, v46, v140
	v_mul_f32_e32 v135, v47, v140
	v_fma_f32 v120, v120, v88, v104
	v_fma_f32 v121, v121, v89, v105
	v_fma_f32 v122, v122, v90, v106
	v_fma_f32 v123, v123, v91, v107
	v_fma_f32 v124, v124, v92, v108
	v_fma_f32 v125, v125, v93, v109
	v_fma_f32 v126, v126, v94, v110
	v_fma_f32 v127, v127, v95, v111
	v_fma_f32 v128, v128, v96, v112
	v_fma_f32 v129, v129, v97, v113
	v_fma_f32 v130, v130, v98, v114
	v_fma_f32 v131, v131, v99, v115
	v_fma_f32 v132, v132, v100, v116
	v_fma_f32 v133, v133, v101, v117
	v_fma_f32 v134, v134, v102, v118
	v_fma_f32 v135, v135, v103, v119
	v_cvt_pk_bf16_f32 v156, v120, v121
	v_cvt_pk_bf16_f32 v157, v122, v123
	v_cvt_pk_bf16_f32 v158, v124, v125
	v_cvt_pk_bf16_f32 v159, v126, v127
	v_cvt_pk_bf16_f32 v160, v128, v129
	v_cvt_pk_bf16_f32 v161, v130, v131
	v_cvt_pk_bf16_f32 v162, v132, v133
	v_cvt_pk_bf16_f32 v163, v134, v135
	s_lshl_b32 vcc_lo, s19, 11
	s_add_u32 vcc_lo, vcc_lo, 0x3800000
	s_add_u32 s100, s14, vcc_lo
	s_addc_u32 s101, s15, 0
	global_store_dwordx2 v137, v[156:157], s[100:101] offset:0
	global_store_dwordx2 v137, v[158:159], s[100:101] offset:512
	global_store_dwordx2 v137, v[160:161], s[100:101] offset:1024
	global_store_dwordx2 v137, v[162:163], s[100:101] offset:1536
	s_waitcnt vmcnt(12)
; __device__ __forceinline__ void row_phase(const Params& P, int glayer, int layer, int xsrc, bool hasY, int gate_idx, const float* gpost,
;                           int xdst, bool doH, const float* gpre, int sh_idx, int nrows) {
;     ...
;         if (doH) {
;           float ss = 0.f;
; #pragma unroll
;           for (int i = 0; i < 4; ++i) ss += xv[i].x * xv[i].x + xv[i].y * xv[i].y + xv[i].z * xv[i].z + xv[i].w * xv[i].w;
;           ss = wave_sum(ss);
;           const float rstd = __builtin_amdgcn_rsqf(ss * (1.f / 1024.f) + EPSF);
;           u16* h = P.hy + (long)row * 1024;
; #pragma unroll
;           for (int i = 0; i < 4; ++i) {
;             const int col = (i * 64 + lane) * 4;
;             const float4 g = *reinterpret_cast<const float4*>(gpre + col);
;             const float4 sh = *reinterpret_cast<const float4*>(modp + sh_idx * 1024 + col);
;             const float4 sc = *reinterpret_cast<const float4*>(modp + (sh_idx + 1) * 1024 + col);
;             const unsigned h0 = f2bf(xv[i].x * rstd * g.x * (1.f + sc.x) + sh.x);
;             const unsigned h1 = f2bf(xv[i].y * rstd * g.y * (1.f + sc.y) + sh.y);
;             const unsigned h2 = f2bf(xv[i].z * rstd * g.z * (1.f + sc.z) + sh.z);
;             const unsigned h3 = f2bf(xv[i].w * rstd * g.w * (1.f + sc.w) + sh.w);
;             *reinterpret_cast<uint2*>(h + col) = make_uint2(h0 | (h1 << 16), h2 | (h3 << 16));
;           }
	v_mul_f32_e32 v138, v166, v166
	v_mul_f32_e32 v149, v167, v167
	v_mul_f32_e32 v150, v168, v168
	v_mul_f32_e32 v154, v169, v169
	v_fma_f32 v138, v170, v170, v138
	v_fma_f32 v149, v171, v171, v149
	v_fma_f32 v150, v172, v172, v150
	v_fma_f32 v154, v173, v173, v154
	v_fma_f32 v138, v174, v174, v138
	v_fma_f32 v149, v175, v175, v149
	v_fma_f32 v150, v176, v176, v150
	v_fma_f32 v154, v177, v177, v154
	v_fma_f32 v138, v178, v178, v138
	v_fma_f32 v149, v179, v179, v149
	v_fma_f32 v150, v180, v180, v150
	v_fma_f32 v154, v181, v181, v154
	v_add_f32_e32 v138, v138, v149
	v_add_f32_e32 v150, v150, v154
	v_add_f32_e32 v138, v138, v150
	s_nop 1
	v_add_f32_dpp v138, v138, v138 quad_perm:[1,0,3,2] row_mask:0xf bank_mask:0xf
	s_nop 1
	v_add_f32_dpp v138, v138, v138 quad_perm:[2,3,0,1] row_mask:0xf bank_mask:0xf
	s_nop 1
	v_add_f32_dpp v138, v138, v138 row_half_mirror row_mask:0xf bank_mask:0xf
	s_nop 1
	v_add_f32_dpp v138, v138, v138 row_mirror row_mask:0xf bank_mask:0xf
	v_mov_b32_e32 v139, v138
	s_nop 1
	v_permlane16_swap_b32_e32 v138, v139
	v_add_f32_e32 v138, v138, v139
	v_mov_b32_e32 v139, v138
	s_nop 1
	v_permlane32_swap_b32_e32 v138, v139
	v_add_f32_e32 v138, v138, v139
	v_mul_f32_e32 v138, 0x3a800000, v138
	v_add_f32_e32 v138, 0x358637bd, v138
	v_rsq_f32_e32 v140, v138
	s_nop 0
	v_mul_f32_e32 v120, v166, v140
	v_mul_f32_e32 v121, v167, v140
	v_mul_f32_e32 v122, v168, v140
	v_mul_f32_e32 v123, v169, v140
	v_mul_f32_e32 v124, v170, v140
	v_mul_f32_e32 v125, v171, v140
	v_mul_f32_e32 v126, v172, v140
	v_mul_f32_e32 v127, v173, v140
	v_mul_f32_e32 v128, v174, v140
	v_mul_f32_e32 v129, v175, v140
	v_mul_f32_e32 v130, v176, v140
	v_mul_f32_e32 v131, v177, v140
	v_mul_f32_e32 v132, v178, v140
	v_mul_f32_e32 v133, v179, v140
	v_mul_f32_e32 v134, v180, v140
	v_mul_f32_e32 v135, v181, v140
	v_fma_f32 v120, v120, v88, v104
	v_fma_f32 v121, v121, v89, v105
	v_fma_f32 v122, v122, v90, v106
	v_fma_f32 v123, v123, v91, v107
	v_fma_f32 v124, v124, v92, v108
	v_fma_f32 v125, v125, v93, v109
	v_fma_f32 v126, v126, v94, v110
	v_fma_f32 v127, v127, v95, v111
	v_fma_f32 v128, v128, v96, v112
	v_fma_f32 v129, v129, v97, v113
	v_fma_f32 v130, v130, v98, v114
	v_fma_f32 v131, v131, v99, v115
	v_fma_f32 v132, v132, v100, v116
	v_fma_f32 v133, v133, v101, v117
	v_fma_f32 v134, v134, v102, v118
	v_fma_f32 v135, v135, v103, v119
	v_cvt_pk_bf16_f32 v156, v120, v121
	v_cvt_pk_bf16_f32 v157, v122, v123
	v_cvt_pk_bf16_f32 v158, v124, v125
	v_cvt_pk_bf16_f32 v159, v126, v127
	v_cvt_pk_bf16_f32 v160, v128, v129
	v_cvt_pk_bf16_f32 v161, v130, v131
	v_cvt_pk_bf16_f32 v162, v132, v133
	v_cvt_pk_bf16_f32 v163, v134, v135
	s_lshl_b32 vcc_lo, s19, 11
	s_add_u32 vcc_lo, vcc_lo, 0x3c00000
	s_add_u32 s100, s14, vcc_lo
	s_addc_u32 s101, s15, 0
	global_store_dwordx2 v137, v[156:157], s[100:101] offset:0
	global_store_dwordx2 v137, v[158:159], s[100:101] offset:512
	global_store_dwordx2 v137, v[160:161], s[100:101] offset:1024
	global_store_dwordx2 v137, v[162:163], s[100:101] offset:1536
	s_waitcnt vmcnt(0)
	s_cmp_lt_u32 s19, 0x400
	s_cbranch_scc0 .Lmy_r1_done
; __device__ __forceinline__ void row_phase(const Params& P, int glayer, int layer, int xsrc, bool hasY, int gate_idx, const float* gpost,
;                           int xdst, bool doH, const float* gpre, int sh_idx, int nrows) {
;     ...
;           if (xsrc == 0) xin_ = R < N_X ? P.x + (long)R * 1024 : P.ctx + (long)(R - N_X) * 1024;
;           else           xin_ = P.xc + (long)(R - N_X) * 1024;
; #pragma unroll
;           for (int i = 0; i < 4; ++i) xr[u][i] = *reinterpret_cast<const uint4*>(xin_ + (i * 64 + lane) * 4);
;     ...
;         if (doH) {
;           float ss = 0.f;
; #pragma unroll
;           for (int i = 0; i < 4; ++i) ss += xv[i].x * xv[i].x + xv[i].y * xv[i].y + xv[i].z * xv[i].z + xv[i].w * xv[i].w;
;           ss = wave_sum(ss);
;           const float rstd = __builtin_amdgcn_rsqf(ss * (1.f / 1024.f) + EPSF);
;           u16* h = P.hy + (long)row * 1024;
; #pragma unroll
;           for (int i = 0; i < 4; ++i) {
;             const int col = (i * 64 + lane) * 4;
;             const float4 g = *reinterpret_cast<const float4*>(gpre + col);
;             const float4 sh = *reinterpret_cast<const float4*>(modp + sh_idx * 1024 + col);
;             const float4 sc = *reinterpret_cast<const float4*>(modp + (sh_idx + 1) * 1024 + col);
;             const unsigned h0 = f2bf(xv[i].x * rstd * g.x * (1.f + sc.x) + sh.x);
;             const unsigned h1 = f2bf(xv[i].y * rstd * g.y * (1.f + sc.y) + sh.y);
;             const unsigned h2 = f2bf(xv[i].z * rstd * g.z * (1.f + sc.z) + sh.z);
;             const unsigned h3 = f2bf(xv[i].w * rstd * g.w * (1.f + sc.w) + sh.w);
;             *reinterpret_cast<uint2*>(h + col) = make_uint2(h0 | (h1 << 16), h2 | (h3 << 16));
;           }
	s_load_dwordx2 s[12:13], s[4:5], 0x10
	s_waitcnt lgkmcnt(0)
	s_add_u32 s100, s20, 0x18000
	s_addc_u32 s101, s21, 0
	global_load_dwordx4 v[104:107], v136, s[100:101] offset:0
	global_load_dwordx4 v[108:111], v136, s[100:101] offset:1024
	global_load_dwordx4 v[112:115], v136, s[100:101] offset:2048
	global_load_dwordx4 v[116:119], v136, s[100:101] offset:3072
	s_add_u32 s100, s100, 0x1000
	s_addc_u32 s101, s101, 0
	global_load_dwordx4 v[16:19], v136, s[100:101] offset:0
	global_load_dwordx4 v[20:23], v136, s[100:101] offset:1024
	global_load_dwordx4 v[24:27], v136, s[100:101] offset:2048
	global_load_dwordx4 v[28:31], v136, s[100:101] offset:3072
	s_load_dwordx2 s[98:99], s[4:5], 0x30
	s_waitcnt lgkmcnt(0)
	global_load_dwordx4 v[88:91], v136, s[98:99] offset:0
	global_load_dwordx4 v[92:95], v136, s[98:99] offset:1024
	global_load_dwordx4 v[96:99], v136, s[98:99] offset:2048
	global_load_dwordx4 v[100:103], v136, s[98:99] offset:3072
	s_waitcnt vmcnt(0)
	v_fma_f32 v88, v88, v16, v88
	v_fma_f32 v89, v89, v17, v89
	v_fma_f32 v90, v90, v18, v90
	v_fma_f32 v91, v91, v19, v91
	v_fma_f32 v92, v92, v20, v92
	v_fma_f32 v93, v93, v21, v93
	v_fma_f32 v94, v94, v22, v94
	v_fma_f32 v95, v95, v23, v95
	v_fma_f32 v96, v96, v24, v96
	v_fma_f32 v97, v97, v25, v97
	v_fma_f32 v98, v98, v26, v98
	v_fma_f32 v99, v99, v27, v99
	v_fma_f32 v100, v100, v28, v100
	v_fma_f32 v101, v101, v29, v101
	v_fma_f32 v102, v102, v30, v102
	v_fma_f32 v103, v103, v31, v103
	s_lshl_b32 vcc_lo, s19, 12
	s_add_u32 s100, s12, vcc_lo
	s_addc_u32 s101, s13, 0
	global_load_dwordx4 v[0:3], v136, s[100:101] offset:0
	global_load_dwordx4 v[4:7], v136, s[100:101] offset:1024
	global_load_dwordx4 v[8:11], v136, s[100:101] offset:2048
	global_load_dwordx4 v[12:15], v136, s[100:101] offset:3072
	s_waitcnt vmcnt(0)
	v_mul_f32_e32 v138, v0, v0
	v_mul_f32_e32 v149, v1, v1
	v_mul_f32_e32 v150, v2, v2
	v_mul_f32_e32 v154, v3, v3
	v_fma_f32 v138, v4, v4, v138
	v_fma_f32 v149, v5, v5, v149
	v_fma_f32 v150, v6, v6, v150
	v_fma_f32 v154, v7, v7, v154
	v_fma_f32 v138, v8, v8, v138
	v_fma_f32 v149, v9, v9, v149
	v_fma_f32 v150, v10, v10, v150
	v_fma_f32 v154, v11, v11, v154
	v_fma_f32 v138, v12, v12, v138
	v_fma_f32 v149, v13, v13, v149
	v_fma_f32 v150, v14, v14, v150
	v_fma_f32 v154, v15, v15, v154
	v_add_f32_e32 v138, v138, v149
	v_add_f32_e32 v150, v150, v154
	v_add_f32_e32 v138, v138, v150
	s_nop 1
	v_add_f32_dpp v138, v138, v138 quad_perm:[1,0,3,2] row_mask:0xf bank_mask:0xf
	s_nop 1
	v_add_f32_dpp v138, v138, v138 quad_perm:[2,3,0,1] row_mask:0xf bank_mask:0xf
	s_nop 1
	v_add_f32_dpp v138, v138, v138 row_half_mirror row_mask:0xf bank_mask:0xf
	s_nop 1
	v_add_f32_dpp v138, v138, v138 row_mirror row_mask:0xf bank_mask:0xf
	v_mov_b32_e32 v139, v138
	s_nop 1
	v_permlane16_swap_b32_e32 v138, v139
	v_add_f32_e32 v138, v138, v139
	v_mov_b32_e32 v139, v138
	s_nop 1
	v_permlane32_swap_b32_e32 v138, v139
	v_add_f32_e32 v138, v138, v139
	v_mul_f32_e32 v138, 0x3a800000, v138
	v_add_f32_e32 v138, 0x358637bd, v138
	v_rsq_f32_e32 v140, v138
	s_nop 0
	v_mul_f32_e32 v120, v0, v140
	v_mul_f32_e32 v121, v1, v140
	v_mul_f32_e32 v122, v2, v140
	v_mul_f32_e32 v123, v3, v140
	v_mul_f32_e32 v124, v4, v140
	v_mul_f32_e32 v125, v5, v140
	v_mul_f32_e32 v126, v6, v140
	v_mul_f32_e32 v127, v7, v140
	v_mul_f32_e32 v128, v8, v140
	v_mul_f32_e32 v129, v9, v140
	v_mul_f32_e32 v130, v10, v140
	v_mul_f32_e32 v131, v11, v140
	v_mul_f32_e32 v132, v12, v140
	v_mul_f32_e32 v133, v13, v140
	v_mul_f32_e32 v134, v14, v140
	v_mul_f32_e32 v135, v15, v140
	v_fma_f32 v120, v120, v88, v104
	v_fma_f32 v121, v121, v89, v105
	v_fma_f32 v122, v122, v90, v106
	v_fma_f32 v123, v123, v91, v107
	v_fma_f32 v124, v124, v92, v108
	v_fma_f32 v125, v125, v93, v109
	v_fma_f32 v126, v126, v94, v110
	v_fma_f32 v127, v127, v95, v111
	v_fma_f32 v128, v128, v96, v112
	v_fma_f32 v129, v129, v97, v113
	v_fma_f32 v130, v130, v98, v114
	v_fma_f32 v131, v131, v99, v115
	v_fma_f32 v132, v132, v100, v116
	v_fma_f32 v133, v133, v101, v117
	v_fma_f32 v134, v134, v102, v118
	v_fma_f32 v135, v135, v103, v119
	v_cvt_pk_bf16_f32 v156, v120, v121
	v_cvt_pk_bf16_f32 v157, v122, v123
	v_cvt_pk_bf16_f32 v158, v124, v125
	v_cvt_pk_bf16_f32 v159, v126, v127
	v_cvt_pk_bf16_f32 v160, v128, v129
	v_cvt_pk_bf16_f32 v161, v130, v131
	v_cvt_pk_bf16_f32 v162, v132, v133
	v_cvt_pk_bf16_f32 v163, v134, v135
	s_lshl_b32 vcc_lo, s19, 11
	s_add_u32 vcc_lo, vcc_lo, 0x4000000
	s_add_u32 s100, s14, vcc_lo
	s_addc_u32 s101, s15, 0
	global_store_dwordx2 v137, v[156:157], s[100:101] offset:0
	global_store_dwordx2 v137, v[158:159], s[100:101] offset:512
	global_store_dwordx2 v137, v[160:161], s[100:101] offset:1024
	global_store_dwordx2 v137, v[162:163], s[100:101] offset:1536

; __device__ __forceinline__ void row_phase(const Params& P, int glayer, int layer, int xsrc, bool hasY, int gate_idx, const float* gpost,
;                           int xdst, bool doH, const float* gpre, int sh_idx, int nrows) {
;     ...
;     for (int u = 0; u < 4; ++u) {
;       const int R = rb + u * stride;
;       if (R < nrows) {
;         if (xsrc != 0 && R < N_X) {
;           const u16* xs_ = ((xsrc == 1) ? resA : P.zf) + (long)R * 1024;
; #pragma unroll
;           for (int i = 0; i < 4; ++i) {
;             const uint2 t2 = *reinterpret_cast<const uint2*>(xs_ + (i * 64 + lane) * 4);
;             xr[u][i].x = t2.x; xr[u][i].y = t2.y;
;           }
;         } else {
;           const float* xin_;
;           if (xsrc == 0) xin_ = R < N_X ? P.x + (long)R * 1024 : P.ctx + (long)(R - N_X) * 1024;
;           else           xin_ = P.xc + (long)(R - N_X) * 1024;
; #pragma unroll
;           for (int i = 0; i < 4; ++i) xr[u][i] = *reinterpret_cast<const uint4*>(xin_ + (i * 64 + lane) * 4);
;         }
;         if (hasY) {
;           const u16* y_ = P.hy + (long)R * 1024;
; #pragma unroll
;           for (int i = 0; i < 4; ++i) yy[u][i] = *reinterpret_cast<const uint2*>(y_ + (i * 64 + lane) * 4);
;         }
;     ...
;           for (int i = 0; i < 4; ++i) {
;             const int col = (i * 64 + lane) * 4;
;             const float4 gt = *reinterpret_cast<const float4*>(modg + gate_idx * 1024 + col);
;             const float4 gp = *reinterpret_cast<const float4*>(gpost + col);
;             xv[i].x += gt.x * (yv[i].x * rstd * gp.x); xv[i].y += gt.y * (yv[i].y * rstd * gp.y);
;             xv[i].z += gt.z * (yv[i].z * rstd * gp.z); xv[i].w += gt.w * (yv[i].w * rstd * gp.w);
;           }
.LBB0_921:
	s_cmp_gt_i32 s34, 7
	s_cselect_b64 s[0:1], -1, 0
	s_cmp_lt_i32 s35, 8
	s_cselect_b64 s[4:5], -1, 0
	s_or_b64 s[0:1], s[0:1], s[4:5]
	s_and_b64 vcc, exec, s[0:1]
	s_cbranch_vccnz .LBB0_1007
	v_lshl_add_u32 v64, s2, 3, v204
	s_mov_b32 s3, 0x8400
	v_mov_b32_e32 v0, v153
	v_cmp_gt_i32_e32 vcc, s3, v64
	s_and_saveexec_b64 s[8:9], vcc
	s_cbranch_execz .LBB0_953
	v_readlane_b32 s4, v252, 0
	v_readlane_b32 s5, v252, 1
	v_readfirstlane_b32 s19, v204
	s_nop 3
	s_sub_u32 s4, s4, 0x170
	s_subb_u32 s5, s5, 0
	s_load_dwordx2 s[12:13], s[4:5], 0x0
	s_load_dwordx2 s[14:15], s[4:5], 0x140
	s_load_dwordx2 s[16:17], s[4:5], 0xc8
	s_load_dwordx2 s[20:21], s[4:5], 0x100
	s_lshl_b32 s98, s2, 3
	s_add_u32 s19, s98, s19
	v_and_b32_e32 v136, 63, v152
	v_lshlrev_b32_e32 v137, 3, v136
	v_lshlrev_b32_e32 v136, 4, v136
	s_waitcnt lgkmcnt(0)
	s_lshl_b32 vcc_lo, s19, 12
	s_add_u32 s100, s12, vcc_lo
	s_addc_u32 s101, s13, 0
	global_load_dwordx4 v[0:3], v136, s[100:101] offset:0
	global_load_dwordx4 v[4:7], v136, s[100:101] offset:1024
	global_load_dwordx4 v[8:11], v136, s[100:101] offset:2048
	global_load_dwordx4 v[12:15], v136, s[100:101] offset:3072
	s_lshl_b32 vcc_lo, s19, 11
	s_add_u32 s100, s14, vcc_lo
	s_addc_u32 s101, s15, 0
	global_load_dwordx2 v[48:49], v137, s[100:101] offset:0
	global_load_dwordx2 v[50:51], v137, s[100:101] offset:512
	global_load_dwordx2 v[52:53], v137, s[100:101] offset:1024
	global_load_dwordx2 v[54:55], v137, s[100:101] offset:1536
	s_lshl_b32 vcc_lo, s19, 12
	s_add_u32 vcc_lo, vcc_lo, 0x800000
	s_add_u32 s100, s12, vcc_lo
	s_addc_u32 s101, s13, 0
	global_load_dwordx4 v[16:19], v136, s[100:101] offset:0
	global_load_dwordx4 v[20:23], v136, s[100:101] offset:1024
	global_load_dwordx4 v[24:27], v136, s[100:101] offset:2048
	global_load_dwordx4 v[28:31], v136, s[100:101] offset:3072
	s_lshl_b32 vcc_lo, s19, 11
	s_add_u32 vcc_lo, vcc_lo, 0x400000
	s_add_u32 s100, s14, vcc_lo
	s_addc_u32 s101, s15, 0
	global_load_dwordx2 v[56:57], v137, s[100:101] offset:0
	global_load_dwordx2 v[58:59], v137, s[100:101] offset:512
	global_load_dwordx2 v[60:61], v137, s[100:101] offset:1024
	global_load_dwordx2 v[62:63], v137, s[100:101] offset:1536
	s_lshl_b32 vcc_lo, s19, 12
	s_add_u32 vcc_lo, vcc_lo, 0x1000000
	s_add_u32 s100, s12, vcc_lo
	s_addc_u32 s101, s13, 0
	global_load_dwordx4 v[32:35], v136, s[100:101] offset:0
	global_load_dwordx4 v[36:39], v136, s[100:101] offset:1024
	global_load_dwordx4 v[40:43], v136, s[100:101] offset:2048
	global_load_dwordx4 v[44:47], v136, s[100:101] offset:3072
	s_lshl_b32 vcc_lo, s19, 11
	s_add_u32 vcc_lo, vcc_lo, 0x800000
	s_add_u32 s100, s14, vcc_lo
	s_addc_u32 s101, s15, 0
	global_load_dwordx2 v[64:65], v137, s[100:101] offset:0
	global_load_dwordx2 v[66:67], v137, s[100:101] offset:512
	global_load_dwordx2 v[68:69], v137, s[100:101] offset:1024
	global_load_dwordx2 v[70:71], v137, s[100:101] offset:1536
	s_add_u32 s100, s20, 0x2000
	s_addc_u32 s101, s21, 0
	global_load_dwordx4 v[72:75], v136, s[100:101] offset:0
	global_load_dwordx4 v[76:79], v136, s[100:101] offset:1024
	global_load_dwordx4 v[80:83], v136, s[100:101] offset:2048
	global_load_dwordx4 v[84:87], v136, s[100:101] offset:3072
	s_load_dwordx2 s[98:99], s[4:5], 0x38
	s_waitcnt lgkmcnt(0)
	global_load_dwordx4 v[120:123], v136, s[98:99] offset:0
	global_load_dwordx4 v[124:127], v136, s[98:99] offset:1024
	global_load_dwordx4 v[128:131], v136, s[98:99] offset:2048
	global_load_dwordx4 v[132:135], v136, s[98:99] offset:3072
	s_add_u32 s100, s20, 0x3000
	s_addc_u32 s101, s21, 0
	global_load_dwordx4 v[104:107], v136, s[100:101] offset:0
	global_load_dwordx4 v[108:111], v136, s[100:101] offset:1024
	global_load_dwordx4 v[112:115], v136, s[100:101] offset:2048
	global_load_dwordx4 v[116:119], v136, s[100:101] offset:3072
	s_add_u32 s100, s100, 0x1000
	s_addc_u32 s101, s101, 0
	global_load_dwordx4 v[166:169], v136, s[100:101] offset:0
	global_load_dwordx4 v[170:173], v136, s[100:101] offset:1024
	global_load_dwordx4 v[174:177], v136, s[100:101] offset:2048
	global_load_dwordx4 v[178:181], v136, s[100:101] offset:3072
	s_load_dwordx2 s[98:99], s[4:5], 0x40
	s_waitcnt lgkmcnt(0)
	global_load_dwordx4 v[88:91], v136, s[98:99] offset:0
	global_load_dwordx4 v[92:95], v136, s[98:99] offset:1024
	global_load_dwordx4 v[96:99], v136, s[98:99] offset:2048
	global_load_dwordx4 v[100:103], v136, s[98:99] offset:3072
	s_waitcnt vmcnt(0)
; __device__ __forceinline__ void row_phase(const Params& P, int glayer, int layer, int xsrc, bool hasY, int gate_idx, const float* gpost,
;                           int xdst, bool doH, const float* gpre, int sh_idx, int nrows) {
;     ...
;         if (hasY) {
;           float4 yv[4];
;           float ss = 0.f;
; #pragma unroll
;           for (int i = 0; i < 4; ++i) {
;             const uint2 raw = yy[u][i];
;             yv[i].x = bf2f((u16)(raw.x & 0xffff)); yv[i].y = bf2f((u16)(raw.x >> 16));
;             yv[i].z = bf2f((u16)(raw.y & 0xffff)); yv[i].w = bf2f((u16)(raw.y >> 16));
;             ss += yv[i].x * yv[i].x + yv[i].y * yv[i].y + yv[i].z * yv[i].z + yv[i].w * yv[i].w;
;           }
;           ss = wave_sum(ss);
;           const float rstd = __builtin_amdgcn_rsqf(ss * (1.f / 1024.f) + EPSF);
; #pragma unroll
;           for (int i = 0; i < 4; ++i) {
;             const int col = (i * 64 + lane) * 4;
;             const float4 gt = *reinterpret_cast<const float4*>(modg + gate_idx * 1024 + col);
;             const float4 gp = *reinterpret_cast<const float4*>(gpost + col);
;             xv[i].x += gt.x * (yv[i].x * rstd * gp.x); xv[i].y += gt.y * (yv[i].y * rstd * gp.y);
;             xv[i].z += gt.z * (yv[i].z * rstd * gp.z); xv[i].w += gt.w * (yv[i].w * rstd * gp.w);
;           }
;         }
;         if (xdst == 3 || (xdst == 1 && row >= N_X)) {
;           float* xout = (xdst == 3) ? P.out + (long)row * 1024 : P.xc + (long)(row - N_X) * 1024;
; #pragma unroll
;           for (int i = 0; i < 4; ++i) *reinterpret_cast<float4*>(xout + (i * 64 + lane) * 4) = xv[i];
;         } else if (xdst != 0) {
;           u16* xo = ((xdst == 1) ? resA : P.zf) + (long)row * 1024;
; #pragma unroll
;           for (int i = 0; i < 4; ++i) {
;             const unsigned b0 = f2bf(xv[i].x), b1 = f2bf(xv[i].y), b2 = f2bf(xv[i].z), b3 = f2bf(xv[i].w);
;             *reinterpret_cast<uint2*>(xo + (i * 64 + lane) * 4) = make_uint2(b0 | (b1 << 16), b2 | (b3 << 16));
;           }
;         }
;         if (doH) {
;           float ss = 0.f;
; #pragma unroll
;           for (int i = 0; i < 4; ++i) ss += xv[i].x * xv[i].x + xv[i].y * xv[i].y + xv[i].z * xv[i].z + xv[i].w * xv[i].w;
;           ss = wave_sum(ss);
;           const float rstd = __builtin_amdgcn_rsqf(ss * (1.f / 1024.f) + EPSF);
;           u16* h = P.hy + (long)row * 1024;
; #pragma unroll
	v_mul_f32_e32 v72, v72, v120
	v_mul_f32_e32 v73, v73, v121
	v_mul_f32_e32 v74, v74, v122
	v_mul_f32_e32 v75, v75, v123
	v_mul_f32_e32 v76, v76, v124
	v_mul_f32_e32 v77, v77, v125
	v_mul_f32_e32 v78, v78, v126
	v_mul_f32_e32 v79, v79, v127
	v_mul_f32_e32 v80, v80, v128
	v_mul_f32_e32 v81, v81, v129
	v_mul_f32_e32 v82, v82, v130
	v_mul_f32_e32 v83, v83, v131
	v_mul_f32_e32 v84, v84, v132
	v_mul_f32_e32 v85, v85, v133
	v_mul_f32_e32 v86, v86, v134
	v_mul_f32_e32 v87, v87, v135
	v_fma_f32 v88, v88, v166, v88
	v_fma_f32 v89, v89, v167, v89
	v_fma_f32 v90, v90, v168, v90
	v_fma_f32 v91, v91, v169, v91
	v_fma_f32 v92, v92, v170, v92
	v_fma_f32 v93, v93, v171, v93
	v_fma_f32 v94, v94, v172, v94
	v_fma_f32 v95, v95, v173, v95
	v_fma_f32 v96, v96, v174, v96
	v_fma_f32 v97, v97, v175, v97
	v_fma_f32 v98, v98, v176, v98
	v_fma_f32 v99, v99, v177, v99
	v_fma_f32 v100, v100, v178, v100
	v_fma_f32 v101, v101, v179, v101
	v_fma_f32 v102, v102, v180, v102
	v_fma_f32 v103, v103, v181, v103
	s_lshl_b32 vcc_lo, s19, 12
	s_add_u32 vcc_lo, vcc_lo, 0x1800000
	s_add_u32 s100, s12, vcc_lo
	s_addc_u32 s101, s13, 0
	global_load_dwordx4 v[166:169], v136, s[100:101] offset:0
	global_load_dwordx4 v[170:173], v136, s[100:101] offset:1024
	global_load_dwordx4 v[174:177], v136, s[100:101] offset:2048
	global_load_dwordx4 v[178:181], v136, s[100:101] offset:3072
	s_lshl_b32 vcc_lo, s19, 11
	s_add_u32 vcc_lo, vcc_lo, 0xc00000
	s_add_u32 s100, s14, vcc_lo
	s_addc_u32 s101, s15, 0
	global_load_dwordx2 v[182:183], v137, s[100:101] offset:0
	global_load_dwordx2 v[184:185], v137, s[100:101] offset:512
	global_load_dwordx2 v[186:187], v137, s[100:101] offset:1024
	global_load_dwordx2 v[188:189], v137, s[100:101] offset:1536
	v_lshlrev_b32_e32 v120, 16, v48
	v_and_b32_e32 v121, 0xffff0000, v48
	v_lshlrev_b32_e32 v122, 16, v49
	v_and_b32_e32 v123, 0xffff0000, v49
	v_lshlrev_b32_e32 v124, 16, v50
	v_and_b32_e32 v125, 0xffff0000, v50
	v_lshlrev_b32_e32 v126, 16, v51
	v_and_b32_e32 v127, 0xffff0000, v51
	v_lshlrev_b32_e32 v128, 16, v52
	v_and_b32_e32 v129, 0xffff0000, v52
	v_lshlrev_b32_e32 v130, 16, v53
	v_and_b32_e32 v131, 0xffff0000, v53
	v_lshlrev_b32_e32 v132, 16, v54
	v_and_b32_e32 v133, 0xffff0000, v54
	v_lshlrev_b32_e32 v134, 16, v55
	v_and_b32_e32 v135, 0xffff0000, v55
	v_mul_f32_e32 v138, v120, v120
	v_mul_f32_e32 v149, v121, v121
	v_mul_f32_e32 v150, v122, v122
	v_mul_f32_e32 v154, v123, v123
	v_fma_f32 v138, v124, v124, v138
	v_fma_f32 v149, v125, v125, v149
	v_fma_f32 v150, v126, v126, v150
	v_fma_f32 v154, v127, v127, v154
	v_fma_f32 v138, v128, v128, v138
	v_fma_f32 v149, v129, v129, v149
	v_fma_f32 v150, v130, v130, v150
	v_fma_f32 v154, v131, v131, v154
	v_fma_f32 v138, v132, v132, v138
	v_fma_f32 v149, v133, v133, v149
	v_fma_f32 v150, v134, v134, v150
	v_fma_f32 v154, v135, v135, v154
	v_add_f32_e32 v138, v138, v149
	v_add_f32_e32 v150, v150, v154
	v_add_f32_e32 v138, v138, v150
	s_nop 1
	v_add_f32_dpp v138, v138, v138 quad_perm:[1,0,3,2] row_mask:0xf bank_mask:0xf
	s_nop 1
	v_add_f32_dpp v138, v138, v138 quad_perm:[2,3,0,1] row_mask:0xf bank_mask:0xf
	s_nop 1
	v_add_f32_dpp v138, v138, v138 row_half_mirror row_mask:0xf bank_mask:0xf
	s_nop 1
	v_add_f32_dpp v138, v138, v138 row_mirror row_mask:0xf bank_mask:0xf
	v_mov_b32_e32 v139, v138
	s_nop 1
	v_permlane16_swap_b32_e32 v138, v139
	v_add_f32_e32 v138, v138, v139
	v_mov_b32_e32 v139, v138
	s_nop 1
	v_permlane32_swap_b32_e32 v138, v139
	v_add_f32_e32 v138, v138, v139
	v_mul_f32_e32 v138, 0x3a800000, v138
	v_add_f32_e32 v138, 0x358637bd, v138
	v_rsq_f32_e32 v140, v138
	s_nop 0
	v_mul_f32_e32 v120, v120, v140
	v_mul_f32_e32 v121, v121, v140
	v_mul_f32_e32 v122, v122, v140
	v_mul_f32_e32 v123, v123, v140
	v_mul_f32_e32 v124, v124, v140
	v_mul_f32_e32 v125, v125, v140
	v_mul_f32_e32 v126, v126, v140
	v_mul_f32_e32 v127, v127, v140
	v_mul_f32_e32 v128, v128, v140
	v_mul_f32_e32 v129, v129, v140
	v_mul_f32_e32 v130, v130, v140
	v_mul_f32_e32 v131, v131, v140
	v_mul_f32_e32 v132, v132, v140
	v_mul_f32_e32 v133, v133, v140
	v_mul_f32_e32 v134, v134, v140
	v_mul_f32_e32 v135, v135, v140
	v_fma_f32 v0, v120, v72, v0
	v_fma_f32 v1, v121, v73, v1
	v_fma_f32 v2, v122, v74, v2
	v_fma_f32 v3, v123, v75, v3
	v_fma_f32 v4, v124, v76, v4
	v_fma_f32 v5, v125, v77, v5
	v_fma_f32 v6, v126, v78, v6
	v_fma_f32 v7, v127, v79, v7
	v_fma_f32 v8, v128, v80, v8
	v_fma_f32 v9, v129, v81, v9
	v_fma_f32 v10, v130, v82, v10
	v_fma_f32 v11, v131, v83, v11
	v_fma_f32 v12, v132, v84, v12
	v_fma_f32 v13, v133, v85, v13
	v_fma_f32 v14, v134, v86, v14
	v_fma_f32 v15, v135, v87, v15
	v_cvt_pk_bf16_f32 v156, v0, v1
	v_cvt_pk_bf16_f32 v157, v2, v3
	v_cvt_pk_bf16_f32 v158, v4, v5
	v_cvt_pk_bf16_f32 v159, v6, v7
	v_cvt_pk_bf16_f32 v160, v8, v9
	v_cvt_pk_bf16_f32 v161, v10, v11
	v_cvt_pk_bf16_f32 v162, v12, v13
	v_cvt_pk_bf16_f32 v163, v14, v15
	s_lshl_b32 vcc_lo, s19, 11
	s_add_u32 s100, s16, vcc_lo
	s_addc_u32 s101, s17, 0
	global_store_dwordx2 v137, v[156:157], s[100:101] offset:0
	global_store_dwordx2 v137, v[158:159], s[100:101] offset:512
	global_store_dwordx2 v137, v[160:161], s[100:101] offset:1024
	global_store_dwordx2 v137, v[162:163], s[100:101] offset:1536
	v_mul_f32_e32 v138, v0, v0
	v_mul_f32_e32 v149, v1, v1
	v_mul_f32_e32 v150, v2, v2
	v_mul_f32_e32 v154, v3, v3
	v_fma_f32 v138, v4, v4, v138
	v_fma_f32 v149, v5, v5, v149
	v_fma_f32 v150, v6, v6, v150
	v_fma_f32 v154, v7, v7, v154
	v_fma_f32 v138, v8, v8, v138
	v_fma_f32 v149, v9, v9, v149
	v_fma_f32 v150, v10, v10, v150
	v_fma_f32 v154, v11, v11, v154
	v_fma_f32 v138, v12, v12, v138
	v_fma_f32 v149, v13, v13, v149
	v_fma_f32 v150, v14, v14, v150
	v_fma_f32 v154, v15, v15, v154
; __device__ __forceinline__ void row_phase(const Params& P, int glayer, int layer, int xsrc, bool hasY, int gate_idx, const float* gpost,
;                           int xdst, bool doH, const float* gpre, int sh_idx, int nrows) {
;     ...
;         if (hasY) {
;           float4 yv[4];
;           float ss = 0.f;
; #pragma unroll
;           for (int i = 0; i < 4; ++i) {
;             const uint2 raw = yy[u][i];
;             yv[i].x = bf2f((u16)(raw.x & 0xffff)); yv[i].y = bf2f((u16)(raw.x >> 16));
;             yv[i].z = bf2f((u16)(raw.y & 0xffff)); yv[i].w = bf2f((u16)(raw.y >> 16));
;             ss += yv[i].x * yv[i].x + yv[i].y * yv[i].y + yv[i].z * yv[i].z + yv[i].w * yv[i].w;
;           }
;           ss = wave_sum(ss);
;           const float rstd = __builtin_amdgcn_rsqf(ss * (1.f / 1024.f) + EPSF);
; #pragma unroll
;           for (int i = 0; i < 4; ++i) {
;             const int col = (i * 64 + lane) * 4;
;             const float4 gt = *reinterpret_cast<const float4*>(modg + gate_idx * 1024 + col);
;             const float4 gp = *reinterpret_cast<const float4*>(gpost + col);
;             xv[i].x += gt.x * (yv[i].x * rstd * gp.x); xv[i].y += gt.y * (yv[i].y * rstd * gp.y);
;             xv[i].z += gt.z * (yv[i].z * rstd * gp.z); xv[i].w += gt.w * (yv[i].w * rstd * gp.w);
;           }
;         }
;         if (xdst == 3 || (xdst == 1 && row >= N_X)) {
;           float* xout = (xdst == 3) ? P.out + (long)row * 1024 : P.xc + (long)(row - N_X) * 1024;
; #pragma unroll
;           for (int i = 0; i < 4; ++i) *reinterpret_cast<float4*>(xout + (i * 64 + lane) * 4) = xv[i];
;         } else if (xdst != 0) {
;           u16* xo = ((xdst == 1) ? resA : P.zf) + (long)row * 1024;
; #pragma unroll
;           for (int i = 0; i < 4; ++i) {
;             const unsigned b0 = f2bf(xv[i].x), b1 = f2bf(xv[i].y), b2 = f2bf(xv[i].z), b3 = f2bf(xv[i].w);
;             *reinterpret_cast<uint2*>(xo + (i * 64 + lane) * 4) = make_uint2(b0 | (b1 << 16), b2 | (b3 << 16));
;           }
;         }
;         if (doH) {
;           float ss = 0.f;
; #pragma unroll
;           for (int i = 0; i < 4; ++i) ss += xv[i].x * xv[i].x + xv[i].y * xv[i].y + xv[i].z * xv[i].z + xv[i].w * xv[i].w;
;           ss = wave_sum(ss);
;           const float rstd = __builtin_amdgcn_rsqf(ss * (1.f / 1024.f) + EPSF);
;           u16* h = P.hy + (long)row * 1024;
; #pragma unroll
	v_add_f32_e32 v138, v138, v149
	v_add_f32_e32 v150, v150, v154
	v_add_f32_e32 v138, v138, v150
	s_nop 1
	v_add_f32_dpp v138, v138, v138 quad_perm:[1,0,3,2] row_mask:0xf bank_mask:0xf
	s_nop 1
	v_add_f32_dpp v138, v138, v138 quad_perm:[2,3,0,1] row_mask:0xf bank_mask:0xf
	s_nop 1
	v_add_f32_dpp v138, v138, v138 row_half_mirror row_mask:0xf bank_mask:0xf
	s_nop 1
	v_add_f32_dpp v138, v138, v138 row_mirror row_mask:0xf bank_mask:0xf
	v_mov_b32_e32 v139, v138
	s_nop 1
	v_permlane16_swap_b32_e32 v138, v139
	v_add_f32_e32 v138, v138, v139
	v_mov_b32_e32 v139, v138
	s_nop 1
	v_permlane32_swap_b32_e32 v138, v139
	v_add_f32_e32 v138, v138, v139
	v_mul_f32_e32 v138, 0x3a800000, v138
	v_add_f32_e32 v138, 0x358637bd, v138
	v_rsq_f32_e32 v140, v138
	s_nop 0
	v_mul_f32_e32 v120, v0, v140
	v_mul_f32_e32 v121, v1, v140
	v_mul_f32_e32 v122, v2, v140
	v_mul_f32_e32 v123, v3, v140
	v_mul_f32_e32 v124, v4, v140
	v_mul_f32_e32 v125, v5, v140
	v_mul_f32_e32 v126, v6, v140
	v_mul_f32_e32 v127, v7, v140
	v_mul_f32_e32 v128, v8, v140
	v_mul_f32_e32 v129, v9, v140
	v_mul_f32_e32 v130, v10, v140
	v_mul_f32_e32 v131, v11, v140
	v_mul_f32_e32 v132, v12, v140
	v_mul_f32_e32 v133, v13, v140
	v_mul_f32_e32 v134, v14, v140
	v_mul_f32_e32 v135, v15, v140
	v_fma_f32 v120, v120, v88, v104
	v_fma_f32 v121, v121, v89, v105
	v_fma_f32 v122, v122, v90, v106
	v_fma_f32 v123, v123, v91, v107
	v_fma_f32 v124, v124, v92, v108
	v_fma_f32 v125, v125, v93, v109
	v_fma_f32 v126, v126, v94, v110
	v_fma_f32 v127, v127, v95, v111
	v_fma_f32 v128, v128, v96, v112
	v_fma_f32 v129, v129, v97, v113
	v_fma_f32 v130, v130, v98, v114
	v_fma_f32 v131, v131, v99, v115
	v_fma_f32 v132, v132, v100, v116
	v_fma_f32 v133, v133, v101, v117
	v_fma_f32 v134, v134, v102, v118
	v_fma_f32 v135, v135, v103, v119
	v_cvt_pk_bf16_f32 v156, v120, v121
	v_cvt_pk_bf16_f32 v157, v122, v123
	v_cvt_pk_bf16_f32 v158, v124, v125
	v_cvt_pk_bf16_f32 v159, v126, v127
	v_cvt_pk_bf16_f32 v160, v128, v129
	v_cvt_pk_bf16_f32 v161, v130, v131
	v_cvt_pk_bf16_f32 v162, v132, v133
	v_cvt_pk_bf16_f32 v163, v134, v135
	s_lshl_b32 vcc_lo, s19, 11
	s_add_u32 s100, s14, vcc_lo
	s_addc_u32 s101, s15, 0
	global_store_dwordx2 v137, v[156:157], s[100:101] offset:0
	global_store_dwordx2 v137, v[158:159], s[100:101] offset:512
	global_store_dwordx2 v137, v[160:161], s[100:101] offset:1024
	global_store_dwordx2 v137, v[162:163], s[100:101] offset:1536
	s_lshl_b32 vcc_lo, s19, 12
	s_add_u32 vcc_lo, vcc_lo, 0x2000000
	s_add_u32 s100, s12, vcc_lo
	s_addc_u32 s101, s13, 0
	global_load_dwordx4 v[0:3], v136, s[100:101] offset:0
	global_load_dwordx4 v[4:7], v136, s[100:101] offset:1024
	global_load_dwordx4 v[8:11], v136, s[100:101] offset:2048
	global_load_dwordx4 v[12:15], v136, s[100:101] offset:3072
	s_lshl_b32 vcc_lo, s19, 11
	s_add_u32 vcc_lo, vcc_lo, 0x1000000
	s_add_u32 s100, s14, vcc_lo
	s_addc_u32 s101, s15, 0
	global_load_dwordx2 v[48:49], v137, s[100:101] offset:0
	global_load_dwordx2 v[50:51], v137, s[100:101] offset:512
	global_load_dwordx2 v[52:53], v137, s[100:101] offset:1024
	global_load_dwordx2 v[54:55], v137, s[100:101] offset:1536
	v_lshlrev_b32_e32 v120, 16, v56
	v_and_b32_e32 v121, 0xffff0000, v56
	v_lshlrev_b32_e32 v122, 16, v57
	v_and_b32_e32 v123, 0xffff0000, v57
	v_lshlrev_b32_e32 v124, 16, v58
	v_and_b32_e32 v125, 0xffff0000, v58
	v_lshlrev_b32_e32 v126, 16, v59
	v_and_b32_e32 v127, 0xffff0000, v59
	v_lshlrev_b32_e32 v128, 16, v60
	v_and_b32_e32 v129, 0xffff0000, v60
	v_lshlrev_b32_e32 v130, 16, v61
	v_and_b32_e32 v131, 0xffff0000, v61
	v_lshlrev_b32_e32 v132, 16, v62
	v_and_b32_e32 v133, 0xffff0000, v62
	v_lshlrev_b32_e32 v134, 16, v63
	v_and_b32_e32 v135, 0xffff0000, v63
	v_mul_f32_e32 v138, v120, v120
	v_mul_f32_e32 v149, v121, v121
	v_mul_f32_e32 v150, v122, v122
	v_mul_f32_e32 v154, v123, v123
	v_fma_f32 v138, v124, v124, v138
	v_fma_f32 v149, v125, v125, v149
	v_fma_f32 v150, v126, v126, v150
	v_fma_f32 v154, v127, v127, v154
	v_fma_f32 v138, v128, v128, v138
	v_fma_f32 v149, v129, v129, v149
	v_fma_f32 v150, v130, v130, v150
	v_fma_f32 v154, v131, v131, v154
	v_fma_f32 v138, v132, v132, v138
	v_fma_f32 v149, v133, v133, v149
	v_fma_f32 v150, v134, v134, v150
	v_fma_f32 v154, v135, v135, v154
	v_add_f32_e32 v138, v138, v149
	v_add_f32_e32 v150, v150, v154
	v_add_f32_e32 v138, v138, v150
	s_nop 1
	v_add_f32_dpp v138, v138, v138 quad_perm:[1,0,3,2] row_mask:0xf bank_mask:0xf
	s_nop 1
	v_add_f32_dpp v138, v138, v138 quad_perm:[2,3,0,1] row_mask:0xf bank_mask:0xf
	s_nop 1
	v_add_f32_dpp v138, v138, v138 row_half_mirror row_mask:0xf bank_mask:0xf
	s_nop 1
	v_add_f32_dpp v138, v138, v138 row_mirror row_mask:0xf bank_mask:0xf
	v_mov_b32_e32 v139, v138
	s_nop 1
	v_permlane16_swap_b32_e32 v138, v139
	v_add_f32_e32 v138, v138, v139
	v_mov_b32_e32 v139, v138
	s_nop 1
	v_permlane32_swap_b32_e32 v138, v139
	v_add_f32_e32 v138, v138, v139
	v_mul_f32_e32 v138, 0x3a800000, v138
	v_add_f32_e32 v138, 0x358637bd, v138
	v_rsq_f32_e32 v140, v138
	s_nop 0
	v_mul_f32_e32 v120, v120, v140
	v_mul_f32_e32 v121, v121, v140
	v_mul_f32_e32 v122, v122, v140
	v_mul_f32_e32 v123, v123, v140
	v_mul_f32_e32 v124, v124, v140
	v_mul_f32_e32 v125, v125, v140
	v_mul_f32_e32 v126, v126, v140
	v_mul_f32_e32 v127, v127, v140
	v_mul_f32_e32 v128, v128, v140
	v_mul_f32_e32 v129, v129, v140
	v_mul_f32_e32 v130, v130, v140
	v_mul_f32_e32 v131, v131, v140
	v_mul_f32_e32 v132, v132, v140
	v_mul_f32_e32 v133, v133, v140
	v_mul_f32_e32 v134, v134, v140
	v_mul_f32_e32 v135, v135, v140
	v_fma_f32 v16, v120, v72, v16
	v_fma_f32 v17, v121, v73, v17
	v_fma_f32 v18, v122, v74, v18
	v_fma_f32 v19, v123, v75, v19
	v_fma_f32 v20, v124, v76, v20
	v_fma_f32 v21, v125, v77, v21
; __device__ __forceinline__ void row_phase(const Params& P, int glayer, int layer, int xsrc, bool hasY, int gate_idx, const float* gpost,
;                           int xdst, bool doH, const float* gpre, int sh_idx, int nrows) {
;     ...
;         if (hasY) {
;           float4 yv[4];
;           float ss = 0.f;
; #pragma unroll
;           for (int i = 0; i < 4; ++i) {
;             const uint2 raw = yy[u][i];
;             yv[i].x = bf2f((u16)(raw.x & 0xffff)); yv[i].y = bf2f((u16)(raw.x >> 16));
;             yv[i].z = bf2f((u16)(raw.y & 0xffff)); yv[i].w = bf2f((u16)(raw.y >> 16));
;             ss += yv[i].x * yv[i].x + yv[i].y * yv[i].y + yv[i].z * yv[i].z + yv[i].w * yv[i].w;
;           }
;           ss = wave_sum(ss);
;           const float rstd = __builtin_amdgcn_rsqf(ss * (1.f / 1024.f) + EPSF);
; #pragma unroll
;           for (int i = 0; i < 4; ++i) {
;             const int col = (i * 64 + lane) * 4;
;             const float4 gt = *reinterpret_cast<const float4*>(modg + gate_idx * 1024 + col);
;             const float4 gp = *reinterpret_cast<const float4*>(gpost + col);
;             xv[i].x += gt.x * (yv[i].x * rstd * gp.x); xv[i].y += gt.y * (yv[i].y * rstd * gp.y);
;             xv[i].z += gt.z * (yv[i].z * rstd * gp.z); xv[i].w += gt.w * (yv[i].w * rstd * gp.w);
;           }
;         }
;         if (xdst == 3 || (xdst == 1 && row >= N_X)) {
;           float* xout = (xdst == 3) ? P.out + (long)row * 1024 : P.xc + (long)(row - N_X) * 1024;
; #pragma unroll
;           for (int i = 0; i < 4; ++i) *reinterpret_cast<float4*>(xout + (i * 64 + lane) * 4) = xv[i];
;         } else if (xdst != 0) {
;           u16* xo = ((xdst == 1) ? resA : P.zf) + (long)row * 1024;
; #pragma unroll
;           for (int i = 0; i < 4; ++i) {
;             const unsigned b0 = f2bf(xv[i].x), b1 = f2bf(xv[i].y), b2 = f2bf(xv[i].z), b3 = f2bf(xv[i].w);
;             *reinterpret_cast<uint2*>(xo + (i * 64 + lane) * 4) = make_uint2(b0 | (b1 << 16), b2 | (b3 << 16));
;           }
;         }
;         if (doH) {
;           float ss = 0.f;
; #pragma unroll
;           for (int i = 0; i < 4; ++i) ss += xv[i].x * xv[i].x + xv[i].y * xv[i].y + xv[i].z * xv[i].z + xv[i].w * xv[i].w;
;           ss = wave_sum(ss);
;           const float rstd = __builtin_amdgcn_rsqf(ss * (1.f / 1024.f) + EPSF);
;           u16* h = P.hy + (long)row * 1024;
; #pragma unroll
	v_fma_f32 v22, v126, v78, v22
	v_fma_f32 v23, v127, v79, v23
	v_fma_f32 v24, v128, v80, v24
	v_fma_f32 v25, v129, v81, v25
	v_fma_f32 v26, v130, v82, v26
	v_fma_f32 v27, v131, v83, v27
	v_fma_f32 v28, v132, v84, v28
	v_fma_f32 v29, v133, v85, v29
	v_fma_f32 v30, v134, v86, v30
	v_fma_f32 v31, v135, v87, v31
	v_cvt_pk_bf16_f32 v156, v16, v17
	v_cvt_pk_bf16_f32 v157, v18, v19
	v_cvt_pk_bf16_f32 v158, v20, v21
	v_cvt_pk_bf16_f32 v159, v22, v23
	v_cvt_pk_bf16_f32 v160, v24, v25
	v_cvt_pk_bf16_f32 v161, v26, v27
	v_cvt_pk_bf16_f32 v162, v28, v29
	v_cvt_pk_bf16_f32 v163, v30, v31
	s_lshl_b32 vcc_lo, s19, 11
	s_add_u32 vcc_lo, vcc_lo, 0x400000
	s_add_u32 s100, s16, vcc_lo
	s_addc_u32 s101, s17, 0
	global_store_dwordx2 v137, v[156:157], s[100:101] offset:0
	global_store_dwordx2 v137, v[158:159], s[100:101] offset:512
	global_store_dwordx2 v137, v[160:161], s[100:101] offset:1024
	global_store_dwordx2 v137, v[162:163], s[100:101] offset:1536
	v_mul_f32_e32 v138, v16, v16
	v_mul_f32_e32 v149, v17, v17
	v_mul_f32_e32 v150, v18, v18
	v_mul_f32_e32 v154, v19, v19
	v_fma_f32 v138, v20, v20, v138
	v_fma_f32 v149, v21, v21, v149
	v_fma_f32 v150, v22, v22, v150
	v_fma_f32 v154, v23, v23, v154
	v_fma_f32 v138, v24, v24, v138
	v_fma_f32 v149, v25, v25, v149
	v_fma_f32 v150, v26, v26, v150
	v_fma_f32 v154, v27, v27, v154
	v_fma_f32 v138, v28, v28, v138
	v_fma_f32 v149, v29, v29, v149
	v_fma_f32 v150, v30, v30, v150
	v_fma_f32 v154, v31, v31, v154
	v_add_f32_e32 v138, v138, v149
	v_add_f32_e32 v150, v150, v154
	v_add_f32_e32 v138, v138, v150
	s_nop 1
	v_add_f32_dpp v138, v138, v138 quad_perm:[1,0,3,2] row_mask:0xf bank_mask:0xf
	s_nop 1
	v_add_f32_dpp v138, v138, v138 quad_perm:[2,3,0,1] row_mask:0xf bank_mask:0xf
	s_nop 1
	v_add_f32_dpp v138, v138, v138 row_half_mirror row_mask:0xf bank_mask:0xf
	s_nop 1
	v_add_f32_dpp v138, v138, v138 row_mirror row_mask:0xf bank_mask:0xf
	v_mov_b32_e32 v139, v138
	s_nop 1
	v_permlane16_swap_b32_e32 v138, v139
	v_add_f32_e32 v138, v138, v139
	v_mov_b32_e32 v139, v138
	s_nop 1
	v_permlane32_swap_b32_e32 v138, v139
	v_add_f32_e32 v138, v138, v139
	v_mul_f32_e32 v138, 0x3a800000, v138
	v_add_f32_e32 v138, 0x358637bd, v138
	v_rsq_f32_e32 v140, v138
	s_nop 0
	v_mul_f32_e32 v120, v16, v140
	v_mul_f32_e32 v121, v17, v140
	v_mul_f32_e32 v122, v18, v140
	v_mul_f32_e32 v123, v19, v140
	v_mul_f32_e32 v124, v20, v140
	v_mul_f32_e32 v125, v21, v140
	v_mul_f32_e32 v126, v22, v140
	v_mul_f32_e32 v127, v23, v140
	v_mul_f32_e32 v128, v24, v140
	v_mul_f32_e32 v129, v25, v140
	v_mul_f32_e32 v130, v26, v140
	v_mul_f32_e32 v131, v27, v140
	v_mul_f32_e32 v132, v28, v140
	v_mul_f32_e32 v133, v29, v140
	v_mul_f32_e32 v134, v30, v140
	v_mul_f32_e32 v135, v31, v140
	v_fma_f32 v120, v120, v88, v104
	v_fma_f32 v121, v121, v89, v105
	v_fma_f32 v122, v122, v90, v106
	v_fma_f32 v123, v123, v91, v107
	v_fma_f32 v124, v124, v92, v108
	v_fma_f32 v125, v125, v93, v109
	v_fma_f32 v126, v126, v94, v110
	v_fma_f32 v127, v127, v95, v111
	v_fma_f32 v128, v128, v96, v112
	v_fma_f32 v129, v129, v97, v113
	v_fma_f32 v130, v130, v98, v114
	v_fma_f32 v131, v131, v99, v115
	v_fma_f32 v132, v132, v100, v116
	v_fma_f32 v133, v133, v101, v117
	v_fma_f32 v134, v134, v102, v118
	v_fma_f32 v135, v135, v103, v119
	v_cvt_pk_bf16_f32 v156, v120, v121
	v_cvt_pk_bf16_f32 v157, v122, v123
	v_cvt_pk_bf16_f32 v158, v124, v125
	v_cvt_pk_bf16_f32 v159, v126, v127
	v_cvt_pk_bf16_f32 v160, v128, v129
	v_cvt_pk_bf16_f32 v161, v130, v131
	v_cvt_pk_bf16_f32 v162, v132, v133
	v_cvt_pk_bf16_f32 v163, v134, v135
	s_lshl_b32 vcc_lo, s19, 11
	s_add_u32 vcc_lo, vcc_lo, 0x400000
	s_add_u32 s100, s14, vcc_lo
	s_addc_u32 s101, s15, 0
	global_store_dwordx2 v137, v[156:157], s[100:101] offset:0
	global_store_dwordx2 v137, v[158:159], s[100:101] offset:512
	global_store_dwordx2 v137, v[160:161], s[100:101] offset:1024
	global_store_dwordx2 v137, v[162:163], s[100:101] offset:1536
	s_lshl_b32 vcc_lo, s19, 12
	s_add_u32 vcc_lo, vcc_lo, 0x2800000
	s_add_u32 s100, s12, vcc_lo
	s_addc_u32 s101, s13, 0
	global_load_dwordx4 v[16:19], v136, s[100:101] offset:0
	global_load_dwordx4 v[20:23], v136, s[100:101] offset:1024
	global_load_dwordx4 v[24:27], v136, s[100:101] offset:2048
	global_load_dwordx4 v[28:31], v136, s[100:101] offset:3072
	s_lshl_b32 vcc_lo, s19, 11
	s_add_u32 vcc_lo, vcc_lo, 0x1400000
	s_add_u32 s100, s14, vcc_lo
	s_addc_u32 s101, s15, 0
	global_load_dwordx2 v[56:57], v137, s[100:101] offset:0
	global_load_dwordx2 v[58:59], v137, s[100:101] offset:512
	global_load_dwordx2 v[60:61], v137, s[100:101] offset:1024
	global_load_dwordx2 v[62:63], v137, s[100:101] offset:1536
	v_lshlrev_b32_e32 v120, 16, v64
	v_and_b32_e32 v121, 0xffff0000, v64
	v_lshlrev_b32_e32 v122, 16, v65
	v_and_b32_e32 v123, 0xffff0000, v65
	v_lshlrev_b32_e32 v124, 16, v66
	v_and_b32_e32 v125, 0xffff0000, v66
	v_lshlrev_b32_e32 v126, 16, v67
	v_and_b32_e32 v127, 0xffff0000, v67
	v_lshlrev_b32_e32 v128, 16, v68
	v_and_b32_e32 v129, 0xffff0000, v68
	v_lshlrev_b32_e32 v130, 16, v69
	v_and_b32_e32 v131, 0xffff0000, v69
	v_lshlrev_b32_e32 v132, 16, v70
	v_and_b32_e32 v133, 0xffff0000, v70
	v_lshlrev_b32_e32 v134, 16, v71
	v_and_b32_e32 v135, 0xffff0000, v71
	v_mul_f32_e32 v138, v120, v120
	v_mul_f32_e32 v149, v121, v121
	v_mul_f32_e32 v150, v122, v122
	v_mul_f32_e32 v154, v123, v123
	v_fma_f32 v138, v124, v124, v138
	v_fma_f32 v149, v125, v125, v149
	v_fma_f32 v150, v126, v126, v150
	v_fma_f32 v154, v127, v127, v154
	v_fma_f32 v138, v128, v128, v138
	v_fma_f32 v149, v129, v129, v149
	v_fma_f32 v150, v130, v130, v150
	v_fma_f32 v154, v131, v131, v154
	v_fma_f32 v138, v132, v132, v138
	v_fma_f32 v149, v133, v133, v149
; __device__ __forceinline__ void row_phase(const Params& P, int glayer, int layer, int xsrc, bool hasY, int gate_idx, const float* gpost,
;                           int xdst, bool doH, const float* gpre, int sh_idx, int nrows) {
;     ...
;         if (hasY) {
;           float4 yv[4];
;           float ss = 0.f;
; #pragma unroll
;           for (int i = 0; i < 4; ++i) {
;             const uint2 raw = yy[u][i];
;             yv[i].x = bf2f((u16)(raw.x & 0xffff)); yv[i].y = bf2f((u16)(raw.x >> 16));
;             yv[i].z = bf2f((u16)(raw.y & 0xffff)); yv[i].w = bf2f((u16)(raw.y >> 16));
;             ss += yv[i].x * yv[i].x + yv[i].y * yv[i].y + yv[i].z * yv[i].z + yv[i].w * yv[i].w;
;           }
;           ss = wave_sum(ss);
;           const float rstd = __builtin_amdgcn_rsqf(ss * (1.f / 1024.f) + EPSF);
; #pragma unroll
;           for (int i = 0; i < 4; ++i) {
;             const int col = (i * 64 + lane) * 4;
;             const float4 gt = *reinterpret_cast<const float4*>(modg + gate_idx * 1024 + col);
;             const float4 gp = *reinterpret_cast<const float4*>(gpost + col);
;             xv[i].x += gt.x * (yv[i].x * rstd * gp.x); xv[i].y += gt.y * (yv[i].y * rstd * gp.y);
;             xv[i].z += gt.z * (yv[i].z * rstd * gp.z); xv[i].w += gt.w * (yv[i].w * rstd * gp.w);
;           }
;         }
;         if (xdst == 3 || (xdst == 1 && row >= N_X)) {
;           float* xout = (xdst == 3) ? P.out + (long)row * 1024 : P.xc + (long)(row - N_X) * 1024;
; #pragma unroll
;           for (int i = 0; i < 4; ++i) *reinterpret_cast<float4*>(xout + (i * 64 + lane) * 4) = xv[i];
;         } else if (xdst != 0) {
;           u16* xo = ((xdst == 1) ? resA : P.zf) + (long)row * 1024;
; #pragma unroll
;           for (int i = 0; i < 4; ++i) {
;             const unsigned b0 = f2bf(xv[i].x), b1 = f2bf(xv[i].y), b2 = f2bf(xv[i].z), b3 = f2bf(xv[i].w);
;             *reinterpret_cast<uint2*>(xo + (i * 64 + lane) * 4) = make_uint2(b0 | (b1 << 16), b2 | (b3 << 16));
;           }
;         }
;         if (doH) {
;           float ss = 0.f;
; #pragma unroll
;           for (int i = 0; i < 4; ++i) ss += xv[i].x * xv[i].x + xv[i].y * xv[i].y + xv[i].z * xv[i].z + xv[i].w * xv[i].w;
;           ss = wave_sum(ss);
;           const float rstd = __builtin_amdgcn_rsqf(ss * (1.f / 1024.f) + EPSF);
;           u16* h = P.hy + (long)row * 1024;
; #pragma unroll
	v_fma_f32 v150, v134, v134, v150
	v_fma_f32 v154, v135, v135, v154
	v_add_f32_e32 v138, v138, v149
	v_add_f32_e32 v150, v150, v154
	v_add_f32_e32 v138, v138, v150
	s_nop 1
	v_add_f32_dpp v138, v138, v138 quad_perm:[1,0,3,2] row_mask:0xf bank_mask:0xf
	s_nop 1
	v_add_f32_dpp v138, v138, v138 quad_perm:[2,3,0,1] row_mask:0xf bank_mask:0xf
	s_nop 1
	v_add_f32_dpp v138, v138, v138 row_half_mirror row_mask:0xf bank_mask:0xf
	s_nop 1
	v_add_f32_dpp v138, v138, v138 row_mirror row_mask:0xf bank_mask:0xf
	v_mov_b32_e32 v139, v138
	s_nop 1
	v_permlane16_swap_b32_e32 v138, v139
	v_add_f32_e32 v138, v138, v139
	v_mov_b32_e32 v139, v138
	s_nop 1
	v_permlane32_swap_b32_e32 v138, v139
	v_add_f32_e32 v138, v138, v139
	v_mul_f32_e32 v138, 0x3a800000, v138
	v_add_f32_e32 v138, 0x358637bd, v138
	v_rsq_f32_e32 v140, v138
	s_nop 0
	v_mul_f32_e32 v120, v120, v140
	v_mul_f32_e32 v121, v121, v140
	v_mul_f32_e32 v122, v122, v140
	v_mul_f32_e32 v123, v123, v140
	v_mul_f32_e32 v124, v124, v140
	v_mul_f32_e32 v125, v125, v140
	v_mul_f32_e32 v126, v126, v140
	v_mul_f32_e32 v127, v127, v140
	v_mul_f32_e32 v128, v128, v140
	v_mul_f32_e32 v129, v129, v140
	v_mul_f32_e32 v130, v130, v140
	v_mul_f32_e32 v131, v131, v140
	v_mul_f32_e32 v132, v132, v140
	v_mul_f32_e32 v133, v133, v140
	v_mul_f32_e32 v134, v134, v140
	v_mul_f32_e32 v135, v135, v140
	v_fma_f32 v32, v120, v72, v32
	v_fma_f32 v33, v121, v73, v33
	v_fma_f32 v34, v122, v74, v34
	v_fma_f32 v35, v123, v75, v35
	v_fma_f32 v36, v124, v76, v36
	v_fma_f32 v37, v125, v77, v37
	v_fma_f32 v38, v126, v78, v38
	v_fma_f32 v39, v127, v79, v39
	v_fma_f32 v40, v128, v80, v40
	v_fma_f32 v41, v129, v81, v41
	v_fma_f32 v42, v130, v82, v42
	v_fma_f32 v43, v131, v83, v43
	v_fma_f32 v44, v132, v84, v44
	v_fma_f32 v45, v133, v85, v45
	v_fma_f32 v46, v134, v86, v46
	v_fma_f32 v47, v135, v87, v47
	v_cvt_pk_bf16_f32 v156, v32, v33
	v_cvt_pk_bf16_f32 v157, v34, v35
	v_cvt_pk_bf16_f32 v158, v36, v37
	v_cvt_pk_bf16_f32 v159, v38, v39
	v_cvt_pk_bf16_f32 v160, v40, v41
	v_cvt_pk_bf16_f32 v161, v42, v43
	v_cvt_pk_bf16_f32 v162, v44, v45
	v_cvt_pk_bf16_f32 v163, v46, v47
	s_lshl_b32 vcc_lo, s19, 11
	s_add_u32 vcc_lo, vcc_lo, 0x800000
	s_add_u32 s100, s16, vcc_lo
	s_addc_u32 s101, s17, 0
	global_store_dwordx2 v137, v[156:157], s[100:101] offset:0
	global_store_dwordx2 v137, v[158:159], s[100:101] offset:512
	global_store_dwordx2 v137, v[160:161], s[100:101] offset:1024
	global_store_dwordx2 v137, v[162:163], s[100:101] offset:1536
	v_mul_f32_e32 v138, v32, v32
	v_mul_f32_e32 v149, v33, v33
	v_mul_f32_e32 v150, v34, v34
	v_mul_f32_e32 v154, v35, v35
	v_fma_f32 v138, v36, v36, v138
	v_fma_f32 v149, v37, v37, v149
	v_fma_f32 v150, v38, v38, v150
	v_fma_f32 v154, v39, v39, v154
	v_fma_f32 v138, v40, v40, v138
	v_fma_f32 v149, v41, v41, v149
	v_fma_f32 v150, v42, v42, v150
	v_fma_f32 v154, v43, v43, v154
	v_fma_f32 v138, v44, v44, v138
	v_fma_f32 v149, v45, v45, v149
	v_fma_f32 v150, v46, v46, v150
	v_fma_f32 v154, v47, v47, v154
	v_add_f32_e32 v138, v138, v149
	v_add_f32_e32 v150, v150, v154
	v_add_f32_e32 v138, v138, v150
	s_nop 1
	v_add_f32_dpp v138, v138, v138 quad_perm:[1,0,3,2] row_mask:0xf bank_mask:0xf
	s_nop 1
	v_add_f32_dpp v138, v138, v138 quad_perm:[2,3,0,1] row_mask:0xf bank_mask:0xf
	s_nop 1
	v_add_f32_dpp v138, v138, v138 row_half_mirror row_mask:0xf bank_mask:0xf
	s_nop 1
	v_add_f32_dpp v138, v138, v138 row_mirror row_mask:0xf bank_mask:0xf
	v_mov_b32_e32 v139, v138
	s_nop 1
	v_permlane16_swap_b32_e32 v138, v139
	v_add_f32_e32 v138, v138, v139
	v_mov_b32_e32 v139, v138
	s_nop 1
	v_permlane32_swap_b32_e32 v138, v139
	v_add_f32_e32 v138, v138, v139
	v_mul_f32_e32 v138, 0x3a800000, v138
	v_add_f32_e32 v138, 0x358637bd, v138
	v_rsq_f32_e32 v140, v138
	s_nop 0
	v_mul_f32_e32 v120, v32, v140
	v_mul_f32_e32 v121, v33, v140
	v_mul_f32_e32 v122, v34, v140
	v_mul_f32_e32 v123, v35, v140
	v_mul_f32_e32 v124, v36, v140
	v_mul_f32_e32 v125, v37, v140
	v_mul_f32_e32 v126, v38, v140
	v_mul_f32_e32 v127, v39, v140
	v_mul_f32_e32 v128, v40, v140
	v_mul_f32_e32 v129, v41, v140
	v_mul_f32_e32 v130, v42, v140
	v_mul_f32_e32 v131, v43, v140
	v_mul_f32_e32 v132, v44, v140
	v_mul_f32_e32 v133, v45, v140
	v_mul_f32_e32 v134, v46, v140
	v_mul_f32_e32 v135, v47, v140
	v_fma_f32 v120, v120, v88, v104
	v_fma_f32 v121, v121, v89, v105
	v_fma_f32 v122, v122, v90, v106
	v_fma_f32 v123, v123, v91, v107
	v_fma_f32 v124, v124, v92, v108
	v_fma_f32 v125, v125, v93, v109
	v_fma_f32 v126, v126, v94, v110
	v_fma_f32 v127, v127, v95, v111
	v_fma_f32 v128, v128, v96, v112
	v_fma_f32 v129, v129, v97, v113
	v_fma_f32 v130, v130, v98, v114
	v_fma_f32 v131, v131, v99, v115
	v_fma_f32 v132, v132, v100, v116
	v_fma_f32 v133, v133, v101, v117
	v_fma_f32 v134, v134, v102, v118
	v_fma_f32 v135, v135, v103, v119
	v_cvt_pk_bf16_f32 v156, v120, v121
	v_cvt_pk_bf16_f32 v157, v122, v123
	v_cvt_pk_bf16_f32 v158, v124, v125
	v_cvt_pk_bf16_f32 v159, v126, v127
	v_cvt_pk_bf16_f32 v160, v128, v129
	v_cvt_pk_bf16_f32 v161, v130, v131
	v_cvt_pk_bf16_f32 v162, v132, v133
	v_cvt_pk_bf16_f32 v163, v134, v135
	s_lshl_b32 vcc_lo, s19, 11
	s_add_u32 vcc_lo, vcc_lo, 0x800000
	s_add_u32 s100, s14, vcc_lo
	s_addc_u32 s101, s15, 0
	global_store_dwordx2 v137, v[156:157], s[100:101] offset:0
	global_store_dwordx2 v137, v[158:159], s[100:101] offset:512
	global_store_dwordx2 v137, v[160:161], s[100:101] offset:1024
	global_store_dwordx2 v137, v[162:163], s[100:101] offset:1536
	s_lshl_b32 vcc_lo, s19, 12
	s_add_u32 vcc_lo, vcc_lo, 0x3000000
	s_add_u32 s100, s12, vcc_lo
	s_addc_u32 s101, s13, 0
	global_load_dwordx4 v[32:35], v136, s[100:101] offset:0
	global_load_dwordx4 v[36:39], v136, s[100:101] offset:1024
	global_load_dwordx4 v[40:43], v136, s[100:101] offset:2048
	global_load_dwordx4 v[44:47], v136, s[100:101] offset:3072
	s_lshl_b32 vcc_lo, s19, 11
	s_add_u32 vcc_lo, vcc_lo, 0x1800000
	s_add_u32 s100, s14, vcc_lo
	s_addc_u32 s101, s15, 0
	global_load_dwordx2 v[64:65], v137, s[100:101] offset:0
	global_load_dwordx2 v[66:67], v137, s[100:101] offset:512
	global_load_dwordx2 v[68:69], v137, s[100:101] offset:1024
	global_load_dwordx2 v[70:71], v137, s[100:101] offset:1536
	s_waitcnt vmcnt(48)
; __device__ __forceinline__ void row_phase(const Params& P, int glayer, int layer, int xsrc, bool hasY, int gate_idx, const float* gpost,
;                           int xdst, bool doH, const float* gpre, int sh_idx, int nrows) {
;     ...
;         if (hasY) {
;           float4 yv[4];
;           float ss = 0.f;
; #pragma unroll
;           for (int i = 0; i < 4; ++i) {
;             const uint2 raw = yy[u][i];
;             yv[i].x = bf2f((u16)(raw.x & 0xffff)); yv[i].y = bf2f((u16)(raw.x >> 16));
;             yv[i].z = bf2f((u16)(raw.y & 0xffff)); yv[i].w = bf2f((u16)(raw.y >> 16));
;             ss += yv[i].x * yv[i].x + yv[i].y * yv[i].y + yv[i].z * yv[i].z + yv[i].w * yv[i].w;
;           }
;           ss = wave_sum(ss);
;           const float rstd = __builtin_amdgcn_rsqf(ss * (1.f / 1024.f) + EPSF);
; #pragma unroll
;           for (int i = 0; i < 4; ++i) {
;             const int col = (i * 64 + lane) * 4;
;             const float4 gt = *reinterpret_cast<const float4*>(modg + gate_idx * 1024 + col);
;             const float4 gp = *reinterpret_cast<const float4*>(gpost + col);
;             xv[i].x += gt.x * (yv[i].x * rstd * gp.x); xv[i].y += gt.y * (yv[i].y * rstd * gp.y);
;             xv[i].z += gt.z * (yv[i].z * rstd * gp.z); xv[i].w += gt.w * (yv[i].w * rstd * gp.w);
;           }
;         }
;         if (xdst == 3 || (xdst == 1 && row >= N_X)) {
;           float* xout = (xdst == 3) ? P.out + (long)row * 1024 : P.xc + (long)(row - N_X) * 1024;
; #pragma unroll
;           for (int i = 0; i < 4; ++i) *reinterpret_cast<float4*>(xout + (i * 64 + lane) * 4) = xv[i];
;         } else if (xdst != 0) {
;           u16* xo = ((xdst == 1) ? resA : P.zf) + (long)row * 1024;
; #pragma unroll
;           for (int i = 0; i < 4; ++i) {
;             const unsigned b0 = f2bf(xv[i].x), b1 = f2bf(xv[i].y), b2 = f2bf(xv[i].z), b3 = f2bf(xv[i].w);
;             *reinterpret_cast<uint2*>(xo + (i * 64 + lane) * 4) = make_uint2(b0 | (b1 << 16), b2 | (b3 << 16));
;           }
;         }
;         if (doH) {
;           float ss = 0.f;
; #pragma unroll
;           for (int i = 0; i < 4; ++i) ss += xv[i].x * xv[i].x + xv[i].y * xv[i].y + xv[i].z * xv[i].z + xv[i].w * xv[i].w;
;           ss = wave_sum(ss);
;           const float rstd = __builtin_amdgcn_rsqf(ss * (1.f / 1024.f) + EPSF);
;           u16* h = P.hy + (long)row * 1024;
; #pragma unroll
	v_lshlrev_b32_e32 v120, 16, v182
	v_and_b32_e32 v121, 0xffff0000, v182
	v_lshlrev_b32_e32 v122, 16, v183
	v_and_b32_e32 v123, 0xffff0000, v183
	v_lshlrev_b32_e32 v124, 16, v184
	v_and_b32_e32 v125, 0xffff0000, v184
	v_lshlrev_b32_e32 v126, 16, v185
	v_and_b32_e32 v127, 0xffff0000, v185
	v_lshlrev_b32_e32 v128, 16, v186
	v_and_b32_e32 v129, 0xffff0000, v186
	v_lshlrev_b32_e32 v130, 16, v187
	v_and_b32_e32 v131, 0xffff0000, v187
	v_lshlrev_b32_e32 v132, 16, v188
	v_and_b32_e32 v133, 0xffff0000, v188
	v_lshlrev_b32_e32 v134, 16, v189
	v_and_b32_e32 v135, 0xffff0000, v189
	v_mul_f32_e32 v138, v120, v120
	v_mul_f32_e32 v149, v121, v121
	v_mul_f32_e32 v150, v122, v122
	v_mul_f32_e32 v154, v123, v123
	v_fma_f32 v138, v124, v124, v138
	v_fma_f32 v149, v125, v125, v149
	v_fma_f32 v150, v126, v126, v150
	v_fma_f32 v154, v127, v127, v154
	v_fma_f32 v138, v128, v128, v138
	v_fma_f32 v149, v129, v129, v149
	v_fma_f32 v150, v130, v130, v150
	v_fma_f32 v154, v131, v131, v154
	v_fma_f32 v138, v132, v132, v138
	v_fma_f32 v149, v133, v133, v149
	v_fma_f32 v150, v134, v134, v150
	v_fma_f32 v154, v135, v135, v154
	v_add_f32_e32 v138, v138, v149
	v_add_f32_e32 v150, v150, v154
	v_add_f32_e32 v138, v138, v150
	s_nop 1
	v_add_f32_dpp v138, v138, v138 quad_perm:[1,0,3,2] row_mask:0xf bank_mask:0xf
	s_nop 1
	v_add_f32_dpp v138, v138, v138 quad_perm:[2,3,0,1] row_mask:0xf bank_mask:0xf
	s_nop 1
	v_add_f32_dpp v138, v138, v138 row_half_mirror row_mask:0xf bank_mask:0xf
	s_nop 1
	v_add_f32_dpp v138, v138, v138 row_mirror row_mask:0xf bank_mask:0xf
	v_mov_b32_e32 v139, v138
	s_nop 1
	v_permlane16_swap_b32_e32 v138, v139
	v_add_f32_e32 v138, v138, v139
	v_mov_b32_e32 v139, v138
	s_nop 1
	v_permlane32_swap_b32_e32 v138, v139
	v_add_f32_e32 v138, v138, v139
	v_mul_f32_e32 v138, 0x3a800000, v138
	v_add_f32_e32 v138, 0x358637bd, v138
	v_rsq_f32_e32 v140, v138
	s_nop 0
	v_mul_f32_e32 v120, v120, v140
	v_mul_f32_e32 v121, v121, v140
	v_mul_f32_e32 v122, v122, v140
	v_mul_f32_e32 v123, v123, v140
	v_mul_f32_e32 v124, v124, v140
	v_mul_f32_e32 v125, v125, v140
	v_mul_f32_e32 v126, v126, v140
	v_mul_f32_e32 v127, v127, v140
	v_mul_f32_e32 v128, v128, v140
	v_mul_f32_e32 v129, v129, v140
	v_mul_f32_e32 v130, v130, v140
	v_mul_f32_e32 v131, v131, v140
	v_mul_f32_e32 v132, v132, v140
	v_mul_f32_e32 v133, v133, v140
	v_mul_f32_e32 v134, v134, v140
	v_mul_f32_e32 v135, v135, v140
	v_fma_f32 v166, v120, v72, v166
	v_fma_f32 v167, v121, v73, v167
	v_fma_f32 v168, v122, v74, v168
	v_fma_f32 v169, v123, v75, v169
	v_fma_f32 v170, v124, v76, v170
	v_fma_f32 v171, v125, v77, v171
	v_fma_f32 v172, v126, v78, v172
	v_fma_f32 v173, v127, v79, v173
	v_fma_f32 v174, v128, v80, v174
	v_fma_f32 v175, v129, v81, v175
	v_fma_f32 v176, v130, v82, v176
	v_fma_f32 v177, v131, v83, v177
	v_fma_f32 v178, v132, v84, v178
	v_fma_f32 v179, v133, v85, v179
	v_fma_f32 v180, v134, v86, v180
	v_fma_f32 v181, v135, v87, v181
	v_cvt_pk_bf16_f32 v156, v166, v167
	v_cvt_pk_bf16_f32 v157, v168, v169
	v_cvt_pk_bf16_f32 v158, v170, v171
	v_cvt_pk_bf16_f32 v159, v172, v173
	v_cvt_pk_bf16_f32 v160, v174, v175
	v_cvt_pk_bf16_f32 v161, v176, v177
	v_cvt_pk_bf16_f32 v162, v178, v179
	v_cvt_pk_bf16_f32 v163, v180, v181
	s_lshl_b32 vcc_lo, s19, 11
	s_add_u32 vcc_lo, vcc_lo, 0xc00000
	s_add_u32 s100, s16, vcc_lo
	s_addc_u32 s101, s17, 0
	global_store_dwordx2 v137, v[156:157], s[100:101] offset:0
	global_store_dwordx2 v137, v[158:159], s[100:101] offset:512
	global_store_dwordx2 v137, v[160:161], s[100:101] offset:1024
	global_store_dwordx2 v137, v[162:163], s[100:101] offset:1536
	v_mul_f32_e32 v138, v166, v166
	v_mul_f32_e32 v149, v167, v167
	v_mul_f32_e32 v150, v168, v168
	v_mul_f32_e32 v154, v169, v169
	v_fma_f32 v138, v170, v170, v138
	v_fma_f32 v149, v171, v171, v149
	v_fma_f32 v150, v172, v172, v150
	v_fma_f32 v154, v173, v173, v154
	v_fma_f32 v138, v174, v174, v138
	v_fma_f32 v149, v175, v175, v149
	v_fma_f32 v150, v176, v176, v150
	v_fma_f32 v154, v177, v177, v154
	v_fma_f32 v138, v178, v178, v138
	v_fma_f32 v149, v179, v179, v149
	v_fma_f32 v150, v180, v180, v150
	v_fma_f32 v154, v181, v181, v154
	v_add_f32_e32 v138, v138, v149
	v_add_f32_e32 v150, v150, v154
	v_add_f32_e32 v138, v138, v150
	s_nop 1
	v_add_f32_dpp v138, v138, v138 quad_perm:[1,0,3,2] row_mask:0xf bank_mask:0xf
	s_nop 1
	v_add_f32_dpp v138, v138, v138 quad_perm:[2,3,0,1] row_mask:0xf bank_mask:0xf
	s_nop 1
	v_add_f32_dpp v138, v138, v138 row_half_mirror row_mask:0xf bank_mask:0xf
	s_nop 1
	v_add_f32_dpp v138, v138, v138 row_mirror row_mask:0xf bank_mask:0xf
	v_mov_b32_e32 v139, v138
	s_nop 1
	v_permlane16_swap_b32_e32 v138, v139
	v_add_f32_e32 v138, v138, v139
	v_mov_b32_e32 v139, v138
	s_nop 1
	v_permlane32_swap_b32_e32 v138, v139
	v_add_f32_e32 v138, v138, v139
	v_mul_f32_e32 v138, 0x3a800000, v138
	v_add_f32_e32 v138, 0x358637bd, v138
	v_rsq_f32_e32 v140, v138
	s_nop 0
	v_mul_f32_e32 v120, v166, v140
	v_mul_f32_e32 v121, v167, v140
	v_mul_f32_e32 v122, v168, v140
	v_mul_f32_e32 v123, v169, v140
	v_mul_f32_e32 v124, v170, v140
	v_mul_f32_e32 v125, v171, v140
	v_mul_f32_e32 v126, v172, v140
	v_mul_f32_e32 v127, v173, v140
	v_mul_f32_e32 v128, v174, v140
	v_mul_f32_e32 v129, v175, v140
	v_mul_f32_e32 v130, v176, v140
	v_mul_f32_e32 v131, v177, v140
	v_mul_f32_e32 v132, v178, v140
	v_mul_f32_e32 v133, v179, v140
	v_mul_f32_e32 v134, v180, v140
	v_mul_f32_e32 v135, v181, v140
	v_fma_f32 v120, v120, v88, v104
	v_fma_f32 v121, v121, v89, v105
	v_fma_f32 v122, v122, v90, v106
	v_fma_f32 v123, v123, v91, v107
	v_fma_f32 v124, v124, v92, v108
	v_fma_f32 v125, v125, v93, v109
	v_fma_f32 v126, v126, v94, v110
	v_fma_f32 v127, v127, v95, v111
	v_fma_f32 v128, v128, v96, v112
	v_fma_f32 v129, v129, v97, v113
	v_fma_f32 v130, v130, v98, v114
	v_fma_f32 v131, v131, v99, v115
	v_fma_f32 v132, v132, v100, v116
	v_fma_f32 v133, v133, v101, v117
	v_fma_f32 v134, v134, v102, v118
	v_fma_f32 v135, v135, v103, v119
	v_cvt_pk_bf16_f32 v156, v120, v121
	v_cvt_pk_bf16_f32 v157, v122, v123
	v_cvt_pk_bf16_f32 v158, v124, v125
	v_cvt_pk_bf16_f32 v159, v126, v127
	v_cvt_pk_bf16_f32 v160, v128, v129
	v_cvt_pk_bf16_f32 v161, v130, v131
	v_cvt_pk_bf16_f32 v162, v132, v133
	v_cvt_pk_bf16_f32 v163, v134, v135
	s_lshl_b32 vcc_lo, s19, 11
	s_add_u32 vcc_lo, vcc_lo, 0xc00000
	s_add_u32 s100, s14, vcc_lo
	s_addc_u32 s101, s15, 0
	global_store_dwordx2 v137, v[156:157], s[100:101] offset:0
	global_store_dwordx2 v137, v[158:159], s[100:101] offset:512
	global_store_dwordx2 v137, v[160:161], s[100:101] offset:1024
	global_store_dwordx2 v137, v[162:163], s[100:101] offset:1536
	s_add_u32 s100, s20, 0x8000
	s_addc_u32 s101, s21, 0
	global_load_dwordx4 v[72:75], v136, s[100:101] offset:0
	global_load_dwordx4 v[76:79], v136, s[100:101] offset:1024
	global_load_dwordx4 v[80:83], v136, s[100:101] offset:2048
	global_load_dwordx4 v[84:87], v136, s[100:101] offset:3072
	s_load_dwordx2 s[98:99], s[4:5], 0x38
	s_waitcnt lgkmcnt(0)
; __device__ __forceinline__ void row_phase(const Params& P, int glayer, int layer, int xsrc, bool hasY, int gate_idx, const float* gpost,
;                           int xdst, bool doH, const float* gpre, int sh_idx, int nrows) {
;     ...
;         if (hasY) {
;           float4 yv[4];
;           float ss = 0.f;
; #pragma unroll
;           for (int i = 0; i < 4; ++i) {
;             const uint2 raw = yy[u][i];
;             yv[i].x = bf2f((u16)(raw.x & 0xffff)); yv[i].y = bf2f((u16)(raw.x >> 16));
;             yv[i].z = bf2f((u16)(raw.y & 0xffff)); yv[i].w = bf2f((u16)(raw.y >> 16));
;             ss += yv[i].x * yv[i].x + yv[i].y * yv[i].y + yv[i].z * yv[i].z + yv[i].w * yv[i].w;
;           }
;           ss = wave_sum(ss);
;           const float rstd = __builtin_amdgcn_rsqf(ss * (1.f / 1024.f) + EPSF);
; #pragma unroll
;           for (int i = 0; i < 4; ++i) {
;             const int col = (i * 64 + lane) * 4;
;             const float4 gt = *reinterpret_cast<const float4*>(modg + gate_idx * 1024 + col);
;             const float4 gp = *reinterpret_cast<const float4*>(gpost + col);
;             xv[i].x += gt.x * (yv[i].x * rstd * gp.x); xv[i].y += gt.y * (yv[i].y * rstd * gp.y);
;             xv[i].z += gt.z * (yv[i].z * rstd * gp.z); xv[i].w += gt.w * (yv[i].w * rstd * gp.w);
;           }
;         }
;         if (xdst == 3 || (xdst == 1 && row >= N_X)) {
;           float* xout = (xdst == 3) ? P.out + (long)row * 1024 : P.xc + (long)(row - N_X) * 1024;
; #pragma unroll
;           for (int i = 0; i < 4; ++i) *reinterpret_cast<float4*>(xout + (i * 64 + lane) * 4) = xv[i];
;         } else if (xdst != 0) {
;           u16* xo = ((xdst == 1) ? resA : P.zf) + (long)row * 1024;
; #pragma unroll
;           for (int i = 0; i < 4; ++i) {
;             const unsigned b0 = f2bf(xv[i].x), b1 = f2bf(xv[i].y), b2 = f2bf(xv[i].z), b3 = f2bf(xv[i].w);
;             *reinterpret_cast<uint2*>(xo + (i * 64 + lane) * 4) = make_uint2(b0 | (b1 << 16), b2 | (b3 << 16));
;           }
;         }
;         if (doH) {
;           float ss = 0.f;
; #pragma unroll
;           for (int i = 0; i < 4; ++i) ss += xv[i].x * xv[i].x + xv[i].y * xv[i].y + xv[i].z * xv[i].z + xv[i].w * xv[i].w;
;           ss = wave_sum(ss);
;           const float rstd = __builtin_amdgcn_rsqf(ss * (1.f / 1024.f) + EPSF);
;           u16* h = P.hy + (long)row * 1024;
; #pragma unroll
	global_load_dwordx4 v[120:123], v136, s[98:99] offset:0
	global_load_dwordx4 v[124:127], v136, s[98:99] offset:1024
	global_load_dwordx4 v[128:131], v136, s[98:99] offset:2048
	global_load_dwordx4 v[132:135], v136, s[98:99] offset:3072
	s_add_u32 s100, s20, 0x9000
	s_addc_u32 s101, s21, 0
	global_load_dwordx4 v[104:107], v136, s[100:101] offset:0
	global_load_dwordx4 v[108:111], v136, s[100:101] offset:1024
	global_load_dwordx4 v[112:115], v136, s[100:101] offset:2048
	global_load_dwordx4 v[116:119], v136, s[100:101] offset:3072
	s_add_u32 s100, s100, 0x1000
	s_addc_u32 s101, s101, 0
	global_load_dwordx4 v[166:169], v136, s[100:101] offset:0
	global_load_dwordx4 v[170:173], v136, s[100:101] offset:1024
	global_load_dwordx4 v[174:177], v136, s[100:101] offset:2048
	global_load_dwordx4 v[178:181], v136, s[100:101] offset:3072
	s_load_dwordx2 s[98:99], s[4:5], 0x40
	s_waitcnt lgkmcnt(0)
	global_load_dwordx4 v[88:91], v136, s[98:99] offset:0
	global_load_dwordx4 v[92:95], v136, s[98:99] offset:1024
	global_load_dwordx4 v[96:99], v136, s[98:99] offset:2048
	global_load_dwordx4 v[100:103], v136, s[98:99] offset:3072
	s_waitcnt vmcnt(0)
	v_mul_f32_e32 v72, v72, v120
	v_mul_f32_e32 v73, v73, v121
	v_mul_f32_e32 v74, v74, v122
	v_mul_f32_e32 v75, v75, v123
	v_mul_f32_e32 v76, v76, v124
	v_mul_f32_e32 v77, v77, v125
	v_mul_f32_e32 v78, v78, v126
	v_mul_f32_e32 v79, v79, v127
	v_mul_f32_e32 v80, v80, v128
	v_mul_f32_e32 v81, v81, v129
	v_mul_f32_e32 v82, v82, v130
	v_mul_f32_e32 v83, v83, v131
	v_mul_f32_e32 v84, v84, v132
	v_mul_f32_e32 v85, v85, v133
	v_mul_f32_e32 v86, v86, v134
	v_mul_f32_e32 v87, v87, v135
	v_fma_f32 v88, v88, v166, v88
	v_fma_f32 v89, v89, v167, v89
	v_fma_f32 v90, v90, v168, v90
	v_fma_f32 v91, v91, v169, v91
	v_fma_f32 v92, v92, v170, v92
	v_fma_f32 v93, v93, v171, v93
	v_fma_f32 v94, v94, v172, v94
	v_fma_f32 v95, v95, v173, v95
	v_fma_f32 v96, v96, v174, v96
	v_fma_f32 v97, v97, v175, v97
	v_fma_f32 v98, v98, v176, v98
	v_fma_f32 v99, v99, v177, v99
	v_fma_f32 v100, v100, v178, v100
	v_fma_f32 v101, v101, v179, v101
	v_fma_f32 v102, v102, v180, v102
	v_fma_f32 v103, v103, v181, v103
	s_lshl_b32 vcc_lo, s19, 12
	s_add_u32 vcc_lo, vcc_lo, 0x3800000
	s_add_u32 s100, s12, vcc_lo
	s_addc_u32 s101, s13, 0
	global_load_dwordx4 v[166:169], v136, s[100:101] offset:0
	global_load_dwordx4 v[170:173], v136, s[100:101] offset:1024
	global_load_dwordx4 v[174:177], v136, s[100:101] offset:2048
	global_load_dwordx4 v[178:181], v136, s[100:101] offset:3072
	s_lshl_b32 vcc_lo, s19, 11
	s_add_u32 vcc_lo, vcc_lo, 0x1c00000
	s_add_u32 s100, s14, vcc_lo
	s_addc_u32 s101, s15, 0
	global_load_dwordx2 v[182:183], v137, s[100:101] offset:0
	global_load_dwordx2 v[184:185], v137, s[100:101] offset:512
	global_load_dwordx2 v[186:187], v137, s[100:101] offset:1024
	global_load_dwordx2 v[188:189], v137, s[100:101] offset:1536
	v_lshlrev_b32_e32 v120, 16, v48
	v_and_b32_e32 v121, 0xffff0000, v48
	v_lshlrev_b32_e32 v122, 16, v49
	v_and_b32_e32 v123, 0xffff0000, v49
	v_lshlrev_b32_e32 v124, 16, v50
	v_and_b32_e32 v125, 0xffff0000, v50
	v_lshlrev_b32_e32 v126, 16, v51
	v_and_b32_e32 v127, 0xffff0000, v51
	v_lshlrev_b32_e32 v128, 16, v52
	v_and_b32_e32 v129, 0xffff0000, v52
	v_lshlrev_b32_e32 v130, 16, v53
	v_and_b32_e32 v131, 0xffff0000, v53
	v_lshlrev_b32_e32 v132, 16, v54
	v_and_b32_e32 v133, 0xffff0000, v54
	v_lshlrev_b32_e32 v134, 16, v55
	v_and_b32_e32 v135, 0xffff0000, v55
	v_mul_f32_e32 v138, v120, v120
	v_mul_f32_e32 v149, v121, v121
	v_mul_f32_e32 v150, v122, v122
	v_mul_f32_e32 v154, v123, v123
	v_fma_f32 v138, v124, v124, v138
	v_fma_f32 v149, v125, v125, v149
	v_fma_f32 v150, v126, v126, v150
	v_fma_f32 v154, v127, v127, v154
	v_fma_f32 v138, v128, v128, v138
	v_fma_f32 v149, v129, v129, v149
	v_fma_f32 v150, v130, v130, v150
	v_fma_f32 v154, v131, v131, v154
	v_fma_f32 v138, v132, v132, v138
	v_fma_f32 v149, v133, v133, v149
	v_fma_f32 v150, v134, v134, v150
	v_fma_f32 v154, v135, v135, v154
	v_add_f32_e32 v138, v138, v149
	v_add_f32_e32 v150, v150, v154
	v_add_f32_e32 v138, v138, v150
	s_nop 1
	v_add_f32_dpp v138, v138, v138 quad_perm:[1,0,3,2] row_mask:0xf bank_mask:0xf
	s_nop 1
	v_add_f32_dpp v138, v138, v138 quad_perm:[2,3,0,1] row_mask:0xf bank_mask:0xf
	s_nop 1
	v_add_f32_dpp v138, v138, v138 row_half_mirror row_mask:0xf bank_mask:0xf
	s_nop 1
	v_add_f32_dpp v138, v138, v138 row_mirror row_mask:0xf bank_mask:0xf
	v_mov_b32_e32 v139, v138
	s_nop 1
	v_permlane16_swap_b32_e32 v138, v139
	v_add_f32_e32 v138, v138, v139
	v_mov_b32_e32 v139, v138
	s_nop 1
	v_permlane32_swap_b32_e32 v138, v139
	v_add_f32_e32 v138, v138, v139
	v_mul_f32_e32 v138, 0x3a800000, v138
	v_add_f32_e32 v138, 0x358637bd, v138
	v_rsq_f32_e32 v140, v138
	s_nop 0
	v_mul_f32_e32 v120, v120, v140
	v_mul_f32_e32 v121, v121, v140
	v_mul_f32_e32 v122, v122, v140
	v_mul_f32_e32 v123, v123, v140
	v_mul_f32_e32 v124, v124, v140
	v_mul_f32_e32 v125, v125, v140
	v_mul_f32_e32 v126, v126, v140
	v_mul_f32_e32 v127, v127, v140
	v_mul_f32_e32 v128, v128, v140
	v_mul_f32_e32 v129, v129, v140
	v_mul_f32_e32 v130, v130, v140
	v_mul_f32_e32 v131, v131, v140
	v_mul_f32_e32 v132, v132, v140
	v_mul_f32_e32 v133, v133, v140
	v_mul_f32_e32 v134, v134, v140
	v_mul_f32_e32 v135, v135, v140
	v_fma_f32 v0, v120, v72, v0
	v_fma_f32 v1, v121, v73, v1
	v_fma_f32 v2, v122, v74, v2
	v_fma_f32 v3, v123, v75, v3
	v_fma_f32 v4, v124, v76, v4
	v_fma_f32 v5, v125, v77, v5
	v_fma_f32 v6, v126, v78, v6
	v_fma_f32 v7, v127, v79, v7
	v_fma_f32 v8, v128, v80, v8
	v_fma_f32 v9, v129, v81, v9
	v_fma_f32 v10, v130, v82, v10
	v_fma_f32 v11, v131, v83, v11
	v_fma_f32 v12, v132, v84, v12
	v_fma_f32 v13, v133, v85, v13
; __device__ __forceinline__ void row_phase(const Params& P, int glayer, int layer, int xsrc, bool hasY, int gate_idx, const float* gpost,
;                           int xdst, bool doH, const float* gpre, int sh_idx, int nrows) {
;     ...
;         if (hasY) {
;           float4 yv[4];
;           float ss = 0.f;
; #pragma unroll
;           for (int i = 0; i < 4; ++i) {
;             const uint2 raw = yy[u][i];
;             yv[i].x = bf2f((u16)(raw.x & 0xffff)); yv[i].y = bf2f((u16)(raw.x >> 16));
;             yv[i].z = bf2f((u16)(raw.y & 0xffff)); yv[i].w = bf2f((u16)(raw.y >> 16));
;             ss += yv[i].x * yv[i].x + yv[i].y * yv[i].y + yv[i].z * yv[i].z + yv[i].w * yv[i].w;
;           }
;           ss = wave_sum(ss);
;           const float rstd = __builtin_amdgcn_rsqf(ss * (1.f / 1024.f) + EPSF);
; #pragma unroll
;           for (int i = 0; i < 4; ++i) {
;             const int col = (i * 64 + lane) * 4;
;             const float4 gt = *reinterpret_cast<const float4*>(modg + gate_idx * 1024 + col);
;             const float4 gp = *reinterpret_cast<const float4*>(gpost + col);
;             xv[i].x += gt.x * (yv[i].x * rstd * gp.x); xv[i].y += gt.y * (yv[i].y * rstd * gp.y);
;             xv[i].z += gt.z * (yv[i].z * rstd * gp.z); xv[i].w += gt.w * (yv[i].w * rstd * gp.w);
;           }
;         }
;         if (xdst == 3 || (xdst == 1 && row >= N_X)) {
;           float* xout = (xdst == 3) ? P.out + (long)row * 1024 : P.xc + (long)(row - N_X) * 1024;
; #pragma unroll
;           for (int i = 0; i < 4; ++i) *reinterpret_cast<float4*>(xout + (i * 64 + lane) * 4) = xv[i];
;         } else if (xdst != 0) {
;           u16* xo = ((xdst == 1) ? resA : P.zf) + (long)row * 1024;
; #pragma unroll
;           for (int i = 0; i < 4; ++i) {
;             const unsigned b0 = f2bf(xv[i].x), b1 = f2bf(xv[i].y), b2 = f2bf(xv[i].z), b3 = f2bf(xv[i].w);
;             *reinterpret_cast<uint2*>(xo + (i * 64 + lane) * 4) = make_uint2(b0 | (b1 << 16), b2 | (b3 << 16));
;           }
;         }
;         if (doH) {
;           float ss = 0.f;
; #pragma unroll
;           for (int i = 0; i < 4; ++i) ss += xv[i].x * xv[i].x + xv[i].y * xv[i].y + xv[i].z * xv[i].z + xv[i].w * xv[i].w;
;           ss = wave_sum(ss);
;           const float rstd = __builtin_amdgcn_rsqf(ss * (1.f / 1024.f) + EPSF);
;           u16* h = P.hy + (long)row * 1024;
; #pragma unroll
	v_fma_f32 v14, v134, v86, v14
	v_fma_f32 v15, v135, v87, v15
	v_cvt_pk_bf16_f32 v156, v0, v1
	v_cvt_pk_bf16_f32 v157, v2, v3
	v_cvt_pk_bf16_f32 v158, v4, v5
	v_cvt_pk_bf16_f32 v159, v6, v7
	v_cvt_pk_bf16_f32 v160, v8, v9
	v_cvt_pk_bf16_f32 v161, v10, v11
	v_cvt_pk_bf16_f32 v162, v12, v13
	v_cvt_pk_bf16_f32 v163, v14, v15
	s_lshl_b32 vcc_lo, s19, 11
	s_add_u32 vcc_lo, vcc_lo, 0x1000000
	s_add_u32 s100, s16, vcc_lo
	s_addc_u32 s101, s17, 0
	global_store_dwordx2 v137, v[156:157], s[100:101] offset:0
	global_store_dwordx2 v137, v[158:159], s[100:101] offset:512
	global_store_dwordx2 v137, v[160:161], s[100:101] offset:1024
	global_store_dwordx2 v137, v[162:163], s[100:101] offset:1536
	v_mul_f32_e32 v138, v0, v0
	v_mul_f32_e32 v149, v1, v1
	v_mul_f32_e32 v150, v2, v2
	v_mul_f32_e32 v154, v3, v3
	v_fma_f32 v138, v4, v4, v138
	v_fma_f32 v149, v5, v5, v149
	v_fma_f32 v150, v6, v6, v150
	v_fma_f32 v154, v7, v7, v154
	v_fma_f32 v138, v8, v8, v138
	v_fma_f32 v149, v9, v9, v149
	v_fma_f32 v150, v10, v10, v150
	v_fma_f32 v154, v11, v11, v154
	v_fma_f32 v138, v12, v12, v138
	v_fma_f32 v149, v13, v13, v149
	v_fma_f32 v150, v14, v14, v150
	v_fma_f32 v154, v15, v15, v154
	v_add_f32_e32 v138, v138, v149
	v_add_f32_e32 v150, v150, v154
	v_add_f32_e32 v138, v138, v150
	s_nop 1
	v_add_f32_dpp v138, v138, v138 quad_perm:[1,0,3,2] row_mask:0xf bank_mask:0xf
	s_nop 1
	v_add_f32_dpp v138, v138, v138 quad_perm:[2,3,0,1] row_mask:0xf bank_mask:0xf
	s_nop 1
	v_add_f32_dpp v138, v138, v138 row_half_mirror row_mask:0xf bank_mask:0xf
	s_nop 1
	v_add_f32_dpp v138, v138, v138 row_mirror row_mask:0xf bank_mask:0xf
	v_mov_b32_e32 v139, v138
	s_nop 1
	v_permlane16_swap_b32_e32 v138, v139
	v_add_f32_e32 v138, v138, v139
	v_mov_b32_e32 v139, v138
	s_nop 1
	v_permlane32_swap_b32_e32 v138, v139
	v_add_f32_e32 v138, v138, v139
	v_mul_f32_e32 v138, 0x3a800000, v138
	v_add_f32_e32 v138, 0x358637bd, v138
	v_rsq_f32_e32 v140, v138
	s_nop 0
	v_mul_f32_e32 v120, v0, v140
	v_mul_f32_e32 v121, v1, v140
	v_mul_f32_e32 v122, v2, v140
	v_mul_f32_e32 v123, v3, v140
	v_mul_f32_e32 v124, v4, v140
	v_mul_f32_e32 v125, v5, v140
	v_mul_f32_e32 v126, v6, v140
	v_mul_f32_e32 v127, v7, v140
	v_mul_f32_e32 v128, v8, v140
	v_mul_f32_e32 v129, v9, v140
	v_mul_f32_e32 v130, v10, v140
	v_mul_f32_e32 v131, v11, v140
	v_mul_f32_e32 v132, v12, v140
	v_mul_f32_e32 v133, v13, v140
	v_mul_f32_e32 v134, v14, v140
	v_mul_f32_e32 v135, v15, v140
	v_fma_f32 v120, v120, v88, v104
	v_fma_f32 v121, v121, v89, v105
	v_fma_f32 v122, v122, v90, v106
	v_fma_f32 v123, v123, v91, v107
	v_fma_f32 v124, v124, v92, v108
	v_fma_f32 v125, v125, v93, v109
	v_fma_f32 v126, v126, v94, v110
	v_fma_f32 v127, v127, v95, v111
	v_fma_f32 v128, v128, v96, v112
	v_fma_f32 v129, v129, v97, v113
	v_fma_f32 v130, v130, v98, v114
	v_fma_f32 v131, v131, v99, v115
	v_fma_f32 v132, v132, v100, v116
	v_fma_f32 v133, v133, v101, v117
	v_fma_f32 v134, v134, v102, v118
	v_fma_f32 v135, v135, v103, v119
	v_cvt_pk_bf16_f32 v156, v120, v121
	v_cvt_pk_bf16_f32 v157, v122, v123
	v_cvt_pk_bf16_f32 v158, v124, v125
	v_cvt_pk_bf16_f32 v159, v126, v127
	v_cvt_pk_bf16_f32 v160, v128, v129
	v_cvt_pk_bf16_f32 v161, v130, v131
	v_cvt_pk_bf16_f32 v162, v132, v133
	v_cvt_pk_bf16_f32 v163, v134, v135
	s_lshl_b32 vcc_lo, s19, 11
	s_add_u32 vcc_lo, vcc_lo, 0x1000000
	s_add_u32 s100, s14, vcc_lo
	s_addc_u32 s101, s15, 0
	global_store_dwordx2 v137, v[156:157], s[100:101] offset:0
	global_store_dwordx2 v137, v[158:159], s[100:101] offset:512
	global_store_dwordx2 v137, v[160:161], s[100:101] offset:1024
	global_store_dwordx2 v137, v[162:163], s[100:101] offset:1536
	s_lshl_b32 vcc_lo, s19, 12
	s_add_u32 vcc_lo, vcc_lo, 0x4000000
	s_add_u32 s100, s12, vcc_lo
	s_addc_u32 s101, s13, 0
	global_load_dwordx4 v[0:3], v136, s[100:101] offset:0
	global_load_dwordx4 v[4:7], v136, s[100:101] offset:1024
	global_load_dwordx4 v[8:11], v136, s[100:101] offset:2048
	global_load_dwordx4 v[12:15], v136, s[100:101] offset:3072
	s_lshl_b32 vcc_lo, s19, 11
	s_add_u32 vcc_lo, vcc_lo, 0x2000000
	s_add_u32 s100, s14, vcc_lo
	s_addc_u32 s101, s15, 0
	global_load_dwordx2 v[48:49], v137, s[100:101] offset:0
	global_load_dwordx2 v[50:51], v137, s[100:101] offset:512
	global_load_dwordx2 v[52:53], v137, s[100:101] offset:1024
	global_load_dwordx2 v[54:55], v137, s[100:101] offset:1536
	v_lshlrev_b32_e32 v120, 16, v56
	v_and_b32_e32 v121, 0xffff0000, v56
	v_lshlrev_b32_e32 v122, 16, v57
	v_and_b32_e32 v123, 0xffff0000, v57
	v_lshlrev_b32_e32 v124, 16, v58
	v_and_b32_e32 v125, 0xffff0000, v58
	v_lshlrev_b32_e32 v126, 16, v59
	v_and_b32_e32 v127, 0xffff0000, v59
	v_lshlrev_b32_e32 v128, 16, v60
	v_and_b32_e32 v129, 0xffff0000, v60
	v_lshlrev_b32_e32 v130, 16, v61
	v_and_b32_e32 v131, 0xffff0000, v61
	v_lshlrev_b32_e32 v132, 16, v62
	v_and_b32_e32 v133, 0xffff0000, v62
	v_lshlrev_b32_e32 v134, 16, v63
	v_and_b32_e32 v135, 0xffff0000, v63
	v_mul_f32_e32 v138, v120, v120
	v_mul_f32_e32 v149, v121, v121
	v_mul_f32_e32 v150, v122, v122
	v_mul_f32_e32 v154, v123, v123
	v_fma_f32 v138, v124, v124, v138
	v_fma_f32 v149, v125, v125, v149
	v_fma_f32 v150, v126, v126, v150
	v_fma_f32 v154, v127, v127, v154
	v_fma_f32 v138, v128, v128, v138
	v_fma_f32 v149, v129, v129, v149
	v_fma_f32 v150, v130, v130, v150
	v_fma_f32 v154, v131, v131, v154
	v_fma_f32 v138, v132, v132, v138
	v_fma_f32 v149, v133, v133, v149
	v_fma_f32 v150, v134, v134, v150
	v_fma_f32 v154, v135, v135, v154
	v_add_f32_e32 v138, v138, v149
	v_add_f32_e32 v150, v150, v154
	v_add_f32_e32 v138, v138, v150
	s_nop 1
	v_add_f32_dpp v138, v138, v138 quad_perm:[1,0,3,2] row_mask:0xf bank_mask:0xf
	s_nop 1
	v_add_f32_dpp v138, v138, v138 quad_perm:[2,3,0,1] row_mask:0xf bank_mask:0xf
; __device__ __forceinline__ void row_phase(const Params& P, int glayer, int layer, int xsrc, bool hasY, int gate_idx, const float* gpost,
;                           int xdst, bool doH, const float* gpre, int sh_idx, int nrows) {
;     ...
;         if (hasY) {
;           float4 yv[4];
;           float ss = 0.f;
; #pragma unroll
;           for (int i = 0; i < 4; ++i) {
;             const uint2 raw = yy[u][i];
;             yv[i].x = bf2f((u16)(raw.x & 0xffff)); yv[i].y = bf2f((u16)(raw.x >> 16));
;             yv[i].z = bf2f((u16)(raw.y & 0xffff)); yv[i].w = bf2f((u16)(raw.y >> 16));
;             ss += yv[i].x * yv[i].x + yv[i].y * yv[i].y + yv[i].z * yv[i].z + yv[i].w * yv[i].w;
;           }
;           ss = wave_sum(ss);
;           const float rstd = __builtin_amdgcn_rsqf(ss * (1.f / 1024.f) + EPSF);
; #pragma unroll
;           for (int i = 0; i < 4; ++i) {
;             const int col = (i * 64 + lane) * 4;
;             const float4 gt = *reinterpret_cast<const float4*>(modg + gate_idx * 1024 + col);
;             const float4 gp = *reinterpret_cast<const float4*>(gpost + col);
;             xv[i].x += gt.x * (yv[i].x * rstd * gp.x); xv[i].y += gt.y * (yv[i].y * rstd * gp.y);
;             xv[i].z += gt.z * (yv[i].z * rstd * gp.z); xv[i].w += gt.w * (yv[i].w * rstd * gp.w);
;           }
;         }
;         if (xdst == 3 || (xdst == 1 && row >= N_X)) {
;           float* xout = (xdst == 3) ? P.out + (long)row * 1024 : P.xc + (long)(row - N_X) * 1024;
; #pragma unroll
;           for (int i = 0; i < 4; ++i) *reinterpret_cast<float4*>(xout + (i * 64 + lane) * 4) = xv[i];
;         } else if (xdst != 0) {
;           u16* xo = ((xdst == 1) ? resA : P.zf) + (long)row * 1024;
; #pragma unroll
;           for (int i = 0; i < 4; ++i) {
;             const unsigned b0 = f2bf(xv[i].x), b1 = f2bf(xv[i].y), b2 = f2bf(xv[i].z), b3 = f2bf(xv[i].w);
;             *reinterpret_cast<uint2*>(xo + (i * 64 + lane) * 4) = make_uint2(b0 | (b1 << 16), b2 | (b3 << 16));
;           }
;         }
;         if (doH) {
;           float ss = 0.f;
; #pragma unroll
;           for (int i = 0; i < 4; ++i) ss += xv[i].x * xv[i].x + xv[i].y * xv[i].y + xv[i].z * xv[i].z + xv[i].w * xv[i].w;
;           ss = wave_sum(ss);
;           const float rstd = __builtin_amdgcn_rsqf(ss * (1.f / 1024.f) + EPSF);
;           u16* h = P.hy + (long)row * 1024;
; #pragma unroll
	s_nop 1
	v_add_f32_dpp v138, v138, v138 row_half_mirror row_mask:0xf bank_mask:0xf
	s_nop 1
	v_add_f32_dpp v138, v138, v138 row_mirror row_mask:0xf bank_mask:0xf
	v_mov_b32_e32 v139, v138
	s_nop 1
	v_permlane16_swap_b32_e32 v138, v139
	v_add_f32_e32 v138, v138, v139
	v_mov_b32_e32 v139, v138
	s_nop 1
	v_permlane32_swap_b32_e32 v138, v139
	v_add_f32_e32 v138, v138, v139
	v_mul_f32_e32 v138, 0x3a800000, v138
	v_add_f32_e32 v138, 0x358637bd, v138
	v_rsq_f32_e32 v140, v138
	s_nop 0
	v_mul_f32_e32 v120, v120, v140
	v_mul_f32_e32 v121, v121, v140
	v_mul_f32_e32 v122, v122, v140
	v_mul_f32_e32 v123, v123, v140
	v_mul_f32_e32 v124, v124, v140
	v_mul_f32_e32 v125, v125, v140
	v_mul_f32_e32 v126, v126, v140
	v_mul_f32_e32 v127, v127, v140
	v_mul_f32_e32 v128, v128, v140
	v_mul_f32_e32 v129, v129, v140
	v_mul_f32_e32 v130, v130, v140
	v_mul_f32_e32 v131, v131, v140
	v_mul_f32_e32 v132, v132, v140
	v_mul_f32_e32 v133, v133, v140
	v_mul_f32_e32 v134, v134, v140
	v_mul_f32_e32 v135, v135, v140
	v_fma_f32 v16, v120, v72, v16
	v_fma_f32 v17, v121, v73, v17
	v_fma_f32 v18, v122, v74, v18
	v_fma_f32 v19, v123, v75, v19
	v_fma_f32 v20, v124, v76, v20
	v_fma_f32 v21, v125, v77, v21
	v_fma_f32 v22, v126, v78, v22
	v_fma_f32 v23, v127, v79, v23
	v_fma_f32 v24, v128, v80, v24
	v_fma_f32 v25, v129, v81, v25
	v_fma_f32 v26, v130, v82, v26
	v_fma_f32 v27, v131, v83, v27
	v_fma_f32 v28, v132, v84, v28
	v_fma_f32 v29, v133, v85, v29
	v_fma_f32 v30, v134, v86, v30
	v_fma_f32 v31, v135, v87, v31
	v_cvt_pk_bf16_f32 v156, v16, v17
	v_cvt_pk_bf16_f32 v157, v18, v19
	v_cvt_pk_bf16_f32 v158, v20, v21
	v_cvt_pk_bf16_f32 v159, v22, v23
	v_cvt_pk_bf16_f32 v160, v24, v25
	v_cvt_pk_bf16_f32 v161, v26, v27
	v_cvt_pk_bf16_f32 v162, v28, v29
	v_cvt_pk_bf16_f32 v163, v30, v31
	s_lshl_b32 vcc_lo, s19, 11
	s_add_u32 vcc_lo, vcc_lo, 0x1400000
	s_add_u32 s100, s16, vcc_lo
	s_addc_u32 s101, s17, 0
	global_store_dwordx2 v137, v[156:157], s[100:101] offset:0
	global_store_dwordx2 v137, v[158:159], s[100:101] offset:512
	global_store_dwordx2 v137, v[160:161], s[100:101] offset:1024
	global_store_dwordx2 v137, v[162:163], s[100:101] offset:1536
	v_mul_f32_e32 v138, v16, v16
	v_mul_f32_e32 v149, v17, v17
	v_mul_f32_e32 v150, v18, v18
	v_mul_f32_e32 v154, v19, v19
	v_fma_f32 v138, v20, v20, v138
	v_fma_f32 v149, v21, v21, v149
	v_fma_f32 v150, v22, v22, v150
	v_fma_f32 v154, v23, v23, v154
	v_fma_f32 v138, v24, v24, v138
	v_fma_f32 v149, v25, v25, v149
	v_fma_f32 v150, v26, v26, v150
	v_fma_f32 v154, v27, v27, v154
	v_fma_f32 v138, v28, v28, v138
	v_fma_f32 v149, v29, v29, v149
	v_fma_f32 v150, v30, v30, v150
	v_fma_f32 v154, v31, v31, v154
	v_add_f32_e32 v138, v138, v149
	v_add_f32_e32 v150, v150, v154
	v_add_f32_e32 v138, v138, v150
	s_nop 1
	v_add_f32_dpp v138, v138, v138 quad_perm:[1,0,3,2] row_mask:0xf bank_mask:0xf
	s_nop 1
	v_add_f32_dpp v138, v138, v138 quad_perm:[2,3,0,1] row_mask:0xf bank_mask:0xf
	s_nop 1
	v_add_f32_dpp v138, v138, v138 row_half_mirror row_mask:0xf bank_mask:0xf
	s_nop 1
	v_add_f32_dpp v138, v138, v138 row_mirror row_mask:0xf bank_mask:0xf
	v_mov_b32_e32 v139, v138
	s_nop 1
	v_permlane16_swap_b32_e32 v138, v139
	v_add_f32_e32 v138, v138, v139
	v_mov_b32_e32 v139, v138
	s_nop 1
	v_permlane32_swap_b32_e32 v138, v139
	v_add_f32_e32 v138, v138, v139
	v_mul_f32_e32 v138, 0x3a800000, v138
	v_add_f32_e32 v138, 0x358637bd, v138
	v_rsq_f32_e32 v140, v138
	s_nop 0
	v_mul_f32_e32 v120, v16, v140
	v_mul_f32_e32 v121, v17, v140
	v_mul_f32_e32 v122, v18, v140
	v_mul_f32_e32 v123, v19, v140
	v_mul_f32_e32 v124, v20, v140
	v_mul_f32_e32 v125, v21, v140
	v_mul_f32_e32 v126, v22, v140
	v_mul_f32_e32 v127, v23, v140
	v_mul_f32_e32 v128, v24, v140
	v_mul_f32_e32 v129, v25, v140
	v_mul_f32_e32 v130, v26, v140
	v_mul_f32_e32 v131, v27, v140
	v_mul_f32_e32 v132, v28, v140
	v_mul_f32_e32 v133, v29, v140
	v_mul_f32_e32 v134, v30, v140
	v_mul_f32_e32 v135, v31, v140
	v_fma_f32 v120, v120, v88, v104
	v_fma_f32 v121, v121, v89, v105
	v_fma_f32 v122, v122, v90, v106
	v_fma_f32 v123, v123, v91, v107
	v_fma_f32 v124, v124, v92, v108
	v_fma_f32 v125, v125, v93, v109
	v_fma_f32 v126, v126, v94, v110
	v_fma_f32 v127, v127, v95, v111
	v_fma_f32 v128, v128, v96, v112
	v_fma_f32 v129, v129, v97, v113
	v_fma_f32 v130, v130, v98, v114
	v_fma_f32 v131, v131, v99, v115
	v_fma_f32 v132, v132, v100, v116
	v_fma_f32 v133, v133, v101, v117
	v_fma_f32 v134, v134, v102, v118
	v_fma_f32 v135, v135, v103, v119
	v_cvt_pk_bf16_f32 v156, v120, v121
	v_cvt_pk_bf16_f32 v157, v122, v123
	v_cvt_pk_bf16_f32 v158, v124, v125
	v_cvt_pk_bf16_f32 v159, v126, v127
	v_cvt_pk_bf16_f32 v160, v128, v129
	v_cvt_pk_bf16_f32 v161, v130, v131
	v_cvt_pk_bf16_f32 v162, v132, v133
	v_cvt_pk_bf16_f32 v163, v134, v135
	s_lshl_b32 vcc_lo, s19, 11
	s_add_u32 vcc_lo, vcc_lo, 0x1400000
	s_add_u32 s100, s14, vcc_lo
	s_addc_u32 s101, s15, 0
	global_store_dwordx2 v137, v[156:157], s[100:101] offset:0
	global_store_dwordx2 v137, v[158:159], s[100:101] offset:512
	global_store_dwordx2 v137, v[160:161], s[100:101] offset:1024
	global_store_dwordx2 v137, v[162:163], s[100:101] offset:1536
	s_lshl_b32 vcc_lo, s19, 12
	s_add_u32 vcc_lo, vcc_lo, 0x4800000
	s_add_u32 s100, s12, vcc_lo
	s_addc_u32 s101, s13, 0
	global_load_dwordx4 v[16:19], v136, s[100:101] offset:0
	global_load_dwordx4 v[20:23], v136, s[100:101] offset:1024
	global_load_dwordx4 v[24:27], v136, s[100:101] offset:2048
	global_load_dwordx4 v[28:31], v136, s[100:101] offset:3072
	s_lshl_b32 vcc_lo, s19, 11
	s_add_u32 vcc_lo, vcc_lo, 0x2400000
	s_add_u32 s100, s14, vcc_lo
	s_addc_u32 s101, s15, 0
	global_load_dwordx2 v[56:57], v137, s[100:101] offset:0
	global_load_dwordx2 v[58:59], v137, s[100:101] offset:512
; __device__ __forceinline__ float bf2f(u16 h) { return __uint_as_float(((unsigned)h) << 16); }
; __device__ __forceinline__ void row_phase(const Params& P, int glayer, int layer, int xsrc, bool hasY, int gate_idx, const float* gpost,
;                           int xdst, bool doH, const float* gpre, int sh_idx, int nrows) {
;     ...
;         if (hasY) {
;           float4 yv[4];
;           float ss = 0.f;
; #pragma unroll
;           for (int i = 0; i < 4; ++i) {
;             const uint2 raw = yy[u][i];
;             yv[i].x = bf2f((u16)(raw.x & 0xffff)); yv[i].y = bf2f((u16)(raw.x >> 16));
;             yv[i].z = bf2f((u16)(raw.y & 0xffff)); yv[i].w = bf2f((u16)(raw.y >> 16));
;             ss += yv[i].x * yv[i].x + yv[i].y * yv[i].y + yv[i].z * yv[i].z + yv[i].w * yv[i].w;
;           }
;           ss = wave_sum(ss);
;           const float rstd = __builtin_amdgcn_rsqf(ss * (1.f / 1024.f) + EPSF);
; #pragma unroll
;           for (int i = 0; i < 4; ++i) {
;             const int col = (i * 64 + lane) * 4;
;             const float4 gt = *reinterpret_cast<const float4*>(modg + gate_idx * 1024 + col);
;             const float4 gp = *reinterpret_cast<const float4*>(gpost + col);
;             xv[i].x += gt.x * (yv[i].x * rstd * gp.x); xv[i].y += gt.y * (yv[i].y * rstd * gp.y);
;             xv[i].z += gt.z * (yv[i].z * rstd * gp.z); xv[i].w += gt.w * (yv[i].w * rstd * gp.w);
;           }
;         }
;         if (xdst == 3 || (xdst == 1 && row >= N_X)) {
;           float* xout = (xdst == 3) ? P.out + (long)row * 1024 : P.xc + (long)(row - N_X) * 1024;
; #pragma unroll
;           for (int i = 0; i < 4; ++i) *reinterpret_cast<float4*>(xout + (i * 64 + lane) * 4) = xv[i];
;         } else if (xdst != 0) {
;           u16* xo = ((xdst == 1) ? resA : P.zf) + (long)row * 1024;
; #pragma unroll
;           for (int i = 0; i < 4; ++i) {
;             const unsigned b0 = f2bf(xv[i].x), b1 = f2bf(xv[i].y), b2 = f2bf(xv[i].z), b3 = f2bf(xv[i].w);
;             *reinterpret_cast<uint2*>(xo + (i * 64 + lane) * 4) = make_uint2(b0 | (b1 << 16), b2 | (b3 << 16));
;           }
;         }
	global_load_dwordx2 v[60:61], v137, s[100:101] offset:1024
	global_load_dwordx2 v[62:63], v137, s[100:101] offset:1536
	v_lshlrev_b32_e32 v120, 16, v64
	v_and_b32_e32 v121, 0xffff0000, v64
	v_lshlrev_b32_e32 v122, 16, v65
	v_and_b32_e32 v123, 0xffff0000, v65
	v_lshlrev_b32_e32 v124, 16, v66
	v_and_b32_e32 v125, 0xffff0000, v66
	v_lshlrev_b32_e32 v126, 16, v67
	v_and_b32_e32 v127, 0xffff0000, v67
	v_lshlrev_b32_e32 v128, 16, v68
	v_and_b32_e32 v129, 0xffff0000, v68
	v_lshlrev_b32_e32 v130, 16, v69
	v_and_b32_e32 v131, 0xffff0000, v69
	v_lshlrev_b32_e32 v132, 16, v70
	v_and_b32_e32 v133, 0xffff0000, v70
	v_lshlrev_b32_e32 v134, 16, v71
	v_and_b32_e32 v135, 0xffff0000, v71
	v_mul_f32_e32 v138, v120, v120
	v_mul_f32_e32 v149, v121, v121
	v_mul_f32_e32 v150, v122, v122
	v_mul_f32_e32 v154, v123, v123
	v_fma_f32 v138, v124, v124, v138
	v_fma_f32 v149, v125, v125, v149
	v_fma_f32 v150, v126, v126, v150
	v_fma_f32 v154, v127, v127, v154
	v_fma_f32 v138, v128, v128, v138
	v_fma_f32 v149, v129, v129, v149
	v_fma_f32 v150, v130, v130, v150
	v_fma_f32 v154, v131, v131, v154
	v_fma_f32 v138, v132, v132, v138
	v_fma_f32 v149, v133, v133, v149
	v_fma_f32 v150, v134, v134, v150
	v_fma_f32 v154, v135, v135, v154
	v_add_f32_e32 v138, v138, v149
	v_add_f32_e32 v150, v150, v154
	v_add_f32_e32 v138, v138, v150
	s_nop 1
	v_add_f32_dpp v138, v138, v138 quad_perm:[1,0,3,2] row_mask:0xf bank_mask:0xf
	s_nop 1
	v_add_f32_dpp v138, v138, v138 quad_perm:[2,3,0,1] row_mask:0xf bank_mask:0xf
	s_nop 1
	v_add_f32_dpp v138, v138, v138 row_half_mirror row_mask:0xf bank_mask:0xf
	s_nop 1
	v_add_f32_dpp v138, v138, v138 row_mirror row_mask:0xf bank_mask:0xf
	v_mov_b32_e32 v139, v138
	s_nop 1
	v_permlane16_swap_b32_e32 v138, v139
	v_add_f32_e32 v138, v138, v139
	v_mov_b32_e32 v139, v138
	s_nop 1
	v_permlane32_swap_b32_e32 v138, v139
	v_add_f32_e32 v138, v138, v139
	v_mul_f32_e32 v138, 0x3a800000, v138
	v_add_f32_e32 v138, 0x358637bd, v138
	v_rsq_f32_e32 v140, v138
	s_nop 0
	v_mul_f32_e32 v120, v120, v140
	v_mul_f32_e32 v121, v121, v140
	v_mul_f32_e32 v122, v122, v140
	v_mul_f32_e32 v123, v123, v140
	v_mul_f32_e32 v124, v124, v140
	v_mul_f32_e32 v125, v125, v140
	v_mul_f32_e32 v126, v126, v140
	v_mul_f32_e32 v127, v127, v140
	v_mul_f32_e32 v128, v128, v140
	v_mul_f32_e32 v129, v129, v140
	v_mul_f32_e32 v130, v130, v140
	v_mul_f32_e32 v131, v131, v140
	v_mul_f32_e32 v132, v132, v140
	v_mul_f32_e32 v133, v133, v140
	v_mul_f32_e32 v134, v134, v140
	v_mul_f32_e32 v135, v135, v140
	v_fma_f32 v32, v120, v72, v32
	v_fma_f32 v33, v121, v73, v33
	v_fma_f32 v34, v122, v74, v34
	v_fma_f32 v35, v123, v75, v35
	v_fma_f32 v36, v124, v76, v36
	v_fma_f32 v37, v125, v77, v37
	v_fma_f32 v38, v126, v78, v38
	v_fma_f32 v39, v127, v79, v39
	v_fma_f32 v40, v128, v80, v40
	v_fma_f32 v41, v129, v81, v41
	v_fma_f32 v42, v130, v82, v42
	v_fma_f32 v43, v131, v83, v43
	v_fma_f32 v44, v132, v84, v44
	v_fma_f32 v45, v133, v85, v45
	v_fma_f32 v46, v134, v86, v46
	v_fma_f32 v47, v135, v87, v47
	v_cvt_pk_bf16_f32 v156, v32, v33
	v_cvt_pk_bf16_f32 v157, v34, v35
	v_cvt_pk_bf16_f32 v158, v36, v37
	v_cvt_pk_bf16_f32 v159, v38, v39
	v_cvt_pk_bf16_f32 v160, v40, v41
	v_cvt_pk_bf16_f32 v161, v42, v43
	v_cvt_pk_bf16_f32 v162, v44, v45
	v_cvt_pk_bf16_f32 v163, v46, v47
	s_lshl_b32 vcc_lo, s19, 11
	s_add_u32 vcc_lo, vcc_lo, 0x1800000
	s_add_u32 s100, s16, vcc_lo
	s_addc_u32 s101, s17, 0
	global_store_dwordx2 v137, v[156:157], s[100:101] offset:0
	global_store_dwordx2 v137, v[158:159], s[100:101] offset:512
	global_store_dwordx2 v137, v[160:161], s[100:101] offset:1024
	global_store_dwordx2 v137, v[162:163], s[100:101] offset:1536
	v_mul_f32_e32 v138, v32, v32
	v_mul_f32_e32 v149, v33, v33
	v_mul_f32_e32 v150, v34, v34
	v_mul_f32_e32 v154, v35, v35
	v_fma_f32 v138, v36, v36, v138
	v_fma_f32 v149, v37, v37, v149
	v_fma_f32 v150, v38, v38, v150
	v_fma_f32 v154, v39, v39, v154
	v_fma_f32 v138, v40, v40, v138
	v_fma_f32 v149, v41, v41, v149
	v_fma_f32 v150, v42, v42, v150
	v_fma_f32 v154, v43, v43, v154
	v_fma_f32 v138, v44, v44, v138
	v_fma_f32 v149, v45, v45, v149
	v_fma_f32 v150, v46, v46, v150
	v_fma_f32 v154, v47, v47, v154
	v_add_f32_e32 v138, v138, v149
	v_add_f32_e32 v150, v150, v154
	v_add_f32_e32 v138, v138, v150
	s_nop 1
	v_add_f32_dpp v138, v138, v138 quad_perm:[1,0,3,2] row_mask:0xf bank_mask:0xf
	s_nop 1
	v_add_f32_dpp v138, v138, v138 quad_perm:[2,3,0,1] row_mask:0xf bank_mask:0xf
	s_nop 1
	v_add_f32_dpp v138, v138, v138 row_half_mirror row_mask:0xf bank_mask:0xf
	s_nop 1
	v_add_f32_dpp v138, v138, v138 row_mirror row_mask:0xf bank_mask:0xf
	v_mov_b32_e32 v139, v138
	s_nop 1
	v_permlane16_swap_b32_e32 v138, v139
	v_add_f32_e32 v138, v138, v139
	v_mov_b32_e32 v139, v138
	s_nop 1
	v_permlane32_swap_b32_e32 v138, v139
	v_add_f32_e32 v138, v138, v139
	v_mul_f32_e32 v138, 0x3a800000, v138
	v_add_f32_e32 v138, 0x358637bd, v138
	v_rsq_f32_e32 v140, v138
	s_nop 0
	v_mul_f32_e32 v120, v32, v140
	v_mul_f32_e32 v121, v33, v140
	v_mul_f32_e32 v122, v34, v140
	v_mul_f32_e32 v123, v35, v140
	v_mul_f32_e32 v124, v36, v140
	v_mul_f32_e32 v125, v37, v140
	v_mul_f32_e32 v126, v38, v140
	v_mul_f32_e32 v127, v39, v140
	v_mul_f32_e32 v128, v40, v140
	v_mul_f32_e32 v129, v41, v140
	v_mul_f32_e32 v130, v42, v140
	v_mul_f32_e32 v131, v43, v140
	v_mul_f32_e32 v132, v44, v140
	v_mul_f32_e32 v133, v45, v140
	v_mul_f32_e32 v134, v46, v140
	v_mul_f32_e32 v135, v47, v140
	v_fma_f32 v120, v120, v88, v104
	v_fma_f32 v121, v121, v89, v105
	v_fma_f32 v122, v122, v90, v106
	v_fma_f32 v123, v123, v91, v107
	v_fma_f32 v124, v124, v92, v108
	v_fma_f32 v125, v125, v93, v109
	v_fma_f32 v126, v126, v94, v110
	v_fma_f32 v127, v127, v95, v111
; __device__ __forceinline__ void row_phase(const Params& P, int glayer, int layer, int xsrc, bool hasY, int gate_idx, const float* gpost,
;                           int xdst, bool doH, const float* gpre, int sh_idx, int nrows) {
;     ...
;     for (int u = 0; u < 4; ++u) {
;       const int R = rb + u * stride;
;       if (R < nrows) {
;         if (xsrc != 0 && R < N_X) {
;           const u16* xs_ = ((xsrc == 1) ? resA : P.zf) + (long)R * 1024;
; #pragma unroll
;           for (int i = 0; i < 4; ++i) {
;             const uint2 t2 = *reinterpret_cast<const uint2*>(xs_ + (i * 64 + lane) * 4);
;             xr[u][i].x = t2.x; xr[u][i].y = t2.y;
;           }
;         } else {
;           const float* xin_;
;           if (xsrc == 0) xin_ = R < N_X ? P.x + (long)R * 1024 : P.ctx + (long)(R - N_X) * 1024;
;           else           xin_ = P.xc + (long)(R - N_X) * 1024;
; #pragma unroll
;           for (int i = 0; i < 4; ++i) xr[u][i] = *reinterpret_cast<const uint4*>(xin_ + (i * 64 + lane) * 4);
;         }
;         if (hasY) {
;           const u16* y_ = P.hy + (long)R * 1024;
; #pragma unroll
;     ...
;         if (doH) {
;           float ss = 0.f;
; #pragma unroll
;           for (int i = 0; i < 4; ++i) ss += xv[i].x * xv[i].x + xv[i].y * xv[i].y + xv[i].z * xv[i].z + xv[i].w * xv[i].w;
;           ss = wave_sum(ss);
;           const float rstd = __builtin_amdgcn_rsqf(ss * (1.f / 1024.f) + EPSF);
;           u16* h = P.hy + (long)row * 1024;
; #pragma unroll
;           for (int i = 0; i < 4; ++i) {
;             const int col = (i * 64 + lane) * 4;
;             const float4 g = *reinterpret_cast<const float4*>(gpre + col);
;             const float4 sh = *reinterpret_cast<const float4*>(modp + sh_idx * 1024 + col);
;             const float4 sc = *reinterpret_cast<const float4*>(modp + (sh_idx + 1) * 1024 + col);
;             const unsigned h0 = f2bf(xv[i].x * rstd * g.x * (1.f + sc.x) + sh.x);
;             const unsigned h1 = f2bf(xv[i].y * rstd * g.y * (1.f + sc.y) + sh.y);
;             const unsigned h2 = f2bf(xv[i].z * rstd * g.z * (1.f + sc.z) + sh.z);
;             const unsigned h3 = f2bf(xv[i].w * rstd * g.w * (1.f + sc.w) + sh.w);
;             *reinterpret_cast<uint2*>(h + col) = make_uint2(h0 | (h1 << 16), h2 | (h3 << 16));
;           }
;         }
	v_fma_f32 v128, v128, v96, v112
	v_fma_f32 v129, v129, v97, v113
	v_fma_f32 v130, v130, v98, v114
	v_fma_f32 v131, v131, v99, v115
	v_fma_f32 v132, v132, v100, v116
	v_fma_f32 v133, v133, v101, v117
	v_fma_f32 v134, v134, v102, v118
	v_fma_f32 v135, v135, v103, v119
	v_cvt_pk_bf16_f32 v156, v120, v121
	v_cvt_pk_bf16_f32 v157, v122, v123
	v_cvt_pk_bf16_f32 v158, v124, v125
	v_cvt_pk_bf16_f32 v159, v126, v127
	v_cvt_pk_bf16_f32 v160, v128, v129
	v_cvt_pk_bf16_f32 v161, v130, v131
	v_cvt_pk_bf16_f32 v162, v132, v133
	v_cvt_pk_bf16_f32 v163, v134, v135
	s_lshl_b32 vcc_lo, s19, 11
	s_add_u32 vcc_lo, vcc_lo, 0x1800000
	s_add_u32 s100, s14, vcc_lo
	s_addc_u32 s101, s15, 0
	global_store_dwordx2 v137, v[156:157], s[100:101] offset:0
	global_store_dwordx2 v137, v[158:159], s[100:101] offset:512
	global_store_dwordx2 v137, v[160:161], s[100:101] offset:1024
	global_store_dwordx2 v137, v[162:163], s[100:101] offset:1536
	s_lshl_b32 vcc_lo, s19, 12
	s_add_u32 vcc_lo, vcc_lo, 0x5000000
	s_add_u32 s100, s12, vcc_lo
	s_addc_u32 s101, s13, 0
	global_load_dwordx4 v[32:35], v136, s[100:101] offset:0
	global_load_dwordx4 v[36:39], v136, s[100:101] offset:1024
	global_load_dwordx4 v[40:43], v136, s[100:101] offset:2048
	global_load_dwordx4 v[44:47], v136, s[100:101] offset:3072
	s_lshl_b32 vcc_lo, s19, 11
	s_add_u32 vcc_lo, vcc_lo, 0x2800000
	s_add_u32 s100, s14, vcc_lo
	s_addc_u32 s101, s15, 0
	global_load_dwordx2 v[64:65], v137, s[100:101] offset:0
	global_load_dwordx2 v[66:67], v137, s[100:101] offset:512
	global_load_dwordx2 v[68:69], v137, s[100:101] offset:1024
	global_load_dwordx2 v[70:71], v137, s[100:101] offset:1536
	s_waitcnt vmcnt(48)
	v_lshlrev_b32_e32 v120, 16, v182
	v_and_b32_e32 v121, 0xffff0000, v182
	v_lshlrev_b32_e32 v122, 16, v183
	v_and_b32_e32 v123, 0xffff0000, v183
	v_lshlrev_b32_e32 v124, 16, v184
	v_and_b32_e32 v125, 0xffff0000, v184
	v_lshlrev_b32_e32 v126, 16, v185
	v_and_b32_e32 v127, 0xffff0000, v185
	v_lshlrev_b32_e32 v128, 16, v186
	v_and_b32_e32 v129, 0xffff0000, v186
	v_lshlrev_b32_e32 v130, 16, v187
	v_and_b32_e32 v131, 0xffff0000, v187
	v_lshlrev_b32_e32 v132, 16, v188
	v_and_b32_e32 v133, 0xffff0000, v188
	v_lshlrev_b32_e32 v134, 16, v189
	v_and_b32_e32 v135, 0xffff0000, v189
	v_mul_f32_e32 v138, v120, v120
	v_mul_f32_e32 v149, v121, v121
	v_mul_f32_e32 v150, v122, v122
	v_mul_f32_e32 v154, v123, v123
	v_fma_f32 v138, v124, v124, v138
	v_fma_f32 v149, v125, v125, v149
	v_fma_f32 v150, v126, v126, v150
	v_fma_f32 v154, v127, v127, v154
	v_fma_f32 v138, v128, v128, v138
	v_fma_f32 v149, v129, v129, v149
	v_fma_f32 v150, v130, v130, v150
	v_fma_f32 v154, v131, v131, v154
	v_fma_f32 v138, v132, v132, v138
	v_fma_f32 v149, v133, v133, v149
	v_fma_f32 v150, v134, v134, v150
	v_fma_f32 v154, v135, v135, v154
	v_add_f32_e32 v138, v138, v149
	v_add_f32_e32 v150, v150, v154
	v_add_f32_e32 v138, v138, v150
	s_nop 1
	v_add_f32_dpp v138, v138, v138 quad_perm:[1,0,3,2] row_mask:0xf bank_mask:0xf
	s_nop 1
	v_add_f32_dpp v138, v138, v138 quad_perm:[2,3,0,1] row_mask:0xf bank_mask:0xf
	s_nop 1
	v_add_f32_dpp v138, v138, v138 row_half_mirror row_mask:0xf bank_mask:0xf
	s_nop 1
	v_add_f32_dpp v138, v138, v138 row_mirror row_mask:0xf bank_mask:0xf
	v_mov_b32_e32 v139, v138
	s_nop 1
	v_permlane16_swap_b32_e32 v138, v139
	v_add_f32_e32 v138, v138, v139
	v_mov_b32_e32 v139, v138
	s_nop 1
	v_permlane32_swap_b32_e32 v138, v139
	v_add_f32_e32 v138, v138, v139
	v_mul_f32_e32 v138, 0x3a800000, v138
	v_add_f32_e32 v138, 0x358637bd, v138
	v_rsq_f32_e32 v140, v138
	s_nop 0
	v_mul_f32_e32 v120, v120, v140
	v_mul_f32_e32 v121, v121, v140
	v_mul_f32_e32 v122, v122, v140
	v_mul_f32_e32 v123, v123, v140
	v_mul_f32_e32 v124, v124, v140
	v_mul_f32_e32 v125, v125, v140
	v_mul_f32_e32 v126, v126, v140
	v_mul_f32_e32 v127, v127, v140
	v_mul_f32_e32 v128, v128, v140
	v_mul_f32_e32 v129, v129, v140
	v_mul_f32_e32 v130, v130, v140
	v_mul_f32_e32 v131, v131, v140
	v_mul_f32_e32 v132, v132, v140
	v_mul_f32_e32 v133, v133, v140
	v_mul_f32_e32 v134, v134, v140
	v_mul_f32_e32 v135, v135, v140
	v_fma_f32 v166, v120, v72, v166
	v_fma_f32 v167, v121, v73, v167
	v_fma_f32 v168, v122, v74, v168
	v_fma_f32 v169, v123, v75, v169
	v_fma_f32 v170, v124, v76, v170
	v_fma_f32 v171, v125, v77, v171
	v_fma_f32 v172, v126, v78, v172
	v_fma_f32 v173, v127, v79, v173
	v_fma_f32 v174, v128, v80, v174
	v_fma_f32 v175, v129, v81, v175
	v_fma_f32 v176, v130, v82, v176
	v_fma_f32 v177, v131, v83, v177
	v_fma_f32 v178, v132, v84, v178
	v_fma_f32 v179, v133, v85, v179
	v_fma_f32 v180, v134, v86, v180
	v_fma_f32 v181, v135, v87, v181
	v_cvt_pk_bf16_f32 v156, v166, v167
	v_cvt_pk_bf16_f32 v157, v168, v169
	v_cvt_pk_bf16_f32 v158, v170, v171
	v_cvt_pk_bf16_f32 v159, v172, v173
	v_cvt_pk_bf16_f32 v160, v174, v175
	v_cvt_pk_bf16_f32 v161, v176, v177
	v_cvt_pk_bf16_f32 v162, v178, v179
	v_cvt_pk_bf16_f32 v163, v180, v181
	s_lshl_b32 vcc_lo, s19, 11
	s_add_u32 vcc_lo, vcc_lo, 0x1c00000
	s_add_u32 s100, s16, vcc_lo
	s_addc_u32 s101, s17, 0
	global_store_dwordx2 v137, v[156:157], s[100:101] offset:0
	global_store_dwordx2 v137, v[158:159], s[100:101] offset:512
	global_store_dwordx2 v137, v[160:161], s[100:101] offset:1024
	global_store_dwordx2 v137, v[162:163], s[100:101] offset:1536
	v_mul_f32_e32 v138, v166, v166
	v_mul_f32_e32 v149, v167, v167
	v_mul_f32_e32 v150, v168, v168
	v_mul_f32_e32 v154, v169, v169
	v_fma_f32 v138, v170, v170, v138
	v_fma_f32 v149, v171, v171, v149
	v_fma_f32 v150, v172, v172, v150
	v_fma_f32 v154, v173, v173, v154
	v_fma_f32 v138, v174, v174, v138
	v_fma_f32 v149, v175, v175, v149
	v_fma_f32 v150, v176, v176, v150
	v_fma_f32 v154, v177, v177, v154
	v_fma_f32 v138, v178, v178, v138
; __device__ __forceinline__ void row_phase(const Params& P, int glayer, int layer, int xsrc, bool hasY, int gate_idx, const float* gpost,
;                           int xdst, bool doH, const float* gpre, int sh_idx, int nrows) {
;     ...
; #pragma unroll
;           for (int i = 0; i < 4; ++i) {
;             const int col = (i * 64 + lane) * 4;
;             const float4 gt = *reinterpret_cast<const float4*>(modg + gate_idx * 1024 + col);
;             const float4 gp = *reinterpret_cast<const float4*>(gpost + col);
;             xv[i].x += gt.x * (yv[i].x * rstd * gp.x); xv[i].y += gt.y * (yv[i].y * rstd * gp.y);
;             xv[i].z += gt.z * (yv[i].z * rstd * gp.z); xv[i].w += gt.w * (yv[i].w * rstd * gp.w);
;           }
;     ...
;         if (doH) {
;           float ss = 0.f;
; #pragma unroll
;           for (int i = 0; i < 4; ++i) ss += xv[i].x * xv[i].x + xv[i].y * xv[i].y + xv[i].z * xv[i].z + xv[i].w * xv[i].w;
;           ss = wave_sum(ss);
;           const float rstd = __builtin_amdgcn_rsqf(ss * (1.f / 1024.f) + EPSF);
;           u16* h = P.hy + (long)row * 1024;
; #pragma unroll
;           for (int i = 0; i < 4; ++i) {
;             const int col = (i * 64 + lane) * 4;
;             const float4 g = *reinterpret_cast<const float4*>(gpre + col);
;             const float4 sh = *reinterpret_cast<const float4*>(modp + sh_idx * 1024 + col);
;             const float4 sc = *reinterpret_cast<const float4*>(modp + (sh_idx + 1) * 1024 + col);
;             const unsigned h0 = f2bf(xv[i].x * rstd * g.x * (1.f + sc.x) + sh.x);
;             const unsigned h1 = f2bf(xv[i].y * rstd * g.y * (1.f + sc.y) + sh.y);
;             const unsigned h2 = f2bf(xv[i].z * rstd * g.z * (1.f + sc.z) + sh.z);
;             const unsigned h3 = f2bf(xv[i].w * rstd * g.w * (1.f + sc.w) + sh.w);
;             *reinterpret_cast<uint2*>(h + col) = make_uint2(h0 | (h1 << 16), h2 | (h3 << 16));
;           }
;         }
	v_fma_f32 v149, v179, v179, v149
	v_fma_f32 v150, v180, v180, v150
	v_fma_f32 v154, v181, v181, v154
	v_add_f32_e32 v138, v138, v149
	v_add_f32_e32 v150, v150, v154
	v_add_f32_e32 v138, v138, v150
	s_nop 1
	v_add_f32_dpp v138, v138, v138 quad_perm:[1,0,3,2] row_mask:0xf bank_mask:0xf
	s_nop 1
	v_add_f32_dpp v138, v138, v138 quad_perm:[2,3,0,1] row_mask:0xf bank_mask:0xf
	s_nop 1
	v_add_f32_dpp v138, v138, v138 row_half_mirror row_mask:0xf bank_mask:0xf
	s_nop 1
	v_add_f32_dpp v138, v138, v138 row_mirror row_mask:0xf bank_mask:0xf
	v_mov_b32_e32 v139, v138
	s_nop 1
	v_permlane16_swap_b32_e32 v138, v139
	v_add_f32_e32 v138, v138, v139
	v_mov_b32_e32 v139, v138
	s_nop 1
	v_permlane32_swap_b32_e32 v138, v139
	v_add_f32_e32 v138, v138, v139
	v_mul_f32_e32 v138, 0x3a800000, v138
	v_add_f32_e32 v138, 0x358637bd, v138
	v_rsq_f32_e32 v140, v138
	s_nop 0
	v_mul_f32_e32 v120, v166, v140
	v_mul_f32_e32 v121, v167, v140
	v_mul_f32_e32 v122, v168, v140
	v_mul_f32_e32 v123, v169, v140
	v_mul_f32_e32 v124, v170, v140
	v_mul_f32_e32 v125, v171, v140
	v_mul_f32_e32 v126, v172, v140
	v_mul_f32_e32 v127, v173, v140
	v_mul_f32_e32 v128, v174, v140
	v_mul_f32_e32 v129, v175, v140
	v_mul_f32_e32 v130, v176, v140
	v_mul_f32_e32 v131, v177, v140
	v_mul_f32_e32 v132, v178, v140
	v_mul_f32_e32 v133, v179, v140
	v_mul_f32_e32 v134, v180, v140
	v_mul_f32_e32 v135, v181, v140
	v_fma_f32 v120, v120, v88, v104
	v_fma_f32 v121, v121, v89, v105
	v_fma_f32 v122, v122, v90, v106
	v_fma_f32 v123, v123, v91, v107
	v_fma_f32 v124, v124, v92, v108
	v_fma_f32 v125, v125, v93, v109
	v_fma_f32 v126, v126, v94, v110
	v_fma_f32 v127, v127, v95, v111
	v_fma_f32 v128, v128, v96, v112
	v_fma_f32 v129, v129, v97, v113
	v_fma_f32 v130, v130, v98, v114
	v_fma_f32 v131, v131, v99, v115
	v_fma_f32 v132, v132, v100, v116
	v_fma_f32 v133, v133, v101, v117
	v_fma_f32 v134, v134, v102, v118
	v_fma_f32 v135, v135, v103, v119
	v_cvt_pk_bf16_f32 v156, v120, v121
	v_cvt_pk_bf16_f32 v157, v122, v123
	v_cvt_pk_bf16_f32 v158, v124, v125
	v_cvt_pk_bf16_f32 v159, v126, v127
	v_cvt_pk_bf16_f32 v160, v128, v129
	v_cvt_pk_bf16_f32 v161, v130, v131
	v_cvt_pk_bf16_f32 v162, v132, v133
	v_cvt_pk_bf16_f32 v163, v134, v135
	s_lshl_b32 vcc_lo, s19, 11
	s_add_u32 vcc_lo, vcc_lo, 0x1c00000
	s_add_u32 s100, s14, vcc_lo
	s_addc_u32 s101, s15, 0
	global_store_dwordx2 v137, v[156:157], s[100:101] offset:0
	global_store_dwordx2 v137, v[158:159], s[100:101] offset:512
	global_store_dwordx2 v137, v[160:161], s[100:101] offset:1024
	global_store_dwordx2 v137, v[162:163], s[100:101] offset:1536
	s_add_u32 s100, s20, 0xe000
	s_addc_u32 s101, s21, 0
	global_load_dwordx4 v[72:75], v136, s[100:101] offset:0
	global_load_dwordx4 v[76:79], v136, s[100:101] offset:1024
	global_load_dwordx4 v[80:83], v136, s[100:101] offset:2048
	global_load_dwordx4 v[84:87], v136, s[100:101] offset:3072
	s_load_dwordx2 s[98:99], s[4:5], 0x38
	s_waitcnt lgkmcnt(0)
	global_load_dwordx4 v[120:123], v136, s[98:99] offset:0
	global_load_dwordx4 v[124:127], v136, s[98:99] offset:1024
	global_load_dwordx4 v[128:131], v136, s[98:99] offset:2048
	global_load_dwordx4 v[132:135], v136, s[98:99] offset:3072
	s_add_u32 s100, s20, 0xf000
	s_addc_u32 s101, s21, 0
	global_load_dwordx4 v[104:107], v136, s[100:101] offset:0
	global_load_dwordx4 v[108:111], v136, s[100:101] offset:1024
	global_load_dwordx4 v[112:115], v136, s[100:101] offset:2048
	global_load_dwordx4 v[116:119], v136, s[100:101] offset:3072
	s_add_u32 s100, s100, 0x1000
	s_addc_u32 s101, s101, 0
	global_load_dwordx4 v[166:169], v136, s[100:101] offset:0
	global_load_dwordx4 v[170:173], v136, s[100:101] offset:1024
	global_load_dwordx4 v[174:177], v136, s[100:101] offset:2048
	global_load_dwordx4 v[178:181], v136, s[100:101] offset:3072
	s_load_dwordx2 s[98:99], s[4:5], 0x40
	s_waitcnt lgkmcnt(0)
	global_load_dwordx4 v[88:91], v136, s[98:99] offset:0
	global_load_dwordx4 v[92:95], v136, s[98:99] offset:1024
	global_load_dwordx4 v[96:99], v136, s[98:99] offset:2048
	global_load_dwordx4 v[100:103], v136, s[98:99] offset:3072
	s_waitcnt vmcnt(0)
	v_mul_f32_e32 v72, v72, v120
	v_mul_f32_e32 v73, v73, v121
	v_mul_f32_e32 v74, v74, v122
	v_mul_f32_e32 v75, v75, v123
	v_mul_f32_e32 v76, v76, v124
	v_mul_f32_e32 v77, v77, v125
	v_mul_f32_e32 v78, v78, v126
	v_mul_f32_e32 v79, v79, v127
	v_mul_f32_e32 v80, v80, v128
	v_mul_f32_e32 v81, v81, v129
	v_mul_f32_e32 v82, v82, v130
	v_mul_f32_e32 v83, v83, v131
	v_mul_f32_e32 v84, v84, v132
	v_mul_f32_e32 v85, v85, v133
	v_mul_f32_e32 v86, v86, v134
	v_mul_f32_e32 v87, v87, v135
	v_fma_f32 v88, v88, v166, v88
	v_fma_f32 v89, v89, v167, v89
	v_fma_f32 v90, v90, v168, v90
	v_fma_f32 v91, v91, v169, v91
	v_fma_f32 v92, v92, v170, v92
	v_fma_f32 v93, v93, v171, v93
	v_fma_f32 v94, v94, v172, v94
	v_fma_f32 v95, v95, v173, v95
	v_fma_f32 v96, v96, v174, v96
	v_fma_f32 v97, v97, v175, v97
	v_fma_f32 v98, v98, v176, v98
	v_fma_f32 v99, v99, v177, v99
	v_fma_f32 v100, v100, v178, v100
	v_fma_f32 v101, v101, v179, v101
	v_fma_f32 v102, v102, v180, v102
	v_fma_f32 v103, v103, v181, v103
	s_lshl_b32 vcc_lo, s19, 12
	s_add_u32 vcc_lo, vcc_lo, 0x5800000
	s_add_u32 s100, s12, vcc_lo
	s_addc_u32 s101, s13, 0
	global_load_dwordx4 v[166:169], v136, s[100:101] offset:0
	global_load_dwordx4 v[170:173], v136, s[100:101] offset:1024
	global_load_dwordx4 v[174:177], v136, s[100:101] offset:2048
	global_load_dwordx4 v[178:181], v136, s[100:101] offset:3072
	s_lshl_b32 vcc_lo, s19, 11
	s_add_u32 vcc_lo, vcc_lo, 0x2c00000
	s_add_u32 s100, s14, vcc_lo
	s_addc_u32 s101, s15, 0
	global_load_dwordx2 v[182:183], v137, s[100:101] offset:0
	global_load_dwordx2 v[184:185], v137, s[100:101] offset:512
; __device__ __forceinline__ float bf2f(u16 h) { return __uint_as_float(((unsigned)h) << 16); }
; __device__ __forceinline__ void row_phase(const Params& P, int glayer, int layer, int xsrc, bool hasY, int gate_idx, const float* gpost,
;                           int xdst, bool doH, const float* gpre, int sh_idx, int nrows) {
;     ...
;         if (hasY) {
;           float4 yv[4];
;           float ss = 0.f;
; #pragma unroll
;           for (int i = 0; i < 4; ++i) {
;             const uint2 raw = yy[u][i];
;             yv[i].x = bf2f((u16)(raw.x & 0xffff)); yv[i].y = bf2f((u16)(raw.x >> 16));
;             yv[i].z = bf2f((u16)(raw.y & 0xffff)); yv[i].w = bf2f((u16)(raw.y >> 16));
;             ss += yv[i].x * yv[i].x + yv[i].y * yv[i].y + yv[i].z * yv[i].z + yv[i].w * yv[i].w;
;           }
;           ss = wave_sum(ss);
;           const float rstd = __builtin_amdgcn_rsqf(ss * (1.f / 1024.f) + EPSF);
; #pragma unroll
;           for (int i = 0; i < 4; ++i) {
;             const int col = (i * 64 + lane) * 4;
;             const float4 gt = *reinterpret_cast<const float4*>(modg + gate_idx * 1024 + col);
;             const float4 gp = *reinterpret_cast<const float4*>(gpost + col);
;             xv[i].x += gt.x * (yv[i].x * rstd * gp.x); xv[i].y += gt.y * (yv[i].y * rstd * gp.y);
;             xv[i].z += gt.z * (yv[i].z * rstd * gp.z); xv[i].w += gt.w * (yv[i].w * rstd * gp.w);
;           }
;         }
;         if (xdst == 3 || (xdst == 1 && row >= N_X)) {
;           float* xout = (xdst == 3) ? P.out + (long)row * 1024 : P.xc + (long)(row - N_X) * 1024;
; #pragma unroll
;           for (int i = 0; i < 4; ++i) *reinterpret_cast<float4*>(xout + (i * 64 + lane) * 4) = xv[i];
;         } else if (xdst != 0) {
;           u16* xo = ((xdst == 1) ? resA : P.zf) + (long)row * 1024;
; #pragma unroll
;           for (int i = 0; i < 4; ++i) {
;             const unsigned b0 = f2bf(xv[i].x), b1 = f2bf(xv[i].y), b2 = f2bf(xv[i].z), b3 = f2bf(xv[i].w);
;             *reinterpret_cast<uint2*>(xo + (i * 64 + lane) * 4) = make_uint2(b0 | (b1 << 16), b2 | (b3 << 16));
;           }
;         }
	global_load_dwordx2 v[186:187], v137, s[100:101] offset:1024
	global_load_dwordx2 v[188:189], v137, s[100:101] offset:1536
	v_lshlrev_b32_e32 v120, 16, v48
	v_and_b32_e32 v121, 0xffff0000, v48
	v_lshlrev_b32_e32 v122, 16, v49
	v_and_b32_e32 v123, 0xffff0000, v49
	v_lshlrev_b32_e32 v124, 16, v50
	v_and_b32_e32 v125, 0xffff0000, v50
	v_lshlrev_b32_e32 v126, 16, v51
	v_and_b32_e32 v127, 0xffff0000, v51
	v_lshlrev_b32_e32 v128, 16, v52
	v_and_b32_e32 v129, 0xffff0000, v52
	v_lshlrev_b32_e32 v130, 16, v53
	v_and_b32_e32 v131, 0xffff0000, v53
	v_lshlrev_b32_e32 v132, 16, v54
	v_and_b32_e32 v133, 0xffff0000, v54
	v_lshlrev_b32_e32 v134, 16, v55
	v_and_b32_e32 v135, 0xffff0000, v55
	v_mul_f32_e32 v138, v120, v120
	v_mul_f32_e32 v149, v121, v121
	v_mul_f32_e32 v150, v122, v122
	v_mul_f32_e32 v154, v123, v123
	v_fma_f32 v138, v124, v124, v138
	v_fma_f32 v149, v125, v125, v149
	v_fma_f32 v150, v126, v126, v150
	v_fma_f32 v154, v127, v127, v154
	v_fma_f32 v138, v128, v128, v138
	v_fma_f32 v149, v129, v129, v149
	v_fma_f32 v150, v130, v130, v150
	v_fma_f32 v154, v131, v131, v154
	v_fma_f32 v138, v132, v132, v138
	v_fma_f32 v149, v133, v133, v149
	v_fma_f32 v150, v134, v134, v150
	v_fma_f32 v154, v135, v135, v154
	v_add_f32_e32 v138, v138, v149
	v_add_f32_e32 v150, v150, v154
	v_add_f32_e32 v138, v138, v150
	s_nop 1
	v_add_f32_dpp v138, v138, v138 quad_perm:[1,0,3,2] row_mask:0xf bank_mask:0xf
	s_nop 1
	v_add_f32_dpp v138, v138, v138 quad_perm:[2,3,0,1] row_mask:0xf bank_mask:0xf
	s_nop 1
	v_add_f32_dpp v138, v138, v138 row_half_mirror row_mask:0xf bank_mask:0xf
	s_nop 1
	v_add_f32_dpp v138, v138, v138 row_mirror row_mask:0xf bank_mask:0xf
	v_mov_b32_e32 v139, v138
	s_nop 1
	v_permlane16_swap_b32_e32 v138, v139
	v_add_f32_e32 v138, v138, v139
	v_mov_b32_e32 v139, v138
	s_nop 1
	v_permlane32_swap_b32_e32 v138, v139
	v_add_f32_e32 v138, v138, v139
	v_mul_f32_e32 v138, 0x3a800000, v138
	v_add_f32_e32 v138, 0x358637bd, v138
	v_rsq_f32_e32 v140, v138
	s_nop 0
	v_mul_f32_e32 v120, v120, v140
	v_mul_f32_e32 v121, v121, v140
	v_mul_f32_e32 v122, v122, v140
	v_mul_f32_e32 v123, v123, v140
	v_mul_f32_e32 v124, v124, v140
	v_mul_f32_e32 v125, v125, v140
	v_mul_f32_e32 v126, v126, v140
	v_mul_f32_e32 v127, v127, v140
	v_mul_f32_e32 v128, v128, v140
	v_mul_f32_e32 v129, v129, v140
	v_mul_f32_e32 v130, v130, v140
	v_mul_f32_e32 v131, v131, v140
	v_mul_f32_e32 v132, v132, v140
	v_mul_f32_e32 v133, v133, v140
	v_mul_f32_e32 v134, v134, v140
	v_mul_f32_e32 v135, v135, v140
	v_fma_f32 v0, v120, v72, v0
	v_fma_f32 v1, v121, v73, v1
	v_fma_f32 v2, v122, v74, v2
	v_fma_f32 v3, v123, v75, v3
	v_fma_f32 v4, v124, v76, v4
	v_fma_f32 v5, v125, v77, v5
	v_fma_f32 v6, v126, v78, v6
	v_fma_f32 v7, v127, v79, v7
	v_fma_f32 v8, v128, v80, v8
	v_fma_f32 v9, v129, v81, v9
	v_fma_f32 v10, v130, v82, v10
	v_fma_f32 v11, v131, v83, v11
	v_fma_f32 v12, v132, v84, v12
	v_fma_f32 v13, v133, v85, v13
	v_fma_f32 v14, v134, v86, v14
	v_fma_f32 v15, v135, v87, v15
	v_cvt_pk_bf16_f32 v156, v0, v1
	v_cvt_pk_bf16_f32 v157, v2, v3
	v_cvt_pk_bf16_f32 v158, v4, v5
	v_cvt_pk_bf16_f32 v159, v6, v7
	v_cvt_pk_bf16_f32 v160, v8, v9
	v_cvt_pk_bf16_f32 v161, v10, v11
	v_cvt_pk_bf16_f32 v162, v12, v13
	v_cvt_pk_bf16_f32 v163, v14, v15
	s_lshl_b32 vcc_lo, s19, 11
	s_add_u32 vcc_lo, vcc_lo, 0x2000000
	s_add_u32 s100, s16, vcc_lo
	s_addc_u32 s101, s17, 0
	global_store_dwordx2 v137, v[156:157], s[100:101] offset:0
	global_store_dwordx2 v137, v[158:159], s[100:101] offset:512
	global_store_dwordx2 v137, v[160:161], s[100:101] offset:1024
	global_store_dwordx2 v137, v[162:163], s[100:101] offset:1536
	v_mul_f32_e32 v138, v0, v0
	v_mul_f32_e32 v149, v1, v1
	v_mul_f32_e32 v150, v2, v2
	v_mul_f32_e32 v154, v3, v3
	v_fma_f32 v138, v4, v4, v138
	v_fma_f32 v149, v5, v5, v149
	v_fma_f32 v150, v6, v6, v150
	v_fma_f32 v154, v7, v7, v154
	v_fma_f32 v138, v8, v8, v138
	v_fma_f32 v149, v9, v9, v149
	v_fma_f32 v150, v10, v10, v150
	v_fma_f32 v154, v11, v11, v154
	v_fma_f32 v138, v12, v12, v138
	v_fma_f32 v149, v13, v13, v149
	v_fma_f32 v150, v14, v14, v150
	v_fma_f32 v154, v15, v15, v154
	v_add_f32_e32 v138, v138, v149
	v_add_f32_e32 v150, v150, v154
	v_add_f32_e32 v138, v138, v150
	s_nop 1
	v_add_f32_dpp v138, v138, v138 quad_perm:[1,0,3,2] row_mask:0xf bank_mask:0xf
	s_nop 1
	v_add_f32_dpp v138, v138, v138 quad_perm:[2,3,0,1] row_mask:0xf bank_mask:0xf
	s_nop 1
	v_add_f32_dpp v138, v138, v138 row_half_mirror row_mask:0xf bank_mask:0xf
	s_nop 1
	v_add_f32_dpp v138, v138, v138 row_mirror row_mask:0xf bank_mask:0xf
	v_mov_b32_e32 v139, v138
	s_nop 1
	v_permlane16_swap_b32_e32 v138, v139
	v_add_f32_e32 v138, v138, v139
	v_mov_b32_e32 v139, v138
	s_nop 1
	v_permlane32_swap_b32_e32 v138, v139
	v_add_f32_e32 v138, v138, v139
	v_mul_f32_e32 v138, 0x3a800000, v138
	v_add_f32_e32 v138, 0x358637bd, v138
	v_rsq_f32_e32 v140, v138
	s_nop 0
	v_mul_f32_e32 v120, v0, v140
	v_mul_f32_e32 v121, v1, v140
	v_mul_f32_e32 v122, v2, v140
	v_mul_f32_e32 v123, v3, v140
	v_mul_f32_e32 v124, v4, v140
	v_mul_f32_e32 v125, v5, v140
	v_mul_f32_e32 v126, v6, v140
	v_mul_f32_e32 v127, v7, v140
	v_mul_f32_e32 v128, v8, v140
	v_mul_f32_e32 v129, v9, v140
	v_mul_f32_e32 v130, v10, v140
	v_mul_f32_e32 v131, v11, v140
	v_mul_f32_e32 v132, v12, v140
	v_mul_f32_e32 v133, v13, v140
	v_mul_f32_e32 v134, v14, v140
	v_mul_f32_e32 v135, v15, v140
	v_fma_f32 v120, v120, v88, v104
	v_fma_f32 v121, v121, v89, v105
	v_fma_f32 v122, v122, v90, v106
	v_fma_f32 v123, v123, v91, v107
	v_fma_f32 v124, v124, v92, v108
	v_fma_f32 v125, v125, v93, v109
	v_fma_f32 v126, v126, v94, v110
	v_fma_f32 v127, v127, v95, v111
	v_fma_f32 v128, v128, v96, v112
	v_fma_f32 v129, v129, v97, v113
; __device__ __forceinline__ void row_phase(const Params& P, int glayer, int layer, int xsrc, bool hasY, int gate_idx, const float* gpost,
;                           int xdst, bool doH, const float* gpre, int sh_idx, int nrows) {
;     ...
;         if (hasY) {
;           float4 yv[4];
;           float ss = 0.f;
; #pragma unroll
;           for (int i = 0; i < 4; ++i) {
;             const uint2 raw = yy[u][i];
;             yv[i].x = bf2f((u16)(raw.x & 0xffff)); yv[i].y = bf2f((u16)(raw.x >> 16));
;             yv[i].z = bf2f((u16)(raw.y & 0xffff)); yv[i].w = bf2f((u16)(raw.y >> 16));
;             ss += yv[i].x * yv[i].x + yv[i].y * yv[i].y + yv[i].z * yv[i].z + yv[i].w * yv[i].w;
;           }
;           ss = wave_sum(ss);
;           const float rstd = __builtin_amdgcn_rsqf(ss * (1.f / 1024.f) + EPSF);
; #pragma unroll
;           for (int i = 0; i < 4; ++i) {
;             const int col = (i * 64 + lane) * 4;
;             const float4 gt = *reinterpret_cast<const float4*>(modg + gate_idx * 1024 + col);
;             const float4 gp = *reinterpret_cast<const float4*>(gpost + col);
;             xv[i].x += gt.x * (yv[i].x * rstd * gp.x); xv[i].y += gt.y * (yv[i].y * rstd * gp.y);
;     ...
;         if (doH) {
;           float ss = 0.f;
; #pragma unroll
;           for (int i = 0; i < 4; ++i) ss += xv[i].x * xv[i].x + xv[i].y * xv[i].y + xv[i].z * xv[i].z + xv[i].w * xv[i].w;
;           ss = wave_sum(ss);
;           const float rstd = __builtin_amdgcn_rsqf(ss * (1.f / 1024.f) + EPSF);
;           u16* h = P.hy + (long)row * 1024;
; #pragma unroll
;           for (int i = 0; i < 4; ++i) {
;             const int col = (i * 64 + lane) * 4;
;             const float4 g = *reinterpret_cast<const float4*>(gpre + col);
;             const float4 sh = *reinterpret_cast<const float4*>(modp + sh_idx * 1024 + col);
;             const float4 sc = *reinterpret_cast<const float4*>(modp + (sh_idx + 1) * 1024 + col);
;             const unsigned h0 = f2bf(xv[i].x * rstd * g.x * (1.f + sc.x) + sh.x);
;             const unsigned h1 = f2bf(xv[i].y * rstd * g.y * (1.f + sc.y) + sh.y);
;             const unsigned h2 = f2bf(xv[i].z * rstd * g.z * (1.f + sc.z) + sh.z);
;             const unsigned h3 = f2bf(xv[i].w * rstd * g.w * (1.f + sc.w) + sh.w);
;             *reinterpret_cast<uint2*>(h + col) = make_uint2(h0 | (h1 << 16), h2 | (h3 << 16));
;           }
;         }
	v_fma_f32 v130, v130, v98, v114
	v_fma_f32 v131, v131, v99, v115
	v_fma_f32 v132, v132, v100, v116
	v_fma_f32 v133, v133, v101, v117
	v_fma_f32 v134, v134, v102, v118
	v_fma_f32 v135, v135, v103, v119
	v_cvt_pk_bf16_f32 v156, v120, v121
	v_cvt_pk_bf16_f32 v157, v122, v123
	v_cvt_pk_bf16_f32 v158, v124, v125
	v_cvt_pk_bf16_f32 v159, v126, v127
	v_cvt_pk_bf16_f32 v160, v128, v129
	v_cvt_pk_bf16_f32 v161, v130, v131
	v_cvt_pk_bf16_f32 v162, v132, v133
	v_cvt_pk_bf16_f32 v163, v134, v135
	s_lshl_b32 vcc_lo, s19, 11
	s_add_u32 vcc_lo, vcc_lo, 0x2000000
	s_add_u32 s100, s14, vcc_lo
	s_addc_u32 s101, s15, 0
	global_store_dwordx2 v137, v[156:157], s[100:101] offset:0
	global_store_dwordx2 v137, v[158:159], s[100:101] offset:512
	global_store_dwordx2 v137, v[160:161], s[100:101] offset:1024
	global_store_dwordx2 v137, v[162:163], s[100:101] offset:1536
	s_lshl_b32 vcc_lo, s19, 12
	s_add_u32 vcc_lo, vcc_lo, 0x6000000
	s_add_u32 s100, s12, vcc_lo
	s_addc_u32 s101, s13, 0
	global_load_dwordx4 v[0:3], v136, s[100:101] offset:0
	global_load_dwordx4 v[4:7], v136, s[100:101] offset:1024
	global_load_dwordx4 v[8:11], v136, s[100:101] offset:2048
	global_load_dwordx4 v[12:15], v136, s[100:101] offset:3072
	s_lshl_b32 vcc_lo, s19, 11
	s_add_u32 vcc_lo, vcc_lo, 0x3000000
	s_add_u32 s100, s14, vcc_lo
	s_addc_u32 s101, s15, 0
	global_load_dwordx2 v[48:49], v137, s[100:101] offset:0
	global_load_dwordx2 v[50:51], v137, s[100:101] offset:512
	global_load_dwordx2 v[52:53], v137, s[100:101] offset:1024
	global_load_dwordx2 v[54:55], v137, s[100:101] offset:1536
	v_lshlrev_b32_e32 v120, 16, v56
	v_and_b32_e32 v121, 0xffff0000, v56
	v_lshlrev_b32_e32 v122, 16, v57
	v_and_b32_e32 v123, 0xffff0000, v57
	v_lshlrev_b32_e32 v124, 16, v58
	v_and_b32_e32 v125, 0xffff0000, v58
	v_lshlrev_b32_e32 v126, 16, v59
	v_and_b32_e32 v127, 0xffff0000, v59
	v_lshlrev_b32_e32 v128, 16, v60
	v_and_b32_e32 v129, 0xffff0000, v60
	v_lshlrev_b32_e32 v130, 16, v61
	v_and_b32_e32 v131, 0xffff0000, v61
	v_lshlrev_b32_e32 v132, 16, v62
	v_and_b32_e32 v133, 0xffff0000, v62
	v_lshlrev_b32_e32 v134, 16, v63
	v_and_b32_e32 v135, 0xffff0000, v63
	v_mul_f32_e32 v138, v120, v120
	v_mul_f32_e32 v149, v121, v121
	v_mul_f32_e32 v150, v122, v122
	v_mul_f32_e32 v154, v123, v123
	v_fma_f32 v138, v124, v124, v138
	v_fma_f32 v149, v125, v125, v149
	v_fma_f32 v150, v126, v126, v150
	v_fma_f32 v154, v127, v127, v154
	v_fma_f32 v138, v128, v128, v138
	v_fma_f32 v149, v129, v129, v149
	v_fma_f32 v150, v130, v130, v150
	v_fma_f32 v154, v131, v131, v154
	v_fma_f32 v138, v132, v132, v138
	v_fma_f32 v149, v133, v133, v149
	v_fma_f32 v150, v134, v134, v150
	v_fma_f32 v154, v135, v135, v154
	v_add_f32_e32 v138, v138, v149
	v_add_f32_e32 v150, v150, v154
	v_add_f32_e32 v138, v138, v150
	s_nop 1
	v_add_f32_dpp v138, v138, v138 quad_perm:[1,0,3,2] row_mask:0xf bank_mask:0xf
	s_nop 1
	v_add_f32_dpp v138, v138, v138 quad_perm:[2,3,0,1] row_mask:0xf bank_mask:0xf
	s_nop 1
	v_add_f32_dpp v138, v138, v138 row_half_mirror row_mask:0xf bank_mask:0xf
	s_nop 1
	v_add_f32_dpp v138, v138, v138 row_mirror row_mask:0xf bank_mask:0xf
	v_mov_b32_e32 v139, v138
	s_nop 1
	v_permlane16_swap_b32_e32 v138, v139
	v_add_f32_e32 v138, v138, v139
	v_mov_b32_e32 v139, v138
	s_nop 1
	v_permlane32_swap_b32_e32 v138, v139
	v_add_f32_e32 v138, v138, v139
	v_mul_f32_e32 v138, 0x3a800000, v138
	v_add_f32_e32 v138, 0x358637bd, v138
	v_rsq_f32_e32 v140, v138
	s_nop 0
	v_mul_f32_e32 v120, v120, v140
	v_mul_f32_e32 v121, v121, v140
	v_mul_f32_e32 v122, v122, v140
	v_mul_f32_e32 v123, v123, v140
	v_mul_f32_e32 v124, v124, v140
	v_mul_f32_e32 v125, v125, v140
	v_mul_f32_e32 v126, v126, v140
	v_mul_f32_e32 v127, v127, v140
	v_mul_f32_e32 v128, v128, v140
	v_mul_f32_e32 v129, v129, v140
	v_mul_f32_e32 v130, v130, v140
	v_mul_f32_e32 v131, v131, v140
	v_mul_f32_e32 v132, v132, v140
	v_mul_f32_e32 v133, v133, v140
	v_mul_f32_e32 v134, v134, v140
	v_mul_f32_e32 v135, v135, v140
	v_fma_f32 v16, v120, v72, v16
	v_fma_f32 v17, v121, v73, v17
	v_fma_f32 v18, v122, v74, v18
	v_fma_f32 v19, v123, v75, v19
	v_fma_f32 v20, v124, v76, v20
	v_fma_f32 v21, v125, v77, v21
	v_fma_f32 v22, v126, v78, v22
	v_fma_f32 v23, v127, v79, v23
	v_fma_f32 v24, v128, v80, v24
	v_fma_f32 v25, v129, v81, v25
	v_fma_f32 v26, v130, v82, v26
	v_fma_f32 v27, v131, v83, v27
	v_fma_f32 v28, v132, v84, v28
	v_fma_f32 v29, v133, v85, v29
	v_fma_f32 v30, v134, v86, v30
	v_fma_f32 v31, v135, v87, v31
	v_cvt_pk_bf16_f32 v156, v16, v17
	v_cvt_pk_bf16_f32 v157, v18, v19
	v_cvt_pk_bf16_f32 v158, v20, v21
	v_cvt_pk_bf16_f32 v159, v22, v23
	v_cvt_pk_bf16_f32 v160, v24, v25
	v_cvt_pk_bf16_f32 v161, v26, v27
	v_cvt_pk_bf16_f32 v162, v28, v29
	v_cvt_pk_bf16_f32 v163, v30, v31
	s_lshl_b32 vcc_lo, s19, 11
	s_add_u32 vcc_lo, vcc_lo, 0x2400000
	s_add_u32 s100, s16, vcc_lo
	s_addc_u32 s101, s17, 0
	global_store_dwordx2 v137, v[156:157], s[100:101] offset:0
	global_store_dwordx2 v137, v[158:159], s[100:101] offset:512
	global_store_dwordx2 v137, v[160:161], s[100:101] offset:1024
	global_store_dwordx2 v137, v[162:163], s[100:101] offset:1536
	v_mul_f32_e32 v138, v16, v16
	v_mul_f32_e32 v149, v17, v17
	v_mul_f32_e32 v150, v18, v18
	v_mul_f32_e32 v154, v19, v19
	v_fma_f32 v138, v20, v20, v138
	v_fma_f32 v149, v21, v21, v149
	v_fma_f32 v150, v22, v22, v150
	v_fma_f32 v154, v23, v23, v154
	v_fma_f32 v138, v24, v24, v138
	v_fma_f32 v149, v25, v25, v149
	v_fma_f32 v150, v26, v26, v150
	v_fma_f32 v154, v27, v27, v154
	v_fma_f32 v138, v28, v28, v138
	v_fma_f32 v149, v29, v29, v149
	v_fma_f32 v150, v30, v30, v150
	v_fma_f32 v154, v31, v31, v154
	v_add_f32_e32 v138, v138, v149
	v_add_f32_e32 v150, v150, v154
; __device__ __forceinline__ void row_phase(const Params& P, int glayer, int layer, int xsrc, bool hasY, int gate_idx, const float* gpost,
;                           int xdst, bool doH, const float* gpre, int sh_idx, int nrows) {
;     ...
;     for (int u = 0; u < 4; ++u) {
;       const int R = rb + u * stride;
;       if (R < nrows) {
;         if (xsrc != 0 && R < N_X) {
;           const u16* xs_ = ((xsrc == 1) ? resA : P.zf) + (long)R * 1024;
; #pragma unroll
;           for (int i = 0; i < 4; ++i) {
;             const uint2 t2 = *reinterpret_cast<const uint2*>(xs_ + (i * 64 + lane) * 4);
;             xr[u][i].x = t2.x; xr[u][i].y = t2.y;
;           }
;         } else {
;           const float* xin_;
;           if (xsrc == 0) xin_ = R < N_X ? P.x + (long)R * 1024 : P.ctx + (long)(R - N_X) * 1024;
;           else           xin_ = P.xc + (long)(R - N_X) * 1024;
; #pragma unroll
;           for (int i = 0; i < 4; ++i) xr[u][i] = *reinterpret_cast<const uint4*>(xin_ + (i * 64 + lane) * 4);
;         }
;         if (hasY) {
;           const u16* y_ = P.hy + (long)R * 1024;
; #pragma unroll
;     ...
;         if (doH) {
;           float ss = 0.f;
; #pragma unroll
;           for (int i = 0; i < 4; ++i) ss += xv[i].x * xv[i].x + xv[i].y * xv[i].y + xv[i].z * xv[i].z + xv[i].w * xv[i].w;
;           ss = wave_sum(ss);
;           const float rstd = __builtin_amdgcn_rsqf(ss * (1.f / 1024.f) + EPSF);
;           u16* h = P.hy + (long)row * 1024;
; #pragma unroll
;           for (int i = 0; i < 4; ++i) {
;             const int col = (i * 64 + lane) * 4;
;             const float4 g = *reinterpret_cast<const float4*>(gpre + col);
;             const float4 sh = *reinterpret_cast<const float4*>(modp + sh_idx * 1024 + col);
;             const float4 sc = *reinterpret_cast<const float4*>(modp + (sh_idx + 1) * 1024 + col);
;             const unsigned h0 = f2bf(xv[i].x * rstd * g.x * (1.f + sc.x) + sh.x);
;             const unsigned h1 = f2bf(xv[i].y * rstd * g.y * (1.f + sc.y) + sh.y);
;             const unsigned h2 = f2bf(xv[i].z * rstd * g.z * (1.f + sc.z) + sh.z);
;             const unsigned h3 = f2bf(xv[i].w * rstd * g.w * (1.f + sc.w) + sh.w);
;             *reinterpret_cast<uint2*>(h + col) = make_uint2(h0 | (h1 << 16), h2 | (h3 << 16));
;           }
;         }
	v_add_f32_e32 v138, v138, v150
	s_nop 1
	v_add_f32_dpp v138, v138, v138 quad_perm:[1,0,3,2] row_mask:0xf bank_mask:0xf
	s_nop 1
	v_add_f32_dpp v138, v138, v138 quad_perm:[2,3,0,1] row_mask:0xf bank_mask:0xf
	s_nop 1
	v_add_f32_dpp v138, v138, v138 row_half_mirror row_mask:0xf bank_mask:0xf
	s_nop 1
	v_add_f32_dpp v138, v138, v138 row_mirror row_mask:0xf bank_mask:0xf
	v_mov_b32_e32 v139, v138
	s_nop 1
	v_permlane16_swap_b32_e32 v138, v139
	v_add_f32_e32 v138, v138, v139
	v_mov_b32_e32 v139, v138
	s_nop 1
	v_permlane32_swap_b32_e32 v138, v139
	v_add_f32_e32 v138, v138, v139
	v_mul_f32_e32 v138, 0x3a800000, v138
	v_add_f32_e32 v138, 0x358637bd, v138
	v_rsq_f32_e32 v140, v138
	s_nop 0
	v_mul_f32_e32 v120, v16, v140
	v_mul_f32_e32 v121, v17, v140
	v_mul_f32_e32 v122, v18, v140
	v_mul_f32_e32 v123, v19, v140
	v_mul_f32_e32 v124, v20, v140
	v_mul_f32_e32 v125, v21, v140
	v_mul_f32_e32 v126, v22, v140
	v_mul_f32_e32 v127, v23, v140
	v_mul_f32_e32 v128, v24, v140
	v_mul_f32_e32 v129, v25, v140
	v_mul_f32_e32 v130, v26, v140
	v_mul_f32_e32 v131, v27, v140
	v_mul_f32_e32 v132, v28, v140
	v_mul_f32_e32 v133, v29, v140
	v_mul_f32_e32 v134, v30, v140
	v_mul_f32_e32 v135, v31, v140
	v_fma_f32 v120, v120, v88, v104
	v_fma_f32 v121, v121, v89, v105
	v_fma_f32 v122, v122, v90, v106
	v_fma_f32 v123, v123, v91, v107
	v_fma_f32 v124, v124, v92, v108
	v_fma_f32 v125, v125, v93, v109
	v_fma_f32 v126, v126, v94, v110
	v_fma_f32 v127, v127, v95, v111
	v_fma_f32 v128, v128, v96, v112
	v_fma_f32 v129, v129, v97, v113
	v_fma_f32 v130, v130, v98, v114
	v_fma_f32 v131, v131, v99, v115
	v_fma_f32 v132, v132, v100, v116
	v_fma_f32 v133, v133, v101, v117
	v_fma_f32 v134, v134, v102, v118
	v_fma_f32 v135, v135, v103, v119
	v_cvt_pk_bf16_f32 v156, v120, v121
	v_cvt_pk_bf16_f32 v157, v122, v123
	v_cvt_pk_bf16_f32 v158, v124, v125
	v_cvt_pk_bf16_f32 v159, v126, v127
	v_cvt_pk_bf16_f32 v160, v128, v129
	v_cvt_pk_bf16_f32 v161, v130, v131
	v_cvt_pk_bf16_f32 v162, v132, v133
	v_cvt_pk_bf16_f32 v163, v134, v135
	s_lshl_b32 vcc_lo, s19, 11
	s_add_u32 vcc_lo, vcc_lo, 0x2400000
	s_add_u32 s100, s14, vcc_lo
	s_addc_u32 s101, s15, 0
	global_store_dwordx2 v137, v[156:157], s[100:101] offset:0
	global_store_dwordx2 v137, v[158:159], s[100:101] offset:512
	global_store_dwordx2 v137, v[160:161], s[100:101] offset:1024
	global_store_dwordx2 v137, v[162:163], s[100:101] offset:1536
	s_lshl_b32 vcc_lo, s19, 12
	s_add_u32 vcc_lo, vcc_lo, 0x6800000
	s_add_u32 s100, s12, vcc_lo
	s_addc_u32 s101, s13, 0
	global_load_dwordx4 v[16:19], v136, s[100:101] offset:0
	global_load_dwordx4 v[20:23], v136, s[100:101] offset:1024
	global_load_dwordx4 v[24:27], v136, s[100:101] offset:2048
	global_load_dwordx4 v[28:31], v136, s[100:101] offset:3072
	s_lshl_b32 vcc_lo, s19, 11
	s_add_u32 vcc_lo, vcc_lo, 0x3400000
	s_add_u32 s100, s14, vcc_lo
	s_addc_u32 s101, s15, 0
	global_load_dwordx2 v[56:57], v137, s[100:101] offset:0
	global_load_dwordx2 v[58:59], v137, s[100:101] offset:512
	global_load_dwordx2 v[60:61], v137, s[100:101] offset:1024
	global_load_dwordx2 v[62:63], v137, s[100:101] offset:1536
	v_lshlrev_b32_e32 v120, 16, v64
	v_and_b32_e32 v121, 0xffff0000, v64
	v_lshlrev_b32_e32 v122, 16, v65
	v_and_b32_e32 v123, 0xffff0000, v65
	v_lshlrev_b32_e32 v124, 16, v66
	v_and_b32_e32 v125, 0xffff0000, v66
	v_lshlrev_b32_e32 v126, 16, v67
	v_and_b32_e32 v127, 0xffff0000, v67
	v_lshlrev_b32_e32 v128, 16, v68
	v_and_b32_e32 v129, 0xffff0000, v68
	v_lshlrev_b32_e32 v130, 16, v69
	v_and_b32_e32 v131, 0xffff0000, v69
	v_lshlrev_b32_e32 v132, 16, v70
	v_and_b32_e32 v133, 0xffff0000, v70
	v_lshlrev_b32_e32 v134, 16, v71
	v_and_b32_e32 v135, 0xffff0000, v71
	v_mul_f32_e32 v138, v120, v120
	v_mul_f32_e32 v149, v121, v121
	v_mul_f32_e32 v150, v122, v122
	v_mul_f32_e32 v154, v123, v123
	v_fma_f32 v138, v124, v124, v138
	v_fma_f32 v149, v125, v125, v149
	v_fma_f32 v150, v126, v126, v150
	v_fma_f32 v154, v127, v127, v154
	v_fma_f32 v138, v128, v128, v138
	v_fma_f32 v149, v129, v129, v149
	v_fma_f32 v150, v130, v130, v150
	v_fma_f32 v154, v131, v131, v154
	v_fma_f32 v138, v132, v132, v138
	v_fma_f32 v149, v133, v133, v149
	v_fma_f32 v150, v134, v134, v150
	v_fma_f32 v154, v135, v135, v154
	v_add_f32_e32 v138, v138, v149
	v_add_f32_e32 v150, v150, v154
	v_add_f32_e32 v138, v138, v150
	s_nop 1
	v_add_f32_dpp v138, v138, v138 quad_perm:[1,0,3,2] row_mask:0xf bank_mask:0xf
	s_nop 1
	v_add_f32_dpp v138, v138, v138 quad_perm:[2,3,0,1] row_mask:0xf bank_mask:0xf
	s_nop 1
	v_add_f32_dpp v138, v138, v138 row_half_mirror row_mask:0xf bank_mask:0xf
	s_nop 1
	v_add_f32_dpp v138, v138, v138 row_mirror row_mask:0xf bank_mask:0xf
	v_mov_b32_e32 v139, v138
	s_nop 1
	v_permlane16_swap_b32_e32 v138, v139
	v_add_f32_e32 v138, v138, v139
	v_mov_b32_e32 v139, v138
	s_nop 1
	v_permlane32_swap_b32_e32 v138, v139
	v_add_f32_e32 v138, v138, v139
	v_mul_f32_e32 v138, 0x3a800000, v138
	v_add_f32_e32 v138, 0x358637bd, v138
	v_rsq_f32_e32 v140, v138
	s_nop 0
	v_mul_f32_e32 v120, v120, v140
	v_mul_f32_e32 v121, v121, v140
	v_mul_f32_e32 v122, v122, v140
	v_mul_f32_e32 v123, v123, v140
	v_mul_f32_e32 v124, v124, v140
	v_mul_f32_e32 v125, v125, v140
	v_mul_f32_e32 v126, v126, v140
	v_mul_f32_e32 v127, v127, v140
	v_mul_f32_e32 v128, v128, v140
	v_mul_f32_e32 v129, v129, v140
	v_mul_f32_e32 v130, v130, v140
	v_mul_f32_e32 v131, v131, v140
	v_mul_f32_e32 v132, v132, v140
	v_mul_f32_e32 v133, v133, v140
	v_mul_f32_e32 v134, v134, v140
	v_mul_f32_e32 v135, v135, v140
	v_fma_f32 v32, v120, v72, v32
	v_fma_f32 v33, v121, v73, v33
	v_fma_f32 v34, v122, v74, v34
	v_fma_f32 v35, v123, v75, v35
	v_fma_f32 v36, v124, v76, v36
	v_fma_f32 v37, v125, v77, v37
; __device__ __forceinline__ void row_phase(const Params& P, int glayer, int layer, int xsrc, bool hasY, int gate_idx, const float* gpost,
;                           int xdst, bool doH, const float* gpre, int sh_idx, int nrows) {
;     ...
;     for (int u = 0; u < 4; ++u) {
;       const int R = rb + u * stride;
;       if (R < nrows) {
;         if (xsrc != 0 && R < N_X) {
;           const u16* xs_ = ((xsrc == 1) ? resA : P.zf) + (long)R * 1024;
; #pragma unroll
;           for (int i = 0; i < 4; ++i) {
;     ...
;         if (xdst == 3 || (xdst == 1 && row >= N_X)) {
;           float* xout = (xdst == 3) ? P.out + (long)row * 1024 : P.xc + (long)(row - N_X) * 1024;
; #pragma unroll
;           for (int i = 0; i < 4; ++i) *reinterpret_cast<float4*>(xout + (i * 64 + lane) * 4) = xv[i];
;         } else if (xdst != 0) {
;           u16* xo = ((xdst == 1) ? resA : P.zf) + (long)row * 1024;
; #pragma unroll
;           for (int i = 0; i < 4; ++i) {
;             const unsigned b0 = f2bf(xv[i].x), b1 = f2bf(xv[i].y), b2 = f2bf(xv[i].z), b3 = f2bf(xv[i].w);
;             *reinterpret_cast<uint2*>(xo + (i * 64 + lane) * 4) = make_uint2(b0 | (b1 << 16), b2 | (b3 << 16));
;           }
;         }
;         if (doH) {
;           float ss = 0.f;
; #pragma unroll
;           for (int i = 0; i < 4; ++i) ss += xv[i].x * xv[i].x + xv[i].y * xv[i].y + xv[i].z * xv[i].z + xv[i].w * xv[i].w;
;           ss = wave_sum(ss);
;           const float rstd = __builtin_amdgcn_rsqf(ss * (1.f / 1024.f) + EPSF);
;           u16* h = P.hy + (long)row * 1024;
; #pragma unroll
;           for (int i = 0; i < 4; ++i) {
;             const int col = (i * 64 + lane) * 4;
;             const float4 g = *reinterpret_cast<const float4*>(gpre + col);
;             const float4 sh = *reinterpret_cast<const float4*>(modp + sh_idx * 1024 + col);
;             const float4 sc = *reinterpret_cast<const float4*>(modp + (sh_idx + 1) * 1024 + col);
;             const unsigned h0 = f2bf(xv[i].x * rstd * g.x * (1.f + sc.x) + sh.x);
;             const unsigned h1 = f2bf(xv[i].y * rstd * g.y * (1.f + sc.y) + sh.y);
;             const unsigned h2 = f2bf(xv[i].z * rstd * g.z * (1.f + sc.z) + sh.z);
;             const unsigned h3 = f2bf(xv[i].w * rstd * g.w * (1.f + sc.w) + sh.w);
;             *reinterpret_cast<uint2*>(h + col) = make_uint2(h0 | (h1 << 16), h2 | (h3 << 16));
;           }
;         }
	v_fma_f32 v38, v126, v78, v38
	v_fma_f32 v39, v127, v79, v39
	v_fma_f32 v40, v128, v80, v40
	v_fma_f32 v41, v129, v81, v41
	v_fma_f32 v42, v130, v82, v42
	v_fma_f32 v43, v131, v83, v43
	v_fma_f32 v44, v132, v84, v44
	v_fma_f32 v45, v133, v85, v45
	v_fma_f32 v46, v134, v86, v46
	v_fma_f32 v47, v135, v87, v47
	v_cvt_pk_bf16_f32 v156, v32, v33
	v_cvt_pk_bf16_f32 v157, v34, v35
	v_cvt_pk_bf16_f32 v158, v36, v37
	v_cvt_pk_bf16_f32 v159, v38, v39
	v_cvt_pk_bf16_f32 v160, v40, v41
	v_cvt_pk_bf16_f32 v161, v42, v43
	v_cvt_pk_bf16_f32 v162, v44, v45
	v_cvt_pk_bf16_f32 v163, v46, v47
	s_lshl_b32 vcc_lo, s19, 11
	s_add_u32 vcc_lo, vcc_lo, 0x2800000
	s_add_u32 s100, s16, vcc_lo
	s_addc_u32 s101, s17, 0
	global_store_dwordx2 v137, v[156:157], s[100:101] offset:0
	global_store_dwordx2 v137, v[158:159], s[100:101] offset:512
	global_store_dwordx2 v137, v[160:161], s[100:101] offset:1024
	global_store_dwordx2 v137, v[162:163], s[100:101] offset:1536
	v_mul_f32_e32 v138, v32, v32
	v_mul_f32_e32 v149, v33, v33
	v_mul_f32_e32 v150, v34, v34
	v_mul_f32_e32 v154, v35, v35
	v_fma_f32 v138, v36, v36, v138
	v_fma_f32 v149, v37, v37, v149
	v_fma_f32 v150, v38, v38, v150
	v_fma_f32 v154, v39, v39, v154
	v_fma_f32 v138, v40, v40, v138
	v_fma_f32 v149, v41, v41, v149
	v_fma_f32 v150, v42, v42, v150
	v_fma_f32 v154, v43, v43, v154
	v_fma_f32 v138, v44, v44, v138
	v_fma_f32 v149, v45, v45, v149
	v_fma_f32 v150, v46, v46, v150
	v_fma_f32 v154, v47, v47, v154
	v_add_f32_e32 v138, v138, v149
	v_add_f32_e32 v150, v150, v154
	v_add_f32_e32 v138, v138, v150
	s_nop 1
	v_add_f32_dpp v138, v138, v138 quad_perm:[1,0,3,2] row_mask:0xf bank_mask:0xf
	s_nop 1
	v_add_f32_dpp v138, v138, v138 quad_perm:[2,3,0,1] row_mask:0xf bank_mask:0xf
	s_nop 1
	v_add_f32_dpp v138, v138, v138 row_half_mirror row_mask:0xf bank_mask:0xf
	s_nop 1
	v_add_f32_dpp v138, v138, v138 row_mirror row_mask:0xf bank_mask:0xf
	v_mov_b32_e32 v139, v138
	s_nop 1
	v_permlane16_swap_b32_e32 v138, v139
	v_add_f32_e32 v138, v138, v139
	v_mov_b32_e32 v139, v138
	s_nop 1
	v_permlane32_swap_b32_e32 v138, v139
	v_add_f32_e32 v138, v138, v139
	v_mul_f32_e32 v138, 0x3a800000, v138
	v_add_f32_e32 v138, 0x358637bd, v138
	v_rsq_f32_e32 v140, v138
	s_nop 0
	v_mul_f32_e32 v120, v32, v140
	v_mul_f32_e32 v121, v33, v140
	v_mul_f32_e32 v122, v34, v140
	v_mul_f32_e32 v123, v35, v140
	v_mul_f32_e32 v124, v36, v140
	v_mul_f32_e32 v125, v37, v140
	v_mul_f32_e32 v126, v38, v140
	v_mul_f32_e32 v127, v39, v140
	v_mul_f32_e32 v128, v40, v140
	v_mul_f32_e32 v129, v41, v140
	v_mul_f32_e32 v130, v42, v140
	v_mul_f32_e32 v131, v43, v140
	v_mul_f32_e32 v132, v44, v140
	v_mul_f32_e32 v133, v45, v140
	v_mul_f32_e32 v134, v46, v140
	v_mul_f32_e32 v135, v47, v140
	v_fma_f32 v120, v120, v88, v104
	v_fma_f32 v121, v121, v89, v105
	v_fma_f32 v122, v122, v90, v106
	v_fma_f32 v123, v123, v91, v107
	v_fma_f32 v124, v124, v92, v108
	v_fma_f32 v125, v125, v93, v109
	v_fma_f32 v126, v126, v94, v110
	v_fma_f32 v127, v127, v95, v111
	v_fma_f32 v128, v128, v96, v112
	v_fma_f32 v129, v129, v97, v113
	v_fma_f32 v130, v130, v98, v114
	v_fma_f32 v131, v131, v99, v115
	v_fma_f32 v132, v132, v100, v116
	v_fma_f32 v133, v133, v101, v117
	v_fma_f32 v134, v134, v102, v118
	v_fma_f32 v135, v135, v103, v119
	v_cvt_pk_bf16_f32 v156, v120, v121
	v_cvt_pk_bf16_f32 v157, v122, v123
	v_cvt_pk_bf16_f32 v158, v124, v125
	v_cvt_pk_bf16_f32 v159, v126, v127
	v_cvt_pk_bf16_f32 v160, v128, v129
	v_cvt_pk_bf16_f32 v161, v130, v131
	v_cvt_pk_bf16_f32 v162, v132, v133
	v_cvt_pk_bf16_f32 v163, v134, v135
	s_lshl_b32 vcc_lo, s19, 11
	s_add_u32 vcc_lo, vcc_lo, 0x2800000
	s_add_u32 s100, s14, vcc_lo
	s_addc_u32 s101, s15, 0
	global_store_dwordx2 v137, v[156:157], s[100:101] offset:0
	global_store_dwordx2 v137, v[158:159], s[100:101] offset:512
	global_store_dwordx2 v137, v[160:161], s[100:101] offset:1024
	global_store_dwordx2 v137, v[162:163], s[100:101] offset:1536
	s_lshl_b32 vcc_lo, s19, 12
	s_add_u32 vcc_lo, vcc_lo, 0x7000000
	s_add_u32 s100, s12, vcc_lo
	s_addc_u32 s101, s13, 0
	global_load_dwordx4 v[32:35], v136, s[100:101] offset:0
	global_load_dwordx4 v[36:39], v136, s[100:101] offset:1024
	global_load_dwordx4 v[40:43], v136, s[100:101] offset:2048
	global_load_dwordx4 v[44:47], v136, s[100:101] offset:3072
	s_lshl_b32 vcc_lo, s19, 11
	s_add_u32 vcc_lo, vcc_lo, 0x3800000
	s_add_u32 s100, s14, vcc_lo
	s_addc_u32 s101, s15, 0
	global_load_dwordx2 v[64:65], v137, s[100:101] offset:0
	global_load_dwordx2 v[66:67], v137, s[100:101] offset:512
	global_load_dwordx2 v[68:69], v137, s[100:101] offset:1024
	global_load_dwordx2 v[70:71], v137, s[100:101] offset:1536
	s_waitcnt vmcnt(48)
; __device__ __forceinline__ void row_phase(const Params& P, int glayer, int layer, int xsrc, bool hasY, int gate_idx, const float* gpost,
;                           int xdst, bool doH, const float* gpre, int sh_idx, int nrows) {
;     ...
;         if (hasY) {
;           float4 yv[4];
;           float ss = 0.f;
; #pragma unroll
;           for (int i = 0; i < 4; ++i) {
;             const uint2 raw = yy[u][i];
;             yv[i].x = bf2f((u16)(raw.x & 0xffff)); yv[i].y = bf2f((u16)(raw.x >> 16));
;             yv[i].z = bf2f((u16)(raw.y & 0xffff)); yv[i].w = bf2f((u16)(raw.y >> 16));
;             ss += yv[i].x * yv[i].x + yv[i].y * yv[i].y + yv[i].z * yv[i].z + yv[i].w * yv[i].w;
;           }
;           ss = wave_sum(ss);
;           const float rstd = __builtin_amdgcn_rsqf(ss * (1.f / 1024.f) + EPSF);
; #pragma unroll
;           for (int i = 0; i < 4; ++i) {
;             const int col = (i * 64 + lane) * 4;
;             const float4 gt = *reinterpret_cast<const float4*>(modg + gate_idx * 1024 + col);
;             const float4 gp = *reinterpret_cast<const float4*>(gpost + col);
;             xv[i].x += gt.x * (yv[i].x * rstd * gp.x); xv[i].y += gt.y * (yv[i].y * rstd * gp.y);
;             xv[i].z += gt.z * (yv[i].z * rstd * gp.z); xv[i].w += gt.w * (yv[i].w * rstd * gp.w);
;           }
;         }
;         if (xdst == 3 || (xdst == 1 && row >= N_X)) {
;           float* xout = (xdst == 3) ? P.out + (long)row * 1024 : P.xc + (long)(row - N_X) * 1024;
; #pragma unroll
;           for (int i = 0; i < 4; ++i) *reinterpret_cast<float4*>(xout + (i * 64 + lane) * 4) = xv[i];
;         } else if (xdst != 0) {
;           u16* xo = ((xdst == 1) ? resA : P.zf) + (long)row * 1024;
; #pragma unroll
;           for (int i = 0; i < 4; ++i) {
;             const unsigned b0 = f2bf(xv[i].x), b1 = f2bf(xv[i].y), b2 = f2bf(xv[i].z), b3 = f2bf(xv[i].w);
;             *reinterpret_cast<uint2*>(xo + (i * 64 + lane) * 4) = make_uint2(b0 | (b1 << 16), b2 | (b3 << 16));
;           }
;         }
;         if (doH) {
;           float ss = 0.f;
; #pragma unroll
;           for (int i = 0; i < 4; ++i) ss += xv[i].x * xv[i].x + xv[i].y * xv[i].y + xv[i].z * xv[i].z + xv[i].w * xv[i].w;
;           ss = wave_sum(ss);
;           const float rstd = __builtin_amdgcn_rsqf(ss * (1.f / 1024.f) + EPSF);
;           u16* h = P.hy + (long)row * 1024;
; #pragma unroll
	v_lshlrev_b32_e32 v120, 16, v182
	v_and_b32_e32 v121, 0xffff0000, v182
	v_lshlrev_b32_e32 v122, 16, v183
	v_and_b32_e32 v123, 0xffff0000, v183
	v_lshlrev_b32_e32 v124, 16, v184
	v_and_b32_e32 v125, 0xffff0000, v184
	v_lshlrev_b32_e32 v126, 16, v185
	v_and_b32_e32 v127, 0xffff0000, v185
	v_lshlrev_b32_e32 v128, 16, v186
	v_and_b32_e32 v129, 0xffff0000, v186
	v_lshlrev_b32_e32 v130, 16, v187
	v_and_b32_e32 v131, 0xffff0000, v187
	v_lshlrev_b32_e32 v132, 16, v188
	v_and_b32_e32 v133, 0xffff0000, v188
	v_lshlrev_b32_e32 v134, 16, v189
	v_and_b32_e32 v135, 0xffff0000, v189
	v_mul_f32_e32 v138, v120, v120
	v_mul_f32_e32 v149, v121, v121
	v_mul_f32_e32 v150, v122, v122
	v_mul_f32_e32 v154, v123, v123
	v_fma_f32 v138, v124, v124, v138
	v_fma_f32 v149, v125, v125, v149
	v_fma_f32 v150, v126, v126, v150
	v_fma_f32 v154, v127, v127, v154
	v_fma_f32 v138, v128, v128, v138
	v_fma_f32 v149, v129, v129, v149
	v_fma_f32 v150, v130, v130, v150
	v_fma_f32 v154, v131, v131, v154
	v_fma_f32 v138, v132, v132, v138
	v_fma_f32 v149, v133, v133, v149
	v_fma_f32 v150, v134, v134, v150
	v_fma_f32 v154, v135, v135, v154
	v_add_f32_e32 v138, v138, v149
	v_add_f32_e32 v150, v150, v154
	v_add_f32_e32 v138, v138, v150
	s_nop 1
	v_add_f32_dpp v138, v138, v138 quad_perm:[1,0,3,2] row_mask:0xf bank_mask:0xf
	s_nop 1
	v_add_f32_dpp v138, v138, v138 quad_perm:[2,3,0,1] row_mask:0xf bank_mask:0xf
	s_nop 1
	v_add_f32_dpp v138, v138, v138 row_half_mirror row_mask:0xf bank_mask:0xf
	s_nop 1
	v_add_f32_dpp v138, v138, v138 row_mirror row_mask:0xf bank_mask:0xf
	v_mov_b32_e32 v139, v138
	s_nop 1
	v_permlane16_swap_b32_e32 v138, v139
	v_add_f32_e32 v138, v138, v139
	v_mov_b32_e32 v139, v138
	s_nop 1
	v_permlane32_swap_b32_e32 v138, v139
	v_add_f32_e32 v138, v138, v139
	v_mul_f32_e32 v138, 0x3a800000, v138
	v_add_f32_e32 v138, 0x358637bd, v138
	v_rsq_f32_e32 v140, v138
	s_nop 0
	v_mul_f32_e32 v120, v120, v140
	v_mul_f32_e32 v121, v121, v140
	v_mul_f32_e32 v122, v122, v140
	v_mul_f32_e32 v123, v123, v140
	v_mul_f32_e32 v124, v124, v140
	v_mul_f32_e32 v125, v125, v140
	v_mul_f32_e32 v126, v126, v140
	v_mul_f32_e32 v127, v127, v140
	v_mul_f32_e32 v128, v128, v140
	v_mul_f32_e32 v129, v129, v140
	v_mul_f32_e32 v130, v130, v140
	v_mul_f32_e32 v131, v131, v140
	v_mul_f32_e32 v132, v132, v140
	v_mul_f32_e32 v133, v133, v140
	v_mul_f32_e32 v134, v134, v140
	v_mul_f32_e32 v135, v135, v140
	v_fma_f32 v166, v120, v72, v166
	v_fma_f32 v167, v121, v73, v167
	v_fma_f32 v168, v122, v74, v168
	v_fma_f32 v169, v123, v75, v169
	v_fma_f32 v170, v124, v76, v170
	v_fma_f32 v171, v125, v77, v171
	v_fma_f32 v172, v126, v78, v172
	v_fma_f32 v173, v127, v79, v173
	v_fma_f32 v174, v128, v80, v174
	v_fma_f32 v175, v129, v81, v175
	v_fma_f32 v176, v130, v82, v176
	v_fma_f32 v177, v131, v83, v177
	v_fma_f32 v178, v132, v84, v178
	v_fma_f32 v179, v133, v85, v179
	v_fma_f32 v180, v134, v86, v180
	v_fma_f32 v181, v135, v87, v181
	v_cvt_pk_bf16_f32 v156, v166, v167
	v_cvt_pk_bf16_f32 v157, v168, v169
	v_cvt_pk_bf16_f32 v158, v170, v171
	v_cvt_pk_bf16_f32 v159, v172, v173
	v_cvt_pk_bf16_f32 v160, v174, v175
	v_cvt_pk_bf16_f32 v161, v176, v177
	v_cvt_pk_bf16_f32 v162, v178, v179
	v_cvt_pk_bf16_f32 v163, v180, v181
	s_lshl_b32 vcc_lo, s19, 11
	s_add_u32 vcc_lo, vcc_lo, 0x2c00000
	s_add_u32 s100, s16, vcc_lo
	s_addc_u32 s101, s17, 0
	global_store_dwordx2 v137, v[156:157], s[100:101] offset:0
	global_store_dwordx2 v137, v[158:159], s[100:101] offset:512
	global_store_dwordx2 v137, v[160:161], s[100:101] offset:1024
	global_store_dwordx2 v137, v[162:163], s[100:101] offset:1536
	v_mul_f32_e32 v138, v166, v166
	v_mul_f32_e32 v149, v167, v167
	v_mul_f32_e32 v150, v168, v168
	v_mul_f32_e32 v154, v169, v169
	v_fma_f32 v138, v170, v170, v138
	v_fma_f32 v149, v171, v171, v149
	v_fma_f32 v150, v172, v172, v150
	v_fma_f32 v154, v173, v173, v154
	v_fma_f32 v138, v174, v174, v138
	v_fma_f32 v149, v175, v175, v149
	v_fma_f32 v150, v176, v176, v150
	v_fma_f32 v154, v177, v177, v154
	v_fma_f32 v138, v178, v178, v138
	v_fma_f32 v149, v179, v179, v149
	v_fma_f32 v150, v180, v180, v150
	v_fma_f32 v154, v181, v181, v154
	v_add_f32_e32 v138, v138, v149
	v_add_f32_e32 v150, v150, v154
	v_add_f32_e32 v138, v138, v150
	s_nop 1
	v_add_f32_dpp v138, v138, v138 quad_perm:[1,0,3,2] row_mask:0xf bank_mask:0xf
	s_nop 1
	v_add_f32_dpp v138, v138, v138 quad_perm:[2,3,0,1] row_mask:0xf bank_mask:0xf
	s_nop 1
	v_add_f32_dpp v138, v138, v138 row_half_mirror row_mask:0xf bank_mask:0xf
	s_nop 1
	v_add_f32_dpp v138, v138, v138 row_mirror row_mask:0xf bank_mask:0xf
	v_mov_b32_e32 v139, v138
	s_nop 1
	v_permlane16_swap_b32_e32 v138, v139
	v_add_f32_e32 v138, v138, v139
	v_mov_b32_e32 v139, v138
	s_nop 1
	v_permlane32_swap_b32_e32 v138, v139
	v_add_f32_e32 v138, v138, v139
	v_mul_f32_e32 v138, 0x3a800000, v138
	v_add_f32_e32 v138, 0x358637bd, v138
	v_rsq_f32_e32 v140, v138
	s_nop 0
	v_mul_f32_e32 v120, v166, v140
	v_mul_f32_e32 v121, v167, v140
	v_mul_f32_e32 v122, v168, v140
	v_mul_f32_e32 v123, v169, v140
	v_mul_f32_e32 v124, v170, v140
	v_mul_f32_e32 v125, v171, v140
	v_mul_f32_e32 v126, v172, v140
	v_mul_f32_e32 v127, v173, v140
	v_mul_f32_e32 v128, v174, v140
	v_mul_f32_e32 v129, v175, v140
	v_mul_f32_e32 v130, v176, v140
	v_mul_f32_e32 v131, v177, v140
	v_mul_f32_e32 v132, v178, v140
	v_mul_f32_e32 v133, v179, v140
	v_mul_f32_e32 v134, v180, v140
	v_mul_f32_e32 v135, v181, v140
	v_fma_f32 v120, v120, v88, v104
	v_fma_f32 v121, v121, v89, v105
	v_fma_f32 v122, v122, v90, v106
	v_fma_f32 v123, v123, v91, v107
	v_fma_f32 v124, v124, v92, v108
	v_fma_f32 v125, v125, v93, v109
	v_fma_f32 v126, v126, v94, v110
	v_fma_f32 v127, v127, v95, v111
	v_fma_f32 v128, v128, v96, v112
	v_fma_f32 v129, v129, v97, v113
	v_fma_f32 v130, v130, v98, v114
	v_fma_f32 v131, v131, v99, v115
	v_fma_f32 v132, v132, v100, v116
	v_fma_f32 v133, v133, v101, v117
	v_fma_f32 v134, v134, v102, v118
	v_fma_f32 v135, v135, v103, v119
	v_cvt_pk_bf16_f32 v156, v120, v121
	v_cvt_pk_bf16_f32 v157, v122, v123
	v_cvt_pk_bf16_f32 v158, v124, v125
	v_cvt_pk_bf16_f32 v159, v126, v127
	v_cvt_pk_bf16_f32 v160, v128, v129
	v_cvt_pk_bf16_f32 v161, v130, v131
	v_cvt_pk_bf16_f32 v162, v132, v133
	v_cvt_pk_bf16_f32 v163, v134, v135
	s_lshl_b32 vcc_lo, s19, 11
	s_add_u32 vcc_lo, vcc_lo, 0x2c00000
	s_add_u32 s100, s14, vcc_lo
	s_addc_u32 s101, s15, 0
	global_store_dwordx2 v137, v[156:157], s[100:101] offset:0
	global_store_dwordx2 v137, v[158:159], s[100:101] offset:512
	global_store_dwordx2 v137, v[160:161], s[100:101] offset:1024
	global_store_dwordx2 v137, v[162:163], s[100:101] offset:1536
	s_add_u32 s100, s20, 0x14000
	s_addc_u32 s101, s21, 0
	global_load_dwordx4 v[72:75], v136, s[100:101] offset:0
	global_load_dwordx4 v[76:79], v136, s[100:101] offset:1024
	global_load_dwordx4 v[80:83], v136, s[100:101] offset:2048
	global_load_dwordx4 v[84:87], v136, s[100:101] offset:3072
	s_load_dwordx2 s[98:99], s[4:5], 0x38
	s_waitcnt lgkmcnt(0)
; __device__ __forceinline__ void row_phase(const Params& P, int glayer, int layer, int xsrc, bool hasY, int gate_idx, const float* gpost,
;                           int xdst, bool doH, const float* gpre, int sh_idx, int nrows) {
;     ...
;     for (int u = 0; u < 4; ++u) {
;       const int R = rb + u * stride;
;       if (R < nrows) {
;         if (xsrc != 0 && R < N_X) {
;           const u16* xs_ = ((xsrc == 1) ? resA : P.zf) + (long)R * 1024;
; #pragma unroll
;           for (int i = 0; i < 4; ++i) {
;             const uint2 t2 = *reinterpret_cast<const uint2*>(xs_ + (i * 64 + lane) * 4);
;             xr[u][i].x = t2.x; xr[u][i].y = t2.y;
;           }
;         } else {
;           const float* xin_;
;           if (xsrc == 0) xin_ = R < N_X ? P.x + (long)R * 1024 : P.ctx + (long)(R - N_X) * 1024;
;           else           xin_ = P.xc + (long)(R - N_X) * 1024;
; #pragma unroll
;           for (int i = 0; i < 4; ++i) xr[u][i] = *reinterpret_cast<const uint4*>(xin_ + (i * 64 + lane) * 4);
;         }
;         if (hasY) {
;           const u16* y_ = P.hy + (long)R * 1024;
; #pragma unroll
;           for (int i = 0; i < 4; ++i) yy[u][i] = *reinterpret_cast<const uint2*>(y_ + (i * 64 + lane) * 4);
;         }
;     ...
; #pragma unroll
;           for (int i = 0; i < 4; ++i) {
;             const int col = (i * 64 + lane) * 4;
;             const float4 gt = *reinterpret_cast<const float4*>(modg + gate_idx * 1024 + col);
;             const float4 gp = *reinterpret_cast<const float4*>(gpost + col);
;             xv[i].x += gt.x * (yv[i].x * rstd * gp.x); xv[i].y += gt.y * (yv[i].y * rstd * gp.y);
;             xv[i].z += gt.z * (yv[i].z * rstd * gp.z); xv[i].w += gt.w * (yv[i].w * rstd * gp.w);
;           }
;     ...
;             const float4 g = *reinterpret_cast<const float4*>(gpre + col);
;             const float4 sh = *reinterpret_cast<const float4*>(modp + sh_idx * 1024 + col);
;             const float4 sc = *reinterpret_cast<const float4*>(modp + (sh_idx + 1) * 1024 + col);
	global_load_dwordx4 v[120:123], v136, s[98:99] offset:0
	global_load_dwordx4 v[124:127], v136, s[98:99] offset:1024
	global_load_dwordx4 v[128:131], v136, s[98:99] offset:2048
	global_load_dwordx4 v[132:135], v136, s[98:99] offset:3072
	s_add_u32 s100, s20, 0x15000
	s_addc_u32 s101, s21, 0
	global_load_dwordx4 v[104:107], v136, s[100:101] offset:0
	global_load_dwordx4 v[108:111], v136, s[100:101] offset:1024
	global_load_dwordx4 v[112:115], v136, s[100:101] offset:2048
	global_load_dwordx4 v[116:119], v136, s[100:101] offset:3072
	s_add_u32 s100, s100, 0x1000
	s_addc_u32 s101, s101, 0
	global_load_dwordx4 v[166:169], v136, s[100:101] offset:0
	global_load_dwordx4 v[170:173], v136, s[100:101] offset:1024
	global_load_dwordx4 v[174:177], v136, s[100:101] offset:2048
	global_load_dwordx4 v[178:181], v136, s[100:101] offset:3072
	s_load_dwordx2 s[98:99], s[4:5], 0x40
	s_waitcnt lgkmcnt(0)
	global_load_dwordx4 v[88:91], v136, s[98:99] offset:0
	global_load_dwordx4 v[92:95], v136, s[98:99] offset:1024
	global_load_dwordx4 v[96:99], v136, s[98:99] offset:2048
	global_load_dwordx4 v[100:103], v136, s[98:99] offset:3072
	s_waitcnt vmcnt(0)
	v_mul_f32_e32 v72, v72, v120
	v_mul_f32_e32 v73, v73, v121
	v_mul_f32_e32 v74, v74, v122
	v_mul_f32_e32 v75, v75, v123
	v_mul_f32_e32 v76, v76, v124
	v_mul_f32_e32 v77, v77, v125
	v_mul_f32_e32 v78, v78, v126
	v_mul_f32_e32 v79, v79, v127
	v_mul_f32_e32 v80, v80, v128
	v_mul_f32_e32 v81, v81, v129
	v_mul_f32_e32 v82, v82, v130
	v_mul_f32_e32 v83, v83, v131
	v_mul_f32_e32 v84, v84, v132
	v_mul_f32_e32 v85, v85, v133
	v_mul_f32_e32 v86, v86, v134
	v_mul_f32_e32 v87, v87, v135
	v_fma_f32 v88, v88, v166, v88
	v_fma_f32 v89, v89, v167, v89
	v_fma_f32 v90, v90, v168, v90
	v_fma_f32 v91, v91, v169, v91
	v_fma_f32 v92, v92, v170, v92
	v_fma_f32 v93, v93, v171, v93
	v_fma_f32 v94, v94, v172, v94
	v_fma_f32 v95, v95, v173, v95
	v_fma_f32 v96, v96, v174, v96
	v_fma_f32 v97, v97, v175, v97
	v_fma_f32 v98, v98, v176, v98
	v_fma_f32 v99, v99, v177, v99
	v_fma_f32 v100, v100, v178, v100
	v_fma_f32 v101, v101, v179, v101
	v_fma_f32 v102, v102, v180, v102
	v_fma_f32 v103, v103, v181, v103
	s_lshl_b32 vcc_lo, s19, 12
	s_add_u32 vcc_lo, vcc_lo, 0x7800000
	s_add_u32 s100, s12, vcc_lo
	s_addc_u32 s101, s13, 0
	global_load_dwordx4 v[166:169], v136, s[100:101] offset:0
	global_load_dwordx4 v[170:173], v136, s[100:101] offset:1024
	global_load_dwordx4 v[174:177], v136, s[100:101] offset:2048
	global_load_dwordx4 v[178:181], v136, s[100:101] offset:3072
	s_lshl_b32 vcc_lo, s19, 11
	s_add_u32 vcc_lo, vcc_lo, 0x3c00000
	s_add_u32 s100, s14, vcc_lo
	s_addc_u32 s101, s15, 0
	global_load_dwordx2 v[182:183], v137, s[100:101] offset:0
	global_load_dwordx2 v[184:185], v137, s[100:101] offset:512
	global_load_dwordx2 v[186:187], v137, s[100:101] offset:1024
	global_load_dwordx2 v[188:189], v137, s[100:101] offset:1536
	v_lshlrev_b32_e32 v120, 16, v48
	v_and_b32_e32 v121, 0xffff0000, v48
	v_lshlrev_b32_e32 v122, 16, v49
	v_and_b32_e32 v123, 0xffff0000, v49
	v_lshlrev_b32_e32 v124, 16, v50
	v_and_b32_e32 v125, 0xffff0000, v50
	v_lshlrev_b32_e32 v126, 16, v51
	v_and_b32_e32 v127, 0xffff0000, v51
	v_lshlrev_b32_e32 v128, 16, v52
	v_and_b32_e32 v129, 0xffff0000, v52
	v_lshlrev_b32_e32 v130, 16, v53
	v_and_b32_e32 v131, 0xffff0000, v53
	v_lshlrev_b32_e32 v132, 16, v54
	v_and_b32_e32 v133, 0xffff0000, v54
	v_lshlrev_b32_e32 v134, 16, v55
	v_and_b32_e32 v135, 0xffff0000, v55
	v_mul_f32_e32 v138, v120, v120
	v_mul_f32_e32 v149, v121, v121
	v_mul_f32_e32 v150, v122, v122
	v_mul_f32_e32 v154, v123, v123
	v_fma_f32 v138, v124, v124, v138
	v_fma_f32 v149, v125, v125, v149
	v_fma_f32 v150, v126, v126, v150
	v_fma_f32 v154, v127, v127, v154
	v_fma_f32 v138, v128, v128, v138
	v_fma_f32 v149, v129, v129, v149
	v_fma_f32 v150, v130, v130, v150
	v_fma_f32 v154, v131, v131, v154
	v_fma_f32 v138, v132, v132, v138
	v_fma_f32 v149, v133, v133, v149
	v_fma_f32 v150, v134, v134, v150
	v_fma_f32 v154, v135, v135, v154
	v_add_f32_e32 v138, v138, v149
	v_add_f32_e32 v150, v150, v154
	v_add_f32_e32 v138, v138, v150
	s_nop 1
	v_add_f32_dpp v138, v138, v138 quad_perm:[1,0,3,2] row_mask:0xf bank_mask:0xf
	s_nop 1
	v_add_f32_dpp v138, v138, v138 quad_perm:[2,3,0,1] row_mask:0xf bank_mask:0xf
	s_nop 1
	v_add_f32_dpp v138, v138, v138 row_half_mirror row_mask:0xf bank_mask:0xf
	s_nop 1
	v_add_f32_dpp v138, v138, v138 row_mirror row_mask:0xf bank_mask:0xf
	v_mov_b32_e32 v139, v138
	s_nop 1
	v_permlane16_swap_b32_e32 v138, v139
	v_add_f32_e32 v138, v138, v139
	v_mov_b32_e32 v139, v138
	s_nop 1
	v_permlane32_swap_b32_e32 v138, v139
	v_add_f32_e32 v138, v138, v139
	v_mul_f32_e32 v138, 0x3a800000, v138
	v_add_f32_e32 v138, 0x358637bd, v138
	v_rsq_f32_e32 v140, v138
	s_nop 0
	v_mul_f32_e32 v120, v120, v140
	v_mul_f32_e32 v121, v121, v140
	v_mul_f32_e32 v122, v122, v140
	v_mul_f32_e32 v123, v123, v140
	v_mul_f32_e32 v124, v124, v140
	v_mul_f32_e32 v125, v125, v140
	v_mul_f32_e32 v126, v126, v140
	v_mul_f32_e32 v127, v127, v140
	v_mul_f32_e32 v128, v128, v140
	v_mul_f32_e32 v129, v129, v140
	v_mul_f32_e32 v130, v130, v140
	v_mul_f32_e32 v131, v131, v140
	v_mul_f32_e32 v132, v132, v140
	v_mul_f32_e32 v133, v133, v140
	v_mul_f32_e32 v134, v134, v140
	v_mul_f32_e32 v135, v135, v140
	v_fma_f32 v0, v120, v72, v0
	v_fma_f32 v1, v121, v73, v1
	v_fma_f32 v2, v122, v74, v2
	v_fma_f32 v3, v123, v75, v3
	v_fma_f32 v4, v124, v76, v4
	v_fma_f32 v5, v125, v77, v5
	v_fma_f32 v6, v126, v78, v6
	v_fma_f32 v7, v127, v79, v7
	v_fma_f32 v8, v128, v80, v8
	v_fma_f32 v9, v129, v81, v9
	v_fma_f32 v10, v130, v82, v10
	v_fma_f32 v11, v131, v83, v11
	v_fma_f32 v12, v132, v84, v12
	v_fma_f32 v13, v133, v85, v13
; __device__ __forceinline__ void row_phase(const Params& P, int glayer, int layer, int xsrc, bool hasY, int gate_idx, const float* gpost,
;                           int xdst, bool doH, const float* gpre, int sh_idx, int nrows) {
;     ...
;         if (hasY) {
;           float4 yv[4];
;           float ss = 0.f;
; #pragma unroll
;           for (int i = 0; i < 4; ++i) {
;             const uint2 raw = yy[u][i];
;             yv[i].x = bf2f((u16)(raw.x & 0xffff)); yv[i].y = bf2f((u16)(raw.x >> 16));
;             yv[i].z = bf2f((u16)(raw.y & 0xffff)); yv[i].w = bf2f((u16)(raw.y >> 16));
;             ss += yv[i].x * yv[i].x + yv[i].y * yv[i].y + yv[i].z * yv[i].z + yv[i].w * yv[i].w;
;           }
;           ss = wave_sum(ss);
;           const float rstd = __builtin_amdgcn_rsqf(ss * (1.f / 1024.f) + EPSF);
; #pragma unroll
;           for (int i = 0; i < 4; ++i) {
;             const int col = (i * 64 + lane) * 4;
;             const float4 gt = *reinterpret_cast<const float4*>(modg + gate_idx * 1024 + col);
;             const float4 gp = *reinterpret_cast<const float4*>(gpost + col);
;             xv[i].x += gt.x * (yv[i].x * rstd * gp.x); xv[i].y += gt.y * (yv[i].y * rstd * gp.y);
;     ...
;         if (doH) {
;           float ss = 0.f;
; #pragma unroll
;           for (int i = 0; i < 4; ++i) ss += xv[i].x * xv[i].x + xv[i].y * xv[i].y + xv[i].z * xv[i].z + xv[i].w * xv[i].w;
;           ss = wave_sum(ss);
;           const float rstd = __builtin_amdgcn_rsqf(ss * (1.f / 1024.f) + EPSF);
;           u16* h = P.hy + (long)row * 1024;
; #pragma unroll
;           for (int i = 0; i < 4; ++i) {
;             const int col = (i * 64 + lane) * 4;
;             const float4 g = *reinterpret_cast<const float4*>(gpre + col);
;             const float4 sh = *reinterpret_cast<const float4*>(modp + sh_idx * 1024 + col);
;             const float4 sc = *reinterpret_cast<const float4*>(modp + (sh_idx + 1) * 1024 + col);
;             const unsigned h0 = f2bf(xv[i].x * rstd * g.x * (1.f + sc.x) + sh.x);
;             const unsigned h1 = f2bf(xv[i].y * rstd * g.y * (1.f + sc.y) + sh.y);
;             const unsigned h2 = f2bf(xv[i].z * rstd * g.z * (1.f + sc.z) + sh.z);
;             const unsigned h3 = f2bf(xv[i].w * rstd * g.w * (1.f + sc.w) + sh.w);
;             *reinterpret_cast<uint2*>(h + col) = make_uint2(h0 | (h1 << 16), h2 | (h3 << 16));
;           }
;         }
	v_fma_f32 v14, v134, v86, v14
	v_fma_f32 v15, v135, v87, v15
	v_cvt_pk_bf16_f32 v156, v0, v1
	v_cvt_pk_bf16_f32 v157, v2, v3
	v_cvt_pk_bf16_f32 v158, v4, v5
	v_cvt_pk_bf16_f32 v159, v6, v7
	v_cvt_pk_bf16_f32 v160, v8, v9
	v_cvt_pk_bf16_f32 v161, v10, v11
	v_cvt_pk_bf16_f32 v162, v12, v13
	v_cvt_pk_bf16_f32 v163, v14, v15
	s_lshl_b32 vcc_lo, s19, 11
	s_add_u32 vcc_lo, vcc_lo, 0x3000000
	s_add_u32 s100, s16, vcc_lo
	s_addc_u32 s101, s17, 0
	global_store_dwordx2 v137, v[156:157], s[100:101] offset:0
	global_store_dwordx2 v137, v[158:159], s[100:101] offset:512
	global_store_dwordx2 v137, v[160:161], s[100:101] offset:1024
	global_store_dwordx2 v137, v[162:163], s[100:101] offset:1536
	v_mul_f32_e32 v138, v0, v0
	v_mul_f32_e32 v149, v1, v1
	v_mul_f32_e32 v150, v2, v2
	v_mul_f32_e32 v154, v3, v3
	v_fma_f32 v138, v4, v4, v138
	v_fma_f32 v149, v5, v5, v149
	v_fma_f32 v150, v6, v6, v150
	v_fma_f32 v154, v7, v7, v154
	v_fma_f32 v138, v8, v8, v138
	v_fma_f32 v149, v9, v9, v149
	v_fma_f32 v150, v10, v10, v150
	v_fma_f32 v154, v11, v11, v154
	v_fma_f32 v138, v12, v12, v138
	v_fma_f32 v149, v13, v13, v149
	v_fma_f32 v150, v14, v14, v150
	v_fma_f32 v154, v15, v15, v154
	v_add_f32_e32 v138, v138, v149
	v_add_f32_e32 v150, v150, v154
	v_add_f32_e32 v138, v138, v150
	s_nop 1
	v_add_f32_dpp v138, v138, v138 quad_perm:[1,0,3,2] row_mask:0xf bank_mask:0xf
	s_nop 1
	v_add_f32_dpp v138, v138, v138 quad_perm:[2,3,0,1] row_mask:0xf bank_mask:0xf
	s_nop 1
	v_add_f32_dpp v138, v138, v138 row_half_mirror row_mask:0xf bank_mask:0xf
	s_nop 1
	v_add_f32_dpp v138, v138, v138 row_mirror row_mask:0xf bank_mask:0xf
	v_mov_b32_e32 v139, v138
	s_nop 1
	v_permlane16_swap_b32_e32 v138, v139
	v_add_f32_e32 v138, v138, v139
	v_mov_b32_e32 v139, v138
	s_nop 1
	v_permlane32_swap_b32_e32 v138, v139
	v_add_f32_e32 v138, v138, v139
	v_mul_f32_e32 v138, 0x3a800000, v138
	v_add_f32_e32 v138, 0x358637bd, v138
	v_rsq_f32_e32 v140, v138
	s_nop 0
	v_mul_f32_e32 v120, v0, v140
	v_mul_f32_e32 v121, v1, v140
	v_mul_f32_e32 v122, v2, v140
	v_mul_f32_e32 v123, v3, v140
	v_mul_f32_e32 v124, v4, v140
	v_mul_f32_e32 v125, v5, v140
	v_mul_f32_e32 v126, v6, v140
	v_mul_f32_e32 v127, v7, v140
	v_mul_f32_e32 v128, v8, v140
	v_mul_f32_e32 v129, v9, v140
	v_mul_f32_e32 v130, v10, v140
	v_mul_f32_e32 v131, v11, v140
	v_mul_f32_e32 v132, v12, v140
	v_mul_f32_e32 v133, v13, v140
	v_mul_f32_e32 v134, v14, v140
	v_mul_f32_e32 v135, v15, v140
	v_fma_f32 v120, v120, v88, v104
	v_fma_f32 v121, v121, v89, v105
	v_fma_f32 v122, v122, v90, v106
	v_fma_f32 v123, v123, v91, v107
	v_fma_f32 v124, v124, v92, v108
	v_fma_f32 v125, v125, v93, v109
	v_fma_f32 v126, v126, v94, v110
	v_fma_f32 v127, v127, v95, v111
	v_fma_f32 v128, v128, v96, v112
	v_fma_f32 v129, v129, v97, v113
	v_fma_f32 v130, v130, v98, v114
	v_fma_f32 v131, v131, v99, v115
	v_fma_f32 v132, v132, v100, v116
	v_fma_f32 v133, v133, v101, v117
	v_fma_f32 v134, v134, v102, v118
	v_fma_f32 v135, v135, v103, v119
	v_cvt_pk_bf16_f32 v156, v120, v121
	v_cvt_pk_bf16_f32 v157, v122, v123
	v_cvt_pk_bf16_f32 v158, v124, v125
	v_cvt_pk_bf16_f32 v159, v126, v127
	v_cvt_pk_bf16_f32 v160, v128, v129
	v_cvt_pk_bf16_f32 v161, v130, v131
	v_cvt_pk_bf16_f32 v162, v132, v133
	v_cvt_pk_bf16_f32 v163, v134, v135
	s_lshl_b32 vcc_lo, s19, 11
	s_add_u32 vcc_lo, vcc_lo, 0x3000000
	s_add_u32 s100, s14, vcc_lo
	s_addc_u32 s101, s15, 0
	global_store_dwordx2 v137, v[156:157], s[100:101] offset:0
	global_store_dwordx2 v137, v[158:159], s[100:101] offset:512
	global_store_dwordx2 v137, v[160:161], s[100:101] offset:1024
	global_store_dwordx2 v137, v[162:163], s[100:101] offset:1536
	v_lshlrev_b32_e32 v120, 16, v56
	v_and_b32_e32 v121, 0xffff0000, v56
	v_lshlrev_b32_e32 v122, 16, v57
	v_and_b32_e32 v123, 0xffff0000, v57
	v_lshlrev_b32_e32 v124, 16, v58
	v_and_b32_e32 v125, 0xffff0000, v58
	v_lshlrev_b32_e32 v126, 16, v59
	v_and_b32_e32 v127, 0xffff0000, v59
	v_lshlrev_b32_e32 v128, 16, v60
	v_and_b32_e32 v129, 0xffff0000, v60
	v_lshlrev_b32_e32 v130, 16, v61
	v_and_b32_e32 v131, 0xffff0000, v61
	v_lshlrev_b32_e32 v132, 16, v62
	v_and_b32_e32 v133, 0xffff0000, v62
	v_lshlrev_b32_e32 v134, 16, v63
	v_and_b32_e32 v135, 0xffff0000, v63
	v_mul_f32_e32 v138, v120, v120
	v_mul_f32_e32 v149, v121, v121
	v_mul_f32_e32 v150, v122, v122
	v_mul_f32_e32 v154, v123, v123
	v_fma_f32 v138, v124, v124, v138
	v_fma_f32 v149, v125, v125, v149
	v_fma_f32 v150, v126, v126, v150
	v_fma_f32 v154, v127, v127, v154
	v_fma_f32 v138, v128, v128, v138
	v_fma_f32 v149, v129, v129, v149
	v_fma_f32 v150, v130, v130, v150
	v_fma_f32 v154, v131, v131, v154
	v_fma_f32 v138, v132, v132, v138
	v_fma_f32 v149, v133, v133, v149
	v_fma_f32 v150, v134, v134, v150
	v_fma_f32 v154, v135, v135, v154
	v_add_f32_e32 v138, v138, v149
	v_add_f32_e32 v150, v150, v154
	v_add_f32_e32 v138, v138, v150
	s_nop 1
	v_add_f32_dpp v138, v138, v138 quad_perm:[1,0,3,2] row_mask:0xf bank_mask:0xf
	s_nop 1
	v_add_f32_dpp v138, v138, v138 quad_perm:[2,3,0,1] row_mask:0xf bank_mask:0xf
	s_nop 1
	v_add_f32_dpp v138, v138, v138 row_half_mirror row_mask:0xf bank_mask:0xf
	s_nop 1
	v_add_f32_dpp v138, v138, v138 row_mirror row_mask:0xf bank_mask:0xf
	v_mov_b32_e32 v139, v138
	s_nop 1
	v_permlane16_swap_b32_e32 v138, v139
	v_add_f32_e32 v138, v138, v139
	v_mov_b32_e32 v139, v138
	s_nop 1
	v_permlane32_swap_b32_e32 v138, v139
	v_add_f32_e32 v138, v138, v139
	v_mul_f32_e32 v138, 0x3a800000, v138
	v_add_f32_e32 v138, 0x358637bd, v138
	v_rsq_f32_e32 v140, v138
	s_nop 0
	v_mul_f32_e32 v120, v120, v140
	v_mul_f32_e32 v121, v121, v140
	v_mul_f32_e32 v122, v122, v140
	v_mul_f32_e32 v123, v123, v140
	v_mul_f32_e32 v124, v124, v140
	v_mul_f32_e32 v125, v125, v140
; __device__ __forceinline__ void row_phase(const Params& P, int glayer, int layer, int xsrc, bool hasY, int gate_idx, const float* gpost,
;                           int xdst, bool doH, const float* gpre, int sh_idx, int nrows) {
;     ...
;         if (hasY) {
;           float4 yv[4];
;           float ss = 0.f;
; #pragma unroll
;           for (int i = 0; i < 4; ++i) {
;             const uint2 raw = yy[u][i];
;             yv[i].x = bf2f((u16)(raw.x & 0xffff)); yv[i].y = bf2f((u16)(raw.x >> 16));
;     ...
;         if (xdst == 3 || (xdst == 1 && row >= N_X)) {
;           float* xout = (xdst == 3) ? P.out + (long)row * 1024 : P.xc + (long)(row - N_X) * 1024;
; #pragma unroll
;           for (int i = 0; i < 4; ++i) *reinterpret_cast<float4*>(xout + (i * 64 + lane) * 4) = xv[i];
;         } else if (xdst != 0) {
;           u16* xo = ((xdst == 1) ? resA : P.zf) + (long)row * 1024;
; #pragma unroll
;           for (int i = 0; i < 4; ++i) {
;             const unsigned b0 = f2bf(xv[i].x), b1 = f2bf(xv[i].y), b2 = f2bf(xv[i].z), b3 = f2bf(xv[i].w);
;             *reinterpret_cast<uint2*>(xo + (i * 64 + lane) * 4) = make_uint2(b0 | (b1 << 16), b2 | (b3 << 16));
;           }
;         }
;         if (doH) {
;           float ss = 0.f;
; #pragma unroll
;           for (int i = 0; i < 4; ++i) ss += xv[i].x * xv[i].x + xv[i].y * xv[i].y + xv[i].z * xv[i].z + xv[i].w * xv[i].w;
;           ss = wave_sum(ss);
;           const float rstd = __builtin_amdgcn_rsqf(ss * (1.f / 1024.f) + EPSF);
;           u16* h = P.hy + (long)row * 1024;
; #pragma unroll
;           for (int i = 0; i < 4; ++i) {
;             const int col = (i * 64 + lane) * 4;
;             const float4 g = *reinterpret_cast<const float4*>(gpre + col);
;             const float4 sh = *reinterpret_cast<const float4*>(modp + sh_idx * 1024 + col);
;             const float4 sc = *reinterpret_cast<const float4*>(modp + (sh_idx + 1) * 1024 + col);
;             const unsigned h0 = f2bf(xv[i].x * rstd * g.x * (1.f + sc.x) + sh.x);
;             const unsigned h1 = f2bf(xv[i].y * rstd * g.y * (1.f + sc.y) + sh.y);
;             const unsigned h2 = f2bf(xv[i].z * rstd * g.z * (1.f + sc.z) + sh.z);
;             const unsigned h3 = f2bf(xv[i].w * rstd * g.w * (1.f + sc.w) + sh.w);
;             *reinterpret_cast<uint2*>(h + col) = make_uint2(h0 | (h1 << 16), h2 | (h3 << 16));
;           }
;         }
	v_mul_f32_e32 v126, v126, v140
	v_mul_f32_e32 v127, v127, v140
	v_mul_f32_e32 v128, v128, v140
	v_mul_f32_e32 v129, v129, v140
	v_mul_f32_e32 v130, v130, v140
	v_mul_f32_e32 v131, v131, v140
	v_mul_f32_e32 v132, v132, v140
	v_mul_f32_e32 v133, v133, v140
	v_mul_f32_e32 v134, v134, v140
	v_mul_f32_e32 v135, v135, v140
	v_fma_f32 v16, v120, v72, v16
	v_fma_f32 v17, v121, v73, v17
	v_fma_f32 v18, v122, v74, v18
	v_fma_f32 v19, v123, v75, v19
	v_fma_f32 v20, v124, v76, v20
	v_fma_f32 v21, v125, v77, v21
	v_fma_f32 v22, v126, v78, v22
	v_fma_f32 v23, v127, v79, v23
	v_fma_f32 v24, v128, v80, v24
	v_fma_f32 v25, v129, v81, v25
	v_fma_f32 v26, v130, v82, v26
	v_fma_f32 v27, v131, v83, v27
	v_fma_f32 v28, v132, v84, v28
	v_fma_f32 v29, v133, v85, v29
	v_fma_f32 v30, v134, v86, v30
	v_fma_f32 v31, v135, v87, v31
	v_cvt_pk_bf16_f32 v156, v16, v17
	v_cvt_pk_bf16_f32 v157, v18, v19
	v_cvt_pk_bf16_f32 v158, v20, v21
	v_cvt_pk_bf16_f32 v159, v22, v23
	v_cvt_pk_bf16_f32 v160, v24, v25
	v_cvt_pk_bf16_f32 v161, v26, v27
	v_cvt_pk_bf16_f32 v162, v28, v29
	v_cvt_pk_bf16_f32 v163, v30, v31
	s_lshl_b32 vcc_lo, s19, 11
	s_add_u32 vcc_lo, vcc_lo, 0x3400000
	s_add_u32 s100, s16, vcc_lo
	s_addc_u32 s101, s17, 0
	global_store_dwordx2 v137, v[156:157], s[100:101] offset:0
	global_store_dwordx2 v137, v[158:159], s[100:101] offset:512
	global_store_dwordx2 v137, v[160:161], s[100:101] offset:1024
	global_store_dwordx2 v137, v[162:163], s[100:101] offset:1536
	v_mul_f32_e32 v138, v16, v16
	v_mul_f32_e32 v149, v17, v17
	v_mul_f32_e32 v150, v18, v18
	v_mul_f32_e32 v154, v19, v19
	v_fma_f32 v138, v20, v20, v138
	v_fma_f32 v149, v21, v21, v149
	v_fma_f32 v150, v22, v22, v150
	v_fma_f32 v154, v23, v23, v154
	v_fma_f32 v138, v24, v24, v138
	v_fma_f32 v149, v25, v25, v149
	v_fma_f32 v150, v26, v26, v150
	v_fma_f32 v154, v27, v27, v154
	v_fma_f32 v138, v28, v28, v138
	v_fma_f32 v149, v29, v29, v149
	v_fma_f32 v150, v30, v30, v150
	v_fma_f32 v154, v31, v31, v154
	v_add_f32_e32 v138, v138, v149
	v_add_f32_e32 v150, v150, v154
	v_add_f32_e32 v138, v138, v150
	s_nop 1
	v_add_f32_dpp v138, v138, v138 quad_perm:[1,0,3,2] row_mask:0xf bank_mask:0xf
	s_nop 1
	v_add_f32_dpp v138, v138, v138 quad_perm:[2,3,0,1] row_mask:0xf bank_mask:0xf
	s_nop 1
	v_add_f32_dpp v138, v138, v138 row_half_mirror row_mask:0xf bank_mask:0xf
	s_nop 1
	v_add_f32_dpp v138, v138, v138 row_mirror row_mask:0xf bank_mask:0xf
	v_mov_b32_e32 v139, v138
	s_nop 1
	v_permlane16_swap_b32_e32 v138, v139
	v_add_f32_e32 v138, v138, v139
	v_mov_b32_e32 v139, v138
	s_nop 1
	v_permlane32_swap_b32_e32 v138, v139
	v_add_f32_e32 v138, v138, v139
	v_mul_f32_e32 v138, 0x3a800000, v138
	v_add_f32_e32 v138, 0x358637bd, v138
	v_rsq_f32_e32 v140, v138
	s_nop 0
	v_mul_f32_e32 v120, v16, v140
	v_mul_f32_e32 v121, v17, v140
	v_mul_f32_e32 v122, v18, v140
	v_mul_f32_e32 v123, v19, v140
	v_mul_f32_e32 v124, v20, v140
	v_mul_f32_e32 v125, v21, v140
	v_mul_f32_e32 v126, v22, v140
	v_mul_f32_e32 v127, v23, v140
	v_mul_f32_e32 v128, v24, v140
	v_mul_f32_e32 v129, v25, v140
	v_mul_f32_e32 v130, v26, v140
	v_mul_f32_e32 v131, v27, v140
	v_mul_f32_e32 v132, v28, v140
	v_mul_f32_e32 v133, v29, v140
	v_mul_f32_e32 v134, v30, v140
	v_mul_f32_e32 v135, v31, v140
	v_fma_f32 v120, v120, v88, v104
	v_fma_f32 v121, v121, v89, v105
	v_fma_f32 v122, v122, v90, v106
	v_fma_f32 v123, v123, v91, v107
	v_fma_f32 v124, v124, v92, v108
	v_fma_f32 v125, v125, v93, v109
	v_fma_f32 v126, v126, v94, v110
	v_fma_f32 v127, v127, v95, v111
	v_fma_f32 v128, v128, v96, v112
	v_fma_f32 v129, v129, v97, v113
	v_fma_f32 v130, v130, v98, v114
	v_fma_f32 v131, v131, v99, v115
	v_fma_f32 v132, v132, v100, v116
	v_fma_f32 v133, v133, v101, v117
	v_fma_f32 v134, v134, v102, v118
	v_fma_f32 v135, v135, v103, v119
	v_cvt_pk_bf16_f32 v156, v120, v121
	v_cvt_pk_bf16_f32 v157, v122, v123
	v_cvt_pk_bf16_f32 v158, v124, v125
	v_cvt_pk_bf16_f32 v159, v126, v127
	v_cvt_pk_bf16_f32 v160, v128, v129
	v_cvt_pk_bf16_f32 v161, v130, v131
	v_cvt_pk_bf16_f32 v162, v132, v133
	v_cvt_pk_bf16_f32 v163, v134, v135
	s_lshl_b32 vcc_lo, s19, 11
	s_add_u32 vcc_lo, vcc_lo, 0x3400000
	s_add_u32 s100, s14, vcc_lo
	s_addc_u32 s101, s15, 0
	global_store_dwordx2 v137, v[156:157], s[100:101] offset:0
	global_store_dwordx2 v137, v[158:159], s[100:101] offset:512
	global_store_dwordx2 v137, v[160:161], s[100:101] offset:1024
	global_store_dwordx2 v137, v[162:163], s[100:101] offset:1536
	v_lshlrev_b32_e32 v120, 16, v64
	v_and_b32_e32 v121, 0xffff0000, v64
	v_lshlrev_b32_e32 v122, 16, v65
	v_and_b32_e32 v123, 0xffff0000, v65
	v_lshlrev_b32_e32 v124, 16, v66
	v_and_b32_e32 v125, 0xffff0000, v66
	v_lshlrev_b32_e32 v126, 16, v67
	v_and_b32_e32 v127, 0xffff0000, v67
	v_lshlrev_b32_e32 v128, 16, v68
	v_and_b32_e32 v129, 0xffff0000, v68
	v_lshlrev_b32_e32 v130, 16, v69
	v_and_b32_e32 v131, 0xffff0000, v69
	v_lshlrev_b32_e32 v132, 16, v70
	v_and_b32_e32 v133, 0xffff0000, v70
	v_lshlrev_b32_e32 v134, 16, v71
	v_and_b32_e32 v135, 0xffff0000, v71
	v_mul_f32_e32 v138, v120, v120
	v_mul_f32_e32 v149, v121, v121
	v_mul_f32_e32 v150, v122, v122
	v_mul_f32_e32 v154, v123, v123
	v_fma_f32 v138, v124, v124, v138
	v_fma_f32 v149, v125, v125, v149
	v_fma_f32 v150, v126, v126, v150
	v_fma_f32 v154, v127, v127, v154
	v_fma_f32 v138, v128, v128, v138
	v_fma_f32 v149, v129, v129, v149
	v_fma_f32 v150, v130, v130, v150
	v_fma_f32 v154, v131, v131, v154
	v_fma_f32 v138, v132, v132, v138
	v_fma_f32 v149, v133, v133, v149
	v_fma_f32 v150, v134, v134, v150
	v_fma_f32 v154, v135, v135, v154
	v_add_f32_e32 v138, v138, v149
	v_add_f32_e32 v150, v150, v154
	v_add_f32_e32 v138, v138, v150
	s_nop 1
	v_add_f32_dpp v138, v138, v138 quad_perm:[1,0,3,2] row_mask:0xf bank_mask:0xf
; __device__ __forceinline__ void row_phase(const Params& P, int glayer, int layer, int xsrc, bool hasY, int gate_idx, const float* gpost,
;                           int xdst, bool doH, const float* gpre, int sh_idx, int nrows) {
;     ...
;         if (hasY) {
;           float4 yv[4];
;           float ss = 0.f;
; #pragma unroll
;           for (int i = 0; i < 4; ++i) {
;             const uint2 raw = yy[u][i];
;             yv[i].x = bf2f((u16)(raw.x & 0xffff)); yv[i].y = bf2f((u16)(raw.x >> 16));
;             yv[i].z = bf2f((u16)(raw.y & 0xffff)); yv[i].w = bf2f((u16)(raw.y >> 16));
;             ss += yv[i].x * yv[i].x + yv[i].y * yv[i].y + yv[i].z * yv[i].z + yv[i].w * yv[i].w;
;           }
;           ss = wave_sum(ss);
;           const float rstd = __builtin_amdgcn_rsqf(ss * (1.f / 1024.f) + EPSF);
; #pragma unroll
;           for (int i = 0; i < 4; ++i) {
;             const int col = (i * 64 + lane) * 4;
;             const float4 gt = *reinterpret_cast<const float4*>(modg + gate_idx * 1024 + col);
;             const float4 gp = *reinterpret_cast<const float4*>(gpost + col);
;             xv[i].x += gt.x * (yv[i].x * rstd * gp.x); xv[i].y += gt.y * (yv[i].y * rstd * gp.y);
;             xv[i].z += gt.z * (yv[i].z * rstd * gp.z); xv[i].w += gt.w * (yv[i].w * rstd * gp.w);
;           }
;         }
;         if (xdst == 3 || (xdst == 1 && row >= N_X)) {
;           float* xout = (xdst == 3) ? P.out + (long)row * 1024 : P.xc + (long)(row - N_X) * 1024;
; #pragma unroll
;           for (int i = 0; i < 4; ++i) *reinterpret_cast<float4*>(xout + (i * 64 + lane) * 4) = xv[i];
;         } else if (xdst != 0) {
;           u16* xo = ((xdst == 1) ? resA : P.zf) + (long)row * 1024;
; #pragma unroll
;           for (int i = 0; i < 4; ++i) {
;             const unsigned b0 = f2bf(xv[i].x), b1 = f2bf(xv[i].y), b2 = f2bf(xv[i].z), b3 = f2bf(xv[i].w);
;             *reinterpret_cast<uint2*>(xo + (i * 64 + lane) * 4) = make_uint2(b0 | (b1 << 16), b2 | (b3 << 16));
;           }
;         }
;         if (doH) {
;           float ss = 0.f;
; #pragma unroll
;           for (int i = 0; i < 4; ++i) ss += xv[i].x * xv[i].x + xv[i].y * xv[i].y + xv[i].z * xv[i].z + xv[i].w * xv[i].w;
;           ss = wave_sum(ss);
;           const float rstd = __builtin_amdgcn_rsqf(ss * (1.f / 1024.f) + EPSF);
;           u16* h = P.hy + (long)row * 1024;
; #pragma unroll
	s_nop 1
	v_add_f32_dpp v138, v138, v138 quad_perm:[2,3,0,1] row_mask:0xf bank_mask:0xf
	s_nop 1
	v_add_f32_dpp v138, v138, v138 row_half_mirror row_mask:0xf bank_mask:0xf
	s_nop 1
	v_add_f32_dpp v138, v138, v138 row_mirror row_mask:0xf bank_mask:0xf
	v_mov_b32_e32 v139, v138
	s_nop 1
	v_permlane16_swap_b32_e32 v138, v139
	v_add_f32_e32 v138, v138, v139
	v_mov_b32_e32 v139, v138
	s_nop 1
	v_permlane32_swap_b32_e32 v138, v139
	v_add_f32_e32 v138, v138, v139
	v_mul_f32_e32 v138, 0x3a800000, v138
	v_add_f32_e32 v138, 0x358637bd, v138
	v_rsq_f32_e32 v140, v138
	s_nop 0
	v_mul_f32_e32 v120, v120, v140
	v_mul_f32_e32 v121, v121, v140
	v_mul_f32_e32 v122, v122, v140
	v_mul_f32_e32 v123, v123, v140
	v_mul_f32_e32 v124, v124, v140
	v_mul_f32_e32 v125, v125, v140
	v_mul_f32_e32 v126, v126, v140
	v_mul_f32_e32 v127, v127, v140
	v_mul_f32_e32 v128, v128, v140
	v_mul_f32_e32 v129, v129, v140
	v_mul_f32_e32 v130, v130, v140
	v_mul_f32_e32 v131, v131, v140
	v_mul_f32_e32 v132, v132, v140
	v_mul_f32_e32 v133, v133, v140
	v_mul_f32_e32 v134, v134, v140
	v_mul_f32_e32 v135, v135, v140
	v_fma_f32 v32, v120, v72, v32
	v_fma_f32 v33, v121, v73, v33
	v_fma_f32 v34, v122, v74, v34
	v_fma_f32 v35, v123, v75, v35
	v_fma_f32 v36, v124, v76, v36
	v_fma_f32 v37, v125, v77, v37
	v_fma_f32 v38, v126, v78, v38
	v_fma_f32 v39, v127, v79, v39
	v_fma_f32 v40, v128, v80, v40
	v_fma_f32 v41, v129, v81, v41
	v_fma_f32 v42, v130, v82, v42
	v_fma_f32 v43, v131, v83, v43
	v_fma_f32 v44, v132, v84, v44
	v_fma_f32 v45, v133, v85, v45
	v_fma_f32 v46, v134, v86, v46
	v_fma_f32 v47, v135, v87, v47
	v_cvt_pk_bf16_f32 v156, v32, v33
	v_cvt_pk_bf16_f32 v157, v34, v35
	v_cvt_pk_bf16_f32 v158, v36, v37
	v_cvt_pk_bf16_f32 v159, v38, v39
	v_cvt_pk_bf16_f32 v160, v40, v41
	v_cvt_pk_bf16_f32 v161, v42, v43
	v_cvt_pk_bf16_f32 v162, v44, v45
	v_cvt_pk_bf16_f32 v163, v46, v47
	s_lshl_b32 vcc_lo, s19, 11
	s_add_u32 vcc_lo, vcc_lo, 0x3800000
	s_add_u32 s100, s16, vcc_lo
	s_addc_u32 s101, s17, 0
	global_store_dwordx2 v137, v[156:157], s[100:101] offset:0
	global_store_dwordx2 v137, v[158:159], s[100:101] offset:512
	global_store_dwordx2 v137, v[160:161], s[100:101] offset:1024
	global_store_dwordx2 v137, v[162:163], s[100:101] offset:1536
	v_mul_f32_e32 v138, v32, v32
	v_mul_f32_e32 v149, v33, v33
	v_mul_f32_e32 v150, v34, v34
	v_mul_f32_e32 v154, v35, v35
	v_fma_f32 v138, v36, v36, v138
	v_fma_f32 v149, v37, v37, v149
	v_fma_f32 v150, v38, v38, v150
	v_fma_f32 v154, v39, v39, v154
	v_fma_f32 v138, v40, v40, v138
	v_fma_f32 v149, v41, v41, v149
	v_fma_f32 v150, v42, v42, v150
	v_fma_f32 v154, v43, v43, v154
	v_fma_f32 v138, v44, v44, v138
	v_fma_f32 v149, v45, v45, v149
	v_fma_f32 v150, v46, v46, v150
	v_fma_f32 v154, v47, v47, v154
	v_add_f32_e32 v138, v138, v149
	v_add_f32_e32 v150, v150, v154
	v_add_f32_e32 v138, v138, v150
	s_nop 1
	v_add_f32_dpp v138, v138, v138 quad_perm:[1,0,3,2] row_mask:0xf bank_mask:0xf
	s_nop 1
	v_add_f32_dpp v138, v138, v138 quad_perm:[2,3,0,1] row_mask:0xf bank_mask:0xf
	s_nop 1
	v_add_f32_dpp v138, v138, v138 row_half_mirror row_mask:0xf bank_mask:0xf
	s_nop 1
	v_add_f32_dpp v138, v138, v138 row_mirror row_mask:0xf bank_mask:0xf
	v_mov_b32_e32 v139, v138
	s_nop 1
	v_permlane16_swap_b32_e32 v138, v139
	v_add_f32_e32 v138, v138, v139
	v_mov_b32_e32 v139, v138
	s_nop 1
	v_permlane32_swap_b32_e32 v138, v139
	v_add_f32_e32 v138, v138, v139
	v_mul_f32_e32 v138, 0x3a800000, v138
	v_add_f32_e32 v138, 0x358637bd, v138
	v_rsq_f32_e32 v140, v138
	s_nop 0
	v_mul_f32_e32 v120, v32, v140
	v_mul_f32_e32 v121, v33, v140
	v_mul_f32_e32 v122, v34, v140
	v_mul_f32_e32 v123, v35, v140
	v_mul_f32_e32 v124, v36, v140
	v_mul_f32_e32 v125, v37, v140
	v_mul_f32_e32 v126, v38, v140
	v_mul_f32_e32 v127, v39, v140
	v_mul_f32_e32 v128, v40, v140
	v_mul_f32_e32 v129, v41, v140
	v_mul_f32_e32 v130, v42, v140
	v_mul_f32_e32 v131, v43, v140
	v_mul_f32_e32 v132, v44, v140
	v_mul_f32_e32 v133, v45, v140
	v_mul_f32_e32 v134, v46, v140
	v_mul_f32_e32 v135, v47, v140
	v_fma_f32 v120, v120, v88, v104
	v_fma_f32 v121, v121, v89, v105
	v_fma_f32 v122, v122, v90, v106
	v_fma_f32 v123, v123, v91, v107
	v_fma_f32 v124, v124, v92, v108
	v_fma_f32 v125, v125, v93, v109
	v_fma_f32 v126, v126, v94, v110
	v_fma_f32 v127, v127, v95, v111
	v_fma_f32 v128, v128, v96, v112
	v_fma_f32 v129, v129, v97, v113
	v_fma_f32 v130, v130, v98, v114
	v_fma_f32 v131, v131, v99, v115
	v_fma_f32 v132, v132, v100, v116
	v_fma_f32 v133, v133, v101, v117
	v_fma_f32 v134, v134, v102, v118
	v_fma_f32 v135, v135, v103, v119
	v_cvt_pk_bf16_f32 v156, v120, v121
	v_cvt_pk_bf16_f32 v157, v122, v123
	v_cvt_pk_bf16_f32 v158, v124, v125
	v_cvt_pk_bf16_f32 v159, v126, v127
	v_cvt_pk_bf16_f32 v160, v128, v129
	v_cvt_pk_bf16_f32 v161, v130, v131
	v_cvt_pk_bf16_f32 v162, v132, v133
	v_cvt_pk_bf16_f32 v163, v134, v135
	s_lshl_b32 vcc_lo, s19, 11
	s_add_u32 vcc_lo, vcc_lo, 0x3800000
	s_add_u32 s100, s14, vcc_lo
	s_addc_u32 s101, s15, 0
	global_store_dwordx2 v137, v[156:157], s[100:101] offset:0
	global_store_dwordx2 v137, v[158:159], s[100:101] offset:512
	global_store_dwordx2 v137, v[160:161], s[100:101] offset:1024
	global_store_dwordx2 v137, v[162:163], s[100:101] offset:1536
	s_waitcnt vmcnt(24)
; __device__ __forceinline__ void row_phase(const Params& P, int glayer, int layer, int xsrc, bool hasY, int gate_idx, const float* gpost,
;                           int xdst, bool doH, const float* gpre, int sh_idx, int nrows) {
;     ...
;         if (hasY) {
;           float4 yv[4];
;           float ss = 0.f;
; #pragma unroll
;           for (int i = 0; i < 4; ++i) {
;             const uint2 raw = yy[u][i];
;             yv[i].x = bf2f((u16)(raw.x & 0xffff)); yv[i].y = bf2f((u16)(raw.x >> 16));
;             yv[i].z = bf2f((u16)(raw.y & 0xffff)); yv[i].w = bf2f((u16)(raw.y >> 16));
;             ss += yv[i].x * yv[i].x + yv[i].y * yv[i].y + yv[i].z * yv[i].z + yv[i].w * yv[i].w;
;           }
;           ss = wave_sum(ss);
;           const float rstd = __builtin_amdgcn_rsqf(ss * (1.f / 1024.f) + EPSF);
; #pragma unroll
;           for (int i = 0; i < 4; ++i) {
;             const int col = (i * 64 + lane) * 4;
;             const float4 gt = *reinterpret_cast<const float4*>(modg + gate_idx * 1024 + col);
;             const float4 gp = *reinterpret_cast<const float4*>(gpost + col);
;             xv[i].x += gt.x * (yv[i].x * rstd * gp.x); xv[i].y += gt.y * (yv[i].y * rstd * gp.y);
;             xv[i].z += gt.z * (yv[i].z * rstd * gp.z); xv[i].w += gt.w * (yv[i].w * rstd * gp.w);
;           }
;         }
;         if (xdst == 3 || (xdst == 1 && row >= N_X)) {
;           float* xout = (xdst == 3) ? P.out + (long)row * 1024 : P.xc + (long)(row - N_X) * 1024;
; #pragma unroll
;           for (int i = 0; i < 4; ++i) *reinterpret_cast<float4*>(xout + (i * 64 + lane) * 4) = xv[i];
;         } else if (xdst != 0) {
;           u16* xo = ((xdst == 1) ? resA : P.zf) + (long)row * 1024;
; #pragma unroll
;           for (int i = 0; i < 4; ++i) {
;             const unsigned b0 = f2bf(xv[i].x), b1 = f2bf(xv[i].y), b2 = f2bf(xv[i].z), b3 = f2bf(xv[i].w);
;             *reinterpret_cast<uint2*>(xo + (i * 64 + lane) * 4) = make_uint2(b0 | (b1 << 16), b2 | (b3 << 16));
;           }
;         }
;         if (doH) {
;           float ss = 0.f;
; #pragma unroll
;           for (int i = 0; i < 4; ++i) ss += xv[i].x * xv[i].x + xv[i].y * xv[i].y + xv[i].z * xv[i].z + xv[i].w * xv[i].w;
;           ss = wave_sum(ss);
;           const float rstd = __builtin_amdgcn_rsqf(ss * (1.f / 1024.f) + EPSF);
;           u16* h = P.hy + (long)row * 1024;
; #pragma unroll
	v_lshlrev_b32_e32 v120, 16, v182
	v_and_b32_e32 v121, 0xffff0000, v182
	v_lshlrev_b32_e32 v122, 16, v183
	v_and_b32_e32 v123, 0xffff0000, v183
	v_lshlrev_b32_e32 v124, 16, v184
	v_and_b32_e32 v125, 0xffff0000, v184
	v_lshlrev_b32_e32 v126, 16, v185
	v_and_b32_e32 v127, 0xffff0000, v185
	v_lshlrev_b32_e32 v128, 16, v186
	v_and_b32_e32 v129, 0xffff0000, v186
	v_lshlrev_b32_e32 v130, 16, v187
	v_and_b32_e32 v131, 0xffff0000, v187
	v_lshlrev_b32_e32 v132, 16, v188
	v_and_b32_e32 v133, 0xffff0000, v188
	v_lshlrev_b32_e32 v134, 16, v189
	v_and_b32_e32 v135, 0xffff0000, v189
	v_mul_f32_e32 v138, v120, v120
	v_mul_f32_e32 v149, v121, v121
	v_mul_f32_e32 v150, v122, v122
	v_mul_f32_e32 v154, v123, v123
	v_fma_f32 v138, v124, v124, v138
	v_fma_f32 v149, v125, v125, v149
	v_fma_f32 v150, v126, v126, v150
	v_fma_f32 v154, v127, v127, v154
	v_fma_f32 v138, v128, v128, v138
	v_fma_f32 v149, v129, v129, v149
	v_fma_f32 v150, v130, v130, v150
	v_fma_f32 v154, v131, v131, v154
	v_fma_f32 v138, v132, v132, v138
	v_fma_f32 v149, v133, v133, v149
	v_fma_f32 v150, v134, v134, v150
	v_fma_f32 v154, v135, v135, v154
	v_add_f32_e32 v138, v138, v149
	v_add_f32_e32 v150, v150, v154
	v_add_f32_e32 v138, v138, v150
	s_nop 1
	v_add_f32_dpp v138, v138, v138 quad_perm:[1,0,3,2] row_mask:0xf bank_mask:0xf
	s_nop 1
	v_add_f32_dpp v138, v138, v138 quad_perm:[2,3,0,1] row_mask:0xf bank_mask:0xf
	s_nop 1
	v_add_f32_dpp v138, v138, v138 row_half_mirror row_mask:0xf bank_mask:0xf
	s_nop 1
	v_add_f32_dpp v138, v138, v138 row_mirror row_mask:0xf bank_mask:0xf
	v_mov_b32_e32 v139, v138
	s_nop 1
	v_permlane16_swap_b32_e32 v138, v139
	v_add_f32_e32 v138, v138, v139
	v_mov_b32_e32 v139, v138
	s_nop 1
	v_permlane32_swap_b32_e32 v138, v139
	v_add_f32_e32 v138, v138, v139
	v_mul_f32_e32 v138, 0x3a800000, v138
	v_add_f32_e32 v138, 0x358637bd, v138
	v_rsq_f32_e32 v140, v138
	s_nop 0
	v_mul_f32_e32 v120, v120, v140
	v_mul_f32_e32 v121, v121, v140
	v_mul_f32_e32 v122, v122, v140
	v_mul_f32_e32 v123, v123, v140
	v_mul_f32_e32 v124, v124, v140
	v_mul_f32_e32 v125, v125, v140
	v_mul_f32_e32 v126, v126, v140
	v_mul_f32_e32 v127, v127, v140
	v_mul_f32_e32 v128, v128, v140
	v_mul_f32_e32 v129, v129, v140
	v_mul_f32_e32 v130, v130, v140
	v_mul_f32_e32 v131, v131, v140
	v_mul_f32_e32 v132, v132, v140
	v_mul_f32_e32 v133, v133, v140
	v_mul_f32_e32 v134, v134, v140
	v_mul_f32_e32 v135, v135, v140
	v_fma_f32 v166, v120, v72, v166
	v_fma_f32 v167, v121, v73, v167
	v_fma_f32 v168, v122, v74, v168
	v_fma_f32 v169, v123, v75, v169
	v_fma_f32 v170, v124, v76, v170
	v_fma_f32 v171, v125, v77, v171
	v_fma_f32 v172, v126, v78, v172
	v_fma_f32 v173, v127, v79, v173
	v_fma_f32 v174, v128, v80, v174
	v_fma_f32 v175, v129, v81, v175
	v_fma_f32 v176, v130, v82, v176
	v_fma_f32 v177, v131, v83, v177
	v_fma_f32 v178, v132, v84, v178
	v_fma_f32 v179, v133, v85, v179
	v_fma_f32 v180, v134, v86, v180
	v_fma_f32 v181, v135, v87, v181
	v_cvt_pk_bf16_f32 v156, v166, v167
	v_cvt_pk_bf16_f32 v157, v168, v169
	v_cvt_pk_bf16_f32 v158, v170, v171
	v_cvt_pk_bf16_f32 v159, v172, v173
	v_cvt_pk_bf16_f32 v160, v174, v175
	v_cvt_pk_bf16_f32 v161, v176, v177
	v_cvt_pk_bf16_f32 v162, v178, v179
	v_cvt_pk_bf16_f32 v163, v180, v181
	s_lshl_b32 vcc_lo, s19, 11
	s_add_u32 vcc_lo, vcc_lo, 0x3c00000
	s_add_u32 s100, s16, vcc_lo
	s_addc_u32 s101, s17, 0
	global_store_dwordx2 v137, v[156:157], s[100:101] offset:0
	global_store_dwordx2 v137, v[158:159], s[100:101] offset:512
	global_store_dwordx2 v137, v[160:161], s[100:101] offset:1024
	global_store_dwordx2 v137, v[162:163], s[100:101] offset:1536
	v_mul_f32_e32 v138, v166, v166
	v_mul_f32_e32 v149, v167, v167
	v_mul_f32_e32 v150, v168, v168
	v_mul_f32_e32 v154, v169, v169
	v_fma_f32 v138, v170, v170, v138
	v_fma_f32 v149, v171, v171, v149
	v_fma_f32 v150, v172, v172, v150
	v_fma_f32 v154, v173, v173, v154
	v_fma_f32 v138, v174, v174, v138
	v_fma_f32 v149, v175, v175, v149
	v_fma_f32 v150, v176, v176, v150
	v_fma_f32 v154, v177, v177, v154
	v_fma_f32 v138, v178, v178, v138
	v_fma_f32 v149, v179, v179, v149
	v_fma_f32 v150, v180, v180, v150
	v_fma_f32 v154, v181, v181, v154
	v_add_f32_e32 v138, v138, v149
	v_add_f32_e32 v150, v150, v154
	v_add_f32_e32 v138, v138, v150
	s_nop 1
	v_add_f32_dpp v138, v138, v138 quad_perm:[1,0,3,2] row_mask:0xf bank_mask:0xf
	s_nop 1
	v_add_f32_dpp v138, v138, v138 quad_perm:[2,3,0,1] row_mask:0xf bank_mask:0xf
	s_nop 1
	v_add_f32_dpp v138, v138, v138 row_half_mirror row_mask:0xf bank_mask:0xf
	s_nop 1
	v_add_f32_dpp v138, v138, v138 row_mirror row_mask:0xf bank_mask:0xf
	v_mov_b32_e32 v139, v138
	s_nop 1
	v_permlane16_swap_b32_e32 v138, v139
	v_add_f32_e32 v138, v138, v139
	v_mov_b32_e32 v139, v138
	s_nop 1
	v_permlane32_swap_b32_e32 v138, v139
	v_add_f32_e32 v138, v138, v139
	v_mul_f32_e32 v138, 0x3a800000, v138
	v_add_f32_e32 v138, 0x358637bd, v138
	v_rsq_f32_e32 v140, v138
	s_nop 0
	v_mul_f32_e32 v120, v166, v140
	v_mul_f32_e32 v121, v167, v140
	v_mul_f32_e32 v122, v168, v140
	v_mul_f32_e32 v123, v169, v140
	v_mul_f32_e32 v124, v170, v140
	v_mul_f32_e32 v125, v171, v140
	v_mul_f32_e32 v126, v172, v140
	v_mul_f32_e32 v127, v173, v140
	v_mul_f32_e32 v128, v174, v140
	v_mul_f32_e32 v129, v175, v140
	v_mul_f32_e32 v130, v176, v140
	v_mul_f32_e32 v131, v177, v140
	v_mul_f32_e32 v132, v178, v140
	v_mul_f32_e32 v133, v179, v140
	v_mul_f32_e32 v134, v180, v140
	v_mul_f32_e32 v135, v181, v140
	v_fma_f32 v120, v120, v88, v104
	v_fma_f32 v121, v121, v89, v105
	v_fma_f32 v122, v122, v90, v106
	v_fma_f32 v123, v123, v91, v107
	v_fma_f32 v124, v124, v92, v108
	v_fma_f32 v125, v125, v93, v109
	v_fma_f32 v126, v126, v94, v110
	v_fma_f32 v127, v127, v95, v111
	v_fma_f32 v128, v128, v96, v112
	v_fma_f32 v129, v129, v97, v113
	v_fma_f32 v130, v130, v98, v114
	v_fma_f32 v131, v131, v99, v115
	v_fma_f32 v132, v132, v100, v116
	v_fma_f32 v133, v133, v101, v117
	v_fma_f32 v134, v134, v102, v118
	v_fma_f32 v135, v135, v103, v119
	v_cvt_pk_bf16_f32 v156, v120, v121
	v_cvt_pk_bf16_f32 v157, v122, v123
	v_cvt_pk_bf16_f32 v158, v124, v125
	v_cvt_pk_bf16_f32 v159, v126, v127
	v_cvt_pk_bf16_f32 v160, v128, v129
	v_cvt_pk_bf16_f32 v161, v130, v131
	v_cvt_pk_bf16_f32 v162, v132, v133
	v_cvt_pk_bf16_f32 v163, v134, v135
	s_lshl_b32 vcc_lo, s19, 11
	s_add_u32 vcc_lo, vcc_lo, 0x3c00000
	s_add_u32 s100, s14, vcc_lo
	s_addc_u32 s101, s15, 0
	global_store_dwordx2 v137, v[156:157], s[100:101] offset:0
	global_store_dwordx2 v137, v[158:159], s[100:101] offset:512
	global_store_dwordx2 v137, v[160:161], s[100:101] offset:1024
	global_store_dwordx2 v137, v[162:163], s[100:101] offset:1536
	s_waitcnt vmcnt(0)
	s_cmp_lt_u32 s19, 0x400
	s_cbranch_scc0 .Lmy_r7_done
; __device__ __forceinline__ void row_phase(const Params& P, int glayer, int layer, int xsrc, bool hasY, int gate_idx, const float* gpost,
;                           int xdst, bool doH, const float* gpre, int sh_idx, int nrows) {
;     ...
;           const float* xin_;
;           if (xsrc == 0) xin_ = R < N_X ? P.x + (long)R * 1024 : P.ctx + (long)(R - N_X) * 1024;
;           else           xin_ = P.xc + (long)(R - N_X) * 1024;
; #pragma unroll
;           for (int i = 0; i < 4; ++i) xr[u][i] = *reinterpret_cast<const uint4*>(xin_ + (i * 64 + lane) * 4);
;         }
;         if (hasY) {
;           const u16* y_ = P.hy + (long)R * 1024;
; #pragma unroll
;           for (int i = 0; i < 4; ++i) yy[u][i] = *reinterpret_cast<const uint2*>(y_ + (i * 64 + lane) * 4);
;         }
;       }
;     }
; #pragma unroll
;     for (int u = 0; u < 4; ++u) {
;       const int row = rb + u * stride;
;       if (row < nrows) {
;         const int mi = row < N_X ? (row >> 13) : 4;
;         const float* modp = P.mod + (long)(layer * 5 + mi) * 6144;
;         const float* modg = P.mod + (long)(glayer * 5 + mi) * 6144;
;         float4 xv[4];
;         if (xsrc != 0 && row < N_X) {
; #pragma unroll
;           for (int i = 0; i < 4; ++i) {
;             const uint4 raw = xr[u][i];
;             xv[i].x = bf2f((u16)(raw.x & 0xffff)); xv[i].y = bf2f((u16)(raw.x >> 16));
;             xv[i].z = bf2f((u16)(raw.y & 0xffff)); xv[i].w = bf2f((u16)(raw.y >> 16));
;           }
;         } else {
; #pragma unroll
;           for (int i = 0; i < 4; ++i) {
;             xv[i].x = __uint_as_float(xr[u][i].x); xv[i].y = __uint_as_float(xr[u][i].y);
;             xv[i].z = __uint_as_float(xr[u][i].z); xv[i].w = __uint_as_float(xr[u][i].w);
;           }
;         }
;         if (hasY) {
;           float4 yv[4];
;           float ss = 0.f;
; #pragma unroll
;           for (int i = 0; i < 4; ++i) {
;             const uint2 raw = yy[u][i];
;             yv[i].x = bf2f((u16)(raw.x & 0xffff)); yv[i].y = bf2f((u16)(raw.x >> 16));
;             yv[i].z = bf2f((u16)(raw.y & 0xffff)); yv[i].w = bf2f((u16)(raw.y >> 16));
;             ss += yv[i].x * yv[i].x + yv[i].y * yv[i].y + yv[i].z * yv[i].z + yv[i].w * yv[i].w;
;           }
;           ss = wave_sum(ss);
;           const float rstd = __builtin_amdgcn_rsqf(ss * (1.f / 1024.f) + EPSF);
; #pragma unroll
;           for (int i = 0; i < 4; ++i) {
	s_load_dwordx2 s[12:13], s[4:5], 0x10
	s_waitcnt lgkmcnt(0)
	s_add_u32 s100, s20, 0x1a000
	s_addc_u32 s101, s21, 0
	global_load_dwordx4 v[72:75], v136, s[100:101] offset:0
	global_load_dwordx4 v[76:79], v136, s[100:101] offset:1024
	global_load_dwordx4 v[80:83], v136, s[100:101] offset:2048
	global_load_dwordx4 v[84:87], v136, s[100:101] offset:3072
	s_load_dwordx2 s[98:99], s[4:5], 0x38
	s_waitcnt lgkmcnt(0)
	global_load_dwordx4 v[120:123], v136, s[98:99] offset:0
	global_load_dwordx4 v[124:127], v136, s[98:99] offset:1024
	global_load_dwordx4 v[128:131], v136, s[98:99] offset:2048
	global_load_dwordx4 v[132:135], v136, s[98:99] offset:3072
	s_add_u32 s100, s20, 0x1b000
	s_addc_u32 s101, s21, 0
	global_load_dwordx4 v[104:107], v136, s[100:101] offset:0
	global_load_dwordx4 v[108:111], v136, s[100:101] offset:1024
	global_load_dwordx4 v[112:115], v136, s[100:101] offset:2048
	global_load_dwordx4 v[116:119], v136, s[100:101] offset:3072
	s_add_u32 s100, s100, 0x1000
	s_addc_u32 s101, s101, 0
	global_load_dwordx4 v[16:19], v136, s[100:101] offset:0
	global_load_dwordx4 v[20:23], v136, s[100:101] offset:1024
	global_load_dwordx4 v[24:27], v136, s[100:101] offset:2048
	global_load_dwordx4 v[28:31], v136, s[100:101] offset:3072
	s_load_dwordx2 s[98:99], s[4:5], 0x40
	s_waitcnt lgkmcnt(0)
	global_load_dwordx4 v[88:91], v136, s[98:99] offset:0
	global_load_dwordx4 v[92:95], v136, s[98:99] offset:1024
	global_load_dwordx4 v[96:99], v136, s[98:99] offset:2048
	global_load_dwordx4 v[100:103], v136, s[98:99] offset:3072
	s_waitcnt vmcnt(0)
	v_mul_f32_e32 v72, v72, v120
	v_mul_f32_e32 v73, v73, v121
	v_mul_f32_e32 v74, v74, v122
	v_mul_f32_e32 v75, v75, v123
	v_mul_f32_e32 v76, v76, v124
	v_mul_f32_e32 v77, v77, v125
	v_mul_f32_e32 v78, v78, v126
	v_mul_f32_e32 v79, v79, v127
	v_mul_f32_e32 v80, v80, v128
	v_mul_f32_e32 v81, v81, v129
	v_mul_f32_e32 v82, v82, v130
	v_mul_f32_e32 v83, v83, v131
	v_mul_f32_e32 v84, v84, v132
	v_mul_f32_e32 v85, v85, v133
	v_mul_f32_e32 v86, v86, v134
	v_mul_f32_e32 v87, v87, v135
	v_fma_f32 v88, v88, v16, v88
	v_fma_f32 v89, v89, v17, v89
	v_fma_f32 v90, v90, v18, v90
	v_fma_f32 v91, v91, v19, v91
	v_fma_f32 v92, v92, v20, v92
	v_fma_f32 v93, v93, v21, v93
	v_fma_f32 v94, v94, v22, v94
	v_fma_f32 v95, v95, v23, v95
	v_fma_f32 v96, v96, v24, v96
	v_fma_f32 v97, v97, v25, v97
	v_fma_f32 v98, v98, v26, v98
	v_fma_f32 v99, v99, v27, v99
	v_fma_f32 v100, v100, v28, v100
	v_fma_f32 v101, v101, v29, v101
	v_fma_f32 v102, v102, v30, v102
	v_fma_f32 v103, v103, v31, v103
	s_lshl_b32 vcc_lo, s19, 12
	s_add_u32 s100, s12, vcc_lo
	s_addc_u32 s101, s13, 0
	global_load_dwordx4 v[0:3], v136, s[100:101] offset:0
	global_load_dwordx4 v[4:7], v136, s[100:101] offset:1024
	global_load_dwordx4 v[8:11], v136, s[100:101] offset:2048
	global_load_dwordx4 v[12:15], v136, s[100:101] offset:3072
	s_lshl_b32 vcc_lo, s19, 11
	s_add_u32 vcc_lo, vcc_lo, 0x4000000
	s_add_u32 s100, s14, vcc_lo
	s_addc_u32 s101, s15, 0
	global_load_dwordx2 v[48:49], v137, s[100:101] offset:0
	global_load_dwordx2 v[50:51], v137, s[100:101] offset:512
	global_load_dwordx2 v[52:53], v137, s[100:101] offset:1024
	global_load_dwordx2 v[54:55], v137, s[100:101] offset:1536
	s_waitcnt vmcnt(0)
	v_lshlrev_b32_e32 v120, 16, v48
	v_and_b32_e32 v121, 0xffff0000, v48
	v_lshlrev_b32_e32 v122, 16, v49
	v_and_b32_e32 v123, 0xffff0000, v49
	v_lshlrev_b32_e32 v124, 16, v50
	v_and_b32_e32 v125, 0xffff0000, v50
	v_lshlrev_b32_e32 v126, 16, v51
	v_and_b32_e32 v127, 0xffff0000, v51
	v_lshlrev_b32_e32 v128, 16, v52
	v_and_b32_e32 v129, 0xffff0000, v52
	v_lshlrev_b32_e32 v130, 16, v53
	v_and_b32_e32 v131, 0xffff0000, v53
	v_lshlrev_b32_e32 v132, 16, v54
	v_and_b32_e32 v133, 0xffff0000, v54
	v_lshlrev_b32_e32 v134, 16, v55
	v_and_b32_e32 v135, 0xffff0000, v55
	v_mul_f32_e32 v138, v120, v120
	v_mul_f32_e32 v149, v121, v121
	v_mul_f32_e32 v150, v122, v122
	v_mul_f32_e32 v154, v123, v123
	v_fma_f32 v138, v124, v124, v138
	v_fma_f32 v149, v125, v125, v149
	v_fma_f32 v150, v126, v126, v150
	v_fma_f32 v154, v127, v127, v154
	v_fma_f32 v138, v128, v128, v138
	v_fma_f32 v149, v129, v129, v149
	v_fma_f32 v150, v130, v130, v150
	v_fma_f32 v154, v131, v131, v154
	v_fma_f32 v138, v132, v132, v138
	v_fma_f32 v149, v133, v133, v149
	v_fma_f32 v150, v134, v134, v150
	v_fma_f32 v154, v135, v135, v154
	v_add_f32_e32 v138, v138, v149
	v_add_f32_e32 v150, v150, v154
	v_add_f32_e32 v138, v138, v150
	s_nop 1
	v_add_f32_dpp v138, v138, v138 quad_perm:[1,0,3,2] row_mask:0xf bank_mask:0xf
	s_nop 1
	v_add_f32_dpp v138, v138, v138 quad_perm:[2,3,0,1] row_mask:0xf bank_mask:0xf
	s_nop 1
	v_add_f32_dpp v138, v138, v138 row_half_mirror row_mask:0xf bank_mask:0xf
	s_nop 1
	v_add_f32_dpp v138, v138, v138 row_mirror row_mask:0xf bank_mask:0xf
	v_mov_b32_e32 v139, v138
	s_nop 1
	v_permlane16_swap_b32_e32 v138, v139
	v_add_f32_e32 v138, v138, v139
	v_mov_b32_e32 v139, v138
	s_nop 1
	v_permlane32_swap_b32_e32 v138, v139
	v_add_f32_e32 v138, v138, v139
	v_mul_f32_e32 v138, 0x3a800000, v138
	v_add_f32_e32 v138, 0x358637bd, v138
	v_rsq_f32_e32 v140, v138
	s_nop 0
	v_mul_f32_e32 v120, v120, v140
	v_mul_f32_e32 v121, v121, v140
	v_mul_f32_e32 v122, v122, v140
	v_mul_f32_e32 v123, v123, v140
	v_mul_f32_e32 v124, v124, v140
	v_mul_f32_e32 v125, v125, v140
	v_mul_f32_e32 v126, v126, v140
	v_mul_f32_e32 v127, v127, v140
	v_mul_f32_e32 v128, v128, v140
	v_mul_f32_e32 v129, v129, v140
	v_mul_f32_e32 v130, v130, v140
	v_mul_f32_e32 v131, v131, v140
	v_mul_f32_e32 v132, v132, v140
	v_mul_f32_e32 v133, v133, v140
	v_mul_f32_e32 v134, v134, v140
	v_mul_f32_e32 v135, v135, v140
	v_fma_f32 v0, v120, v72, v0
	v_fma_f32 v1, v121, v73, v1
	v_fma_f32 v2, v122, v74, v2
	v_fma_f32 v3, v123, v75, v3
	v_fma_f32 v4, v124, v76, v4
	v_fma_f32 v5, v125, v77, v5
	v_fma_f32 v6, v126, v78, v6
	v_fma_f32 v7, v127, v79, v7
	v_fma_f32 v8, v128, v80, v8
	v_fma_f32 v9, v129, v81, v9
	v_fma_f32 v10, v130, v82, v10
	v_fma_f32 v11, v131, v83, v11
	v_fma_f32 v12, v132, v84, v12
	v_fma_f32 v13, v133, v85, v13
	v_fma_f32 v14, v134, v86, v14
	v_fma_f32 v15, v135, v87, v15
	s_load_dwordx2 s[98:99], s[4:5], 0x138
	s_waitcnt lgkmcnt(0)
; __device__ __forceinline__ void row_phase(const Params& P, int glayer, int layer, int xsrc, bool hasY, int gate_idx, const float* gpost,
;                           int xdst, bool doH, const float* gpre, int sh_idx, int nrows) {
;     ...
;         if (xdst == 3 || (xdst == 1 && row >= N_X)) {
;           float* xout = (xdst == 3) ? P.out + (long)row * 1024 : P.xc + (long)(row - N_X) * 1024;
; #pragma unroll
;           for (int i = 0; i < 4; ++i) *reinterpret_cast<float4*>(xout + (i * 64 + lane) * 4) = xv[i];
;         } else if (xdst != 0) {
;           u16* xo = ((xdst == 1) ? resA : P.zf) + (long)row * 1024;
; #pragma unroll
;           for (int i = 0; i < 4; ++i) {
;             const unsigned b0 = f2bf(xv[i].x), b1 = f2bf(xv[i].y), b2 = f2bf(xv[i].z), b3 = f2bf(xv[i].w);
;             *reinterpret_cast<uint2*>(xo + (i * 64 + lane) * 4) = make_uint2(b0 | (b1 << 16), b2 | (b3 << 16));
;           }
;         }
;         if (doH) {
;           float ss = 0.f;
; #pragma unroll
;           for (int i = 0; i < 4; ++i) ss += xv[i].x * xv[i].x + xv[i].y * xv[i].y + xv[i].z * xv[i].z + xv[i].w * xv[i].w;
;           ss = wave_sum(ss);
;           const float rstd = __builtin_amdgcn_rsqf(ss * (1.f / 1024.f) + EPSF);
;           u16* h = P.hy + (long)row * 1024;
; #pragma unroll
;           for (int i = 0; i < 4; ++i) {
;             const int col = (i * 64 + lane) * 4;
;             const float4 g = *reinterpret_cast<const float4*>(gpre + col);
;             const float4 sh = *reinterpret_cast<const float4*>(modp + sh_idx * 1024 + col);
;             const float4 sc = *reinterpret_cast<const float4*>(modp + (sh_idx + 1) * 1024 + col);
;             const unsigned h0 = f2bf(xv[i].x * rstd * g.x * (1.f + sc.x) + sh.x);
;             const unsigned h1 = f2bf(xv[i].y * rstd * g.y * (1.f + sc.y) + sh.y);
;             const unsigned h2 = f2bf(xv[i].z * rstd * g.z * (1.f + sc.z) + sh.z);
;             const unsigned h3 = f2bf(xv[i].w * rstd * g.w * (1.f + sc.w) + sh.w);
;             *reinterpret_cast<uint2*>(h + col) = make_uint2(h0 | (h1 << 16), h2 | (h3 << 16));
;           }
	s_lshl_b32 vcc_lo, s19, 12
	s_add_u32 s100, s98, vcc_lo
	s_addc_u32 s101, s99, 0
	global_store_dwordx4 v136, v[0:3], s[100:101] offset:0
	global_store_dwordx4 v136, v[4:7], s[100:101] offset:1024
	global_store_dwordx4 v136, v[8:11], s[100:101] offset:2048
	global_store_dwordx4 v136, v[12:15], s[100:101] offset:3072
	v_mul_f32_e32 v138, v0, v0
	v_mul_f32_e32 v149, v1, v1
	v_mul_f32_e32 v150, v2, v2
	v_mul_f32_e32 v154, v3, v3
	v_fma_f32 v138, v4, v4, v138
	v_fma_f32 v149, v5, v5, v149
	v_fma_f32 v150, v6, v6, v150
	v_fma_f32 v154, v7, v7, v154
	v_fma_f32 v138, v8, v8, v138
	v_fma_f32 v149, v9, v9, v149
	v_fma_f32 v150, v10, v10, v150
	v_fma_f32 v154, v11, v11, v154
	v_fma_f32 v138, v12, v12, v138
	v_fma_f32 v149, v13, v13, v149
	v_fma_f32 v150, v14, v14, v150
	v_fma_f32 v154, v15, v15, v154
	v_add_f32_e32 v138, v138, v149
	v_add_f32_e32 v150, v150, v154
	v_add_f32_e32 v138, v138, v150
	s_nop 1
	v_add_f32_dpp v138, v138, v138 quad_perm:[1,0,3,2] row_mask:0xf bank_mask:0xf
	s_nop 1
	v_add_f32_dpp v138, v138, v138 quad_perm:[2,3,0,1] row_mask:0xf bank_mask:0xf
	s_nop 1
	v_add_f32_dpp v138, v138, v138 row_half_mirror row_mask:0xf bank_mask:0xf
	s_nop 1
	v_add_f32_dpp v138, v138, v138 row_mirror row_mask:0xf bank_mask:0xf
	v_mov_b32_e32 v139, v138
	s_nop 1
	v_permlane16_swap_b32_e32 v138, v139
	v_add_f32_e32 v138, v138, v139
	v_mov_b32_e32 v139, v138
	s_nop 1
	v_permlane32_swap_b32_e32 v138, v139
	v_add_f32_e32 v138, v138, v139
	v_mul_f32_e32 v138, 0x3a800000, v138
	v_add_f32_e32 v138, 0x358637bd, v138
	v_rsq_f32_e32 v140, v138
	s_nop 0
	v_mul_f32_e32 v120, v0, v140
	v_mul_f32_e32 v121, v1, v140
	v_mul_f32_e32 v122, v2, v140
	v_mul_f32_e32 v123, v3, v140
	v_mul_f32_e32 v124, v4, v140
	v_mul_f32_e32 v125, v5, v140
	v_mul_f32_e32 v126, v6, v140
	v_mul_f32_e32 v127, v7, v140
	v_mul_f32_e32 v128, v8, v140
	v_mul_f32_e32 v129, v9, v140
	v_mul_f32_e32 v130, v10, v140
	v_mul_f32_e32 v131, v11, v140
	v_mul_f32_e32 v132, v12, v140
	v_mul_f32_e32 v133, v13, v140
	v_mul_f32_e32 v134, v14, v140
	v_mul_f32_e32 v135, v15, v140
	v_fma_f32 v120, v120, v88, v104
	v_fma_f32 v121, v121, v89, v105
	v_fma_f32 v122, v122, v90, v106
	v_fma_f32 v123, v123, v91, v107
	v_fma_f32 v124, v124, v92, v108
	v_fma_f32 v125, v125, v93, v109
	v_fma_f32 v126, v126, v94, v110
	v_fma_f32 v127, v127, v95, v111
	v_fma_f32 v128, v128, v96, v112
	v_fma_f32 v129, v129, v97, v113
	v_fma_f32 v130, v130, v98, v114
	v_fma_f32 v131, v131, v99, v115
	v_fma_f32 v132, v132, v100, v116
	v_fma_f32 v133, v133, v101, v117
	v_fma_f32 v134, v134, v102, v118
	v_fma_f32 v135, v135, v103, v119
	v_cvt_pk_bf16_f32 v156, v120, v121
	v_cvt_pk_bf16_f32 v157, v122, v123
	v_cvt_pk_bf16_f32 v158, v124, v125
	v_cvt_pk_bf16_f32 v159, v126, v127
	v_cvt_pk_bf16_f32 v160, v128, v129
	v_cvt_pk_bf16_f32 v161, v130, v131
	v_cvt_pk_bf16_f32 v162, v132, v133
	v_cvt_pk_bf16_f32 v163, v134, v135
	s_lshl_b32 vcc_lo, s19, 11
	s_add_u32 vcc_lo, vcc_lo, 0x4000000
	s_add_u32 s100, s14, vcc_lo
	s_addc_u32 s101, s15, 0
	global_store_dwordx2 v137, v[156:157], s[100:101] offset:0
	global_store_dwordx2 v137, v[158:159], s[100:101] offset:512
	global_store_dwordx2 v137, v[160:161], s[100:101] offset:1024
	global_store_dwordx2 v137, v[162:163], s[100:101] offset:1536

; __device__ __forceinline__ void row_phase(const Params& P, int glayer, int layer, int xsrc, bool hasY, int gate_idx, const float* gpost,
;                           int xdst, bool doH, const float* gpre, int sh_idx, int nrows) {
;   const int lane = threadIdx.x & 63, wid = threadIdx.x >> 6;
;   const int stride = gridDim.x * 8;
;   u16* resA = reinterpret_cast<u16*>(P.out);
;   for (int rb = blockIdx.x * 8 + wid; rb < nrows; rb += 4 * stride) {
;     uint4 xr[4][4];
;     uint2 yy[4][4];
; #pragma unroll
;     for (int u = 0; u < 4; ++u) {
;       const int R = rb + u * stride;
;       if (R < nrows) {
;         if (xsrc != 0 && R < N_X) {
;           const u16* xs_ = ((xsrc == 1) ? resA : P.zf) + (long)R * 1024;
; #pragma unroll
;           for (int i = 0; i < 4; ++i) {
;             const uint2 t2 = *reinterpret_cast<const uint2*>(xs_ + (i * 64 + lane) * 4);
;             xr[u][i].x = t2.x; xr[u][i].y = t2.y;
;           }
;         } else {
;           const float* xin_;
;           if (xsrc == 0) xin_ = R < N_X ? P.x + (long)R * 1024 : P.ctx + (long)(R - N_X) * 1024;
;           else           xin_ = P.xc + (long)(R - N_X) * 1024;
; #pragma unroll
;           for (int i = 0; i < 4; ++i) xr[u][i] = *reinterpret_cast<const uint4*>(xin_ + (i * 64 + lane) * 4);
;         }
;         if (hasY) {
;           const u16* y_ = P.hy + (long)R * 1024;
; #pragma unroll
;           for (int i = 0; i < 4; ++i) yy[u][i] = *reinterpret_cast<const uint2*>(y_ + (i * 64 + lane) * 4);
;         }
.LBB0_1247:
	s_cmp_gt_i32 s34, 10
	s_cselect_b64 s[0:1], -1, 0
	s_cmp_lt_i32 s35, 11
	s_cselect_b64 s[4:5], -1, 0
	s_or_b64 s[0:1], s[0:1], s[4:5]
	s_and_b64 vcc, exec, s[0:1]
	s_cbranch_vccnz .LBB0_1357
	v_lshl_add_u32 v22, s2, 3, v204
	s_mov_b32 s3, 0x8400
	v_mov_b32_e32 v0, v153
	v_cmp_gt_i32_e32 vcc, s3, v22
	s_and_saveexec_b64 s[10:11], vcc
	s_cbranch_execz .LBB0_1303
	v_readlane_b32 s4, v252, 0
	v_readlane_b32 s5, v252, 1
	v_readfirstlane_b32 s19, v204
	s_nop 3
	s_sub_u32 s4, s4, 0x170
	s_subb_u32 s5, s5, 0
	s_load_dwordx2 s[12:13], s[4:5], 0xc8
	s_load_dwordx2 s[14:15], s[4:5], 0x140
	s_load_dwordx2 s[16:17], s[4:5], 0xc8
	s_load_dwordx2 s[20:21], s[4:5], 0x100
	s_lshl_b32 s98, s2, 3
	s_add_u32 s19, s98, s19
	v_and_b32_e32 v136, 63, v152
	v_lshlrev_b32_e32 v137, 3, v136
	v_lshlrev_b32_e32 v136, 4, v136
	s_waitcnt lgkmcnt(0)
	s_lshl_b32 vcc_lo, s19, 11
	s_add_u32 s100, s12, vcc_lo
	s_addc_u32 s101, s13, 0
	global_load_dwordx2 v[8:9], v137, s[100:101] offset:0
	global_load_dwordx2 v[10:11], v137, s[100:101] offset:512
	global_load_dwordx2 v[12:13], v137, s[100:101] offset:1024
	global_load_dwordx2 v[14:15], v137, s[100:101] offset:1536
	s_lshl_b32 vcc_lo, s19, 11
	s_add_u32 s100, s14, vcc_lo
	s_addc_u32 s101, s15, 0
	global_load_dwordx2 v[48:49], v137, s[100:101] offset:0
	global_load_dwordx2 v[50:51], v137, s[100:101] offset:512
	global_load_dwordx2 v[52:53], v137, s[100:101] offset:1024
	global_load_dwordx2 v[54:55], v137, s[100:101] offset:1536
	s_lshl_b32 vcc_lo, s19, 11
	s_add_u32 vcc_lo, vcc_lo, 0x400000
	s_add_u32 s100, s12, vcc_lo
	s_addc_u32 s101, s13, 0
	global_load_dwordx2 v[24:25], v137, s[100:101] offset:0
	global_load_dwordx2 v[26:27], v137, s[100:101] offset:512
	global_load_dwordx2 v[28:29], v137, s[100:101] offset:1024
	global_load_dwordx2 v[30:31], v137, s[100:101] offset:1536
	s_lshl_b32 vcc_lo, s19, 11
	s_add_u32 vcc_lo, vcc_lo, 0x400000
	s_add_u32 s100, s14, vcc_lo
	s_addc_u32 s101, s15, 0
	global_load_dwordx2 v[56:57], v137, s[100:101] offset:0
	global_load_dwordx2 v[58:59], v137, s[100:101] offset:512
	global_load_dwordx2 v[60:61], v137, s[100:101] offset:1024
	global_load_dwordx2 v[62:63], v137, s[100:101] offset:1536
	s_lshl_b32 vcc_lo, s19, 11
	s_add_u32 vcc_lo, vcc_lo, 0x800000
	s_add_u32 s100, s12, vcc_lo
	s_addc_u32 s101, s13, 0
	global_load_dwordx2 v[40:41], v137, s[100:101] offset:0
	global_load_dwordx2 v[42:43], v137, s[100:101] offset:512
	global_load_dwordx2 v[44:45], v137, s[100:101] offset:1024
	global_load_dwordx2 v[46:47], v137, s[100:101] offset:1536
	s_lshl_b32 vcc_lo, s19, 11
	s_add_u32 vcc_lo, vcc_lo, 0x800000
	s_add_u32 s100, s14, vcc_lo
	s_addc_u32 s101, s15, 0
	global_load_dwordx2 v[64:65], v137, s[100:101] offset:0
	global_load_dwordx2 v[66:67], v137, s[100:101] offset:512
	global_load_dwordx2 v[68:69], v137, s[100:101] offset:1024
	global_load_dwordx2 v[70:71], v137, s[100:101] offset:1536
	s_add_u32 s100, s20, 0x5000
	s_addc_u32 s101, s21, 0
	global_load_dwordx4 v[72:75], v136, s[100:101] offset:0
	global_load_dwordx4 v[76:79], v136, s[100:101] offset:1024
	global_load_dwordx4 v[80:83], v136, s[100:101] offset:2048
	global_load_dwordx4 v[84:87], v136, s[100:101] offset:3072
	s_load_dwordx2 s[98:99], s[4:5], 0x48
	s_waitcnt lgkmcnt(0)
	global_load_dwordx4 v[120:123], v136, s[98:99] offset:0
	global_load_dwordx4 v[124:127], v136, s[98:99] offset:1024
	global_load_dwordx4 v[128:131], v136, s[98:99] offset:2048
	global_load_dwordx4 v[132:135], v136, s[98:99] offset:3072
	s_add_u32 s100, s20, 0x1e000
	s_addc_u32 s101, s21, 0
	global_load_dwordx4 v[104:107], v136, s[100:101] offset:0
	global_load_dwordx4 v[108:111], v136, s[100:101] offset:1024
	global_load_dwordx4 v[112:115], v136, s[100:101] offset:2048
	global_load_dwordx4 v[116:119], v136, s[100:101] offset:3072
	s_add_u32 s100, s100, 0x1000
	s_addc_u32 s101, s101, 0
	global_load_dwordx4 v[166:169], v136, s[100:101] offset:0
	global_load_dwordx4 v[170:173], v136, s[100:101] offset:1024
	global_load_dwordx4 v[174:177], v136, s[100:101] offset:2048
	global_load_dwordx4 v[178:181], v136, s[100:101] offset:3072
	s_load_dwordx2 s[98:99], s[4:5], 0x30
	s_waitcnt lgkmcnt(0)
	s_add_u32 s98, s98, 0x1000
	s_addc_u32 s99, s99, 0
	global_load_dwordx4 v[88:91], v136, s[98:99] offset:0
	global_load_dwordx4 v[92:95], v136, s[98:99] offset:1024
	global_load_dwordx4 v[96:99], v136, s[98:99] offset:2048
	global_load_dwordx4 v[100:103], v136, s[98:99] offset:3072
	s_waitcnt vmcnt(0)
; __device__ __forceinline__ void row_phase(const Params& P, int glayer, int layer, int xsrc, bool hasY, int gate_idx, const float* gpost,
;                           int xdst, bool doH, const float* gpre, int sh_idx, int nrows) {
;     ...
;         if (xsrc != 0 && row < N_X) {
; #pragma unroll
;           for (int i = 0; i < 4; ++i) {
;             const uint4 raw = xr[u][i];
;             xv[i].x = bf2f((u16)(raw.x & 0xffff)); xv[i].y = bf2f((u16)(raw.x >> 16));
;             xv[i].z = bf2f((u16)(raw.y & 0xffff)); xv[i].w = bf2f((u16)(raw.y >> 16));
;           }
;         } else {
; #pragma unroll
;           for (int i = 0; i < 4; ++i) {
;             xv[i].x = __uint_as_float(xr[u][i].x); xv[i].y = __uint_as_float(xr[u][i].y);
;             xv[i].z = __uint_as_float(xr[u][i].z); xv[i].w = __uint_as_float(xr[u][i].w);
;           }
;         }
;         if (hasY) {
;           float4 yv[4];
;           float ss = 0.f;
; #pragma unroll
;           for (int i = 0; i < 4; ++i) {
;             const uint2 raw = yy[u][i];
;             yv[i].x = bf2f((u16)(raw.x & 0xffff)); yv[i].y = bf2f((u16)(raw.x >> 16));
;             yv[i].z = bf2f((u16)(raw.y & 0xffff)); yv[i].w = bf2f((u16)(raw.y >> 16));
;             ss += yv[i].x * yv[i].x + yv[i].y * yv[i].y + yv[i].z * yv[i].z + yv[i].w * yv[i].w;
;           }
;           ss = wave_sum(ss);
;           const float rstd = __builtin_amdgcn_rsqf(ss * (1.f / 1024.f) + EPSF);
; #pragma unroll
;           for (int i = 0; i < 4; ++i) {
;             const int col = (i * 64 + lane) * 4;
;             const float4 gt = *reinterpret_cast<const float4*>(modg + gate_idx * 1024 + col);
;             const float4 gp = *reinterpret_cast<const float4*>(gpost + col);
;             xv[i].x += gt.x * (yv[i].x * rstd * gp.x); xv[i].y += gt.y * (yv[i].y * rstd * gp.y);
;             xv[i].z += gt.z * (yv[i].z * rstd * gp.z); xv[i].w += gt.w * (yv[i].w * rstd * gp.w);
;           }
;         }
;         if (xdst == 3 || (xdst == 1 && row >= N_X)) {
;           float* xout = (xdst == 3) ? P.out + (long)row * 1024 : P.xc + (long)(row - N_X) * 1024;
; #pragma unroll
;           for (int i = 0; i < 4; ++i) *reinterpret_cast<float4*>(xout + (i * 64 + lane) * 4) = xv[i];
;         } else if (xdst != 0) {
;           u16* xo = ((xdst == 1) ? resA : P.zf) + (long)row * 1024;
; #pragma unroll
;           for (int i = 0; i < 4; ++i) {
	v_mul_f32_e32 v72, v72, v120
	v_mul_f32_e32 v73, v73, v121
	v_mul_f32_e32 v74, v74, v122
	v_mul_f32_e32 v75, v75, v123
	v_mul_f32_e32 v76, v76, v124
	v_mul_f32_e32 v77, v77, v125
	v_mul_f32_e32 v78, v78, v126
	v_mul_f32_e32 v79, v79, v127
	v_mul_f32_e32 v80, v80, v128
	v_mul_f32_e32 v81, v81, v129
	v_mul_f32_e32 v82, v82, v130
	v_mul_f32_e32 v83, v83, v131
	v_mul_f32_e32 v84, v84, v132
	v_mul_f32_e32 v85, v85, v133
	v_mul_f32_e32 v86, v86, v134
	v_mul_f32_e32 v87, v87, v135
	v_fma_f32 v88, v88, v166, v88
	v_fma_f32 v89, v89, v167, v89
	v_fma_f32 v90, v90, v168, v90
	v_fma_f32 v91, v91, v169, v91
	v_fma_f32 v92, v92, v170, v92
	v_fma_f32 v93, v93, v171, v93
	v_fma_f32 v94, v94, v172, v94
	v_fma_f32 v95, v95, v173, v95
	v_fma_f32 v96, v96, v174, v96
	v_fma_f32 v97, v97, v175, v97
	v_fma_f32 v98, v98, v176, v98
	v_fma_f32 v99, v99, v177, v99
	v_fma_f32 v100, v100, v178, v100
	v_fma_f32 v101, v101, v179, v101
	v_fma_f32 v102, v102, v180, v102
	v_fma_f32 v103, v103, v181, v103
	s_lshl_b32 vcc_lo, s19, 11
	s_add_u32 vcc_lo, vcc_lo, 0xc00000
	s_add_u32 s100, s12, vcc_lo
	s_addc_u32 s101, s13, 0
	global_load_dwordx2 v[174:175], v137, s[100:101] offset:0
	global_load_dwordx2 v[176:177], v137, s[100:101] offset:512
	global_load_dwordx2 v[178:179], v137, s[100:101] offset:1024
	global_load_dwordx2 v[180:181], v137, s[100:101] offset:1536
	s_lshl_b32 vcc_lo, s19, 11
	s_add_u32 vcc_lo, vcc_lo, 0xc00000
	s_add_u32 s100, s14, vcc_lo
	s_addc_u32 s101, s15, 0
	global_load_dwordx2 v[182:183], v137, s[100:101] offset:0
	global_load_dwordx2 v[184:185], v137, s[100:101] offset:512
	global_load_dwordx2 v[186:187], v137, s[100:101] offset:1024
	global_load_dwordx2 v[188:189], v137, s[100:101] offset:1536
	v_lshlrev_b32_e32 v120, 16, v48
	v_and_b32_e32 v121, 0xffff0000, v48
	v_lshlrev_b32_e32 v122, 16, v49
	v_and_b32_e32 v123, 0xffff0000, v49
	v_lshlrev_b32_e32 v124, 16, v50
	v_and_b32_e32 v125, 0xffff0000, v50
	v_lshlrev_b32_e32 v126, 16, v51
	v_and_b32_e32 v127, 0xffff0000, v51
	v_lshlrev_b32_e32 v128, 16, v52
	v_and_b32_e32 v129, 0xffff0000, v52
	v_lshlrev_b32_e32 v130, 16, v53
	v_and_b32_e32 v131, 0xffff0000, v53
	v_lshlrev_b32_e32 v132, 16, v54
	v_and_b32_e32 v133, 0xffff0000, v54
	v_lshlrev_b32_e32 v134, 16, v55
	v_and_b32_e32 v135, 0xffff0000, v55
	v_mul_f32_e32 v138, v120, v120
	v_mul_f32_e32 v149, v121, v121
	v_mul_f32_e32 v150, v122, v122
	v_mul_f32_e32 v154, v123, v123
	v_fma_f32 v138, v124, v124, v138
	v_fma_f32 v149, v125, v125, v149
	v_fma_f32 v150, v126, v126, v150
	v_fma_f32 v154, v127, v127, v154
	v_fma_f32 v138, v128, v128, v138
	v_fma_f32 v149, v129, v129, v149
	v_fma_f32 v150, v130, v130, v150
	v_fma_f32 v154, v131, v131, v154
	v_fma_f32 v138, v132, v132, v138
	v_fma_f32 v149, v133, v133, v149
	v_fma_f32 v150, v134, v134, v150
	v_fma_f32 v154, v135, v135, v154
	v_add_f32_e32 v138, v138, v149
	v_add_f32_e32 v150, v150, v154
	v_add_f32_e32 v138, v138, v150
	s_nop 1
	v_add_f32_dpp v138, v138, v138 quad_perm:[1,0,3,2] row_mask:0xf bank_mask:0xf
	s_nop 1
	v_add_f32_dpp v138, v138, v138 quad_perm:[2,3,0,1] row_mask:0xf bank_mask:0xf
	s_nop 1
	v_add_f32_dpp v138, v138, v138 row_half_mirror row_mask:0xf bank_mask:0xf
	s_nop 1
	v_add_f32_dpp v138, v138, v138 row_mirror row_mask:0xf bank_mask:0xf
	v_mov_b32_e32 v139, v138
	s_nop 1
	v_permlane16_swap_b32_e32 v138, v139
	v_add_f32_e32 v138, v138, v139
	v_mov_b32_e32 v139, v138
	s_nop 1
	v_permlane32_swap_b32_e32 v138, v139
	v_add_f32_e32 v138, v138, v139
	v_mul_f32_e32 v138, 0x3a800000, v138
	v_add_f32_e32 v138, 0x358637bd, v138
	v_rsq_f32_e32 v140, v138
	v_lshlrev_b32_e32 v0, 16, v8
	v_and_b32_e32 v1, 0xffff0000, v8
	v_lshlrev_b32_e32 v2, 16, v9
	v_and_b32_e32 v3, 0xffff0000, v9
	v_lshlrev_b32_e32 v4, 16, v10
	v_and_b32_e32 v5, 0xffff0000, v10
	v_lshlrev_b32_e32 v6, 16, v11
	v_and_b32_e32 v7, 0xffff0000, v11
	v_lshlrev_b32_e32 v8, 16, v12
	v_and_b32_e32 v9, 0xffff0000, v12
	v_lshlrev_b32_e32 v10, 16, v13
	v_and_b32_e32 v11, 0xffff0000, v13
	v_lshlrev_b32_e32 v12, 16, v14
	v_and_b32_e32 v13, 0xffff0000, v14
	v_lshlrev_b32_e32 v14, 16, v15
	v_and_b32_e32 v15, 0xffff0000, v15
	s_nop 0
	v_mul_f32_e32 v120, v120, v140
	v_mul_f32_e32 v121, v121, v140
	v_mul_f32_e32 v122, v122, v140
	v_mul_f32_e32 v123, v123, v140
	v_mul_f32_e32 v124, v124, v140
	v_mul_f32_e32 v125, v125, v140
	v_mul_f32_e32 v126, v126, v140
	v_mul_f32_e32 v127, v127, v140
	v_mul_f32_e32 v128, v128, v140
	v_mul_f32_e32 v129, v129, v140
	v_mul_f32_e32 v130, v130, v140
	v_mul_f32_e32 v131, v131, v140
	v_mul_f32_e32 v132, v132, v140
	v_mul_f32_e32 v133, v133, v140
	v_mul_f32_e32 v134, v134, v140
	v_mul_f32_e32 v135, v135, v140
	v_fma_f32 v0, v120, v72, v0
	v_fma_f32 v1, v121, v73, v1
	v_fma_f32 v2, v122, v74, v2
	v_fma_f32 v3, v123, v75, v3
	v_fma_f32 v4, v124, v76, v4
	v_fma_f32 v5, v125, v77, v5
	v_fma_f32 v6, v126, v78, v6
	v_fma_f32 v7, v127, v79, v7
	v_fma_f32 v8, v128, v80, v8
	v_fma_f32 v9, v129, v81, v9
	v_fma_f32 v10, v130, v82, v10
	v_fma_f32 v11, v131, v83, v11
	v_fma_f32 v12, v132, v84, v12
	v_fma_f32 v13, v133, v85, v13
	v_fma_f32 v14, v134, v86, v14
	v_fma_f32 v15, v135, v87, v15
	v_cvt_pk_bf16_f32 v156, v0, v1
	v_cvt_pk_bf16_f32 v157, v2, v3
	v_cvt_pk_bf16_f32 v158, v4, v5
	v_cvt_pk_bf16_f32 v159, v6, v7
	v_cvt_pk_bf16_f32 v160, v8, v9
	v_cvt_pk_bf16_f32 v161, v10, v11
	v_cvt_pk_bf16_f32 v162, v12, v13
	v_cvt_pk_bf16_f32 v163, v14, v15
	s_lshl_b32 vcc_lo, s19, 11
	s_add_u32 s100, s16, vcc_lo
	s_addc_u32 s101, s17, 0
	global_store_dwordx2 v137, v[156:157], s[100:101] offset:0
	global_store_dwordx2 v137, v[158:159], s[100:101] offset:512
	global_store_dwordx2 v137, v[160:161], s[100:101] offset:1024
; __device__ __forceinline__ void row_phase(const Params& P, int glayer, int layer, int xsrc, bool hasY, int gate_idx, const float* gpost,
;                           int xdst, bool doH, const float* gpre, int sh_idx, int nrows) {
;     ...
;     for (int u = 0; u < 4; ++u) {
;       const int R = rb + u * stride;
;       if (R < nrows) {
;         if (xsrc != 0 && R < N_X) {
;           const u16* xs_ = ((xsrc == 1) ? resA : P.zf) + (long)R * 1024;
; #pragma unroll
;           for (int i = 0; i < 4; ++i) {
;             const uint2 t2 = *reinterpret_cast<const uint2*>(xs_ + (i * 64 + lane) * 4);
;             xr[u][i].x = t2.x; xr[u][i].y = t2.y;
;           }
;         } else {
;           const float* xin_;
;           if (xsrc == 0) xin_ = R < N_X ? P.x + (long)R * 1024 : P.ctx + (long)(R - N_X) * 1024;
;           else           xin_ = P.xc + (long)(R - N_X) * 1024;
; #pragma unroll
;           for (int i = 0; i < 4; ++i) xr[u][i] = *reinterpret_cast<const uint4*>(xin_ + (i * 64 + lane) * 4);
;         }
;         if (hasY) {
;           const u16* y_ = P.hy + (long)R * 1024;
; #pragma unroll
;     ...
;         if (doH) {
;           float ss = 0.f;
; #pragma unroll
;           for (int i = 0; i < 4; ++i) ss += xv[i].x * xv[i].x + xv[i].y * xv[i].y + xv[i].z * xv[i].z + xv[i].w * xv[i].w;
;           ss = wave_sum(ss);
;           const float rstd = __builtin_amdgcn_rsqf(ss * (1.f / 1024.f) + EPSF);
;           u16* h = P.hy + (long)row * 1024;
; #pragma unroll
;           for (int i = 0; i < 4; ++i) {
;             const int col = (i * 64 + lane) * 4;
;             const float4 g = *reinterpret_cast<const float4*>(gpre + col);
;             const float4 sh = *reinterpret_cast<const float4*>(modp + sh_idx * 1024 + col);
;             const float4 sc = *reinterpret_cast<const float4*>(modp + (sh_idx + 1) * 1024 + col);
;             const unsigned h0 = f2bf(xv[i].x * rstd * g.x * (1.f + sc.x) + sh.x);
;             const unsigned h1 = f2bf(xv[i].y * rstd * g.y * (1.f + sc.y) + sh.y);
;             const unsigned h2 = f2bf(xv[i].z * rstd * g.z * (1.f + sc.z) + sh.z);
;             const unsigned h3 = f2bf(xv[i].w * rstd * g.w * (1.f + sc.w) + sh.w);
;             *reinterpret_cast<uint2*>(h + col) = make_uint2(h0 | (h1 << 16), h2 | (h3 << 16));
;           }
;         }
	global_store_dwordx2 v137, v[162:163], s[100:101] offset:1536
	v_mul_f32_e32 v138, v0, v0
	v_mul_f32_e32 v149, v1, v1
	v_mul_f32_e32 v150, v2, v2
	v_mul_f32_e32 v154, v3, v3
	v_fma_f32 v138, v4, v4, v138
	v_fma_f32 v149, v5, v5, v149
	v_fma_f32 v150, v6, v6, v150
	v_fma_f32 v154, v7, v7, v154
	v_fma_f32 v138, v8, v8, v138
	v_fma_f32 v149, v9, v9, v149
	v_fma_f32 v150, v10, v10, v150
	v_fma_f32 v154, v11, v11, v154
	v_fma_f32 v138, v12, v12, v138
	v_fma_f32 v149, v13, v13, v149
	v_fma_f32 v150, v14, v14, v150
	v_fma_f32 v154, v15, v15, v154
	v_add_f32_e32 v138, v138, v149
	v_add_f32_e32 v150, v150, v154
	v_add_f32_e32 v138, v138, v150
	s_nop 1
	v_add_f32_dpp v138, v138, v138 quad_perm:[1,0,3,2] row_mask:0xf bank_mask:0xf
	s_nop 1
	v_add_f32_dpp v138, v138, v138 quad_perm:[2,3,0,1] row_mask:0xf bank_mask:0xf
	s_nop 1
	v_add_f32_dpp v138, v138, v138 row_half_mirror row_mask:0xf bank_mask:0xf
	s_nop 1
	v_add_f32_dpp v138, v138, v138 row_mirror row_mask:0xf bank_mask:0xf
	v_mov_b32_e32 v139, v138
	s_nop 1
	v_permlane16_swap_b32_e32 v138, v139
	v_add_f32_e32 v138, v138, v139
	v_mov_b32_e32 v139, v138
	s_nop 1
	v_permlane32_swap_b32_e32 v138, v139
	v_add_f32_e32 v138, v138, v139
	v_mul_f32_e32 v138, 0x3a800000, v138
	v_add_f32_e32 v138, 0x358637bd, v138
	v_rsq_f32_e32 v140, v138
	s_nop 0
	v_mul_f32_e32 v120, v0, v140
	v_mul_f32_e32 v121, v1, v140
	v_mul_f32_e32 v122, v2, v140
	v_mul_f32_e32 v123, v3, v140
	v_mul_f32_e32 v124, v4, v140
	v_mul_f32_e32 v125, v5, v140
	v_mul_f32_e32 v126, v6, v140
	v_mul_f32_e32 v127, v7, v140
	v_mul_f32_e32 v128, v8, v140
	v_mul_f32_e32 v129, v9, v140
	v_mul_f32_e32 v130, v10, v140
	v_mul_f32_e32 v131, v11, v140
	v_mul_f32_e32 v132, v12, v140
	v_mul_f32_e32 v133, v13, v140
	v_mul_f32_e32 v134, v14, v140
	v_mul_f32_e32 v135, v15, v140
	v_fma_f32 v120, v120, v88, v104
	v_fma_f32 v121, v121, v89, v105
	v_fma_f32 v122, v122, v90, v106
	v_fma_f32 v123, v123, v91, v107
	v_fma_f32 v124, v124, v92, v108
	v_fma_f32 v125, v125, v93, v109
	v_fma_f32 v126, v126, v94, v110
	v_fma_f32 v127, v127, v95, v111
	v_fma_f32 v128, v128, v96, v112
	v_fma_f32 v129, v129, v97, v113
	v_fma_f32 v130, v130, v98, v114
	v_fma_f32 v131, v131, v99, v115
	v_fma_f32 v132, v132, v100, v116
	v_fma_f32 v133, v133, v101, v117
	v_fma_f32 v134, v134, v102, v118
	v_fma_f32 v135, v135, v103, v119
	v_cvt_pk_bf16_f32 v156, v120, v121
	v_cvt_pk_bf16_f32 v157, v122, v123
	v_cvt_pk_bf16_f32 v158, v124, v125
	v_cvt_pk_bf16_f32 v159, v126, v127
	v_cvt_pk_bf16_f32 v160, v128, v129
	v_cvt_pk_bf16_f32 v161, v130, v131
	v_cvt_pk_bf16_f32 v162, v132, v133
	v_cvt_pk_bf16_f32 v163, v134, v135
	s_lshl_b32 vcc_lo, s19, 11
	s_add_u32 s100, s14, vcc_lo
	s_addc_u32 s101, s15, 0
	global_store_dwordx2 v137, v[156:157], s[100:101] offset:0
	global_store_dwordx2 v137, v[158:159], s[100:101] offset:512
	global_store_dwordx2 v137, v[160:161], s[100:101] offset:1024
	global_store_dwordx2 v137, v[162:163], s[100:101] offset:1536
	s_lshl_b32 vcc_lo, s19, 11
	s_add_u32 vcc_lo, vcc_lo, 0x1000000
	s_add_u32 s100, s12, vcc_lo
	s_addc_u32 s101, s13, 0
	global_load_dwordx2 v[8:9], v137, s[100:101] offset:0
	global_load_dwordx2 v[10:11], v137, s[100:101] offset:512
	global_load_dwordx2 v[12:13], v137, s[100:101] offset:1024
	global_load_dwordx2 v[14:15], v137, s[100:101] offset:1536
	s_lshl_b32 vcc_lo, s19, 11
	s_add_u32 vcc_lo, vcc_lo, 0x1000000
	s_add_u32 s100, s14, vcc_lo
	s_addc_u32 s101, s15, 0
	global_load_dwordx2 v[48:49], v137, s[100:101] offset:0
	global_load_dwordx2 v[50:51], v137, s[100:101] offset:512
	global_load_dwordx2 v[52:53], v137, s[100:101] offset:1024
	global_load_dwordx2 v[54:55], v137, s[100:101] offset:1536
	v_lshlrev_b32_e32 v120, 16, v56
	v_and_b32_e32 v121, 0xffff0000, v56
	v_lshlrev_b32_e32 v122, 16, v57
	v_and_b32_e32 v123, 0xffff0000, v57
	v_lshlrev_b32_e32 v124, 16, v58
	v_and_b32_e32 v125, 0xffff0000, v58
	v_lshlrev_b32_e32 v126, 16, v59
	v_and_b32_e32 v127, 0xffff0000, v59
	v_lshlrev_b32_e32 v128, 16, v60
	v_and_b32_e32 v129, 0xffff0000, v60
	v_lshlrev_b32_e32 v130, 16, v61
	v_and_b32_e32 v131, 0xffff0000, v61
	v_lshlrev_b32_e32 v132, 16, v62
	v_and_b32_e32 v133, 0xffff0000, v62
	v_lshlrev_b32_e32 v134, 16, v63
	v_and_b32_e32 v135, 0xffff0000, v63
	v_mul_f32_e32 v138, v120, v120
	v_mul_f32_e32 v149, v121, v121
	v_mul_f32_e32 v150, v122, v122
	v_mul_f32_e32 v154, v123, v123
	v_fma_f32 v138, v124, v124, v138
	v_fma_f32 v149, v125, v125, v149
	v_fma_f32 v150, v126, v126, v150
	v_fma_f32 v154, v127, v127, v154
	v_fma_f32 v138, v128, v128, v138
	v_fma_f32 v149, v129, v129, v149
	v_fma_f32 v150, v130, v130, v150
	v_fma_f32 v154, v131, v131, v154
	v_fma_f32 v138, v132, v132, v138
	v_fma_f32 v149, v133, v133, v149
	v_fma_f32 v150, v134, v134, v150
	v_fma_f32 v154, v135, v135, v154
	v_add_f32_e32 v138, v138, v149
	v_add_f32_e32 v150, v150, v154
	v_add_f32_e32 v138, v138, v150
	s_nop 1
	v_add_f32_dpp v138, v138, v138 quad_perm:[1,0,3,2] row_mask:0xf bank_mask:0xf
	s_nop 1
	v_add_f32_dpp v138, v138, v138 quad_perm:[2,3,0,1] row_mask:0xf bank_mask:0xf
	s_nop 1
	v_add_f32_dpp v138, v138, v138 row_half_mirror row_mask:0xf bank_mask:0xf
	s_nop 1
	v_add_f32_dpp v138, v138, v138 row_mirror row_mask:0xf bank_mask:0xf
	v_mov_b32_e32 v139, v138
	s_nop 1
	v_permlane16_swap_b32_e32 v138, v139
	v_add_f32_e32 v138, v138, v139
	v_mov_b32_e32 v139, v138
	s_nop 1
	v_permlane32_swap_b32_e32 v138, v139
	v_add_f32_e32 v138, v138, v139
	v_mul_f32_e32 v138, 0x3a800000, v138
	v_add_f32_e32 v138, 0x358637bd, v138
	v_rsq_f32_e32 v140, v138
	v_lshlrev_b32_e32 v16, 16, v24
	v_and_b32_e32 v17, 0xffff0000, v24
	v_lshlrev_b32_e32 v18, 16, v25
	v_and_b32_e32 v19, 0xffff0000, v25
; __device__ __forceinline__ void row_phase(const Params& P, int glayer, int layer, int xsrc, bool hasY, int gate_idx, const float* gpost,
;                           int xdst, bool doH, const float* gpre, int sh_idx, int nrows) {
;     ...
;         if (xsrc != 0 && row < N_X) {
; #pragma unroll
;           for (int i = 0; i < 4; ++i) {
;             const uint4 raw = xr[u][i];
;             xv[i].x = bf2f((u16)(raw.x & 0xffff)); xv[i].y = bf2f((u16)(raw.x >> 16));
;             xv[i].z = bf2f((u16)(raw.y & 0xffff)); xv[i].w = bf2f((u16)(raw.y >> 16));
;           }
;         } else {
; #pragma unroll
;           for (int i = 0; i < 4; ++i) {
;             xv[i].x = __uint_as_float(xr[u][i].x); xv[i].y = __uint_as_float(xr[u][i].y);
;             xv[i].z = __uint_as_float(xr[u][i].z); xv[i].w = __uint_as_float(xr[u][i].w);
;           }
;         }
;         if (hasY) {
;           float4 yv[4];
;           float ss = 0.f;
; #pragma unroll
;           for (int i = 0; i < 4; ++i) {
;             const uint2 raw = yy[u][i];
;             yv[i].x = bf2f((u16)(raw.x & 0xffff)); yv[i].y = bf2f((u16)(raw.x >> 16));
;             yv[i].z = bf2f((u16)(raw.y & 0xffff)); yv[i].w = bf2f((u16)(raw.y >> 16));
;             ss += yv[i].x * yv[i].x + yv[i].y * yv[i].y + yv[i].z * yv[i].z + yv[i].w * yv[i].w;
;           }
;           ss = wave_sum(ss);
;           const float rstd = __builtin_amdgcn_rsqf(ss * (1.f / 1024.f) + EPSF);
; #pragma unroll
;           for (int i = 0; i < 4; ++i) {
;             const int col = (i * 64 + lane) * 4;
;             const float4 gt = *reinterpret_cast<const float4*>(modg + gate_idx * 1024 + col);
;             const float4 gp = *reinterpret_cast<const float4*>(gpost + col);
;             xv[i].x += gt.x * (yv[i].x * rstd * gp.x); xv[i].y += gt.y * (yv[i].y * rstd * gp.y);
;             xv[i].z += gt.z * (yv[i].z * rstd * gp.z); xv[i].w += gt.w * (yv[i].w * rstd * gp.w);
;           }
;         }
;         if (xdst == 3 || (xdst == 1 && row >= N_X)) {
;           float* xout = (xdst == 3) ? P.out + (long)row * 1024 : P.xc + (long)(row - N_X) * 1024;
; #pragma unroll
;           for (int i = 0; i < 4; ++i) *reinterpret_cast<float4*>(xout + (i * 64 + lane) * 4) = xv[i];
;         } else if (xdst != 0) {
;           u16* xo = ((xdst == 1) ? resA : P.zf) + (long)row * 1024;
; #pragma unroll
;           for (int i = 0; i < 4; ++i) {
	v_lshlrev_b32_e32 v20, 16, v26
	v_and_b32_e32 v21, 0xffff0000, v26
	v_lshlrev_b32_e32 v22, 16, v27
	v_and_b32_e32 v23, 0xffff0000, v27
	v_lshlrev_b32_e32 v24, 16, v28
	v_and_b32_e32 v25, 0xffff0000, v28
	v_lshlrev_b32_e32 v26, 16, v29
	v_and_b32_e32 v27, 0xffff0000, v29
	v_lshlrev_b32_e32 v28, 16, v30
	v_and_b32_e32 v29, 0xffff0000, v30
	v_lshlrev_b32_e32 v30, 16, v31
	v_and_b32_e32 v31, 0xffff0000, v31
	s_nop 0
	v_mul_f32_e32 v120, v120, v140
	v_mul_f32_e32 v121, v121, v140
	v_mul_f32_e32 v122, v122, v140
	v_mul_f32_e32 v123, v123, v140
	v_mul_f32_e32 v124, v124, v140
	v_mul_f32_e32 v125, v125, v140
	v_mul_f32_e32 v126, v126, v140
	v_mul_f32_e32 v127, v127, v140
	v_mul_f32_e32 v128, v128, v140
	v_mul_f32_e32 v129, v129, v140
	v_mul_f32_e32 v130, v130, v140
	v_mul_f32_e32 v131, v131, v140
	v_mul_f32_e32 v132, v132, v140
	v_mul_f32_e32 v133, v133, v140
	v_mul_f32_e32 v134, v134, v140
	v_mul_f32_e32 v135, v135, v140
	v_fma_f32 v16, v120, v72, v16
	v_fma_f32 v17, v121, v73, v17
	v_fma_f32 v18, v122, v74, v18
	v_fma_f32 v19, v123, v75, v19
	v_fma_f32 v20, v124, v76, v20
	v_fma_f32 v21, v125, v77, v21
	v_fma_f32 v22, v126, v78, v22
	v_fma_f32 v23, v127, v79, v23
	v_fma_f32 v24, v128, v80, v24
	v_fma_f32 v25, v129, v81, v25
	v_fma_f32 v26, v130, v82, v26
	v_fma_f32 v27, v131, v83, v27
	v_fma_f32 v28, v132, v84, v28
	v_fma_f32 v29, v133, v85, v29
	v_fma_f32 v30, v134, v86, v30
	v_fma_f32 v31, v135, v87, v31
	v_cvt_pk_bf16_f32 v156, v16, v17
	v_cvt_pk_bf16_f32 v157, v18, v19
	v_cvt_pk_bf16_f32 v158, v20, v21
	v_cvt_pk_bf16_f32 v159, v22, v23
	v_cvt_pk_bf16_f32 v160, v24, v25
	v_cvt_pk_bf16_f32 v161, v26, v27
	v_cvt_pk_bf16_f32 v162, v28, v29
	v_cvt_pk_bf16_f32 v163, v30, v31
	s_lshl_b32 vcc_lo, s19, 11
	s_add_u32 vcc_lo, vcc_lo, 0x400000
	s_add_u32 s100, s16, vcc_lo
	s_addc_u32 s101, s17, 0
	global_store_dwordx2 v137, v[156:157], s[100:101] offset:0
	global_store_dwordx2 v137, v[158:159], s[100:101] offset:512
	global_store_dwordx2 v137, v[160:161], s[100:101] offset:1024
	global_store_dwordx2 v137, v[162:163], s[100:101] offset:1536
	v_mul_f32_e32 v138, v16, v16
	v_mul_f32_e32 v149, v17, v17
	v_mul_f32_e32 v150, v18, v18
	v_mul_f32_e32 v154, v19, v19
	v_fma_f32 v138, v20, v20, v138
	v_fma_f32 v149, v21, v21, v149
	v_fma_f32 v150, v22, v22, v150
	v_fma_f32 v154, v23, v23, v154
	v_fma_f32 v138, v24, v24, v138
	v_fma_f32 v149, v25, v25, v149
	v_fma_f32 v150, v26, v26, v150
	v_fma_f32 v154, v27, v27, v154
	v_fma_f32 v138, v28, v28, v138
	v_fma_f32 v149, v29, v29, v149
	v_fma_f32 v150, v30, v30, v150
	v_fma_f32 v154, v31, v31, v154
	v_add_f32_e32 v138, v138, v149
	v_add_f32_e32 v150, v150, v154
	v_add_f32_e32 v138, v138, v150
	s_nop 1
	v_add_f32_dpp v138, v138, v138 quad_perm:[1,0,3,2] row_mask:0xf bank_mask:0xf
	s_nop 1
	v_add_f32_dpp v138, v138, v138 quad_perm:[2,3,0,1] row_mask:0xf bank_mask:0xf
	s_nop 1
	v_add_f32_dpp v138, v138, v138 row_half_mirror row_mask:0xf bank_mask:0xf
	s_nop 1
	v_add_f32_dpp v138, v138, v138 row_mirror row_mask:0xf bank_mask:0xf
	v_mov_b32_e32 v139, v138
	s_nop 1
	v_permlane16_swap_b32_e32 v138, v139
	v_add_f32_e32 v138, v138, v139
	v_mov_b32_e32 v139, v138
	s_nop 1
	v_permlane32_swap_b32_e32 v138, v139
	v_add_f32_e32 v138, v138, v139
	v_mul_f32_e32 v138, 0x3a800000, v138
	v_add_f32_e32 v138, 0x358637bd, v138
	v_rsq_f32_e32 v140, v138
	s_nop 0
	v_mul_f32_e32 v120, v16, v140
	v_mul_f32_e32 v121, v17, v140
	v_mul_f32_e32 v122, v18, v140
	v_mul_f32_e32 v123, v19, v140
	v_mul_f32_e32 v124, v20, v140
	v_mul_f32_e32 v125, v21, v140
	v_mul_f32_e32 v126, v22, v140
	v_mul_f32_e32 v127, v23, v140
	v_mul_f32_e32 v128, v24, v140
	v_mul_f32_e32 v129, v25, v140
	v_mul_f32_e32 v130, v26, v140
	v_mul_f32_e32 v131, v27, v140
	v_mul_f32_e32 v132, v28, v140
	v_mul_f32_e32 v133, v29, v140
	v_mul_f32_e32 v134, v30, v140
	v_mul_f32_e32 v135, v31, v140
	v_fma_f32 v120, v120, v88, v104
	v_fma_f32 v121, v121, v89, v105
	v_fma_f32 v122, v122, v90, v106
	v_fma_f32 v123, v123, v91, v107
	v_fma_f32 v124, v124, v92, v108
	v_fma_f32 v125, v125, v93, v109
	v_fma_f32 v126, v126, v94, v110
	v_fma_f32 v127, v127, v95, v111
	v_fma_f32 v128, v128, v96, v112
	v_fma_f32 v129, v129, v97, v113
	v_fma_f32 v130, v130, v98, v114
	v_fma_f32 v131, v131, v99, v115
	v_fma_f32 v132, v132, v100, v116
	v_fma_f32 v133, v133, v101, v117
	v_fma_f32 v134, v134, v102, v118
	v_fma_f32 v135, v135, v103, v119
	v_cvt_pk_bf16_f32 v156, v120, v121
	v_cvt_pk_bf16_f32 v157, v122, v123
	v_cvt_pk_bf16_f32 v158, v124, v125
	v_cvt_pk_bf16_f32 v159, v126, v127
	v_cvt_pk_bf16_f32 v160, v128, v129
	v_cvt_pk_bf16_f32 v161, v130, v131
	v_cvt_pk_bf16_f32 v162, v132, v133
	v_cvt_pk_bf16_f32 v163, v134, v135
	s_lshl_b32 vcc_lo, s19, 11
	s_add_u32 vcc_lo, vcc_lo, 0x400000
	s_add_u32 s100, s14, vcc_lo
	s_addc_u32 s101, s15, 0
	global_store_dwordx2 v137, v[156:157], s[100:101] offset:0
	global_store_dwordx2 v137, v[158:159], s[100:101] offset:512
	global_store_dwordx2 v137, v[160:161], s[100:101] offset:1024
	global_store_dwordx2 v137, v[162:163], s[100:101] offset:1536
	s_lshl_b32 vcc_lo, s19, 11
	s_add_u32 vcc_lo, vcc_lo, 0x1400000
	s_add_u32 s100, s12, vcc_lo
	s_addc_u32 s101, s13, 0
	global_load_dwordx2 v[24:25], v137, s[100:101] offset:0
	global_load_dwordx2 v[26:27], v137, s[100:101] offset:512
	global_load_dwordx2 v[28:29], v137, s[100:101] offset:1024
	global_load_dwordx2 v[30:31], v137, s[100:101] offset:1536
	s_lshl_b32 vcc_lo, s19, 11
	s_add_u32 vcc_lo, vcc_lo, 0x1400000
	s_add_u32 s100, s14, vcc_lo
	s_addc_u32 s101, s15, 0
	global_load_dwordx2 v[56:57], v137, s[100:101] offset:0
	global_load_dwordx2 v[58:59], v137, s[100:101] offset:512
	global_load_dwordx2 v[60:61], v137, s[100:101] offset:1024
; __device__ __forceinline__ void row_phase(const Params& P, int glayer, int layer, int xsrc, bool hasY, int gate_idx, const float* gpost,
;                           int xdst, bool doH, const float* gpre, int sh_idx, int nrows) {
;     ...
;             const uint2 raw = yy[u][i];
;             yv[i].x = bf2f((u16)(raw.x & 0xffff)); yv[i].y = bf2f((u16)(raw.x >> 16));
;             yv[i].z = bf2f((u16)(raw.y & 0xffff)); yv[i].w = bf2f((u16)(raw.y >> 16));
;             ss += yv[i].x * yv[i].x + yv[i].y * yv[i].y + yv[i].z * yv[i].z + yv[i].w * yv[i].w;
;           }
;           ss = wave_sum(ss);
;           const float rstd = __builtin_amdgcn_rsqf(ss * (1.f / 1024.f) + EPSF);
; #pragma unroll
;           for (int i = 0; i < 4; ++i) {
;             const int col = (i * 64 + lane) * 4;
;             const float4 gt = *reinterpret_cast<const float4*>(modg + gate_idx * 1024 + col);
;             const float4 gp = *reinterpret_cast<const float4*>(gpost + col);
;             xv[i].x += gt.x * (yv[i].x * rstd * gp.x); xv[i].y += gt.y * (yv[i].y * rstd * gp.y);
;             xv[i].z += gt.z * (yv[i].z * rstd * gp.z); xv[i].w += gt.w * (yv[i].w * rstd * gp.w);
;           }
;         }
;         if (xdst == 3 || (xdst == 1 && row >= N_X)) {
;           float* xout = (xdst == 3) ? P.out + (long)row * 1024 : P.xc + (long)(row - N_X) * 1024;
; #pragma unroll
;           for (int i = 0; i < 4; ++i) *reinterpret_cast<float4*>(xout + (i * 64 + lane) * 4) = xv[i];
;         } else if (xdst != 0) {
;           u16* xo = ((xdst == 1) ? resA : P.zf) + (long)row * 1024;
; #pragma unroll
;           for (int i = 0; i < 4; ++i) {
;             const unsigned b0 = f2bf(xv[i].x), b1 = f2bf(xv[i].y), b2 = f2bf(xv[i].z), b3 = f2bf(xv[i].w);
;             *reinterpret_cast<uint2*>(xo + (i * 64 + lane) * 4) = make_uint2(b0 | (b1 << 16), b2 | (b3 << 16));
;           }
;         }
;         if (doH) {
;           float ss = 0.f;
; #pragma unroll
;           for (int i = 0; i < 4; ++i) ss += xv[i].x * xv[i].x + xv[i].y * xv[i].y + xv[i].z * xv[i].z + xv[i].w * xv[i].w;
;           ss = wave_sum(ss);
;           const float rstd = __builtin_amdgcn_rsqf(ss * (1.f / 1024.f) + EPSF);
;           u16* h = P.hy + (long)row * 1024;
; #pragma unroll
;           for (int i = 0; i < 4; ++i) {
;             const int col = (i * 64 + lane) * 4;
	global_load_dwordx2 v[62:63], v137, s[100:101] offset:1536
	v_lshlrev_b32_e32 v120, 16, v64
	v_and_b32_e32 v121, 0xffff0000, v64
	v_lshlrev_b32_e32 v122, 16, v65
	v_and_b32_e32 v123, 0xffff0000, v65
	v_lshlrev_b32_e32 v124, 16, v66
	v_and_b32_e32 v125, 0xffff0000, v66
	v_lshlrev_b32_e32 v126, 16, v67
	v_and_b32_e32 v127, 0xffff0000, v67
	v_lshlrev_b32_e32 v128, 16, v68
	v_and_b32_e32 v129, 0xffff0000, v68
	v_lshlrev_b32_e32 v130, 16, v69
	v_and_b32_e32 v131, 0xffff0000, v69
	v_lshlrev_b32_e32 v132, 16, v70
	v_and_b32_e32 v133, 0xffff0000, v70
	v_lshlrev_b32_e32 v134, 16, v71
	v_and_b32_e32 v135, 0xffff0000, v71
	v_mul_f32_e32 v138, v120, v120
	v_mul_f32_e32 v149, v121, v121
	v_mul_f32_e32 v150, v122, v122
	v_mul_f32_e32 v154, v123, v123
	v_fma_f32 v138, v124, v124, v138
	v_fma_f32 v149, v125, v125, v149
	v_fma_f32 v150, v126, v126, v150
	v_fma_f32 v154, v127, v127, v154
	v_fma_f32 v138, v128, v128, v138
	v_fma_f32 v149, v129, v129, v149
	v_fma_f32 v150, v130, v130, v150
	v_fma_f32 v154, v131, v131, v154
	v_fma_f32 v138, v132, v132, v138
	v_fma_f32 v149, v133, v133, v149
	v_fma_f32 v150, v134, v134, v150
	v_fma_f32 v154, v135, v135, v154
	v_add_f32_e32 v138, v138, v149
	v_add_f32_e32 v150, v150, v154
	v_add_f32_e32 v138, v138, v150
	s_nop 1
	v_add_f32_dpp v138, v138, v138 quad_perm:[1,0,3,2] row_mask:0xf bank_mask:0xf
	s_nop 1
	v_add_f32_dpp v138, v138, v138 quad_perm:[2,3,0,1] row_mask:0xf bank_mask:0xf
	s_nop 1
	v_add_f32_dpp v138, v138, v138 row_half_mirror row_mask:0xf bank_mask:0xf
	s_nop 1
	v_add_f32_dpp v138, v138, v138 row_mirror row_mask:0xf bank_mask:0xf
	v_mov_b32_e32 v139, v138
	s_nop 1
	v_permlane16_swap_b32_e32 v138, v139
	v_add_f32_e32 v138, v138, v139
	v_mov_b32_e32 v139, v138
	s_nop 1
	v_permlane32_swap_b32_e32 v138, v139
	v_add_f32_e32 v138, v138, v139
	v_mul_f32_e32 v138, 0x3a800000, v138
	v_add_f32_e32 v138, 0x358637bd, v138
	v_rsq_f32_e32 v140, v138
	v_lshlrev_b32_e32 v32, 16, v40
	v_and_b32_e32 v33, 0xffff0000, v40
	v_lshlrev_b32_e32 v34, 16, v41
	v_and_b32_e32 v35, 0xffff0000, v41
	v_lshlrev_b32_e32 v36, 16, v42
	v_and_b32_e32 v37, 0xffff0000, v42
	v_lshlrev_b32_e32 v38, 16, v43
	v_and_b32_e32 v39, 0xffff0000, v43
	v_lshlrev_b32_e32 v40, 16, v44
	v_and_b32_e32 v41, 0xffff0000, v44
	v_lshlrev_b32_e32 v42, 16, v45
	v_and_b32_e32 v43, 0xffff0000, v45
	v_lshlrev_b32_e32 v44, 16, v46
	v_and_b32_e32 v45, 0xffff0000, v46
	v_lshlrev_b32_e32 v46, 16, v47
	v_and_b32_e32 v47, 0xffff0000, v47
	s_nop 0
	v_mul_f32_e32 v120, v120, v140
	v_mul_f32_e32 v121, v121, v140
	v_mul_f32_e32 v122, v122, v140
	v_mul_f32_e32 v123, v123, v140
	v_mul_f32_e32 v124, v124, v140
	v_mul_f32_e32 v125, v125, v140
	v_mul_f32_e32 v126, v126, v140
	v_mul_f32_e32 v127, v127, v140
	v_mul_f32_e32 v128, v128, v140
	v_mul_f32_e32 v129, v129, v140
	v_mul_f32_e32 v130, v130, v140
	v_mul_f32_e32 v131, v131, v140
	v_mul_f32_e32 v132, v132, v140
	v_mul_f32_e32 v133, v133, v140
	v_mul_f32_e32 v134, v134, v140
	v_mul_f32_e32 v135, v135, v140
	v_fma_f32 v32, v120, v72, v32
	v_fma_f32 v33, v121, v73, v33
	v_fma_f32 v34, v122, v74, v34
	v_fma_f32 v35, v123, v75, v35
	v_fma_f32 v36, v124, v76, v36
	v_fma_f32 v37, v125, v77, v37
	v_fma_f32 v38, v126, v78, v38
	v_fma_f32 v39, v127, v79, v39
	v_fma_f32 v40, v128, v80, v40
	v_fma_f32 v41, v129, v81, v41
	v_fma_f32 v42, v130, v82, v42
	v_fma_f32 v43, v131, v83, v43
	v_fma_f32 v44, v132, v84, v44
	v_fma_f32 v45, v133, v85, v45
	v_fma_f32 v46, v134, v86, v46
	v_fma_f32 v47, v135, v87, v47
	v_cvt_pk_bf16_f32 v156, v32, v33
	v_cvt_pk_bf16_f32 v157, v34, v35
	v_cvt_pk_bf16_f32 v158, v36, v37
	v_cvt_pk_bf16_f32 v159, v38, v39
	v_cvt_pk_bf16_f32 v160, v40, v41
	v_cvt_pk_bf16_f32 v161, v42, v43
	v_cvt_pk_bf16_f32 v162, v44, v45
	v_cvt_pk_bf16_f32 v163, v46, v47
	s_lshl_b32 vcc_lo, s19, 11
	s_add_u32 vcc_lo, vcc_lo, 0x800000
	s_add_u32 s100, s16, vcc_lo
	s_addc_u32 s101, s17, 0
	global_store_dwordx2 v137, v[156:157], s[100:101] offset:0
	global_store_dwordx2 v137, v[158:159], s[100:101] offset:512
	global_store_dwordx2 v137, v[160:161], s[100:101] offset:1024
	global_store_dwordx2 v137, v[162:163], s[100:101] offset:1536
	v_mul_f32_e32 v138, v32, v32
	v_mul_f32_e32 v149, v33, v33
	v_mul_f32_e32 v150, v34, v34
	v_mul_f32_e32 v154, v35, v35
	v_fma_f32 v138, v36, v36, v138
	v_fma_f32 v149, v37, v37, v149
	v_fma_f32 v150, v38, v38, v150
	v_fma_f32 v154, v39, v39, v154
	v_fma_f32 v138, v40, v40, v138
	v_fma_f32 v149, v41, v41, v149
	v_fma_f32 v150, v42, v42, v150
	v_fma_f32 v154, v43, v43, v154
	v_fma_f32 v138, v44, v44, v138
	v_fma_f32 v149, v45, v45, v149
	v_fma_f32 v150, v46, v46, v150
	v_fma_f32 v154, v47, v47, v154
	v_add_f32_e32 v138, v138, v149
	v_add_f32_e32 v150, v150, v154
	v_add_f32_e32 v138, v138, v150
	s_nop 1
	v_add_f32_dpp v138, v138, v138 quad_perm:[1,0,3,2] row_mask:0xf bank_mask:0xf
	s_nop 1
	v_add_f32_dpp v138, v138, v138 quad_perm:[2,3,0,1] row_mask:0xf bank_mask:0xf
	s_nop 1
	v_add_f32_dpp v138, v138, v138 row_half_mirror row_mask:0xf bank_mask:0xf
	s_nop 1
	v_add_f32_dpp v138, v138, v138 row_mirror row_mask:0xf bank_mask:0xf
	v_mov_b32_e32 v139, v138
	s_nop 1
	v_permlane16_swap_b32_e32 v138, v139
	v_add_f32_e32 v138, v138, v139
	v_mov_b32_e32 v139, v138
	s_nop 1
	v_permlane32_swap_b32_e32 v138, v139
	v_add_f32_e32 v138, v138, v139
	v_mul_f32_e32 v138, 0x3a800000, v138
	v_add_f32_e32 v138, 0x358637bd, v138
	v_rsq_f32_e32 v140, v138
	s_nop 0
	v_mul_f32_e32 v120, v32, v140
	v_mul_f32_e32 v121, v33, v140
	v_mul_f32_e32 v122, v34, v140
	v_mul_f32_e32 v123, v35, v140
	v_mul_f32_e32 v124, v36, v140
	v_mul_f32_e32 v125, v37, v140
	v_mul_f32_e32 v126, v38, v140
	v_mul_f32_e32 v127, v39, v140
	v_mul_f32_e32 v128, v40, v140
; __device__ __forceinline__ void row_phase(const Params& P, int glayer, int layer, int xsrc, bool hasY, int gate_idx, const float* gpost,
;                           int xdst, bool doH, const float* gpre, int sh_idx, int nrows) {
;     ...
;             const uint2 raw = yy[u][i];
;             yv[i].x = bf2f((u16)(raw.x & 0xffff)); yv[i].y = bf2f((u16)(raw.x >> 16));
;             yv[i].z = bf2f((u16)(raw.y & 0xffff)); yv[i].w = bf2f((u16)(raw.y >> 16));
;             ss += yv[i].x * yv[i].x + yv[i].y * yv[i].y + yv[i].z * yv[i].z + yv[i].w * yv[i].w;
;           }
;           ss = wave_sum(ss);
;           const float rstd = __builtin_amdgcn_rsqf(ss * (1.f / 1024.f) + EPSF);
; #pragma unroll
;           for (int i = 0; i < 4; ++i) {
;             const int col = (i * 64 + lane) * 4;
;             const float4 gt = *reinterpret_cast<const float4*>(modg + gate_idx * 1024 + col);
;             const float4 gp = *reinterpret_cast<const float4*>(gpost + col);
;             xv[i].x += gt.x * (yv[i].x * rstd * gp.x); xv[i].y += gt.y * (yv[i].y * rstd * gp.y);
;             xv[i].z += gt.z * (yv[i].z * rstd * gp.z); xv[i].w += gt.w * (yv[i].w * rstd * gp.w);
;           }
;         }
;         if (xdst == 3 || (xdst == 1 && row >= N_X)) {
;           float* xout = (xdst == 3) ? P.out + (long)row * 1024 : P.xc + (long)(row - N_X) * 1024;
; #pragma unroll
;           for (int i = 0; i < 4; ++i) *reinterpret_cast<float4*>(xout + (i * 64 + lane) * 4) = xv[i];
;         } else if (xdst != 0) {
;           u16* xo = ((xdst == 1) ? resA : P.zf) + (long)row * 1024;
; #pragma unroll
;           for (int i = 0; i < 4; ++i) {
;             const unsigned b0 = f2bf(xv[i].x), b1 = f2bf(xv[i].y), b2 = f2bf(xv[i].z), b3 = f2bf(xv[i].w);
;             *reinterpret_cast<uint2*>(xo + (i * 64 + lane) * 4) = make_uint2(b0 | (b1 << 16), b2 | (b3 << 16));
;           }
;         }
;         if (doH) {
;           float ss = 0.f;
; #pragma unroll
;           for (int i = 0; i < 4; ++i) ss += xv[i].x * xv[i].x + xv[i].y * xv[i].y + xv[i].z * xv[i].z + xv[i].w * xv[i].w;
;           ss = wave_sum(ss);
;           const float rstd = __builtin_amdgcn_rsqf(ss * (1.f / 1024.f) + EPSF);
;           u16* h = P.hy + (long)row * 1024;
; #pragma unroll
;           for (int i = 0; i < 4; ++i) {
;             const int col = (i * 64 + lane) * 4;
	v_mul_f32_e32 v129, v41, v140
	v_mul_f32_e32 v130, v42, v140
	v_mul_f32_e32 v131, v43, v140
	v_mul_f32_e32 v132, v44, v140
	v_mul_f32_e32 v133, v45, v140
	v_mul_f32_e32 v134, v46, v140
	v_mul_f32_e32 v135, v47, v140
	v_fma_f32 v120, v120, v88, v104
	v_fma_f32 v121, v121, v89, v105
	v_fma_f32 v122, v122, v90, v106
	v_fma_f32 v123, v123, v91, v107
	v_fma_f32 v124, v124, v92, v108
	v_fma_f32 v125, v125, v93, v109
	v_fma_f32 v126, v126, v94, v110
	v_fma_f32 v127, v127, v95, v111
	v_fma_f32 v128, v128, v96, v112
	v_fma_f32 v129, v129, v97, v113
	v_fma_f32 v130, v130, v98, v114
	v_fma_f32 v131, v131, v99, v115
	v_fma_f32 v132, v132, v100, v116
	v_fma_f32 v133, v133, v101, v117
	v_fma_f32 v134, v134, v102, v118
	v_fma_f32 v135, v135, v103, v119
	v_cvt_pk_bf16_f32 v156, v120, v121
	v_cvt_pk_bf16_f32 v157, v122, v123
	v_cvt_pk_bf16_f32 v158, v124, v125
	v_cvt_pk_bf16_f32 v159, v126, v127
	v_cvt_pk_bf16_f32 v160, v128, v129
	v_cvt_pk_bf16_f32 v161, v130, v131
	v_cvt_pk_bf16_f32 v162, v132, v133
	v_cvt_pk_bf16_f32 v163, v134, v135
	s_lshl_b32 vcc_lo, s19, 11
	s_add_u32 vcc_lo, vcc_lo, 0x800000
	s_add_u32 s100, s14, vcc_lo
	s_addc_u32 s101, s15, 0
	global_store_dwordx2 v137, v[156:157], s[100:101] offset:0
	global_store_dwordx2 v137, v[158:159], s[100:101] offset:512
	global_store_dwordx2 v137, v[160:161], s[100:101] offset:1024
	global_store_dwordx2 v137, v[162:163], s[100:101] offset:1536
	s_lshl_b32 vcc_lo, s19, 11
	s_add_u32 vcc_lo, vcc_lo, 0x1800000
	s_add_u32 s100, s12, vcc_lo
	s_addc_u32 s101, s13, 0
	global_load_dwordx2 v[40:41], v137, s[100:101] offset:0
	global_load_dwordx2 v[42:43], v137, s[100:101] offset:512
	global_load_dwordx2 v[44:45], v137, s[100:101] offset:1024
	global_load_dwordx2 v[46:47], v137, s[100:101] offset:1536
	s_lshl_b32 vcc_lo, s19, 11
	s_add_u32 vcc_lo, vcc_lo, 0x1800000
	s_add_u32 s100, s14, vcc_lo
	s_addc_u32 s101, s15, 0
	global_load_dwordx2 v[64:65], v137, s[100:101] offset:0
	global_load_dwordx2 v[66:67], v137, s[100:101] offset:512
	global_load_dwordx2 v[68:69], v137, s[100:101] offset:1024
	global_load_dwordx2 v[70:71], v137, s[100:101] offset:1536
	s_waitcnt vmcnt(48)
	v_lshlrev_b32_e32 v120, 16, v182
	v_and_b32_e32 v121, 0xffff0000, v182
	v_lshlrev_b32_e32 v122, 16, v183
	v_and_b32_e32 v123, 0xffff0000, v183
	v_lshlrev_b32_e32 v124, 16, v184
	v_and_b32_e32 v125, 0xffff0000, v184
	v_lshlrev_b32_e32 v126, 16, v185
	v_and_b32_e32 v127, 0xffff0000, v185
	v_lshlrev_b32_e32 v128, 16, v186
	v_and_b32_e32 v129, 0xffff0000, v186
	v_lshlrev_b32_e32 v130, 16, v187
	v_and_b32_e32 v131, 0xffff0000, v187
	v_lshlrev_b32_e32 v132, 16, v188
	v_and_b32_e32 v133, 0xffff0000, v188
	v_lshlrev_b32_e32 v134, 16, v189
	v_and_b32_e32 v135, 0xffff0000, v189
	v_mul_f32_e32 v138, v120, v120
	v_mul_f32_e32 v149, v121, v121
	v_mul_f32_e32 v150, v122, v122
	v_mul_f32_e32 v154, v123, v123
	v_fma_f32 v138, v124, v124, v138
	v_fma_f32 v149, v125, v125, v149
	v_fma_f32 v150, v126, v126, v150
	v_fma_f32 v154, v127, v127, v154
	v_fma_f32 v138, v128, v128, v138
	v_fma_f32 v149, v129, v129, v149
	v_fma_f32 v150, v130, v130, v150
	v_fma_f32 v154, v131, v131, v154
	v_fma_f32 v138, v132, v132, v138
	v_fma_f32 v149, v133, v133, v149
	v_fma_f32 v150, v134, v134, v150
	v_fma_f32 v154, v135, v135, v154
	v_add_f32_e32 v138, v138, v149
	v_add_f32_e32 v150, v150, v154
	v_add_f32_e32 v138, v138, v150
	s_nop 1
	v_add_f32_dpp v138, v138, v138 quad_perm:[1,0,3,2] row_mask:0xf bank_mask:0xf
	s_nop 1
	v_add_f32_dpp v138, v138, v138 quad_perm:[2,3,0,1] row_mask:0xf bank_mask:0xf
	s_nop 1
	v_add_f32_dpp v138, v138, v138 row_half_mirror row_mask:0xf bank_mask:0xf
	s_nop 1
	v_add_f32_dpp v138, v138, v138 row_mirror row_mask:0xf bank_mask:0xf
	v_mov_b32_e32 v139, v138
	s_nop 1
	v_permlane16_swap_b32_e32 v138, v139
	v_add_f32_e32 v138, v138, v139
	v_mov_b32_e32 v139, v138
	s_nop 1
	v_permlane32_swap_b32_e32 v138, v139
	v_add_f32_e32 v138, v138, v139
	v_mul_f32_e32 v138, 0x3a800000, v138
	v_add_f32_e32 v138, 0x358637bd, v138
	v_rsq_f32_e32 v140, v138
	v_lshlrev_b32_e32 v166, 16, v174
	v_and_b32_e32 v167, 0xffff0000, v174
	v_lshlrev_b32_e32 v168, 16, v175
	v_and_b32_e32 v169, 0xffff0000, v175
	v_lshlrev_b32_e32 v170, 16, v176
	v_and_b32_e32 v171, 0xffff0000, v176
	v_lshlrev_b32_e32 v172, 16, v177
	v_and_b32_e32 v173, 0xffff0000, v177
	v_lshlrev_b32_e32 v174, 16, v178
	v_and_b32_e32 v175, 0xffff0000, v178
	v_lshlrev_b32_e32 v176, 16, v179
	v_and_b32_e32 v177, 0xffff0000, v179
	v_lshlrev_b32_e32 v178, 16, v180
	v_and_b32_e32 v179, 0xffff0000, v180
	v_lshlrev_b32_e32 v180, 16, v181
	v_and_b32_e32 v181, 0xffff0000, v181
	s_nop 0
	v_mul_f32_e32 v120, v120, v140
	v_mul_f32_e32 v121, v121, v140
	v_mul_f32_e32 v122, v122, v140
	v_mul_f32_e32 v123, v123, v140
	v_mul_f32_e32 v124, v124, v140
	v_mul_f32_e32 v125, v125, v140
	v_mul_f32_e32 v126, v126, v140
	v_mul_f32_e32 v127, v127, v140
	v_mul_f32_e32 v128, v128, v140
	v_mul_f32_e32 v129, v129, v140
	v_mul_f32_e32 v130, v130, v140
	v_mul_f32_e32 v131, v131, v140
	v_mul_f32_e32 v132, v132, v140
	v_mul_f32_e32 v133, v133, v140
	v_mul_f32_e32 v134, v134, v140
	v_mul_f32_e32 v135, v135, v140
	v_fma_f32 v166, v120, v72, v166
	v_fma_f32 v167, v121, v73, v167
	v_fma_f32 v168, v122, v74, v168
	v_fma_f32 v169, v123, v75, v169
	v_fma_f32 v170, v124, v76, v170
	v_fma_f32 v171, v125, v77, v171
	v_fma_f32 v172, v126, v78, v172
	v_fma_f32 v173, v127, v79, v173
	v_fma_f32 v174, v128, v80, v174
	v_fma_f32 v175, v129, v81, v175
	v_fma_f32 v176, v130, v82, v176
	v_fma_f32 v177, v131, v83, v177
	v_fma_f32 v178, v132, v84, v178
	v_fma_f32 v179, v133, v85, v179
	v_fma_f32 v180, v134, v86, v180
	v_fma_f32 v181, v135, v87, v181
	v_cvt_pk_bf16_f32 v156, v166, v167
; __device__ __forceinline__ void row_phase(const Params& P, int glayer, int layer, int xsrc, bool hasY, int gate_idx, const float* gpost,
;                           int xdst, bool doH, const float* gpre, int sh_idx, int nrows) {
;     ...
;             const uint2 raw = yy[u][i];
;             yv[i].x = bf2f((u16)(raw.x & 0xffff)); yv[i].y = bf2f((u16)(raw.x >> 16));
;             yv[i].z = bf2f((u16)(raw.y & 0xffff)); yv[i].w = bf2f((u16)(raw.y >> 16));
;             ss += yv[i].x * yv[i].x + yv[i].y * yv[i].y + yv[i].z * yv[i].z + yv[i].w * yv[i].w;
;           }
;           ss = wave_sum(ss);
;           const float rstd = __builtin_amdgcn_rsqf(ss * (1.f / 1024.f) + EPSF);
; #pragma unroll
;           for (int i = 0; i < 4; ++i) {
;             const int col = (i * 64 + lane) * 4;
;             const float4 gt = *reinterpret_cast<const float4*>(modg + gate_idx * 1024 + col);
;             const float4 gp = *reinterpret_cast<const float4*>(gpost + col);
;             xv[i].x += gt.x * (yv[i].x * rstd * gp.x); xv[i].y += gt.y * (yv[i].y * rstd * gp.y);
;             xv[i].z += gt.z * (yv[i].z * rstd * gp.z); xv[i].w += gt.w * (yv[i].w * rstd * gp.w);
;           }
;         }
;         if (xdst == 3 || (xdst == 1 && row >= N_X)) {
;           float* xout = (xdst == 3) ? P.out + (long)row * 1024 : P.xc + (long)(row - N_X) * 1024;
; #pragma unroll
;           for (int i = 0; i < 4; ++i) *reinterpret_cast<float4*>(xout + (i * 64 + lane) * 4) = xv[i];
;         } else if (xdst != 0) {
;           u16* xo = ((xdst == 1) ? resA : P.zf) + (long)row * 1024;
; #pragma unroll
;           for (int i = 0; i < 4; ++i) {
;             const unsigned b0 = f2bf(xv[i].x), b1 = f2bf(xv[i].y), b2 = f2bf(xv[i].z), b3 = f2bf(xv[i].w);
;             *reinterpret_cast<uint2*>(xo + (i * 64 + lane) * 4) = make_uint2(b0 | (b1 << 16), b2 | (b3 << 16));
;           }
;         }
;         if (doH) {
;           float ss = 0.f;
; #pragma unroll
;           for (int i = 0; i < 4; ++i) ss += xv[i].x * xv[i].x + xv[i].y * xv[i].y + xv[i].z * xv[i].z + xv[i].w * xv[i].w;
;           ss = wave_sum(ss);
;           const float rstd = __builtin_amdgcn_rsqf(ss * (1.f / 1024.f) + EPSF);
;           u16* h = P.hy + (long)row * 1024;
; #pragma unroll
;           for (int i = 0; i < 4; ++i) {
;             const int col = (i * 64 + lane) * 4;
	v_cvt_pk_bf16_f32 v157, v168, v169
	v_cvt_pk_bf16_f32 v158, v170, v171
	v_cvt_pk_bf16_f32 v159, v172, v173
	v_cvt_pk_bf16_f32 v160, v174, v175
	v_cvt_pk_bf16_f32 v161, v176, v177
	v_cvt_pk_bf16_f32 v162, v178, v179
	v_cvt_pk_bf16_f32 v163, v180, v181
	s_lshl_b32 vcc_lo, s19, 11
	s_add_u32 vcc_lo, vcc_lo, 0xc00000
	s_add_u32 s100, s16, vcc_lo
	s_addc_u32 s101, s17, 0
	global_store_dwordx2 v137, v[156:157], s[100:101] offset:0
	global_store_dwordx2 v137, v[158:159], s[100:101] offset:512
	global_store_dwordx2 v137, v[160:161], s[100:101] offset:1024
	global_store_dwordx2 v137, v[162:163], s[100:101] offset:1536
	v_mul_f32_e32 v138, v166, v166
	v_mul_f32_e32 v149, v167, v167
	v_mul_f32_e32 v150, v168, v168
	v_mul_f32_e32 v154, v169, v169
	v_fma_f32 v138, v170, v170, v138
	v_fma_f32 v149, v171, v171, v149
	v_fma_f32 v150, v172, v172, v150
	v_fma_f32 v154, v173, v173, v154
	v_fma_f32 v138, v174, v174, v138
	v_fma_f32 v149, v175, v175, v149
	v_fma_f32 v150, v176, v176, v150
	v_fma_f32 v154, v177, v177, v154
	v_fma_f32 v138, v178, v178, v138
	v_fma_f32 v149, v179, v179, v149
	v_fma_f32 v150, v180, v180, v150
	v_fma_f32 v154, v181, v181, v154
	v_add_f32_e32 v138, v138, v149
	v_add_f32_e32 v150, v150, v154
	v_add_f32_e32 v138, v138, v150
	s_nop 1
	v_add_f32_dpp v138, v138, v138 quad_perm:[1,0,3,2] row_mask:0xf bank_mask:0xf
	s_nop 1
	v_add_f32_dpp v138, v138, v138 quad_perm:[2,3,0,1] row_mask:0xf bank_mask:0xf
	s_nop 1
	v_add_f32_dpp v138, v138, v138 row_half_mirror row_mask:0xf bank_mask:0xf
	s_nop 1
	v_add_f32_dpp v138, v138, v138 row_mirror row_mask:0xf bank_mask:0xf
	v_mov_b32_e32 v139, v138
	s_nop 1
	v_permlane16_swap_b32_e32 v138, v139
	v_add_f32_e32 v138, v138, v139
	v_mov_b32_e32 v139, v138
	s_nop 1
	v_permlane32_swap_b32_e32 v138, v139
	v_add_f32_e32 v138, v138, v139
	v_mul_f32_e32 v138, 0x3a800000, v138
	v_add_f32_e32 v138, 0x358637bd, v138
	v_rsq_f32_e32 v140, v138
	s_nop 0
	v_mul_f32_e32 v120, v166, v140
	v_mul_f32_e32 v121, v167, v140
	v_mul_f32_e32 v122, v168, v140
	v_mul_f32_e32 v123, v169, v140
	v_mul_f32_e32 v124, v170, v140
	v_mul_f32_e32 v125, v171, v140
	v_mul_f32_e32 v126, v172, v140
	v_mul_f32_e32 v127, v173, v140
	v_mul_f32_e32 v128, v174, v140
	v_mul_f32_e32 v129, v175, v140
	v_mul_f32_e32 v130, v176, v140
	v_mul_f32_e32 v131, v177, v140
	v_mul_f32_e32 v132, v178, v140
	v_mul_f32_e32 v133, v179, v140
	v_mul_f32_e32 v134, v180, v140
	v_mul_f32_e32 v135, v181, v140
	v_fma_f32 v120, v120, v88, v104
	v_fma_f32 v121, v121, v89, v105
	v_fma_f32 v122, v122, v90, v106
	v_fma_f32 v123, v123, v91, v107
	v_fma_f32 v124, v124, v92, v108
	v_fma_f32 v125, v125, v93, v109
	v_fma_f32 v126, v126, v94, v110
	v_fma_f32 v127, v127, v95, v111
	v_fma_f32 v128, v128, v96, v112
	v_fma_f32 v129, v129, v97, v113
	v_fma_f32 v130, v130, v98, v114
	v_fma_f32 v131, v131, v99, v115
	v_fma_f32 v132, v132, v100, v116
	v_fma_f32 v133, v133, v101, v117
	v_fma_f32 v134, v134, v102, v118
	v_fma_f32 v135, v135, v103, v119
	v_cvt_pk_bf16_f32 v156, v120, v121
	v_cvt_pk_bf16_f32 v157, v122, v123
	v_cvt_pk_bf16_f32 v158, v124, v125
	v_cvt_pk_bf16_f32 v159, v126, v127
	v_cvt_pk_bf16_f32 v160, v128, v129
	v_cvt_pk_bf16_f32 v161, v130, v131
	v_cvt_pk_bf16_f32 v162, v132, v133
	v_cvt_pk_bf16_f32 v163, v134, v135
	s_lshl_b32 vcc_lo, s19, 11
	s_add_u32 vcc_lo, vcc_lo, 0xc00000
	s_add_u32 s100, s14, vcc_lo
	s_addc_u32 s101, s15, 0
	global_store_dwordx2 v137, v[156:157], s[100:101] offset:0
	global_store_dwordx2 v137, v[158:159], s[100:101] offset:512
	global_store_dwordx2 v137, v[160:161], s[100:101] offset:1024
	global_store_dwordx2 v137, v[162:163], s[100:101] offset:1536
	s_add_u32 s100, s20, 0xb000
	s_addc_u32 s101, s21, 0
	global_load_dwordx4 v[72:75], v136, s[100:101] offset:0
	global_load_dwordx4 v[76:79], v136, s[100:101] offset:1024
	global_load_dwordx4 v[80:83], v136, s[100:101] offset:2048
	global_load_dwordx4 v[84:87], v136, s[100:101] offset:3072
	s_load_dwordx2 s[98:99], s[4:5], 0x48
	s_waitcnt lgkmcnt(0)
	global_load_dwordx4 v[120:123], v136, s[98:99] offset:0
	global_load_dwordx4 v[124:127], v136, s[98:99] offset:1024
	global_load_dwordx4 v[128:131], v136, s[98:99] offset:2048
	global_load_dwordx4 v[132:135], v136, s[98:99] offset:3072
	s_add_u32 s100, s20, 0x24000
	s_addc_u32 s101, s21, 0
	global_load_dwordx4 v[104:107], v136, s[100:101] offset:0
	global_load_dwordx4 v[108:111], v136, s[100:101] offset:1024
	global_load_dwordx4 v[112:115], v136, s[100:101] offset:2048
	global_load_dwordx4 v[116:119], v136, s[100:101] offset:3072
	s_add_u32 s100, s100, 0x1000
	s_addc_u32 s101, s101, 0
	global_load_dwordx4 v[166:169], v136, s[100:101] offset:0
	global_load_dwordx4 v[170:173], v136, s[100:101] offset:1024
	global_load_dwordx4 v[174:177], v136, s[100:101] offset:2048
	global_load_dwordx4 v[178:181], v136, s[100:101] offset:3072
	s_load_dwordx2 s[98:99], s[4:5], 0x30
	s_waitcnt lgkmcnt(0)
	s_add_u32 s98, s98, 0x1000
	s_addc_u32 s99, s99, 0
	global_load_dwordx4 v[88:91], v136, s[98:99] offset:0
	global_load_dwordx4 v[92:95], v136, s[98:99] offset:1024
	global_load_dwordx4 v[96:99], v136, s[98:99] offset:2048
	global_load_dwordx4 v[100:103], v136, s[98:99] offset:3072
	s_waitcnt vmcnt(0)
; __device__ __forceinline__ void row_phase(const Params& P, int glayer, int layer, int xsrc, bool hasY, int gate_idx, const float* gpost,
;                           int xdst, bool doH, const float* gpre, int sh_idx, int nrows) {
;     ...
;     for (int u = 0; u < 4; ++u) {
;       const int R = rb + u * stride;
;       if (R < nrows) {
;         if (xsrc != 0 && R < N_X) {
;           const u16* xs_ = ((xsrc == 1) ? resA : P.zf) + (long)R * 1024;
; #pragma unroll
;           for (int i = 0; i < 4; ++i) {
;             const uint2 t2 = *reinterpret_cast<const uint2*>(xs_ + (i * 64 + lane) * 4);
;             xr[u][i].x = t2.x; xr[u][i].y = t2.y;
;           }
;         } else {
;           const float* xin_;
;           if (xsrc == 0) xin_ = R < N_X ? P.x + (long)R * 1024 : P.ctx + (long)(R - N_X) * 1024;
;           else           xin_ = P.xc + (long)(R - N_X) * 1024;
; #pragma unroll
;           for (int i = 0; i < 4; ++i) xr[u][i] = *reinterpret_cast<const uint4*>(xin_ + (i * 64 + lane) * 4);
;         }
;         if (hasY) {
;           const u16* y_ = P.hy + (long)R * 1024;
; #pragma unroll
;     ...
; #pragma unroll
;           for (int i = 0; i < 4; ++i) {
;             const int col = (i * 64 + lane) * 4;
;             const float4 gt = *reinterpret_cast<const float4*>(modg + gate_idx * 1024 + col);
;             const float4 gp = *reinterpret_cast<const float4*>(gpost + col);
;             xv[i].x += gt.x * (yv[i].x * rstd * gp.x); xv[i].y += gt.y * (yv[i].y * rstd * gp.y);
;             xv[i].z += gt.z * (yv[i].z * rstd * gp.z); xv[i].w += gt.w * (yv[i].w * rstd * gp.w);
;           }
;     ...
;           for (int i = 0; i < 4; ++i) {
;             const int col = (i * 64 + lane) * 4;
;             const float4 g = *reinterpret_cast<const float4*>(gpre + col);
;             const float4 sh = *reinterpret_cast<const float4*>(modp + sh_idx * 1024 + col);
;             const float4 sc = *reinterpret_cast<const float4*>(modp + (sh_idx + 1) * 1024 + col);
;             const unsigned h0 = f2bf(xv[i].x * rstd * g.x * (1.f + sc.x) + sh.x);
;             const unsigned h1 = f2bf(xv[i].y * rstd * g.y * (1.f + sc.y) + sh.y);
;             const unsigned h2 = f2bf(xv[i].z * rstd * g.z * (1.f + sc.z) + sh.z);
;             const unsigned h3 = f2bf(xv[i].w * rstd * g.w * (1.f + sc.w) + sh.w);
	v_mul_f32_e32 v72, v72, v120
	v_mul_f32_e32 v73, v73, v121
	v_mul_f32_e32 v74, v74, v122
	v_mul_f32_e32 v75, v75, v123
	v_mul_f32_e32 v76, v76, v124
	v_mul_f32_e32 v77, v77, v125
	v_mul_f32_e32 v78, v78, v126
	v_mul_f32_e32 v79, v79, v127
	v_mul_f32_e32 v80, v80, v128
	v_mul_f32_e32 v81, v81, v129
	v_mul_f32_e32 v82, v82, v130
	v_mul_f32_e32 v83, v83, v131
	v_mul_f32_e32 v84, v84, v132
	v_mul_f32_e32 v85, v85, v133
	v_mul_f32_e32 v86, v86, v134
	v_mul_f32_e32 v87, v87, v135
	v_fma_f32 v88, v88, v166, v88
	v_fma_f32 v89, v89, v167, v89
	v_fma_f32 v90, v90, v168, v90
	v_fma_f32 v91, v91, v169, v91
	v_fma_f32 v92, v92, v170, v92
	v_fma_f32 v93, v93, v171, v93
	v_fma_f32 v94, v94, v172, v94
	v_fma_f32 v95, v95, v173, v95
	v_fma_f32 v96, v96, v174, v96
	v_fma_f32 v97, v97, v175, v97
	v_fma_f32 v98, v98, v176, v98
	v_fma_f32 v99, v99, v177, v99
	v_fma_f32 v100, v100, v178, v100
	v_fma_f32 v101, v101, v179, v101
	v_fma_f32 v102, v102, v180, v102
	v_fma_f32 v103, v103, v181, v103
	s_lshl_b32 vcc_lo, s19, 11
	s_add_u32 vcc_lo, vcc_lo, 0x1c00000
	s_add_u32 s100, s12, vcc_lo
	s_addc_u32 s101, s13, 0
	global_load_dwordx2 v[174:175], v137, s[100:101] offset:0
	global_load_dwordx2 v[176:177], v137, s[100:101] offset:512
	global_load_dwordx2 v[178:179], v137, s[100:101] offset:1024
	global_load_dwordx2 v[180:181], v137, s[100:101] offset:1536
	s_lshl_b32 vcc_lo, s19, 11
	s_add_u32 vcc_lo, vcc_lo, 0x1c00000
	s_add_u32 s100, s14, vcc_lo
	s_addc_u32 s101, s15, 0
	global_load_dwordx2 v[182:183], v137, s[100:101] offset:0
	global_load_dwordx2 v[184:185], v137, s[100:101] offset:512
	global_load_dwordx2 v[186:187], v137, s[100:101] offset:1024
	global_load_dwordx2 v[188:189], v137, s[100:101] offset:1536
	v_lshlrev_b32_e32 v120, 16, v48
	v_and_b32_e32 v121, 0xffff0000, v48
	v_lshlrev_b32_e32 v122, 16, v49
	v_and_b32_e32 v123, 0xffff0000, v49
	v_lshlrev_b32_e32 v124, 16, v50
	v_and_b32_e32 v125, 0xffff0000, v50
	v_lshlrev_b32_e32 v126, 16, v51
	v_and_b32_e32 v127, 0xffff0000, v51
	v_lshlrev_b32_e32 v128, 16, v52
	v_and_b32_e32 v129, 0xffff0000, v52
	v_lshlrev_b32_e32 v130, 16, v53
	v_and_b32_e32 v131, 0xffff0000, v53
	v_lshlrev_b32_e32 v132, 16, v54
	v_and_b32_e32 v133, 0xffff0000, v54
	v_lshlrev_b32_e32 v134, 16, v55
	v_and_b32_e32 v135, 0xffff0000, v55
	v_mul_f32_e32 v138, v120, v120
	v_mul_f32_e32 v149, v121, v121
	v_mul_f32_e32 v150, v122, v122
	v_mul_f32_e32 v154, v123, v123
	v_fma_f32 v138, v124, v124, v138
	v_fma_f32 v149, v125, v125, v149
	v_fma_f32 v150, v126, v126, v150
	v_fma_f32 v154, v127, v127, v154
	v_fma_f32 v138, v128, v128, v138
	v_fma_f32 v149, v129, v129, v149
	v_fma_f32 v150, v130, v130, v150
	v_fma_f32 v154, v131, v131, v154
	v_fma_f32 v138, v132, v132, v138
	v_fma_f32 v149, v133, v133, v149
	v_fma_f32 v150, v134, v134, v150
	v_fma_f32 v154, v135, v135, v154
	v_add_f32_e32 v138, v138, v149
	v_add_f32_e32 v150, v150, v154
	v_add_f32_e32 v138, v138, v150
	s_nop 1
	v_add_f32_dpp v138, v138, v138 quad_perm:[1,0,3,2] row_mask:0xf bank_mask:0xf
	s_nop 1
	v_add_f32_dpp v138, v138, v138 quad_perm:[2,3,0,1] row_mask:0xf bank_mask:0xf
	s_nop 1
	v_add_f32_dpp v138, v138, v138 row_half_mirror row_mask:0xf bank_mask:0xf
	s_nop 1
	v_add_f32_dpp v138, v138, v138 row_mirror row_mask:0xf bank_mask:0xf
	v_mov_b32_e32 v139, v138
	s_nop 1
	v_permlane16_swap_b32_e32 v138, v139
	v_add_f32_e32 v138, v138, v139
	v_mov_b32_e32 v139, v138
	s_nop 1
	v_permlane32_swap_b32_e32 v138, v139
	v_add_f32_e32 v138, v138, v139
	v_mul_f32_e32 v138, 0x3a800000, v138
	v_add_f32_e32 v138, 0x358637bd, v138
	v_rsq_f32_e32 v140, v138
	v_lshlrev_b32_e32 v0, 16, v8
	v_and_b32_e32 v1, 0xffff0000, v8
	v_lshlrev_b32_e32 v2, 16, v9
	v_and_b32_e32 v3, 0xffff0000, v9
	v_lshlrev_b32_e32 v4, 16, v10
	v_and_b32_e32 v5, 0xffff0000, v10
	v_lshlrev_b32_e32 v6, 16, v11
	v_and_b32_e32 v7, 0xffff0000, v11
	v_lshlrev_b32_e32 v8, 16, v12
	v_and_b32_e32 v9, 0xffff0000, v12
	v_lshlrev_b32_e32 v10, 16, v13
	v_and_b32_e32 v11, 0xffff0000, v13
	v_lshlrev_b32_e32 v12, 16, v14
	v_and_b32_e32 v13, 0xffff0000, v14
	v_lshlrev_b32_e32 v14, 16, v15
	v_and_b32_e32 v15, 0xffff0000, v15
	s_nop 0
	v_mul_f32_e32 v120, v120, v140
	v_mul_f32_e32 v121, v121, v140
	v_mul_f32_e32 v122, v122, v140
	v_mul_f32_e32 v123, v123, v140
	v_mul_f32_e32 v124, v124, v140
	v_mul_f32_e32 v125, v125, v140
	v_mul_f32_e32 v126, v126, v140
	v_mul_f32_e32 v127, v127, v140
	v_mul_f32_e32 v128, v128, v140
	v_mul_f32_e32 v129, v129, v140
	v_mul_f32_e32 v130, v130, v140
	v_mul_f32_e32 v131, v131, v140
	v_mul_f32_e32 v132, v132, v140
	v_mul_f32_e32 v133, v133, v140
	v_mul_f32_e32 v134, v134, v140
	v_mul_f32_e32 v135, v135, v140
	v_fma_f32 v0, v120, v72, v0
	v_fma_f32 v1, v121, v73, v1
	v_fma_f32 v2, v122, v74, v2
	v_fma_f32 v3, v123, v75, v3
	v_fma_f32 v4, v124, v76, v4
	v_fma_f32 v5, v125, v77, v5
	v_fma_f32 v6, v126, v78, v6
	v_fma_f32 v7, v127, v79, v7
	v_fma_f32 v8, v128, v80, v8
	v_fma_f32 v9, v129, v81, v9
	v_fma_f32 v10, v130, v82, v10
	v_fma_f32 v11, v131, v83, v11
	v_fma_f32 v12, v132, v84, v12
	v_fma_f32 v13, v133, v85, v13
	v_fma_f32 v14, v134, v86, v14
	v_fma_f32 v15, v135, v87, v15
	v_cvt_pk_bf16_f32 v156, v0, v1
	v_cvt_pk_bf16_f32 v157, v2, v3
	v_cvt_pk_bf16_f32 v158, v4, v5
	v_cvt_pk_bf16_f32 v159, v6, v7
	v_cvt_pk_bf16_f32 v160, v8, v9
	v_cvt_pk_bf16_f32 v161, v10, v11
	v_cvt_pk_bf16_f32 v162, v12, v13
	v_cvt_pk_bf16_f32 v163, v14, v15
	s_lshl_b32 vcc_lo, s19, 11
	s_add_u32 vcc_lo, vcc_lo, 0x1000000
	s_add_u32 s100, s16, vcc_lo
	s_addc_u32 s101, s17, 0
	global_store_dwordx2 v137, v[156:157], s[100:101] offset:0
	global_store_dwordx2 v137, v[158:159], s[100:101] offset:512
	global_store_dwordx2 v137, v[160:161], s[100:101] offset:1024
; __device__ __forceinline__ void row_phase(const Params& P, int glayer, int layer, int xsrc, bool hasY, int gate_idx, const float* gpost,
;                           int xdst, bool doH, const float* gpre, int sh_idx, int nrows) {
;     ...
;     for (int u = 0; u < 4; ++u) {
;       const int R = rb + u * stride;
;       if (R < nrows) {
;         if (xsrc != 0 && R < N_X) {
;           const u16* xs_ = ((xsrc == 1) ? resA : P.zf) + (long)R * 1024;
; #pragma unroll
;           for (int i = 0; i < 4; ++i) {
;             const uint2 t2 = *reinterpret_cast<const uint2*>(xs_ + (i * 64 + lane) * 4);
;             xr[u][i].x = t2.x; xr[u][i].y = t2.y;
;           }
;         } else {
;           const float* xin_;
;           if (xsrc == 0) xin_ = R < N_X ? P.x + (long)R * 1024 : P.ctx + (long)(R - N_X) * 1024;
;           else           xin_ = P.xc + (long)(R - N_X) * 1024;
; #pragma unroll
;           for (int i = 0; i < 4; ++i) xr[u][i] = *reinterpret_cast<const uint4*>(xin_ + (i * 64 + lane) * 4);
;         }
;         if (hasY) {
;           const u16* y_ = P.hy + (long)R * 1024;
; #pragma unroll
;           for (int i = 0; i < 4; ++i) yy[u][i] = *reinterpret_cast<const uint2*>(y_ + (i * 64 + lane) * 4);
;         }
;     ...
;             const uint2 raw = yy[u][i];
;     ...
;           for (int i = 0; i < 4; ++i) ss += xv[i].x * xv[i].x + xv[i].y * xv[i].y + xv[i].z * xv[i].z + xv[i].w * xv[i].w;
;           ss = wave_sum(ss);
;           const float rstd = __builtin_amdgcn_rsqf(ss * (1.f / 1024.f) + EPSF);
;           u16* h = P.hy + (long)row * 1024;
; #pragma unroll
;           for (int i = 0; i < 4; ++i) {
;             const int col = (i * 64 + lane) * 4;
;             const float4 g = *reinterpret_cast<const float4*>(gpre + col);
;             const float4 sh = *reinterpret_cast<const float4*>(modp + sh_idx * 1024 + col);
;             const float4 sc = *reinterpret_cast<const float4*>(modp + (sh_idx + 1) * 1024 + col);
;             const unsigned h0 = f2bf(xv[i].x * rstd * g.x * (1.f + sc.x) + sh.x);
;             const unsigned h1 = f2bf(xv[i].y * rstd * g.y * (1.f + sc.y) + sh.y);
;             const unsigned h2 = f2bf(xv[i].z * rstd * g.z * (1.f + sc.z) + sh.z);
;             const unsigned h3 = f2bf(xv[i].w * rstd * g.w * (1.f + sc.w) + sh.w);
;             *reinterpret_cast<uint2*>(h + col) = make_uint2(h0 | (h1 << 16), h2 | (h3 << 16));
;           }
	global_store_dwordx2 v137, v[162:163], s[100:101] offset:1536
	v_mul_f32_e32 v138, v0, v0
	v_mul_f32_e32 v149, v1, v1
	v_mul_f32_e32 v150, v2, v2
	v_mul_f32_e32 v154, v3, v3
	v_fma_f32 v138, v4, v4, v138
	v_fma_f32 v149, v5, v5, v149
	v_fma_f32 v150, v6, v6, v150
	v_fma_f32 v154, v7, v7, v154
	v_fma_f32 v138, v8, v8, v138
	v_fma_f32 v149, v9, v9, v149
	v_fma_f32 v150, v10, v10, v150
	v_fma_f32 v154, v11, v11, v154
	v_fma_f32 v138, v12, v12, v138
	v_fma_f32 v149, v13, v13, v149
	v_fma_f32 v150, v14, v14, v150
	v_fma_f32 v154, v15, v15, v154
	v_add_f32_e32 v138, v138, v149
	v_add_f32_e32 v150, v150, v154
	v_add_f32_e32 v138, v138, v150
	s_nop 1
	v_add_f32_dpp v138, v138, v138 quad_perm:[1,0,3,2] row_mask:0xf bank_mask:0xf
	s_nop 1
	v_add_f32_dpp v138, v138, v138 quad_perm:[2,3,0,1] row_mask:0xf bank_mask:0xf
	s_nop 1
	v_add_f32_dpp v138, v138, v138 row_half_mirror row_mask:0xf bank_mask:0xf
	s_nop 1
	v_add_f32_dpp v138, v138, v138 row_mirror row_mask:0xf bank_mask:0xf
	v_mov_b32_e32 v139, v138
	s_nop 1
	v_permlane16_swap_b32_e32 v138, v139
	v_add_f32_e32 v138, v138, v139
	v_mov_b32_e32 v139, v138
	s_nop 1
	v_permlane32_swap_b32_e32 v138, v139
	v_add_f32_e32 v138, v138, v139
	v_mul_f32_e32 v138, 0x3a800000, v138
	v_add_f32_e32 v138, 0x358637bd, v138
	v_rsq_f32_e32 v140, v138
	s_nop 0
	v_mul_f32_e32 v120, v0, v140
	v_mul_f32_e32 v121, v1, v140
	v_mul_f32_e32 v122, v2, v140
	v_mul_f32_e32 v123, v3, v140
	v_mul_f32_e32 v124, v4, v140
	v_mul_f32_e32 v125, v5, v140
	v_mul_f32_e32 v126, v6, v140
	v_mul_f32_e32 v127, v7, v140
	v_mul_f32_e32 v128, v8, v140
	v_mul_f32_e32 v129, v9, v140
	v_mul_f32_e32 v130, v10, v140
	v_mul_f32_e32 v131, v11, v140
	v_mul_f32_e32 v132, v12, v140
	v_mul_f32_e32 v133, v13, v140
	v_mul_f32_e32 v134, v14, v140
	v_mul_f32_e32 v135, v15, v140
	v_fma_f32 v120, v120, v88, v104
	v_fma_f32 v121, v121, v89, v105
	v_fma_f32 v122, v122, v90, v106
	v_fma_f32 v123, v123, v91, v107
	v_fma_f32 v124, v124, v92, v108
	v_fma_f32 v125, v125, v93, v109
	v_fma_f32 v126, v126, v94, v110
	v_fma_f32 v127, v127, v95, v111
	v_fma_f32 v128, v128, v96, v112
	v_fma_f32 v129, v129, v97, v113
	v_fma_f32 v130, v130, v98, v114
	v_fma_f32 v131, v131, v99, v115
	v_fma_f32 v132, v132, v100, v116
	v_fma_f32 v133, v133, v101, v117
	v_fma_f32 v134, v134, v102, v118
	v_fma_f32 v135, v135, v103, v119
	v_cvt_pk_bf16_f32 v156, v120, v121
	v_cvt_pk_bf16_f32 v157, v122, v123
	v_cvt_pk_bf16_f32 v158, v124, v125
	v_cvt_pk_bf16_f32 v159, v126, v127
	v_cvt_pk_bf16_f32 v160, v128, v129
	v_cvt_pk_bf16_f32 v161, v130, v131
	v_cvt_pk_bf16_f32 v162, v132, v133
	v_cvt_pk_bf16_f32 v163, v134, v135
	s_lshl_b32 vcc_lo, s19, 11
	s_add_u32 vcc_lo, vcc_lo, 0x1000000
	s_add_u32 s100, s14, vcc_lo
	s_addc_u32 s101, s15, 0
	global_store_dwordx2 v137, v[156:157], s[100:101] offset:0
	global_store_dwordx2 v137, v[158:159], s[100:101] offset:512
	global_store_dwordx2 v137, v[160:161], s[100:101] offset:1024
	global_store_dwordx2 v137, v[162:163], s[100:101] offset:1536
	s_lshl_b32 vcc_lo, s19, 11
	s_add_u32 vcc_lo, vcc_lo, 0x2000000
	s_add_u32 s100, s12, vcc_lo
	s_addc_u32 s101, s13, 0
	global_load_dwordx2 v[8:9], v137, s[100:101] offset:0
	global_load_dwordx2 v[10:11], v137, s[100:101] offset:512
	global_load_dwordx2 v[12:13], v137, s[100:101] offset:1024
	global_load_dwordx2 v[14:15], v137, s[100:101] offset:1536
	s_lshl_b32 vcc_lo, s19, 11
	s_add_u32 vcc_lo, vcc_lo, 0x2000000
	s_add_u32 s100, s14, vcc_lo
	s_addc_u32 s101, s15, 0
	global_load_dwordx2 v[48:49], v137, s[100:101] offset:0
	global_load_dwordx2 v[50:51], v137, s[100:101] offset:512
	global_load_dwordx2 v[52:53], v137, s[100:101] offset:1024
	global_load_dwordx2 v[54:55], v137, s[100:101] offset:1536
	v_lshlrev_b32_e32 v120, 16, v56
	v_and_b32_e32 v121, 0xffff0000, v56
	v_lshlrev_b32_e32 v122, 16, v57
	v_and_b32_e32 v123, 0xffff0000, v57
	v_lshlrev_b32_e32 v124, 16, v58
	v_and_b32_e32 v125, 0xffff0000, v58
	v_lshlrev_b32_e32 v126, 16, v59
	v_and_b32_e32 v127, 0xffff0000, v59
	v_lshlrev_b32_e32 v128, 16, v60
	v_and_b32_e32 v129, 0xffff0000, v60
	v_lshlrev_b32_e32 v130, 16, v61
	v_and_b32_e32 v131, 0xffff0000, v61
	v_lshlrev_b32_e32 v132, 16, v62
	v_and_b32_e32 v133, 0xffff0000, v62
	v_lshlrev_b32_e32 v134, 16, v63
	v_and_b32_e32 v135, 0xffff0000, v63
	v_mul_f32_e32 v138, v120, v120
	v_mul_f32_e32 v149, v121, v121
	v_mul_f32_e32 v150, v122, v122
	v_mul_f32_e32 v154, v123, v123
	v_fma_f32 v138, v124, v124, v138
	v_fma_f32 v149, v125, v125, v149
	v_fma_f32 v150, v126, v126, v150
	v_fma_f32 v154, v127, v127, v154
	v_fma_f32 v138, v128, v128, v138
	v_fma_f32 v149, v129, v129, v149
	v_fma_f32 v150, v130, v130, v150
	v_fma_f32 v154, v131, v131, v154
	v_fma_f32 v138, v132, v132, v138
	v_fma_f32 v149, v133, v133, v149
	v_fma_f32 v150, v134, v134, v150
	v_fma_f32 v154, v135, v135, v154
	v_add_f32_e32 v138, v138, v149
	v_add_f32_e32 v150, v150, v154
	v_add_f32_e32 v138, v138, v150
	s_nop 1
	v_add_f32_dpp v138, v138, v138 quad_perm:[1,0,3,2] row_mask:0xf bank_mask:0xf
	s_nop 1
	v_add_f32_dpp v138, v138, v138 quad_perm:[2,3,0,1] row_mask:0xf bank_mask:0xf
	s_nop 1
	v_add_f32_dpp v138, v138, v138 row_half_mirror row_mask:0xf bank_mask:0xf
	s_nop 1
	v_add_f32_dpp v138, v138, v138 row_mirror row_mask:0xf bank_mask:0xf
	v_mov_b32_e32 v139, v138
	s_nop 1
	v_permlane16_swap_b32_e32 v138, v139
	v_add_f32_e32 v138, v138, v139
	v_mov_b32_e32 v139, v138
	s_nop 1
	v_permlane32_swap_b32_e32 v138, v139
	v_add_f32_e32 v138, v138, v139
	v_mul_f32_e32 v138, 0x3a800000, v138
	v_add_f32_e32 v138, 0x358637bd, v138
	v_rsq_f32_e32 v140, v138
	v_lshlrev_b32_e32 v16, 16, v24
	v_and_b32_e32 v17, 0xffff0000, v24
	v_lshlrev_b32_e32 v18, 16, v25
; __device__ __forceinline__ void row_phase(const Params& P, int glayer, int layer, int xsrc, bool hasY, int gate_idx, const float* gpost,
;                           int xdst, bool doH, const float* gpre, int sh_idx, int nrows) {
;     ...
; #pragma unroll
;           for (int i = 0; i < 4; ++i) {
;             const int col = (i * 64 + lane) * 4;
;             const float4 gt = *reinterpret_cast<const float4*>(modg + gate_idx * 1024 + col);
;             const float4 gp = *reinterpret_cast<const float4*>(gpost + col);
;             xv[i].x += gt.x * (yv[i].x * rstd * gp.x); xv[i].y += gt.y * (yv[i].y * rstd * gp.y);
;             xv[i].z += gt.z * (yv[i].z * rstd * gp.z); xv[i].w += gt.w * (yv[i].w * rstd * gp.w);
;           }
;         }
;         if (xdst == 3 || (xdst == 1 && row >= N_X)) {
;           float* xout = (xdst == 3) ? P.out + (long)row * 1024 : P.xc + (long)(row - N_X) * 1024;
; #pragma unroll
;           for (int i = 0; i < 4; ++i) *reinterpret_cast<float4*>(xout + (i * 64 + lane) * 4) = xv[i];
;         } else if (xdst != 0) {
;           u16* xo = ((xdst == 1) ? resA : P.zf) + (long)row * 1024;
; #pragma unroll
;           for (int i = 0; i < 4; ++i) {
;             const unsigned b0 = f2bf(xv[i].x), b1 = f2bf(xv[i].y), b2 = f2bf(xv[i].z), b3 = f2bf(xv[i].w);
;             *reinterpret_cast<uint2*>(xo + (i * 64 + lane) * 4) = make_uint2(b0 | (b1 << 16), b2 | (b3 << 16));
;           }
;         }
;         if (doH) {
;           float ss = 0.f;
; #pragma unroll
;           for (int i = 0; i < 4; ++i) ss += xv[i].x * xv[i].x + xv[i].y * xv[i].y + xv[i].z * xv[i].z + xv[i].w * xv[i].w;
;           ss = wave_sum(ss);
;           const float rstd = __builtin_amdgcn_rsqf(ss * (1.f / 1024.f) + EPSF);
;           u16* h = P.hy + (long)row * 1024;
; #pragma unroll
;           for (int i = 0; i < 4; ++i) {
;             const int col = (i * 64 + lane) * 4;
;             const float4 g = *reinterpret_cast<const float4*>(gpre + col);
;             const float4 sh = *reinterpret_cast<const float4*>(modp + sh_idx * 1024 + col);
;             const float4 sc = *reinterpret_cast<const float4*>(modp + (sh_idx + 1) * 1024 + col);
;             const unsigned h0 = f2bf(xv[i].x * rstd * g.x * (1.f + sc.x) + sh.x);
;             const unsigned h1 = f2bf(xv[i].y * rstd * g.y * (1.f + sc.y) + sh.y);
	v_and_b32_e32 v19, 0xffff0000, v25
	v_lshlrev_b32_e32 v20, 16, v26
	v_and_b32_e32 v21, 0xffff0000, v26
	v_lshlrev_b32_e32 v22, 16, v27
	v_and_b32_e32 v23, 0xffff0000, v27
	v_lshlrev_b32_e32 v24, 16, v28
	v_and_b32_e32 v25, 0xffff0000, v28
	v_lshlrev_b32_e32 v26, 16, v29
	v_and_b32_e32 v27, 0xffff0000, v29
	v_lshlrev_b32_e32 v28, 16, v30
	v_and_b32_e32 v29, 0xffff0000, v30
	v_lshlrev_b32_e32 v30, 16, v31
	v_and_b32_e32 v31, 0xffff0000, v31
	s_nop 0
	v_mul_f32_e32 v120, v120, v140
	v_mul_f32_e32 v121, v121, v140
	v_mul_f32_e32 v122, v122, v140
	v_mul_f32_e32 v123, v123, v140
	v_mul_f32_e32 v124, v124, v140
	v_mul_f32_e32 v125, v125, v140
	v_mul_f32_e32 v126, v126, v140
	v_mul_f32_e32 v127, v127, v140
	v_mul_f32_e32 v128, v128, v140
	v_mul_f32_e32 v129, v129, v140
	v_mul_f32_e32 v130, v130, v140
	v_mul_f32_e32 v131, v131, v140
	v_mul_f32_e32 v132, v132, v140
	v_mul_f32_e32 v133, v133, v140
	v_mul_f32_e32 v134, v134, v140
	v_mul_f32_e32 v135, v135, v140
	v_fma_f32 v16, v120, v72, v16
	v_fma_f32 v17, v121, v73, v17
	v_fma_f32 v18, v122, v74, v18
	v_fma_f32 v19, v123, v75, v19
	v_fma_f32 v20, v124, v76, v20
	v_fma_f32 v21, v125, v77, v21
	v_fma_f32 v22, v126, v78, v22
	v_fma_f32 v23, v127, v79, v23
	v_fma_f32 v24, v128, v80, v24
	v_fma_f32 v25, v129, v81, v25
	v_fma_f32 v26, v130, v82, v26
	v_fma_f32 v27, v131, v83, v27
	v_fma_f32 v28, v132, v84, v28
	v_fma_f32 v29, v133, v85, v29
	v_fma_f32 v30, v134, v86, v30
	v_fma_f32 v31, v135, v87, v31
	v_cvt_pk_bf16_f32 v156, v16, v17
	v_cvt_pk_bf16_f32 v157, v18, v19
	v_cvt_pk_bf16_f32 v158, v20, v21
	v_cvt_pk_bf16_f32 v159, v22, v23
	v_cvt_pk_bf16_f32 v160, v24, v25
	v_cvt_pk_bf16_f32 v161, v26, v27
	v_cvt_pk_bf16_f32 v162, v28, v29
	v_cvt_pk_bf16_f32 v163, v30, v31
	s_lshl_b32 vcc_lo, s19, 11
	s_add_u32 vcc_lo, vcc_lo, 0x1400000
	s_add_u32 s100, s16, vcc_lo
	s_addc_u32 s101, s17, 0
	global_store_dwordx2 v137, v[156:157], s[100:101] offset:0
	global_store_dwordx2 v137, v[158:159], s[100:101] offset:512
	global_store_dwordx2 v137, v[160:161], s[100:101] offset:1024
	global_store_dwordx2 v137, v[162:163], s[100:101] offset:1536
	v_mul_f32_e32 v138, v16, v16
	v_mul_f32_e32 v149, v17, v17
	v_mul_f32_e32 v150, v18, v18
	v_mul_f32_e32 v154, v19, v19
	v_fma_f32 v138, v20, v20, v138
	v_fma_f32 v149, v21, v21, v149
	v_fma_f32 v150, v22, v22, v150
	v_fma_f32 v154, v23, v23, v154
	v_fma_f32 v138, v24, v24, v138
	v_fma_f32 v149, v25, v25, v149
	v_fma_f32 v150, v26, v26, v150
	v_fma_f32 v154, v27, v27, v154
	v_fma_f32 v138, v28, v28, v138
	v_fma_f32 v149, v29, v29, v149
	v_fma_f32 v150, v30, v30, v150
	v_fma_f32 v154, v31, v31, v154
	v_add_f32_e32 v138, v138, v149
	v_add_f32_e32 v150, v150, v154
	v_add_f32_e32 v138, v138, v150
	s_nop 1
	v_add_f32_dpp v138, v138, v138 quad_perm:[1,0,3,2] row_mask:0xf bank_mask:0xf
	s_nop 1
	v_add_f32_dpp v138, v138, v138 quad_perm:[2,3,0,1] row_mask:0xf bank_mask:0xf
	s_nop 1
	v_add_f32_dpp v138, v138, v138 row_half_mirror row_mask:0xf bank_mask:0xf
	s_nop 1
	v_add_f32_dpp v138, v138, v138 row_mirror row_mask:0xf bank_mask:0xf
	v_mov_b32_e32 v139, v138
	s_nop 1
	v_permlane16_swap_b32_e32 v138, v139
	v_add_f32_e32 v138, v138, v139
	v_mov_b32_e32 v139, v138
	s_nop 1
	v_permlane32_swap_b32_e32 v138, v139
	v_add_f32_e32 v138, v138, v139
	v_mul_f32_e32 v138, 0x3a800000, v138
	v_add_f32_e32 v138, 0x358637bd, v138
	v_rsq_f32_e32 v140, v138
	s_nop 0
	v_mul_f32_e32 v120, v16, v140
	v_mul_f32_e32 v121, v17, v140
	v_mul_f32_e32 v122, v18, v140
	v_mul_f32_e32 v123, v19, v140
	v_mul_f32_e32 v124, v20, v140
	v_mul_f32_e32 v125, v21, v140
	v_mul_f32_e32 v126, v22, v140
	v_mul_f32_e32 v127, v23, v140
	v_mul_f32_e32 v128, v24, v140
	v_mul_f32_e32 v129, v25, v140
	v_mul_f32_e32 v130, v26, v140
	v_mul_f32_e32 v131, v27, v140
	v_mul_f32_e32 v132, v28, v140
	v_mul_f32_e32 v133, v29, v140
	v_mul_f32_e32 v134, v30, v140
	v_mul_f32_e32 v135, v31, v140
	v_fma_f32 v120, v120, v88, v104
	v_fma_f32 v121, v121, v89, v105
	v_fma_f32 v122, v122, v90, v106
	v_fma_f32 v123, v123, v91, v107
	v_fma_f32 v124, v124, v92, v108
	v_fma_f32 v125, v125, v93, v109
	v_fma_f32 v126, v126, v94, v110
	v_fma_f32 v127, v127, v95, v111
	v_fma_f32 v128, v128, v96, v112
	v_fma_f32 v129, v129, v97, v113
	v_fma_f32 v130, v130, v98, v114
	v_fma_f32 v131, v131, v99, v115
	v_fma_f32 v132, v132, v100, v116
	v_fma_f32 v133, v133, v101, v117
	v_fma_f32 v134, v134, v102, v118
	v_fma_f32 v135, v135, v103, v119
	v_cvt_pk_bf16_f32 v156, v120, v121
	v_cvt_pk_bf16_f32 v157, v122, v123
	v_cvt_pk_bf16_f32 v158, v124, v125
	v_cvt_pk_bf16_f32 v159, v126, v127
	v_cvt_pk_bf16_f32 v160, v128, v129
	v_cvt_pk_bf16_f32 v161, v130, v131
	v_cvt_pk_bf16_f32 v162, v132, v133
	v_cvt_pk_bf16_f32 v163, v134, v135
	s_lshl_b32 vcc_lo, s19, 11
	s_add_u32 vcc_lo, vcc_lo, 0x1400000
	s_add_u32 s100, s14, vcc_lo
	s_addc_u32 s101, s15, 0
	global_store_dwordx2 v137, v[156:157], s[100:101] offset:0
	global_store_dwordx2 v137, v[158:159], s[100:101] offset:512
	global_store_dwordx2 v137, v[160:161], s[100:101] offset:1024
	global_store_dwordx2 v137, v[162:163], s[100:101] offset:1536
	s_lshl_b32 vcc_lo, s19, 11
	s_add_u32 vcc_lo, vcc_lo, 0x2400000
	s_add_u32 s100, s12, vcc_lo
	s_addc_u32 s101, s13, 0
	global_load_dwordx2 v[24:25], v137, s[100:101] offset:0
	global_load_dwordx2 v[26:27], v137, s[100:101] offset:512
	global_load_dwordx2 v[28:29], v137, s[100:101] offset:1024
	global_load_dwordx2 v[30:31], v137, s[100:101] offset:1536
	s_lshl_b32 vcc_lo, s19, 11
	s_add_u32 vcc_lo, vcc_lo, 0x2400000
	s_add_u32 s100, s14, vcc_lo
	s_addc_u32 s101, s15, 0
	global_load_dwordx2 v[56:57], v137, s[100:101] offset:0
	global_load_dwordx2 v[58:59], v137, s[100:101] offset:512
; __device__ __forceinline__ float bf2f(u16 h) { return __uint_as_float(((unsigned)h) << 16); }
; __device__ __forceinline__ void row_phase(const Params& P, int glayer, int layer, int xsrc, bool hasY, int gate_idx, const float* gpost,
;                           int xdst, bool doH, const float* gpre, int sh_idx, int nrows) {
;     ...
;             const uint2 raw = yy[u][i];
;             yv[i].x = bf2f((u16)(raw.x & 0xffff)); yv[i].y = bf2f((u16)(raw.x >> 16));
;             yv[i].z = bf2f((u16)(raw.y & 0xffff)); yv[i].w = bf2f((u16)(raw.y >> 16));
;             ss += yv[i].x * yv[i].x + yv[i].y * yv[i].y + yv[i].z * yv[i].z + yv[i].w * yv[i].w;
;           }
;           ss = wave_sum(ss);
;           const float rstd = __builtin_amdgcn_rsqf(ss * (1.f / 1024.f) + EPSF);
; #pragma unroll
;           for (int i = 0; i < 4; ++i) {
;             const int col = (i * 64 + lane) * 4;
;             const float4 gt = *reinterpret_cast<const float4*>(modg + gate_idx * 1024 + col);
;             const float4 gp = *reinterpret_cast<const float4*>(gpost + col);
;             xv[i].x += gt.x * (yv[i].x * rstd * gp.x); xv[i].y += gt.y * (yv[i].y * rstd * gp.y);
;             xv[i].z += gt.z * (yv[i].z * rstd * gp.z); xv[i].w += gt.w * (yv[i].w * rstd * gp.w);
;           }
;         }
;         if (xdst == 3 || (xdst == 1 && row >= N_X)) {
;           float* xout = (xdst == 3) ? P.out + (long)row * 1024 : P.xc + (long)(row - N_X) * 1024;
; #pragma unroll
;           for (int i = 0; i < 4; ++i) *reinterpret_cast<float4*>(xout + (i * 64 + lane) * 4) = xv[i];
;         } else if (xdst != 0) {
;           u16* xo = ((xdst == 1) ? resA : P.zf) + (long)row * 1024;
; #pragma unroll
;           for (int i = 0; i < 4; ++i) {
;             const unsigned b0 = f2bf(xv[i].x), b1 = f2bf(xv[i].y), b2 = f2bf(xv[i].z), b3 = f2bf(xv[i].w);
;             *reinterpret_cast<uint2*>(xo + (i * 64 + lane) * 4) = make_uint2(b0 | (b1 << 16), b2 | (b3 << 16));
;           }
;         }
;         if (doH) {
;           float ss = 0.f;
; #pragma unroll
;           for (int i = 0; i < 4; ++i) ss += xv[i].x * xv[i].x + xv[i].y * xv[i].y + xv[i].z * xv[i].z + xv[i].w * xv[i].w;
;           ss = wave_sum(ss);
;           const float rstd = __builtin_amdgcn_rsqf(ss * (1.f / 1024.f) + EPSF);
	global_load_dwordx2 v[60:61], v137, s[100:101] offset:1024
	global_load_dwordx2 v[62:63], v137, s[100:101] offset:1536
	v_lshlrev_b32_e32 v120, 16, v64
	v_and_b32_e32 v121, 0xffff0000, v64
	v_lshlrev_b32_e32 v122, 16, v65
	v_and_b32_e32 v123, 0xffff0000, v65
	v_lshlrev_b32_e32 v124, 16, v66
	v_and_b32_e32 v125, 0xffff0000, v66
	v_lshlrev_b32_e32 v126, 16, v67
	v_and_b32_e32 v127, 0xffff0000, v67
	v_lshlrev_b32_e32 v128, 16, v68
	v_and_b32_e32 v129, 0xffff0000, v68
	v_lshlrev_b32_e32 v130, 16, v69
	v_and_b32_e32 v131, 0xffff0000, v69
	v_lshlrev_b32_e32 v132, 16, v70
	v_and_b32_e32 v133, 0xffff0000, v70
	v_lshlrev_b32_e32 v134, 16, v71
	v_and_b32_e32 v135, 0xffff0000, v71
	v_mul_f32_e32 v138, v120, v120
	v_mul_f32_e32 v149, v121, v121
	v_mul_f32_e32 v150, v122, v122
	v_mul_f32_e32 v154, v123, v123
	v_fma_f32 v138, v124, v124, v138
	v_fma_f32 v149, v125, v125, v149
	v_fma_f32 v150, v126, v126, v150
	v_fma_f32 v154, v127, v127, v154
	v_fma_f32 v138, v128, v128, v138
	v_fma_f32 v149, v129, v129, v149
	v_fma_f32 v150, v130, v130, v150
	v_fma_f32 v154, v131, v131, v154
	v_fma_f32 v138, v132, v132, v138
	v_fma_f32 v149, v133, v133, v149
	v_fma_f32 v150, v134, v134, v150
	v_fma_f32 v154, v135, v135, v154
	v_add_f32_e32 v138, v138, v149
	v_add_f32_e32 v150, v150, v154
	v_add_f32_e32 v138, v138, v150
	s_nop 1
	v_add_f32_dpp v138, v138, v138 quad_perm:[1,0,3,2] row_mask:0xf bank_mask:0xf
	s_nop 1
	v_add_f32_dpp v138, v138, v138 quad_perm:[2,3,0,1] row_mask:0xf bank_mask:0xf
	s_nop 1
	v_add_f32_dpp v138, v138, v138 row_half_mirror row_mask:0xf bank_mask:0xf
	s_nop 1
	v_add_f32_dpp v138, v138, v138 row_mirror row_mask:0xf bank_mask:0xf
	v_mov_b32_e32 v139, v138
	s_nop 1
	v_permlane16_swap_b32_e32 v138, v139
	v_add_f32_e32 v138, v138, v139
	v_mov_b32_e32 v139, v138
	s_nop 1
	v_permlane32_swap_b32_e32 v138, v139
	v_add_f32_e32 v138, v138, v139
	v_mul_f32_e32 v138, 0x3a800000, v138
	v_add_f32_e32 v138, 0x358637bd, v138
	v_rsq_f32_e32 v140, v138
	v_lshlrev_b32_e32 v32, 16, v40
	v_and_b32_e32 v33, 0xffff0000, v40
	v_lshlrev_b32_e32 v34, 16, v41
	v_and_b32_e32 v35, 0xffff0000, v41
	v_lshlrev_b32_e32 v36, 16, v42
	v_and_b32_e32 v37, 0xffff0000, v42
	v_lshlrev_b32_e32 v38, 16, v43
	v_and_b32_e32 v39, 0xffff0000, v43
	v_lshlrev_b32_e32 v40, 16, v44
	v_and_b32_e32 v41, 0xffff0000, v44
	v_lshlrev_b32_e32 v42, 16, v45
	v_and_b32_e32 v43, 0xffff0000, v45
	v_lshlrev_b32_e32 v44, 16, v46
	v_and_b32_e32 v45, 0xffff0000, v46
	v_lshlrev_b32_e32 v46, 16, v47
	v_and_b32_e32 v47, 0xffff0000, v47
	s_nop 0
	v_mul_f32_e32 v120, v120, v140
	v_mul_f32_e32 v121, v121, v140
	v_mul_f32_e32 v122, v122, v140
	v_mul_f32_e32 v123, v123, v140
	v_mul_f32_e32 v124, v124, v140
	v_mul_f32_e32 v125, v125, v140
	v_mul_f32_e32 v126, v126, v140
	v_mul_f32_e32 v127, v127, v140
	v_mul_f32_e32 v128, v128, v140
	v_mul_f32_e32 v129, v129, v140
	v_mul_f32_e32 v130, v130, v140
	v_mul_f32_e32 v131, v131, v140
	v_mul_f32_e32 v132, v132, v140
	v_mul_f32_e32 v133, v133, v140
	v_mul_f32_e32 v134, v134, v140
	v_mul_f32_e32 v135, v135, v140
	v_fma_f32 v32, v120, v72, v32
	v_fma_f32 v33, v121, v73, v33
	v_fma_f32 v34, v122, v74, v34
	v_fma_f32 v35, v123, v75, v35
	v_fma_f32 v36, v124, v76, v36
	v_fma_f32 v37, v125, v77, v37
	v_fma_f32 v38, v126, v78, v38
	v_fma_f32 v39, v127, v79, v39
	v_fma_f32 v40, v128, v80, v40
	v_fma_f32 v41, v129, v81, v41
	v_fma_f32 v42, v130, v82, v42
	v_fma_f32 v43, v131, v83, v43
	v_fma_f32 v44, v132, v84, v44
	v_fma_f32 v45, v133, v85, v45
	v_fma_f32 v46, v134, v86, v46
	v_fma_f32 v47, v135, v87, v47
	v_cvt_pk_bf16_f32 v156, v32, v33
	v_cvt_pk_bf16_f32 v157, v34, v35
	v_cvt_pk_bf16_f32 v158, v36, v37
	v_cvt_pk_bf16_f32 v159, v38, v39
	v_cvt_pk_bf16_f32 v160, v40, v41
	v_cvt_pk_bf16_f32 v161, v42, v43
	v_cvt_pk_bf16_f32 v162, v44, v45
	v_cvt_pk_bf16_f32 v163, v46, v47
	s_lshl_b32 vcc_lo, s19, 11
	s_add_u32 vcc_lo, vcc_lo, 0x1800000
	s_add_u32 s100, s16, vcc_lo
	s_addc_u32 s101, s17, 0
	global_store_dwordx2 v137, v[156:157], s[100:101] offset:0
	global_store_dwordx2 v137, v[158:159], s[100:101] offset:512
	global_store_dwordx2 v137, v[160:161], s[100:101] offset:1024
	global_store_dwordx2 v137, v[162:163], s[100:101] offset:1536
	v_mul_f32_e32 v138, v32, v32
	v_mul_f32_e32 v149, v33, v33
	v_mul_f32_e32 v150, v34, v34
	v_mul_f32_e32 v154, v35, v35
	v_fma_f32 v138, v36, v36, v138
	v_fma_f32 v149, v37, v37, v149
	v_fma_f32 v150, v38, v38, v150
	v_fma_f32 v154, v39, v39, v154
	v_fma_f32 v138, v40, v40, v138
	v_fma_f32 v149, v41, v41, v149
	v_fma_f32 v150, v42, v42, v150
	v_fma_f32 v154, v43, v43, v154
	v_fma_f32 v138, v44, v44, v138
	v_fma_f32 v149, v45, v45, v149
	v_fma_f32 v150, v46, v46, v150
	v_fma_f32 v154, v47, v47, v154
	v_add_f32_e32 v138, v138, v149
	v_add_f32_e32 v150, v150, v154
	v_add_f32_e32 v138, v138, v150
	s_nop 1
	v_add_f32_dpp v138, v138, v138 quad_perm:[1,0,3,2] row_mask:0xf bank_mask:0xf
	s_nop 1
	v_add_f32_dpp v138, v138, v138 quad_perm:[2,3,0,1] row_mask:0xf bank_mask:0xf
	s_nop 1
	v_add_f32_dpp v138, v138, v138 row_half_mirror row_mask:0xf bank_mask:0xf
	s_nop 1
	v_add_f32_dpp v138, v138, v138 row_mirror row_mask:0xf bank_mask:0xf
	v_mov_b32_e32 v139, v138
	s_nop 1
	v_permlane16_swap_b32_e32 v138, v139
	v_add_f32_e32 v138, v138, v139
	v_mov_b32_e32 v139, v138
	s_nop 1
	v_permlane32_swap_b32_e32 v138, v139
	v_add_f32_e32 v138, v138, v139
	v_mul_f32_e32 v138, 0x3a800000, v138
	v_add_f32_e32 v138, 0x358637bd, v138
	v_rsq_f32_e32 v140, v138
	s_nop 0
	v_mul_f32_e32 v120, v32, v140
	v_mul_f32_e32 v121, v33, v140
	v_mul_f32_e32 v122, v34, v140
	v_mul_f32_e32 v123, v35, v140
	v_mul_f32_e32 v124, v36, v140
	v_mul_f32_e32 v125, v37, v140
	v_mul_f32_e32 v126, v38, v140
; __device__ __forceinline__ void row_phase(const Params& P, int glayer, int layer, int xsrc, bool hasY, int gate_idx, const float* gpost,
;                           int xdst, bool doH, const float* gpre, int sh_idx, int nrows) {
;     ...
;     for (int u = 0; u < 4; ++u) {
;       const int R = rb + u * stride;
;       if (R < nrows) {
;         if (xsrc != 0 && R < N_X) {
;           const u16* xs_ = ((xsrc == 1) ? resA : P.zf) + (long)R * 1024;
; #pragma unroll
;           for (int i = 0; i < 4; ++i) {
;             const uint2 t2 = *reinterpret_cast<const uint2*>(xs_ + (i * 64 + lane) * 4);
;             xr[u][i].x = t2.x; xr[u][i].y = t2.y;
;           }
;         } else {
;           const float* xin_;
;           if (xsrc == 0) xin_ = R < N_X ? P.x + (long)R * 1024 : P.ctx + (long)(R - N_X) * 1024;
;           else           xin_ = P.xc + (long)(R - N_X) * 1024;
; #pragma unroll
;           for (int i = 0; i < 4; ++i) xr[u][i] = *reinterpret_cast<const uint4*>(xin_ + (i * 64 + lane) * 4);
;         }
;         if (hasY) {
;           const u16* y_ = P.hy + (long)R * 1024;
; #pragma unroll
;           for (int i = 0; i < 4; ++i) yy[u][i] = *reinterpret_cast<const uint2*>(y_ + (i * 64 + lane) * 4);
;         }
;     ...
;             const uint2 raw = yy[u][i];
;             yv[i].x = bf2f((u16)(raw.x & 0xffff)); yv[i].y = bf2f((u16)(raw.x >> 16));
;     ...
;           const float rstd = __builtin_amdgcn_rsqf(ss * (1.f / 1024.f) + EPSF);
;           u16* h = P.hy + (long)row * 1024;
; #pragma unroll
;           for (int i = 0; i < 4; ++i) {
;             const int col = (i * 64 + lane) * 4;
;             const float4 g = *reinterpret_cast<const float4*>(gpre + col);
;             const float4 sh = *reinterpret_cast<const float4*>(modp + sh_idx * 1024 + col);
;             const float4 sc = *reinterpret_cast<const float4*>(modp + (sh_idx + 1) * 1024 + col);
;             const unsigned h0 = f2bf(xv[i].x * rstd * g.x * (1.f + sc.x) + sh.x);
;             const unsigned h1 = f2bf(xv[i].y * rstd * g.y * (1.f + sc.y) + sh.y);
;             const unsigned h2 = f2bf(xv[i].z * rstd * g.z * (1.f + sc.z) + sh.z);
;             const unsigned h3 = f2bf(xv[i].w * rstd * g.w * (1.f + sc.w) + sh.w);
;             *reinterpret_cast<uint2*>(h + col) = make_uint2(h0 | (h1 << 16), h2 | (h3 << 16));
;           }
	v_mul_f32_e32 v127, v39, v140
	v_mul_f32_e32 v128, v40, v140
	v_mul_f32_e32 v129, v41, v140
	v_mul_f32_e32 v130, v42, v140
	v_mul_f32_e32 v131, v43, v140
	v_mul_f32_e32 v132, v44, v140
	v_mul_f32_e32 v133, v45, v140
	v_mul_f32_e32 v134, v46, v140
	v_mul_f32_e32 v135, v47, v140
	v_fma_f32 v120, v120, v88, v104
	v_fma_f32 v121, v121, v89, v105
	v_fma_f32 v122, v122, v90, v106
	v_fma_f32 v123, v123, v91, v107
	v_fma_f32 v124, v124, v92, v108
	v_fma_f32 v125, v125, v93, v109
	v_fma_f32 v126, v126, v94, v110
	v_fma_f32 v127, v127, v95, v111
	v_fma_f32 v128, v128, v96, v112
	v_fma_f32 v129, v129, v97, v113
	v_fma_f32 v130, v130, v98, v114
	v_fma_f32 v131, v131, v99, v115
	v_fma_f32 v132, v132, v100, v116
	v_fma_f32 v133, v133, v101, v117
	v_fma_f32 v134, v134, v102, v118
	v_fma_f32 v135, v135, v103, v119
	v_cvt_pk_bf16_f32 v156, v120, v121
	v_cvt_pk_bf16_f32 v157, v122, v123
	v_cvt_pk_bf16_f32 v158, v124, v125
	v_cvt_pk_bf16_f32 v159, v126, v127
	v_cvt_pk_bf16_f32 v160, v128, v129
	v_cvt_pk_bf16_f32 v161, v130, v131
	v_cvt_pk_bf16_f32 v162, v132, v133
	v_cvt_pk_bf16_f32 v163, v134, v135
	s_lshl_b32 vcc_lo, s19, 11
	s_add_u32 vcc_lo, vcc_lo, 0x1800000
	s_add_u32 s100, s14, vcc_lo
	s_addc_u32 s101, s15, 0
	global_store_dwordx2 v137, v[156:157], s[100:101] offset:0
	global_store_dwordx2 v137, v[158:159], s[100:101] offset:512
	global_store_dwordx2 v137, v[160:161], s[100:101] offset:1024
	global_store_dwordx2 v137, v[162:163], s[100:101] offset:1536
	s_lshl_b32 vcc_lo, s19, 11
	s_add_u32 vcc_lo, vcc_lo, 0x2800000
	s_add_u32 s100, s12, vcc_lo
	s_addc_u32 s101, s13, 0
	global_load_dwordx2 v[40:41], v137, s[100:101] offset:0
	global_load_dwordx2 v[42:43], v137, s[100:101] offset:512
	global_load_dwordx2 v[44:45], v137, s[100:101] offset:1024
	global_load_dwordx2 v[46:47], v137, s[100:101] offset:1536
	s_lshl_b32 vcc_lo, s19, 11
	s_add_u32 vcc_lo, vcc_lo, 0x2800000
	s_add_u32 s100, s14, vcc_lo
	s_addc_u32 s101, s15, 0
	global_load_dwordx2 v[64:65], v137, s[100:101] offset:0
	global_load_dwordx2 v[66:67], v137, s[100:101] offset:512
	global_load_dwordx2 v[68:69], v137, s[100:101] offset:1024
	global_load_dwordx2 v[70:71], v137, s[100:101] offset:1536
	s_waitcnt vmcnt(48)
	v_lshlrev_b32_e32 v120, 16, v182
	v_and_b32_e32 v121, 0xffff0000, v182
	v_lshlrev_b32_e32 v122, 16, v183
	v_and_b32_e32 v123, 0xffff0000, v183
	v_lshlrev_b32_e32 v124, 16, v184
	v_and_b32_e32 v125, 0xffff0000, v184
	v_lshlrev_b32_e32 v126, 16, v185
	v_and_b32_e32 v127, 0xffff0000, v185
	v_lshlrev_b32_e32 v128, 16, v186
	v_and_b32_e32 v129, 0xffff0000, v186
	v_lshlrev_b32_e32 v130, 16, v187
	v_and_b32_e32 v131, 0xffff0000, v187
	v_lshlrev_b32_e32 v132, 16, v188
	v_and_b32_e32 v133, 0xffff0000, v188
	v_lshlrev_b32_e32 v134, 16, v189
	v_and_b32_e32 v135, 0xffff0000, v189
	v_mul_f32_e32 v138, v120, v120
	v_mul_f32_e32 v149, v121, v121
	v_mul_f32_e32 v150, v122, v122
	v_mul_f32_e32 v154, v123, v123
	v_fma_f32 v138, v124, v124, v138
	v_fma_f32 v149, v125, v125, v149
	v_fma_f32 v150, v126, v126, v150
	v_fma_f32 v154, v127, v127, v154
	v_fma_f32 v138, v128, v128, v138
	v_fma_f32 v149, v129, v129, v149
	v_fma_f32 v150, v130, v130, v150
	v_fma_f32 v154, v131, v131, v154
	v_fma_f32 v138, v132, v132, v138
	v_fma_f32 v149, v133, v133, v149
	v_fma_f32 v150, v134, v134, v150
	v_fma_f32 v154, v135, v135, v154
	v_add_f32_e32 v138, v138, v149
	v_add_f32_e32 v150, v150, v154
	v_add_f32_e32 v138, v138, v150
	s_nop 1
	v_add_f32_dpp v138, v138, v138 quad_perm:[1,0,3,2] row_mask:0xf bank_mask:0xf
	s_nop 1
	v_add_f32_dpp v138, v138, v138 quad_perm:[2,3,0,1] row_mask:0xf bank_mask:0xf
	s_nop 1
	v_add_f32_dpp v138, v138, v138 row_half_mirror row_mask:0xf bank_mask:0xf
	s_nop 1
	v_add_f32_dpp v138, v138, v138 row_mirror row_mask:0xf bank_mask:0xf
	v_mov_b32_e32 v139, v138
	s_nop 1
	v_permlane16_swap_b32_e32 v138, v139
	v_add_f32_e32 v138, v138, v139
	v_mov_b32_e32 v139, v138
	s_nop 1
	v_permlane32_swap_b32_e32 v138, v139
	v_add_f32_e32 v138, v138, v139
	v_mul_f32_e32 v138, 0x3a800000, v138
	v_add_f32_e32 v138, 0x358637bd, v138
	v_rsq_f32_e32 v140, v138
	v_lshlrev_b32_e32 v166, 16, v174
	v_and_b32_e32 v167, 0xffff0000, v174
	v_lshlrev_b32_e32 v168, 16, v175
	v_and_b32_e32 v169, 0xffff0000, v175
	v_lshlrev_b32_e32 v170, 16, v176
	v_and_b32_e32 v171, 0xffff0000, v176
	v_lshlrev_b32_e32 v172, 16, v177
	v_and_b32_e32 v173, 0xffff0000, v177
	v_lshlrev_b32_e32 v174, 16, v178
	v_and_b32_e32 v175, 0xffff0000, v178
	v_lshlrev_b32_e32 v176, 16, v179
	v_and_b32_e32 v177, 0xffff0000, v179
	v_lshlrev_b32_e32 v178, 16, v180
	v_and_b32_e32 v179, 0xffff0000, v180
	v_lshlrev_b32_e32 v180, 16, v181
	v_and_b32_e32 v181, 0xffff0000, v181
	s_nop 0
	v_mul_f32_e32 v120, v120, v140
	v_mul_f32_e32 v121, v121, v140
	v_mul_f32_e32 v122, v122, v140
	v_mul_f32_e32 v123, v123, v140
	v_mul_f32_e32 v124, v124, v140
	v_mul_f32_e32 v125, v125, v140
	v_mul_f32_e32 v126, v126, v140
	v_mul_f32_e32 v127, v127, v140
	v_mul_f32_e32 v128, v128, v140
	v_mul_f32_e32 v129, v129, v140
	v_mul_f32_e32 v130, v130, v140
	v_mul_f32_e32 v131, v131, v140
	v_mul_f32_e32 v132, v132, v140
	v_mul_f32_e32 v133, v133, v140
	v_mul_f32_e32 v134, v134, v140
	v_mul_f32_e32 v135, v135, v140
	v_fma_f32 v166, v120, v72, v166
	v_fma_f32 v167, v121, v73, v167
	v_fma_f32 v168, v122, v74, v168
	v_fma_f32 v169, v123, v75, v169
	v_fma_f32 v170, v124, v76, v170
	v_fma_f32 v171, v125, v77, v171
	v_fma_f32 v172, v126, v78, v172
	v_fma_f32 v173, v127, v79, v173
	v_fma_f32 v174, v128, v80, v174
	v_fma_f32 v175, v129, v81, v175
	v_fma_f32 v176, v130, v82, v176
	v_fma_f32 v177, v131, v83, v177
	v_fma_f32 v178, v132, v84, v178
	v_fma_f32 v179, v133, v85, v179
	v_fma_f32 v180, v134, v86, v180
; __device__ __forceinline__ void row_phase(const Params& P, int glayer, int layer, int xsrc, bool hasY, int gate_idx, const float* gpost,
;                           int xdst, bool doH, const float* gpre, int sh_idx, int nrows) {
;     ...
; #pragma unroll
;           for (int i = 0; i < 4; ++i) {
;             const int col = (i * 64 + lane) * 4;
;             const float4 gt = *reinterpret_cast<const float4*>(modg + gate_idx * 1024 + col);
;             const float4 gp = *reinterpret_cast<const float4*>(gpost + col);
;             xv[i].x += gt.x * (yv[i].x * rstd * gp.x); xv[i].y += gt.y * (yv[i].y * rstd * gp.y);
;             xv[i].z += gt.z * (yv[i].z * rstd * gp.z); xv[i].w += gt.w * (yv[i].w * rstd * gp.w);
;           }
;     ...
;           const float rstd = __builtin_amdgcn_rsqf(ss * (1.f / 1024.f) + EPSF);
;           u16* h = P.hy + (long)row * 1024;
; #pragma unroll
;           for (int i = 0; i < 4; ++i) {
;             const int col = (i * 64 + lane) * 4;
;             const float4 g = *reinterpret_cast<const float4*>(gpre + col);
;             const float4 sh = *reinterpret_cast<const float4*>(modp + sh_idx * 1024 + col);
;             const float4 sc = *reinterpret_cast<const float4*>(modp + (sh_idx + 1) * 1024 + col);
;             const unsigned h0 = f2bf(xv[i].x * rstd * g.x * (1.f + sc.x) + sh.x);
;             const unsigned h1 = f2bf(xv[i].y * rstd * g.y * (1.f + sc.y) + sh.y);
;             const unsigned h2 = f2bf(xv[i].z * rstd * g.z * (1.f + sc.z) + sh.z);
;             const unsigned h3 = f2bf(xv[i].w * rstd * g.w * (1.f + sc.w) + sh.w);
;             *reinterpret_cast<uint2*>(h + col) = make_uint2(h0 | (h1 << 16), h2 | (h3 << 16));
;           }
	v_fma_f32 v181, v135, v87, v181
	v_cvt_pk_bf16_f32 v156, v166, v167
	v_cvt_pk_bf16_f32 v157, v168, v169
	v_cvt_pk_bf16_f32 v158, v170, v171
	v_cvt_pk_bf16_f32 v159, v172, v173
	v_cvt_pk_bf16_f32 v160, v174, v175
	v_cvt_pk_bf16_f32 v161, v176, v177
	v_cvt_pk_bf16_f32 v162, v178, v179
	v_cvt_pk_bf16_f32 v163, v180, v181
	s_lshl_b32 vcc_lo, s19, 11
	s_add_u32 vcc_lo, vcc_lo, 0x1c00000
	s_add_u32 s100, s16, vcc_lo
	s_addc_u32 s101, s17, 0
	global_store_dwordx2 v137, v[156:157], s[100:101] offset:0
	global_store_dwordx2 v137, v[158:159], s[100:101] offset:512
	global_store_dwordx2 v137, v[160:161], s[100:101] offset:1024
	global_store_dwordx2 v137, v[162:163], s[100:101] offset:1536
	v_mul_f32_e32 v138, v166, v166
	v_mul_f32_e32 v149, v167, v167
	v_mul_f32_e32 v150, v168, v168
	v_mul_f32_e32 v154, v169, v169
	v_fma_f32 v138, v170, v170, v138
	v_fma_f32 v149, v171, v171, v149
	v_fma_f32 v150, v172, v172, v150
	v_fma_f32 v154, v173, v173, v154
	v_fma_f32 v138, v174, v174, v138
	v_fma_f32 v149, v175, v175, v149
	v_fma_f32 v150, v176, v176, v150
	v_fma_f32 v154, v177, v177, v154
	v_fma_f32 v138, v178, v178, v138
	v_fma_f32 v149, v179, v179, v149
	v_fma_f32 v150, v180, v180, v150
	v_fma_f32 v154, v181, v181, v154
	v_add_f32_e32 v138, v138, v149
	v_add_f32_e32 v150, v150, v154
	v_add_f32_e32 v138, v138, v150
	s_nop 1
	v_add_f32_dpp v138, v138, v138 quad_perm:[1,0,3,2] row_mask:0xf bank_mask:0xf
	s_nop 1
	v_add_f32_dpp v138, v138, v138 quad_perm:[2,3,0,1] row_mask:0xf bank_mask:0xf
	s_nop 1
	v_add_f32_dpp v138, v138, v138 row_half_mirror row_mask:0xf bank_mask:0xf
	s_nop 1
	v_add_f32_dpp v138, v138, v138 row_mirror row_mask:0xf bank_mask:0xf
	v_mov_b32_e32 v139, v138
	s_nop 1
	v_permlane16_swap_b32_e32 v138, v139
	v_add_f32_e32 v138, v138, v139
	v_mov_b32_e32 v139, v138
	s_nop 1
	v_permlane32_swap_b32_e32 v138, v139
	v_add_f32_e32 v138, v138, v139
	v_mul_f32_e32 v138, 0x3a800000, v138
	v_add_f32_e32 v138, 0x358637bd, v138
	v_rsq_f32_e32 v140, v138
	s_nop 0
	v_mul_f32_e32 v120, v166, v140
	v_mul_f32_e32 v121, v167, v140
	v_mul_f32_e32 v122, v168, v140
	v_mul_f32_e32 v123, v169, v140
	v_mul_f32_e32 v124, v170, v140
	v_mul_f32_e32 v125, v171, v140
	v_mul_f32_e32 v126, v172, v140
	v_mul_f32_e32 v127, v173, v140
	v_mul_f32_e32 v128, v174, v140
	v_mul_f32_e32 v129, v175, v140
	v_mul_f32_e32 v130, v176, v140
	v_mul_f32_e32 v131, v177, v140
	v_mul_f32_e32 v132, v178, v140
	v_mul_f32_e32 v133, v179, v140
	v_mul_f32_e32 v134, v180, v140
	v_mul_f32_e32 v135, v181, v140
	v_fma_f32 v120, v120, v88, v104
	v_fma_f32 v121, v121, v89, v105
	v_fma_f32 v122, v122, v90, v106
	v_fma_f32 v123, v123, v91, v107
	v_fma_f32 v124, v124, v92, v108
	v_fma_f32 v125, v125, v93, v109
	v_fma_f32 v126, v126, v94, v110
	v_fma_f32 v127, v127, v95, v111
	v_fma_f32 v128, v128, v96, v112
	v_fma_f32 v129, v129, v97, v113
	v_fma_f32 v130, v130, v98, v114
	v_fma_f32 v131, v131, v99, v115
	v_fma_f32 v132, v132, v100, v116
	v_fma_f32 v133, v133, v101, v117
	v_fma_f32 v134, v134, v102, v118
	v_fma_f32 v135, v135, v103, v119
	v_cvt_pk_bf16_f32 v156, v120, v121
	v_cvt_pk_bf16_f32 v157, v122, v123
	v_cvt_pk_bf16_f32 v158, v124, v125
	v_cvt_pk_bf16_f32 v159, v126, v127
	v_cvt_pk_bf16_f32 v160, v128, v129
	v_cvt_pk_bf16_f32 v161, v130, v131
	v_cvt_pk_bf16_f32 v162, v132, v133
	v_cvt_pk_bf16_f32 v163, v134, v135
	s_lshl_b32 vcc_lo, s19, 11
	s_add_u32 vcc_lo, vcc_lo, 0x1c00000
	s_add_u32 s100, s14, vcc_lo
	s_addc_u32 s101, s15, 0
	global_store_dwordx2 v137, v[156:157], s[100:101] offset:0
	global_store_dwordx2 v137, v[158:159], s[100:101] offset:512
	global_store_dwordx2 v137, v[160:161], s[100:101] offset:1024
	global_store_dwordx2 v137, v[162:163], s[100:101] offset:1536
	s_add_u32 s100, s20, 0x11000
	s_addc_u32 s101, s21, 0
	global_load_dwordx4 v[72:75], v136, s[100:101] offset:0
	global_load_dwordx4 v[76:79], v136, s[100:101] offset:1024
	global_load_dwordx4 v[80:83], v136, s[100:101] offset:2048
	global_load_dwordx4 v[84:87], v136, s[100:101] offset:3072
	s_load_dwordx2 s[98:99], s[4:5], 0x48
	s_waitcnt lgkmcnt(0)
	global_load_dwordx4 v[120:123], v136, s[98:99] offset:0
	global_load_dwordx4 v[124:127], v136, s[98:99] offset:1024
	global_load_dwordx4 v[128:131], v136, s[98:99] offset:2048
	global_load_dwordx4 v[132:135], v136, s[98:99] offset:3072
	s_add_u32 s100, s20, 0x2a000
	s_addc_u32 s101, s21, 0
	global_load_dwordx4 v[104:107], v136, s[100:101] offset:0
	global_load_dwordx4 v[108:111], v136, s[100:101] offset:1024
	global_load_dwordx4 v[112:115], v136, s[100:101] offset:2048
	global_load_dwordx4 v[116:119], v136, s[100:101] offset:3072
	s_add_u32 s100, s100, 0x1000
	s_addc_u32 s101, s101, 0
	global_load_dwordx4 v[166:169], v136, s[100:101] offset:0
	global_load_dwordx4 v[170:173], v136, s[100:101] offset:1024
	global_load_dwordx4 v[174:177], v136, s[100:101] offset:2048
	global_load_dwordx4 v[178:181], v136, s[100:101] offset:3072
	s_load_dwordx2 s[98:99], s[4:5], 0x30
	s_waitcnt lgkmcnt(0)
	s_add_u32 s98, s98, 0x1000
	s_addc_u32 s99, s99, 0
	global_load_dwordx4 v[88:91], v136, s[98:99] offset:0
	global_load_dwordx4 v[92:95], v136, s[98:99] offset:1024
	global_load_dwordx4 v[96:99], v136, s[98:99] offset:2048
	global_load_dwordx4 v[100:103], v136, s[98:99] offset:3072
	s_waitcnt vmcnt(0)
; __device__ __forceinline__ void row_phase(const Params& P, int glayer, int layer, int xsrc, bool hasY, int gate_idx, const float* gpost,
;                           int xdst, bool doH, const float* gpre, int sh_idx, int nrows) {
;     ...
;     for (int u = 0; u < 4; ++u) {
;       const int R = rb + u * stride;
;       if (R < nrows) {
;         if (xsrc != 0 && R < N_X) {
;           const u16* xs_ = ((xsrc == 1) ? resA : P.zf) + (long)R * 1024;
; #pragma unroll
;           for (int i = 0; i < 4; ++i) {
;             const uint2 t2 = *reinterpret_cast<const uint2*>(xs_ + (i * 64 + lane) * 4);
;             xr[u][i].x = t2.x; xr[u][i].y = t2.y;
;           }
;         } else {
;           const float* xin_;
;           if (xsrc == 0) xin_ = R < N_X ? P.x + (long)R * 1024 : P.ctx + (long)(R - N_X) * 1024;
;           else           xin_ = P.xc + (long)(R - N_X) * 1024;
; #pragma unroll
;           for (int i = 0; i < 4; ++i) xr[u][i] = *reinterpret_cast<const uint4*>(xin_ + (i * 64 + lane) * 4);
;         }
;         if (hasY) {
;           const u16* y_ = P.hy + (long)R * 1024;
; #pragma unroll
;     ...
; #pragma unroll
;           for (int i = 0; i < 4; ++i) {
;             const int col = (i * 64 + lane) * 4;
;             const float4 gt = *reinterpret_cast<const float4*>(modg + gate_idx * 1024 + col);
;             const float4 gp = *reinterpret_cast<const float4*>(gpost + col);
;             xv[i].x += gt.x * (yv[i].x * rstd * gp.x); xv[i].y += gt.y * (yv[i].y * rstd * gp.y);
;             xv[i].z += gt.z * (yv[i].z * rstd * gp.z); xv[i].w += gt.w * (yv[i].w * rstd * gp.w);
;           }
;     ...
;           for (int i = 0; i < 4; ++i) {
;             const int col = (i * 64 + lane) * 4;
;             const float4 g = *reinterpret_cast<const float4*>(gpre + col);
;             const float4 sh = *reinterpret_cast<const float4*>(modp + sh_idx * 1024 + col);
;             const float4 sc = *reinterpret_cast<const float4*>(modp + (sh_idx + 1) * 1024 + col);
;             const unsigned h0 = f2bf(xv[i].x * rstd * g.x * (1.f + sc.x) + sh.x);
;             const unsigned h1 = f2bf(xv[i].y * rstd * g.y * (1.f + sc.y) + sh.y);
;             const unsigned h2 = f2bf(xv[i].z * rstd * g.z * (1.f + sc.z) + sh.z);
;             const unsigned h3 = f2bf(xv[i].w * rstd * g.w * (1.f + sc.w) + sh.w);
	v_mul_f32_e32 v72, v72, v120
	v_mul_f32_e32 v73, v73, v121
	v_mul_f32_e32 v74, v74, v122
	v_mul_f32_e32 v75, v75, v123
	v_mul_f32_e32 v76, v76, v124
	v_mul_f32_e32 v77, v77, v125
	v_mul_f32_e32 v78, v78, v126
	v_mul_f32_e32 v79, v79, v127
	v_mul_f32_e32 v80, v80, v128
	v_mul_f32_e32 v81, v81, v129
	v_mul_f32_e32 v82, v82, v130
	v_mul_f32_e32 v83, v83, v131
	v_mul_f32_e32 v84, v84, v132
	v_mul_f32_e32 v85, v85, v133
	v_mul_f32_e32 v86, v86, v134
	v_mul_f32_e32 v87, v87, v135
	v_fma_f32 v88, v88, v166, v88
	v_fma_f32 v89, v89, v167, v89
	v_fma_f32 v90, v90, v168, v90
	v_fma_f32 v91, v91, v169, v91
	v_fma_f32 v92, v92, v170, v92
	v_fma_f32 v93, v93, v171, v93
	v_fma_f32 v94, v94, v172, v94
	v_fma_f32 v95, v95, v173, v95
	v_fma_f32 v96, v96, v174, v96
	v_fma_f32 v97, v97, v175, v97
	v_fma_f32 v98, v98, v176, v98
	v_fma_f32 v99, v99, v177, v99
	v_fma_f32 v100, v100, v178, v100
	v_fma_f32 v101, v101, v179, v101
	v_fma_f32 v102, v102, v180, v102
	v_fma_f32 v103, v103, v181, v103
	s_lshl_b32 vcc_lo, s19, 11
	s_add_u32 vcc_lo, vcc_lo, 0x2c00000
	s_add_u32 s100, s12, vcc_lo
	s_addc_u32 s101, s13, 0
	global_load_dwordx2 v[174:175], v137, s[100:101] offset:0
	global_load_dwordx2 v[176:177], v137, s[100:101] offset:512
	global_load_dwordx2 v[178:179], v137, s[100:101] offset:1024
	global_load_dwordx2 v[180:181], v137, s[100:101] offset:1536
	s_lshl_b32 vcc_lo, s19, 11
	s_add_u32 vcc_lo, vcc_lo, 0x2c00000
	s_add_u32 s100, s14, vcc_lo
	s_addc_u32 s101, s15, 0
	global_load_dwordx2 v[182:183], v137, s[100:101] offset:0
	global_load_dwordx2 v[184:185], v137, s[100:101] offset:512
	global_load_dwordx2 v[186:187], v137, s[100:101] offset:1024
	global_load_dwordx2 v[188:189], v137, s[100:101] offset:1536
	v_lshlrev_b32_e32 v120, 16, v48
	v_and_b32_e32 v121, 0xffff0000, v48
	v_lshlrev_b32_e32 v122, 16, v49
	v_and_b32_e32 v123, 0xffff0000, v49
	v_lshlrev_b32_e32 v124, 16, v50
	v_and_b32_e32 v125, 0xffff0000, v50
	v_lshlrev_b32_e32 v126, 16, v51
	v_and_b32_e32 v127, 0xffff0000, v51
	v_lshlrev_b32_e32 v128, 16, v52
	v_and_b32_e32 v129, 0xffff0000, v52
	v_lshlrev_b32_e32 v130, 16, v53
	v_and_b32_e32 v131, 0xffff0000, v53
	v_lshlrev_b32_e32 v132, 16, v54
	v_and_b32_e32 v133, 0xffff0000, v54
	v_lshlrev_b32_e32 v134, 16, v55
	v_and_b32_e32 v135, 0xffff0000, v55
	v_mul_f32_e32 v138, v120, v120
	v_mul_f32_e32 v149, v121, v121
	v_mul_f32_e32 v150, v122, v122
	v_mul_f32_e32 v154, v123, v123
	v_fma_f32 v138, v124, v124, v138
	v_fma_f32 v149, v125, v125, v149
	v_fma_f32 v150, v126, v126, v150
	v_fma_f32 v154, v127, v127, v154
	v_fma_f32 v138, v128, v128, v138
	v_fma_f32 v149, v129, v129, v149
	v_fma_f32 v150, v130, v130, v150
	v_fma_f32 v154, v131, v131, v154
	v_fma_f32 v138, v132, v132, v138
	v_fma_f32 v149, v133, v133, v149
	v_fma_f32 v150, v134, v134, v150
	v_fma_f32 v154, v135, v135, v154
	v_add_f32_e32 v138, v138, v149
	v_add_f32_e32 v150, v150, v154
	v_add_f32_e32 v138, v138, v150
	s_nop 1
	v_add_f32_dpp v138, v138, v138 quad_perm:[1,0,3,2] row_mask:0xf bank_mask:0xf
	s_nop 1
	v_add_f32_dpp v138, v138, v138 quad_perm:[2,3,0,1] row_mask:0xf bank_mask:0xf
	s_nop 1
	v_add_f32_dpp v138, v138, v138 row_half_mirror row_mask:0xf bank_mask:0xf
	s_nop 1
	v_add_f32_dpp v138, v138, v138 row_mirror row_mask:0xf bank_mask:0xf
	v_mov_b32_e32 v139, v138
	s_nop 1
	v_permlane16_swap_b32_e32 v138, v139
	v_add_f32_e32 v138, v138, v139
	v_mov_b32_e32 v139, v138
	s_nop 1
	v_permlane32_swap_b32_e32 v138, v139
	v_add_f32_e32 v138, v138, v139
	v_mul_f32_e32 v138, 0x3a800000, v138
	v_add_f32_e32 v138, 0x358637bd, v138
	v_rsq_f32_e32 v140, v138
	v_lshlrev_b32_e32 v0, 16, v8
	v_and_b32_e32 v1, 0xffff0000, v8
	v_lshlrev_b32_e32 v2, 16, v9
	v_and_b32_e32 v3, 0xffff0000, v9
	v_lshlrev_b32_e32 v4, 16, v10
	v_and_b32_e32 v5, 0xffff0000, v10
	v_lshlrev_b32_e32 v6, 16, v11
	v_and_b32_e32 v7, 0xffff0000, v11
	v_lshlrev_b32_e32 v8, 16, v12
	v_and_b32_e32 v9, 0xffff0000, v12
	v_lshlrev_b32_e32 v10, 16, v13
	v_and_b32_e32 v11, 0xffff0000, v13
	v_lshlrev_b32_e32 v12, 16, v14
	v_and_b32_e32 v13, 0xffff0000, v14
	v_lshlrev_b32_e32 v14, 16, v15
	v_and_b32_e32 v15, 0xffff0000, v15
	s_nop 0
	v_mul_f32_e32 v120, v120, v140
	v_mul_f32_e32 v121, v121, v140
	v_mul_f32_e32 v122, v122, v140
	v_mul_f32_e32 v123, v123, v140
	v_mul_f32_e32 v124, v124, v140
	v_mul_f32_e32 v125, v125, v140
	v_mul_f32_e32 v126, v126, v140
	v_mul_f32_e32 v127, v127, v140
	v_mul_f32_e32 v128, v128, v140
	v_mul_f32_e32 v129, v129, v140
	v_mul_f32_e32 v130, v130, v140
	v_mul_f32_e32 v131, v131, v140
	v_mul_f32_e32 v132, v132, v140
	v_mul_f32_e32 v133, v133, v140
	v_mul_f32_e32 v134, v134, v140
	v_mul_f32_e32 v135, v135, v140
	v_fma_f32 v0, v120, v72, v0
	v_fma_f32 v1, v121, v73, v1
	v_fma_f32 v2, v122, v74, v2
	v_fma_f32 v3, v123, v75, v3
	v_fma_f32 v4, v124, v76, v4
	v_fma_f32 v5, v125, v77, v5
	v_fma_f32 v6, v126, v78, v6
	v_fma_f32 v7, v127, v79, v7
	v_fma_f32 v8, v128, v80, v8
	v_fma_f32 v9, v129, v81, v9
	v_fma_f32 v10, v130, v82, v10
	v_fma_f32 v11, v131, v83, v11
	v_fma_f32 v12, v132, v84, v12
	v_fma_f32 v13, v133, v85, v13
	v_fma_f32 v14, v134, v86, v14
	v_fma_f32 v15, v135, v87, v15
	v_cvt_pk_bf16_f32 v156, v0, v1
	v_cvt_pk_bf16_f32 v157, v2, v3
	v_cvt_pk_bf16_f32 v158, v4, v5
	v_cvt_pk_bf16_f32 v159, v6, v7
	v_cvt_pk_bf16_f32 v160, v8, v9
	v_cvt_pk_bf16_f32 v161, v10, v11
	v_cvt_pk_bf16_f32 v162, v12, v13
	v_cvt_pk_bf16_f32 v163, v14, v15
	s_lshl_b32 vcc_lo, s19, 11
	s_add_u32 vcc_lo, vcc_lo, 0x2000000
	s_add_u32 s100, s16, vcc_lo
	s_addc_u32 s101, s17, 0
	global_store_dwordx2 v137, v[156:157], s[100:101] offset:0
	global_store_dwordx2 v137, v[158:159], s[100:101] offset:512
	global_store_dwordx2 v137, v[160:161], s[100:101] offset:1024
; __device__ __forceinline__ void row_phase(const Params& P, int glayer, int layer, int xsrc, bool hasY, int gate_idx, const float* gpost,
;                           int xdst, bool doH, const float* gpre, int sh_idx, int nrows) {
;     ...
;     for (int u = 0; u < 4; ++u) {
;       const int R = rb + u * stride;
;       if (R < nrows) {
;         if (xsrc != 0 && R < N_X) {
;           const u16* xs_ = ((xsrc == 1) ? resA : P.zf) + (long)R * 1024;
; #pragma unroll
;           for (int i = 0; i < 4; ++i) {
;             const uint2 t2 = *reinterpret_cast<const uint2*>(xs_ + (i * 64 + lane) * 4);
;             xr[u][i].x = t2.x; xr[u][i].y = t2.y;
;           }
;         } else {
;           const float* xin_;
;           if (xsrc == 0) xin_ = R < N_X ? P.x + (long)R * 1024 : P.ctx + (long)(R - N_X) * 1024;
;           else           xin_ = P.xc + (long)(R - N_X) * 1024;
; #pragma unroll
;           for (int i = 0; i < 4; ++i) xr[u][i] = *reinterpret_cast<const uint4*>(xin_ + (i * 64 + lane) * 4);
;         }
;         if (hasY) {
;           const u16* y_ = P.hy + (long)R * 1024;
; #pragma unroll
;           for (int i = 0; i < 4; ++i) yy[u][i] = *reinterpret_cast<const uint2*>(y_ + (i * 64 + lane) * 4);
;         }
;     ...
;             const uint2 raw = yy[u][i];
;     ...
;           for (int i = 0; i < 4; ++i) ss += xv[i].x * xv[i].x + xv[i].y * xv[i].y + xv[i].z * xv[i].z + xv[i].w * xv[i].w;
;           ss = wave_sum(ss);
;           const float rstd = __builtin_amdgcn_rsqf(ss * (1.f / 1024.f) + EPSF);
;           u16* h = P.hy + (long)row * 1024;
; #pragma unroll
;           for (int i = 0; i < 4; ++i) {
;             const int col = (i * 64 + lane) * 4;
;             const float4 g = *reinterpret_cast<const float4*>(gpre + col);
;             const float4 sh = *reinterpret_cast<const float4*>(modp + sh_idx * 1024 + col);
;             const float4 sc = *reinterpret_cast<const float4*>(modp + (sh_idx + 1) * 1024 + col);
;             const unsigned h0 = f2bf(xv[i].x * rstd * g.x * (1.f + sc.x) + sh.x);
;             const unsigned h1 = f2bf(xv[i].y * rstd * g.y * (1.f + sc.y) + sh.y);
;             const unsigned h2 = f2bf(xv[i].z * rstd * g.z * (1.f + sc.z) + sh.z);
;             const unsigned h3 = f2bf(xv[i].w * rstd * g.w * (1.f + sc.w) + sh.w);
;             *reinterpret_cast<uint2*>(h + col) = make_uint2(h0 | (h1 << 16), h2 | (h3 << 16));
;           }
	global_store_dwordx2 v137, v[162:163], s[100:101] offset:1536
	v_mul_f32_e32 v138, v0, v0
	v_mul_f32_e32 v149, v1, v1
	v_mul_f32_e32 v150, v2, v2
	v_mul_f32_e32 v154, v3, v3
	v_fma_f32 v138, v4, v4, v138
	v_fma_f32 v149, v5, v5, v149
	v_fma_f32 v150, v6, v6, v150
	v_fma_f32 v154, v7, v7, v154
	v_fma_f32 v138, v8, v8, v138
	v_fma_f32 v149, v9, v9, v149
	v_fma_f32 v150, v10, v10, v150
	v_fma_f32 v154, v11, v11, v154
	v_fma_f32 v138, v12, v12, v138
	v_fma_f32 v149, v13, v13, v149
	v_fma_f32 v150, v14, v14, v150
	v_fma_f32 v154, v15, v15, v154
	v_add_f32_e32 v138, v138, v149
	v_add_f32_e32 v150, v150, v154
	v_add_f32_e32 v138, v138, v150
	s_nop 1
	v_add_f32_dpp v138, v138, v138 quad_perm:[1,0,3,2] row_mask:0xf bank_mask:0xf
	s_nop 1
	v_add_f32_dpp v138, v138, v138 quad_perm:[2,3,0,1] row_mask:0xf bank_mask:0xf
	s_nop 1
	v_add_f32_dpp v138, v138, v138 row_half_mirror row_mask:0xf bank_mask:0xf
	s_nop 1
	v_add_f32_dpp v138, v138, v138 row_mirror row_mask:0xf bank_mask:0xf
	v_mov_b32_e32 v139, v138
	s_nop 1
	v_permlane16_swap_b32_e32 v138, v139
	v_add_f32_e32 v138, v138, v139
	v_mov_b32_e32 v139, v138
	s_nop 1
	v_permlane32_swap_b32_e32 v138, v139
	v_add_f32_e32 v138, v138, v139
	v_mul_f32_e32 v138, 0x3a800000, v138
	v_add_f32_e32 v138, 0x358637bd, v138
	v_rsq_f32_e32 v140, v138
	s_nop 0
	v_mul_f32_e32 v120, v0, v140
	v_mul_f32_e32 v121, v1, v140
	v_mul_f32_e32 v122, v2, v140
	v_mul_f32_e32 v123, v3, v140
	v_mul_f32_e32 v124, v4, v140
	v_mul_f32_e32 v125, v5, v140
	v_mul_f32_e32 v126, v6, v140
	v_mul_f32_e32 v127, v7, v140
	v_mul_f32_e32 v128, v8, v140
	v_mul_f32_e32 v129, v9, v140
	v_mul_f32_e32 v130, v10, v140
	v_mul_f32_e32 v131, v11, v140
	v_mul_f32_e32 v132, v12, v140
	v_mul_f32_e32 v133, v13, v140
	v_mul_f32_e32 v134, v14, v140
	v_mul_f32_e32 v135, v15, v140
	v_fma_f32 v120, v120, v88, v104
	v_fma_f32 v121, v121, v89, v105
	v_fma_f32 v122, v122, v90, v106
	v_fma_f32 v123, v123, v91, v107
	v_fma_f32 v124, v124, v92, v108
	v_fma_f32 v125, v125, v93, v109
	v_fma_f32 v126, v126, v94, v110
	v_fma_f32 v127, v127, v95, v111
	v_fma_f32 v128, v128, v96, v112
	v_fma_f32 v129, v129, v97, v113
	v_fma_f32 v130, v130, v98, v114
	v_fma_f32 v131, v131, v99, v115
	v_fma_f32 v132, v132, v100, v116
	v_fma_f32 v133, v133, v101, v117
	v_fma_f32 v134, v134, v102, v118
	v_fma_f32 v135, v135, v103, v119
	v_cvt_pk_bf16_f32 v156, v120, v121
	v_cvt_pk_bf16_f32 v157, v122, v123
	v_cvt_pk_bf16_f32 v158, v124, v125
	v_cvt_pk_bf16_f32 v159, v126, v127
	v_cvt_pk_bf16_f32 v160, v128, v129
	v_cvt_pk_bf16_f32 v161, v130, v131
	v_cvt_pk_bf16_f32 v162, v132, v133
	v_cvt_pk_bf16_f32 v163, v134, v135
	s_lshl_b32 vcc_lo, s19, 11
	s_add_u32 vcc_lo, vcc_lo, 0x2000000
	s_add_u32 s100, s14, vcc_lo
	s_addc_u32 s101, s15, 0
	global_store_dwordx2 v137, v[156:157], s[100:101] offset:0
	global_store_dwordx2 v137, v[158:159], s[100:101] offset:512
	global_store_dwordx2 v137, v[160:161], s[100:101] offset:1024
	global_store_dwordx2 v137, v[162:163], s[100:101] offset:1536
	s_lshl_b32 vcc_lo, s19, 11
	s_add_u32 vcc_lo, vcc_lo, 0x3000000
	s_add_u32 s100, s12, vcc_lo
	s_addc_u32 s101, s13, 0
	global_load_dwordx2 v[8:9], v137, s[100:101] offset:0
	global_load_dwordx2 v[10:11], v137, s[100:101] offset:512
	global_load_dwordx2 v[12:13], v137, s[100:101] offset:1024
	global_load_dwordx2 v[14:15], v137, s[100:101] offset:1536
	s_lshl_b32 vcc_lo, s19, 11
	s_add_u32 vcc_lo, vcc_lo, 0x3000000
	s_add_u32 s100, s14, vcc_lo
	s_addc_u32 s101, s15, 0
	global_load_dwordx2 v[48:49], v137, s[100:101] offset:0
	global_load_dwordx2 v[50:51], v137, s[100:101] offset:512
	global_load_dwordx2 v[52:53], v137, s[100:101] offset:1024
	global_load_dwordx2 v[54:55], v137, s[100:101] offset:1536
	v_lshlrev_b32_e32 v120, 16, v56
	v_and_b32_e32 v121, 0xffff0000, v56
	v_lshlrev_b32_e32 v122, 16, v57
	v_and_b32_e32 v123, 0xffff0000, v57
	v_lshlrev_b32_e32 v124, 16, v58
	v_and_b32_e32 v125, 0xffff0000, v58
	v_lshlrev_b32_e32 v126, 16, v59
	v_and_b32_e32 v127, 0xffff0000, v59
	v_lshlrev_b32_e32 v128, 16, v60
	v_and_b32_e32 v129, 0xffff0000, v60
	v_lshlrev_b32_e32 v130, 16, v61
	v_and_b32_e32 v131, 0xffff0000, v61
	v_lshlrev_b32_e32 v132, 16, v62
	v_and_b32_e32 v133, 0xffff0000, v62
	v_lshlrev_b32_e32 v134, 16, v63
	v_and_b32_e32 v135, 0xffff0000, v63
	v_mul_f32_e32 v138, v120, v120
	v_mul_f32_e32 v149, v121, v121
	v_mul_f32_e32 v150, v122, v122
	v_mul_f32_e32 v154, v123, v123
	v_fma_f32 v138, v124, v124, v138
	v_fma_f32 v149, v125, v125, v149
	v_fma_f32 v150, v126, v126, v150
	v_fma_f32 v154, v127, v127, v154
	v_fma_f32 v138, v128, v128, v138
	v_fma_f32 v149, v129, v129, v149
	v_fma_f32 v150, v130, v130, v150
	v_fma_f32 v154, v131, v131, v154
	v_fma_f32 v138, v132, v132, v138
	v_fma_f32 v149, v133, v133, v149
	v_fma_f32 v150, v134, v134, v150
	v_fma_f32 v154, v135, v135, v154
	v_add_f32_e32 v138, v138, v149
	v_add_f32_e32 v150, v150, v154
	v_add_f32_e32 v138, v138, v150
	s_nop 1
	v_add_f32_dpp v138, v138, v138 quad_perm:[1,0,3,2] row_mask:0xf bank_mask:0xf
	s_nop 1
	v_add_f32_dpp v138, v138, v138 quad_perm:[2,3,0,1] row_mask:0xf bank_mask:0xf
	s_nop 1
	v_add_f32_dpp v138, v138, v138 row_half_mirror row_mask:0xf bank_mask:0xf
	s_nop 1
	v_add_f32_dpp v138, v138, v138 row_mirror row_mask:0xf bank_mask:0xf
	v_mov_b32_e32 v139, v138
	s_nop 1
	v_permlane16_swap_b32_e32 v138, v139
	v_add_f32_e32 v138, v138, v139
	v_mov_b32_e32 v139, v138
	s_nop 1
	v_permlane32_swap_b32_e32 v138, v139
	v_add_f32_e32 v138, v138, v139
	v_mul_f32_e32 v138, 0x3a800000, v138
	v_add_f32_e32 v138, 0x358637bd, v138
	v_rsq_f32_e32 v140, v138
	v_lshlrev_b32_e32 v16, 16, v24
	v_and_b32_e32 v17, 0xffff0000, v24
	v_lshlrev_b32_e32 v18, 16, v25
; __device__ __forceinline__ void row_phase(const Params& P, int glayer, int layer, int xsrc, bool hasY, int gate_idx, const float* gpost,
;                           int xdst, bool doH, const float* gpre, int sh_idx, int nrows) {
;     ...
; #pragma unroll
;           for (int i = 0; i < 4; ++i) {
;             const int col = (i * 64 + lane) * 4;
;             const float4 gt = *reinterpret_cast<const float4*>(modg + gate_idx * 1024 + col);
;             const float4 gp = *reinterpret_cast<const float4*>(gpost + col);
;             xv[i].x += gt.x * (yv[i].x * rstd * gp.x); xv[i].y += gt.y * (yv[i].y * rstd * gp.y);
;             xv[i].z += gt.z * (yv[i].z * rstd * gp.z); xv[i].w += gt.w * (yv[i].w * rstd * gp.w);
;           }
;         }
;         if (xdst == 3 || (xdst == 1 && row >= N_X)) {
;           float* xout = (xdst == 3) ? P.out + (long)row * 1024 : P.xc + (long)(row - N_X) * 1024;
; #pragma unroll
;           for (int i = 0; i < 4; ++i) *reinterpret_cast<float4*>(xout + (i * 64 + lane) * 4) = xv[i];
;         } else if (xdst != 0) {
;           u16* xo = ((xdst == 1) ? resA : P.zf) + (long)row * 1024;
; #pragma unroll
;           for (int i = 0; i < 4; ++i) {
;             const unsigned b0 = f2bf(xv[i].x), b1 = f2bf(xv[i].y), b2 = f2bf(xv[i].z), b3 = f2bf(xv[i].w);
;             *reinterpret_cast<uint2*>(xo + (i * 64 + lane) * 4) = make_uint2(b0 | (b1 << 16), b2 | (b3 << 16));
;           }
;         }
;         if (doH) {
;           float ss = 0.f;
; #pragma unroll
;           for (int i = 0; i < 4; ++i) ss += xv[i].x * xv[i].x + xv[i].y * xv[i].y + xv[i].z * xv[i].z + xv[i].w * xv[i].w;
;           ss = wave_sum(ss);
;           const float rstd = __builtin_amdgcn_rsqf(ss * (1.f / 1024.f) + EPSF);
;           u16* h = P.hy + (long)row * 1024;
; #pragma unroll
;           for (int i = 0; i < 4; ++i) {
;             const int col = (i * 64 + lane) * 4;
;             const float4 g = *reinterpret_cast<const float4*>(gpre + col);
;             const float4 sh = *reinterpret_cast<const float4*>(modp + sh_idx * 1024 + col);
;             const float4 sc = *reinterpret_cast<const float4*>(modp + (sh_idx + 1) * 1024 + col);
;             const unsigned h0 = f2bf(xv[i].x * rstd * g.x * (1.f + sc.x) + sh.x);
;             const unsigned h1 = f2bf(xv[i].y * rstd * g.y * (1.f + sc.y) + sh.y);
	v_and_b32_e32 v19, 0xffff0000, v25
	v_lshlrev_b32_e32 v20, 16, v26
	v_and_b32_e32 v21, 0xffff0000, v26
	v_lshlrev_b32_e32 v22, 16, v27
	v_and_b32_e32 v23, 0xffff0000, v27
	v_lshlrev_b32_e32 v24, 16, v28
	v_and_b32_e32 v25, 0xffff0000, v28
	v_lshlrev_b32_e32 v26, 16, v29
	v_and_b32_e32 v27, 0xffff0000, v29
	v_lshlrev_b32_e32 v28, 16, v30
	v_and_b32_e32 v29, 0xffff0000, v30
	v_lshlrev_b32_e32 v30, 16, v31
	v_and_b32_e32 v31, 0xffff0000, v31
	s_nop 0
	v_mul_f32_e32 v120, v120, v140
	v_mul_f32_e32 v121, v121, v140
	v_mul_f32_e32 v122, v122, v140
	v_mul_f32_e32 v123, v123, v140
	v_mul_f32_e32 v124, v124, v140
	v_mul_f32_e32 v125, v125, v140
	v_mul_f32_e32 v126, v126, v140
	v_mul_f32_e32 v127, v127, v140
	v_mul_f32_e32 v128, v128, v140
	v_mul_f32_e32 v129, v129, v140
	v_mul_f32_e32 v130, v130, v140
	v_mul_f32_e32 v131, v131, v140
	v_mul_f32_e32 v132, v132, v140
	v_mul_f32_e32 v133, v133, v140
	v_mul_f32_e32 v134, v134, v140
	v_mul_f32_e32 v135, v135, v140
	v_fma_f32 v16, v120, v72, v16
	v_fma_f32 v17, v121, v73, v17
	v_fma_f32 v18, v122, v74, v18
	v_fma_f32 v19, v123, v75, v19
	v_fma_f32 v20, v124, v76, v20
	v_fma_f32 v21, v125, v77, v21
	v_fma_f32 v22, v126, v78, v22
	v_fma_f32 v23, v127, v79, v23
	v_fma_f32 v24, v128, v80, v24
	v_fma_f32 v25, v129, v81, v25
	v_fma_f32 v26, v130, v82, v26
	v_fma_f32 v27, v131, v83, v27
	v_fma_f32 v28, v132, v84, v28
	v_fma_f32 v29, v133, v85, v29
	v_fma_f32 v30, v134, v86, v30
	v_fma_f32 v31, v135, v87, v31
	v_cvt_pk_bf16_f32 v156, v16, v17
	v_cvt_pk_bf16_f32 v157, v18, v19
	v_cvt_pk_bf16_f32 v158, v20, v21
	v_cvt_pk_bf16_f32 v159, v22, v23
	v_cvt_pk_bf16_f32 v160, v24, v25
	v_cvt_pk_bf16_f32 v161, v26, v27
	v_cvt_pk_bf16_f32 v162, v28, v29
	v_cvt_pk_bf16_f32 v163, v30, v31
	s_lshl_b32 vcc_lo, s19, 11
	s_add_u32 vcc_lo, vcc_lo, 0x2400000
	s_add_u32 s100, s16, vcc_lo
	s_addc_u32 s101, s17, 0
	global_store_dwordx2 v137, v[156:157], s[100:101] offset:0
	global_store_dwordx2 v137, v[158:159], s[100:101] offset:512
	global_store_dwordx2 v137, v[160:161], s[100:101] offset:1024
	global_store_dwordx2 v137, v[162:163], s[100:101] offset:1536
	v_mul_f32_e32 v138, v16, v16
	v_mul_f32_e32 v149, v17, v17
	v_mul_f32_e32 v150, v18, v18
	v_mul_f32_e32 v154, v19, v19
	v_fma_f32 v138, v20, v20, v138
	v_fma_f32 v149, v21, v21, v149
	v_fma_f32 v150, v22, v22, v150
	v_fma_f32 v154, v23, v23, v154
	v_fma_f32 v138, v24, v24, v138
	v_fma_f32 v149, v25, v25, v149
	v_fma_f32 v150, v26, v26, v150
	v_fma_f32 v154, v27, v27, v154
	v_fma_f32 v138, v28, v28, v138
	v_fma_f32 v149, v29, v29, v149
	v_fma_f32 v150, v30, v30, v150
	v_fma_f32 v154, v31, v31, v154
	v_add_f32_e32 v138, v138, v149
	v_add_f32_e32 v150, v150, v154
	v_add_f32_e32 v138, v138, v150
	s_nop 1
	v_add_f32_dpp v138, v138, v138 quad_perm:[1,0,3,2] row_mask:0xf bank_mask:0xf
	s_nop 1
	v_add_f32_dpp v138, v138, v138 quad_perm:[2,3,0,1] row_mask:0xf bank_mask:0xf
	s_nop 1
	v_add_f32_dpp v138, v138, v138 row_half_mirror row_mask:0xf bank_mask:0xf
	s_nop 1
	v_add_f32_dpp v138, v138, v138 row_mirror row_mask:0xf bank_mask:0xf
	v_mov_b32_e32 v139, v138
	s_nop 1
	v_permlane16_swap_b32_e32 v138, v139
	v_add_f32_e32 v138, v138, v139
	v_mov_b32_e32 v139, v138
	s_nop 1
	v_permlane32_swap_b32_e32 v138, v139
	v_add_f32_e32 v138, v138, v139
	v_mul_f32_e32 v138, 0x3a800000, v138
	v_add_f32_e32 v138, 0x358637bd, v138
	v_rsq_f32_e32 v140, v138
	s_nop 0
	v_mul_f32_e32 v120, v16, v140
	v_mul_f32_e32 v121, v17, v140
	v_mul_f32_e32 v122, v18, v140
	v_mul_f32_e32 v123, v19, v140
	v_mul_f32_e32 v124, v20, v140
	v_mul_f32_e32 v125, v21, v140
	v_mul_f32_e32 v126, v22, v140
	v_mul_f32_e32 v127, v23, v140
	v_mul_f32_e32 v128, v24, v140
	v_mul_f32_e32 v129, v25, v140
	v_mul_f32_e32 v130, v26, v140
	v_mul_f32_e32 v131, v27, v140
	v_mul_f32_e32 v132, v28, v140
	v_mul_f32_e32 v133, v29, v140
	v_mul_f32_e32 v134, v30, v140
	v_mul_f32_e32 v135, v31, v140
	v_fma_f32 v120, v120, v88, v104
	v_fma_f32 v121, v121, v89, v105
	v_fma_f32 v122, v122, v90, v106
	v_fma_f32 v123, v123, v91, v107
	v_fma_f32 v124, v124, v92, v108
	v_fma_f32 v125, v125, v93, v109
	v_fma_f32 v126, v126, v94, v110
	v_fma_f32 v127, v127, v95, v111
	v_fma_f32 v128, v128, v96, v112
	v_fma_f32 v129, v129, v97, v113
	v_fma_f32 v130, v130, v98, v114
	v_fma_f32 v131, v131, v99, v115
	v_fma_f32 v132, v132, v100, v116
	v_fma_f32 v133, v133, v101, v117
	v_fma_f32 v134, v134, v102, v118
	v_fma_f32 v135, v135, v103, v119
	v_cvt_pk_bf16_f32 v156, v120, v121
	v_cvt_pk_bf16_f32 v157, v122, v123
	v_cvt_pk_bf16_f32 v158, v124, v125
	v_cvt_pk_bf16_f32 v159, v126, v127
	v_cvt_pk_bf16_f32 v160, v128, v129
	v_cvt_pk_bf16_f32 v161, v130, v131
	v_cvt_pk_bf16_f32 v162, v132, v133
	v_cvt_pk_bf16_f32 v163, v134, v135
	s_lshl_b32 vcc_lo, s19, 11
	s_add_u32 vcc_lo, vcc_lo, 0x2400000
	s_add_u32 s100, s14, vcc_lo
	s_addc_u32 s101, s15, 0
	global_store_dwordx2 v137, v[156:157], s[100:101] offset:0
	global_store_dwordx2 v137, v[158:159], s[100:101] offset:512
	global_store_dwordx2 v137, v[160:161], s[100:101] offset:1024
	global_store_dwordx2 v137, v[162:163], s[100:101] offset:1536
	s_lshl_b32 vcc_lo, s19, 11
	s_add_u32 vcc_lo, vcc_lo, 0x3400000
	s_add_u32 s100, s12, vcc_lo
	s_addc_u32 s101, s13, 0
	global_load_dwordx2 v[24:25], v137, s[100:101] offset:0
	global_load_dwordx2 v[26:27], v137, s[100:101] offset:512
	global_load_dwordx2 v[28:29], v137, s[100:101] offset:1024
	global_load_dwordx2 v[30:31], v137, s[100:101] offset:1536
	s_lshl_b32 vcc_lo, s19, 11
	s_add_u32 vcc_lo, vcc_lo, 0x3400000
	s_add_u32 s100, s14, vcc_lo
	s_addc_u32 s101, s15, 0
	global_load_dwordx2 v[56:57], v137, s[100:101] offset:0
	global_load_dwordx2 v[58:59], v137, s[100:101] offset:512
; __device__ __forceinline__ float bf2f(u16 h) { return __uint_as_float(((unsigned)h) << 16); }
; __device__ __forceinline__ void row_phase(const Params& P, int glayer, int layer, int xsrc, bool hasY, int gate_idx, const float* gpost,
;                           int xdst, bool doH, const float* gpre, int sh_idx, int nrows) {
;     ...
;             const uint2 raw = yy[u][i];
;             yv[i].x = bf2f((u16)(raw.x & 0xffff)); yv[i].y = bf2f((u16)(raw.x >> 16));
;             yv[i].z = bf2f((u16)(raw.y & 0xffff)); yv[i].w = bf2f((u16)(raw.y >> 16));
;             ss += yv[i].x * yv[i].x + yv[i].y * yv[i].y + yv[i].z * yv[i].z + yv[i].w * yv[i].w;
;           }
;           ss = wave_sum(ss);
;           const float rstd = __builtin_amdgcn_rsqf(ss * (1.f / 1024.f) + EPSF);
; #pragma unroll
;           for (int i = 0; i < 4; ++i) {
;             const int col = (i * 64 + lane) * 4;
;             const float4 gt = *reinterpret_cast<const float4*>(modg + gate_idx * 1024 + col);
;             const float4 gp = *reinterpret_cast<const float4*>(gpost + col);
;             xv[i].x += gt.x * (yv[i].x * rstd * gp.x); xv[i].y += gt.y * (yv[i].y * rstd * gp.y);
;             xv[i].z += gt.z * (yv[i].z * rstd * gp.z); xv[i].w += gt.w * (yv[i].w * rstd * gp.w);
;           }
;         }
;         if (xdst == 3 || (xdst == 1 && row >= N_X)) {
;           float* xout = (xdst == 3) ? P.out + (long)row * 1024 : P.xc + (long)(row - N_X) * 1024;
; #pragma unroll
;           for (int i = 0; i < 4; ++i) *reinterpret_cast<float4*>(xout + (i * 64 + lane) * 4) = xv[i];
;         } else if (xdst != 0) {
;           u16* xo = ((xdst == 1) ? resA : P.zf) + (long)row * 1024;
; #pragma unroll
;           for (int i = 0; i < 4; ++i) {
;             const unsigned b0 = f2bf(xv[i].x), b1 = f2bf(xv[i].y), b2 = f2bf(xv[i].z), b3 = f2bf(xv[i].w);
;             *reinterpret_cast<uint2*>(xo + (i * 64 + lane) * 4) = make_uint2(b0 | (b1 << 16), b2 | (b3 << 16));
;           }
;         }
;         if (doH) {
;           float ss = 0.f;
; #pragma unroll
;           for (int i = 0; i < 4; ++i) ss += xv[i].x * xv[i].x + xv[i].y * xv[i].y + xv[i].z * xv[i].z + xv[i].w * xv[i].w;
;           ss = wave_sum(ss);
;           const float rstd = __builtin_amdgcn_rsqf(ss * (1.f / 1024.f) + EPSF);
	global_load_dwordx2 v[60:61], v137, s[100:101] offset:1024
	global_load_dwordx2 v[62:63], v137, s[100:101] offset:1536
	v_lshlrev_b32_e32 v120, 16, v64
	v_and_b32_e32 v121, 0xffff0000, v64
	v_lshlrev_b32_e32 v122, 16, v65
	v_and_b32_e32 v123, 0xffff0000, v65
	v_lshlrev_b32_e32 v124, 16, v66
	v_and_b32_e32 v125, 0xffff0000, v66
	v_lshlrev_b32_e32 v126, 16, v67
	v_and_b32_e32 v127, 0xffff0000, v67
	v_lshlrev_b32_e32 v128, 16, v68
	v_and_b32_e32 v129, 0xffff0000, v68
	v_lshlrev_b32_e32 v130, 16, v69
	v_and_b32_e32 v131, 0xffff0000, v69
	v_lshlrev_b32_e32 v132, 16, v70
	v_and_b32_e32 v133, 0xffff0000, v70
	v_lshlrev_b32_e32 v134, 16, v71
	v_and_b32_e32 v135, 0xffff0000, v71
	v_mul_f32_e32 v138, v120, v120
	v_mul_f32_e32 v149, v121, v121
	v_mul_f32_e32 v150, v122, v122
	v_mul_f32_e32 v154, v123, v123
	v_fma_f32 v138, v124, v124, v138
	v_fma_f32 v149, v125, v125, v149
	v_fma_f32 v150, v126, v126, v150
	v_fma_f32 v154, v127, v127, v154
	v_fma_f32 v138, v128, v128, v138
	v_fma_f32 v149, v129, v129, v149
	v_fma_f32 v150, v130, v130, v150
	v_fma_f32 v154, v131, v131, v154
	v_fma_f32 v138, v132, v132, v138
	v_fma_f32 v149, v133, v133, v149
	v_fma_f32 v150, v134, v134, v150
	v_fma_f32 v154, v135, v135, v154
	v_add_f32_e32 v138, v138, v149
	v_add_f32_e32 v150, v150, v154
	v_add_f32_e32 v138, v138, v150
	s_nop 1
	v_add_f32_dpp v138, v138, v138 quad_perm:[1,0,3,2] row_mask:0xf bank_mask:0xf
	s_nop 1
	v_add_f32_dpp v138, v138, v138 quad_perm:[2,3,0,1] row_mask:0xf bank_mask:0xf
	s_nop 1
	v_add_f32_dpp v138, v138, v138 row_half_mirror row_mask:0xf bank_mask:0xf
	s_nop 1
	v_add_f32_dpp v138, v138, v138 row_mirror row_mask:0xf bank_mask:0xf
	v_mov_b32_e32 v139, v138
	s_nop 1
	v_permlane16_swap_b32_e32 v138, v139
	v_add_f32_e32 v138, v138, v139
	v_mov_b32_e32 v139, v138
	s_nop 1
	v_permlane32_swap_b32_e32 v138, v139
	v_add_f32_e32 v138, v138, v139
	v_mul_f32_e32 v138, 0x3a800000, v138
	v_add_f32_e32 v138, 0x358637bd, v138
	v_rsq_f32_e32 v140, v138
	v_lshlrev_b32_e32 v32, 16, v40
	v_and_b32_e32 v33, 0xffff0000, v40
	v_lshlrev_b32_e32 v34, 16, v41
	v_and_b32_e32 v35, 0xffff0000, v41
	v_lshlrev_b32_e32 v36, 16, v42
	v_and_b32_e32 v37, 0xffff0000, v42
	v_lshlrev_b32_e32 v38, 16, v43
	v_and_b32_e32 v39, 0xffff0000, v43
	v_lshlrev_b32_e32 v40, 16, v44
	v_and_b32_e32 v41, 0xffff0000, v44
	v_lshlrev_b32_e32 v42, 16, v45
	v_and_b32_e32 v43, 0xffff0000, v45
	v_lshlrev_b32_e32 v44, 16, v46
	v_and_b32_e32 v45, 0xffff0000, v46
	v_lshlrev_b32_e32 v46, 16, v47
	v_and_b32_e32 v47, 0xffff0000, v47
	s_nop 0
	v_mul_f32_e32 v120, v120, v140
	v_mul_f32_e32 v121, v121, v140
	v_mul_f32_e32 v122, v122, v140
	v_mul_f32_e32 v123, v123, v140
	v_mul_f32_e32 v124, v124, v140
	v_mul_f32_e32 v125, v125, v140
	v_mul_f32_e32 v126, v126, v140
	v_mul_f32_e32 v127, v127, v140
	v_mul_f32_e32 v128, v128, v140
	v_mul_f32_e32 v129, v129, v140
	v_mul_f32_e32 v130, v130, v140
	v_mul_f32_e32 v131, v131, v140
	v_mul_f32_e32 v132, v132, v140
	v_mul_f32_e32 v133, v133, v140
	v_mul_f32_e32 v134, v134, v140
	v_mul_f32_e32 v135, v135, v140
	v_fma_f32 v32, v120, v72, v32
	v_fma_f32 v33, v121, v73, v33
	v_fma_f32 v34, v122, v74, v34
	v_fma_f32 v35, v123, v75, v35
	v_fma_f32 v36, v124, v76, v36
	v_fma_f32 v37, v125, v77, v37
	v_fma_f32 v38, v126, v78, v38
	v_fma_f32 v39, v127, v79, v39
	v_fma_f32 v40, v128, v80, v40
	v_fma_f32 v41, v129, v81, v41
	v_fma_f32 v42, v130, v82, v42
	v_fma_f32 v43, v131, v83, v43
	v_fma_f32 v44, v132, v84, v44
	v_fma_f32 v45, v133, v85, v45
	v_fma_f32 v46, v134, v86, v46
	v_fma_f32 v47, v135, v87, v47
	v_cvt_pk_bf16_f32 v156, v32, v33
	v_cvt_pk_bf16_f32 v157, v34, v35
	v_cvt_pk_bf16_f32 v158, v36, v37
	v_cvt_pk_bf16_f32 v159, v38, v39
	v_cvt_pk_bf16_f32 v160, v40, v41
	v_cvt_pk_bf16_f32 v161, v42, v43
	v_cvt_pk_bf16_f32 v162, v44, v45
	v_cvt_pk_bf16_f32 v163, v46, v47
	s_lshl_b32 vcc_lo, s19, 11
	s_add_u32 vcc_lo, vcc_lo, 0x2800000
	s_add_u32 s100, s16, vcc_lo
	s_addc_u32 s101, s17, 0
	global_store_dwordx2 v137, v[156:157], s[100:101] offset:0
	global_store_dwordx2 v137, v[158:159], s[100:101] offset:512
	global_store_dwordx2 v137, v[160:161], s[100:101] offset:1024
	global_store_dwordx2 v137, v[162:163], s[100:101] offset:1536
	v_mul_f32_e32 v138, v32, v32
	v_mul_f32_e32 v149, v33, v33
	v_mul_f32_e32 v150, v34, v34
	v_mul_f32_e32 v154, v35, v35
	v_fma_f32 v138, v36, v36, v138
	v_fma_f32 v149, v37, v37, v149
	v_fma_f32 v150, v38, v38, v150
	v_fma_f32 v154, v39, v39, v154
	v_fma_f32 v138, v40, v40, v138
	v_fma_f32 v149, v41, v41, v149
	v_fma_f32 v150, v42, v42, v150
	v_fma_f32 v154, v43, v43, v154
	v_fma_f32 v138, v44, v44, v138
	v_fma_f32 v149, v45, v45, v149
	v_fma_f32 v150, v46, v46, v150
	v_fma_f32 v154, v47, v47, v154
	v_add_f32_e32 v138, v138, v149
	v_add_f32_e32 v150, v150, v154
	v_add_f32_e32 v138, v138, v150
	s_nop 1
	v_add_f32_dpp v138, v138, v138 quad_perm:[1,0,3,2] row_mask:0xf bank_mask:0xf
	s_nop 1
	v_add_f32_dpp v138, v138, v138 quad_perm:[2,3,0,1] row_mask:0xf bank_mask:0xf
	s_nop 1
	v_add_f32_dpp v138, v138, v138 row_half_mirror row_mask:0xf bank_mask:0xf
	s_nop 1
	v_add_f32_dpp v138, v138, v138 row_mirror row_mask:0xf bank_mask:0xf
	v_mov_b32_e32 v139, v138
	s_nop 1
	v_permlane16_swap_b32_e32 v138, v139
	v_add_f32_e32 v138, v138, v139
	v_mov_b32_e32 v139, v138
	s_nop 1
	v_permlane32_swap_b32_e32 v138, v139
	v_add_f32_e32 v138, v138, v139
	v_mul_f32_e32 v138, 0x3a800000, v138
	v_add_f32_e32 v138, 0x358637bd, v138
	v_rsq_f32_e32 v140, v138
	s_nop 0
	v_mul_f32_e32 v120, v32, v140
	v_mul_f32_e32 v121, v33, v140
	v_mul_f32_e32 v122, v34, v140
	v_mul_f32_e32 v123, v35, v140
	v_mul_f32_e32 v124, v36, v140
	v_mul_f32_e32 v125, v37, v140
	v_mul_f32_e32 v126, v38, v140
; __device__ __forceinline__ void row_phase(const Params& P, int glayer, int layer, int xsrc, bool hasY, int gate_idx, const float* gpost,
;                           int xdst, bool doH, const float* gpre, int sh_idx, int nrows) {
;     ...
;     for (int u = 0; u < 4; ++u) {
;       const int R = rb + u * stride;
;       if (R < nrows) {
;         if (xsrc != 0 && R < N_X) {
;           const u16* xs_ = ((xsrc == 1) ? resA : P.zf) + (long)R * 1024;
; #pragma unroll
;           for (int i = 0; i < 4; ++i) {
;             const uint2 t2 = *reinterpret_cast<const uint2*>(xs_ + (i * 64 + lane) * 4);
;             xr[u][i].x = t2.x; xr[u][i].y = t2.y;
;           }
;         } else {
;           const float* xin_;
;           if (xsrc == 0) xin_ = R < N_X ? P.x + (long)R * 1024 : P.ctx + (long)(R - N_X) * 1024;
;           else           xin_ = P.xc + (long)(R - N_X) * 1024;
; #pragma unroll
;           for (int i = 0; i < 4; ++i) xr[u][i] = *reinterpret_cast<const uint4*>(xin_ + (i * 64 + lane) * 4);
;         }
;         if (hasY) {
;           const u16* y_ = P.hy + (long)R * 1024;
; #pragma unroll
;           for (int i = 0; i < 4; ++i) yy[u][i] = *reinterpret_cast<const uint2*>(y_ + (i * 64 + lane) * 4);
;         }
;     ...
;             const uint2 raw = yy[u][i];
;             yv[i].x = bf2f((u16)(raw.x & 0xffff)); yv[i].y = bf2f((u16)(raw.x >> 16));
;     ...
;           const float rstd = __builtin_amdgcn_rsqf(ss * (1.f / 1024.f) + EPSF);
;           u16* h = P.hy + (long)row * 1024;
; #pragma unroll
;           for (int i = 0; i < 4; ++i) {
;             const int col = (i * 64 + lane) * 4;
;             const float4 g = *reinterpret_cast<const float4*>(gpre + col);
;             const float4 sh = *reinterpret_cast<const float4*>(modp + sh_idx * 1024 + col);
;             const float4 sc = *reinterpret_cast<const float4*>(modp + (sh_idx + 1) * 1024 + col);
;             const unsigned h0 = f2bf(xv[i].x * rstd * g.x * (1.f + sc.x) + sh.x);
;             const unsigned h1 = f2bf(xv[i].y * rstd * g.y * (1.f + sc.y) + sh.y);
;             const unsigned h2 = f2bf(xv[i].z * rstd * g.z * (1.f + sc.z) + sh.z);
;             const unsigned h3 = f2bf(xv[i].w * rstd * g.w * (1.f + sc.w) + sh.w);
;             *reinterpret_cast<uint2*>(h + col) = make_uint2(h0 | (h1 << 16), h2 | (h3 << 16));
;           }
	v_mul_f32_e32 v127, v39, v140
	v_mul_f32_e32 v128, v40, v140
	v_mul_f32_e32 v129, v41, v140
	v_mul_f32_e32 v130, v42, v140
	v_mul_f32_e32 v131, v43, v140
	v_mul_f32_e32 v132, v44, v140
	v_mul_f32_e32 v133, v45, v140
	v_mul_f32_e32 v134, v46, v140
	v_mul_f32_e32 v135, v47, v140
	v_fma_f32 v120, v120, v88, v104
	v_fma_f32 v121, v121, v89, v105
	v_fma_f32 v122, v122, v90, v106
	v_fma_f32 v123, v123, v91, v107
	v_fma_f32 v124, v124, v92, v108
	v_fma_f32 v125, v125, v93, v109
	v_fma_f32 v126, v126, v94, v110
	v_fma_f32 v127, v127, v95, v111
	v_fma_f32 v128, v128, v96, v112
	v_fma_f32 v129, v129, v97, v113
	v_fma_f32 v130, v130, v98, v114
	v_fma_f32 v131, v131, v99, v115
	v_fma_f32 v132, v132, v100, v116
	v_fma_f32 v133, v133, v101, v117
	v_fma_f32 v134, v134, v102, v118
	v_fma_f32 v135, v135, v103, v119
	v_cvt_pk_bf16_f32 v156, v120, v121
	v_cvt_pk_bf16_f32 v157, v122, v123
	v_cvt_pk_bf16_f32 v158, v124, v125
	v_cvt_pk_bf16_f32 v159, v126, v127
	v_cvt_pk_bf16_f32 v160, v128, v129
	v_cvt_pk_bf16_f32 v161, v130, v131
	v_cvt_pk_bf16_f32 v162, v132, v133
	v_cvt_pk_bf16_f32 v163, v134, v135
	s_lshl_b32 vcc_lo, s19, 11
	s_add_u32 vcc_lo, vcc_lo, 0x2800000
	s_add_u32 s100, s14, vcc_lo
	s_addc_u32 s101, s15, 0
	global_store_dwordx2 v137, v[156:157], s[100:101] offset:0
	global_store_dwordx2 v137, v[158:159], s[100:101] offset:512
	global_store_dwordx2 v137, v[160:161], s[100:101] offset:1024
	global_store_dwordx2 v137, v[162:163], s[100:101] offset:1536
	s_lshl_b32 vcc_lo, s19, 11
	s_add_u32 vcc_lo, vcc_lo, 0x3800000
	s_add_u32 s100, s12, vcc_lo
	s_addc_u32 s101, s13, 0
	global_load_dwordx2 v[40:41], v137, s[100:101] offset:0
	global_load_dwordx2 v[42:43], v137, s[100:101] offset:512
	global_load_dwordx2 v[44:45], v137, s[100:101] offset:1024
	global_load_dwordx2 v[46:47], v137, s[100:101] offset:1536
	s_lshl_b32 vcc_lo, s19, 11
	s_add_u32 vcc_lo, vcc_lo, 0x3800000
	s_add_u32 s100, s14, vcc_lo
	s_addc_u32 s101, s15, 0
	global_load_dwordx2 v[64:65], v137, s[100:101] offset:0
	global_load_dwordx2 v[66:67], v137, s[100:101] offset:512
	global_load_dwordx2 v[68:69], v137, s[100:101] offset:1024
	global_load_dwordx2 v[70:71], v137, s[100:101] offset:1536
	s_waitcnt vmcnt(48)
	v_lshlrev_b32_e32 v120, 16, v182
	v_and_b32_e32 v121, 0xffff0000, v182
	v_lshlrev_b32_e32 v122, 16, v183
	v_and_b32_e32 v123, 0xffff0000, v183
	v_lshlrev_b32_e32 v124, 16, v184
	v_and_b32_e32 v125, 0xffff0000, v184
	v_lshlrev_b32_e32 v126, 16, v185
	v_and_b32_e32 v127, 0xffff0000, v185
	v_lshlrev_b32_e32 v128, 16, v186
	v_and_b32_e32 v129, 0xffff0000, v186
	v_lshlrev_b32_e32 v130, 16, v187
	v_and_b32_e32 v131, 0xffff0000, v187
	v_lshlrev_b32_e32 v132, 16, v188
	v_and_b32_e32 v133, 0xffff0000, v188
	v_lshlrev_b32_e32 v134, 16, v189
	v_and_b32_e32 v135, 0xffff0000, v189
	v_mul_f32_e32 v138, v120, v120
	v_mul_f32_e32 v149, v121, v121
	v_mul_f32_e32 v150, v122, v122
	v_mul_f32_e32 v154, v123, v123
	v_fma_f32 v138, v124, v124, v138
	v_fma_f32 v149, v125, v125, v149
	v_fma_f32 v150, v126, v126, v150
	v_fma_f32 v154, v127, v127, v154
	v_fma_f32 v138, v128, v128, v138
	v_fma_f32 v149, v129, v129, v149
	v_fma_f32 v150, v130, v130, v150
	v_fma_f32 v154, v131, v131, v154
	v_fma_f32 v138, v132, v132, v138
	v_fma_f32 v149, v133, v133, v149
	v_fma_f32 v150, v134, v134, v150
	v_fma_f32 v154, v135, v135, v154
	v_add_f32_e32 v138, v138, v149
	v_add_f32_e32 v150, v150, v154
	v_add_f32_e32 v138, v138, v150
	s_nop 1
	v_add_f32_dpp v138, v138, v138 quad_perm:[1,0,3,2] row_mask:0xf bank_mask:0xf
	s_nop 1
	v_add_f32_dpp v138, v138, v138 quad_perm:[2,3,0,1] row_mask:0xf bank_mask:0xf
	s_nop 1
	v_add_f32_dpp v138, v138, v138 row_half_mirror row_mask:0xf bank_mask:0xf
	s_nop 1
	v_add_f32_dpp v138, v138, v138 row_mirror row_mask:0xf bank_mask:0xf
	v_mov_b32_e32 v139, v138
	s_nop 1
	v_permlane16_swap_b32_e32 v138, v139
	v_add_f32_e32 v138, v138, v139
	v_mov_b32_e32 v139, v138
	s_nop 1
	v_permlane32_swap_b32_e32 v138, v139
	v_add_f32_e32 v138, v138, v139
	v_mul_f32_e32 v138, 0x3a800000, v138
	v_add_f32_e32 v138, 0x358637bd, v138
	v_rsq_f32_e32 v140, v138
	v_lshlrev_b32_e32 v166, 16, v174
	v_and_b32_e32 v167, 0xffff0000, v174
	v_lshlrev_b32_e32 v168, 16, v175
	v_and_b32_e32 v169, 0xffff0000, v175
	v_lshlrev_b32_e32 v170, 16, v176
	v_and_b32_e32 v171, 0xffff0000, v176
	v_lshlrev_b32_e32 v172, 16, v177
	v_and_b32_e32 v173, 0xffff0000, v177
	v_lshlrev_b32_e32 v174, 16, v178
	v_and_b32_e32 v175, 0xffff0000, v178
	v_lshlrev_b32_e32 v176, 16, v179
	v_and_b32_e32 v177, 0xffff0000, v179
	v_lshlrev_b32_e32 v178, 16, v180
	v_and_b32_e32 v179, 0xffff0000, v180
	v_lshlrev_b32_e32 v180, 16, v181
	v_and_b32_e32 v181, 0xffff0000, v181
	s_nop 0
	v_mul_f32_e32 v120, v120, v140
	v_mul_f32_e32 v121, v121, v140
	v_mul_f32_e32 v122, v122, v140
	v_mul_f32_e32 v123, v123, v140
	v_mul_f32_e32 v124, v124, v140
	v_mul_f32_e32 v125, v125, v140
	v_mul_f32_e32 v126, v126, v140
	v_mul_f32_e32 v127, v127, v140
	v_mul_f32_e32 v128, v128, v140
	v_mul_f32_e32 v129, v129, v140
	v_mul_f32_e32 v130, v130, v140
	v_mul_f32_e32 v131, v131, v140
	v_mul_f32_e32 v132, v132, v140
	v_mul_f32_e32 v133, v133, v140
	v_mul_f32_e32 v134, v134, v140
	v_mul_f32_e32 v135, v135, v140
	v_fma_f32 v166, v120, v72, v166
	v_fma_f32 v167, v121, v73, v167
	v_fma_f32 v168, v122, v74, v168
	v_fma_f32 v169, v123, v75, v169
	v_fma_f32 v170, v124, v76, v170
	v_fma_f32 v171, v125, v77, v171
	v_fma_f32 v172, v126, v78, v172
	v_fma_f32 v173, v127, v79, v173
	v_fma_f32 v174, v128, v80, v174
	v_fma_f32 v175, v129, v81, v175
	v_fma_f32 v176, v130, v82, v176
	v_fma_f32 v177, v131, v83, v177
	v_fma_f32 v178, v132, v84, v178
	v_fma_f32 v179, v133, v85, v179
	v_fma_f32 v180, v134, v86, v180
; __device__ __forceinline__ void row_phase(const Params& P, int glayer, int layer, int xsrc, bool hasY, int gate_idx, const float* gpost,
;                           int xdst, bool doH, const float* gpre, int sh_idx, int nrows) {
;     ...
; #pragma unroll
;           for (int i = 0; i < 4; ++i) {
;             const int col = (i * 64 + lane) * 4;
;             const float4 gt = *reinterpret_cast<const float4*>(modg + gate_idx * 1024 + col);
;             const float4 gp = *reinterpret_cast<const float4*>(gpost + col);
;             xv[i].x += gt.x * (yv[i].x * rstd * gp.x); xv[i].y += gt.y * (yv[i].y * rstd * gp.y);
;             xv[i].z += gt.z * (yv[i].z * rstd * gp.z); xv[i].w += gt.w * (yv[i].w * rstd * gp.w);
;           }
;     ...
;           const float rstd = __builtin_amdgcn_rsqf(ss * (1.f / 1024.f) + EPSF);
;           u16* h = P.hy + (long)row * 1024;
; #pragma unroll
;           for (int i = 0; i < 4; ++i) {
;             const int col = (i * 64 + lane) * 4;
;             const float4 g = *reinterpret_cast<const float4*>(gpre + col);
;             const float4 sh = *reinterpret_cast<const float4*>(modp + sh_idx * 1024 + col);
;             const float4 sc = *reinterpret_cast<const float4*>(modp + (sh_idx + 1) * 1024 + col);
;             const unsigned h0 = f2bf(xv[i].x * rstd * g.x * (1.f + sc.x) + sh.x);
;             const unsigned h1 = f2bf(xv[i].y * rstd * g.y * (1.f + sc.y) + sh.y);
;             const unsigned h2 = f2bf(xv[i].z * rstd * g.z * (1.f + sc.z) + sh.z);
;             const unsigned h3 = f2bf(xv[i].w * rstd * g.w * (1.f + sc.w) + sh.w);
;             *reinterpret_cast<uint2*>(h + col) = make_uint2(h0 | (h1 << 16), h2 | (h3 << 16));
;           }
	v_fma_f32 v181, v135, v87, v181
	v_cvt_pk_bf16_f32 v156, v166, v167
	v_cvt_pk_bf16_f32 v157, v168, v169
	v_cvt_pk_bf16_f32 v158, v170, v171
	v_cvt_pk_bf16_f32 v159, v172, v173
	v_cvt_pk_bf16_f32 v160, v174, v175
	v_cvt_pk_bf16_f32 v161, v176, v177
	v_cvt_pk_bf16_f32 v162, v178, v179
	v_cvt_pk_bf16_f32 v163, v180, v181
	s_lshl_b32 vcc_lo, s19, 11
	s_add_u32 vcc_lo, vcc_lo, 0x2c00000
	s_add_u32 s100, s16, vcc_lo
	s_addc_u32 s101, s17, 0
	global_store_dwordx2 v137, v[156:157], s[100:101] offset:0
	global_store_dwordx2 v137, v[158:159], s[100:101] offset:512
	global_store_dwordx2 v137, v[160:161], s[100:101] offset:1024
	global_store_dwordx2 v137, v[162:163], s[100:101] offset:1536
	v_mul_f32_e32 v138, v166, v166
	v_mul_f32_e32 v149, v167, v167
	v_mul_f32_e32 v150, v168, v168
	v_mul_f32_e32 v154, v169, v169
	v_fma_f32 v138, v170, v170, v138
	v_fma_f32 v149, v171, v171, v149
	v_fma_f32 v150, v172, v172, v150
	v_fma_f32 v154, v173, v173, v154
	v_fma_f32 v138, v174, v174, v138
	v_fma_f32 v149, v175, v175, v149
	v_fma_f32 v150, v176, v176, v150
	v_fma_f32 v154, v177, v177, v154
	v_fma_f32 v138, v178, v178, v138
	v_fma_f32 v149, v179, v179, v149
	v_fma_f32 v150, v180, v180, v150
	v_fma_f32 v154, v181, v181, v154
	v_add_f32_e32 v138, v138, v149
	v_add_f32_e32 v150, v150, v154
	v_add_f32_e32 v138, v138, v150
	s_nop 1
	v_add_f32_dpp v138, v138, v138 quad_perm:[1,0,3,2] row_mask:0xf bank_mask:0xf
	s_nop 1
	v_add_f32_dpp v138, v138, v138 quad_perm:[2,3,0,1] row_mask:0xf bank_mask:0xf
	s_nop 1
	v_add_f32_dpp v138, v138, v138 row_half_mirror row_mask:0xf bank_mask:0xf
	s_nop 1
	v_add_f32_dpp v138, v138, v138 row_mirror row_mask:0xf bank_mask:0xf
	v_mov_b32_e32 v139, v138
	s_nop 1
	v_permlane16_swap_b32_e32 v138, v139
	v_add_f32_e32 v138, v138, v139
	v_mov_b32_e32 v139, v138
	s_nop 1
	v_permlane32_swap_b32_e32 v138, v139
	v_add_f32_e32 v138, v138, v139
	v_mul_f32_e32 v138, 0x3a800000, v138
	v_add_f32_e32 v138, 0x358637bd, v138
	v_rsq_f32_e32 v140, v138
	s_nop 0
	v_mul_f32_e32 v120, v166, v140
	v_mul_f32_e32 v121, v167, v140
	v_mul_f32_e32 v122, v168, v140
	v_mul_f32_e32 v123, v169, v140
	v_mul_f32_e32 v124, v170, v140
	v_mul_f32_e32 v125, v171, v140
	v_mul_f32_e32 v126, v172, v140
	v_mul_f32_e32 v127, v173, v140
	v_mul_f32_e32 v128, v174, v140
	v_mul_f32_e32 v129, v175, v140
	v_mul_f32_e32 v130, v176, v140
	v_mul_f32_e32 v131, v177, v140
	v_mul_f32_e32 v132, v178, v140
	v_mul_f32_e32 v133, v179, v140
	v_mul_f32_e32 v134, v180, v140
	v_mul_f32_e32 v135, v181, v140
	v_fma_f32 v120, v120, v88, v104
	v_fma_f32 v121, v121, v89, v105
	v_fma_f32 v122, v122, v90, v106
	v_fma_f32 v123, v123, v91, v107
	v_fma_f32 v124, v124, v92, v108
	v_fma_f32 v125, v125, v93, v109
	v_fma_f32 v126, v126, v94, v110
	v_fma_f32 v127, v127, v95, v111
	v_fma_f32 v128, v128, v96, v112
	v_fma_f32 v129, v129, v97, v113
	v_fma_f32 v130, v130, v98, v114
	v_fma_f32 v131, v131, v99, v115
	v_fma_f32 v132, v132, v100, v116
	v_fma_f32 v133, v133, v101, v117
	v_fma_f32 v134, v134, v102, v118
	v_fma_f32 v135, v135, v103, v119
	v_cvt_pk_bf16_f32 v156, v120, v121
	v_cvt_pk_bf16_f32 v157, v122, v123
	v_cvt_pk_bf16_f32 v158, v124, v125
	v_cvt_pk_bf16_f32 v159, v126, v127
	v_cvt_pk_bf16_f32 v160, v128, v129
	v_cvt_pk_bf16_f32 v161, v130, v131
	v_cvt_pk_bf16_f32 v162, v132, v133
	v_cvt_pk_bf16_f32 v163, v134, v135
	s_lshl_b32 vcc_lo, s19, 11
	s_add_u32 vcc_lo, vcc_lo, 0x2c00000
	s_add_u32 s100, s14, vcc_lo
	s_addc_u32 s101, s15, 0
	global_store_dwordx2 v137, v[156:157], s[100:101] offset:0
	global_store_dwordx2 v137, v[158:159], s[100:101] offset:512
	global_store_dwordx2 v137, v[160:161], s[100:101] offset:1024
	global_store_dwordx2 v137, v[162:163], s[100:101] offset:1536
	s_add_u32 s100, s20, 0x17000
	s_addc_u32 s101, s21, 0
	global_load_dwordx4 v[72:75], v136, s[100:101] offset:0
	global_load_dwordx4 v[76:79], v136, s[100:101] offset:1024
	global_load_dwordx4 v[80:83], v136, s[100:101] offset:2048
	global_load_dwordx4 v[84:87], v136, s[100:101] offset:3072
	s_load_dwordx2 s[98:99], s[4:5], 0x48
	s_waitcnt lgkmcnt(0)
	global_load_dwordx4 v[120:123], v136, s[98:99] offset:0
	global_load_dwordx4 v[124:127], v136, s[98:99] offset:1024
	global_load_dwordx4 v[128:131], v136, s[98:99] offset:2048
	global_load_dwordx4 v[132:135], v136, s[98:99] offset:3072
	s_add_u32 s100, s20, 0x30000
	s_addc_u32 s101, s21, 0
	global_load_dwordx4 v[104:107], v136, s[100:101] offset:0
	global_load_dwordx4 v[108:111], v136, s[100:101] offset:1024
	global_load_dwordx4 v[112:115], v136, s[100:101] offset:2048
	global_load_dwordx4 v[116:119], v136, s[100:101] offset:3072
	s_add_u32 s100, s100, 0x1000
	s_addc_u32 s101, s101, 0
	global_load_dwordx4 v[166:169], v136, s[100:101] offset:0
	global_load_dwordx4 v[170:173], v136, s[100:101] offset:1024
	global_load_dwordx4 v[174:177], v136, s[100:101] offset:2048
	global_load_dwordx4 v[178:181], v136, s[100:101] offset:3072
	s_load_dwordx2 s[98:99], s[4:5], 0x30
	s_waitcnt lgkmcnt(0)
	s_add_u32 s98, s98, 0x1000
	s_addc_u32 s99, s99, 0
	global_load_dwordx4 v[88:91], v136, s[98:99] offset:0
	global_load_dwordx4 v[92:95], v136, s[98:99] offset:1024
	global_load_dwordx4 v[96:99], v136, s[98:99] offset:2048
	global_load_dwordx4 v[100:103], v136, s[98:99] offset:3072
	s_waitcnt vmcnt(0)
; __device__ __forceinline__ void row_phase(const Params& P, int glayer, int layer, int xsrc, bool hasY, int gate_idx, const float* gpost,
;                           int xdst, bool doH, const float* gpre, int sh_idx, int nrows) {
;     ...
;     for (int u = 0; u < 4; ++u) {
;       const int R = rb + u * stride;
;       if (R < nrows) {
;         if (xsrc != 0 && R < N_X) {
;           const u16* xs_ = ((xsrc == 1) ? resA : P.zf) + (long)R * 1024;
; #pragma unroll
;           for (int i = 0; i < 4; ++i) {
;             const uint2 t2 = *reinterpret_cast<const uint2*>(xs_ + (i * 64 + lane) * 4);
;             xr[u][i].x = t2.x; xr[u][i].y = t2.y;
;           }
;         } else {
;           const float* xin_;
;           if (xsrc == 0) xin_ = R < N_X ? P.x + (long)R * 1024 : P.ctx + (long)(R - N_X) * 1024;
;           else           xin_ = P.xc + (long)(R - N_X) * 1024;
; #pragma unroll
;           for (int i = 0; i < 4; ++i) xr[u][i] = *reinterpret_cast<const uint4*>(xin_ + (i * 64 + lane) * 4);
;         }
;         if (hasY) {
;           const u16* y_ = P.hy + (long)R * 1024;
; #pragma unroll
;     ...
; #pragma unroll
;           for (int i = 0; i < 4; ++i) {
;             const int col = (i * 64 + lane) * 4;
;             const float4 gt = *reinterpret_cast<const float4*>(modg + gate_idx * 1024 + col);
;             const float4 gp = *reinterpret_cast<const float4*>(gpost + col);
;             xv[i].x += gt.x * (yv[i].x * rstd * gp.x); xv[i].y += gt.y * (yv[i].y * rstd * gp.y);
;             xv[i].z += gt.z * (yv[i].z * rstd * gp.z); xv[i].w += gt.w * (yv[i].w * rstd * gp.w);
;           }
;     ...
;           for (int i = 0; i < 4; ++i) {
;             const int col = (i * 64 + lane) * 4;
;             const float4 g = *reinterpret_cast<const float4*>(gpre + col);
;             const float4 sh = *reinterpret_cast<const float4*>(modp + sh_idx * 1024 + col);
;             const float4 sc = *reinterpret_cast<const float4*>(modp + (sh_idx + 1) * 1024 + col);
;             const unsigned h0 = f2bf(xv[i].x * rstd * g.x * (1.f + sc.x) + sh.x);
;             const unsigned h1 = f2bf(xv[i].y * rstd * g.y * (1.f + sc.y) + sh.y);
;             const unsigned h2 = f2bf(xv[i].z * rstd * g.z * (1.f + sc.z) + sh.z);
;             const unsigned h3 = f2bf(xv[i].w * rstd * g.w * (1.f + sc.w) + sh.w);
	v_mul_f32_e32 v72, v72, v120
	v_mul_f32_e32 v73, v73, v121
	v_mul_f32_e32 v74, v74, v122
	v_mul_f32_e32 v75, v75, v123
	v_mul_f32_e32 v76, v76, v124
	v_mul_f32_e32 v77, v77, v125
	v_mul_f32_e32 v78, v78, v126
	v_mul_f32_e32 v79, v79, v127
	v_mul_f32_e32 v80, v80, v128
	v_mul_f32_e32 v81, v81, v129
	v_mul_f32_e32 v82, v82, v130
	v_mul_f32_e32 v83, v83, v131
	v_mul_f32_e32 v84, v84, v132
	v_mul_f32_e32 v85, v85, v133
	v_mul_f32_e32 v86, v86, v134
	v_mul_f32_e32 v87, v87, v135
	v_fma_f32 v88, v88, v166, v88
	v_fma_f32 v89, v89, v167, v89
	v_fma_f32 v90, v90, v168, v90
	v_fma_f32 v91, v91, v169, v91
	v_fma_f32 v92, v92, v170, v92
	v_fma_f32 v93, v93, v171, v93
	v_fma_f32 v94, v94, v172, v94
	v_fma_f32 v95, v95, v173, v95
	v_fma_f32 v96, v96, v174, v96
	v_fma_f32 v97, v97, v175, v97
	v_fma_f32 v98, v98, v176, v98
	v_fma_f32 v99, v99, v177, v99
	v_fma_f32 v100, v100, v178, v100
	v_fma_f32 v101, v101, v179, v101
	v_fma_f32 v102, v102, v180, v102
	v_fma_f32 v103, v103, v181, v103
	s_lshl_b32 vcc_lo, s19, 11
	s_add_u32 vcc_lo, vcc_lo, 0x3c00000
	s_add_u32 s100, s12, vcc_lo
	s_addc_u32 s101, s13, 0
	global_load_dwordx2 v[174:175], v137, s[100:101] offset:0
	global_load_dwordx2 v[176:177], v137, s[100:101] offset:512
	global_load_dwordx2 v[178:179], v137, s[100:101] offset:1024
	global_load_dwordx2 v[180:181], v137, s[100:101] offset:1536
	s_lshl_b32 vcc_lo, s19, 11
	s_add_u32 vcc_lo, vcc_lo, 0x3c00000
	s_add_u32 s100, s14, vcc_lo
	s_addc_u32 s101, s15, 0
	global_load_dwordx2 v[182:183], v137, s[100:101] offset:0
	global_load_dwordx2 v[184:185], v137, s[100:101] offset:512
	global_load_dwordx2 v[186:187], v137, s[100:101] offset:1024
	global_load_dwordx2 v[188:189], v137, s[100:101] offset:1536
	v_lshlrev_b32_e32 v120, 16, v48
	v_and_b32_e32 v121, 0xffff0000, v48
	v_lshlrev_b32_e32 v122, 16, v49
	v_and_b32_e32 v123, 0xffff0000, v49
	v_lshlrev_b32_e32 v124, 16, v50
	v_and_b32_e32 v125, 0xffff0000, v50
	v_lshlrev_b32_e32 v126, 16, v51
	v_and_b32_e32 v127, 0xffff0000, v51
	v_lshlrev_b32_e32 v128, 16, v52
	v_and_b32_e32 v129, 0xffff0000, v52
	v_lshlrev_b32_e32 v130, 16, v53
	v_and_b32_e32 v131, 0xffff0000, v53
	v_lshlrev_b32_e32 v132, 16, v54
	v_and_b32_e32 v133, 0xffff0000, v54
	v_lshlrev_b32_e32 v134, 16, v55
	v_and_b32_e32 v135, 0xffff0000, v55
	v_mul_f32_e32 v138, v120, v120
	v_mul_f32_e32 v149, v121, v121
	v_mul_f32_e32 v150, v122, v122
	v_mul_f32_e32 v154, v123, v123
	v_fma_f32 v138, v124, v124, v138
	v_fma_f32 v149, v125, v125, v149
	v_fma_f32 v150, v126, v126, v150
	v_fma_f32 v154, v127, v127, v154
	v_fma_f32 v138, v128, v128, v138
	v_fma_f32 v149, v129, v129, v149
	v_fma_f32 v150, v130, v130, v150
	v_fma_f32 v154, v131, v131, v154
	v_fma_f32 v138, v132, v132, v138
	v_fma_f32 v149, v133, v133, v149
	v_fma_f32 v150, v134, v134, v150
	v_fma_f32 v154, v135, v135, v154
	v_add_f32_e32 v138, v138, v149
	v_add_f32_e32 v150, v150, v154
	v_add_f32_e32 v138, v138, v150
	s_nop 1
	v_add_f32_dpp v138, v138, v138 quad_perm:[1,0,3,2] row_mask:0xf bank_mask:0xf
	s_nop 1
	v_add_f32_dpp v138, v138, v138 quad_perm:[2,3,0,1] row_mask:0xf bank_mask:0xf
	s_nop 1
	v_add_f32_dpp v138, v138, v138 row_half_mirror row_mask:0xf bank_mask:0xf
	s_nop 1
	v_add_f32_dpp v138, v138, v138 row_mirror row_mask:0xf bank_mask:0xf
	v_mov_b32_e32 v139, v138
	s_nop 1
	v_permlane16_swap_b32_e32 v138, v139
	v_add_f32_e32 v138, v138, v139
	v_mov_b32_e32 v139, v138
	s_nop 1
	v_permlane32_swap_b32_e32 v138, v139
	v_add_f32_e32 v138, v138, v139
	v_mul_f32_e32 v138, 0x3a800000, v138
	v_add_f32_e32 v138, 0x358637bd, v138
	v_rsq_f32_e32 v140, v138
	v_lshlrev_b32_e32 v0, 16, v8
	v_and_b32_e32 v1, 0xffff0000, v8
	v_lshlrev_b32_e32 v2, 16, v9
	v_and_b32_e32 v3, 0xffff0000, v9
	v_lshlrev_b32_e32 v4, 16, v10
	v_and_b32_e32 v5, 0xffff0000, v10
	v_lshlrev_b32_e32 v6, 16, v11
	v_and_b32_e32 v7, 0xffff0000, v11
	v_lshlrev_b32_e32 v8, 16, v12
	v_and_b32_e32 v9, 0xffff0000, v12
	v_lshlrev_b32_e32 v10, 16, v13
	v_and_b32_e32 v11, 0xffff0000, v13
	v_lshlrev_b32_e32 v12, 16, v14
	v_and_b32_e32 v13, 0xffff0000, v14
	v_lshlrev_b32_e32 v14, 16, v15
	v_and_b32_e32 v15, 0xffff0000, v15
	s_nop 0
	v_mul_f32_e32 v120, v120, v140
	v_mul_f32_e32 v121, v121, v140
	v_mul_f32_e32 v122, v122, v140
	v_mul_f32_e32 v123, v123, v140
	v_mul_f32_e32 v124, v124, v140
	v_mul_f32_e32 v125, v125, v140
	v_mul_f32_e32 v126, v126, v140
	v_mul_f32_e32 v127, v127, v140
	v_mul_f32_e32 v128, v128, v140
	v_mul_f32_e32 v129, v129, v140
	v_mul_f32_e32 v130, v130, v140
	v_mul_f32_e32 v131, v131, v140
	v_mul_f32_e32 v132, v132, v140
	v_mul_f32_e32 v133, v133, v140
	v_mul_f32_e32 v134, v134, v140
	v_mul_f32_e32 v135, v135, v140
	v_fma_f32 v0, v120, v72, v0
	v_fma_f32 v1, v121, v73, v1
	v_fma_f32 v2, v122, v74, v2
	v_fma_f32 v3, v123, v75, v3
	v_fma_f32 v4, v124, v76, v4
	v_fma_f32 v5, v125, v77, v5
	v_fma_f32 v6, v126, v78, v6
	v_fma_f32 v7, v127, v79, v7
	v_fma_f32 v8, v128, v80, v8
	v_fma_f32 v9, v129, v81, v9
	v_fma_f32 v10, v130, v82, v10
	v_fma_f32 v11, v131, v83, v11
	v_fma_f32 v12, v132, v84, v12
	v_fma_f32 v13, v133, v85, v13
	v_fma_f32 v14, v134, v86, v14
	v_fma_f32 v15, v135, v87, v15
	v_cvt_pk_bf16_f32 v156, v0, v1
	v_cvt_pk_bf16_f32 v157, v2, v3
	v_cvt_pk_bf16_f32 v158, v4, v5
	v_cvt_pk_bf16_f32 v159, v6, v7
	v_cvt_pk_bf16_f32 v160, v8, v9
	v_cvt_pk_bf16_f32 v161, v10, v11
	v_cvt_pk_bf16_f32 v162, v12, v13
	v_cvt_pk_bf16_f32 v163, v14, v15
	s_lshl_b32 vcc_lo, s19, 11
	s_add_u32 vcc_lo, vcc_lo, 0x3000000
	s_add_u32 s100, s16, vcc_lo
	s_addc_u32 s101, s17, 0
	global_store_dwordx2 v137, v[156:157], s[100:101] offset:0
	global_store_dwordx2 v137, v[158:159], s[100:101] offset:512
	global_store_dwordx2 v137, v[160:161], s[100:101] offset:1024
; __device__ __forceinline__ float bf2f(u16 h) { return __uint_as_float(((unsigned)h) << 16); }
; __device__ __forceinline__ void row_phase(const Params& P, int glayer, int layer, int xsrc, bool hasY, int gate_idx, const float* gpost,
;                           int xdst, bool doH, const float* gpre, int sh_idx, int nrows) {
;     ...
;             const uint2 raw = yy[u][i];
;             yv[i].x = bf2f((u16)(raw.x & 0xffff)); yv[i].y = bf2f((u16)(raw.x >> 16));
;             yv[i].z = bf2f((u16)(raw.y & 0xffff)); yv[i].w = bf2f((u16)(raw.y >> 16));
;             ss += yv[i].x * yv[i].x + yv[i].y * yv[i].y + yv[i].z * yv[i].z + yv[i].w * yv[i].w;
;           }
;           ss = wave_sum(ss);
;           const float rstd = __builtin_amdgcn_rsqf(ss * (1.f / 1024.f) + EPSF);
; #pragma unroll
;           for (int i = 0; i < 4; ++i) {
;             const int col = (i * 64 + lane) * 4;
;             const float4 gt = *reinterpret_cast<const float4*>(modg + gate_idx * 1024 + col);
;             const float4 gp = *reinterpret_cast<const float4*>(gpost + col);
;             xv[i].x += gt.x * (yv[i].x * rstd * gp.x); xv[i].y += gt.y * (yv[i].y * rstd * gp.y);
;             xv[i].z += gt.z * (yv[i].z * rstd * gp.z); xv[i].w += gt.w * (yv[i].w * rstd * gp.w);
;           }
;     ...
;           for (int i = 0; i < 4; ++i) ss += xv[i].x * xv[i].x + xv[i].y * xv[i].y + xv[i].z * xv[i].z + xv[i].w * xv[i].w;
;           ss = wave_sum(ss);
;           const float rstd = __builtin_amdgcn_rsqf(ss * (1.f / 1024.f) + EPSF);
;           u16* h = P.hy + (long)row * 1024;
; #pragma unroll
;           for (int i = 0; i < 4; ++i) {
;             const int col = (i * 64 + lane) * 4;
;             const float4 g = *reinterpret_cast<const float4*>(gpre + col);
;             const float4 sh = *reinterpret_cast<const float4*>(modp + sh_idx * 1024 + col);
;             const float4 sc = *reinterpret_cast<const float4*>(modp + (sh_idx + 1) * 1024 + col);
;             const unsigned h0 = f2bf(xv[i].x * rstd * g.x * (1.f + sc.x) + sh.x);
;             const unsigned h1 = f2bf(xv[i].y * rstd * g.y * (1.f + sc.y) + sh.y);
;             const unsigned h2 = f2bf(xv[i].z * rstd * g.z * (1.f + sc.z) + sh.z);
;             const unsigned h3 = f2bf(xv[i].w * rstd * g.w * (1.f + sc.w) + sh.w);
;             *reinterpret_cast<uint2*>(h + col) = make_uint2(h0 | (h1 << 16), h2 | (h3 << 16));
;           }
	global_store_dwordx2 v137, v[162:163], s[100:101] offset:1536
	v_mul_f32_e32 v138, v0, v0
	v_mul_f32_e32 v149, v1, v1
	v_mul_f32_e32 v150, v2, v2
	v_mul_f32_e32 v154, v3, v3
	v_fma_f32 v138, v4, v4, v138
	v_fma_f32 v149, v5, v5, v149
	v_fma_f32 v150, v6, v6, v150
	v_fma_f32 v154, v7, v7, v154
	v_fma_f32 v138, v8, v8, v138
	v_fma_f32 v149, v9, v9, v149
	v_fma_f32 v150, v10, v10, v150
	v_fma_f32 v154, v11, v11, v154
	v_fma_f32 v138, v12, v12, v138
	v_fma_f32 v149, v13, v13, v149
	v_fma_f32 v150, v14, v14, v150
	v_fma_f32 v154, v15, v15, v154
	v_add_f32_e32 v138, v138, v149
	v_add_f32_e32 v150, v150, v154
	v_add_f32_e32 v138, v138, v150
	s_nop 1
	v_add_f32_dpp v138, v138, v138 quad_perm:[1,0,3,2] row_mask:0xf bank_mask:0xf
	s_nop 1
	v_add_f32_dpp v138, v138, v138 quad_perm:[2,3,0,1] row_mask:0xf bank_mask:0xf
	s_nop 1
	v_add_f32_dpp v138, v138, v138 row_half_mirror row_mask:0xf bank_mask:0xf
	s_nop 1
	v_add_f32_dpp v138, v138, v138 row_mirror row_mask:0xf bank_mask:0xf
	v_mov_b32_e32 v139, v138
	s_nop 1
	v_permlane16_swap_b32_e32 v138, v139
	v_add_f32_e32 v138, v138, v139
	v_mov_b32_e32 v139, v138
	s_nop 1
	v_permlane32_swap_b32_e32 v138, v139
	v_add_f32_e32 v138, v138, v139
	v_mul_f32_e32 v138, 0x3a800000, v138
	v_add_f32_e32 v138, 0x358637bd, v138
	v_rsq_f32_e32 v140, v138
	s_nop 0
	v_mul_f32_e32 v120, v0, v140
	v_mul_f32_e32 v121, v1, v140
	v_mul_f32_e32 v122, v2, v140
	v_mul_f32_e32 v123, v3, v140
	v_mul_f32_e32 v124, v4, v140
	v_mul_f32_e32 v125, v5, v140
	v_mul_f32_e32 v126, v6, v140
	v_mul_f32_e32 v127, v7, v140
	v_mul_f32_e32 v128, v8, v140
	v_mul_f32_e32 v129, v9, v140
	v_mul_f32_e32 v130, v10, v140
	v_mul_f32_e32 v131, v11, v140
	v_mul_f32_e32 v132, v12, v140
	v_mul_f32_e32 v133, v13, v140
	v_mul_f32_e32 v134, v14, v140
	v_mul_f32_e32 v135, v15, v140
	v_fma_f32 v120, v120, v88, v104
	v_fma_f32 v121, v121, v89, v105
	v_fma_f32 v122, v122, v90, v106
	v_fma_f32 v123, v123, v91, v107
	v_fma_f32 v124, v124, v92, v108
	v_fma_f32 v125, v125, v93, v109
	v_fma_f32 v126, v126, v94, v110
	v_fma_f32 v127, v127, v95, v111
	v_fma_f32 v128, v128, v96, v112
	v_fma_f32 v129, v129, v97, v113
	v_fma_f32 v130, v130, v98, v114
	v_fma_f32 v131, v131, v99, v115
	v_fma_f32 v132, v132, v100, v116
	v_fma_f32 v133, v133, v101, v117
	v_fma_f32 v134, v134, v102, v118
	v_fma_f32 v135, v135, v103, v119
	v_cvt_pk_bf16_f32 v156, v120, v121
	v_cvt_pk_bf16_f32 v157, v122, v123
	v_cvt_pk_bf16_f32 v158, v124, v125
	v_cvt_pk_bf16_f32 v159, v126, v127
	v_cvt_pk_bf16_f32 v160, v128, v129
	v_cvt_pk_bf16_f32 v161, v130, v131
	v_cvt_pk_bf16_f32 v162, v132, v133
	v_cvt_pk_bf16_f32 v163, v134, v135
	s_lshl_b32 vcc_lo, s19, 11
	s_add_u32 vcc_lo, vcc_lo, 0x3000000
	s_add_u32 s100, s14, vcc_lo
	s_addc_u32 s101, s15, 0
	global_store_dwordx2 v137, v[156:157], s[100:101] offset:0
	global_store_dwordx2 v137, v[158:159], s[100:101] offset:512
	global_store_dwordx2 v137, v[160:161], s[100:101] offset:1024
	global_store_dwordx2 v137, v[162:163], s[100:101] offset:1536
	v_lshlrev_b32_e32 v120, 16, v56
	v_and_b32_e32 v121, 0xffff0000, v56
	v_lshlrev_b32_e32 v122, 16, v57
	v_and_b32_e32 v123, 0xffff0000, v57
	v_lshlrev_b32_e32 v124, 16, v58
	v_and_b32_e32 v125, 0xffff0000, v58
	v_lshlrev_b32_e32 v126, 16, v59
	v_and_b32_e32 v127, 0xffff0000, v59
	v_lshlrev_b32_e32 v128, 16, v60
	v_and_b32_e32 v129, 0xffff0000, v60
	v_lshlrev_b32_e32 v130, 16, v61
	v_and_b32_e32 v131, 0xffff0000, v61
	v_lshlrev_b32_e32 v132, 16, v62
	v_and_b32_e32 v133, 0xffff0000, v62
	v_lshlrev_b32_e32 v134, 16, v63
	v_and_b32_e32 v135, 0xffff0000, v63
	v_mul_f32_e32 v138, v120, v120
	v_mul_f32_e32 v149, v121, v121
	v_mul_f32_e32 v150, v122, v122
	v_mul_f32_e32 v154, v123, v123
	v_fma_f32 v138, v124, v124, v138
	v_fma_f32 v149, v125, v125, v149
	v_fma_f32 v150, v126, v126, v150
	v_fma_f32 v154, v127, v127, v154
	v_fma_f32 v138, v128, v128, v138
	v_fma_f32 v149, v129, v129, v149
	v_fma_f32 v150, v130, v130, v150
	v_fma_f32 v154, v131, v131, v154
	v_fma_f32 v138, v132, v132, v138
	v_fma_f32 v149, v133, v133, v149
	v_fma_f32 v150, v134, v134, v150
	v_fma_f32 v154, v135, v135, v154
	v_add_f32_e32 v138, v138, v149
	v_add_f32_e32 v150, v150, v154
	v_add_f32_e32 v138, v138, v150
	s_nop 1
	v_add_f32_dpp v138, v138, v138 quad_perm:[1,0,3,2] row_mask:0xf bank_mask:0xf
	s_nop 1
	v_add_f32_dpp v138, v138, v138 quad_perm:[2,3,0,1] row_mask:0xf bank_mask:0xf
	s_nop 1
	v_add_f32_dpp v138, v138, v138 row_half_mirror row_mask:0xf bank_mask:0xf
	s_nop 1
	v_add_f32_dpp v138, v138, v138 row_mirror row_mask:0xf bank_mask:0xf
	v_mov_b32_e32 v139, v138
	s_nop 1
	v_permlane16_swap_b32_e32 v138, v139
	v_add_f32_e32 v138, v138, v139
	v_mov_b32_e32 v139, v138
	s_nop 1
	v_permlane32_swap_b32_e32 v138, v139
	v_add_f32_e32 v138, v138, v139
	v_mul_f32_e32 v138, 0x3a800000, v138
	v_add_f32_e32 v138, 0x358637bd, v138
	v_rsq_f32_e32 v140, v138
	v_lshlrev_b32_e32 v16, 16, v24
	v_and_b32_e32 v17, 0xffff0000, v24
	v_lshlrev_b32_e32 v18, 16, v25
	v_and_b32_e32 v19, 0xffff0000, v25
	v_lshlrev_b32_e32 v20, 16, v26
	v_and_b32_e32 v21, 0xffff0000, v26
	v_lshlrev_b32_e32 v22, 16, v27
	v_and_b32_e32 v23, 0xffff0000, v27
	v_lshlrev_b32_e32 v24, 16, v28
	v_and_b32_e32 v25, 0xffff0000, v28
	v_lshlrev_b32_e32 v26, 16, v29
	v_and_b32_e32 v27, 0xffff0000, v29
	v_lshlrev_b32_e32 v28, 16, v30
	v_and_b32_e32 v29, 0xffff0000, v30
	v_lshlrev_b32_e32 v30, 16, v31
	v_and_b32_e32 v31, 0xffff0000, v31
	s_nop 0
	v_mul_f32_e32 v120, v120, v140
	v_mul_f32_e32 v121, v121, v140
	v_mul_f32_e32 v122, v122, v140
	v_mul_f32_e32 v123, v123, v140
	v_mul_f32_e32 v124, v124, v140
	v_mul_f32_e32 v125, v125, v140
	v_mul_f32_e32 v126, v126, v140
	v_mul_f32_e32 v127, v127, v140
; __device__ __forceinline__ void row_phase(const Params& P, int glayer, int layer, int xsrc, bool hasY, int gate_idx, const float* gpost,
;                           int xdst, bool doH, const float* gpre, int sh_idx, int nrows) {
;     ...
; #pragma unroll
;           for (int i = 0; i < 4; ++i) {
;             const int col = (i * 64 + lane) * 4;
;             const float4 gt = *reinterpret_cast<const float4*>(modg + gate_idx * 1024 + col);
;             const float4 gp = *reinterpret_cast<const float4*>(gpost + col);
;             xv[i].x += gt.x * (yv[i].x * rstd * gp.x); xv[i].y += gt.y * (yv[i].y * rstd * gp.y);
;             xv[i].z += gt.z * (yv[i].z * rstd * gp.z); xv[i].w += gt.w * (yv[i].w * rstd * gp.w);
;           }
;         }
;         if (xdst == 3 || (xdst == 1 && row >= N_X)) {
;           float* xout = (xdst == 3) ? P.out + (long)row * 1024 : P.xc + (long)(row - N_X) * 1024;
; #pragma unroll
;           for (int i = 0; i < 4; ++i) *reinterpret_cast<float4*>(xout + (i * 64 + lane) * 4) = xv[i];
;         } else if (xdst != 0) {
;           u16* xo = ((xdst == 1) ? resA : P.zf) + (long)row * 1024;
; #pragma unroll
;           for (int i = 0; i < 4; ++i) {
;             const unsigned b0 = f2bf(xv[i].x), b1 = f2bf(xv[i].y), b2 = f2bf(xv[i].z), b3 = f2bf(xv[i].w);
;             *reinterpret_cast<uint2*>(xo + (i * 64 + lane) * 4) = make_uint2(b0 | (b1 << 16), b2 | (b3 << 16));
;           }
;         }
;         if (doH) {
;           float ss = 0.f;
; #pragma unroll
;           for (int i = 0; i < 4; ++i) ss += xv[i].x * xv[i].x + xv[i].y * xv[i].y + xv[i].z * xv[i].z + xv[i].w * xv[i].w;
;           ss = wave_sum(ss);
;           const float rstd = __builtin_amdgcn_rsqf(ss * (1.f / 1024.f) + EPSF);
;           u16* h = P.hy + (long)row * 1024;
; #pragma unroll
;           for (int i = 0; i < 4; ++i) {
;             const int col = (i * 64 + lane) * 4;
;             const float4 g = *reinterpret_cast<const float4*>(gpre + col);
;             const float4 sh = *reinterpret_cast<const float4*>(modp + sh_idx * 1024 + col);
;             const float4 sc = *reinterpret_cast<const float4*>(modp + (sh_idx + 1) * 1024 + col);
;             const unsigned h0 = f2bf(xv[i].x * rstd * g.x * (1.f + sc.x) + sh.x);
;             const unsigned h1 = f2bf(xv[i].y * rstd * g.y * (1.f + sc.y) + sh.y);
	v_mul_f32_e32 v128, v128, v140
	v_mul_f32_e32 v129, v129, v140
	v_mul_f32_e32 v130, v130, v140
	v_mul_f32_e32 v131, v131, v140
	v_mul_f32_e32 v132, v132, v140
	v_mul_f32_e32 v133, v133, v140
	v_mul_f32_e32 v134, v134, v140
	v_mul_f32_e32 v135, v135, v140
	v_fma_f32 v16, v120, v72, v16
	v_fma_f32 v17, v121, v73, v17
	v_fma_f32 v18, v122, v74, v18
	v_fma_f32 v19, v123, v75, v19
	v_fma_f32 v20, v124, v76, v20
	v_fma_f32 v21, v125, v77, v21
	v_fma_f32 v22, v126, v78, v22
	v_fma_f32 v23, v127, v79, v23
	v_fma_f32 v24, v128, v80, v24
	v_fma_f32 v25, v129, v81, v25
	v_fma_f32 v26, v130, v82, v26
	v_fma_f32 v27, v131, v83, v27
	v_fma_f32 v28, v132, v84, v28
	v_fma_f32 v29, v133, v85, v29
	v_fma_f32 v30, v134, v86, v30
	v_fma_f32 v31, v135, v87, v31
	v_cvt_pk_bf16_f32 v156, v16, v17
	v_cvt_pk_bf16_f32 v157, v18, v19
	v_cvt_pk_bf16_f32 v158, v20, v21
	v_cvt_pk_bf16_f32 v159, v22, v23
	v_cvt_pk_bf16_f32 v160, v24, v25
	v_cvt_pk_bf16_f32 v161, v26, v27
	v_cvt_pk_bf16_f32 v162, v28, v29
	v_cvt_pk_bf16_f32 v163, v30, v31
	s_lshl_b32 vcc_lo, s19, 11
	s_add_u32 vcc_lo, vcc_lo, 0x3400000
	s_add_u32 s100, s16, vcc_lo
	s_addc_u32 s101, s17, 0
	global_store_dwordx2 v137, v[156:157], s[100:101] offset:0
	global_store_dwordx2 v137, v[158:159], s[100:101] offset:512
	global_store_dwordx2 v137, v[160:161], s[100:101] offset:1024
	global_store_dwordx2 v137, v[162:163], s[100:101] offset:1536
	v_mul_f32_e32 v138, v16, v16
	v_mul_f32_e32 v149, v17, v17
	v_mul_f32_e32 v150, v18, v18
	v_mul_f32_e32 v154, v19, v19
	v_fma_f32 v138, v20, v20, v138
	v_fma_f32 v149, v21, v21, v149
	v_fma_f32 v150, v22, v22, v150
	v_fma_f32 v154, v23, v23, v154
	v_fma_f32 v138, v24, v24, v138
	v_fma_f32 v149, v25, v25, v149
	v_fma_f32 v150, v26, v26, v150
	v_fma_f32 v154, v27, v27, v154
	v_fma_f32 v138, v28, v28, v138
	v_fma_f32 v149, v29, v29, v149
	v_fma_f32 v150, v30, v30, v150
	v_fma_f32 v154, v31, v31, v154
	v_add_f32_e32 v138, v138, v149
	v_add_f32_e32 v150, v150, v154
	v_add_f32_e32 v138, v138, v150
	s_nop 1
	v_add_f32_dpp v138, v138, v138 quad_perm:[1,0,3,2] row_mask:0xf bank_mask:0xf
	s_nop 1
	v_add_f32_dpp v138, v138, v138 quad_perm:[2,3,0,1] row_mask:0xf bank_mask:0xf
	s_nop 1
	v_add_f32_dpp v138, v138, v138 row_half_mirror row_mask:0xf bank_mask:0xf
	s_nop 1
	v_add_f32_dpp v138, v138, v138 row_mirror row_mask:0xf bank_mask:0xf
	v_mov_b32_e32 v139, v138
	s_nop 1
	v_permlane16_swap_b32_e32 v138, v139
	v_add_f32_e32 v138, v138, v139
	v_mov_b32_e32 v139, v138
	s_nop 1
	v_permlane32_swap_b32_e32 v138, v139
	v_add_f32_e32 v138, v138, v139
	v_mul_f32_e32 v138, 0x3a800000, v138
	v_add_f32_e32 v138, 0x358637bd, v138
	v_rsq_f32_e32 v140, v138
	s_nop 0
	v_mul_f32_e32 v120, v16, v140
	v_mul_f32_e32 v121, v17, v140
	v_mul_f32_e32 v122, v18, v140
	v_mul_f32_e32 v123, v19, v140
	v_mul_f32_e32 v124, v20, v140
	v_mul_f32_e32 v125, v21, v140
	v_mul_f32_e32 v126, v22, v140
	v_mul_f32_e32 v127, v23, v140
	v_mul_f32_e32 v128, v24, v140
	v_mul_f32_e32 v129, v25, v140
	v_mul_f32_e32 v130, v26, v140
	v_mul_f32_e32 v131, v27, v140
	v_mul_f32_e32 v132, v28, v140
	v_mul_f32_e32 v133, v29, v140
	v_mul_f32_e32 v134, v30, v140
	v_mul_f32_e32 v135, v31, v140
	v_fma_f32 v120, v120, v88, v104
	v_fma_f32 v121, v121, v89, v105
	v_fma_f32 v122, v122, v90, v106
	v_fma_f32 v123, v123, v91, v107
	v_fma_f32 v124, v124, v92, v108
	v_fma_f32 v125, v125, v93, v109
	v_fma_f32 v126, v126, v94, v110
	v_fma_f32 v127, v127, v95, v111
	v_fma_f32 v128, v128, v96, v112
	v_fma_f32 v129, v129, v97, v113
	v_fma_f32 v130, v130, v98, v114
	v_fma_f32 v131, v131, v99, v115
	v_fma_f32 v132, v132, v100, v116
	v_fma_f32 v133, v133, v101, v117
	v_fma_f32 v134, v134, v102, v118
	v_fma_f32 v135, v135, v103, v119
	v_cvt_pk_bf16_f32 v156, v120, v121
	v_cvt_pk_bf16_f32 v157, v122, v123
	v_cvt_pk_bf16_f32 v158, v124, v125
	v_cvt_pk_bf16_f32 v159, v126, v127
	v_cvt_pk_bf16_f32 v160, v128, v129
	v_cvt_pk_bf16_f32 v161, v130, v131
	v_cvt_pk_bf16_f32 v162, v132, v133
	v_cvt_pk_bf16_f32 v163, v134, v135
	s_lshl_b32 vcc_lo, s19, 11
	s_add_u32 vcc_lo, vcc_lo, 0x3400000
	s_add_u32 s100, s14, vcc_lo
	s_addc_u32 s101, s15, 0
	global_store_dwordx2 v137, v[156:157], s[100:101] offset:0
	global_store_dwordx2 v137, v[158:159], s[100:101] offset:512
	global_store_dwordx2 v137, v[160:161], s[100:101] offset:1024
	global_store_dwordx2 v137, v[162:163], s[100:101] offset:1536
	v_lshlrev_b32_e32 v120, 16, v64
	v_and_b32_e32 v121, 0xffff0000, v64
	v_lshlrev_b32_e32 v122, 16, v65
	v_and_b32_e32 v123, 0xffff0000, v65
	v_lshlrev_b32_e32 v124, 16, v66
	v_and_b32_e32 v125, 0xffff0000, v66
	v_lshlrev_b32_e32 v126, 16, v67
	v_and_b32_e32 v127, 0xffff0000, v67
	v_lshlrev_b32_e32 v128, 16, v68
	v_and_b32_e32 v129, 0xffff0000, v68
	v_lshlrev_b32_e32 v130, 16, v69
	v_and_b32_e32 v131, 0xffff0000, v69
	v_lshlrev_b32_e32 v132, 16, v70
	v_and_b32_e32 v133, 0xffff0000, v70
	v_lshlrev_b32_e32 v134, 16, v71
	v_and_b32_e32 v135, 0xffff0000, v71
	v_mul_f32_e32 v138, v120, v120
	v_mul_f32_e32 v149, v121, v121
	v_mul_f32_e32 v150, v122, v122
	v_mul_f32_e32 v154, v123, v123
	v_fma_f32 v138, v124, v124, v138
	v_fma_f32 v149, v125, v125, v149
	v_fma_f32 v150, v126, v126, v150
	v_fma_f32 v154, v127, v127, v154
	v_fma_f32 v138, v128, v128, v138
	v_fma_f32 v149, v129, v129, v149
	v_fma_f32 v150, v130, v130, v150
	v_fma_f32 v154, v131, v131, v154
	v_fma_f32 v138, v132, v132, v138
	v_fma_f32 v149, v133, v133, v149
	v_fma_f32 v150, v134, v134, v150
	v_fma_f32 v154, v135, v135, v154
	v_add_f32_e32 v138, v138, v149
	v_add_f32_e32 v150, v150, v154
	v_add_f32_e32 v138, v138, v150
	s_nop 1
	v_add_f32_dpp v138, v138, v138 quad_perm:[1,0,3,2] row_mask:0xf bank_mask:0xf
	s_nop 1
; __device__ __forceinline__ void row_phase(const Params& P, int glayer, int layer, int xsrc, bool hasY, int gate_idx, const float* gpost,
;                           int xdst, bool doH, const float* gpre, int sh_idx, int nrows) {
;     ...
;             const uint2 raw = yy[u][i];
;             yv[i].x = bf2f((u16)(raw.x & 0xffff)); yv[i].y = bf2f((u16)(raw.x >> 16));
;             yv[i].z = bf2f((u16)(raw.y & 0xffff)); yv[i].w = bf2f((u16)(raw.y >> 16));
;             ss += yv[i].x * yv[i].x + yv[i].y * yv[i].y + yv[i].z * yv[i].z + yv[i].w * yv[i].w;
;           }
;           ss = wave_sum(ss);
;           const float rstd = __builtin_amdgcn_rsqf(ss * (1.f / 1024.f) + EPSF);
; #pragma unroll
;           for (int i = 0; i < 4; ++i) {
;             const int col = (i * 64 + lane) * 4;
;             const float4 gt = *reinterpret_cast<const float4*>(modg + gate_idx * 1024 + col);
;             const float4 gp = *reinterpret_cast<const float4*>(gpost + col);
;             xv[i].x += gt.x * (yv[i].x * rstd * gp.x); xv[i].y += gt.y * (yv[i].y * rstd * gp.y);
;             xv[i].z += gt.z * (yv[i].z * rstd * gp.z); xv[i].w += gt.w * (yv[i].w * rstd * gp.w);
;           }
;         }
;         if (xdst == 3 || (xdst == 1 && row >= N_X)) {
;           float* xout = (xdst == 3) ? P.out + (long)row * 1024 : P.xc + (long)(row - N_X) * 1024;
; #pragma unroll
;           for (int i = 0; i < 4; ++i) *reinterpret_cast<float4*>(xout + (i * 64 + lane) * 4) = xv[i];
;         } else if (xdst != 0) {
;           u16* xo = ((xdst == 1) ? resA : P.zf) + (long)row * 1024;
; #pragma unroll
;           for (int i = 0; i < 4; ++i) {
;             const unsigned b0 = f2bf(xv[i].x), b1 = f2bf(xv[i].y), b2 = f2bf(xv[i].z), b3 = f2bf(xv[i].w);
;             *reinterpret_cast<uint2*>(xo + (i * 64 + lane) * 4) = make_uint2(b0 | (b1 << 16), b2 | (b3 << 16));
;           }
;         }
;         if (doH) {
;           float ss = 0.f;
; #pragma unroll
;           for (int i = 0; i < 4; ++i) ss += xv[i].x * xv[i].x + xv[i].y * xv[i].y + xv[i].z * xv[i].z + xv[i].w * xv[i].w;
;           ss = wave_sum(ss);
;           const float rstd = __builtin_amdgcn_rsqf(ss * (1.f / 1024.f) + EPSF);
;           u16* h = P.hy + (long)row * 1024;
; #pragma unroll
;           for (int i = 0; i < 4; ++i) {
;             const int col = (i * 64 + lane) * 4;
	v_add_f32_dpp v138, v138, v138 quad_perm:[2,3,0,1] row_mask:0xf bank_mask:0xf
	s_nop 1
	v_add_f32_dpp v138, v138, v138 row_half_mirror row_mask:0xf bank_mask:0xf
	s_nop 1
	v_add_f32_dpp v138, v138, v138 row_mirror row_mask:0xf bank_mask:0xf
	v_mov_b32_e32 v139, v138
	s_nop 1
	v_permlane16_swap_b32_e32 v138, v139
	v_add_f32_e32 v138, v138, v139
	v_mov_b32_e32 v139, v138
	s_nop 1
	v_permlane32_swap_b32_e32 v138, v139
	v_add_f32_e32 v138, v138, v139
	v_mul_f32_e32 v138, 0x3a800000, v138
	v_add_f32_e32 v138, 0x358637bd, v138
	v_rsq_f32_e32 v140, v138
	v_lshlrev_b32_e32 v32, 16, v40
	v_and_b32_e32 v33, 0xffff0000, v40
	v_lshlrev_b32_e32 v34, 16, v41
	v_and_b32_e32 v35, 0xffff0000, v41
	v_lshlrev_b32_e32 v36, 16, v42
	v_and_b32_e32 v37, 0xffff0000, v42
	v_lshlrev_b32_e32 v38, 16, v43
	v_and_b32_e32 v39, 0xffff0000, v43
	v_lshlrev_b32_e32 v40, 16, v44
	v_and_b32_e32 v41, 0xffff0000, v44
	v_lshlrev_b32_e32 v42, 16, v45
	v_and_b32_e32 v43, 0xffff0000, v45
	v_lshlrev_b32_e32 v44, 16, v46
	v_and_b32_e32 v45, 0xffff0000, v46
	v_lshlrev_b32_e32 v46, 16, v47
	v_and_b32_e32 v47, 0xffff0000, v47
	s_nop 0
	v_mul_f32_e32 v120, v120, v140
	v_mul_f32_e32 v121, v121, v140
	v_mul_f32_e32 v122, v122, v140
	v_mul_f32_e32 v123, v123, v140
	v_mul_f32_e32 v124, v124, v140
	v_mul_f32_e32 v125, v125, v140
	v_mul_f32_e32 v126, v126, v140
	v_mul_f32_e32 v127, v127, v140
	v_mul_f32_e32 v128, v128, v140
	v_mul_f32_e32 v129, v129, v140
	v_mul_f32_e32 v130, v130, v140
	v_mul_f32_e32 v131, v131, v140
	v_mul_f32_e32 v132, v132, v140
	v_mul_f32_e32 v133, v133, v140
	v_mul_f32_e32 v134, v134, v140
	v_mul_f32_e32 v135, v135, v140
	v_fma_f32 v32, v120, v72, v32
	v_fma_f32 v33, v121, v73, v33
	v_fma_f32 v34, v122, v74, v34
	v_fma_f32 v35, v123, v75, v35
	v_fma_f32 v36, v124, v76, v36
	v_fma_f32 v37, v125, v77, v37
	v_fma_f32 v38, v126, v78, v38
	v_fma_f32 v39, v127, v79, v39
	v_fma_f32 v40, v128, v80, v40
	v_fma_f32 v41, v129, v81, v41
	v_fma_f32 v42, v130, v82, v42
	v_fma_f32 v43, v131, v83, v43
	v_fma_f32 v44, v132, v84, v44
	v_fma_f32 v45, v133, v85, v45
	v_fma_f32 v46, v134, v86, v46
	v_fma_f32 v47, v135, v87, v47
	v_cvt_pk_bf16_f32 v156, v32, v33
	v_cvt_pk_bf16_f32 v157, v34, v35
	v_cvt_pk_bf16_f32 v158, v36, v37
	v_cvt_pk_bf16_f32 v159, v38, v39
	v_cvt_pk_bf16_f32 v160, v40, v41
	v_cvt_pk_bf16_f32 v161, v42, v43
	v_cvt_pk_bf16_f32 v162, v44, v45
	v_cvt_pk_bf16_f32 v163, v46, v47
	s_lshl_b32 vcc_lo, s19, 11
	s_add_u32 vcc_lo, vcc_lo, 0x3800000
	s_add_u32 s100, s16, vcc_lo
	s_addc_u32 s101, s17, 0
	global_store_dwordx2 v137, v[156:157], s[100:101] offset:0
	global_store_dwordx2 v137, v[158:159], s[100:101] offset:512
	global_store_dwordx2 v137, v[160:161], s[100:101] offset:1024
	global_store_dwordx2 v137, v[162:163], s[100:101] offset:1536
	v_mul_f32_e32 v138, v32, v32
	v_mul_f32_e32 v149, v33, v33
	v_mul_f32_e32 v150, v34, v34
	v_mul_f32_e32 v154, v35, v35
	v_fma_f32 v138, v36, v36, v138
	v_fma_f32 v149, v37, v37, v149
	v_fma_f32 v150, v38, v38, v150
	v_fma_f32 v154, v39, v39, v154
	v_fma_f32 v138, v40, v40, v138
	v_fma_f32 v149, v41, v41, v149
	v_fma_f32 v150, v42, v42, v150
	v_fma_f32 v154, v43, v43, v154
	v_fma_f32 v138, v44, v44, v138
	v_fma_f32 v149, v45, v45, v149
	v_fma_f32 v150, v46, v46, v150
	v_fma_f32 v154, v47, v47, v154
	v_add_f32_e32 v138, v138, v149
	v_add_f32_e32 v150, v150, v154
	v_add_f32_e32 v138, v138, v150
	s_nop 1
	v_add_f32_dpp v138, v138, v138 quad_perm:[1,0,3,2] row_mask:0xf bank_mask:0xf
	s_nop 1
	v_add_f32_dpp v138, v138, v138 quad_perm:[2,3,0,1] row_mask:0xf bank_mask:0xf
	s_nop 1
	v_add_f32_dpp v138, v138, v138 row_half_mirror row_mask:0xf bank_mask:0xf
	s_nop 1
	v_add_f32_dpp v138, v138, v138 row_mirror row_mask:0xf bank_mask:0xf
	v_mov_b32_e32 v139, v138
	s_nop 1
	v_permlane16_swap_b32_e32 v138, v139
	v_add_f32_e32 v138, v138, v139
	v_mov_b32_e32 v139, v138
	s_nop 1
	v_permlane32_swap_b32_e32 v138, v139
	v_add_f32_e32 v138, v138, v139
	v_mul_f32_e32 v138, 0x3a800000, v138
	v_add_f32_e32 v138, 0x358637bd, v138
	v_rsq_f32_e32 v140, v138
	s_nop 0
	v_mul_f32_e32 v120, v32, v140
	v_mul_f32_e32 v121, v33, v140
	v_mul_f32_e32 v122, v34, v140
	v_mul_f32_e32 v123, v35, v140
	v_mul_f32_e32 v124, v36, v140
	v_mul_f32_e32 v125, v37, v140
	v_mul_f32_e32 v126, v38, v140
	v_mul_f32_e32 v127, v39, v140
	v_mul_f32_e32 v128, v40, v140
	v_mul_f32_e32 v129, v41, v140
	v_mul_f32_e32 v130, v42, v140
	v_mul_f32_e32 v131, v43, v140
	v_mul_f32_e32 v132, v44, v140
	v_mul_f32_e32 v133, v45, v140
	v_mul_f32_e32 v134, v46, v140
	v_mul_f32_e32 v135, v47, v140
	v_fma_f32 v120, v120, v88, v104
	v_fma_f32 v121, v121, v89, v105
	v_fma_f32 v122, v122, v90, v106
	v_fma_f32 v123, v123, v91, v107
	v_fma_f32 v124, v124, v92, v108
	v_fma_f32 v125, v125, v93, v109
	v_fma_f32 v126, v126, v94, v110
	v_fma_f32 v127, v127, v95, v111
	v_fma_f32 v128, v128, v96, v112
	v_fma_f32 v129, v129, v97, v113
	v_fma_f32 v130, v130, v98, v114
	v_fma_f32 v131, v131, v99, v115
	v_fma_f32 v132, v132, v100, v116
	v_fma_f32 v133, v133, v101, v117
	v_fma_f32 v134, v134, v102, v118
	v_fma_f32 v135, v135, v103, v119
	v_cvt_pk_bf16_f32 v156, v120, v121
	v_cvt_pk_bf16_f32 v157, v122, v123
	v_cvt_pk_bf16_f32 v158, v124, v125
	v_cvt_pk_bf16_f32 v159, v126, v127
	v_cvt_pk_bf16_f32 v160, v128, v129
	v_cvt_pk_bf16_f32 v161, v130, v131
	v_cvt_pk_bf16_f32 v162, v132, v133
	v_cvt_pk_bf16_f32 v163, v134, v135
	s_lshl_b32 vcc_lo, s19, 11
	s_add_u32 vcc_lo, vcc_lo, 0x3800000
	s_add_u32 s100, s14, vcc_lo
	s_addc_u32 s101, s15, 0
	global_store_dwordx2 v137, v[156:157], s[100:101] offset:0
	global_store_dwordx2 v137, v[158:159], s[100:101] offset:512
	global_store_dwordx2 v137, v[160:161], s[100:101] offset:1024
	global_store_dwordx2 v137, v[162:163], s[100:101] offset:1536
	s_waitcnt vmcnt(24)
; __device__ __forceinline__ void row_phase(const Params& P, int glayer, int layer, int xsrc, bool hasY, int gate_idx, const float* gpost,
;                           int xdst, bool doH, const float* gpre, int sh_idx, int nrows) {
;     ...
;         if (hasY) {
;           float4 yv[4];
;           float ss = 0.f;
; #pragma unroll
;           for (int i = 0; i < 4; ++i) {
;             const uint2 raw = yy[u][i];
;             yv[i].x = bf2f((u16)(raw.x & 0xffff)); yv[i].y = bf2f((u16)(raw.x >> 16));
;             yv[i].z = bf2f((u16)(raw.y & 0xffff)); yv[i].w = bf2f((u16)(raw.y >> 16));
;             ss += yv[i].x * yv[i].x + yv[i].y * yv[i].y + yv[i].z * yv[i].z + yv[i].w * yv[i].w;
;           }
;           ss = wave_sum(ss);
;           const float rstd = __builtin_amdgcn_rsqf(ss * (1.f / 1024.f) + EPSF);
; #pragma unroll
;           for (int i = 0; i < 4; ++i) {
;             const int col = (i * 64 + lane) * 4;
;             const float4 gt = *reinterpret_cast<const float4*>(modg + gate_idx * 1024 + col);
;             const float4 gp = *reinterpret_cast<const float4*>(gpost + col);
;             xv[i].x += gt.x * (yv[i].x * rstd * gp.x); xv[i].y += gt.y * (yv[i].y * rstd * gp.y);
;             xv[i].z += gt.z * (yv[i].z * rstd * gp.z); xv[i].w += gt.w * (yv[i].w * rstd * gp.w);
;           }
;         }
;         if (xdst == 3 || (xdst == 1 && row >= N_X)) {
;           float* xout = (xdst == 3) ? P.out + (long)row * 1024 : P.xc + (long)(row - N_X) * 1024;
; #pragma unroll
;           for (int i = 0; i < 4; ++i) *reinterpret_cast<float4*>(xout + (i * 64 + lane) * 4) = xv[i];
;         } else if (xdst != 0) {
;           u16* xo = ((xdst == 1) ? resA : P.zf) + (long)row * 1024;
; #pragma unroll
;           for (int i = 0; i < 4; ++i) {
;             const unsigned b0 = f2bf(xv[i].x), b1 = f2bf(xv[i].y), b2 = f2bf(xv[i].z), b3 = f2bf(xv[i].w);
;             *reinterpret_cast<uint2*>(xo + (i * 64 + lane) * 4) = make_uint2(b0 | (b1 << 16), b2 | (b3 << 16));
;           }
;         }
;         if (doH) {
;           float ss = 0.f;
; #pragma unroll
;           for (int i = 0; i < 4; ++i) ss += xv[i].x * xv[i].x + xv[i].y * xv[i].y + xv[i].z * xv[i].z + xv[i].w * xv[i].w;
;           ss = wave_sum(ss);
;           const float rstd = __builtin_amdgcn_rsqf(ss * (1.f / 1024.f) + EPSF);
;           u16* h = P.hy + (long)row * 1024;
; #pragma unroll
	v_lshlrev_b32_e32 v120, 16, v182
	v_and_b32_e32 v121, 0xffff0000, v182
	v_lshlrev_b32_e32 v122, 16, v183
	v_and_b32_e32 v123, 0xffff0000, v183
	v_lshlrev_b32_e32 v124, 16, v184
	v_and_b32_e32 v125, 0xffff0000, v184
	v_lshlrev_b32_e32 v126, 16, v185
	v_and_b32_e32 v127, 0xffff0000, v185
	v_lshlrev_b32_e32 v128, 16, v186
	v_and_b32_e32 v129, 0xffff0000, v186
	v_lshlrev_b32_e32 v130, 16, v187
	v_and_b32_e32 v131, 0xffff0000, v187
	v_lshlrev_b32_e32 v132, 16, v188
	v_and_b32_e32 v133, 0xffff0000, v188
	v_lshlrev_b32_e32 v134, 16, v189
	v_and_b32_e32 v135, 0xffff0000, v189
	v_mul_f32_e32 v138, v120, v120
	v_mul_f32_e32 v149, v121, v121
	v_mul_f32_e32 v150, v122, v122
	v_mul_f32_e32 v154, v123, v123
	v_fma_f32 v138, v124, v124, v138
	v_fma_f32 v149, v125, v125, v149
	v_fma_f32 v150, v126, v126, v150
	v_fma_f32 v154, v127, v127, v154
	v_fma_f32 v138, v128, v128, v138
	v_fma_f32 v149, v129, v129, v149
	v_fma_f32 v150, v130, v130, v150
	v_fma_f32 v154, v131, v131, v154
	v_fma_f32 v138, v132, v132, v138
	v_fma_f32 v149, v133, v133, v149
	v_fma_f32 v150, v134, v134, v150
	v_fma_f32 v154, v135, v135, v154
	v_add_f32_e32 v138, v138, v149
	v_add_f32_e32 v150, v150, v154
	v_add_f32_e32 v138, v138, v150
	s_nop 1
	v_add_f32_dpp v138, v138, v138 quad_perm:[1,0,3,2] row_mask:0xf bank_mask:0xf
	s_nop 1
	v_add_f32_dpp v138, v138, v138 quad_perm:[2,3,0,1] row_mask:0xf bank_mask:0xf
	s_nop 1
	v_add_f32_dpp v138, v138, v138 row_half_mirror row_mask:0xf bank_mask:0xf
	s_nop 1
	v_add_f32_dpp v138, v138, v138 row_mirror row_mask:0xf bank_mask:0xf
	v_mov_b32_e32 v139, v138
	s_nop 1
	v_permlane16_swap_b32_e32 v138, v139
	v_add_f32_e32 v138, v138, v139
	v_mov_b32_e32 v139, v138
	s_nop 1
	v_permlane32_swap_b32_e32 v138, v139
	v_add_f32_e32 v138, v138, v139
	v_mul_f32_e32 v138, 0x3a800000, v138
	v_add_f32_e32 v138, 0x358637bd, v138
	v_rsq_f32_e32 v140, v138
	v_lshlrev_b32_e32 v166, 16, v174
	v_and_b32_e32 v167, 0xffff0000, v174
	v_lshlrev_b32_e32 v168, 16, v175
	v_and_b32_e32 v169, 0xffff0000, v175
	v_lshlrev_b32_e32 v170, 16, v176
	v_and_b32_e32 v171, 0xffff0000, v176
	v_lshlrev_b32_e32 v172, 16, v177
	v_and_b32_e32 v173, 0xffff0000, v177
	v_lshlrev_b32_e32 v174, 16, v178
	v_and_b32_e32 v175, 0xffff0000, v178
	v_lshlrev_b32_e32 v176, 16, v179
	v_and_b32_e32 v177, 0xffff0000, v179
	v_lshlrev_b32_e32 v178, 16, v180
	v_and_b32_e32 v179, 0xffff0000, v180
	v_lshlrev_b32_e32 v180, 16, v181
	v_and_b32_e32 v181, 0xffff0000, v181
	s_nop 0
	v_mul_f32_e32 v120, v120, v140
	v_mul_f32_e32 v121, v121, v140
	v_mul_f32_e32 v122, v122, v140
	v_mul_f32_e32 v123, v123, v140
	v_mul_f32_e32 v124, v124, v140
	v_mul_f32_e32 v125, v125, v140
	v_mul_f32_e32 v126, v126, v140
	v_mul_f32_e32 v127, v127, v140
	v_mul_f32_e32 v128, v128, v140
	v_mul_f32_e32 v129, v129, v140
	v_mul_f32_e32 v130, v130, v140
	v_mul_f32_e32 v131, v131, v140
	v_mul_f32_e32 v132, v132, v140
	v_mul_f32_e32 v133, v133, v140
	v_mul_f32_e32 v134, v134, v140
	v_mul_f32_e32 v135, v135, v140
	v_fma_f32 v166, v120, v72, v166
	v_fma_f32 v167, v121, v73, v167
	v_fma_f32 v168, v122, v74, v168
	v_fma_f32 v169, v123, v75, v169
	v_fma_f32 v170, v124, v76, v170
	v_fma_f32 v171, v125, v77, v171
	v_fma_f32 v172, v126, v78, v172
	v_fma_f32 v173, v127, v79, v173
	v_fma_f32 v174, v128, v80, v174
	v_fma_f32 v175, v129, v81, v175
	v_fma_f32 v176, v130, v82, v176
	v_fma_f32 v177, v131, v83, v177
	v_fma_f32 v178, v132, v84, v178
	v_fma_f32 v179, v133, v85, v179
	v_fma_f32 v180, v134, v86, v180
	v_fma_f32 v181, v135, v87, v181
	v_cvt_pk_bf16_f32 v156, v166, v167
	v_cvt_pk_bf16_f32 v157, v168, v169
	v_cvt_pk_bf16_f32 v158, v170, v171
	v_cvt_pk_bf16_f32 v159, v172, v173
	v_cvt_pk_bf16_f32 v160, v174, v175
	v_cvt_pk_bf16_f32 v161, v176, v177
	v_cvt_pk_bf16_f32 v162, v178, v179
	v_cvt_pk_bf16_f32 v163, v180, v181
	s_lshl_b32 vcc_lo, s19, 11
	s_add_u32 vcc_lo, vcc_lo, 0x3c00000
	s_add_u32 s100, s16, vcc_lo
	s_addc_u32 s101, s17, 0
	global_store_dwordx2 v137, v[156:157], s[100:101] offset:0
	global_store_dwordx2 v137, v[158:159], s[100:101] offset:512
	global_store_dwordx2 v137, v[160:161], s[100:101] offset:1024
	global_store_dwordx2 v137, v[162:163], s[100:101] offset:1536
	v_mul_f32_e32 v138, v166, v166
	v_mul_f32_e32 v149, v167, v167
	v_mul_f32_e32 v150, v168, v168
	v_mul_f32_e32 v154, v169, v169
	v_fma_f32 v138, v170, v170, v138
	v_fma_f32 v149, v171, v171, v149
	v_fma_f32 v150, v172, v172, v150
	v_fma_f32 v154, v173, v173, v154
	v_fma_f32 v138, v174, v174, v138
	v_fma_f32 v149, v175, v175, v149
	v_fma_f32 v150, v176, v176, v150
	v_fma_f32 v154, v177, v177, v154
	v_fma_f32 v138, v178, v178, v138
	v_fma_f32 v149, v179, v179, v149
	v_fma_f32 v150, v180, v180, v150
	v_fma_f32 v154, v181, v181, v154
	v_add_f32_e32 v138, v138, v149
	v_add_f32_e32 v150, v150, v154
	v_add_f32_e32 v138, v138, v150
	s_nop 1
	v_add_f32_dpp v138, v138, v138 quad_perm:[1,0,3,2] row_mask:0xf bank_mask:0xf
	s_nop 1
	v_add_f32_dpp v138, v138, v138 quad_perm:[2,3,0,1] row_mask:0xf bank_mask:0xf
	s_nop 1
	v_add_f32_dpp v138, v138, v138 row_half_mirror row_mask:0xf bank_mask:0xf
	s_nop 1
	v_add_f32_dpp v138, v138, v138 row_mirror row_mask:0xf bank_mask:0xf
	v_mov_b32_e32 v139, v138
	s_nop 1
	v_permlane16_swap_b32_e32 v138, v139
	v_add_f32_e32 v138, v138, v139
	v_mov_b32_e32 v139, v138
	s_nop 1
	v_permlane32_swap_b32_e32 v138, v139
	v_add_f32_e32 v138, v138, v139
	v_mul_f32_e32 v138, 0x3a800000, v138
	v_add_f32_e32 v138, 0x358637bd, v138
	v_rsq_f32_e32 v140, v138
	s_nop 0
	v_mul_f32_e32 v120, v166, v140
	v_mul_f32_e32 v121, v167, v140
	v_mul_f32_e32 v122, v168, v140
	v_mul_f32_e32 v123, v169, v140
	v_mul_f32_e32 v124, v170, v140
	v_mul_f32_e32 v125, v171, v140
	v_mul_f32_e32 v126, v172, v140
; __device__ __forceinline__ void row_phase(const Params& P, int glayer, int layer, int xsrc, bool hasY, int gate_idx, const float* gpost,
;                           int xdst, bool doH, const float* gpre, int sh_idx, int nrows) {
;     ...
;           const float* xin_;
;           if (xsrc == 0) xin_ = R < N_X ? P.x + (long)R * 1024 : P.ctx + (long)(R - N_X) * 1024;
;           else           xin_ = P.xc + (long)(R - N_X) * 1024;
; #pragma unroll
;           for (int i = 0; i < 4; ++i) xr[u][i] = *reinterpret_cast<const uint4*>(xin_ + (i * 64 + lane) * 4);
;         }
;         if (hasY) {
;           const u16* y_ = P.hy + (long)R * 1024;
; #pragma unroll
;           for (int i = 0; i < 4; ++i) yy[u][i] = *reinterpret_cast<const uint2*>(y_ + (i * 64 + lane) * 4);
;         }
;       }
;     }
; #pragma unroll
;     for (int u = 0; u < 4; ++u) {
;       const int row = rb + u * stride;
;       if (row < nrows) {
;         const int mi = row < N_X ? (row >> 13) : 4;
;         const float* modp = P.mod + (long)(layer * 5 + mi) * 6144;
;         const float* modg = P.mod + (long)(glayer * 5 + mi) * 6144;
;         float4 xv[4];
;         if (xsrc != 0 && row < N_X) {
; #pragma unroll
;           for (int i = 0; i < 4; ++i) {
;             const uint4 raw = xr[u][i];
;             xv[i].x = bf2f((u16)(raw.x & 0xffff)); xv[i].y = bf2f((u16)(raw.x >> 16));
;     ...
;           const float rstd = __builtin_amdgcn_rsqf(ss * (1.f / 1024.f) + EPSF);
;           u16* h = P.hy + (long)row * 1024;
; #pragma unroll
;           for (int i = 0; i < 4; ++i) {
;             const int col = (i * 64 + lane) * 4;
;             const float4 g = *reinterpret_cast<const float4*>(gpre + col);
;             const float4 sh = *reinterpret_cast<const float4*>(modp + sh_idx * 1024 + col);
;             const float4 sc = *reinterpret_cast<const float4*>(modp + (sh_idx + 1) * 1024 + col);
;             const unsigned h0 = f2bf(xv[i].x * rstd * g.x * (1.f + sc.x) + sh.x);
;             const unsigned h1 = f2bf(xv[i].y * rstd * g.y * (1.f + sc.y) + sh.y);
;             const unsigned h2 = f2bf(xv[i].z * rstd * g.z * (1.f + sc.z) + sh.z);
;             const unsigned h3 = f2bf(xv[i].w * rstd * g.w * (1.f + sc.w) + sh.w);
;             *reinterpret_cast<uint2*>(h + col) = make_uint2(h0 | (h1 << 16), h2 | (h3 << 16));
;           }
	v_mul_f32_e32 v127, v173, v140
	v_mul_f32_e32 v128, v174, v140
	v_mul_f32_e32 v129, v175, v140
	v_mul_f32_e32 v130, v176, v140
	v_mul_f32_e32 v131, v177, v140
	v_mul_f32_e32 v132, v178, v140
	v_mul_f32_e32 v133, v179, v140
	v_mul_f32_e32 v134, v180, v140
	v_mul_f32_e32 v135, v181, v140
	v_fma_f32 v120, v120, v88, v104
	v_fma_f32 v121, v121, v89, v105
	v_fma_f32 v122, v122, v90, v106
	v_fma_f32 v123, v123, v91, v107
	v_fma_f32 v124, v124, v92, v108
	v_fma_f32 v125, v125, v93, v109
	v_fma_f32 v126, v126, v94, v110
	v_fma_f32 v127, v127, v95, v111
	v_fma_f32 v128, v128, v96, v112
	v_fma_f32 v129, v129, v97, v113
	v_fma_f32 v130, v130, v98, v114
	v_fma_f32 v131, v131, v99, v115
	v_fma_f32 v132, v132, v100, v116
	v_fma_f32 v133, v133, v101, v117
	v_fma_f32 v134, v134, v102, v118
	v_fma_f32 v135, v135, v103, v119
	v_cvt_pk_bf16_f32 v156, v120, v121
	v_cvt_pk_bf16_f32 v157, v122, v123
	v_cvt_pk_bf16_f32 v158, v124, v125
	v_cvt_pk_bf16_f32 v159, v126, v127
	v_cvt_pk_bf16_f32 v160, v128, v129
	v_cvt_pk_bf16_f32 v161, v130, v131
	v_cvt_pk_bf16_f32 v162, v132, v133
	v_cvt_pk_bf16_f32 v163, v134, v135
	s_lshl_b32 vcc_lo, s19, 11
	s_add_u32 vcc_lo, vcc_lo, 0x3c00000
	s_add_u32 s100, s14, vcc_lo
	s_addc_u32 s101, s15, 0
	global_store_dwordx2 v137, v[156:157], s[100:101] offset:0
	global_store_dwordx2 v137, v[158:159], s[100:101] offset:512
	global_store_dwordx2 v137, v[160:161], s[100:101] offset:1024
	global_store_dwordx2 v137, v[162:163], s[100:101] offset:1536
	s_waitcnt vmcnt(0)
	s_cmp_lt_u32 s19, 0x400
	s_cbranch_scc0 .Lmy_r10_done
	s_load_dwordx2 s[12:13], s[4:5], 0x138
	s_waitcnt lgkmcnt(0)
	s_add_u32 s100, s20, 0x1d000
	s_addc_u32 s101, s21, 0
	global_load_dwordx4 v[72:75], v136, s[100:101] offset:0
	global_load_dwordx4 v[76:79], v136, s[100:101] offset:1024
	global_load_dwordx4 v[80:83], v136, s[100:101] offset:2048
	global_load_dwordx4 v[84:87], v136, s[100:101] offset:3072
	s_load_dwordx2 s[98:99], s[4:5], 0x48
	s_waitcnt lgkmcnt(0)
	global_load_dwordx4 v[120:123], v136, s[98:99] offset:0
	global_load_dwordx4 v[124:127], v136, s[98:99] offset:1024
	global_load_dwordx4 v[128:131], v136, s[98:99] offset:2048
	global_load_dwordx4 v[132:135], v136, s[98:99] offset:3072
	s_add_u32 s100, s20, 0x36000
	s_addc_u32 s101, s21, 0
	global_load_dwordx4 v[104:107], v136, s[100:101] offset:0
	global_load_dwordx4 v[108:111], v136, s[100:101] offset:1024
	global_load_dwordx4 v[112:115], v136, s[100:101] offset:2048
	global_load_dwordx4 v[116:119], v136, s[100:101] offset:3072
	s_add_u32 s100, s100, 0x1000
	s_addc_u32 s101, s101, 0
	global_load_dwordx4 v[16:19], v136, s[100:101] offset:0
	global_load_dwordx4 v[20:23], v136, s[100:101] offset:1024
	global_load_dwordx4 v[24:27], v136, s[100:101] offset:2048
	global_load_dwordx4 v[28:31], v136, s[100:101] offset:3072
	s_load_dwordx2 s[98:99], s[4:5], 0x30
	s_waitcnt lgkmcnt(0)
	s_add_u32 s98, s98, 0x1000
	s_addc_u32 s99, s99, 0
	global_load_dwordx4 v[88:91], v136, s[98:99] offset:0
	global_load_dwordx4 v[92:95], v136, s[98:99] offset:1024
	global_load_dwordx4 v[96:99], v136, s[98:99] offset:2048
	global_load_dwordx4 v[100:103], v136, s[98:99] offset:3072
	s_waitcnt vmcnt(0)
	v_mul_f32_e32 v72, v72, v120
	v_mul_f32_e32 v73, v73, v121
	v_mul_f32_e32 v74, v74, v122
	v_mul_f32_e32 v75, v75, v123
	v_mul_f32_e32 v76, v76, v124
	v_mul_f32_e32 v77, v77, v125
	v_mul_f32_e32 v78, v78, v126
	v_mul_f32_e32 v79, v79, v127
	v_mul_f32_e32 v80, v80, v128
	v_mul_f32_e32 v81, v81, v129
	v_mul_f32_e32 v82, v82, v130
	v_mul_f32_e32 v83, v83, v131
	v_mul_f32_e32 v84, v84, v132
	v_mul_f32_e32 v85, v85, v133
	v_mul_f32_e32 v86, v86, v134
	v_mul_f32_e32 v87, v87, v135
	v_fma_f32 v88, v88, v16, v88
	v_fma_f32 v89, v89, v17, v89
	v_fma_f32 v90, v90, v18, v90
	v_fma_f32 v91, v91, v19, v91
	v_fma_f32 v92, v92, v20, v92
	v_fma_f32 v93, v93, v21, v93
	v_fma_f32 v94, v94, v22, v94
	v_fma_f32 v95, v95, v23, v95
	v_fma_f32 v96, v96, v24, v96
	v_fma_f32 v97, v97, v25, v97
	v_fma_f32 v98, v98, v26, v98
	v_fma_f32 v99, v99, v27, v99
	v_fma_f32 v100, v100, v28, v100
	v_fma_f32 v101, v101, v29, v101
	v_fma_f32 v102, v102, v30, v102
	v_fma_f32 v103, v103, v31, v103
	s_lshl_b32 vcc_lo, s19, 12
	s_add_u32 s100, s12, vcc_lo
	s_addc_u32 s101, s13, 0
	global_load_dwordx4 v[0:3], v136, s[100:101] offset:0
	global_load_dwordx4 v[4:7], v136, s[100:101] offset:1024
	global_load_dwordx4 v[8:11], v136, s[100:101] offset:2048
	global_load_dwordx4 v[12:15], v136, s[100:101] offset:3072
	s_load_dwordx2 s[98:99], s[4:5], 0x158
	s_waitcnt lgkmcnt(0)
	s_lshl_b32 vcc_lo, s19, 12
	s_add_u32 s100, s98, vcc_lo
	s_addc_u32 s101, s99, 0
	global_load_dwordx4 v[120:123], v136, s[100:101] offset:0
	global_load_dwordx4 v[124:127], v136, s[100:101] offset:1024
	global_load_dwordx4 v[128:131], v136, s[100:101] offset:2048
	global_load_dwordx4 v[132:135], v136, s[100:101] offset:3072
	s_add_u32 s100, s100, 0x400000
	s_addc_u32 s101, s101, 0
	global_load_dwordx4 v[16:19], v136, s[100:101] offset:0
	global_load_dwordx4 v[20:23], v136, s[100:101] offset:1024
	global_load_dwordx4 v[24:27], v136, s[100:101] offset:2048
	global_load_dwordx4 v[28:31], v136, s[100:101] offset:3072
	s_add_u32 s100, s100, 0x400000
	s_addc_u32 s101, s101, 0
	global_load_dwordx4 v[32:35], v136, s[100:101] offset:0
	global_load_dwordx4 v[36:39], v136, s[100:101] offset:1024
	global_load_dwordx4 v[40:43], v136, s[100:101] offset:2048
	global_load_dwordx4 v[44:47], v136, s[100:101] offset:3072
	s_add_u32 s100, s100, 0x400000
	s_addc_u32 s101, s101, 0
	global_load_dwordx4 v[48:51], v136, s[100:101] offset:0
	global_load_dwordx4 v[52:55], v136, s[100:101] offset:1024
	global_load_dwordx4 v[56:59], v136, s[100:101] offset:2048
	global_load_dwordx4 v[60:63], v136, s[100:101] offset:3072
	s_add_u32 s100, s100, 0x400000
	s_addc_u32 s101, s101, 0
	s_waitcnt vmcnt(8)
; __device__ __forceinline__ void row_phase(const Params& P, int glayer, int layer, int xsrc, bool hasY, int gate_idx, const float* gpost,
;                           int xdst, bool doH, const float* gpre, int sh_idx, int nrows) {
;     ...
;           else           xin_ = P.xc + (long)(R - N_X) * 1024;
; #pragma unroll
;           for (int i = 0; i < 4; ++i) xr[u][i] = *reinterpret_cast<const uint4*>(xin_ + (i * 64 + lane) * 4);
;         }
;         if (hasY) {
;           const u16* y_ = P.hy + (long)R * 1024;
; #pragma unroll
;           for (int i = 0; i < 4; ++i) yy[u][i] = *reinterpret_cast<const uint2*>(y_ + (i * 64 + lane) * 4);
;         }
	v_add_f32_e32 v120, v120, v16
	v_add_f32_e32 v121, v121, v17
	v_add_f32_e32 v122, v122, v18
	v_add_f32_e32 v123, v123, v19
	v_add_f32_e32 v124, v124, v20
	v_add_f32_e32 v125, v125, v21
	v_add_f32_e32 v126, v126, v22
	v_add_f32_e32 v127, v127, v23
	v_add_f32_e32 v128, v128, v24
	v_add_f32_e32 v129, v129, v25
	v_add_f32_e32 v130, v130, v26
	v_add_f32_e32 v131, v131, v27
	v_add_f32_e32 v132, v132, v28
	v_add_f32_e32 v133, v133, v29
	v_add_f32_e32 v134, v134, v30
	v_add_f32_e32 v135, v135, v31
	global_load_dwordx4 v[16:19], v136, s[100:101] offset:0
	global_load_dwordx4 v[20:23], v136, s[100:101] offset:1024
	global_load_dwordx4 v[24:27], v136, s[100:101] offset:2048
	global_load_dwordx4 v[28:31], v136, s[100:101] offset:3072
	s_add_u32 s100, s100, 0x400000
	s_addc_u32 s101, s101, 0
	s_waitcnt vmcnt(8)
	v_add_f32_e32 v120, v120, v32
	v_add_f32_e32 v121, v121, v33
	v_add_f32_e32 v122, v122, v34
	v_add_f32_e32 v123, v123, v35
	v_add_f32_e32 v124, v124, v36
	v_add_f32_e32 v125, v125, v37
	v_add_f32_e32 v126, v126, v38
	v_add_f32_e32 v127, v127, v39
	v_add_f32_e32 v128, v128, v40
	v_add_f32_e32 v129, v129, v41
	v_add_f32_e32 v130, v130, v42
	v_add_f32_e32 v131, v131, v43
	v_add_f32_e32 v132, v132, v44
	v_add_f32_e32 v133, v133, v45
	v_add_f32_e32 v134, v134, v46
	v_add_f32_e32 v135, v135, v47
	global_load_dwordx4 v[32:35], v136, s[100:101] offset:0
	global_load_dwordx4 v[36:39], v136, s[100:101] offset:1024
	global_load_dwordx4 v[40:43], v136, s[100:101] offset:2048
	global_load_dwordx4 v[44:47], v136, s[100:101] offset:3072
	s_add_u32 s100, s100, 0x400000
	s_addc_u32 s101, s101, 0
	s_waitcnt vmcnt(8)
	v_add_f32_e32 v120, v120, v48
	v_add_f32_e32 v121, v121, v49
	v_add_f32_e32 v122, v122, v50
	v_add_f32_e32 v123, v123, v51
	v_add_f32_e32 v124, v124, v52
	v_add_f32_e32 v125, v125, v53
	v_add_f32_e32 v126, v126, v54
	v_add_f32_e32 v127, v127, v55
	v_add_f32_e32 v128, v128, v56
	v_add_f32_e32 v129, v129, v57
	v_add_f32_e32 v130, v130, v58
	v_add_f32_e32 v131, v131, v59
	v_add_f32_e32 v132, v132, v60
	v_add_f32_e32 v133, v133, v61
	v_add_f32_e32 v134, v134, v62
	v_add_f32_e32 v135, v135, v63
	global_load_dwordx4 v[48:51], v136, s[100:101] offset:0
	global_load_dwordx4 v[52:55], v136, s[100:101] offset:1024
	global_load_dwordx4 v[56:59], v136, s[100:101] offset:2048
	global_load_dwordx4 v[60:63], v136, s[100:101] offset:3072
	s_add_u32 s100, s100, 0x400000
	s_addc_u32 s101, s101, 0
	s_waitcnt vmcnt(8)
	v_add_f32_e32 v120, v120, v16
	v_add_f32_e32 v121, v121, v17
	v_add_f32_e32 v122, v122, v18
	v_add_f32_e32 v123, v123, v19
	v_add_f32_e32 v124, v124, v20
	v_add_f32_e32 v125, v125, v21
	v_add_f32_e32 v126, v126, v22
	v_add_f32_e32 v127, v127, v23
	v_add_f32_e32 v128, v128, v24
	v_add_f32_e32 v129, v129, v25
	v_add_f32_e32 v130, v130, v26
	v_add_f32_e32 v131, v131, v27
	v_add_f32_e32 v132, v132, v28
	v_add_f32_e32 v133, v133, v29
	v_add_f32_e32 v134, v134, v30
	v_add_f32_e32 v135, v135, v31
	global_load_dwordx4 v[16:19], v136, s[100:101] offset:0
	global_load_dwordx4 v[20:23], v136, s[100:101] offset:1024
	global_load_dwordx4 v[24:27], v136, s[100:101] offset:2048
	global_load_dwordx4 v[28:31], v136, s[100:101] offset:3072
	s_add_u32 s100, s100, 0x400000
	s_addc_u32 s101, s101, 0
	s_waitcnt vmcnt(8)
	v_add_f32_e32 v120, v120, v32
	v_add_f32_e32 v121, v121, v33
	v_add_f32_e32 v122, v122, v34
	v_add_f32_e32 v123, v123, v35
	v_add_f32_e32 v124, v124, v36
	v_add_f32_e32 v125, v125, v37
	v_add_f32_e32 v126, v126, v38
	v_add_f32_e32 v127, v127, v39
	v_add_f32_e32 v128, v128, v40
	v_add_f32_e32 v129, v129, v41
	v_add_f32_e32 v130, v130, v42
	v_add_f32_e32 v131, v131, v43
	v_add_f32_e32 v132, v132, v44
	v_add_f32_e32 v133, v133, v45
	v_add_f32_e32 v134, v134, v46
	v_add_f32_e32 v135, v135, v47
	s_waitcnt vmcnt(4)
	v_add_f32_e32 v120, v120, v48
	v_add_f32_e32 v121, v121, v49
	v_add_f32_e32 v122, v122, v50
	v_add_f32_e32 v123, v123, v51
	v_add_f32_e32 v124, v124, v52
	v_add_f32_e32 v125, v125, v53
	v_add_f32_e32 v126, v126, v54
	v_add_f32_e32 v127, v127, v55
	v_add_f32_e32 v128, v128, v56
	v_add_f32_e32 v129, v129, v57
	v_add_f32_e32 v130, v130, v58
	v_add_f32_e32 v131, v131, v59
	v_add_f32_e32 v132, v132, v60
	v_add_f32_e32 v133, v133, v61
	v_add_f32_e32 v134, v134, v62
	v_add_f32_e32 v135, v135, v63
	s_waitcnt vmcnt(0)
; __device__ __forceinline__ void row_phase(const Params& P, int glayer, int layer, int xsrc, bool hasY, int gate_idx, const float* gpost,
;                           int xdst, bool doH, const float* gpre, int sh_idx, int nrows) {
;     ...
;         if (hasY) {
;           float4 yv[4];
;           float ss = 0.f;
; #pragma unroll
;           for (int i = 0; i < 4; ++i) {
;             const uint2 raw = yy[u][i];
;             yv[i].x = bf2f((u16)(raw.x & 0xffff)); yv[i].y = bf2f((u16)(raw.x >> 16));
;             yv[i].z = bf2f((u16)(raw.y & 0xffff)); yv[i].w = bf2f((u16)(raw.y >> 16));
;             ss += yv[i].x * yv[i].x + yv[i].y * yv[i].y + yv[i].z * yv[i].z + yv[i].w * yv[i].w;
;           }
;           ss = wave_sum(ss);
;           const float rstd = __builtin_amdgcn_rsqf(ss * (1.f / 1024.f) + EPSF);
; #pragma unroll
;           for (int i = 0; i < 4; ++i) {
;             const int col = (i * 64 + lane) * 4;
;             const float4 gt = *reinterpret_cast<const float4*>(modg + gate_idx * 1024 + col);
;             const float4 gp = *reinterpret_cast<const float4*>(gpost + col);
;             xv[i].x += gt.x * (yv[i].x * rstd * gp.x); xv[i].y += gt.y * (yv[i].y * rstd * gp.y);
;             xv[i].z += gt.z * (yv[i].z * rstd * gp.z); xv[i].w += gt.w * (yv[i].w * rstd * gp.w);
;           }
;         }
;         if (xdst == 3 || (xdst == 1 && row >= N_X)) {
;           float* xout = (xdst == 3) ? P.out + (long)row * 1024 : P.xc + (long)(row - N_X) * 1024;
; #pragma unroll
;           for (int i = 0; i < 4; ++i) *reinterpret_cast<float4*>(xout + (i * 64 + lane) * 4) = xv[i];
;         } else if (xdst != 0) {
;           u16* xo = ((xdst == 1) ? resA : P.zf) + (long)row * 1024;
; #pragma unroll
;           for (int i = 0; i < 4; ++i) {
;             const unsigned b0 = f2bf(xv[i].x), b1 = f2bf(xv[i].y), b2 = f2bf(xv[i].z), b3 = f2bf(xv[i].w);
;             *reinterpret_cast<uint2*>(xo + (i * 64 + lane) * 4) = make_uint2(b0 | (b1 << 16), b2 | (b3 << 16));
;           }
;         }
;         if (doH) {
;           float ss = 0.f;
; #pragma unroll
;           for (int i = 0; i < 4; ++i) ss += xv[i].x * xv[i].x + xv[i].y * xv[i].y + xv[i].z * xv[i].z + xv[i].w * xv[i].w;
;           ss = wave_sum(ss);
;           const float rstd = __builtin_amdgcn_rsqf(ss * (1.f / 1024.f) + EPSF);
;           u16* h = P.hy + (long)row * 1024;
; #pragma unroll
	v_add_f32_e32 v120, v120, v16
	v_add_f32_e32 v121, v121, v17
	v_add_f32_e32 v122, v122, v18
	v_add_f32_e32 v123, v123, v19
	v_add_f32_e32 v124, v124, v20
	v_add_f32_e32 v125, v125, v21
	v_add_f32_e32 v126, v126, v22
	v_add_f32_e32 v127, v127, v23
	v_add_f32_e32 v128, v128, v24
	v_add_f32_e32 v129, v129, v25
	v_add_f32_e32 v130, v130, v26
	v_add_f32_e32 v131, v131, v27
	v_add_f32_e32 v132, v132, v28
	v_add_f32_e32 v133, v133, v29
	v_add_f32_e32 v134, v134, v30
	v_add_f32_e32 v135, v135, v31
	v_cvt_pk_bf16_f32 v149, v120, v121
	v_lshlrev_b32_e32 v120, 16, v149
	v_and_b32_e32 v121, 0xffff0000, v149
	v_cvt_pk_bf16_f32 v149, v122, v123
	v_lshlrev_b32_e32 v122, 16, v149
	v_and_b32_e32 v123, 0xffff0000, v149
	v_cvt_pk_bf16_f32 v149, v124, v125
	v_lshlrev_b32_e32 v124, 16, v149
	v_and_b32_e32 v125, 0xffff0000, v149
	v_cvt_pk_bf16_f32 v149, v126, v127
	v_lshlrev_b32_e32 v126, 16, v149
	v_and_b32_e32 v127, 0xffff0000, v149
	v_cvt_pk_bf16_f32 v149, v128, v129
	v_lshlrev_b32_e32 v128, 16, v149
	v_and_b32_e32 v129, 0xffff0000, v149
	v_cvt_pk_bf16_f32 v149, v130, v131
	v_lshlrev_b32_e32 v130, 16, v149
	v_and_b32_e32 v131, 0xffff0000, v149
	v_cvt_pk_bf16_f32 v149, v132, v133
	v_lshlrev_b32_e32 v132, 16, v149
	v_and_b32_e32 v133, 0xffff0000, v149
	v_cvt_pk_bf16_f32 v149, v134, v135
	v_lshlrev_b32_e32 v134, 16, v149
	v_and_b32_e32 v135, 0xffff0000, v149
	v_mul_f32_e32 v138, v120, v120
	v_mul_f32_e32 v149, v121, v121
	v_mul_f32_e32 v150, v122, v122
	v_mul_f32_e32 v154, v123, v123
	v_fma_f32 v138, v124, v124, v138
	v_fma_f32 v149, v125, v125, v149
	v_fma_f32 v150, v126, v126, v150
	v_fma_f32 v154, v127, v127, v154
	v_fma_f32 v138, v128, v128, v138
	v_fma_f32 v149, v129, v129, v149
	v_fma_f32 v150, v130, v130, v150
	v_fma_f32 v154, v131, v131, v154
	v_fma_f32 v138, v132, v132, v138
	v_fma_f32 v149, v133, v133, v149
	v_fma_f32 v150, v134, v134, v150
	v_fma_f32 v154, v135, v135, v154
	v_add_f32_e32 v138, v138, v149
	v_add_f32_e32 v150, v150, v154
	v_add_f32_e32 v138, v138, v150
	s_nop 1
	v_add_f32_dpp v138, v138, v138 quad_perm:[1,0,3,2] row_mask:0xf bank_mask:0xf
	s_nop 1
	v_add_f32_dpp v138, v138, v138 quad_perm:[2,3,0,1] row_mask:0xf bank_mask:0xf
	s_nop 1
	v_add_f32_dpp v138, v138, v138 row_half_mirror row_mask:0xf bank_mask:0xf
	s_nop 1
	v_add_f32_dpp v138, v138, v138 row_mirror row_mask:0xf bank_mask:0xf
	v_mov_b32_e32 v139, v138
	s_nop 1
	v_permlane16_swap_b32_e32 v138, v139
	v_add_f32_e32 v138, v138, v139
	v_mov_b32_e32 v139, v138
	s_nop 1
	v_permlane32_swap_b32_e32 v138, v139
	v_add_f32_e32 v138, v138, v139
	v_mul_f32_e32 v138, 0x3a800000, v138
	v_add_f32_e32 v138, 0x358637bd, v138
	v_rsq_f32_e32 v140, v138
	s_nop 0
	v_mul_f32_e32 v120, v120, v140
	v_mul_f32_e32 v121, v121, v140
	v_mul_f32_e32 v122, v122, v140
	v_mul_f32_e32 v123, v123, v140
	v_mul_f32_e32 v124, v124, v140
	v_mul_f32_e32 v125, v125, v140
	v_mul_f32_e32 v126, v126, v140
	v_mul_f32_e32 v127, v127, v140
	v_mul_f32_e32 v128, v128, v140
	v_mul_f32_e32 v129, v129, v140
	v_mul_f32_e32 v130, v130, v140
	v_mul_f32_e32 v131, v131, v140
	v_mul_f32_e32 v132, v132, v140
	v_mul_f32_e32 v133, v133, v140
	v_mul_f32_e32 v134, v134, v140
	v_mul_f32_e32 v135, v135, v140
	v_fma_f32 v0, v120, v72, v0
	v_fma_f32 v1, v121, v73, v1
	v_fma_f32 v2, v122, v74, v2
	v_fma_f32 v3, v123, v75, v3
	v_fma_f32 v4, v124, v76, v4
	v_fma_f32 v5, v125, v77, v5
	v_fma_f32 v6, v126, v78, v6
	v_fma_f32 v7, v127, v79, v7
	v_fma_f32 v8, v128, v80, v8
	v_fma_f32 v9, v129, v81, v9
	v_fma_f32 v10, v130, v82, v10
	v_fma_f32 v11, v131, v83, v11
	v_fma_f32 v12, v132, v84, v12
	v_fma_f32 v13, v133, v85, v13
	v_fma_f32 v14, v134, v86, v14
	v_fma_f32 v15, v135, v87, v15
	s_load_dwordx2 s[98:99], s[4:5], 0x138
	s_waitcnt lgkmcnt(0)
	s_lshl_b32 vcc_lo, s19, 12
	s_add_u32 s100, s98, vcc_lo
	s_addc_u32 s101, s99, 0
	global_store_dwordx4 v136, v[0:3], s[100:101] offset:0
	global_store_dwordx4 v136, v[4:7], s[100:101] offset:1024
	global_store_dwordx4 v136, v[8:11], s[100:101] offset:2048
	global_store_dwordx4 v136, v[12:15], s[100:101] offset:3072
	v_mul_f32_e32 v138, v0, v0
	v_mul_f32_e32 v149, v1, v1
	v_mul_f32_e32 v150, v2, v2
	v_mul_f32_e32 v154, v3, v3
	v_fma_f32 v138, v4, v4, v138
	v_fma_f32 v149, v5, v5, v149
	v_fma_f32 v150, v6, v6, v150
	v_fma_f32 v154, v7, v7, v154
	v_fma_f32 v138, v8, v8, v138
	v_fma_f32 v149, v9, v9, v149
	v_fma_f32 v150, v10, v10, v150
	v_fma_f32 v154, v11, v11, v154
	v_fma_f32 v138, v12, v12, v138
	v_fma_f32 v149, v13, v13, v149
	v_fma_f32 v150, v14, v14, v150
	v_fma_f32 v154, v15, v15, v154
	v_add_f32_e32 v138, v138, v149
	v_add_f32_e32 v150, v150, v154
	v_add_f32_e32 v138, v138, v150
	s_nop 1
	v_add_f32_dpp v138, v138, v138 quad_perm:[1,0,3,2] row_mask:0xf bank_mask:0xf
	s_nop 1
	v_add_f32_dpp v138, v138, v138 quad_perm:[2,3,0,1] row_mask:0xf bank_mask:0xf
	s_nop 1
	v_add_f32_dpp v138, v138, v138 row_half_mirror row_mask:0xf bank_mask:0xf
	s_nop 1
	v_add_f32_dpp v138, v138, v138 row_mirror row_mask:0xf bank_mask:0xf
	v_mov_b32_e32 v139, v138
	s_nop 1
	v_permlane16_swap_b32_e32 v138, v139
	v_add_f32_e32 v138, v138, v139
	v_mov_b32_e32 v139, v138
	s_nop 1
	v_permlane32_swap_b32_e32 v138, v139
	v_add_f32_e32 v138, v138, v139
	v_mul_f32_e32 v138, 0x3a800000, v138
	v_add_f32_e32 v138, 0x358637bd, v138
	v_rsq_f32_e32 v140, v138
	s_nop 0
	v_mul_f32_e32 v120, v0, v140
	v_mul_f32_e32 v121, v1, v140
	v_mul_f32_e32 v122, v2, v140
	v_mul_f32_e32 v123, v3, v140
	v_mul_f32_e32 v124, v4, v140
	v_mul_f32_e32 v125, v5, v140
	v_mul_f32_e32 v126, v6, v140
	v_mul_f32_e32 v127, v7, v140
	v_mul_f32_e32 v128, v8, v140
	v_mul_f32_e32 v129, v9, v140
	v_mul_f32_e32 v130, v10, v140
	v_mul_f32_e32 v131, v11, v140
	v_mul_f32_e32 v132, v12, v140
	v_mul_f32_e32 v133, v13, v140
	v_mul_f32_e32 v134, v14, v140
	v_mul_f32_e32 v135, v15, v140
	v_fma_f32 v120, v120, v88, v104
	v_fma_f32 v121, v121, v89, v105
	v_fma_f32 v122, v122, v90, v106
	v_fma_f32 v123, v123, v91, v107
	v_fma_f32 v124, v124, v92, v108
	v_fma_f32 v125, v125, v93, v109
	v_fma_f32 v126, v126, v94, v110
	v_fma_f32 v127, v127, v95, v111
	v_fma_f32 v128, v128, v96, v112
	v_fma_f32 v129, v129, v97, v113
	v_fma_f32 v130, v130, v98, v114
	v_fma_f32 v131, v131, v99, v115
	v_fma_f32 v132, v132, v100, v116
	v_fma_f32 v133, v133, v101, v117
	v_fma_f32 v134, v134, v102, v118
	v_fma_f32 v135, v135, v103, v119
	v_cvt_pk_bf16_f32 v156, v120, v121
	v_cvt_pk_bf16_f32 v157, v122, v123
	v_cvt_pk_bf16_f32 v158, v124, v125
	v_cvt_pk_bf16_f32 v159, v126, v127
	v_cvt_pk_bf16_f32 v160, v128, v129
	v_cvt_pk_bf16_f32 v161, v130, v131
	v_cvt_pk_bf16_f32 v162, v132, v133
	v_cvt_pk_bf16_f32 v163, v134, v135
	s_lshl_b32 vcc_lo, s19, 11
	s_add_u32 vcc_lo, vcc_lo, 0x4000000
	s_add_u32 s100, s14, vcc_lo
	s_addc_u32 s101, s15, 0
	global_store_dwordx2 v137, v[156:157], s[100:101] offset:0
	global_store_dwordx2 v137, v[158:159], s[100:101] offset:512
	global_store_dwordx2 v137, v[160:161], s[100:101] offset:1024
	global_store_dwordx2 v137, v[162:163], s[100:101] offset:1536

; __device__ __forceinline__ void row_phase(const Params& P, int glayer, int layer, int xsrc, bool hasY, int gate_idx, const float* gpost,
;                           int xdst, bool doH, const float* gpre, int sh_idx, int nrows) {
;   const int lane = threadIdx.x & 63, wid = threadIdx.x >> 6;
;   const int stride = gridDim.x * 8;
;   u16* resA = reinterpret_cast<u16*>(P.out);
;   for (int rb = blockIdx.x * 8 + wid; rb < nrows; rb += 4 * stride) {
;     uint4 xr[4][4];
;     uint2 yy[4][4];
; #pragma unroll
;     for (int u = 0; u < 4; ++u) {
;       const int R = rb + u * stride;
;       if (R < nrows) {
;         if (xsrc != 0 && R < N_X) {
;           const u16* xs_ = ((xsrc == 1) ? resA : P.zf) + (long)R * 1024;
; #pragma unroll
;           for (int i = 0; i < 4; ++i) {
;             const uint2 t2 = *reinterpret_cast<const uint2*>(xs_ + (i * 64 + lane) * 4);
;             xr[u][i].x = t2.x; xr[u][i].y = t2.y;
;           }
;         } else {
;           const float* xin_;
;           if (xsrc == 0) xin_ = R < N_X ? P.x + (long)R * 1024 : P.ctx + (long)(R - N_X) * 1024;
;           else           xin_ = P.xc + (long)(R - N_X) * 1024;
; #pragma unroll
;           for (int i = 0; i < 4; ++i) xr[u][i] = *reinterpret_cast<const uint4*>(xin_ + (i * 64 + lane) * 4);
;         }
;         if (hasY) {
;           const u16* y_ = P.hy + (long)R * 1024;
; #pragma unroll
;           for (int i = 0; i < 4; ++i) yy[u][i] = *reinterpret_cast<const uint2*>(y_ + (i * 64 + lane) * 4);
;         }
;       }
;     }
.LBB0_1662:
	s_cmp_gt_i32 s34, 14
	s_cselect_b64 s[0:1], -1, 0
	s_cmp_lt_i32 s35, 15
	s_cselect_b64 s[4:5], -1, 0
	s_or_b64 s[0:1], s[0:1], s[4:5]
	s_and_b64 vcc, exec, s[0:1]
	s_cbranch_vccnz .LBB0_1732
	s_waitcnt vmcnt(16)
	v_mov_b32_e32 v0, v153
	s_mov_b32 s3, 0x8000
	v_lshl_add_u32 v0, s2, 3, v204
	v_cmp_gt_i32_e32 vcc, s3, v0
	s_and_saveexec_b64 s[6:7], vcc
	s_cbranch_execz .LBB0_1678
	v_readlane_b32 s4, v252, 0
	v_readlane_b32 s5, v252, 1
	v_readfirstlane_b32 s19, v204
	s_nop 3
	s_sub_u32 s4, s4, 0x170
	s_subb_u32 s5, s5, 0
	s_load_dwordx2 s[12:13], s[4:5], 0xc8
	s_load_dwordx2 s[14:15], s[4:5], 0x140
	s_load_dwordx2 s[16:17], s[4:5], 0x150
	s_load_dwordx2 s[20:21], s[4:5], 0x100
	s_lshl_b32 s98, s2, 3
	s_add_u32 s19, s98, s19
	v_and_b32_e32 v136, 63, v152
	v_lshlrev_b32_e32 v137, 3, v136
	v_lshlrev_b32_e32 v136, 4, v136
	s_waitcnt lgkmcnt(0)
	s_lshl_b32 vcc_lo, s19, 11
	s_add_u32 s100, s12, vcc_lo
	s_addc_u32 s101, s13, 0
	global_load_dwordx2 v[8:9], v137, s[100:101] offset:0
	global_load_dwordx2 v[10:11], v137, s[100:101] offset:512
	global_load_dwordx2 v[12:13], v137, s[100:101] offset:1024
	global_load_dwordx2 v[14:15], v137, s[100:101] offset:1536
	s_lshl_b32 vcc_lo, s19, 11
	s_add_u32 s100, s14, vcc_lo
	s_addc_u32 s101, s15, 0
	global_load_dwordx2 v[48:49], v137, s[100:101] offset:0
	global_load_dwordx2 v[50:51], v137, s[100:101] offset:512
	global_load_dwordx2 v[52:53], v137, s[100:101] offset:1024
	global_load_dwordx2 v[54:55], v137, s[100:101] offset:1536
	s_lshl_b32 vcc_lo, s19, 11
	s_add_u32 vcc_lo, vcc_lo, 0x400000
	s_add_u32 s100, s12, vcc_lo
	s_addc_u32 s101, s13, 0
	global_load_dwordx2 v[24:25], v137, s[100:101] offset:0
	global_load_dwordx2 v[26:27], v137, s[100:101] offset:512
	global_load_dwordx2 v[28:29], v137, s[100:101] offset:1024
	global_load_dwordx2 v[30:31], v137, s[100:101] offset:1536
	s_lshl_b32 vcc_lo, s19, 11
	s_add_u32 vcc_lo, vcc_lo, 0x400000
	s_add_u32 s100, s14, vcc_lo
	s_addc_u32 s101, s15, 0
	global_load_dwordx2 v[56:57], v137, s[100:101] offset:0
	global_load_dwordx2 v[58:59], v137, s[100:101] offset:512
	global_load_dwordx2 v[60:61], v137, s[100:101] offset:1024
	global_load_dwordx2 v[62:63], v137, s[100:101] offset:1536
	s_lshl_b32 vcc_lo, s19, 11
	s_add_u32 vcc_lo, vcc_lo, 0x800000
	s_add_u32 s100, s12, vcc_lo
	s_addc_u32 s101, s13, 0
	global_load_dwordx2 v[40:41], v137, s[100:101] offset:0
	global_load_dwordx2 v[42:43], v137, s[100:101] offset:512
	global_load_dwordx2 v[44:45], v137, s[100:101] offset:1024
	global_load_dwordx2 v[46:47], v137, s[100:101] offset:1536
	s_lshl_b32 vcc_lo, s19, 11
	s_add_u32 vcc_lo, vcc_lo, 0x800000
	s_add_u32 s100, s14, vcc_lo
	s_addc_u32 s101, s15, 0
	global_load_dwordx2 v[64:65], v137, s[100:101] offset:0
	global_load_dwordx2 v[66:67], v137, s[100:101] offset:512
	global_load_dwordx2 v[68:69], v137, s[100:101] offset:1024
	global_load_dwordx2 v[70:71], v137, s[100:101] offset:1536
	s_add_u32 s100, s20, 0x20000
	s_addc_u32 s101, s21, 0
	global_load_dwordx4 v[72:75], v136, s[100:101] offset:0
	global_load_dwordx4 v[76:79], v136, s[100:101] offset:1024
	global_load_dwordx4 v[80:83], v136, s[100:101] offset:2048
	global_load_dwordx4 v[84:87], v136, s[100:101] offset:3072
	s_load_dwordx2 s[98:99], s[4:5], 0x38
	s_waitcnt lgkmcnt(0)
	s_add_u32 s98, s98, 0x1000
	s_addc_u32 s99, s99, 0
	global_load_dwordx4 v[120:123], v136, s[98:99] offset:0
	global_load_dwordx4 v[124:127], v136, s[98:99] offset:1024
	global_load_dwordx4 v[128:131], v136, s[98:99] offset:2048
	global_load_dwordx4 v[132:135], v136, s[98:99] offset:3072
	s_add_u32 s100, s20, 0x21000
	s_addc_u32 s101, s21, 0
	global_load_dwordx4 v[104:107], v136, s[100:101] offset:0
	global_load_dwordx4 v[108:111], v136, s[100:101] offset:1024
	global_load_dwordx4 v[112:115], v136, s[100:101] offset:2048
	global_load_dwordx4 v[116:119], v136, s[100:101] offset:3072
	s_add_u32 s100, s100, 0x1000
	s_addc_u32 s101, s101, 0
	global_load_dwordx4 v[166:169], v136, s[100:101] offset:0
	global_load_dwordx4 v[170:173], v136, s[100:101] offset:1024
	global_load_dwordx4 v[174:177], v136, s[100:101] offset:2048
	global_load_dwordx4 v[178:181], v136, s[100:101] offset:3072
	s_load_dwordx2 s[98:99], s[4:5], 0x40
	s_waitcnt lgkmcnt(0)
	s_add_u32 s98, s98, 0x1000
	s_addc_u32 s99, s99, 0
	global_load_dwordx4 v[88:91], v136, s[98:99] offset:0
	global_load_dwordx4 v[92:95], v136, s[98:99] offset:1024
	global_load_dwordx4 v[96:99], v136, s[98:99] offset:2048
	global_load_dwordx4 v[100:103], v136, s[98:99] offset:3072
	s_waitcnt vmcnt(0)
; __device__ __forceinline__ void row_phase(const Params& P, int glayer, int layer, int xsrc, bool hasY, int gate_idx, const float* gpost,
;                           int xdst, bool doH, const float* gpre, int sh_idx, int nrows) {
;     ...
;         if (hasY) {
;           float4 yv[4];
;           float ss = 0.f;
; #pragma unroll
;           for (int i = 0; i < 4; ++i) {
;             const uint2 raw = yy[u][i];
;             yv[i].x = bf2f((u16)(raw.x & 0xffff)); yv[i].y = bf2f((u16)(raw.x >> 16));
;             yv[i].z = bf2f((u16)(raw.y & 0xffff)); yv[i].w = bf2f((u16)(raw.y >> 16));
;             ss += yv[i].x * yv[i].x + yv[i].y * yv[i].y + yv[i].z * yv[i].z + yv[i].w * yv[i].w;
;           }
;           ss = wave_sum(ss);
;           const float rstd = __builtin_amdgcn_rsqf(ss * (1.f / 1024.f) + EPSF);
; #pragma unroll
;           for (int i = 0; i < 4; ++i) {
;             const int col = (i * 64 + lane) * 4;
;             const float4 gt = *reinterpret_cast<const float4*>(modg + gate_idx * 1024 + col);
;             const float4 gp = *reinterpret_cast<const float4*>(gpost + col);
;             xv[i].x += gt.x * (yv[i].x * rstd * gp.x); xv[i].y += gt.y * (yv[i].y * rstd * gp.y);
;             xv[i].z += gt.z * (yv[i].z * rstd * gp.z); xv[i].w += gt.w * (yv[i].w * rstd * gp.w);
;           }
;         }
;         if (xdst == 3 || (xdst == 1 && row >= N_X)) {
;           float* xout = (xdst == 3) ? P.out + (long)row * 1024 : P.xc + (long)(row - N_X) * 1024;
; #pragma unroll
;           for (int i = 0; i < 4; ++i) *reinterpret_cast<float4*>(xout + (i * 64 + lane) * 4) = xv[i];
;         } else if (xdst != 0) {
;           u16* xo = ((xdst == 1) ? resA : P.zf) + (long)row * 1024;
; #pragma unroll
;           for (int i = 0; i < 4; ++i) {
;             const unsigned b0 = f2bf(xv[i].x), b1 = f2bf(xv[i].y), b2 = f2bf(xv[i].z), b3 = f2bf(xv[i].w);
;             *reinterpret_cast<uint2*>(xo + (i * 64 + lane) * 4) = make_uint2(b0 | (b1 << 16), b2 | (b3 << 16));
;           }
;         }
;         if (doH) {
;           float ss = 0.f;
; #pragma unroll
;           for (int i = 0; i < 4; ++i) ss += xv[i].x * xv[i].x + xv[i].y * xv[i].y + xv[i].z * xv[i].z + xv[i].w * xv[i].w;
;           ss = wave_sum(ss);
;           const float rstd = __builtin_amdgcn_rsqf(ss * (1.f / 1024.f) + EPSF);
;           u16* h = P.hy + (long)row * 1024;
; #pragma unroll
	v_mul_f32_e32 v72, v72, v120
	v_mul_f32_e32 v73, v73, v121
	v_mul_f32_e32 v74, v74, v122
	v_mul_f32_e32 v75, v75, v123
	v_mul_f32_e32 v76, v76, v124
	v_mul_f32_e32 v77, v77, v125
	v_mul_f32_e32 v78, v78, v126
	v_mul_f32_e32 v79, v79, v127
	v_mul_f32_e32 v80, v80, v128
	v_mul_f32_e32 v81, v81, v129
	v_mul_f32_e32 v82, v82, v130
	v_mul_f32_e32 v83, v83, v131
	v_mul_f32_e32 v84, v84, v132
	v_mul_f32_e32 v85, v85, v133
	v_mul_f32_e32 v86, v86, v134
	v_mul_f32_e32 v87, v87, v135
	v_fma_f32 v88, v88, v166, v88
	v_fma_f32 v89, v89, v167, v89
	v_fma_f32 v90, v90, v168, v90
	v_fma_f32 v91, v91, v169, v91
	v_fma_f32 v92, v92, v170, v92
	v_fma_f32 v93, v93, v171, v93
	v_fma_f32 v94, v94, v172, v94
	v_fma_f32 v95, v95, v173, v95
	v_fma_f32 v96, v96, v174, v96
	v_fma_f32 v97, v97, v175, v97
	v_fma_f32 v98, v98, v176, v98
	v_fma_f32 v99, v99, v177, v99
	v_fma_f32 v100, v100, v178, v100
	v_fma_f32 v101, v101, v179, v101
	v_fma_f32 v102, v102, v180, v102
	v_fma_f32 v103, v103, v181, v103
	s_lshl_b32 vcc_lo, s19, 11
	s_add_u32 vcc_lo, vcc_lo, 0xc00000
	s_add_u32 s100, s12, vcc_lo
	s_addc_u32 s101, s13, 0
	global_load_dwordx2 v[174:175], v137, s[100:101] offset:0
	global_load_dwordx2 v[176:177], v137, s[100:101] offset:512
	global_load_dwordx2 v[178:179], v137, s[100:101] offset:1024
	global_load_dwordx2 v[180:181], v137, s[100:101] offset:1536
	s_lshl_b32 vcc_lo, s19, 11
	s_add_u32 vcc_lo, vcc_lo, 0xc00000
	s_add_u32 s100, s14, vcc_lo
	s_addc_u32 s101, s15, 0
	global_load_dwordx2 v[182:183], v137, s[100:101] offset:0
	global_load_dwordx2 v[184:185], v137, s[100:101] offset:512
	global_load_dwordx2 v[186:187], v137, s[100:101] offset:1024
	global_load_dwordx2 v[188:189], v137, s[100:101] offset:1536
	v_lshlrev_b32_e32 v120, 16, v48
	v_and_b32_e32 v121, 0xffff0000, v48
	v_lshlrev_b32_e32 v122, 16, v49
	v_and_b32_e32 v123, 0xffff0000, v49
	v_lshlrev_b32_e32 v124, 16, v50
	v_and_b32_e32 v125, 0xffff0000, v50
	v_lshlrev_b32_e32 v126, 16, v51
	v_and_b32_e32 v127, 0xffff0000, v51
	v_lshlrev_b32_e32 v128, 16, v52
	v_and_b32_e32 v129, 0xffff0000, v52
	v_lshlrev_b32_e32 v130, 16, v53
	v_and_b32_e32 v131, 0xffff0000, v53
	v_lshlrev_b32_e32 v132, 16, v54
	v_and_b32_e32 v133, 0xffff0000, v54
	v_lshlrev_b32_e32 v134, 16, v55
	v_and_b32_e32 v135, 0xffff0000, v55
	v_mul_f32_e32 v138, v120, v120
	v_mul_f32_e32 v149, v121, v121
	v_mul_f32_e32 v150, v122, v122
	v_mul_f32_e32 v154, v123, v123
	v_fma_f32 v138, v124, v124, v138
	v_fma_f32 v149, v125, v125, v149
	v_fma_f32 v150, v126, v126, v150
	v_fma_f32 v154, v127, v127, v154
	v_fma_f32 v138, v128, v128, v138
	v_fma_f32 v149, v129, v129, v149
	v_fma_f32 v150, v130, v130, v150
	v_fma_f32 v154, v131, v131, v154
	v_fma_f32 v138, v132, v132, v138
	v_fma_f32 v149, v133, v133, v149
	v_fma_f32 v150, v134, v134, v150
	v_fma_f32 v154, v135, v135, v154
	v_add_f32_e32 v138, v138, v149
	v_add_f32_e32 v150, v150, v154
	v_add_f32_e32 v138, v138, v150
	s_nop 1
	v_add_f32_dpp v138, v138, v138 quad_perm:[1,0,3,2] row_mask:0xf bank_mask:0xf
	s_nop 1
	v_add_f32_dpp v138, v138, v138 quad_perm:[2,3,0,1] row_mask:0xf bank_mask:0xf
	s_nop 1
	v_add_f32_dpp v138, v138, v138 row_half_mirror row_mask:0xf bank_mask:0xf
	s_nop 1
	v_add_f32_dpp v138, v138, v138 row_mirror row_mask:0xf bank_mask:0xf
	v_mov_b32_e32 v139, v138
	s_nop 1
	v_permlane16_swap_b32_e32 v138, v139
	v_add_f32_e32 v138, v138, v139
	v_mov_b32_e32 v139, v138
	s_nop 1
	v_permlane32_swap_b32_e32 v138, v139
	v_add_f32_e32 v138, v138, v139
	v_mul_f32_e32 v138, 0x3a800000, v138
	v_add_f32_e32 v138, 0x358637bd, v138
	v_rsq_f32_e32 v140, v138
	v_lshlrev_b32_e32 v0, 16, v8
	v_and_b32_e32 v1, 0xffff0000, v8
	v_lshlrev_b32_e32 v2, 16, v9
	v_and_b32_e32 v3, 0xffff0000, v9
	v_lshlrev_b32_e32 v4, 16, v10
	v_and_b32_e32 v5, 0xffff0000, v10
	v_lshlrev_b32_e32 v6, 16, v11
	v_and_b32_e32 v7, 0xffff0000, v11
	v_lshlrev_b32_e32 v8, 16, v12
	v_and_b32_e32 v9, 0xffff0000, v12
	v_lshlrev_b32_e32 v10, 16, v13
	v_and_b32_e32 v11, 0xffff0000, v13
	v_lshlrev_b32_e32 v12, 16, v14
	v_and_b32_e32 v13, 0xffff0000, v14
	v_lshlrev_b32_e32 v14, 16, v15
	v_and_b32_e32 v15, 0xffff0000, v15
	s_nop 0
	v_mul_f32_e32 v120, v120, v140
	v_mul_f32_e32 v121, v121, v140
	v_mul_f32_e32 v122, v122, v140
	v_mul_f32_e32 v123, v123, v140
	v_mul_f32_e32 v124, v124, v140
	v_mul_f32_e32 v125, v125, v140
	v_mul_f32_e32 v126, v126, v140
	v_mul_f32_e32 v127, v127, v140
	v_mul_f32_e32 v128, v128, v140
	v_mul_f32_e32 v129, v129, v140
	v_mul_f32_e32 v130, v130, v140
	v_mul_f32_e32 v131, v131, v140
	v_mul_f32_e32 v132, v132, v140
	v_mul_f32_e32 v133, v133, v140
	v_mul_f32_e32 v134, v134, v140
	v_mul_f32_e32 v135, v135, v140
	v_fma_f32 v0, v120, v72, v0
	v_fma_f32 v1, v121, v73, v1
	v_fma_f32 v2, v122, v74, v2
	v_fma_f32 v3, v123, v75, v3
	v_fma_f32 v4, v124, v76, v4
	v_fma_f32 v5, v125, v77, v5
	v_fma_f32 v6, v126, v78, v6
	v_fma_f32 v7, v127, v79, v7
	v_fma_f32 v8, v128, v80, v8
	v_fma_f32 v9, v129, v81, v9
	v_fma_f32 v10, v130, v82, v10
	v_fma_f32 v11, v131, v83, v11
	v_fma_f32 v12, v132, v84, v12
	v_fma_f32 v13, v133, v85, v13
	v_fma_f32 v14, v134, v86, v14
	v_fma_f32 v15, v135, v87, v15
	v_cvt_pk_bf16_f32 v156, v0, v1
	v_cvt_pk_bf16_f32 v157, v2, v3
	v_cvt_pk_bf16_f32 v158, v4, v5
	v_cvt_pk_bf16_f32 v159, v6, v7
	v_cvt_pk_bf16_f32 v160, v8, v9
	v_cvt_pk_bf16_f32 v161, v10, v11
	v_cvt_pk_bf16_f32 v162, v12, v13
	v_cvt_pk_bf16_f32 v163, v14, v15
	s_lshl_b32 vcc_lo, s19, 11
	s_add_u32 s100, s16, vcc_lo
	s_addc_u32 s101, s17, 0
	global_store_dwordx2 v137, v[156:157], s[100:101] offset:0
	global_store_dwordx2 v137, v[158:159], s[100:101] offset:512
	global_store_dwordx2 v137, v[160:161], s[100:101] offset:1024
; __device__ __forceinline__ void row_phase(const Params& P, int glayer, int layer, int xsrc, bool hasY, int gate_idx, const float* gpost,
;                           int xdst, bool doH, const float* gpre, int sh_idx, int nrows) {
;     ...
;         if (hasY) {
;           float4 yv[4];
;           float ss = 0.f;
; #pragma unroll
;           for (int i = 0; i < 4; ++i) {
;             const uint2 raw = yy[u][i];
;             yv[i].x = bf2f((u16)(raw.x & 0xffff)); yv[i].y = bf2f((u16)(raw.x >> 16));
;             yv[i].z = bf2f((u16)(raw.y & 0xffff)); yv[i].w = bf2f((u16)(raw.y >> 16));
;             ss += yv[i].x * yv[i].x + yv[i].y * yv[i].y + yv[i].z * yv[i].z + yv[i].w * yv[i].w;
;           }
;           ss = wave_sum(ss);
;           const float rstd = __builtin_amdgcn_rsqf(ss * (1.f / 1024.f) + EPSF);
; #pragma unroll
;           for (int i = 0; i < 4; ++i) {
;             const int col = (i * 64 + lane) * 4;
;             const float4 gt = *reinterpret_cast<const float4*>(modg + gate_idx * 1024 + col);
;             const float4 gp = *reinterpret_cast<const float4*>(gpost + col);
;             xv[i].x += gt.x * (yv[i].x * rstd * gp.x); xv[i].y += gt.y * (yv[i].y * rstd * gp.y);
;             xv[i].z += gt.z * (yv[i].z * rstd * gp.z); xv[i].w += gt.w * (yv[i].w * rstd * gp.w);
;           }
;         }
;         if (xdst == 3 || (xdst == 1 && row >= N_X)) {
;           float* xout = (xdst == 3) ? P.out + (long)row * 1024 : P.xc + (long)(row - N_X) * 1024;
; #pragma unroll
;           for (int i = 0; i < 4; ++i) *reinterpret_cast<float4*>(xout + (i * 64 + lane) * 4) = xv[i];
;         } else if (xdst != 0) {
;           u16* xo = ((xdst == 1) ? resA : P.zf) + (long)row * 1024;
; #pragma unroll
;           for (int i = 0; i < 4; ++i) {
;             const unsigned b0 = f2bf(xv[i].x), b1 = f2bf(xv[i].y), b2 = f2bf(xv[i].z), b3 = f2bf(xv[i].w);
;             *reinterpret_cast<uint2*>(xo + (i * 64 + lane) * 4) = make_uint2(b0 | (b1 << 16), b2 | (b3 << 16));
;           }
;         }
;         if (doH) {
;           float ss = 0.f;
; #pragma unroll
;           for (int i = 0; i < 4; ++i) ss += xv[i].x * xv[i].x + xv[i].y * xv[i].y + xv[i].z * xv[i].z + xv[i].w * xv[i].w;
;           ss = wave_sum(ss);
;           const float rstd = __builtin_amdgcn_rsqf(ss * (1.f / 1024.f) + EPSF);
;           u16* h = P.hy + (long)row * 1024;
; #pragma unroll
	global_store_dwordx2 v137, v[162:163], s[100:101] offset:1536
	v_mul_f32_e32 v138, v0, v0
	v_mul_f32_e32 v149, v1, v1
	v_mul_f32_e32 v150, v2, v2
	v_mul_f32_e32 v154, v3, v3
	v_fma_f32 v138, v4, v4, v138
	v_fma_f32 v149, v5, v5, v149
	v_fma_f32 v150, v6, v6, v150
	v_fma_f32 v154, v7, v7, v154
	v_fma_f32 v138, v8, v8, v138
	v_fma_f32 v149, v9, v9, v149
	v_fma_f32 v150, v10, v10, v150
	v_fma_f32 v154, v11, v11, v154
	v_fma_f32 v138, v12, v12, v138
	v_fma_f32 v149, v13, v13, v149
	v_fma_f32 v150, v14, v14, v150
	v_fma_f32 v154, v15, v15, v154
	v_add_f32_e32 v138, v138, v149
	v_add_f32_e32 v150, v150, v154
	v_add_f32_e32 v138, v138, v150
	s_nop 1
	v_add_f32_dpp v138, v138, v138 quad_perm:[1,0,3,2] row_mask:0xf bank_mask:0xf
	s_nop 1
	v_add_f32_dpp v138, v138, v138 quad_perm:[2,3,0,1] row_mask:0xf bank_mask:0xf
	s_nop 1
	v_add_f32_dpp v138, v138, v138 row_half_mirror row_mask:0xf bank_mask:0xf
	s_nop 1
	v_add_f32_dpp v138, v138, v138 row_mirror row_mask:0xf bank_mask:0xf
	v_mov_b32_e32 v139, v138
	s_nop 1
	v_permlane16_swap_b32_e32 v138, v139
	v_add_f32_e32 v138, v138, v139
	v_mov_b32_e32 v139, v138
	s_nop 1
	v_permlane32_swap_b32_e32 v138, v139
	v_add_f32_e32 v138, v138, v139
	v_mul_f32_e32 v138, 0x3a800000, v138
	v_add_f32_e32 v138, 0x358637bd, v138
	v_rsq_f32_e32 v140, v138
	s_nop 0
	v_mul_f32_e32 v120, v0, v140
	v_mul_f32_e32 v121, v1, v140
	v_mul_f32_e32 v122, v2, v140
	v_mul_f32_e32 v123, v3, v140
	v_mul_f32_e32 v124, v4, v140
	v_mul_f32_e32 v125, v5, v140
	v_mul_f32_e32 v126, v6, v140
	v_mul_f32_e32 v127, v7, v140
	v_mul_f32_e32 v128, v8, v140
	v_mul_f32_e32 v129, v9, v140
	v_mul_f32_e32 v130, v10, v140
	v_mul_f32_e32 v131, v11, v140
	v_mul_f32_e32 v132, v12, v140
	v_mul_f32_e32 v133, v13, v140
	v_mul_f32_e32 v134, v14, v140
	v_mul_f32_e32 v135, v15, v140
	v_fma_f32 v120, v120, v88, v104
	v_fma_f32 v121, v121, v89, v105
	v_fma_f32 v122, v122, v90, v106
	v_fma_f32 v123, v123, v91, v107
	v_fma_f32 v124, v124, v92, v108
	v_fma_f32 v125, v125, v93, v109
	v_fma_f32 v126, v126, v94, v110
	v_fma_f32 v127, v127, v95, v111
	v_fma_f32 v128, v128, v96, v112
	v_fma_f32 v129, v129, v97, v113
	v_fma_f32 v130, v130, v98, v114
	v_fma_f32 v131, v131, v99, v115
	v_fma_f32 v132, v132, v100, v116
	v_fma_f32 v133, v133, v101, v117
	v_fma_f32 v134, v134, v102, v118
	v_fma_f32 v135, v135, v103, v119
	v_cvt_pk_bf16_f32 v156, v120, v121
	v_cvt_pk_bf16_f32 v157, v122, v123
	v_cvt_pk_bf16_f32 v158, v124, v125
	v_cvt_pk_bf16_f32 v159, v126, v127
	v_cvt_pk_bf16_f32 v160, v128, v129
	v_cvt_pk_bf16_f32 v161, v130, v131
	v_cvt_pk_bf16_f32 v162, v132, v133
	v_cvt_pk_bf16_f32 v163, v134, v135
	s_lshl_b32 vcc_lo, s19, 11
	s_add_u32 s100, s14, vcc_lo
	s_addc_u32 s101, s15, 0
	global_store_dwordx2 v137, v[156:157], s[100:101] offset:0
	global_store_dwordx2 v137, v[158:159], s[100:101] offset:512
	global_store_dwordx2 v137, v[160:161], s[100:101] offset:1024
	global_store_dwordx2 v137, v[162:163], s[100:101] offset:1536
	s_lshl_b32 vcc_lo, s19, 11
	s_add_u32 vcc_lo, vcc_lo, 0x1000000
	s_add_u32 s100, s12, vcc_lo
	s_addc_u32 s101, s13, 0
	global_load_dwordx2 v[8:9], v137, s[100:101] offset:0
	global_load_dwordx2 v[10:11], v137, s[100:101] offset:512
	global_load_dwordx2 v[12:13], v137, s[100:101] offset:1024
	global_load_dwordx2 v[14:15], v137, s[100:101] offset:1536
	s_lshl_b32 vcc_lo, s19, 11
	s_add_u32 vcc_lo, vcc_lo, 0x1000000
	s_add_u32 s100, s14, vcc_lo
	s_addc_u32 s101, s15, 0
	global_load_dwordx2 v[48:49], v137, s[100:101] offset:0
	global_load_dwordx2 v[50:51], v137, s[100:101] offset:512
	global_load_dwordx2 v[52:53], v137, s[100:101] offset:1024
	global_load_dwordx2 v[54:55], v137, s[100:101] offset:1536
	v_lshlrev_b32_e32 v120, 16, v56
	v_and_b32_e32 v121, 0xffff0000, v56
	v_lshlrev_b32_e32 v122, 16, v57
	v_and_b32_e32 v123, 0xffff0000, v57
	v_lshlrev_b32_e32 v124, 16, v58
	v_and_b32_e32 v125, 0xffff0000, v58
	v_lshlrev_b32_e32 v126, 16, v59
	v_and_b32_e32 v127, 0xffff0000, v59
	v_lshlrev_b32_e32 v128, 16, v60
	v_and_b32_e32 v129, 0xffff0000, v60
	v_lshlrev_b32_e32 v130, 16, v61
	v_and_b32_e32 v131, 0xffff0000, v61
	v_lshlrev_b32_e32 v132, 16, v62
	v_and_b32_e32 v133, 0xffff0000, v62
	v_lshlrev_b32_e32 v134, 16, v63
	v_and_b32_e32 v135, 0xffff0000, v63
	v_mul_f32_e32 v138, v120, v120
	v_mul_f32_e32 v149, v121, v121
	v_mul_f32_e32 v150, v122, v122
	v_mul_f32_e32 v154, v123, v123
	v_fma_f32 v138, v124, v124, v138
	v_fma_f32 v149, v125, v125, v149
	v_fma_f32 v150, v126, v126, v150
	v_fma_f32 v154, v127, v127, v154
	v_fma_f32 v138, v128, v128, v138
	v_fma_f32 v149, v129, v129, v149
	v_fma_f32 v150, v130, v130, v150
	v_fma_f32 v154, v131, v131, v154
	v_fma_f32 v138, v132, v132, v138
	v_fma_f32 v149, v133, v133, v149
	v_fma_f32 v150, v134, v134, v150
	v_fma_f32 v154, v135, v135, v154
	v_add_f32_e32 v138, v138, v149
	v_add_f32_e32 v150, v150, v154
	v_add_f32_e32 v138, v138, v150
	s_nop 1
	v_add_f32_dpp v138, v138, v138 quad_perm:[1,0,3,2] row_mask:0xf bank_mask:0xf
	s_nop 1
	v_add_f32_dpp v138, v138, v138 quad_perm:[2,3,0,1] row_mask:0xf bank_mask:0xf
	s_nop 1
	v_add_f32_dpp v138, v138, v138 row_half_mirror row_mask:0xf bank_mask:0xf
	s_nop 1
	v_add_f32_dpp v138, v138, v138 row_mirror row_mask:0xf bank_mask:0xf
	v_mov_b32_e32 v139, v138
	s_nop 1
	v_permlane16_swap_b32_e32 v138, v139
	v_add_f32_e32 v138, v138, v139
	v_mov_b32_e32 v139, v138
	s_nop 1
	v_permlane32_swap_b32_e32 v138, v139
	v_add_f32_e32 v138, v138, v139
	v_mul_f32_e32 v138, 0x3a800000, v138
	v_add_f32_e32 v138, 0x358637bd, v138
	v_rsq_f32_e32 v140, v138
	v_lshlrev_b32_e32 v16, 16, v24
	v_and_b32_e32 v17, 0xffff0000, v24
	v_lshlrev_b32_e32 v18, 16, v25
	v_and_b32_e32 v19, 0xffff0000, v25
; __device__ __forceinline__ void row_phase(const Params& P, int glayer, int layer, int xsrc, bool hasY, int gate_idx, const float* gpost,
;                           int xdst, bool doH, const float* gpre, int sh_idx, int nrows) {
;     ...
;         if (hasY) {
;           float4 yv[4];
;           float ss = 0.f;
; #pragma unroll
;           for (int i = 0; i < 4; ++i) {
;             const uint2 raw = yy[u][i];
;             yv[i].x = bf2f((u16)(raw.x & 0xffff)); yv[i].y = bf2f((u16)(raw.x >> 16));
;             yv[i].z = bf2f((u16)(raw.y & 0xffff)); yv[i].w = bf2f((u16)(raw.y >> 16));
;             ss += yv[i].x * yv[i].x + yv[i].y * yv[i].y + yv[i].z * yv[i].z + yv[i].w * yv[i].w;
;           }
;           ss = wave_sum(ss);
;           const float rstd = __builtin_amdgcn_rsqf(ss * (1.f / 1024.f) + EPSF);
; #pragma unroll
;           for (int i = 0; i < 4; ++i) {
;             const int col = (i * 64 + lane) * 4;
;             const float4 gt = *reinterpret_cast<const float4*>(modg + gate_idx * 1024 + col);
;             const float4 gp = *reinterpret_cast<const float4*>(gpost + col);
;             xv[i].x += gt.x * (yv[i].x * rstd * gp.x); xv[i].y += gt.y * (yv[i].y * rstd * gp.y);
;             xv[i].z += gt.z * (yv[i].z * rstd * gp.z); xv[i].w += gt.w * (yv[i].w * rstd * gp.w);
;           }
;         }
;         if (xdst == 3 || (xdst == 1 && row >= N_X)) {
;           float* xout = (xdst == 3) ? P.out + (long)row * 1024 : P.xc + (long)(row - N_X) * 1024;
; #pragma unroll
;           for (int i = 0; i < 4; ++i) *reinterpret_cast<float4*>(xout + (i * 64 + lane) * 4) = xv[i];
;         } else if (xdst != 0) {
;           u16* xo = ((xdst == 1) ? resA : P.zf) + (long)row * 1024;
; #pragma unroll
;           for (int i = 0; i < 4; ++i) {
;             const unsigned b0 = f2bf(xv[i].x), b1 = f2bf(xv[i].y), b2 = f2bf(xv[i].z), b3 = f2bf(xv[i].w);
;             *reinterpret_cast<uint2*>(xo + (i * 64 + lane) * 4) = make_uint2(b0 | (b1 << 16), b2 | (b3 << 16));
;           }
;         }
;         if (doH) {
;           float ss = 0.f;
; #pragma unroll
;           for (int i = 0; i < 4; ++i) ss += xv[i].x * xv[i].x + xv[i].y * xv[i].y + xv[i].z * xv[i].z + xv[i].w * xv[i].w;
;           ss = wave_sum(ss);
;           const float rstd = __builtin_amdgcn_rsqf(ss * (1.f / 1024.f) + EPSF);
;           u16* h = P.hy + (long)row * 1024;
; #pragma unroll
	v_lshlrev_b32_e32 v20, 16, v26
	v_and_b32_e32 v21, 0xffff0000, v26
	v_lshlrev_b32_e32 v22, 16, v27
	v_and_b32_e32 v23, 0xffff0000, v27
	v_lshlrev_b32_e32 v24, 16, v28
	v_and_b32_e32 v25, 0xffff0000, v28
	v_lshlrev_b32_e32 v26, 16, v29
	v_and_b32_e32 v27, 0xffff0000, v29
	v_lshlrev_b32_e32 v28, 16, v30
	v_and_b32_e32 v29, 0xffff0000, v30
	v_lshlrev_b32_e32 v30, 16, v31
	v_and_b32_e32 v31, 0xffff0000, v31
	s_nop 0
	v_mul_f32_e32 v120, v120, v140
	v_mul_f32_e32 v121, v121, v140
	v_mul_f32_e32 v122, v122, v140
	v_mul_f32_e32 v123, v123, v140
	v_mul_f32_e32 v124, v124, v140
	v_mul_f32_e32 v125, v125, v140
	v_mul_f32_e32 v126, v126, v140
	v_mul_f32_e32 v127, v127, v140
	v_mul_f32_e32 v128, v128, v140
	v_mul_f32_e32 v129, v129, v140
	v_mul_f32_e32 v130, v130, v140
	v_mul_f32_e32 v131, v131, v140
	v_mul_f32_e32 v132, v132, v140
	v_mul_f32_e32 v133, v133, v140
	v_mul_f32_e32 v134, v134, v140
	v_mul_f32_e32 v135, v135, v140
	v_fma_f32 v16, v120, v72, v16
	v_fma_f32 v17, v121, v73, v17
	v_fma_f32 v18, v122, v74, v18
	v_fma_f32 v19, v123, v75, v19
	v_fma_f32 v20, v124, v76, v20
	v_fma_f32 v21, v125, v77, v21
	v_fma_f32 v22, v126, v78, v22
	v_fma_f32 v23, v127, v79, v23
	v_fma_f32 v24, v128, v80, v24
	v_fma_f32 v25, v129, v81, v25
	v_fma_f32 v26, v130, v82, v26
	v_fma_f32 v27, v131, v83, v27
	v_fma_f32 v28, v132, v84, v28
	v_fma_f32 v29, v133, v85, v29
	v_fma_f32 v30, v134, v86, v30
	v_fma_f32 v31, v135, v87, v31
	v_cvt_pk_bf16_f32 v156, v16, v17
	v_cvt_pk_bf16_f32 v157, v18, v19
	v_cvt_pk_bf16_f32 v158, v20, v21
	v_cvt_pk_bf16_f32 v159, v22, v23
	v_cvt_pk_bf16_f32 v160, v24, v25
	v_cvt_pk_bf16_f32 v161, v26, v27
	v_cvt_pk_bf16_f32 v162, v28, v29
	v_cvt_pk_bf16_f32 v163, v30, v31
	s_lshl_b32 vcc_lo, s19, 11
	s_add_u32 vcc_lo, vcc_lo, 0x400000
	s_add_u32 s100, s16, vcc_lo
	s_addc_u32 s101, s17, 0
	global_store_dwordx2 v137, v[156:157], s[100:101] offset:0
	global_store_dwordx2 v137, v[158:159], s[100:101] offset:512
	global_store_dwordx2 v137, v[160:161], s[100:101] offset:1024
	global_store_dwordx2 v137, v[162:163], s[100:101] offset:1536
	v_mul_f32_e32 v138, v16, v16
	v_mul_f32_e32 v149, v17, v17
	v_mul_f32_e32 v150, v18, v18
	v_mul_f32_e32 v154, v19, v19
	v_fma_f32 v138, v20, v20, v138
	v_fma_f32 v149, v21, v21, v149
	v_fma_f32 v150, v22, v22, v150
	v_fma_f32 v154, v23, v23, v154
	v_fma_f32 v138, v24, v24, v138
	v_fma_f32 v149, v25, v25, v149
	v_fma_f32 v150, v26, v26, v150
	v_fma_f32 v154, v27, v27, v154
	v_fma_f32 v138, v28, v28, v138
	v_fma_f32 v149, v29, v29, v149
	v_fma_f32 v150, v30, v30, v150
	v_fma_f32 v154, v31, v31, v154
	v_add_f32_e32 v138, v138, v149
	v_add_f32_e32 v150, v150, v154
	v_add_f32_e32 v138, v138, v150
	s_nop 1
	v_add_f32_dpp v138, v138, v138 quad_perm:[1,0,3,2] row_mask:0xf bank_mask:0xf
	s_nop 1
	v_add_f32_dpp v138, v138, v138 quad_perm:[2,3,0,1] row_mask:0xf bank_mask:0xf
	s_nop 1
	v_add_f32_dpp v138, v138, v138 row_half_mirror row_mask:0xf bank_mask:0xf
	s_nop 1
	v_add_f32_dpp v138, v138, v138 row_mirror row_mask:0xf bank_mask:0xf
	v_mov_b32_e32 v139, v138
	s_nop 1
	v_permlane16_swap_b32_e32 v138, v139
	v_add_f32_e32 v138, v138, v139
	v_mov_b32_e32 v139, v138
	s_nop 1
	v_permlane32_swap_b32_e32 v138, v139
	v_add_f32_e32 v138, v138, v139
	v_mul_f32_e32 v138, 0x3a800000, v138
	v_add_f32_e32 v138, 0x358637bd, v138
	v_rsq_f32_e32 v140, v138
	s_nop 0
	v_mul_f32_e32 v120, v16, v140
	v_mul_f32_e32 v121, v17, v140
	v_mul_f32_e32 v122, v18, v140
	v_mul_f32_e32 v123, v19, v140
	v_mul_f32_e32 v124, v20, v140
	v_mul_f32_e32 v125, v21, v140
	v_mul_f32_e32 v126, v22, v140
	v_mul_f32_e32 v127, v23, v140
	v_mul_f32_e32 v128, v24, v140
	v_mul_f32_e32 v129, v25, v140
	v_mul_f32_e32 v130, v26, v140
	v_mul_f32_e32 v131, v27, v140
	v_mul_f32_e32 v132, v28, v140
	v_mul_f32_e32 v133, v29, v140
	v_mul_f32_e32 v134, v30, v140
	v_mul_f32_e32 v135, v31, v140
	v_fma_f32 v120, v120, v88, v104
	v_fma_f32 v121, v121, v89, v105
	v_fma_f32 v122, v122, v90, v106
	v_fma_f32 v123, v123, v91, v107
	v_fma_f32 v124, v124, v92, v108
	v_fma_f32 v125, v125, v93, v109
	v_fma_f32 v126, v126, v94, v110
	v_fma_f32 v127, v127, v95, v111
	v_fma_f32 v128, v128, v96, v112
	v_fma_f32 v129, v129, v97, v113
	v_fma_f32 v130, v130, v98, v114
	v_fma_f32 v131, v131, v99, v115
	v_fma_f32 v132, v132, v100, v116
	v_fma_f32 v133, v133, v101, v117
	v_fma_f32 v134, v134, v102, v118
	v_fma_f32 v135, v135, v103, v119
	v_cvt_pk_bf16_f32 v156, v120, v121
	v_cvt_pk_bf16_f32 v157, v122, v123
	v_cvt_pk_bf16_f32 v158, v124, v125
	v_cvt_pk_bf16_f32 v159, v126, v127
	v_cvt_pk_bf16_f32 v160, v128, v129
	v_cvt_pk_bf16_f32 v161, v130, v131
	v_cvt_pk_bf16_f32 v162, v132, v133
	v_cvt_pk_bf16_f32 v163, v134, v135
	s_lshl_b32 vcc_lo, s19, 11
	s_add_u32 vcc_lo, vcc_lo, 0x400000
	s_add_u32 s100, s14, vcc_lo
	s_addc_u32 s101, s15, 0
	global_store_dwordx2 v137, v[156:157], s[100:101] offset:0
	global_store_dwordx2 v137, v[158:159], s[100:101] offset:512
	global_store_dwordx2 v137, v[160:161], s[100:101] offset:1024
	global_store_dwordx2 v137, v[162:163], s[100:101] offset:1536
	s_lshl_b32 vcc_lo, s19, 11
	s_add_u32 vcc_lo, vcc_lo, 0x1400000
	s_add_u32 s100, s12, vcc_lo
	s_addc_u32 s101, s13, 0
	global_load_dwordx2 v[24:25], v137, s[100:101] offset:0
	global_load_dwordx2 v[26:27], v137, s[100:101] offset:512
	global_load_dwordx2 v[28:29], v137, s[100:101] offset:1024
	global_load_dwordx2 v[30:31], v137, s[100:101] offset:1536
	s_lshl_b32 vcc_lo, s19, 11
	s_add_u32 vcc_lo, vcc_lo, 0x1400000
	s_add_u32 s100, s14, vcc_lo
	s_addc_u32 s101, s15, 0
	global_load_dwordx2 v[56:57], v137, s[100:101] offset:0
	global_load_dwordx2 v[58:59], v137, s[100:101] offset:512
	global_load_dwordx2 v[60:61], v137, s[100:101] offset:1024
; __device__ __forceinline__ void row_phase(const Params& P, int glayer, int layer, int xsrc, bool hasY, int gate_idx, const float* gpost,
;                           int xdst, bool doH, const float* gpre, int sh_idx, int nrows) {
;     ...
;         if (hasY) {
;           float4 yv[4];
;           float ss = 0.f;
; #pragma unroll
;           for (int i = 0; i < 4; ++i) {
;             const uint2 raw = yy[u][i];
;             yv[i].x = bf2f((u16)(raw.x & 0xffff)); yv[i].y = bf2f((u16)(raw.x >> 16));
;             yv[i].z = bf2f((u16)(raw.y & 0xffff)); yv[i].w = bf2f((u16)(raw.y >> 16));
;             ss += yv[i].x * yv[i].x + yv[i].y * yv[i].y + yv[i].z * yv[i].z + yv[i].w * yv[i].w;
;           }
;           ss = wave_sum(ss);
;           const float rstd = __builtin_amdgcn_rsqf(ss * (1.f / 1024.f) + EPSF);
; #pragma unroll
;           for (int i = 0; i < 4; ++i) {
;             const int col = (i * 64 + lane) * 4;
;             const float4 gt = *reinterpret_cast<const float4*>(modg + gate_idx * 1024 + col);
;             const float4 gp = *reinterpret_cast<const float4*>(gpost + col);
;             xv[i].x += gt.x * (yv[i].x * rstd * gp.x); xv[i].y += gt.y * (yv[i].y * rstd * gp.y);
;             xv[i].z += gt.z * (yv[i].z * rstd * gp.z); xv[i].w += gt.w * (yv[i].w * rstd * gp.w);
;           }
;         }
;         if (xdst == 3 || (xdst == 1 && row >= N_X)) {
;           float* xout = (xdst == 3) ? P.out + (long)row * 1024 : P.xc + (long)(row - N_X) * 1024;
; #pragma unroll
;           for (int i = 0; i < 4; ++i) *reinterpret_cast<float4*>(xout + (i * 64 + lane) * 4) = xv[i];
;         } else if (xdst != 0) {
;           u16* xo = ((xdst == 1) ? resA : P.zf) + (long)row * 1024;
; #pragma unroll
;           for (int i = 0; i < 4; ++i) {
;             const unsigned b0 = f2bf(xv[i].x), b1 = f2bf(xv[i].y), b2 = f2bf(xv[i].z), b3 = f2bf(xv[i].w);
;             *reinterpret_cast<uint2*>(xo + (i * 64 + lane) * 4) = make_uint2(b0 | (b1 << 16), b2 | (b3 << 16));
;           }
;         }
;         if (doH) {
;           float ss = 0.f;
; #pragma unroll
;           for (int i = 0; i < 4; ++i) ss += xv[i].x * xv[i].x + xv[i].y * xv[i].y + xv[i].z * xv[i].z + xv[i].w * xv[i].w;
;           ss = wave_sum(ss);
;           const float rstd = __builtin_amdgcn_rsqf(ss * (1.f / 1024.f) + EPSF);
;           u16* h = P.hy + (long)row * 1024;
; #pragma unroll
	global_load_dwordx2 v[62:63], v137, s[100:101] offset:1536
	v_lshlrev_b32_e32 v120, 16, v64
	v_and_b32_e32 v121, 0xffff0000, v64
	v_lshlrev_b32_e32 v122, 16, v65
	v_and_b32_e32 v123, 0xffff0000, v65
	v_lshlrev_b32_e32 v124, 16, v66
	v_and_b32_e32 v125, 0xffff0000, v66
	v_lshlrev_b32_e32 v126, 16, v67
	v_and_b32_e32 v127, 0xffff0000, v67
	v_lshlrev_b32_e32 v128, 16, v68
	v_and_b32_e32 v129, 0xffff0000, v68
	v_lshlrev_b32_e32 v130, 16, v69
	v_and_b32_e32 v131, 0xffff0000, v69
	v_lshlrev_b32_e32 v132, 16, v70
	v_and_b32_e32 v133, 0xffff0000, v70
	v_lshlrev_b32_e32 v134, 16, v71
	v_and_b32_e32 v135, 0xffff0000, v71
	v_mul_f32_e32 v138, v120, v120
	v_mul_f32_e32 v149, v121, v121
	v_mul_f32_e32 v150, v122, v122
	v_mul_f32_e32 v154, v123, v123
	v_fma_f32 v138, v124, v124, v138
	v_fma_f32 v149, v125, v125, v149
	v_fma_f32 v150, v126, v126, v150
	v_fma_f32 v154, v127, v127, v154
	v_fma_f32 v138, v128, v128, v138
	v_fma_f32 v149, v129, v129, v149
	v_fma_f32 v150, v130, v130, v150
	v_fma_f32 v154, v131, v131, v154
	v_fma_f32 v138, v132, v132, v138
	v_fma_f32 v149, v133, v133, v149
	v_fma_f32 v150, v134, v134, v150
	v_fma_f32 v154, v135, v135, v154
	v_add_f32_e32 v138, v138, v149
	v_add_f32_e32 v150, v150, v154
	v_add_f32_e32 v138, v138, v150
	s_nop 1
	v_add_f32_dpp v138, v138, v138 quad_perm:[1,0,3,2] row_mask:0xf bank_mask:0xf
	s_nop 1
	v_add_f32_dpp v138, v138, v138 quad_perm:[2,3,0,1] row_mask:0xf bank_mask:0xf
	s_nop 1
	v_add_f32_dpp v138, v138, v138 row_half_mirror row_mask:0xf bank_mask:0xf
	s_nop 1
	v_add_f32_dpp v138, v138, v138 row_mirror row_mask:0xf bank_mask:0xf
	v_mov_b32_e32 v139, v138
	s_nop 1
	v_permlane16_swap_b32_e32 v138, v139
	v_add_f32_e32 v138, v138, v139
	v_mov_b32_e32 v139, v138
	s_nop 1
	v_permlane32_swap_b32_e32 v138, v139
	v_add_f32_e32 v138, v138, v139
	v_mul_f32_e32 v138, 0x3a800000, v138
	v_add_f32_e32 v138, 0x358637bd, v138
	v_rsq_f32_e32 v140, v138
	v_lshlrev_b32_e32 v32, 16, v40
	v_and_b32_e32 v33, 0xffff0000, v40
	v_lshlrev_b32_e32 v34, 16, v41
	v_and_b32_e32 v35, 0xffff0000, v41
	v_lshlrev_b32_e32 v36, 16, v42
	v_and_b32_e32 v37, 0xffff0000, v42
	v_lshlrev_b32_e32 v38, 16, v43
	v_and_b32_e32 v39, 0xffff0000, v43
	v_lshlrev_b32_e32 v40, 16, v44
	v_and_b32_e32 v41, 0xffff0000, v44
	v_lshlrev_b32_e32 v42, 16, v45
	v_and_b32_e32 v43, 0xffff0000, v45
	v_lshlrev_b32_e32 v44, 16, v46
	v_and_b32_e32 v45, 0xffff0000, v46
	v_lshlrev_b32_e32 v46, 16, v47
	v_and_b32_e32 v47, 0xffff0000, v47
	s_nop 0
	v_mul_f32_e32 v120, v120, v140
	v_mul_f32_e32 v121, v121, v140
	v_mul_f32_e32 v122, v122, v140
	v_mul_f32_e32 v123, v123, v140
	v_mul_f32_e32 v124, v124, v140
	v_mul_f32_e32 v125, v125, v140
	v_mul_f32_e32 v126, v126, v140
	v_mul_f32_e32 v127, v127, v140
	v_mul_f32_e32 v128, v128, v140
	v_mul_f32_e32 v129, v129, v140
	v_mul_f32_e32 v130, v130, v140
	v_mul_f32_e32 v131, v131, v140
	v_mul_f32_e32 v132, v132, v140
	v_mul_f32_e32 v133, v133, v140
	v_mul_f32_e32 v134, v134, v140
	v_mul_f32_e32 v135, v135, v140
	v_fma_f32 v32, v120, v72, v32
	v_fma_f32 v33, v121, v73, v33
	v_fma_f32 v34, v122, v74, v34
	v_fma_f32 v35, v123, v75, v35
	v_fma_f32 v36, v124, v76, v36
	v_fma_f32 v37, v125, v77, v37
	v_fma_f32 v38, v126, v78, v38
	v_fma_f32 v39, v127, v79, v39
	v_fma_f32 v40, v128, v80, v40
	v_fma_f32 v41, v129, v81, v41
	v_fma_f32 v42, v130, v82, v42
	v_fma_f32 v43, v131, v83, v43
	v_fma_f32 v44, v132, v84, v44
	v_fma_f32 v45, v133, v85, v45
	v_fma_f32 v46, v134, v86, v46
	v_fma_f32 v47, v135, v87, v47
	v_cvt_pk_bf16_f32 v156, v32, v33
	v_cvt_pk_bf16_f32 v157, v34, v35
	v_cvt_pk_bf16_f32 v158, v36, v37
	v_cvt_pk_bf16_f32 v159, v38, v39
	v_cvt_pk_bf16_f32 v160, v40, v41
	v_cvt_pk_bf16_f32 v161, v42, v43
	v_cvt_pk_bf16_f32 v162, v44, v45
	v_cvt_pk_bf16_f32 v163, v46, v47
	s_lshl_b32 vcc_lo, s19, 11
	s_add_u32 vcc_lo, vcc_lo, 0x800000
	s_add_u32 s100, s16, vcc_lo
	s_addc_u32 s101, s17, 0
	global_store_dwordx2 v137, v[156:157], s[100:101] offset:0
	global_store_dwordx2 v137, v[158:159], s[100:101] offset:512
	global_store_dwordx2 v137, v[160:161], s[100:101] offset:1024
	global_store_dwordx2 v137, v[162:163], s[100:101] offset:1536
	v_mul_f32_e32 v138, v32, v32
	v_mul_f32_e32 v149, v33, v33
	v_mul_f32_e32 v150, v34, v34
	v_mul_f32_e32 v154, v35, v35
	v_fma_f32 v138, v36, v36, v138
	v_fma_f32 v149, v37, v37, v149
	v_fma_f32 v150, v38, v38, v150
	v_fma_f32 v154, v39, v39, v154
	v_fma_f32 v138, v40, v40, v138
	v_fma_f32 v149, v41, v41, v149
	v_fma_f32 v150, v42, v42, v150
	v_fma_f32 v154, v43, v43, v154
	v_fma_f32 v138, v44, v44, v138
	v_fma_f32 v149, v45, v45, v149
	v_fma_f32 v150, v46, v46, v150
	v_fma_f32 v154, v47, v47, v154
	v_add_f32_e32 v138, v138, v149
	v_add_f32_e32 v150, v150, v154
	v_add_f32_e32 v138, v138, v150
	s_nop 1
	v_add_f32_dpp v138, v138, v138 quad_perm:[1,0,3,2] row_mask:0xf bank_mask:0xf
	s_nop 1
	v_add_f32_dpp v138, v138, v138 quad_perm:[2,3,0,1] row_mask:0xf bank_mask:0xf
	s_nop 1
	v_add_f32_dpp v138, v138, v138 row_half_mirror row_mask:0xf bank_mask:0xf
	s_nop 1
	v_add_f32_dpp v138, v138, v138 row_mirror row_mask:0xf bank_mask:0xf
	v_mov_b32_e32 v139, v138
	s_nop 1
	v_permlane16_swap_b32_e32 v138, v139
	v_add_f32_e32 v138, v138, v139
	v_mov_b32_e32 v139, v138
	s_nop 1
	v_permlane32_swap_b32_e32 v138, v139
	v_add_f32_e32 v138, v138, v139
	v_mul_f32_e32 v138, 0x3a800000, v138
	v_add_f32_e32 v138, 0x358637bd, v138
	v_rsq_f32_e32 v140, v138
	s_nop 0
	v_mul_f32_e32 v120, v32, v140
	v_mul_f32_e32 v121, v33, v140
	v_mul_f32_e32 v122, v34, v140
	v_mul_f32_e32 v123, v35, v140
	v_mul_f32_e32 v124, v36, v140
	v_mul_f32_e32 v125, v37, v140
	v_mul_f32_e32 v126, v38, v140
	v_mul_f32_e32 v127, v39, v140
	v_mul_f32_e32 v128, v40, v140
; __device__ __forceinline__ void row_phase(const Params& P, int glayer, int layer, int xsrc, bool hasY, int gate_idx, const float* gpost,
;                           int xdst, bool doH, const float* gpre, int sh_idx, int nrows) {
;     ...
;         if (hasY) {
;           float4 yv[4];
;           float ss = 0.f;
; #pragma unroll
;           for (int i = 0; i < 4; ++i) {
;             const uint2 raw = yy[u][i];
;             yv[i].x = bf2f((u16)(raw.x & 0xffff)); yv[i].y = bf2f((u16)(raw.x >> 16));
;             yv[i].z = bf2f((u16)(raw.y & 0xffff)); yv[i].w = bf2f((u16)(raw.y >> 16));
;             ss += yv[i].x * yv[i].x + yv[i].y * yv[i].y + yv[i].z * yv[i].z + yv[i].w * yv[i].w;
;           }
;           ss = wave_sum(ss);
;           const float rstd = __builtin_amdgcn_rsqf(ss * (1.f / 1024.f) + EPSF);
; #pragma unroll
;           for (int i = 0; i < 4; ++i) {
;             const int col = (i * 64 + lane) * 4;
;             const float4 gt = *reinterpret_cast<const float4*>(modg + gate_idx * 1024 + col);
;             const float4 gp = *reinterpret_cast<const float4*>(gpost + col);
;             xv[i].x += gt.x * (yv[i].x * rstd * gp.x); xv[i].y += gt.y * (yv[i].y * rstd * gp.y);
;             xv[i].z += gt.z * (yv[i].z * rstd * gp.z); xv[i].w += gt.w * (yv[i].w * rstd * gp.w);
;           }
;         }
;         if (xdst == 3 || (xdst == 1 && row >= N_X)) {
;           float* xout = (xdst == 3) ? P.out + (long)row * 1024 : P.xc + (long)(row - N_X) * 1024;
; #pragma unroll
;           for (int i = 0; i < 4; ++i) *reinterpret_cast<float4*>(xout + (i * 64 + lane) * 4) = xv[i];
;         } else if (xdst != 0) {
;           u16* xo = ((xdst == 1) ? resA : P.zf) + (long)row * 1024;
; #pragma unroll
;           for (int i = 0; i < 4; ++i) {
;             const unsigned b0 = f2bf(xv[i].x), b1 = f2bf(xv[i].y), b2 = f2bf(xv[i].z), b3 = f2bf(xv[i].w);
;             *reinterpret_cast<uint2*>(xo + (i * 64 + lane) * 4) = make_uint2(b0 | (b1 << 16), b2 | (b3 << 16));
;           }
;         }
;         if (doH) {
;           float ss = 0.f;
; #pragma unroll
;           for (int i = 0; i < 4; ++i) ss += xv[i].x * xv[i].x + xv[i].y * xv[i].y + xv[i].z * xv[i].z + xv[i].w * xv[i].w;
;           ss = wave_sum(ss);
;           const float rstd = __builtin_amdgcn_rsqf(ss * (1.f / 1024.f) + EPSF);
;           u16* h = P.hy + (long)row * 1024;
; #pragma unroll
	v_mul_f32_e32 v129, v41, v140
	v_mul_f32_e32 v130, v42, v140
	v_mul_f32_e32 v131, v43, v140
	v_mul_f32_e32 v132, v44, v140
	v_mul_f32_e32 v133, v45, v140
	v_mul_f32_e32 v134, v46, v140
	v_mul_f32_e32 v135, v47, v140
	v_fma_f32 v120, v120, v88, v104
	v_fma_f32 v121, v121, v89, v105
	v_fma_f32 v122, v122, v90, v106
	v_fma_f32 v123, v123, v91, v107
	v_fma_f32 v124, v124, v92, v108
	v_fma_f32 v125, v125, v93, v109
	v_fma_f32 v126, v126, v94, v110
	v_fma_f32 v127, v127, v95, v111
	v_fma_f32 v128, v128, v96, v112
	v_fma_f32 v129, v129, v97, v113
	v_fma_f32 v130, v130, v98, v114
	v_fma_f32 v131, v131, v99, v115
	v_fma_f32 v132, v132, v100, v116
	v_fma_f32 v133, v133, v101, v117
	v_fma_f32 v134, v134, v102, v118
	v_fma_f32 v135, v135, v103, v119
	v_cvt_pk_bf16_f32 v156, v120, v121
	v_cvt_pk_bf16_f32 v157, v122, v123
	v_cvt_pk_bf16_f32 v158, v124, v125
	v_cvt_pk_bf16_f32 v159, v126, v127
	v_cvt_pk_bf16_f32 v160, v128, v129
	v_cvt_pk_bf16_f32 v161, v130, v131
	v_cvt_pk_bf16_f32 v162, v132, v133
	v_cvt_pk_bf16_f32 v163, v134, v135
	s_lshl_b32 vcc_lo, s19, 11
	s_add_u32 vcc_lo, vcc_lo, 0x800000
	s_add_u32 s100, s14, vcc_lo
	s_addc_u32 s101, s15, 0
	global_store_dwordx2 v137, v[156:157], s[100:101] offset:0
	global_store_dwordx2 v137, v[158:159], s[100:101] offset:512
	global_store_dwordx2 v137, v[160:161], s[100:101] offset:1024
	global_store_dwordx2 v137, v[162:163], s[100:101] offset:1536
	s_lshl_b32 vcc_lo, s19, 11
	s_add_u32 vcc_lo, vcc_lo, 0x1800000
	s_add_u32 s100, s12, vcc_lo
	s_addc_u32 s101, s13, 0
	global_load_dwordx2 v[40:41], v137, s[100:101] offset:0
	global_load_dwordx2 v[42:43], v137, s[100:101] offset:512
	global_load_dwordx2 v[44:45], v137, s[100:101] offset:1024
	global_load_dwordx2 v[46:47], v137, s[100:101] offset:1536
	s_lshl_b32 vcc_lo, s19, 11
	s_add_u32 vcc_lo, vcc_lo, 0x1800000
	s_add_u32 s100, s14, vcc_lo
	s_addc_u32 s101, s15, 0
	global_load_dwordx2 v[64:65], v137, s[100:101] offset:0
	global_load_dwordx2 v[66:67], v137, s[100:101] offset:512
	global_load_dwordx2 v[68:69], v137, s[100:101] offset:1024
	global_load_dwordx2 v[70:71], v137, s[100:101] offset:1536
	s_waitcnt vmcnt(48)
	v_lshlrev_b32_e32 v120, 16, v182
	v_and_b32_e32 v121, 0xffff0000, v182
	v_lshlrev_b32_e32 v122, 16, v183
	v_and_b32_e32 v123, 0xffff0000, v183
	v_lshlrev_b32_e32 v124, 16, v184
	v_and_b32_e32 v125, 0xffff0000, v184
	v_lshlrev_b32_e32 v126, 16, v185
	v_and_b32_e32 v127, 0xffff0000, v185
	v_lshlrev_b32_e32 v128, 16, v186
	v_and_b32_e32 v129, 0xffff0000, v186
	v_lshlrev_b32_e32 v130, 16, v187
	v_and_b32_e32 v131, 0xffff0000, v187
	v_lshlrev_b32_e32 v132, 16, v188
	v_and_b32_e32 v133, 0xffff0000, v188
	v_lshlrev_b32_e32 v134, 16, v189
	v_and_b32_e32 v135, 0xffff0000, v189
	v_mul_f32_e32 v138, v120, v120
	v_mul_f32_e32 v149, v121, v121
	v_mul_f32_e32 v150, v122, v122
	v_mul_f32_e32 v154, v123, v123
	v_fma_f32 v138, v124, v124, v138
	v_fma_f32 v149, v125, v125, v149
	v_fma_f32 v150, v126, v126, v150
	v_fma_f32 v154, v127, v127, v154
	v_fma_f32 v138, v128, v128, v138
	v_fma_f32 v149, v129, v129, v149
	v_fma_f32 v150, v130, v130, v150
	v_fma_f32 v154, v131, v131, v154
	v_fma_f32 v138, v132, v132, v138
	v_fma_f32 v149, v133, v133, v149
	v_fma_f32 v150, v134, v134, v150
	v_fma_f32 v154, v135, v135, v154
	v_add_f32_e32 v138, v138, v149
	v_add_f32_e32 v150, v150, v154
	v_add_f32_e32 v138, v138, v150
	s_nop 1
	v_add_f32_dpp v138, v138, v138 quad_perm:[1,0,3,2] row_mask:0xf bank_mask:0xf
	s_nop 1
	v_add_f32_dpp v138, v138, v138 quad_perm:[2,3,0,1] row_mask:0xf bank_mask:0xf
	s_nop 1
	v_add_f32_dpp v138, v138, v138 row_half_mirror row_mask:0xf bank_mask:0xf
	s_nop 1
	v_add_f32_dpp v138, v138, v138 row_mirror row_mask:0xf bank_mask:0xf
	v_mov_b32_e32 v139, v138
	s_nop 1
	v_permlane16_swap_b32_e32 v138, v139
	v_add_f32_e32 v138, v138, v139
	v_mov_b32_e32 v139, v138
	s_nop 1
	v_permlane32_swap_b32_e32 v138, v139
	v_add_f32_e32 v138, v138, v139
	v_mul_f32_e32 v138, 0x3a800000, v138
	v_add_f32_e32 v138, 0x358637bd, v138
	v_rsq_f32_e32 v140, v138
	v_lshlrev_b32_e32 v166, 16, v174
	v_and_b32_e32 v167, 0xffff0000, v174
	v_lshlrev_b32_e32 v168, 16, v175
	v_and_b32_e32 v169, 0xffff0000, v175
	v_lshlrev_b32_e32 v170, 16, v176
	v_and_b32_e32 v171, 0xffff0000, v176
	v_lshlrev_b32_e32 v172, 16, v177
	v_and_b32_e32 v173, 0xffff0000, v177
	v_lshlrev_b32_e32 v174, 16, v178
	v_and_b32_e32 v175, 0xffff0000, v178
	v_lshlrev_b32_e32 v176, 16, v179
	v_and_b32_e32 v177, 0xffff0000, v179
	v_lshlrev_b32_e32 v178, 16, v180
	v_and_b32_e32 v179, 0xffff0000, v180
	v_lshlrev_b32_e32 v180, 16, v181
	v_and_b32_e32 v181, 0xffff0000, v181
	s_nop 0
	v_mul_f32_e32 v120, v120, v140
	v_mul_f32_e32 v121, v121, v140
	v_mul_f32_e32 v122, v122, v140
	v_mul_f32_e32 v123, v123, v140
	v_mul_f32_e32 v124, v124, v140
	v_mul_f32_e32 v125, v125, v140
	v_mul_f32_e32 v126, v126, v140
	v_mul_f32_e32 v127, v127, v140
	v_mul_f32_e32 v128, v128, v140
	v_mul_f32_e32 v129, v129, v140
	v_mul_f32_e32 v130, v130, v140
	v_mul_f32_e32 v131, v131, v140
	v_mul_f32_e32 v132, v132, v140
	v_mul_f32_e32 v133, v133, v140
	v_mul_f32_e32 v134, v134, v140
	v_mul_f32_e32 v135, v135, v140
	v_fma_f32 v166, v120, v72, v166
	v_fma_f32 v167, v121, v73, v167
	v_fma_f32 v168, v122, v74, v168
	v_fma_f32 v169, v123, v75, v169
	v_fma_f32 v170, v124, v76, v170
	v_fma_f32 v171, v125, v77, v171
	v_fma_f32 v172, v126, v78, v172
	v_fma_f32 v173, v127, v79, v173
	v_fma_f32 v174, v128, v80, v174
	v_fma_f32 v175, v129, v81, v175
	v_fma_f32 v176, v130, v82, v176
	v_fma_f32 v177, v131, v83, v177
	v_fma_f32 v178, v132, v84, v178
	v_fma_f32 v179, v133, v85, v179
	v_fma_f32 v180, v134, v86, v180
	v_fma_f32 v181, v135, v87, v181
	v_cvt_pk_bf16_f32 v156, v166, v167
; __device__ __forceinline__ void row_phase(const Params& P, int glayer, int layer, int xsrc, bool hasY, int gate_idx, const float* gpost,
;                           int xdst, bool doH, const float* gpre, int sh_idx, int nrows) {
;     ...
;         if (xdst == 3 || (xdst == 1 && row >= N_X)) {
;           float* xout = (xdst == 3) ? P.out + (long)row * 1024 : P.xc + (long)(row - N_X) * 1024;
; #pragma unroll
;           for (int i = 0; i < 4; ++i) *reinterpret_cast<float4*>(xout + (i * 64 + lane) * 4) = xv[i];
;         } else if (xdst != 0) {
;           u16* xo = ((xdst == 1) ? resA : P.zf) + (long)row * 1024;
; #pragma unroll
;           for (int i = 0; i < 4; ++i) {
;             const unsigned b0 = f2bf(xv[i].x), b1 = f2bf(xv[i].y), b2 = f2bf(xv[i].z), b3 = f2bf(xv[i].w);
;             *reinterpret_cast<uint2*>(xo + (i * 64 + lane) * 4) = make_uint2(b0 | (b1 << 16), b2 | (b3 << 16));
;           }
;         }
;         if (doH) {
;           float ss = 0.f;
; #pragma unroll
;           for (int i = 0; i < 4; ++i) ss += xv[i].x * xv[i].x + xv[i].y * xv[i].y + xv[i].z * xv[i].z + xv[i].w * xv[i].w;
;           ss = wave_sum(ss);
;           const float rstd = __builtin_amdgcn_rsqf(ss * (1.f / 1024.f) + EPSF);
;           u16* h = P.hy + (long)row * 1024;
; #pragma unroll
;           for (int i = 0; i < 4; ++i) {
;             const int col = (i * 64 + lane) * 4;
;             const float4 g = *reinterpret_cast<const float4*>(gpre + col);
;             const float4 sh = *reinterpret_cast<const float4*>(modp + sh_idx * 1024 + col);
;             const float4 sc = *reinterpret_cast<const float4*>(modp + (sh_idx + 1) * 1024 + col);
;             const unsigned h0 = f2bf(xv[i].x * rstd * g.x * (1.f + sc.x) + sh.x);
;             const unsigned h1 = f2bf(xv[i].y * rstd * g.y * (1.f + sc.y) + sh.y);
;             const unsigned h2 = f2bf(xv[i].z * rstd * g.z * (1.f + sc.z) + sh.z);
;             const unsigned h3 = f2bf(xv[i].w * rstd * g.w * (1.f + sc.w) + sh.w);
;             *reinterpret_cast<uint2*>(h + col) = make_uint2(h0 | (h1 << 16), h2 | (h3 << 16));
;           }
	v_cvt_pk_bf16_f32 v157, v168, v169
	v_cvt_pk_bf16_f32 v158, v170, v171
	v_cvt_pk_bf16_f32 v159, v172, v173
	v_cvt_pk_bf16_f32 v160, v174, v175
	v_cvt_pk_bf16_f32 v161, v176, v177
	v_cvt_pk_bf16_f32 v162, v178, v179
	v_cvt_pk_bf16_f32 v163, v180, v181
	s_lshl_b32 vcc_lo, s19, 11
	s_add_u32 vcc_lo, vcc_lo, 0xc00000
	s_add_u32 s100, s16, vcc_lo
	s_addc_u32 s101, s17, 0
	global_store_dwordx2 v137, v[156:157], s[100:101] offset:0
	global_store_dwordx2 v137, v[158:159], s[100:101] offset:512
	global_store_dwordx2 v137, v[160:161], s[100:101] offset:1024
	global_store_dwordx2 v137, v[162:163], s[100:101] offset:1536
	v_mul_f32_e32 v138, v166, v166
	v_mul_f32_e32 v149, v167, v167
	v_mul_f32_e32 v150, v168, v168
	v_mul_f32_e32 v154, v169, v169
	v_fma_f32 v138, v170, v170, v138
	v_fma_f32 v149, v171, v171, v149
	v_fma_f32 v150, v172, v172, v150
	v_fma_f32 v154, v173, v173, v154
	v_fma_f32 v138, v174, v174, v138
	v_fma_f32 v149, v175, v175, v149
	v_fma_f32 v150, v176, v176, v150
	v_fma_f32 v154, v177, v177, v154
	v_fma_f32 v138, v178, v178, v138
	v_fma_f32 v149, v179, v179, v149
	v_fma_f32 v150, v180, v180, v150
	v_fma_f32 v154, v181, v181, v154
	v_add_f32_e32 v138, v138, v149
	v_add_f32_e32 v150, v150, v154
	v_add_f32_e32 v138, v138, v150
	s_nop 1
	v_add_f32_dpp v138, v138, v138 quad_perm:[1,0,3,2] row_mask:0xf bank_mask:0xf
	s_nop 1
	v_add_f32_dpp v138, v138, v138 quad_perm:[2,3,0,1] row_mask:0xf bank_mask:0xf
	s_nop 1
	v_add_f32_dpp v138, v138, v138 row_half_mirror row_mask:0xf bank_mask:0xf
	s_nop 1
	v_add_f32_dpp v138, v138, v138 row_mirror row_mask:0xf bank_mask:0xf
	v_mov_b32_e32 v139, v138
	s_nop 1
	v_permlane16_swap_b32_e32 v138, v139
	v_add_f32_e32 v138, v138, v139
	v_mov_b32_e32 v139, v138
	s_nop 1
	v_permlane32_swap_b32_e32 v138, v139
	v_add_f32_e32 v138, v138, v139
	v_mul_f32_e32 v138, 0x3a800000, v138
	v_add_f32_e32 v138, 0x358637bd, v138
	v_rsq_f32_e32 v140, v138
	s_nop 0
	v_mul_f32_e32 v120, v166, v140
	v_mul_f32_e32 v121, v167, v140
	v_mul_f32_e32 v122, v168, v140
	v_mul_f32_e32 v123, v169, v140
	v_mul_f32_e32 v124, v170, v140
	v_mul_f32_e32 v125, v171, v140
	v_mul_f32_e32 v126, v172, v140
	v_mul_f32_e32 v127, v173, v140
	v_mul_f32_e32 v128, v174, v140
	v_mul_f32_e32 v129, v175, v140
	v_mul_f32_e32 v130, v176, v140
	v_mul_f32_e32 v131, v177, v140
	v_mul_f32_e32 v132, v178, v140
	v_mul_f32_e32 v133, v179, v140
	v_mul_f32_e32 v134, v180, v140
	v_mul_f32_e32 v135, v181, v140
	v_fma_f32 v120, v120, v88, v104
	v_fma_f32 v121, v121, v89, v105
	v_fma_f32 v122, v122, v90, v106
	v_fma_f32 v123, v123, v91, v107
	v_fma_f32 v124, v124, v92, v108
	v_fma_f32 v125, v125, v93, v109
	v_fma_f32 v126, v126, v94, v110
	v_fma_f32 v127, v127, v95, v111
	v_fma_f32 v128, v128, v96, v112
	v_fma_f32 v129, v129, v97, v113
	v_fma_f32 v130, v130, v98, v114
	v_fma_f32 v131, v131, v99, v115
	v_fma_f32 v132, v132, v100, v116
	v_fma_f32 v133, v133, v101, v117
	v_fma_f32 v134, v134, v102, v118
	v_fma_f32 v135, v135, v103, v119
	v_cvt_pk_bf16_f32 v156, v120, v121
	v_cvt_pk_bf16_f32 v157, v122, v123
	v_cvt_pk_bf16_f32 v158, v124, v125
	v_cvt_pk_bf16_f32 v159, v126, v127
	v_cvt_pk_bf16_f32 v160, v128, v129
	v_cvt_pk_bf16_f32 v161, v130, v131
	v_cvt_pk_bf16_f32 v162, v132, v133
	v_cvt_pk_bf16_f32 v163, v134, v135
	s_lshl_b32 vcc_lo, s19, 11
	s_add_u32 vcc_lo, vcc_lo, 0xc00000
	s_add_u32 s100, s14, vcc_lo
	s_addc_u32 s101, s15, 0
	global_store_dwordx2 v137, v[156:157], s[100:101] offset:0
	global_store_dwordx2 v137, v[158:159], s[100:101] offset:512
	global_store_dwordx2 v137, v[160:161], s[100:101] offset:1024
	global_store_dwordx2 v137, v[162:163], s[100:101] offset:1536
	s_add_u32 s100, s20, 0x26000
	s_addc_u32 s101, s21, 0
	global_load_dwordx4 v[72:75], v136, s[100:101] offset:0
	global_load_dwordx4 v[76:79], v136, s[100:101] offset:1024
	global_load_dwordx4 v[80:83], v136, s[100:101] offset:2048
	global_load_dwordx4 v[84:87], v136, s[100:101] offset:3072
	s_load_dwordx2 s[98:99], s[4:5], 0x38
	s_waitcnt lgkmcnt(0)
	s_add_u32 s98, s98, 0x1000
	s_addc_u32 s99, s99, 0
	global_load_dwordx4 v[120:123], v136, s[98:99] offset:0
	global_load_dwordx4 v[124:127], v136, s[98:99] offset:1024
	global_load_dwordx4 v[128:131], v136, s[98:99] offset:2048
	global_load_dwordx4 v[132:135], v136, s[98:99] offset:3072
	s_add_u32 s100, s20, 0x27000
	s_addc_u32 s101, s21, 0
	global_load_dwordx4 v[104:107], v136, s[100:101] offset:0
	global_load_dwordx4 v[108:111], v136, s[100:101] offset:1024
	global_load_dwordx4 v[112:115], v136, s[100:101] offset:2048
	global_load_dwordx4 v[116:119], v136, s[100:101] offset:3072
	s_add_u32 s100, s100, 0x1000
	s_addc_u32 s101, s101, 0
	global_load_dwordx4 v[166:169], v136, s[100:101] offset:0
	global_load_dwordx4 v[170:173], v136, s[100:101] offset:1024
	global_load_dwordx4 v[174:177], v136, s[100:101] offset:2048
	global_load_dwordx4 v[178:181], v136, s[100:101] offset:3072
	s_load_dwordx2 s[98:99], s[4:5], 0x40
	s_waitcnt lgkmcnt(0)
	s_add_u32 s98, s98, 0x1000
	s_addc_u32 s99, s99, 0
	global_load_dwordx4 v[88:91], v136, s[98:99] offset:0
	global_load_dwordx4 v[92:95], v136, s[98:99] offset:1024
	global_load_dwordx4 v[96:99], v136, s[98:99] offset:2048
	global_load_dwordx4 v[100:103], v136, s[98:99] offset:3072
	s_waitcnt vmcnt(0)
; __device__ __forceinline__ void row_phase(const Params& P, int glayer, int layer, int xsrc, bool hasY, int gate_idx, const float* gpost,
;                           int xdst, bool doH, const float* gpre, int sh_idx, int nrows) {
;     ...
;         if (hasY) {
;           float4 yv[4];
;           float ss = 0.f;
; #pragma unroll
;           for (int i = 0; i < 4; ++i) {
;             const uint2 raw = yy[u][i];
;             yv[i].x = bf2f((u16)(raw.x & 0xffff)); yv[i].y = bf2f((u16)(raw.x >> 16));
;             yv[i].z = bf2f((u16)(raw.y & 0xffff)); yv[i].w = bf2f((u16)(raw.y >> 16));
;             ss += yv[i].x * yv[i].x + yv[i].y * yv[i].y + yv[i].z * yv[i].z + yv[i].w * yv[i].w;
;           }
;           ss = wave_sum(ss);
;           const float rstd = __builtin_amdgcn_rsqf(ss * (1.f / 1024.f) + EPSF);
; #pragma unroll
;           for (int i = 0; i < 4; ++i) {
;             const int col = (i * 64 + lane) * 4;
;             const float4 gt = *reinterpret_cast<const float4*>(modg + gate_idx * 1024 + col);
;             const float4 gp = *reinterpret_cast<const float4*>(gpost + col);
;             xv[i].x += gt.x * (yv[i].x * rstd * gp.x); xv[i].y += gt.y * (yv[i].y * rstd * gp.y);
;             xv[i].z += gt.z * (yv[i].z * rstd * gp.z); xv[i].w += gt.w * (yv[i].w * rstd * gp.w);
;           }
;         }
;         if (xdst == 3 || (xdst == 1 && row >= N_X)) {
;           float* xout = (xdst == 3) ? P.out + (long)row * 1024 : P.xc + (long)(row - N_X) * 1024;
; #pragma unroll
;           for (int i = 0; i < 4; ++i) *reinterpret_cast<float4*>(xout + (i * 64 + lane) * 4) = xv[i];
;         } else if (xdst != 0) {
;           u16* xo = ((xdst == 1) ? resA : P.zf) + (long)row * 1024;
; #pragma unroll
;           for (int i = 0; i < 4; ++i) {
;             const unsigned b0 = f2bf(xv[i].x), b1 = f2bf(xv[i].y), b2 = f2bf(xv[i].z), b3 = f2bf(xv[i].w);
;             *reinterpret_cast<uint2*>(xo + (i * 64 + lane) * 4) = make_uint2(b0 | (b1 << 16), b2 | (b3 << 16));
;           }
;         }
;         if (doH) {
;           float ss = 0.f;
; #pragma unroll
;           for (int i = 0; i < 4; ++i) ss += xv[i].x * xv[i].x + xv[i].y * xv[i].y + xv[i].z * xv[i].z + xv[i].w * xv[i].w;
;           ss = wave_sum(ss);
;           const float rstd = __builtin_amdgcn_rsqf(ss * (1.f / 1024.f) + EPSF);
;           u16* h = P.hy + (long)row * 1024;
; #pragma unroll
	v_mul_f32_e32 v72, v72, v120
	v_mul_f32_e32 v73, v73, v121
	v_mul_f32_e32 v74, v74, v122
	v_mul_f32_e32 v75, v75, v123
	v_mul_f32_e32 v76, v76, v124
	v_mul_f32_e32 v77, v77, v125
	v_mul_f32_e32 v78, v78, v126
	v_mul_f32_e32 v79, v79, v127
	v_mul_f32_e32 v80, v80, v128
	v_mul_f32_e32 v81, v81, v129
	v_mul_f32_e32 v82, v82, v130
	v_mul_f32_e32 v83, v83, v131
	v_mul_f32_e32 v84, v84, v132
	v_mul_f32_e32 v85, v85, v133
	v_mul_f32_e32 v86, v86, v134
	v_mul_f32_e32 v87, v87, v135
	v_fma_f32 v88, v88, v166, v88
	v_fma_f32 v89, v89, v167, v89
	v_fma_f32 v90, v90, v168, v90
	v_fma_f32 v91, v91, v169, v91
	v_fma_f32 v92, v92, v170, v92
	v_fma_f32 v93, v93, v171, v93
	v_fma_f32 v94, v94, v172, v94
	v_fma_f32 v95, v95, v173, v95
	v_fma_f32 v96, v96, v174, v96
	v_fma_f32 v97, v97, v175, v97
	v_fma_f32 v98, v98, v176, v98
	v_fma_f32 v99, v99, v177, v99
	v_fma_f32 v100, v100, v178, v100
	v_fma_f32 v101, v101, v179, v101
	v_fma_f32 v102, v102, v180, v102
	v_fma_f32 v103, v103, v181, v103
	s_lshl_b32 vcc_lo, s19, 11
	s_add_u32 vcc_lo, vcc_lo, 0x1c00000
	s_add_u32 s100, s12, vcc_lo
	s_addc_u32 s101, s13, 0
	global_load_dwordx2 v[174:175], v137, s[100:101] offset:0
	global_load_dwordx2 v[176:177], v137, s[100:101] offset:512
	global_load_dwordx2 v[178:179], v137, s[100:101] offset:1024
	global_load_dwordx2 v[180:181], v137, s[100:101] offset:1536
	s_lshl_b32 vcc_lo, s19, 11
	s_add_u32 vcc_lo, vcc_lo, 0x1c00000
	s_add_u32 s100, s14, vcc_lo
	s_addc_u32 s101, s15, 0
	global_load_dwordx2 v[182:183], v137, s[100:101] offset:0
	global_load_dwordx2 v[184:185], v137, s[100:101] offset:512
	global_load_dwordx2 v[186:187], v137, s[100:101] offset:1024
	global_load_dwordx2 v[188:189], v137, s[100:101] offset:1536
	v_lshlrev_b32_e32 v120, 16, v48
	v_and_b32_e32 v121, 0xffff0000, v48
	v_lshlrev_b32_e32 v122, 16, v49
	v_and_b32_e32 v123, 0xffff0000, v49
	v_lshlrev_b32_e32 v124, 16, v50
	v_and_b32_e32 v125, 0xffff0000, v50
	v_lshlrev_b32_e32 v126, 16, v51
	v_and_b32_e32 v127, 0xffff0000, v51
	v_lshlrev_b32_e32 v128, 16, v52
	v_and_b32_e32 v129, 0xffff0000, v52
	v_lshlrev_b32_e32 v130, 16, v53
	v_and_b32_e32 v131, 0xffff0000, v53
	v_lshlrev_b32_e32 v132, 16, v54
	v_and_b32_e32 v133, 0xffff0000, v54
	v_lshlrev_b32_e32 v134, 16, v55
	v_and_b32_e32 v135, 0xffff0000, v55
	v_mul_f32_e32 v138, v120, v120
	v_mul_f32_e32 v149, v121, v121
	v_mul_f32_e32 v150, v122, v122
	v_mul_f32_e32 v154, v123, v123
	v_fma_f32 v138, v124, v124, v138
	v_fma_f32 v149, v125, v125, v149
	v_fma_f32 v150, v126, v126, v150
	v_fma_f32 v154, v127, v127, v154
	v_fma_f32 v138, v128, v128, v138
	v_fma_f32 v149, v129, v129, v149
	v_fma_f32 v150, v130, v130, v150
	v_fma_f32 v154, v131, v131, v154
	v_fma_f32 v138, v132, v132, v138
	v_fma_f32 v149, v133, v133, v149
	v_fma_f32 v150, v134, v134, v150
	v_fma_f32 v154, v135, v135, v154
	v_add_f32_e32 v138, v138, v149
	v_add_f32_e32 v150, v150, v154
	v_add_f32_e32 v138, v138, v150
	s_nop 1
	v_add_f32_dpp v138, v138, v138 quad_perm:[1,0,3,2] row_mask:0xf bank_mask:0xf
	s_nop 1
	v_add_f32_dpp v138, v138, v138 quad_perm:[2,3,0,1] row_mask:0xf bank_mask:0xf
	s_nop 1
	v_add_f32_dpp v138, v138, v138 row_half_mirror row_mask:0xf bank_mask:0xf
	s_nop 1
	v_add_f32_dpp v138, v138, v138 row_mirror row_mask:0xf bank_mask:0xf
	v_mov_b32_e32 v139, v138
	s_nop 1
	v_permlane16_swap_b32_e32 v138, v139
	v_add_f32_e32 v138, v138, v139
	v_mov_b32_e32 v139, v138
	s_nop 1
	v_permlane32_swap_b32_e32 v138, v139
	v_add_f32_e32 v138, v138, v139
	v_mul_f32_e32 v138, 0x3a800000, v138
	v_add_f32_e32 v138, 0x358637bd, v138
	v_rsq_f32_e32 v140, v138
	v_lshlrev_b32_e32 v0, 16, v8
	v_and_b32_e32 v1, 0xffff0000, v8
	v_lshlrev_b32_e32 v2, 16, v9
	v_and_b32_e32 v3, 0xffff0000, v9
	v_lshlrev_b32_e32 v4, 16, v10
	v_and_b32_e32 v5, 0xffff0000, v10
	v_lshlrev_b32_e32 v6, 16, v11
	v_and_b32_e32 v7, 0xffff0000, v11
	v_lshlrev_b32_e32 v8, 16, v12
	v_and_b32_e32 v9, 0xffff0000, v12
	v_lshlrev_b32_e32 v10, 16, v13
	v_and_b32_e32 v11, 0xffff0000, v13
	v_lshlrev_b32_e32 v12, 16, v14
	v_and_b32_e32 v13, 0xffff0000, v14
	v_lshlrev_b32_e32 v14, 16, v15
	v_and_b32_e32 v15, 0xffff0000, v15
	s_nop 0
	v_mul_f32_e32 v120, v120, v140
	v_mul_f32_e32 v121, v121, v140
	v_mul_f32_e32 v122, v122, v140
	v_mul_f32_e32 v123, v123, v140
	v_mul_f32_e32 v124, v124, v140
	v_mul_f32_e32 v125, v125, v140
	v_mul_f32_e32 v126, v126, v140
	v_mul_f32_e32 v127, v127, v140
	v_mul_f32_e32 v128, v128, v140
	v_mul_f32_e32 v129, v129, v140
	v_mul_f32_e32 v130, v130, v140
	v_mul_f32_e32 v131, v131, v140
	v_mul_f32_e32 v132, v132, v140
	v_mul_f32_e32 v133, v133, v140
	v_mul_f32_e32 v134, v134, v140
	v_mul_f32_e32 v135, v135, v140
	v_fma_f32 v0, v120, v72, v0
	v_fma_f32 v1, v121, v73, v1
	v_fma_f32 v2, v122, v74, v2
	v_fma_f32 v3, v123, v75, v3
	v_fma_f32 v4, v124, v76, v4
	v_fma_f32 v5, v125, v77, v5
	v_fma_f32 v6, v126, v78, v6
	v_fma_f32 v7, v127, v79, v7
	v_fma_f32 v8, v128, v80, v8
	v_fma_f32 v9, v129, v81, v9
	v_fma_f32 v10, v130, v82, v10
	v_fma_f32 v11, v131, v83, v11
	v_fma_f32 v12, v132, v84, v12
	v_fma_f32 v13, v133, v85, v13
	v_fma_f32 v14, v134, v86, v14
	v_fma_f32 v15, v135, v87, v15
	v_cvt_pk_bf16_f32 v156, v0, v1
	v_cvt_pk_bf16_f32 v157, v2, v3
	v_cvt_pk_bf16_f32 v158, v4, v5
	v_cvt_pk_bf16_f32 v159, v6, v7
	v_cvt_pk_bf16_f32 v160, v8, v9
	v_cvt_pk_bf16_f32 v161, v10, v11
	v_cvt_pk_bf16_f32 v162, v12, v13
	v_cvt_pk_bf16_f32 v163, v14, v15
	s_lshl_b32 vcc_lo, s19, 11
	s_add_u32 vcc_lo, vcc_lo, 0x1000000
	s_add_u32 s100, s16, vcc_lo
	s_addc_u32 s101, s17, 0
	global_store_dwordx2 v137, v[156:157], s[100:101] offset:0
	global_store_dwordx2 v137, v[158:159], s[100:101] offset:512
	global_store_dwordx2 v137, v[160:161], s[100:101] offset:1024
; __device__ __forceinline__ void row_phase(const Params& P, int glayer, int layer, int xsrc, bool hasY, int gate_idx, const float* gpost,
;                           int xdst, bool doH, const float* gpre, int sh_idx, int nrows) {
;     ...
;         if (hasY) {
;           float4 yv[4];
;           float ss = 0.f;
; #pragma unroll
;           for (int i = 0; i < 4; ++i) {
;             const uint2 raw = yy[u][i];
;             yv[i].x = bf2f((u16)(raw.x & 0xffff)); yv[i].y = bf2f((u16)(raw.x >> 16));
;             yv[i].z = bf2f((u16)(raw.y & 0xffff)); yv[i].w = bf2f((u16)(raw.y >> 16));
;             ss += yv[i].x * yv[i].x + yv[i].y * yv[i].y + yv[i].z * yv[i].z + yv[i].w * yv[i].w;
;           }
;           ss = wave_sum(ss);
;           const float rstd = __builtin_amdgcn_rsqf(ss * (1.f / 1024.f) + EPSF);
; #pragma unroll
;           for (int i = 0; i < 4; ++i) {
;             const int col = (i * 64 + lane) * 4;
;             const float4 gt = *reinterpret_cast<const float4*>(modg + gate_idx * 1024 + col);
;             const float4 gp = *reinterpret_cast<const float4*>(gpost + col);
;             xv[i].x += gt.x * (yv[i].x * rstd * gp.x); xv[i].y += gt.y * (yv[i].y * rstd * gp.y);
;             xv[i].z += gt.z * (yv[i].z * rstd * gp.z); xv[i].w += gt.w * (yv[i].w * rstd * gp.w);
;           }
;         }
;         if (xdst == 3 || (xdst == 1 && row >= N_X)) {
;           float* xout = (xdst == 3) ? P.out + (long)row * 1024 : P.xc + (long)(row - N_X) * 1024;
; #pragma unroll
;           for (int i = 0; i < 4; ++i) *reinterpret_cast<float4*>(xout + (i * 64 + lane) * 4) = xv[i];
;         } else if (xdst != 0) {
;           u16* xo = ((xdst == 1) ? resA : P.zf) + (long)row * 1024;
; #pragma unroll
;           for (int i = 0; i < 4; ++i) {
;             const unsigned b0 = f2bf(xv[i].x), b1 = f2bf(xv[i].y), b2 = f2bf(xv[i].z), b3 = f2bf(xv[i].w);
;             *reinterpret_cast<uint2*>(xo + (i * 64 + lane) * 4) = make_uint2(b0 | (b1 << 16), b2 | (b3 << 16));
;           }
;         }
;         if (doH) {
;           float ss = 0.f;
; #pragma unroll
;           for (int i = 0; i < 4; ++i) ss += xv[i].x * xv[i].x + xv[i].y * xv[i].y + xv[i].z * xv[i].z + xv[i].w * xv[i].w;
;           ss = wave_sum(ss);
;           const float rstd = __builtin_amdgcn_rsqf(ss * (1.f / 1024.f) + EPSF);
;           u16* h = P.hy + (long)row * 1024;
; #pragma unroll
	global_store_dwordx2 v137, v[162:163], s[100:101] offset:1536
	v_mul_f32_e32 v138, v0, v0
	v_mul_f32_e32 v149, v1, v1
	v_mul_f32_e32 v150, v2, v2
	v_mul_f32_e32 v154, v3, v3
	v_fma_f32 v138, v4, v4, v138
	v_fma_f32 v149, v5, v5, v149
	v_fma_f32 v150, v6, v6, v150
	v_fma_f32 v154, v7, v7, v154
	v_fma_f32 v138, v8, v8, v138
	v_fma_f32 v149, v9, v9, v149
	v_fma_f32 v150, v10, v10, v150
	v_fma_f32 v154, v11, v11, v154
	v_fma_f32 v138, v12, v12, v138
	v_fma_f32 v149, v13, v13, v149
	v_fma_f32 v150, v14, v14, v150
	v_fma_f32 v154, v15, v15, v154
	v_add_f32_e32 v138, v138, v149
	v_add_f32_e32 v150, v150, v154
	v_add_f32_e32 v138, v138, v150
	s_nop 1
	v_add_f32_dpp v138, v138, v138 quad_perm:[1,0,3,2] row_mask:0xf bank_mask:0xf
	s_nop 1
	v_add_f32_dpp v138, v138, v138 quad_perm:[2,3,0,1] row_mask:0xf bank_mask:0xf
	s_nop 1
	v_add_f32_dpp v138, v138, v138 row_half_mirror row_mask:0xf bank_mask:0xf
	s_nop 1
	v_add_f32_dpp v138, v138, v138 row_mirror row_mask:0xf bank_mask:0xf
	v_mov_b32_e32 v139, v138
	s_nop 1
	v_permlane16_swap_b32_e32 v138, v139
	v_add_f32_e32 v138, v138, v139
	v_mov_b32_e32 v139, v138
	s_nop 1
	v_permlane32_swap_b32_e32 v138, v139
	v_add_f32_e32 v138, v138, v139
	v_mul_f32_e32 v138, 0x3a800000, v138
	v_add_f32_e32 v138, 0x358637bd, v138
	v_rsq_f32_e32 v140, v138
	s_nop 0
	v_mul_f32_e32 v120, v0, v140
	v_mul_f32_e32 v121, v1, v140
	v_mul_f32_e32 v122, v2, v140
	v_mul_f32_e32 v123, v3, v140
	v_mul_f32_e32 v124, v4, v140
	v_mul_f32_e32 v125, v5, v140
	v_mul_f32_e32 v126, v6, v140
	v_mul_f32_e32 v127, v7, v140
	v_mul_f32_e32 v128, v8, v140
	v_mul_f32_e32 v129, v9, v140
	v_mul_f32_e32 v130, v10, v140
	v_mul_f32_e32 v131, v11, v140
	v_mul_f32_e32 v132, v12, v140
	v_mul_f32_e32 v133, v13, v140
	v_mul_f32_e32 v134, v14, v140
	v_mul_f32_e32 v135, v15, v140
	v_fma_f32 v120, v120, v88, v104
	v_fma_f32 v121, v121, v89, v105
	v_fma_f32 v122, v122, v90, v106
	v_fma_f32 v123, v123, v91, v107
	v_fma_f32 v124, v124, v92, v108
	v_fma_f32 v125, v125, v93, v109
	v_fma_f32 v126, v126, v94, v110
	v_fma_f32 v127, v127, v95, v111
	v_fma_f32 v128, v128, v96, v112
	v_fma_f32 v129, v129, v97, v113
	v_fma_f32 v130, v130, v98, v114
	v_fma_f32 v131, v131, v99, v115
	v_fma_f32 v132, v132, v100, v116
	v_fma_f32 v133, v133, v101, v117
	v_fma_f32 v134, v134, v102, v118
	v_fma_f32 v135, v135, v103, v119
	v_cvt_pk_bf16_f32 v156, v120, v121
	v_cvt_pk_bf16_f32 v157, v122, v123
	v_cvt_pk_bf16_f32 v158, v124, v125
	v_cvt_pk_bf16_f32 v159, v126, v127
	v_cvt_pk_bf16_f32 v160, v128, v129
	v_cvt_pk_bf16_f32 v161, v130, v131
	v_cvt_pk_bf16_f32 v162, v132, v133
	v_cvt_pk_bf16_f32 v163, v134, v135
	s_lshl_b32 vcc_lo, s19, 11
	s_add_u32 vcc_lo, vcc_lo, 0x1000000
	s_add_u32 s100, s14, vcc_lo
	s_addc_u32 s101, s15, 0
	global_store_dwordx2 v137, v[156:157], s[100:101] offset:0
	global_store_dwordx2 v137, v[158:159], s[100:101] offset:512
	global_store_dwordx2 v137, v[160:161], s[100:101] offset:1024
	global_store_dwordx2 v137, v[162:163], s[100:101] offset:1536
	s_lshl_b32 vcc_lo, s19, 11
	s_add_u32 vcc_lo, vcc_lo, 0x2000000
	s_add_u32 s100, s12, vcc_lo
	s_addc_u32 s101, s13, 0
	global_load_dwordx2 v[8:9], v137, s[100:101] offset:0
	global_load_dwordx2 v[10:11], v137, s[100:101] offset:512
	global_load_dwordx2 v[12:13], v137, s[100:101] offset:1024
	global_load_dwordx2 v[14:15], v137, s[100:101] offset:1536
	s_lshl_b32 vcc_lo, s19, 11
	s_add_u32 vcc_lo, vcc_lo, 0x2000000
	s_add_u32 s100, s14, vcc_lo
	s_addc_u32 s101, s15, 0
	global_load_dwordx2 v[48:49], v137, s[100:101] offset:0
	global_load_dwordx2 v[50:51], v137, s[100:101] offset:512
	global_load_dwordx2 v[52:53], v137, s[100:101] offset:1024
	global_load_dwordx2 v[54:55], v137, s[100:101] offset:1536
	v_lshlrev_b32_e32 v120, 16, v56
	v_and_b32_e32 v121, 0xffff0000, v56
	v_lshlrev_b32_e32 v122, 16, v57
	v_and_b32_e32 v123, 0xffff0000, v57
	v_lshlrev_b32_e32 v124, 16, v58
	v_and_b32_e32 v125, 0xffff0000, v58
	v_lshlrev_b32_e32 v126, 16, v59
	v_and_b32_e32 v127, 0xffff0000, v59
	v_lshlrev_b32_e32 v128, 16, v60
	v_and_b32_e32 v129, 0xffff0000, v60
	v_lshlrev_b32_e32 v130, 16, v61
	v_and_b32_e32 v131, 0xffff0000, v61
	v_lshlrev_b32_e32 v132, 16, v62
	v_and_b32_e32 v133, 0xffff0000, v62
	v_lshlrev_b32_e32 v134, 16, v63
	v_and_b32_e32 v135, 0xffff0000, v63
	v_mul_f32_e32 v138, v120, v120
	v_mul_f32_e32 v149, v121, v121
	v_mul_f32_e32 v150, v122, v122
	v_mul_f32_e32 v154, v123, v123
	v_fma_f32 v138, v124, v124, v138
	v_fma_f32 v149, v125, v125, v149
	v_fma_f32 v150, v126, v126, v150
	v_fma_f32 v154, v127, v127, v154
	v_fma_f32 v138, v128, v128, v138
	v_fma_f32 v149, v129, v129, v149
	v_fma_f32 v150, v130, v130, v150
	v_fma_f32 v154, v131, v131, v154
	v_fma_f32 v138, v132, v132, v138
	v_fma_f32 v149, v133, v133, v149
	v_fma_f32 v150, v134, v134, v150
	v_fma_f32 v154, v135, v135, v154
	v_add_f32_e32 v138, v138, v149
	v_add_f32_e32 v150, v150, v154
	v_add_f32_e32 v138, v138, v150
	s_nop 1
	v_add_f32_dpp v138, v138, v138 quad_perm:[1,0,3,2] row_mask:0xf bank_mask:0xf
	s_nop 1
	v_add_f32_dpp v138, v138, v138 quad_perm:[2,3,0,1] row_mask:0xf bank_mask:0xf
	s_nop 1
	v_add_f32_dpp v138, v138, v138 row_half_mirror row_mask:0xf bank_mask:0xf
	s_nop 1
	v_add_f32_dpp v138, v138, v138 row_mirror row_mask:0xf bank_mask:0xf
	v_mov_b32_e32 v139, v138
	s_nop 1
	v_permlane16_swap_b32_e32 v138, v139
	v_add_f32_e32 v138, v138, v139
	v_mov_b32_e32 v139, v138
	s_nop 1
	v_permlane32_swap_b32_e32 v138, v139
	v_add_f32_e32 v138, v138, v139
	v_mul_f32_e32 v138, 0x3a800000, v138
	v_add_f32_e32 v138, 0x358637bd, v138
	v_rsq_f32_e32 v140, v138
	v_lshlrev_b32_e32 v16, 16, v24
	v_and_b32_e32 v17, 0xffff0000, v24
	v_lshlrev_b32_e32 v18, 16, v25
; __device__ __forceinline__ void row_phase(const Params& P, int glayer, int layer, int xsrc, bool hasY, int gate_idx, const float* gpost,
;                           int xdst, bool doH, const float* gpre, int sh_idx, int nrows) {
;     ...
;         if (hasY) {
;           float4 yv[4];
;           float ss = 0.f;
; #pragma unroll
;           for (int i = 0; i < 4; ++i) {
;             const uint2 raw = yy[u][i];
;             yv[i].x = bf2f((u16)(raw.x & 0xffff)); yv[i].y = bf2f((u16)(raw.x >> 16));
;             yv[i].z = bf2f((u16)(raw.y & 0xffff)); yv[i].w = bf2f((u16)(raw.y >> 16));
;             ss += yv[i].x * yv[i].x + yv[i].y * yv[i].y + yv[i].z * yv[i].z + yv[i].w * yv[i].w;
;           }
;           ss = wave_sum(ss);
;           const float rstd = __builtin_amdgcn_rsqf(ss * (1.f / 1024.f) + EPSF);
; #pragma unroll
;           for (int i = 0; i < 4; ++i) {
;             const int col = (i * 64 + lane) * 4;
;             const float4 gt = *reinterpret_cast<const float4*>(modg + gate_idx * 1024 + col);
;             const float4 gp = *reinterpret_cast<const float4*>(gpost + col);
;             xv[i].x += gt.x * (yv[i].x * rstd * gp.x); xv[i].y += gt.y * (yv[i].y * rstd * gp.y);
;             xv[i].z += gt.z * (yv[i].z * rstd * gp.z); xv[i].w += gt.w * (yv[i].w * rstd * gp.w);
;           }
;         }
;         if (xdst == 3 || (xdst == 1 && row >= N_X)) {
;           float* xout = (xdst == 3) ? P.out + (long)row * 1024 : P.xc + (long)(row - N_X) * 1024;
; #pragma unroll
;           for (int i = 0; i < 4; ++i) *reinterpret_cast<float4*>(xout + (i * 64 + lane) * 4) = xv[i];
;         } else if (xdst != 0) {
;           u16* xo = ((xdst == 1) ? resA : P.zf) + (long)row * 1024;
; #pragma unroll
;           for (int i = 0; i < 4; ++i) {
;             const unsigned b0 = f2bf(xv[i].x), b1 = f2bf(xv[i].y), b2 = f2bf(xv[i].z), b3 = f2bf(xv[i].w);
;             *reinterpret_cast<uint2*>(xo + (i * 64 + lane) * 4) = make_uint2(b0 | (b1 << 16), b2 | (b3 << 16));
;           }
;         }
;         if (doH) {
;           float ss = 0.f;
; #pragma unroll
;           for (int i = 0; i < 4; ++i) ss += xv[i].x * xv[i].x + xv[i].y * xv[i].y + xv[i].z * xv[i].z + xv[i].w * xv[i].w;
;           ss = wave_sum(ss);
;           const float rstd = __builtin_amdgcn_rsqf(ss * (1.f / 1024.f) + EPSF);
;           u16* h = P.hy + (long)row * 1024;
; #pragma unroll
	v_and_b32_e32 v19, 0xffff0000, v25
	v_lshlrev_b32_e32 v20, 16, v26
	v_and_b32_e32 v21, 0xffff0000, v26
	v_lshlrev_b32_e32 v22, 16, v27
	v_and_b32_e32 v23, 0xffff0000, v27
	v_lshlrev_b32_e32 v24, 16, v28
	v_and_b32_e32 v25, 0xffff0000, v28
	v_lshlrev_b32_e32 v26, 16, v29
	v_and_b32_e32 v27, 0xffff0000, v29
	v_lshlrev_b32_e32 v28, 16, v30
	v_and_b32_e32 v29, 0xffff0000, v30
	v_lshlrev_b32_e32 v30, 16, v31
	v_and_b32_e32 v31, 0xffff0000, v31
	s_nop 0
	v_mul_f32_e32 v120, v120, v140
	v_mul_f32_e32 v121, v121, v140
	v_mul_f32_e32 v122, v122, v140
	v_mul_f32_e32 v123, v123, v140
	v_mul_f32_e32 v124, v124, v140
	v_mul_f32_e32 v125, v125, v140
	v_mul_f32_e32 v126, v126, v140
	v_mul_f32_e32 v127, v127, v140
	v_mul_f32_e32 v128, v128, v140
	v_mul_f32_e32 v129, v129, v140
	v_mul_f32_e32 v130, v130, v140
	v_mul_f32_e32 v131, v131, v140
	v_mul_f32_e32 v132, v132, v140
	v_mul_f32_e32 v133, v133, v140
	v_mul_f32_e32 v134, v134, v140
	v_mul_f32_e32 v135, v135, v140
	v_fma_f32 v16, v120, v72, v16
	v_fma_f32 v17, v121, v73, v17
	v_fma_f32 v18, v122, v74, v18
	v_fma_f32 v19, v123, v75, v19
	v_fma_f32 v20, v124, v76, v20
	v_fma_f32 v21, v125, v77, v21
	v_fma_f32 v22, v126, v78, v22
	v_fma_f32 v23, v127, v79, v23
	v_fma_f32 v24, v128, v80, v24
	v_fma_f32 v25, v129, v81, v25
	v_fma_f32 v26, v130, v82, v26
	v_fma_f32 v27, v131, v83, v27
	v_fma_f32 v28, v132, v84, v28
	v_fma_f32 v29, v133, v85, v29
	v_fma_f32 v30, v134, v86, v30
	v_fma_f32 v31, v135, v87, v31
	v_cvt_pk_bf16_f32 v156, v16, v17
	v_cvt_pk_bf16_f32 v157, v18, v19
	v_cvt_pk_bf16_f32 v158, v20, v21
	v_cvt_pk_bf16_f32 v159, v22, v23
	v_cvt_pk_bf16_f32 v160, v24, v25
	v_cvt_pk_bf16_f32 v161, v26, v27
	v_cvt_pk_bf16_f32 v162, v28, v29
	v_cvt_pk_bf16_f32 v163, v30, v31
	s_lshl_b32 vcc_lo, s19, 11
	s_add_u32 vcc_lo, vcc_lo, 0x1400000
	s_add_u32 s100, s16, vcc_lo
	s_addc_u32 s101, s17, 0
	global_store_dwordx2 v137, v[156:157], s[100:101] offset:0
	global_store_dwordx2 v137, v[158:159], s[100:101] offset:512
	global_store_dwordx2 v137, v[160:161], s[100:101] offset:1024
	global_store_dwordx2 v137, v[162:163], s[100:101] offset:1536
	v_mul_f32_e32 v138, v16, v16
	v_mul_f32_e32 v149, v17, v17
	v_mul_f32_e32 v150, v18, v18
	v_mul_f32_e32 v154, v19, v19
	v_fma_f32 v138, v20, v20, v138
	v_fma_f32 v149, v21, v21, v149
	v_fma_f32 v150, v22, v22, v150
	v_fma_f32 v154, v23, v23, v154
	v_fma_f32 v138, v24, v24, v138
	v_fma_f32 v149, v25, v25, v149
	v_fma_f32 v150, v26, v26, v150
	v_fma_f32 v154, v27, v27, v154
	v_fma_f32 v138, v28, v28, v138
	v_fma_f32 v149, v29, v29, v149
	v_fma_f32 v150, v30, v30, v150
	v_fma_f32 v154, v31, v31, v154
	v_add_f32_e32 v138, v138, v149
	v_add_f32_e32 v150, v150, v154
	v_add_f32_e32 v138, v138, v150
	s_nop 1
	v_add_f32_dpp v138, v138, v138 quad_perm:[1,0,3,2] row_mask:0xf bank_mask:0xf
	s_nop 1
	v_add_f32_dpp v138, v138, v138 quad_perm:[2,3,0,1] row_mask:0xf bank_mask:0xf
	s_nop 1
	v_add_f32_dpp v138, v138, v138 row_half_mirror row_mask:0xf bank_mask:0xf
	s_nop 1
	v_add_f32_dpp v138, v138, v138 row_mirror row_mask:0xf bank_mask:0xf
	v_mov_b32_e32 v139, v138
	s_nop 1
	v_permlane16_swap_b32_e32 v138, v139
	v_add_f32_e32 v138, v138, v139
	v_mov_b32_e32 v139, v138
	s_nop 1
	v_permlane32_swap_b32_e32 v138, v139
	v_add_f32_e32 v138, v138, v139
	v_mul_f32_e32 v138, 0x3a800000, v138
	v_add_f32_e32 v138, 0x358637bd, v138
	v_rsq_f32_e32 v140, v138
	s_nop 0
	v_mul_f32_e32 v120, v16, v140
	v_mul_f32_e32 v121, v17, v140
	v_mul_f32_e32 v122, v18, v140
	v_mul_f32_e32 v123, v19, v140
	v_mul_f32_e32 v124, v20, v140
	v_mul_f32_e32 v125, v21, v140
	v_mul_f32_e32 v126, v22, v140
	v_mul_f32_e32 v127, v23, v140
	v_mul_f32_e32 v128, v24, v140
	v_mul_f32_e32 v129, v25, v140
	v_mul_f32_e32 v130, v26, v140
	v_mul_f32_e32 v131, v27, v140
	v_mul_f32_e32 v132, v28, v140
	v_mul_f32_e32 v133, v29, v140
	v_mul_f32_e32 v134, v30, v140
	v_mul_f32_e32 v135, v31, v140
	v_fma_f32 v120, v120, v88, v104
	v_fma_f32 v121, v121, v89, v105
	v_fma_f32 v122, v122, v90, v106
	v_fma_f32 v123, v123, v91, v107
	v_fma_f32 v124, v124, v92, v108
	v_fma_f32 v125, v125, v93, v109
	v_fma_f32 v126, v126, v94, v110
	v_fma_f32 v127, v127, v95, v111
	v_fma_f32 v128, v128, v96, v112
	v_fma_f32 v129, v129, v97, v113
	v_fma_f32 v130, v130, v98, v114
	v_fma_f32 v131, v131, v99, v115
	v_fma_f32 v132, v132, v100, v116
	v_fma_f32 v133, v133, v101, v117
	v_fma_f32 v134, v134, v102, v118
	v_fma_f32 v135, v135, v103, v119
	v_cvt_pk_bf16_f32 v156, v120, v121
	v_cvt_pk_bf16_f32 v157, v122, v123
	v_cvt_pk_bf16_f32 v158, v124, v125
	v_cvt_pk_bf16_f32 v159, v126, v127
	v_cvt_pk_bf16_f32 v160, v128, v129
	v_cvt_pk_bf16_f32 v161, v130, v131
	v_cvt_pk_bf16_f32 v162, v132, v133
	v_cvt_pk_bf16_f32 v163, v134, v135
	s_lshl_b32 vcc_lo, s19, 11
	s_add_u32 vcc_lo, vcc_lo, 0x1400000
	s_add_u32 s100, s14, vcc_lo
	s_addc_u32 s101, s15, 0
	global_store_dwordx2 v137, v[156:157], s[100:101] offset:0
	global_store_dwordx2 v137, v[158:159], s[100:101] offset:512
	global_store_dwordx2 v137, v[160:161], s[100:101] offset:1024
	global_store_dwordx2 v137, v[162:163], s[100:101] offset:1536
	s_lshl_b32 vcc_lo, s19, 11
	s_add_u32 vcc_lo, vcc_lo, 0x2400000
	s_add_u32 s100, s12, vcc_lo
	s_addc_u32 s101, s13, 0
	global_load_dwordx2 v[24:25], v137, s[100:101] offset:0
	global_load_dwordx2 v[26:27], v137, s[100:101] offset:512
	global_load_dwordx2 v[28:29], v137, s[100:101] offset:1024
	global_load_dwordx2 v[30:31], v137, s[100:101] offset:1536
	s_lshl_b32 vcc_lo, s19, 11
	s_add_u32 vcc_lo, vcc_lo, 0x2400000
	s_add_u32 s100, s14, vcc_lo
	s_addc_u32 s101, s15, 0
	global_load_dwordx2 v[56:57], v137, s[100:101] offset:0
	global_load_dwordx2 v[58:59], v137, s[100:101] offset:512
; __device__ __forceinline__ void row_phase(const Params& P, int glayer, int layer, int xsrc, bool hasY, int gate_idx, const float* gpost,
;                           int xdst, bool doH, const float* gpre, int sh_idx, int nrows) {
;     ...
;         if (hasY) {
;           float4 yv[4];
;           float ss = 0.f;
; #pragma unroll
;           for (int i = 0; i < 4; ++i) {
;             const uint2 raw = yy[u][i];
;             yv[i].x = bf2f((u16)(raw.x & 0xffff)); yv[i].y = bf2f((u16)(raw.x >> 16));
;             yv[i].z = bf2f((u16)(raw.y & 0xffff)); yv[i].w = bf2f((u16)(raw.y >> 16));
;             ss += yv[i].x * yv[i].x + yv[i].y * yv[i].y + yv[i].z * yv[i].z + yv[i].w * yv[i].w;
;           }
;           ss = wave_sum(ss);
;           const float rstd = __builtin_amdgcn_rsqf(ss * (1.f / 1024.f) + EPSF);
; #pragma unroll
;           for (int i = 0; i < 4; ++i) {
;             const int col = (i * 64 + lane) * 4;
;             const float4 gt = *reinterpret_cast<const float4*>(modg + gate_idx * 1024 + col);
;             const float4 gp = *reinterpret_cast<const float4*>(gpost + col);
;             xv[i].x += gt.x * (yv[i].x * rstd * gp.x); xv[i].y += gt.y * (yv[i].y * rstd * gp.y);
;             xv[i].z += gt.z * (yv[i].z * rstd * gp.z); xv[i].w += gt.w * (yv[i].w * rstd * gp.w);
;           }
;         }
;         if (xdst == 3 || (xdst == 1 && row >= N_X)) {
;           float* xout = (xdst == 3) ? P.out + (long)row * 1024 : P.xc + (long)(row - N_X) * 1024;
; #pragma unroll
;           for (int i = 0; i < 4; ++i) *reinterpret_cast<float4*>(xout + (i * 64 + lane) * 4) = xv[i];
;         } else if (xdst != 0) {
;           u16* xo = ((xdst == 1) ? resA : P.zf) + (long)row * 1024;
; #pragma unroll
;           for (int i = 0; i < 4; ++i) {
;             const unsigned b0 = f2bf(xv[i].x), b1 = f2bf(xv[i].y), b2 = f2bf(xv[i].z), b3 = f2bf(xv[i].w);
;             *reinterpret_cast<uint2*>(xo + (i * 64 + lane) * 4) = make_uint2(b0 | (b1 << 16), b2 | (b3 << 16));
;           }
;         }
;         if (doH) {
;           float ss = 0.f;
; #pragma unroll
;           for (int i = 0; i < 4; ++i) ss += xv[i].x * xv[i].x + xv[i].y * xv[i].y + xv[i].z * xv[i].z + xv[i].w * xv[i].w;
;           ss = wave_sum(ss);
;           const float rstd = __builtin_amdgcn_rsqf(ss * (1.f / 1024.f) + EPSF);
;           u16* h = P.hy + (long)row * 1024;
; #pragma unroll
	global_load_dwordx2 v[60:61], v137, s[100:101] offset:1024
	global_load_dwordx2 v[62:63], v137, s[100:101] offset:1536
	v_lshlrev_b32_e32 v120, 16, v64
	v_and_b32_e32 v121, 0xffff0000, v64
	v_lshlrev_b32_e32 v122, 16, v65
	v_and_b32_e32 v123, 0xffff0000, v65
	v_lshlrev_b32_e32 v124, 16, v66
	v_and_b32_e32 v125, 0xffff0000, v66
	v_lshlrev_b32_e32 v126, 16, v67
	v_and_b32_e32 v127, 0xffff0000, v67
	v_lshlrev_b32_e32 v128, 16, v68
	v_and_b32_e32 v129, 0xffff0000, v68
	v_lshlrev_b32_e32 v130, 16, v69
	v_and_b32_e32 v131, 0xffff0000, v69
	v_lshlrev_b32_e32 v132, 16, v70
	v_and_b32_e32 v133, 0xffff0000, v70
	v_lshlrev_b32_e32 v134, 16, v71
	v_and_b32_e32 v135, 0xffff0000, v71
	v_mul_f32_e32 v138, v120, v120
	v_mul_f32_e32 v149, v121, v121
	v_mul_f32_e32 v150, v122, v122
	v_mul_f32_e32 v154, v123, v123
	v_fma_f32 v138, v124, v124, v138
	v_fma_f32 v149, v125, v125, v149
	v_fma_f32 v150, v126, v126, v150
	v_fma_f32 v154, v127, v127, v154
	v_fma_f32 v138, v128, v128, v138
	v_fma_f32 v149, v129, v129, v149
	v_fma_f32 v150, v130, v130, v150
	v_fma_f32 v154, v131, v131, v154
	v_fma_f32 v138, v132, v132, v138
	v_fma_f32 v149, v133, v133, v149
	v_fma_f32 v150, v134, v134, v150
	v_fma_f32 v154, v135, v135, v154
	v_add_f32_e32 v138, v138, v149
	v_add_f32_e32 v150, v150, v154
	v_add_f32_e32 v138, v138, v150
	s_nop 1
	v_add_f32_dpp v138, v138, v138 quad_perm:[1,0,3,2] row_mask:0xf bank_mask:0xf
	s_nop 1
	v_add_f32_dpp v138, v138, v138 quad_perm:[2,3,0,1] row_mask:0xf bank_mask:0xf
	s_nop 1
	v_add_f32_dpp v138, v138, v138 row_half_mirror row_mask:0xf bank_mask:0xf
	s_nop 1
	v_add_f32_dpp v138, v138, v138 row_mirror row_mask:0xf bank_mask:0xf
	v_mov_b32_e32 v139, v138
	s_nop 1
	v_permlane16_swap_b32_e32 v138, v139
	v_add_f32_e32 v138, v138, v139
	v_mov_b32_e32 v139, v138
	s_nop 1
	v_permlane32_swap_b32_e32 v138, v139
	v_add_f32_e32 v138, v138, v139
	v_mul_f32_e32 v138, 0x3a800000, v138
	v_add_f32_e32 v138, 0x358637bd, v138
	v_rsq_f32_e32 v140, v138
	v_lshlrev_b32_e32 v32, 16, v40
	v_and_b32_e32 v33, 0xffff0000, v40
	v_lshlrev_b32_e32 v34, 16, v41
	v_and_b32_e32 v35, 0xffff0000, v41
	v_lshlrev_b32_e32 v36, 16, v42
	v_and_b32_e32 v37, 0xffff0000, v42
	v_lshlrev_b32_e32 v38, 16, v43
	v_and_b32_e32 v39, 0xffff0000, v43
	v_lshlrev_b32_e32 v40, 16, v44
	v_and_b32_e32 v41, 0xffff0000, v44
	v_lshlrev_b32_e32 v42, 16, v45
	v_and_b32_e32 v43, 0xffff0000, v45
	v_lshlrev_b32_e32 v44, 16, v46
	v_and_b32_e32 v45, 0xffff0000, v46
	v_lshlrev_b32_e32 v46, 16, v47
	v_and_b32_e32 v47, 0xffff0000, v47
	s_nop 0
	v_mul_f32_e32 v120, v120, v140
	v_mul_f32_e32 v121, v121, v140
	v_mul_f32_e32 v122, v122, v140
	v_mul_f32_e32 v123, v123, v140
	v_mul_f32_e32 v124, v124, v140
	v_mul_f32_e32 v125, v125, v140
	v_mul_f32_e32 v126, v126, v140
	v_mul_f32_e32 v127, v127, v140
	v_mul_f32_e32 v128, v128, v140
	v_mul_f32_e32 v129, v129, v140
	v_mul_f32_e32 v130, v130, v140
	v_mul_f32_e32 v131, v131, v140
	v_mul_f32_e32 v132, v132, v140
	v_mul_f32_e32 v133, v133, v140
	v_mul_f32_e32 v134, v134, v140
	v_mul_f32_e32 v135, v135, v140
	v_fma_f32 v32, v120, v72, v32
	v_fma_f32 v33, v121, v73, v33
	v_fma_f32 v34, v122, v74, v34
	v_fma_f32 v35, v123, v75, v35
	v_fma_f32 v36, v124, v76, v36
	v_fma_f32 v37, v125, v77, v37
	v_fma_f32 v38, v126, v78, v38
	v_fma_f32 v39, v127, v79, v39
	v_fma_f32 v40, v128, v80, v40
	v_fma_f32 v41, v129, v81, v41
	v_fma_f32 v42, v130, v82, v42
	v_fma_f32 v43, v131, v83, v43
	v_fma_f32 v44, v132, v84, v44
	v_fma_f32 v45, v133, v85, v45
	v_fma_f32 v46, v134, v86, v46
	v_fma_f32 v47, v135, v87, v47
	v_cvt_pk_bf16_f32 v156, v32, v33
	v_cvt_pk_bf16_f32 v157, v34, v35
	v_cvt_pk_bf16_f32 v158, v36, v37
	v_cvt_pk_bf16_f32 v159, v38, v39
	v_cvt_pk_bf16_f32 v160, v40, v41
	v_cvt_pk_bf16_f32 v161, v42, v43
	v_cvt_pk_bf16_f32 v162, v44, v45
	v_cvt_pk_bf16_f32 v163, v46, v47
	s_lshl_b32 vcc_lo, s19, 11
	s_add_u32 vcc_lo, vcc_lo, 0x1800000
	s_add_u32 s100, s16, vcc_lo
	s_addc_u32 s101, s17, 0
	global_store_dwordx2 v137, v[156:157], s[100:101] offset:0
	global_store_dwordx2 v137, v[158:159], s[100:101] offset:512
	global_store_dwordx2 v137, v[160:161], s[100:101] offset:1024
	global_store_dwordx2 v137, v[162:163], s[100:101] offset:1536
	v_mul_f32_e32 v138, v32, v32
	v_mul_f32_e32 v149, v33, v33
	v_mul_f32_e32 v150, v34, v34
	v_mul_f32_e32 v154, v35, v35
	v_fma_f32 v138, v36, v36, v138
	v_fma_f32 v149, v37, v37, v149
	v_fma_f32 v150, v38, v38, v150
	v_fma_f32 v154, v39, v39, v154
	v_fma_f32 v138, v40, v40, v138
	v_fma_f32 v149, v41, v41, v149
	v_fma_f32 v150, v42, v42, v150
	v_fma_f32 v154, v43, v43, v154
	v_fma_f32 v138, v44, v44, v138
	v_fma_f32 v149, v45, v45, v149
	v_fma_f32 v150, v46, v46, v150
	v_fma_f32 v154, v47, v47, v154
	v_add_f32_e32 v138, v138, v149
	v_add_f32_e32 v150, v150, v154
	v_add_f32_e32 v138, v138, v150
	s_nop 1
	v_add_f32_dpp v138, v138, v138 quad_perm:[1,0,3,2] row_mask:0xf bank_mask:0xf
	s_nop 1
	v_add_f32_dpp v138, v138, v138 quad_perm:[2,3,0,1] row_mask:0xf bank_mask:0xf
	s_nop 1
	v_add_f32_dpp v138, v138, v138 row_half_mirror row_mask:0xf bank_mask:0xf
	s_nop 1
	v_add_f32_dpp v138, v138, v138 row_mirror row_mask:0xf bank_mask:0xf
	v_mov_b32_e32 v139, v138
	s_nop 1
	v_permlane16_swap_b32_e32 v138, v139
	v_add_f32_e32 v138, v138, v139
	v_mov_b32_e32 v139, v138
	s_nop 1
	v_permlane32_swap_b32_e32 v138, v139
	v_add_f32_e32 v138, v138, v139
	v_mul_f32_e32 v138, 0x3a800000, v138
	v_add_f32_e32 v138, 0x358637bd, v138
	v_rsq_f32_e32 v140, v138
	s_nop 0
	v_mul_f32_e32 v120, v32, v140
	v_mul_f32_e32 v121, v33, v140
	v_mul_f32_e32 v122, v34, v140
	v_mul_f32_e32 v123, v35, v140
	v_mul_f32_e32 v124, v36, v140
	v_mul_f32_e32 v125, v37, v140
	v_mul_f32_e32 v126, v38, v140
; __device__ __forceinline__ void row_phase(const Params& P, int glayer, int layer, int xsrc, bool hasY, int gate_idx, const float* gpost,
;                           int xdst, bool doH, const float* gpre, int sh_idx, int nrows) {
;     ...
;         if (hasY) {
;           float4 yv[4];
;           float ss = 0.f;
; #pragma unroll
;           for (int i = 0; i < 4; ++i) {
;             const uint2 raw = yy[u][i];
;             yv[i].x = bf2f((u16)(raw.x & 0xffff)); yv[i].y = bf2f((u16)(raw.x >> 16));
;             yv[i].z = bf2f((u16)(raw.y & 0xffff)); yv[i].w = bf2f((u16)(raw.y >> 16));
;             ss += yv[i].x * yv[i].x + yv[i].y * yv[i].y + yv[i].z * yv[i].z + yv[i].w * yv[i].w;
;           }
;           ss = wave_sum(ss);
;           const float rstd = __builtin_amdgcn_rsqf(ss * (1.f / 1024.f) + EPSF);
; #pragma unroll
;           for (int i = 0; i < 4; ++i) {
;             const int col = (i * 64 + lane) * 4;
;             const float4 gt = *reinterpret_cast<const float4*>(modg + gate_idx * 1024 + col);
;             const float4 gp = *reinterpret_cast<const float4*>(gpost + col);
;             xv[i].x += gt.x * (yv[i].x * rstd * gp.x); xv[i].y += gt.y * (yv[i].y * rstd * gp.y);
;             xv[i].z += gt.z * (yv[i].z * rstd * gp.z); xv[i].w += gt.w * (yv[i].w * rstd * gp.w);
;           }
;         }
;         if (xdst == 3 || (xdst == 1 && row >= N_X)) {
;           float* xout = (xdst == 3) ? P.out + (long)row * 1024 : P.xc + (long)(row - N_X) * 1024;
; #pragma unroll
;           for (int i = 0; i < 4; ++i) *reinterpret_cast<float4*>(xout + (i * 64 + lane) * 4) = xv[i];
;         } else if (xdst != 0) {
;           u16* xo = ((xdst == 1) ? resA : P.zf) + (long)row * 1024;
; #pragma unroll
;           for (int i = 0; i < 4; ++i) {
;             const unsigned b0 = f2bf(xv[i].x), b1 = f2bf(xv[i].y), b2 = f2bf(xv[i].z), b3 = f2bf(xv[i].w);
;             *reinterpret_cast<uint2*>(xo + (i * 64 + lane) * 4) = make_uint2(b0 | (b1 << 16), b2 | (b3 << 16));
;           }
;         }
;         if (doH) {
;           float ss = 0.f;
; #pragma unroll
;           for (int i = 0; i < 4; ++i) ss += xv[i].x * xv[i].x + xv[i].y * xv[i].y + xv[i].z * xv[i].z + xv[i].w * xv[i].w;
;           ss = wave_sum(ss);
;           const float rstd = __builtin_amdgcn_rsqf(ss * (1.f / 1024.f) + EPSF);
;           u16* h = P.hy + (long)row * 1024;
; #pragma unroll
	v_mul_f32_e32 v127, v39, v140
	v_mul_f32_e32 v128, v40, v140
	v_mul_f32_e32 v129, v41, v140
	v_mul_f32_e32 v130, v42, v140
	v_mul_f32_e32 v131, v43, v140
	v_mul_f32_e32 v132, v44, v140
	v_mul_f32_e32 v133, v45, v140
	v_mul_f32_e32 v134, v46, v140
	v_mul_f32_e32 v135, v47, v140
	v_fma_f32 v120, v120, v88, v104
	v_fma_f32 v121, v121, v89, v105
	v_fma_f32 v122, v122, v90, v106
	v_fma_f32 v123, v123, v91, v107
	v_fma_f32 v124, v124, v92, v108
	v_fma_f32 v125, v125, v93, v109
	v_fma_f32 v126, v126, v94, v110
	v_fma_f32 v127, v127, v95, v111
	v_fma_f32 v128, v128, v96, v112
	v_fma_f32 v129, v129, v97, v113
	v_fma_f32 v130, v130, v98, v114
	v_fma_f32 v131, v131, v99, v115
	v_fma_f32 v132, v132, v100, v116
	v_fma_f32 v133, v133, v101, v117
	v_fma_f32 v134, v134, v102, v118
	v_fma_f32 v135, v135, v103, v119
	v_cvt_pk_bf16_f32 v156, v120, v121
	v_cvt_pk_bf16_f32 v157, v122, v123
	v_cvt_pk_bf16_f32 v158, v124, v125
	v_cvt_pk_bf16_f32 v159, v126, v127
	v_cvt_pk_bf16_f32 v160, v128, v129
	v_cvt_pk_bf16_f32 v161, v130, v131
	v_cvt_pk_bf16_f32 v162, v132, v133
	v_cvt_pk_bf16_f32 v163, v134, v135
	s_lshl_b32 vcc_lo, s19, 11
	s_add_u32 vcc_lo, vcc_lo, 0x1800000
	s_add_u32 s100, s14, vcc_lo
	s_addc_u32 s101, s15, 0
	global_store_dwordx2 v137, v[156:157], s[100:101] offset:0
	global_store_dwordx2 v137, v[158:159], s[100:101] offset:512
	global_store_dwordx2 v137, v[160:161], s[100:101] offset:1024
	global_store_dwordx2 v137, v[162:163], s[100:101] offset:1536
	s_lshl_b32 vcc_lo, s19, 11
	s_add_u32 vcc_lo, vcc_lo, 0x2800000
	s_add_u32 s100, s12, vcc_lo
	s_addc_u32 s101, s13, 0
	global_load_dwordx2 v[40:41], v137, s[100:101] offset:0
	global_load_dwordx2 v[42:43], v137, s[100:101] offset:512
	global_load_dwordx2 v[44:45], v137, s[100:101] offset:1024
	global_load_dwordx2 v[46:47], v137, s[100:101] offset:1536
	s_lshl_b32 vcc_lo, s19, 11
	s_add_u32 vcc_lo, vcc_lo, 0x2800000
	s_add_u32 s100, s14, vcc_lo
	s_addc_u32 s101, s15, 0
	global_load_dwordx2 v[64:65], v137, s[100:101] offset:0
	global_load_dwordx2 v[66:67], v137, s[100:101] offset:512
	global_load_dwordx2 v[68:69], v137, s[100:101] offset:1024
	global_load_dwordx2 v[70:71], v137, s[100:101] offset:1536
	s_waitcnt vmcnt(48)
	v_lshlrev_b32_e32 v120, 16, v182
	v_and_b32_e32 v121, 0xffff0000, v182
	v_lshlrev_b32_e32 v122, 16, v183
	v_and_b32_e32 v123, 0xffff0000, v183
	v_lshlrev_b32_e32 v124, 16, v184
	v_and_b32_e32 v125, 0xffff0000, v184
	v_lshlrev_b32_e32 v126, 16, v185
	v_and_b32_e32 v127, 0xffff0000, v185
	v_lshlrev_b32_e32 v128, 16, v186
	v_and_b32_e32 v129, 0xffff0000, v186
	v_lshlrev_b32_e32 v130, 16, v187
	v_and_b32_e32 v131, 0xffff0000, v187
	v_lshlrev_b32_e32 v132, 16, v188
	v_and_b32_e32 v133, 0xffff0000, v188
	v_lshlrev_b32_e32 v134, 16, v189
	v_and_b32_e32 v135, 0xffff0000, v189
	v_mul_f32_e32 v138, v120, v120
	v_mul_f32_e32 v149, v121, v121
	v_mul_f32_e32 v150, v122, v122
	v_mul_f32_e32 v154, v123, v123
	v_fma_f32 v138, v124, v124, v138
	v_fma_f32 v149, v125, v125, v149
	v_fma_f32 v150, v126, v126, v150
	v_fma_f32 v154, v127, v127, v154
	v_fma_f32 v138, v128, v128, v138
	v_fma_f32 v149, v129, v129, v149
	v_fma_f32 v150, v130, v130, v150
	v_fma_f32 v154, v131, v131, v154
	v_fma_f32 v138, v132, v132, v138
	v_fma_f32 v149, v133, v133, v149
	v_fma_f32 v150, v134, v134, v150
	v_fma_f32 v154, v135, v135, v154
	v_add_f32_e32 v138, v138, v149
	v_add_f32_e32 v150, v150, v154
	v_add_f32_e32 v138, v138, v150
	s_nop 1
	v_add_f32_dpp v138, v138, v138 quad_perm:[1,0,3,2] row_mask:0xf bank_mask:0xf
	s_nop 1
	v_add_f32_dpp v138, v138, v138 quad_perm:[2,3,0,1] row_mask:0xf bank_mask:0xf
	s_nop 1
	v_add_f32_dpp v138, v138, v138 row_half_mirror row_mask:0xf bank_mask:0xf
	s_nop 1
	v_add_f32_dpp v138, v138, v138 row_mirror row_mask:0xf bank_mask:0xf
	v_mov_b32_e32 v139, v138
	s_nop 1
	v_permlane16_swap_b32_e32 v138, v139
	v_add_f32_e32 v138, v138, v139
	v_mov_b32_e32 v139, v138
	s_nop 1
	v_permlane32_swap_b32_e32 v138, v139
	v_add_f32_e32 v138, v138, v139
	v_mul_f32_e32 v138, 0x3a800000, v138
	v_add_f32_e32 v138, 0x358637bd, v138
	v_rsq_f32_e32 v140, v138
	v_lshlrev_b32_e32 v166, 16, v174
	v_and_b32_e32 v167, 0xffff0000, v174
	v_lshlrev_b32_e32 v168, 16, v175
	v_and_b32_e32 v169, 0xffff0000, v175
	v_lshlrev_b32_e32 v170, 16, v176
	v_and_b32_e32 v171, 0xffff0000, v176
	v_lshlrev_b32_e32 v172, 16, v177
	v_and_b32_e32 v173, 0xffff0000, v177
	v_lshlrev_b32_e32 v174, 16, v178
	v_and_b32_e32 v175, 0xffff0000, v178
	v_lshlrev_b32_e32 v176, 16, v179
	v_and_b32_e32 v177, 0xffff0000, v179
	v_lshlrev_b32_e32 v178, 16, v180
	v_and_b32_e32 v179, 0xffff0000, v180
	v_lshlrev_b32_e32 v180, 16, v181
	v_and_b32_e32 v181, 0xffff0000, v181
	s_nop 0
	v_mul_f32_e32 v120, v120, v140
	v_mul_f32_e32 v121, v121, v140
	v_mul_f32_e32 v122, v122, v140
	v_mul_f32_e32 v123, v123, v140
	v_mul_f32_e32 v124, v124, v140
	v_mul_f32_e32 v125, v125, v140
	v_mul_f32_e32 v126, v126, v140
	v_mul_f32_e32 v127, v127, v140
	v_mul_f32_e32 v128, v128, v140
	v_mul_f32_e32 v129, v129, v140
	v_mul_f32_e32 v130, v130, v140
	v_mul_f32_e32 v131, v131, v140
	v_mul_f32_e32 v132, v132, v140
	v_mul_f32_e32 v133, v133, v140
	v_mul_f32_e32 v134, v134, v140
	v_mul_f32_e32 v135, v135, v140
	v_fma_f32 v166, v120, v72, v166
	v_fma_f32 v167, v121, v73, v167
	v_fma_f32 v168, v122, v74, v168
	v_fma_f32 v169, v123, v75, v169
	v_fma_f32 v170, v124, v76, v170
	v_fma_f32 v171, v125, v77, v171
	v_fma_f32 v172, v126, v78, v172
	v_fma_f32 v173, v127, v79, v173
	v_fma_f32 v174, v128, v80, v174
	v_fma_f32 v175, v129, v81, v175
	v_fma_f32 v176, v130, v82, v176
	v_fma_f32 v177, v131, v83, v177
	v_fma_f32 v178, v132, v84, v178
	v_fma_f32 v179, v133, v85, v179
	v_fma_f32 v180, v134, v86, v180
; __device__ __forceinline__ void row_phase(const Params& P, int glayer, int layer, int xsrc, bool hasY, int gate_idx, const float* gpost,
;                           int xdst, bool doH, const float* gpre, int sh_idx, int nrows) {
;     ...
;         if (xdst == 3 || (xdst == 1 && row >= N_X)) {
;           float* xout = (xdst == 3) ? P.out + (long)row * 1024 : P.xc + (long)(row - N_X) * 1024;
; #pragma unroll
;           for (int i = 0; i < 4; ++i) *reinterpret_cast<float4*>(xout + (i * 64 + lane) * 4) = xv[i];
;         } else if (xdst != 0) {
;           u16* xo = ((xdst == 1) ? resA : P.zf) + (long)row * 1024;
; #pragma unroll
;           for (int i = 0; i < 4; ++i) {
;             const unsigned b0 = f2bf(xv[i].x), b1 = f2bf(xv[i].y), b2 = f2bf(xv[i].z), b3 = f2bf(xv[i].w);
;             *reinterpret_cast<uint2*>(xo + (i * 64 + lane) * 4) = make_uint2(b0 | (b1 << 16), b2 | (b3 << 16));
;           }
;         }
;         if (doH) {
;           float ss = 0.f;
; #pragma unroll
;           for (int i = 0; i < 4; ++i) ss += xv[i].x * xv[i].x + xv[i].y * xv[i].y + xv[i].z * xv[i].z + xv[i].w * xv[i].w;
;           ss = wave_sum(ss);
;           const float rstd = __builtin_amdgcn_rsqf(ss * (1.f / 1024.f) + EPSF);
;           u16* h = P.hy + (long)row * 1024;
; #pragma unroll
;           for (int i = 0; i < 4; ++i) {
;             const int col = (i * 64 + lane) * 4;
;             const float4 g = *reinterpret_cast<const float4*>(gpre + col);
;             const float4 sh = *reinterpret_cast<const float4*>(modp + sh_idx * 1024 + col);
;             const float4 sc = *reinterpret_cast<const float4*>(modp + (sh_idx + 1) * 1024 + col);
;             const unsigned h0 = f2bf(xv[i].x * rstd * g.x * (1.f + sc.x) + sh.x);
;             const unsigned h1 = f2bf(xv[i].y * rstd * g.y * (1.f + sc.y) + sh.y);
;             const unsigned h2 = f2bf(xv[i].z * rstd * g.z * (1.f + sc.z) + sh.z);
;             const unsigned h3 = f2bf(xv[i].w * rstd * g.w * (1.f + sc.w) + sh.w);
;             *reinterpret_cast<uint2*>(h + col) = make_uint2(h0 | (h1 << 16), h2 | (h3 << 16));
;           }
	v_fma_f32 v181, v135, v87, v181
	v_cvt_pk_bf16_f32 v156, v166, v167
	v_cvt_pk_bf16_f32 v157, v168, v169
	v_cvt_pk_bf16_f32 v158, v170, v171
	v_cvt_pk_bf16_f32 v159, v172, v173
	v_cvt_pk_bf16_f32 v160, v174, v175
	v_cvt_pk_bf16_f32 v161, v176, v177
	v_cvt_pk_bf16_f32 v162, v178, v179
	v_cvt_pk_bf16_f32 v163, v180, v181
	s_lshl_b32 vcc_lo, s19, 11
	s_add_u32 vcc_lo, vcc_lo, 0x1c00000
	s_add_u32 s100, s16, vcc_lo
	s_addc_u32 s101, s17, 0
	global_store_dwordx2 v137, v[156:157], s[100:101] offset:0
	global_store_dwordx2 v137, v[158:159], s[100:101] offset:512
	global_store_dwordx2 v137, v[160:161], s[100:101] offset:1024
	global_store_dwordx2 v137, v[162:163], s[100:101] offset:1536
	v_mul_f32_e32 v138, v166, v166
	v_mul_f32_e32 v149, v167, v167
	v_mul_f32_e32 v150, v168, v168
	v_mul_f32_e32 v154, v169, v169
	v_fma_f32 v138, v170, v170, v138
	v_fma_f32 v149, v171, v171, v149
	v_fma_f32 v150, v172, v172, v150
	v_fma_f32 v154, v173, v173, v154
	v_fma_f32 v138, v174, v174, v138
	v_fma_f32 v149, v175, v175, v149
	v_fma_f32 v150, v176, v176, v150
	v_fma_f32 v154, v177, v177, v154
	v_fma_f32 v138, v178, v178, v138
	v_fma_f32 v149, v179, v179, v149
	v_fma_f32 v150, v180, v180, v150
	v_fma_f32 v154, v181, v181, v154
	v_add_f32_e32 v138, v138, v149
	v_add_f32_e32 v150, v150, v154
	v_add_f32_e32 v138, v138, v150
	s_nop 1
	v_add_f32_dpp v138, v138, v138 quad_perm:[1,0,3,2] row_mask:0xf bank_mask:0xf
	s_nop 1
	v_add_f32_dpp v138, v138, v138 quad_perm:[2,3,0,1] row_mask:0xf bank_mask:0xf
	s_nop 1
	v_add_f32_dpp v138, v138, v138 row_half_mirror row_mask:0xf bank_mask:0xf
	s_nop 1
	v_add_f32_dpp v138, v138, v138 row_mirror row_mask:0xf bank_mask:0xf
	v_mov_b32_e32 v139, v138
	s_nop 1
	v_permlane16_swap_b32_e32 v138, v139
	v_add_f32_e32 v138, v138, v139
	v_mov_b32_e32 v139, v138
	s_nop 1
	v_permlane32_swap_b32_e32 v138, v139
	v_add_f32_e32 v138, v138, v139
	v_mul_f32_e32 v138, 0x3a800000, v138
	v_add_f32_e32 v138, 0x358637bd, v138
	v_rsq_f32_e32 v140, v138
	s_nop 0
	v_mul_f32_e32 v120, v166, v140
	v_mul_f32_e32 v121, v167, v140
	v_mul_f32_e32 v122, v168, v140
	v_mul_f32_e32 v123, v169, v140
	v_mul_f32_e32 v124, v170, v140
	v_mul_f32_e32 v125, v171, v140
	v_mul_f32_e32 v126, v172, v140
	v_mul_f32_e32 v127, v173, v140
	v_mul_f32_e32 v128, v174, v140
	v_mul_f32_e32 v129, v175, v140
	v_mul_f32_e32 v130, v176, v140
	v_mul_f32_e32 v131, v177, v140
	v_mul_f32_e32 v132, v178, v140
	v_mul_f32_e32 v133, v179, v140
	v_mul_f32_e32 v134, v180, v140
	v_mul_f32_e32 v135, v181, v140
	v_fma_f32 v120, v120, v88, v104
	v_fma_f32 v121, v121, v89, v105
	v_fma_f32 v122, v122, v90, v106
	v_fma_f32 v123, v123, v91, v107
	v_fma_f32 v124, v124, v92, v108
	v_fma_f32 v125, v125, v93, v109
	v_fma_f32 v126, v126, v94, v110
	v_fma_f32 v127, v127, v95, v111
	v_fma_f32 v128, v128, v96, v112
	v_fma_f32 v129, v129, v97, v113
	v_fma_f32 v130, v130, v98, v114
	v_fma_f32 v131, v131, v99, v115
	v_fma_f32 v132, v132, v100, v116
	v_fma_f32 v133, v133, v101, v117
	v_fma_f32 v134, v134, v102, v118
	v_fma_f32 v135, v135, v103, v119
	v_cvt_pk_bf16_f32 v156, v120, v121
	v_cvt_pk_bf16_f32 v157, v122, v123
	v_cvt_pk_bf16_f32 v158, v124, v125
	v_cvt_pk_bf16_f32 v159, v126, v127
	v_cvt_pk_bf16_f32 v160, v128, v129
	v_cvt_pk_bf16_f32 v161, v130, v131
	v_cvt_pk_bf16_f32 v162, v132, v133
	v_cvt_pk_bf16_f32 v163, v134, v135
	s_lshl_b32 vcc_lo, s19, 11
	s_add_u32 vcc_lo, vcc_lo, 0x1c00000
	s_add_u32 s100, s14, vcc_lo
	s_addc_u32 s101, s15, 0
	global_store_dwordx2 v137, v[156:157], s[100:101] offset:0
	global_store_dwordx2 v137, v[158:159], s[100:101] offset:512
	global_store_dwordx2 v137, v[160:161], s[100:101] offset:1024
	global_store_dwordx2 v137, v[162:163], s[100:101] offset:1536
	s_add_u32 s100, s20, 0x2c000
	s_addc_u32 s101, s21, 0
	global_load_dwordx4 v[72:75], v136, s[100:101] offset:0
	global_load_dwordx4 v[76:79], v136, s[100:101] offset:1024
	global_load_dwordx4 v[80:83], v136, s[100:101] offset:2048
	global_load_dwordx4 v[84:87], v136, s[100:101] offset:3072
	s_load_dwordx2 s[98:99], s[4:5], 0x38
	s_waitcnt lgkmcnt(0)
	s_add_u32 s98, s98, 0x1000
	s_addc_u32 s99, s99, 0
	global_load_dwordx4 v[120:123], v136, s[98:99] offset:0
	global_load_dwordx4 v[124:127], v136, s[98:99] offset:1024
	global_load_dwordx4 v[128:131], v136, s[98:99] offset:2048
	global_load_dwordx4 v[132:135], v136, s[98:99] offset:3072
	s_add_u32 s100, s20, 0x2d000
	s_addc_u32 s101, s21, 0
	global_load_dwordx4 v[104:107], v136, s[100:101] offset:0
	global_load_dwordx4 v[108:111], v136, s[100:101] offset:1024
	global_load_dwordx4 v[112:115], v136, s[100:101] offset:2048
	global_load_dwordx4 v[116:119], v136, s[100:101] offset:3072
	s_add_u32 s100, s100, 0x1000
	s_addc_u32 s101, s101, 0
	global_load_dwordx4 v[166:169], v136, s[100:101] offset:0
	global_load_dwordx4 v[170:173], v136, s[100:101] offset:1024
	global_load_dwordx4 v[174:177], v136, s[100:101] offset:2048
	global_load_dwordx4 v[178:181], v136, s[100:101] offset:3072
	s_load_dwordx2 s[98:99], s[4:5], 0x40
	s_waitcnt lgkmcnt(0)
	s_add_u32 s98, s98, 0x1000
	s_addc_u32 s99, s99, 0
	global_load_dwordx4 v[88:91], v136, s[98:99] offset:0
	global_load_dwordx4 v[92:95], v136, s[98:99] offset:1024
	global_load_dwordx4 v[96:99], v136, s[98:99] offset:2048
	global_load_dwordx4 v[100:103], v136, s[98:99] offset:3072
	s_waitcnt vmcnt(0)
; __device__ __forceinline__ void row_phase(const Params& P, int glayer, int layer, int xsrc, bool hasY, int gate_idx, const float* gpost,
;                           int xdst, bool doH, const float* gpre, int sh_idx, int nrows) {
;     ...
;         if (hasY) {
;           float4 yv[4];
;           float ss = 0.f;
; #pragma unroll
;           for (int i = 0; i < 4; ++i) {
;             const uint2 raw = yy[u][i];
;             yv[i].x = bf2f((u16)(raw.x & 0xffff)); yv[i].y = bf2f((u16)(raw.x >> 16));
;             yv[i].z = bf2f((u16)(raw.y & 0xffff)); yv[i].w = bf2f((u16)(raw.y >> 16));
;             ss += yv[i].x * yv[i].x + yv[i].y * yv[i].y + yv[i].z * yv[i].z + yv[i].w * yv[i].w;
;           }
;           ss = wave_sum(ss);
;           const float rstd = __builtin_amdgcn_rsqf(ss * (1.f / 1024.f) + EPSF);
; #pragma unroll
;           for (int i = 0; i < 4; ++i) {
;             const int col = (i * 64 + lane) * 4;
;             const float4 gt = *reinterpret_cast<const float4*>(modg + gate_idx * 1024 + col);
;             const float4 gp = *reinterpret_cast<const float4*>(gpost + col);
;             xv[i].x += gt.x * (yv[i].x * rstd * gp.x); xv[i].y += gt.y * (yv[i].y * rstd * gp.y);
;             xv[i].z += gt.z * (yv[i].z * rstd * gp.z); xv[i].w += gt.w * (yv[i].w * rstd * gp.w);
;           }
;         }
;         if (xdst == 3 || (xdst == 1 && row >= N_X)) {
;           float* xout = (xdst == 3) ? P.out + (long)row * 1024 : P.xc + (long)(row - N_X) * 1024;
; #pragma unroll
;           for (int i = 0; i < 4; ++i) *reinterpret_cast<float4*>(xout + (i * 64 + lane) * 4) = xv[i];
;         } else if (xdst != 0) {
;           u16* xo = ((xdst == 1) ? resA : P.zf) + (long)row * 1024;
; #pragma unroll
;           for (int i = 0; i < 4; ++i) {
;             const unsigned b0 = f2bf(xv[i].x), b1 = f2bf(xv[i].y), b2 = f2bf(xv[i].z), b3 = f2bf(xv[i].w);
;             *reinterpret_cast<uint2*>(xo + (i * 64 + lane) * 4) = make_uint2(b0 | (b1 << 16), b2 | (b3 << 16));
;           }
;         }
;         if (doH) {
;           float ss = 0.f;
; #pragma unroll
;           for (int i = 0; i < 4; ++i) ss += xv[i].x * xv[i].x + xv[i].y * xv[i].y + xv[i].z * xv[i].z + xv[i].w * xv[i].w;
;           ss = wave_sum(ss);
;           const float rstd = __builtin_amdgcn_rsqf(ss * (1.f / 1024.f) + EPSF);
;           u16* h = P.hy + (long)row * 1024;
; #pragma unroll
	v_mul_f32_e32 v72, v72, v120
	v_mul_f32_e32 v73, v73, v121
	v_mul_f32_e32 v74, v74, v122
	v_mul_f32_e32 v75, v75, v123
	v_mul_f32_e32 v76, v76, v124
	v_mul_f32_e32 v77, v77, v125
	v_mul_f32_e32 v78, v78, v126
	v_mul_f32_e32 v79, v79, v127
	v_mul_f32_e32 v80, v80, v128
	v_mul_f32_e32 v81, v81, v129
	v_mul_f32_e32 v82, v82, v130
	v_mul_f32_e32 v83, v83, v131
	v_mul_f32_e32 v84, v84, v132
	v_mul_f32_e32 v85, v85, v133
	v_mul_f32_e32 v86, v86, v134
	v_mul_f32_e32 v87, v87, v135
	v_fma_f32 v88, v88, v166, v88
	v_fma_f32 v89, v89, v167, v89
	v_fma_f32 v90, v90, v168, v90
	v_fma_f32 v91, v91, v169, v91
	v_fma_f32 v92, v92, v170, v92
	v_fma_f32 v93, v93, v171, v93
	v_fma_f32 v94, v94, v172, v94
	v_fma_f32 v95, v95, v173, v95
	v_fma_f32 v96, v96, v174, v96
	v_fma_f32 v97, v97, v175, v97
	v_fma_f32 v98, v98, v176, v98
	v_fma_f32 v99, v99, v177, v99
	v_fma_f32 v100, v100, v178, v100
	v_fma_f32 v101, v101, v179, v101
	v_fma_f32 v102, v102, v180, v102
	v_fma_f32 v103, v103, v181, v103
	s_lshl_b32 vcc_lo, s19, 11
	s_add_u32 vcc_lo, vcc_lo, 0x2c00000
	s_add_u32 s100, s12, vcc_lo
	s_addc_u32 s101, s13, 0
	global_load_dwordx2 v[174:175], v137, s[100:101] offset:0
	global_load_dwordx2 v[176:177], v137, s[100:101] offset:512
	global_load_dwordx2 v[178:179], v137, s[100:101] offset:1024
	global_load_dwordx2 v[180:181], v137, s[100:101] offset:1536
	s_lshl_b32 vcc_lo, s19, 11
	s_add_u32 vcc_lo, vcc_lo, 0x2c00000
	s_add_u32 s100, s14, vcc_lo
	s_addc_u32 s101, s15, 0
	global_load_dwordx2 v[182:183], v137, s[100:101] offset:0
	global_load_dwordx2 v[184:185], v137, s[100:101] offset:512
	global_load_dwordx2 v[186:187], v137, s[100:101] offset:1024
	global_load_dwordx2 v[188:189], v137, s[100:101] offset:1536
	v_lshlrev_b32_e32 v120, 16, v48
	v_and_b32_e32 v121, 0xffff0000, v48
	v_lshlrev_b32_e32 v122, 16, v49
	v_and_b32_e32 v123, 0xffff0000, v49
	v_lshlrev_b32_e32 v124, 16, v50
	v_and_b32_e32 v125, 0xffff0000, v50
	v_lshlrev_b32_e32 v126, 16, v51
	v_and_b32_e32 v127, 0xffff0000, v51
	v_lshlrev_b32_e32 v128, 16, v52
	v_and_b32_e32 v129, 0xffff0000, v52
	v_lshlrev_b32_e32 v130, 16, v53
	v_and_b32_e32 v131, 0xffff0000, v53
	v_lshlrev_b32_e32 v132, 16, v54
	v_and_b32_e32 v133, 0xffff0000, v54
	v_lshlrev_b32_e32 v134, 16, v55
	v_and_b32_e32 v135, 0xffff0000, v55
	v_mul_f32_e32 v138, v120, v120
	v_mul_f32_e32 v149, v121, v121
	v_mul_f32_e32 v150, v122, v122
	v_mul_f32_e32 v154, v123, v123
	v_fma_f32 v138, v124, v124, v138
	v_fma_f32 v149, v125, v125, v149
	v_fma_f32 v150, v126, v126, v150
	v_fma_f32 v154, v127, v127, v154
	v_fma_f32 v138, v128, v128, v138
	v_fma_f32 v149, v129, v129, v149
	v_fma_f32 v150, v130, v130, v150
	v_fma_f32 v154, v131, v131, v154
	v_fma_f32 v138, v132, v132, v138
	v_fma_f32 v149, v133, v133, v149
	v_fma_f32 v150, v134, v134, v150
	v_fma_f32 v154, v135, v135, v154
	v_add_f32_e32 v138, v138, v149
	v_add_f32_e32 v150, v150, v154
	v_add_f32_e32 v138, v138, v150
	s_nop 1
	v_add_f32_dpp v138, v138, v138 quad_perm:[1,0,3,2] row_mask:0xf bank_mask:0xf
	s_nop 1
	v_add_f32_dpp v138, v138, v138 quad_perm:[2,3,0,1] row_mask:0xf bank_mask:0xf
	s_nop 1
	v_add_f32_dpp v138, v138, v138 row_half_mirror row_mask:0xf bank_mask:0xf
	s_nop 1
	v_add_f32_dpp v138, v138, v138 row_mirror row_mask:0xf bank_mask:0xf
	v_mov_b32_e32 v139, v138
	s_nop 1
	v_permlane16_swap_b32_e32 v138, v139
	v_add_f32_e32 v138, v138, v139
	v_mov_b32_e32 v139, v138
	s_nop 1
	v_permlane32_swap_b32_e32 v138, v139
	v_add_f32_e32 v138, v138, v139
	v_mul_f32_e32 v138, 0x3a800000, v138
	v_add_f32_e32 v138, 0x358637bd, v138
	v_rsq_f32_e32 v140, v138
	v_lshlrev_b32_e32 v0, 16, v8
	v_and_b32_e32 v1, 0xffff0000, v8
	v_lshlrev_b32_e32 v2, 16, v9
	v_and_b32_e32 v3, 0xffff0000, v9
	v_lshlrev_b32_e32 v4, 16, v10
	v_and_b32_e32 v5, 0xffff0000, v10
	v_lshlrev_b32_e32 v6, 16, v11
	v_and_b32_e32 v7, 0xffff0000, v11
	v_lshlrev_b32_e32 v8, 16, v12
	v_and_b32_e32 v9, 0xffff0000, v12
	v_lshlrev_b32_e32 v10, 16, v13
	v_and_b32_e32 v11, 0xffff0000, v13
	v_lshlrev_b32_e32 v12, 16, v14
	v_and_b32_e32 v13, 0xffff0000, v14
	v_lshlrev_b32_e32 v14, 16, v15
	v_and_b32_e32 v15, 0xffff0000, v15
	s_nop 0
	v_mul_f32_e32 v120, v120, v140
	v_mul_f32_e32 v121, v121, v140
	v_mul_f32_e32 v122, v122, v140
	v_mul_f32_e32 v123, v123, v140
	v_mul_f32_e32 v124, v124, v140
	v_mul_f32_e32 v125, v125, v140
	v_mul_f32_e32 v126, v126, v140
	v_mul_f32_e32 v127, v127, v140
	v_mul_f32_e32 v128, v128, v140
	v_mul_f32_e32 v129, v129, v140
	v_mul_f32_e32 v130, v130, v140
	v_mul_f32_e32 v131, v131, v140
	v_mul_f32_e32 v132, v132, v140
	v_mul_f32_e32 v133, v133, v140
	v_mul_f32_e32 v134, v134, v140
	v_mul_f32_e32 v135, v135, v140
	v_fma_f32 v0, v120, v72, v0
	v_fma_f32 v1, v121, v73, v1
	v_fma_f32 v2, v122, v74, v2
	v_fma_f32 v3, v123, v75, v3
	v_fma_f32 v4, v124, v76, v4
	v_fma_f32 v5, v125, v77, v5
	v_fma_f32 v6, v126, v78, v6
	v_fma_f32 v7, v127, v79, v7
	v_fma_f32 v8, v128, v80, v8
	v_fma_f32 v9, v129, v81, v9
	v_fma_f32 v10, v130, v82, v10
	v_fma_f32 v11, v131, v83, v11
	v_fma_f32 v12, v132, v84, v12
	v_fma_f32 v13, v133, v85, v13
	v_fma_f32 v14, v134, v86, v14
	v_fma_f32 v15, v135, v87, v15
	v_cvt_pk_bf16_f32 v156, v0, v1
	v_cvt_pk_bf16_f32 v157, v2, v3
	v_cvt_pk_bf16_f32 v158, v4, v5
	v_cvt_pk_bf16_f32 v159, v6, v7
	v_cvt_pk_bf16_f32 v160, v8, v9
	v_cvt_pk_bf16_f32 v161, v10, v11
	v_cvt_pk_bf16_f32 v162, v12, v13
	v_cvt_pk_bf16_f32 v163, v14, v15
	s_lshl_b32 vcc_lo, s19, 11
	s_add_u32 vcc_lo, vcc_lo, 0x2000000
	s_add_u32 s100, s16, vcc_lo
	s_addc_u32 s101, s17, 0
	global_store_dwordx2 v137, v[156:157], s[100:101] offset:0
	global_store_dwordx2 v137, v[158:159], s[100:101] offset:512
	global_store_dwordx2 v137, v[160:161], s[100:101] offset:1024
; __device__ __forceinline__ void row_phase(const Params& P, int glayer, int layer, int xsrc, bool hasY, int gate_idx, const float* gpost,
;                           int xdst, bool doH, const float* gpre, int sh_idx, int nrows) {
;     ...
;         if (hasY) {
;           float4 yv[4];
;           float ss = 0.f;
; #pragma unroll
;           for (int i = 0; i < 4; ++i) {
;             const uint2 raw = yy[u][i];
;             yv[i].x = bf2f((u16)(raw.x & 0xffff)); yv[i].y = bf2f((u16)(raw.x >> 16));
;             yv[i].z = bf2f((u16)(raw.y & 0xffff)); yv[i].w = bf2f((u16)(raw.y >> 16));
;             ss += yv[i].x * yv[i].x + yv[i].y * yv[i].y + yv[i].z * yv[i].z + yv[i].w * yv[i].w;
;           }
;           ss = wave_sum(ss);
;           const float rstd = __builtin_amdgcn_rsqf(ss * (1.f / 1024.f) + EPSF);
; #pragma unroll
;           for (int i = 0; i < 4; ++i) {
;             const int col = (i * 64 + lane) * 4;
;             const float4 gt = *reinterpret_cast<const float4*>(modg + gate_idx * 1024 + col);
;             const float4 gp = *reinterpret_cast<const float4*>(gpost + col);
;             xv[i].x += gt.x * (yv[i].x * rstd * gp.x); xv[i].y += gt.y * (yv[i].y * rstd * gp.y);
;             xv[i].z += gt.z * (yv[i].z * rstd * gp.z); xv[i].w += gt.w * (yv[i].w * rstd * gp.w);
;           }
;         }
;         if (xdst == 3 || (xdst == 1 && row >= N_X)) {
;           float* xout = (xdst == 3) ? P.out + (long)row * 1024 : P.xc + (long)(row - N_X) * 1024;
; #pragma unroll
;           for (int i = 0; i < 4; ++i) *reinterpret_cast<float4*>(xout + (i * 64 + lane) * 4) = xv[i];
;         } else if (xdst != 0) {
;           u16* xo = ((xdst == 1) ? resA : P.zf) + (long)row * 1024;
; #pragma unroll
;           for (int i = 0; i < 4; ++i) {
;             const unsigned b0 = f2bf(xv[i].x), b1 = f2bf(xv[i].y), b2 = f2bf(xv[i].z), b3 = f2bf(xv[i].w);
;             *reinterpret_cast<uint2*>(xo + (i * 64 + lane) * 4) = make_uint2(b0 | (b1 << 16), b2 | (b3 << 16));
;           }
;         }
;         if (doH) {
;           float ss = 0.f;
; #pragma unroll
;           for (int i = 0; i < 4; ++i) ss += xv[i].x * xv[i].x + xv[i].y * xv[i].y + xv[i].z * xv[i].z + xv[i].w * xv[i].w;
;           ss = wave_sum(ss);
;           const float rstd = __builtin_amdgcn_rsqf(ss * (1.f / 1024.f) + EPSF);
;           u16* h = P.hy + (long)row * 1024;
; #pragma unroll
	global_store_dwordx2 v137, v[162:163], s[100:101] offset:1536
	v_mul_f32_e32 v138, v0, v0
	v_mul_f32_e32 v149, v1, v1
	v_mul_f32_e32 v150, v2, v2
	v_mul_f32_e32 v154, v3, v3
	v_fma_f32 v138, v4, v4, v138
	v_fma_f32 v149, v5, v5, v149
	v_fma_f32 v150, v6, v6, v150
	v_fma_f32 v154, v7, v7, v154
	v_fma_f32 v138, v8, v8, v138
	v_fma_f32 v149, v9, v9, v149
	v_fma_f32 v150, v10, v10, v150
	v_fma_f32 v154, v11, v11, v154
	v_fma_f32 v138, v12, v12, v138
	v_fma_f32 v149, v13, v13, v149
	v_fma_f32 v150, v14, v14, v150
	v_fma_f32 v154, v15, v15, v154
	v_add_f32_e32 v138, v138, v149
	v_add_f32_e32 v150, v150, v154
	v_add_f32_e32 v138, v138, v150
	s_nop 1
	v_add_f32_dpp v138, v138, v138 quad_perm:[1,0,3,2] row_mask:0xf bank_mask:0xf
	s_nop 1
	v_add_f32_dpp v138, v138, v138 quad_perm:[2,3,0,1] row_mask:0xf bank_mask:0xf
	s_nop 1
	v_add_f32_dpp v138, v138, v138 row_half_mirror row_mask:0xf bank_mask:0xf
	s_nop 1
	v_add_f32_dpp v138, v138, v138 row_mirror row_mask:0xf bank_mask:0xf
	v_mov_b32_e32 v139, v138
	s_nop 1
	v_permlane16_swap_b32_e32 v138, v139
	v_add_f32_e32 v138, v138, v139
	v_mov_b32_e32 v139, v138
	s_nop 1
	v_permlane32_swap_b32_e32 v138, v139
	v_add_f32_e32 v138, v138, v139
	v_mul_f32_e32 v138, 0x3a800000, v138
	v_add_f32_e32 v138, 0x358637bd, v138
	v_rsq_f32_e32 v140, v138
	s_nop 0
	v_mul_f32_e32 v120, v0, v140
	v_mul_f32_e32 v121, v1, v140
	v_mul_f32_e32 v122, v2, v140
	v_mul_f32_e32 v123, v3, v140
	v_mul_f32_e32 v124, v4, v140
	v_mul_f32_e32 v125, v5, v140
	v_mul_f32_e32 v126, v6, v140
	v_mul_f32_e32 v127, v7, v140
	v_mul_f32_e32 v128, v8, v140
	v_mul_f32_e32 v129, v9, v140
	v_mul_f32_e32 v130, v10, v140
	v_mul_f32_e32 v131, v11, v140
	v_mul_f32_e32 v132, v12, v140
	v_mul_f32_e32 v133, v13, v140
	v_mul_f32_e32 v134, v14, v140
	v_mul_f32_e32 v135, v15, v140
	v_fma_f32 v120, v120, v88, v104
	v_fma_f32 v121, v121, v89, v105
	v_fma_f32 v122, v122, v90, v106
	v_fma_f32 v123, v123, v91, v107
	v_fma_f32 v124, v124, v92, v108
	v_fma_f32 v125, v125, v93, v109
	v_fma_f32 v126, v126, v94, v110
	v_fma_f32 v127, v127, v95, v111
	v_fma_f32 v128, v128, v96, v112
	v_fma_f32 v129, v129, v97, v113
	v_fma_f32 v130, v130, v98, v114
	v_fma_f32 v131, v131, v99, v115
	v_fma_f32 v132, v132, v100, v116
	v_fma_f32 v133, v133, v101, v117
	v_fma_f32 v134, v134, v102, v118
	v_fma_f32 v135, v135, v103, v119
	v_cvt_pk_bf16_f32 v156, v120, v121
	v_cvt_pk_bf16_f32 v157, v122, v123
	v_cvt_pk_bf16_f32 v158, v124, v125
	v_cvt_pk_bf16_f32 v159, v126, v127
	v_cvt_pk_bf16_f32 v160, v128, v129
	v_cvt_pk_bf16_f32 v161, v130, v131
	v_cvt_pk_bf16_f32 v162, v132, v133
	v_cvt_pk_bf16_f32 v163, v134, v135
	s_lshl_b32 vcc_lo, s19, 11
	s_add_u32 vcc_lo, vcc_lo, 0x2000000
	s_add_u32 s100, s14, vcc_lo
	s_addc_u32 s101, s15, 0
	global_store_dwordx2 v137, v[156:157], s[100:101] offset:0
	global_store_dwordx2 v137, v[158:159], s[100:101] offset:512
	global_store_dwordx2 v137, v[160:161], s[100:101] offset:1024
	global_store_dwordx2 v137, v[162:163], s[100:101] offset:1536
	s_lshl_b32 vcc_lo, s19, 11
	s_add_u32 vcc_lo, vcc_lo, 0x3000000
	s_add_u32 s100, s12, vcc_lo
	s_addc_u32 s101, s13, 0
	global_load_dwordx2 v[8:9], v137, s[100:101] offset:0
	global_load_dwordx2 v[10:11], v137, s[100:101] offset:512
	global_load_dwordx2 v[12:13], v137, s[100:101] offset:1024
	global_load_dwordx2 v[14:15], v137, s[100:101] offset:1536
	s_lshl_b32 vcc_lo, s19, 11
	s_add_u32 vcc_lo, vcc_lo, 0x3000000
	s_add_u32 s100, s14, vcc_lo
	s_addc_u32 s101, s15, 0
	global_load_dwordx2 v[48:49], v137, s[100:101] offset:0
	global_load_dwordx2 v[50:51], v137, s[100:101] offset:512
	global_load_dwordx2 v[52:53], v137, s[100:101] offset:1024
	global_load_dwordx2 v[54:55], v137, s[100:101] offset:1536
	v_lshlrev_b32_e32 v120, 16, v56
	v_and_b32_e32 v121, 0xffff0000, v56
	v_lshlrev_b32_e32 v122, 16, v57
	v_and_b32_e32 v123, 0xffff0000, v57
	v_lshlrev_b32_e32 v124, 16, v58
	v_and_b32_e32 v125, 0xffff0000, v58
	v_lshlrev_b32_e32 v126, 16, v59
	v_and_b32_e32 v127, 0xffff0000, v59
	v_lshlrev_b32_e32 v128, 16, v60
	v_and_b32_e32 v129, 0xffff0000, v60
	v_lshlrev_b32_e32 v130, 16, v61
	v_and_b32_e32 v131, 0xffff0000, v61
	v_lshlrev_b32_e32 v132, 16, v62
	v_and_b32_e32 v133, 0xffff0000, v62
	v_lshlrev_b32_e32 v134, 16, v63
	v_and_b32_e32 v135, 0xffff0000, v63
	v_mul_f32_e32 v138, v120, v120
	v_mul_f32_e32 v149, v121, v121
	v_mul_f32_e32 v150, v122, v122
	v_mul_f32_e32 v154, v123, v123
	v_fma_f32 v138, v124, v124, v138
	v_fma_f32 v149, v125, v125, v149
	v_fma_f32 v150, v126, v126, v150
	v_fma_f32 v154, v127, v127, v154
	v_fma_f32 v138, v128, v128, v138
	v_fma_f32 v149, v129, v129, v149
	v_fma_f32 v150, v130, v130, v150
	v_fma_f32 v154, v131, v131, v154
	v_fma_f32 v138, v132, v132, v138
	v_fma_f32 v149, v133, v133, v149
	v_fma_f32 v150, v134, v134, v150
	v_fma_f32 v154, v135, v135, v154
	v_add_f32_e32 v138, v138, v149
	v_add_f32_e32 v150, v150, v154
	v_add_f32_e32 v138, v138, v150
	s_nop 1
	v_add_f32_dpp v138, v138, v138 quad_perm:[1,0,3,2] row_mask:0xf bank_mask:0xf
	s_nop 1
	v_add_f32_dpp v138, v138, v138 quad_perm:[2,3,0,1] row_mask:0xf bank_mask:0xf
	s_nop 1
	v_add_f32_dpp v138, v138, v138 row_half_mirror row_mask:0xf bank_mask:0xf
	s_nop 1
	v_add_f32_dpp v138, v138, v138 row_mirror row_mask:0xf bank_mask:0xf
	v_mov_b32_e32 v139, v138
	s_nop 1
	v_permlane16_swap_b32_e32 v138, v139
	v_add_f32_e32 v138, v138, v139
	v_mov_b32_e32 v139, v138
	s_nop 1
	v_permlane32_swap_b32_e32 v138, v139
	v_add_f32_e32 v138, v138, v139
	v_mul_f32_e32 v138, 0x3a800000, v138
	v_add_f32_e32 v138, 0x358637bd, v138
	v_rsq_f32_e32 v140, v138
	v_lshlrev_b32_e32 v16, 16, v24
	v_and_b32_e32 v17, 0xffff0000, v24
	v_lshlrev_b32_e32 v18, 16, v25
; __device__ __forceinline__ void row_phase(const Params& P, int glayer, int layer, int xsrc, bool hasY, int gate_idx, const float* gpost,
;                           int xdst, bool doH, const float* gpre, int sh_idx, int nrows) {
;     ...
;         if (hasY) {
;           float4 yv[4];
;           float ss = 0.f;
; #pragma unroll
;           for (int i = 0; i < 4; ++i) {
;             const uint2 raw = yy[u][i];
;             yv[i].x = bf2f((u16)(raw.x & 0xffff)); yv[i].y = bf2f((u16)(raw.x >> 16));
;             yv[i].z = bf2f((u16)(raw.y & 0xffff)); yv[i].w = bf2f((u16)(raw.y >> 16));
;             ss += yv[i].x * yv[i].x + yv[i].y * yv[i].y + yv[i].z * yv[i].z + yv[i].w * yv[i].w;
;           }
;           ss = wave_sum(ss);
;           const float rstd = __builtin_amdgcn_rsqf(ss * (1.f / 1024.f) + EPSF);
; #pragma unroll
;           for (int i = 0; i < 4; ++i) {
;             const int col = (i * 64 + lane) * 4;
;             const float4 gt = *reinterpret_cast<const float4*>(modg + gate_idx * 1024 + col);
;             const float4 gp = *reinterpret_cast<const float4*>(gpost + col);
;             xv[i].x += gt.x * (yv[i].x * rstd * gp.x); xv[i].y += gt.y * (yv[i].y * rstd * gp.y);
;             xv[i].z += gt.z * (yv[i].z * rstd * gp.z); xv[i].w += gt.w * (yv[i].w * rstd * gp.w);
;           }
;         }
;         if (xdst == 3 || (xdst == 1 && row >= N_X)) {
;           float* xout = (xdst == 3) ? P.out + (long)row * 1024 : P.xc + (long)(row - N_X) * 1024;
; #pragma unroll
;           for (int i = 0; i < 4; ++i) *reinterpret_cast<float4*>(xout + (i * 64 + lane) * 4) = xv[i];
;         } else if (xdst != 0) {
;           u16* xo = ((xdst == 1) ? resA : P.zf) + (long)row * 1024;
; #pragma unroll
;           for (int i = 0; i < 4; ++i) {
;             const unsigned b0 = f2bf(xv[i].x), b1 = f2bf(xv[i].y), b2 = f2bf(xv[i].z), b3 = f2bf(xv[i].w);
;             *reinterpret_cast<uint2*>(xo + (i * 64 + lane) * 4) = make_uint2(b0 | (b1 << 16), b2 | (b3 << 16));
;           }
;         }
;         if (doH) {
;           float ss = 0.f;
; #pragma unroll
;           for (int i = 0; i < 4; ++i) ss += xv[i].x * xv[i].x + xv[i].y * xv[i].y + xv[i].z * xv[i].z + xv[i].w * xv[i].w;
;           ss = wave_sum(ss);
;           const float rstd = __builtin_amdgcn_rsqf(ss * (1.f / 1024.f) + EPSF);
;           u16* h = P.hy + (long)row * 1024;
; #pragma unroll
	v_and_b32_e32 v19, 0xffff0000, v25
	v_lshlrev_b32_e32 v20, 16, v26
	v_and_b32_e32 v21, 0xffff0000, v26
	v_lshlrev_b32_e32 v22, 16, v27
	v_and_b32_e32 v23, 0xffff0000, v27
	v_lshlrev_b32_e32 v24, 16, v28
	v_and_b32_e32 v25, 0xffff0000, v28
	v_lshlrev_b32_e32 v26, 16, v29
	v_and_b32_e32 v27, 0xffff0000, v29
	v_lshlrev_b32_e32 v28, 16, v30
	v_and_b32_e32 v29, 0xffff0000, v30
	v_lshlrev_b32_e32 v30, 16, v31
	v_and_b32_e32 v31, 0xffff0000, v31
	s_nop 0
	v_mul_f32_e32 v120, v120, v140
	v_mul_f32_e32 v121, v121, v140
	v_mul_f32_e32 v122, v122, v140
	v_mul_f32_e32 v123, v123, v140
	v_mul_f32_e32 v124, v124, v140
	v_mul_f32_e32 v125, v125, v140
	v_mul_f32_e32 v126, v126, v140
	v_mul_f32_e32 v127, v127, v140
	v_mul_f32_e32 v128, v128, v140
	v_mul_f32_e32 v129, v129, v140
	v_mul_f32_e32 v130, v130, v140
	v_mul_f32_e32 v131, v131, v140
	v_mul_f32_e32 v132, v132, v140
	v_mul_f32_e32 v133, v133, v140
	v_mul_f32_e32 v134, v134, v140
	v_mul_f32_e32 v135, v135, v140
	v_fma_f32 v16, v120, v72, v16
	v_fma_f32 v17, v121, v73, v17
	v_fma_f32 v18, v122, v74, v18
	v_fma_f32 v19, v123, v75, v19
	v_fma_f32 v20, v124, v76, v20
	v_fma_f32 v21, v125, v77, v21
	v_fma_f32 v22, v126, v78, v22
	v_fma_f32 v23, v127, v79, v23
	v_fma_f32 v24, v128, v80, v24
	v_fma_f32 v25, v129, v81, v25
	v_fma_f32 v26, v130, v82, v26
	v_fma_f32 v27, v131, v83, v27
	v_fma_f32 v28, v132, v84, v28
	v_fma_f32 v29, v133, v85, v29
	v_fma_f32 v30, v134, v86, v30
	v_fma_f32 v31, v135, v87, v31
	v_cvt_pk_bf16_f32 v156, v16, v17
	v_cvt_pk_bf16_f32 v157, v18, v19
	v_cvt_pk_bf16_f32 v158, v20, v21
	v_cvt_pk_bf16_f32 v159, v22, v23
	v_cvt_pk_bf16_f32 v160, v24, v25
	v_cvt_pk_bf16_f32 v161, v26, v27
	v_cvt_pk_bf16_f32 v162, v28, v29
	v_cvt_pk_bf16_f32 v163, v30, v31
	s_lshl_b32 vcc_lo, s19, 11
	s_add_u32 vcc_lo, vcc_lo, 0x2400000
	s_add_u32 s100, s16, vcc_lo
	s_addc_u32 s101, s17, 0
	global_store_dwordx2 v137, v[156:157], s[100:101] offset:0
	global_store_dwordx2 v137, v[158:159], s[100:101] offset:512
	global_store_dwordx2 v137, v[160:161], s[100:101] offset:1024
	global_store_dwordx2 v137, v[162:163], s[100:101] offset:1536
	v_mul_f32_e32 v138, v16, v16
	v_mul_f32_e32 v149, v17, v17
	v_mul_f32_e32 v150, v18, v18
	v_mul_f32_e32 v154, v19, v19
	v_fma_f32 v138, v20, v20, v138
	v_fma_f32 v149, v21, v21, v149
	v_fma_f32 v150, v22, v22, v150
	v_fma_f32 v154, v23, v23, v154
	v_fma_f32 v138, v24, v24, v138
	v_fma_f32 v149, v25, v25, v149
	v_fma_f32 v150, v26, v26, v150
	v_fma_f32 v154, v27, v27, v154
	v_fma_f32 v138, v28, v28, v138
	v_fma_f32 v149, v29, v29, v149
	v_fma_f32 v150, v30, v30, v150
	v_fma_f32 v154, v31, v31, v154
	v_add_f32_e32 v138, v138, v149
	v_add_f32_e32 v150, v150, v154
	v_add_f32_e32 v138, v138, v150
	s_nop 1
	v_add_f32_dpp v138, v138, v138 quad_perm:[1,0,3,2] row_mask:0xf bank_mask:0xf
	s_nop 1
	v_add_f32_dpp v138, v138, v138 quad_perm:[2,3,0,1] row_mask:0xf bank_mask:0xf
	s_nop 1
	v_add_f32_dpp v138, v138, v138 row_half_mirror row_mask:0xf bank_mask:0xf
	s_nop 1
	v_add_f32_dpp v138, v138, v138 row_mirror row_mask:0xf bank_mask:0xf
	v_mov_b32_e32 v139, v138
	s_nop 1
	v_permlane16_swap_b32_e32 v138, v139
	v_add_f32_e32 v138, v138, v139
	v_mov_b32_e32 v139, v138
	s_nop 1
	v_permlane32_swap_b32_e32 v138, v139
	v_add_f32_e32 v138, v138, v139
	v_mul_f32_e32 v138, 0x3a800000, v138
	v_add_f32_e32 v138, 0x358637bd, v138
	v_rsq_f32_e32 v140, v138
	s_nop 0
	v_mul_f32_e32 v120, v16, v140
	v_mul_f32_e32 v121, v17, v140
	v_mul_f32_e32 v122, v18, v140
	v_mul_f32_e32 v123, v19, v140
	v_mul_f32_e32 v124, v20, v140
	v_mul_f32_e32 v125, v21, v140
	v_mul_f32_e32 v126, v22, v140
	v_mul_f32_e32 v127, v23, v140
	v_mul_f32_e32 v128, v24, v140
	v_mul_f32_e32 v129, v25, v140
	v_mul_f32_e32 v130, v26, v140
	v_mul_f32_e32 v131, v27, v140
	v_mul_f32_e32 v132, v28, v140
	v_mul_f32_e32 v133, v29, v140
	v_mul_f32_e32 v134, v30, v140
	v_mul_f32_e32 v135, v31, v140
	v_fma_f32 v120, v120, v88, v104
	v_fma_f32 v121, v121, v89, v105
	v_fma_f32 v122, v122, v90, v106
	v_fma_f32 v123, v123, v91, v107
	v_fma_f32 v124, v124, v92, v108
	v_fma_f32 v125, v125, v93, v109
	v_fma_f32 v126, v126, v94, v110
	v_fma_f32 v127, v127, v95, v111
	v_fma_f32 v128, v128, v96, v112
	v_fma_f32 v129, v129, v97, v113
	v_fma_f32 v130, v130, v98, v114
	v_fma_f32 v131, v131, v99, v115
	v_fma_f32 v132, v132, v100, v116
	v_fma_f32 v133, v133, v101, v117
	v_fma_f32 v134, v134, v102, v118
	v_fma_f32 v135, v135, v103, v119
	v_cvt_pk_bf16_f32 v156, v120, v121
	v_cvt_pk_bf16_f32 v157, v122, v123
	v_cvt_pk_bf16_f32 v158, v124, v125
	v_cvt_pk_bf16_f32 v159, v126, v127
	v_cvt_pk_bf16_f32 v160, v128, v129
	v_cvt_pk_bf16_f32 v161, v130, v131
	v_cvt_pk_bf16_f32 v162, v132, v133
	v_cvt_pk_bf16_f32 v163, v134, v135
	s_lshl_b32 vcc_lo, s19, 11
	s_add_u32 vcc_lo, vcc_lo, 0x2400000
	s_add_u32 s100, s14, vcc_lo
	s_addc_u32 s101, s15, 0
	global_store_dwordx2 v137, v[156:157], s[100:101] offset:0
	global_store_dwordx2 v137, v[158:159], s[100:101] offset:512
	global_store_dwordx2 v137, v[160:161], s[100:101] offset:1024
	global_store_dwordx2 v137, v[162:163], s[100:101] offset:1536
	s_lshl_b32 vcc_lo, s19, 11
	s_add_u32 vcc_lo, vcc_lo, 0x3400000
	s_add_u32 s100, s12, vcc_lo
	s_addc_u32 s101, s13, 0
	global_load_dwordx2 v[24:25], v137, s[100:101] offset:0
	global_load_dwordx2 v[26:27], v137, s[100:101] offset:512
	global_load_dwordx2 v[28:29], v137, s[100:101] offset:1024
	global_load_dwordx2 v[30:31], v137, s[100:101] offset:1536
	s_lshl_b32 vcc_lo, s19, 11
	s_add_u32 vcc_lo, vcc_lo, 0x3400000
	s_add_u32 s100, s14, vcc_lo
	s_addc_u32 s101, s15, 0
	global_load_dwordx2 v[56:57], v137, s[100:101] offset:0
	global_load_dwordx2 v[58:59], v137, s[100:101] offset:512
; __device__ __forceinline__ void row_phase(const Params& P, int glayer, int layer, int xsrc, bool hasY, int gate_idx, const float* gpost,
;                           int xdst, bool doH, const float* gpre, int sh_idx, int nrows) {
;     ...
;         if (hasY) {
;           float4 yv[4];
;           float ss = 0.f;
; #pragma unroll
;           for (int i = 0; i < 4; ++i) {
;             const uint2 raw = yy[u][i];
;             yv[i].x = bf2f((u16)(raw.x & 0xffff)); yv[i].y = bf2f((u16)(raw.x >> 16));
;             yv[i].z = bf2f((u16)(raw.y & 0xffff)); yv[i].w = bf2f((u16)(raw.y >> 16));
;             ss += yv[i].x * yv[i].x + yv[i].y * yv[i].y + yv[i].z * yv[i].z + yv[i].w * yv[i].w;
;           }
;           ss = wave_sum(ss);
;           const float rstd = __builtin_amdgcn_rsqf(ss * (1.f / 1024.f) + EPSF);
; #pragma unroll
;           for (int i = 0; i < 4; ++i) {
;             const int col = (i * 64 + lane) * 4;
;             const float4 gt = *reinterpret_cast<const float4*>(modg + gate_idx * 1024 + col);
;             const float4 gp = *reinterpret_cast<const float4*>(gpost + col);
;             xv[i].x += gt.x * (yv[i].x * rstd * gp.x); xv[i].y += gt.y * (yv[i].y * rstd * gp.y);
;             xv[i].z += gt.z * (yv[i].z * rstd * gp.z); xv[i].w += gt.w * (yv[i].w * rstd * gp.w);
;           }
;         }
;         if (xdst == 3 || (xdst == 1 && row >= N_X)) {
;           float* xout = (xdst == 3) ? P.out + (long)row * 1024 : P.xc + (long)(row - N_X) * 1024;
; #pragma unroll
;           for (int i = 0; i < 4; ++i) *reinterpret_cast<float4*>(xout + (i * 64 + lane) * 4) = xv[i];
;         } else if (xdst != 0) {
;           u16* xo = ((xdst == 1) ? resA : P.zf) + (long)row * 1024;
; #pragma unroll
;           for (int i = 0; i < 4; ++i) {
;             const unsigned b0 = f2bf(xv[i].x), b1 = f2bf(xv[i].y), b2 = f2bf(xv[i].z), b3 = f2bf(xv[i].w);
;             *reinterpret_cast<uint2*>(xo + (i * 64 + lane) * 4) = make_uint2(b0 | (b1 << 16), b2 | (b3 << 16));
;           }
;         }
;         if (doH) {
;           float ss = 0.f;
; #pragma unroll
;           for (int i = 0; i < 4; ++i) ss += xv[i].x * xv[i].x + xv[i].y * xv[i].y + xv[i].z * xv[i].z + xv[i].w * xv[i].w;
;           ss = wave_sum(ss);
;           const float rstd = __builtin_amdgcn_rsqf(ss * (1.f / 1024.f) + EPSF);
;           u16* h = P.hy + (long)row * 1024;
; #pragma unroll
	global_load_dwordx2 v[60:61], v137, s[100:101] offset:1024
	global_load_dwordx2 v[62:63], v137, s[100:101] offset:1536
	v_lshlrev_b32_e32 v120, 16, v64
	v_and_b32_e32 v121, 0xffff0000, v64
	v_lshlrev_b32_e32 v122, 16, v65
	v_and_b32_e32 v123, 0xffff0000, v65
	v_lshlrev_b32_e32 v124, 16, v66
	v_and_b32_e32 v125, 0xffff0000, v66
	v_lshlrev_b32_e32 v126, 16, v67
	v_and_b32_e32 v127, 0xffff0000, v67
	v_lshlrev_b32_e32 v128, 16, v68
	v_and_b32_e32 v129, 0xffff0000, v68
	v_lshlrev_b32_e32 v130, 16, v69
	v_and_b32_e32 v131, 0xffff0000, v69
	v_lshlrev_b32_e32 v132, 16, v70
	v_and_b32_e32 v133, 0xffff0000, v70
	v_lshlrev_b32_e32 v134, 16, v71
	v_and_b32_e32 v135, 0xffff0000, v71
	v_mul_f32_e32 v138, v120, v120
	v_mul_f32_e32 v149, v121, v121
	v_mul_f32_e32 v150, v122, v122
	v_mul_f32_e32 v154, v123, v123
	v_fma_f32 v138, v124, v124, v138
	v_fma_f32 v149, v125, v125, v149
	v_fma_f32 v150, v126, v126, v150
	v_fma_f32 v154, v127, v127, v154
	v_fma_f32 v138, v128, v128, v138
	v_fma_f32 v149, v129, v129, v149
	v_fma_f32 v150, v130, v130, v150
	v_fma_f32 v154, v131, v131, v154
	v_fma_f32 v138, v132, v132, v138
	v_fma_f32 v149, v133, v133, v149
	v_fma_f32 v150, v134, v134, v150
	v_fma_f32 v154, v135, v135, v154
	v_add_f32_e32 v138, v138, v149
	v_add_f32_e32 v150, v150, v154
	v_add_f32_e32 v138, v138, v150
	s_nop 1
	v_add_f32_dpp v138, v138, v138 quad_perm:[1,0,3,2] row_mask:0xf bank_mask:0xf
	s_nop 1
	v_add_f32_dpp v138, v138, v138 quad_perm:[2,3,0,1] row_mask:0xf bank_mask:0xf
	s_nop 1
	v_add_f32_dpp v138, v138, v138 row_half_mirror row_mask:0xf bank_mask:0xf
	s_nop 1
	v_add_f32_dpp v138, v138, v138 row_mirror row_mask:0xf bank_mask:0xf
	v_mov_b32_e32 v139, v138
	s_nop 1
	v_permlane16_swap_b32_e32 v138, v139
	v_add_f32_e32 v138, v138, v139
	v_mov_b32_e32 v139, v138
	s_nop 1
	v_permlane32_swap_b32_e32 v138, v139
	v_add_f32_e32 v138, v138, v139
	v_mul_f32_e32 v138, 0x3a800000, v138
	v_add_f32_e32 v138, 0x358637bd, v138
	v_rsq_f32_e32 v140, v138
	v_lshlrev_b32_e32 v32, 16, v40
	v_and_b32_e32 v33, 0xffff0000, v40
	v_lshlrev_b32_e32 v34, 16, v41
	v_and_b32_e32 v35, 0xffff0000, v41
	v_lshlrev_b32_e32 v36, 16, v42
	v_and_b32_e32 v37, 0xffff0000, v42
	v_lshlrev_b32_e32 v38, 16, v43
	v_and_b32_e32 v39, 0xffff0000, v43
	v_lshlrev_b32_e32 v40, 16, v44
	v_and_b32_e32 v41, 0xffff0000, v44
	v_lshlrev_b32_e32 v42, 16, v45
	v_and_b32_e32 v43, 0xffff0000, v45
	v_lshlrev_b32_e32 v44, 16, v46
	v_and_b32_e32 v45, 0xffff0000, v46
	v_lshlrev_b32_e32 v46, 16, v47
	v_and_b32_e32 v47, 0xffff0000, v47
	s_nop 0
	v_mul_f32_e32 v120, v120, v140
	v_mul_f32_e32 v121, v121, v140
	v_mul_f32_e32 v122, v122, v140
	v_mul_f32_e32 v123, v123, v140
	v_mul_f32_e32 v124, v124, v140
	v_mul_f32_e32 v125, v125, v140
	v_mul_f32_e32 v126, v126, v140
	v_mul_f32_e32 v127, v127, v140
	v_mul_f32_e32 v128, v128, v140
	v_mul_f32_e32 v129, v129, v140
	v_mul_f32_e32 v130, v130, v140
	v_mul_f32_e32 v131, v131, v140
	v_mul_f32_e32 v132, v132, v140
	v_mul_f32_e32 v133, v133, v140
	v_mul_f32_e32 v134, v134, v140
	v_mul_f32_e32 v135, v135, v140
	v_fma_f32 v32, v120, v72, v32
	v_fma_f32 v33, v121, v73, v33
	v_fma_f32 v34, v122, v74, v34
	v_fma_f32 v35, v123, v75, v35
	v_fma_f32 v36, v124, v76, v36
	v_fma_f32 v37, v125, v77, v37
	v_fma_f32 v38, v126, v78, v38
	v_fma_f32 v39, v127, v79, v39
	v_fma_f32 v40, v128, v80, v40
	v_fma_f32 v41, v129, v81, v41
	v_fma_f32 v42, v130, v82, v42
	v_fma_f32 v43, v131, v83, v43
	v_fma_f32 v44, v132, v84, v44
	v_fma_f32 v45, v133, v85, v45
	v_fma_f32 v46, v134, v86, v46
	v_fma_f32 v47, v135, v87, v47
	v_cvt_pk_bf16_f32 v156, v32, v33
	v_cvt_pk_bf16_f32 v157, v34, v35
	v_cvt_pk_bf16_f32 v158, v36, v37
	v_cvt_pk_bf16_f32 v159, v38, v39
	v_cvt_pk_bf16_f32 v160, v40, v41
	v_cvt_pk_bf16_f32 v161, v42, v43
	v_cvt_pk_bf16_f32 v162, v44, v45
	v_cvt_pk_bf16_f32 v163, v46, v47
	s_lshl_b32 vcc_lo, s19, 11
	s_add_u32 vcc_lo, vcc_lo, 0x2800000
	s_add_u32 s100, s16, vcc_lo
	s_addc_u32 s101, s17, 0
	global_store_dwordx2 v137, v[156:157], s[100:101] offset:0
	global_store_dwordx2 v137, v[158:159], s[100:101] offset:512
	global_store_dwordx2 v137, v[160:161], s[100:101] offset:1024
	global_store_dwordx2 v137, v[162:163], s[100:101] offset:1536
	v_mul_f32_e32 v138, v32, v32
	v_mul_f32_e32 v149, v33, v33
	v_mul_f32_e32 v150, v34, v34
	v_mul_f32_e32 v154, v35, v35
	v_fma_f32 v138, v36, v36, v138
	v_fma_f32 v149, v37, v37, v149
	v_fma_f32 v150, v38, v38, v150
	v_fma_f32 v154, v39, v39, v154
	v_fma_f32 v138, v40, v40, v138
	v_fma_f32 v149, v41, v41, v149
	v_fma_f32 v150, v42, v42, v150
	v_fma_f32 v154, v43, v43, v154
	v_fma_f32 v138, v44, v44, v138
	v_fma_f32 v149, v45, v45, v149
	v_fma_f32 v150, v46, v46, v150
	v_fma_f32 v154, v47, v47, v154
	v_add_f32_e32 v138, v138, v149
	v_add_f32_e32 v150, v150, v154
	v_add_f32_e32 v138, v138, v150
	s_nop 1
	v_add_f32_dpp v138, v138, v138 quad_perm:[1,0,3,2] row_mask:0xf bank_mask:0xf
	s_nop 1
	v_add_f32_dpp v138, v138, v138 quad_perm:[2,3,0,1] row_mask:0xf bank_mask:0xf
	s_nop 1
	v_add_f32_dpp v138, v138, v138 row_half_mirror row_mask:0xf bank_mask:0xf
	s_nop 1
	v_add_f32_dpp v138, v138, v138 row_mirror row_mask:0xf bank_mask:0xf
	v_mov_b32_e32 v139, v138
	s_nop 1
	v_permlane16_swap_b32_e32 v138, v139
	v_add_f32_e32 v138, v138, v139
	v_mov_b32_e32 v139, v138
	s_nop 1
	v_permlane32_swap_b32_e32 v138, v139
	v_add_f32_e32 v138, v138, v139
	v_mul_f32_e32 v138, 0x3a800000, v138
	v_add_f32_e32 v138, 0x358637bd, v138
	v_rsq_f32_e32 v140, v138
	s_nop 0
	v_mul_f32_e32 v120, v32, v140
	v_mul_f32_e32 v121, v33, v140
	v_mul_f32_e32 v122, v34, v140
	v_mul_f32_e32 v123, v35, v140
	v_mul_f32_e32 v124, v36, v140
	v_mul_f32_e32 v125, v37, v140
	v_mul_f32_e32 v126, v38, v140
; __device__ __forceinline__ void row_phase(const Params& P, int glayer, int layer, int xsrc, bool hasY, int gate_idx, const float* gpost,
;                           int xdst, bool doH, const float* gpre, int sh_idx, int nrows) {
;     ...
;             ss += yv[i].x * yv[i].x + yv[i].y * yv[i].y + yv[i].z * yv[i].z + yv[i].w * yv[i].w;
;           }
;           ss = wave_sum(ss);
;           const float rstd = __builtin_amdgcn_rsqf(ss * (1.f / 1024.f) + EPSF);
; #pragma unroll
;           for (int i = 0; i < 4; ++i) {
;             const int col = (i * 64 + lane) * 4;
;             const float4 gt = *reinterpret_cast<const float4*>(modg + gate_idx * 1024 + col);
;             const float4 gp = *reinterpret_cast<const float4*>(gpost + col);
;             xv[i].x += gt.x * (yv[i].x * rstd * gp.x); xv[i].y += gt.y * (yv[i].y * rstd * gp.y);
;             xv[i].z += gt.z * (yv[i].z * rstd * gp.z); xv[i].w += gt.w * (yv[i].w * rstd * gp.w);
;           }
;         }
;         if (xdst == 3 || (xdst == 1 && row >= N_X)) {
;           float* xout = (xdst == 3) ? P.out + (long)row * 1024 : P.xc + (long)(row - N_X) * 1024;
; #pragma unroll
;           for (int i = 0; i < 4; ++i) *reinterpret_cast<float4*>(xout + (i * 64 + lane) * 4) = xv[i];
;         } else if (xdst != 0) {
;           u16* xo = ((xdst == 1) ? resA : P.zf) + (long)row * 1024;
; #pragma unroll
;           for (int i = 0; i < 4; ++i) {
;             const unsigned b0 = f2bf(xv[i].x), b1 = f2bf(xv[i].y), b2 = f2bf(xv[i].z), b3 = f2bf(xv[i].w);
;             *reinterpret_cast<uint2*>(xo + (i * 64 + lane) * 4) = make_uint2(b0 | (b1 << 16), b2 | (b3 << 16));
;           }
;         }
;         if (doH) {
;           float ss = 0.f;
; #pragma unroll
;           for (int i = 0; i < 4; ++i) ss += xv[i].x * xv[i].x + xv[i].y * xv[i].y + xv[i].z * xv[i].z + xv[i].w * xv[i].w;
;           ss = wave_sum(ss);
;           const float rstd = __builtin_amdgcn_rsqf(ss * (1.f / 1024.f) + EPSF);
;           u16* h = P.hy + (long)row * 1024;
; #pragma unroll
;           for (int i = 0; i < 4; ++i) {
;             const int col = (i * 64 + lane) * 4;
;             const float4 g = *reinterpret_cast<const float4*>(gpre + col);
;             const float4 sh = *reinterpret_cast<const float4*>(modp + sh_idx * 1024 + col);
;             const float4 sc = *reinterpret_cast<const float4*>(modp + (sh_idx + 1) * 1024 + col);
	v_mul_f32_e32 v127, v39, v140
	v_mul_f32_e32 v128, v40, v140
	v_mul_f32_e32 v129, v41, v140
	v_mul_f32_e32 v130, v42, v140
	v_mul_f32_e32 v131, v43, v140
	v_mul_f32_e32 v132, v44, v140
	v_mul_f32_e32 v133, v45, v140
	v_mul_f32_e32 v134, v46, v140
	v_mul_f32_e32 v135, v47, v140
	v_fma_f32 v120, v120, v88, v104
	v_fma_f32 v121, v121, v89, v105
	v_fma_f32 v122, v122, v90, v106
	v_fma_f32 v123, v123, v91, v107
	v_fma_f32 v124, v124, v92, v108
	v_fma_f32 v125, v125, v93, v109
	v_fma_f32 v126, v126, v94, v110
	v_fma_f32 v127, v127, v95, v111
	v_fma_f32 v128, v128, v96, v112
	v_fma_f32 v129, v129, v97, v113
	v_fma_f32 v130, v130, v98, v114
	v_fma_f32 v131, v131, v99, v115
	v_fma_f32 v132, v132, v100, v116
	v_fma_f32 v133, v133, v101, v117
	v_fma_f32 v134, v134, v102, v118
	v_fma_f32 v135, v135, v103, v119
	v_cvt_pk_bf16_f32 v156, v120, v121
	v_cvt_pk_bf16_f32 v157, v122, v123
	v_cvt_pk_bf16_f32 v158, v124, v125
	v_cvt_pk_bf16_f32 v159, v126, v127
	v_cvt_pk_bf16_f32 v160, v128, v129
	v_cvt_pk_bf16_f32 v161, v130, v131
	v_cvt_pk_bf16_f32 v162, v132, v133
	v_cvt_pk_bf16_f32 v163, v134, v135
	s_lshl_b32 vcc_lo, s19, 11
	s_add_u32 vcc_lo, vcc_lo, 0x2800000
	s_add_u32 s100, s14, vcc_lo
	s_addc_u32 s101, s15, 0
	global_store_dwordx2 v137, v[156:157], s[100:101] offset:0
	global_store_dwordx2 v137, v[158:159], s[100:101] offset:512
	global_store_dwordx2 v137, v[160:161], s[100:101] offset:1024
	global_store_dwordx2 v137, v[162:163], s[100:101] offset:1536
	s_lshl_b32 vcc_lo, s19, 11
	s_add_u32 vcc_lo, vcc_lo, 0x3800000
	s_add_u32 s100, s12, vcc_lo
	s_addc_u32 s101, s13, 0
	global_load_dwordx2 v[40:41], v137, s[100:101] offset:0
	global_load_dwordx2 v[42:43], v137, s[100:101] offset:512
	global_load_dwordx2 v[44:45], v137, s[100:101] offset:1024
	global_load_dwordx2 v[46:47], v137, s[100:101] offset:1536
	s_lshl_b32 vcc_lo, s19, 11
	s_add_u32 vcc_lo, vcc_lo, 0x3800000
	s_add_u32 s100, s14, vcc_lo
	s_addc_u32 s101, s15, 0
	global_load_dwordx2 v[64:65], v137, s[100:101] offset:0
	global_load_dwordx2 v[66:67], v137, s[100:101] offset:512
	global_load_dwordx2 v[68:69], v137, s[100:101] offset:1024
	global_load_dwordx2 v[70:71], v137, s[100:101] offset:1536
	s_waitcnt vmcnt(48)
	v_lshlrev_b32_e32 v120, 16, v182
	v_and_b32_e32 v121, 0xffff0000, v182
	v_lshlrev_b32_e32 v122, 16, v183
	v_and_b32_e32 v123, 0xffff0000, v183
	v_lshlrev_b32_e32 v124, 16, v184
	v_and_b32_e32 v125, 0xffff0000, v184
	v_lshlrev_b32_e32 v126, 16, v185
	v_and_b32_e32 v127, 0xffff0000, v185
	v_lshlrev_b32_e32 v128, 16, v186
	v_and_b32_e32 v129, 0xffff0000, v186
	v_lshlrev_b32_e32 v130, 16, v187
	v_and_b32_e32 v131, 0xffff0000, v187
	v_lshlrev_b32_e32 v132, 16, v188
	v_and_b32_e32 v133, 0xffff0000, v188
	v_lshlrev_b32_e32 v134, 16, v189
	v_and_b32_e32 v135, 0xffff0000, v189
	v_mul_f32_e32 v138, v120, v120
	v_mul_f32_e32 v149, v121, v121
	v_mul_f32_e32 v150, v122, v122
	v_mul_f32_e32 v154, v123, v123
	v_fma_f32 v138, v124, v124, v138
	v_fma_f32 v149, v125, v125, v149
	v_fma_f32 v150, v126, v126, v150
	v_fma_f32 v154, v127, v127, v154
	v_fma_f32 v138, v128, v128, v138
	v_fma_f32 v149, v129, v129, v149
	v_fma_f32 v150, v130, v130, v150
	v_fma_f32 v154, v131, v131, v154
	v_fma_f32 v138, v132, v132, v138
	v_fma_f32 v149, v133, v133, v149
	v_fma_f32 v150, v134, v134, v150
	v_fma_f32 v154, v135, v135, v154
	v_add_f32_e32 v138, v138, v149
	v_add_f32_e32 v150, v150, v154
	v_add_f32_e32 v138, v138, v150
	s_nop 1
	v_add_f32_dpp v138, v138, v138 quad_perm:[1,0,3,2] row_mask:0xf bank_mask:0xf
	s_nop 1
	v_add_f32_dpp v138, v138, v138 quad_perm:[2,3,0,1] row_mask:0xf bank_mask:0xf
	s_nop 1
	v_add_f32_dpp v138, v138, v138 row_half_mirror row_mask:0xf bank_mask:0xf
	s_nop 1
	v_add_f32_dpp v138, v138, v138 row_mirror row_mask:0xf bank_mask:0xf
	v_mov_b32_e32 v139, v138
	s_nop 1
	v_permlane16_swap_b32_e32 v138, v139
	v_add_f32_e32 v138, v138, v139
	v_mov_b32_e32 v139, v138
	s_nop 1
	v_permlane32_swap_b32_e32 v138, v139
	v_add_f32_e32 v138, v138, v139
	v_mul_f32_e32 v138, 0x3a800000, v138
	v_add_f32_e32 v138, 0x358637bd, v138
	v_rsq_f32_e32 v140, v138
	v_lshlrev_b32_e32 v166, 16, v174
	v_and_b32_e32 v167, 0xffff0000, v174
	v_lshlrev_b32_e32 v168, 16, v175
	v_and_b32_e32 v169, 0xffff0000, v175
	v_lshlrev_b32_e32 v170, 16, v176
	v_and_b32_e32 v171, 0xffff0000, v176
	v_lshlrev_b32_e32 v172, 16, v177
	v_and_b32_e32 v173, 0xffff0000, v177
	v_lshlrev_b32_e32 v174, 16, v178
	v_and_b32_e32 v175, 0xffff0000, v178
	v_lshlrev_b32_e32 v176, 16, v179
	v_and_b32_e32 v177, 0xffff0000, v179
	v_lshlrev_b32_e32 v178, 16, v180
	v_and_b32_e32 v179, 0xffff0000, v180
	v_lshlrev_b32_e32 v180, 16, v181
	v_and_b32_e32 v181, 0xffff0000, v181
	s_nop 0
	v_mul_f32_e32 v120, v120, v140
	v_mul_f32_e32 v121, v121, v140
	v_mul_f32_e32 v122, v122, v140
	v_mul_f32_e32 v123, v123, v140
	v_mul_f32_e32 v124, v124, v140
	v_mul_f32_e32 v125, v125, v140
	v_mul_f32_e32 v126, v126, v140
	v_mul_f32_e32 v127, v127, v140
	v_mul_f32_e32 v128, v128, v140
	v_mul_f32_e32 v129, v129, v140
	v_mul_f32_e32 v130, v130, v140
	v_mul_f32_e32 v131, v131, v140
	v_mul_f32_e32 v132, v132, v140
	v_mul_f32_e32 v133, v133, v140
	v_mul_f32_e32 v134, v134, v140
	v_mul_f32_e32 v135, v135, v140
	v_fma_f32 v166, v120, v72, v166
	v_fma_f32 v167, v121, v73, v167
	v_fma_f32 v168, v122, v74, v168
	v_fma_f32 v169, v123, v75, v169
	v_fma_f32 v170, v124, v76, v170
	v_fma_f32 v171, v125, v77, v171
	v_fma_f32 v172, v126, v78, v172
	v_fma_f32 v173, v127, v79, v173
	v_fma_f32 v174, v128, v80, v174
	v_fma_f32 v175, v129, v81, v175
	v_fma_f32 v176, v130, v82, v176
	v_fma_f32 v177, v131, v83, v177
	v_fma_f32 v178, v132, v84, v178
	v_fma_f32 v179, v133, v85, v179
	v_fma_f32 v180, v134, v86, v180
; __device__ __forceinline__ void row_phase(const Params& P, int glayer, int layer, int xsrc, bool hasY, int gate_idx, const float* gpost,
;                           int xdst, bool doH, const float* gpre, int sh_idx, int nrows) {
;     ...
;             const float4 gt = *reinterpret_cast<const float4*>(modg + gate_idx * 1024 + col);
;             const float4 gp = *reinterpret_cast<const float4*>(gpost + col);
;             xv[i].x += gt.x * (yv[i].x * rstd * gp.x); xv[i].y += gt.y * (yv[i].y * rstd * gp.y);
;             xv[i].z += gt.z * (yv[i].z * rstd * gp.z); xv[i].w += gt.w * (yv[i].w * rstd * gp.w);
;           }
;         }
;         if (xdst == 3 || (xdst == 1 && row >= N_X)) {
;           float* xout = (xdst == 3) ? P.out + (long)row * 1024 : P.xc + (long)(row - N_X) * 1024;
; #pragma unroll
;           for (int i = 0; i < 4; ++i) *reinterpret_cast<float4*>(xout + (i * 64 + lane) * 4) = xv[i];
;         } else if (xdst != 0) {
;           u16* xo = ((xdst == 1) ? resA : P.zf) + (long)row * 1024;
; #pragma unroll
;           for (int i = 0; i < 4; ++i) {
;             const unsigned b0 = f2bf(xv[i].x), b1 = f2bf(xv[i].y), b2 = f2bf(xv[i].z), b3 = f2bf(xv[i].w);
;             *reinterpret_cast<uint2*>(xo + (i * 64 + lane) * 4) = make_uint2(b0 | (b1 << 16), b2 | (b3 << 16));
;           }
;         }
;         if (doH) {
;           float ss = 0.f;
; #pragma unroll
;           for (int i = 0; i < 4; ++i) ss += xv[i].x * xv[i].x + xv[i].y * xv[i].y + xv[i].z * xv[i].z + xv[i].w * xv[i].w;
;           ss = wave_sum(ss);
;           const float rstd = __builtin_amdgcn_rsqf(ss * (1.f / 1024.f) + EPSF);
;           u16* h = P.hy + (long)row * 1024;
; #pragma unroll
;           for (int i = 0; i < 4; ++i) {
;             const int col = (i * 64 + lane) * 4;
;             const float4 g = *reinterpret_cast<const float4*>(gpre + col);
;             const float4 sh = *reinterpret_cast<const float4*>(modp + sh_idx * 1024 + col);
;             const float4 sc = *reinterpret_cast<const float4*>(modp + (sh_idx + 1) * 1024 + col);
;             const unsigned h0 = f2bf(xv[i].x * rstd * g.x * (1.f + sc.x) + sh.x);
;             const unsigned h1 = f2bf(xv[i].y * rstd * g.y * (1.f + sc.y) + sh.y);
;             const unsigned h2 = f2bf(xv[i].z * rstd * g.z * (1.f + sc.z) + sh.z);
;             const unsigned h3 = f2bf(xv[i].w * rstd * g.w * (1.f + sc.w) + sh.w);
	v_fma_f32 v181, v135, v87, v181
	v_cvt_pk_bf16_f32 v156, v166, v167
	v_cvt_pk_bf16_f32 v157, v168, v169
	v_cvt_pk_bf16_f32 v158, v170, v171
	v_cvt_pk_bf16_f32 v159, v172, v173
	v_cvt_pk_bf16_f32 v160, v174, v175
	v_cvt_pk_bf16_f32 v161, v176, v177
	v_cvt_pk_bf16_f32 v162, v178, v179
	v_cvt_pk_bf16_f32 v163, v180, v181
	s_lshl_b32 vcc_lo, s19, 11
	s_add_u32 vcc_lo, vcc_lo, 0x2c00000
	s_add_u32 s100, s16, vcc_lo
	s_addc_u32 s101, s17, 0
	global_store_dwordx2 v137, v[156:157], s[100:101] offset:0
	global_store_dwordx2 v137, v[158:159], s[100:101] offset:512
	global_store_dwordx2 v137, v[160:161], s[100:101] offset:1024
	global_store_dwordx2 v137, v[162:163], s[100:101] offset:1536
	v_mul_f32_e32 v138, v166, v166
	v_mul_f32_e32 v149, v167, v167
	v_mul_f32_e32 v150, v168, v168
	v_mul_f32_e32 v154, v169, v169
	v_fma_f32 v138, v170, v170, v138
	v_fma_f32 v149, v171, v171, v149
	v_fma_f32 v150, v172, v172, v150
	v_fma_f32 v154, v173, v173, v154
	v_fma_f32 v138, v174, v174, v138
	v_fma_f32 v149, v175, v175, v149
	v_fma_f32 v150, v176, v176, v150
	v_fma_f32 v154, v177, v177, v154
	v_fma_f32 v138, v178, v178, v138
	v_fma_f32 v149, v179, v179, v149
	v_fma_f32 v150, v180, v180, v150
	v_fma_f32 v154, v181, v181, v154
	v_add_f32_e32 v138, v138, v149
	v_add_f32_e32 v150, v150, v154
	v_add_f32_e32 v138, v138, v150
	s_nop 1
	v_add_f32_dpp v138, v138, v138 quad_perm:[1,0,3,2] row_mask:0xf bank_mask:0xf
	s_nop 1
	v_add_f32_dpp v138, v138, v138 quad_perm:[2,3,0,1] row_mask:0xf bank_mask:0xf
	s_nop 1
	v_add_f32_dpp v138, v138, v138 row_half_mirror row_mask:0xf bank_mask:0xf
	s_nop 1
	v_add_f32_dpp v138, v138, v138 row_mirror row_mask:0xf bank_mask:0xf
	v_mov_b32_e32 v139, v138
	s_nop 1
	v_permlane16_swap_b32_e32 v138, v139
	v_add_f32_e32 v138, v138, v139
	v_mov_b32_e32 v139, v138
	s_nop 1
	v_permlane32_swap_b32_e32 v138, v139
	v_add_f32_e32 v138, v138, v139
	v_mul_f32_e32 v138, 0x3a800000, v138
	v_add_f32_e32 v138, 0x358637bd, v138
	v_rsq_f32_e32 v140, v138
	s_nop 0
	v_mul_f32_e32 v120, v166, v140
	v_mul_f32_e32 v121, v167, v140
	v_mul_f32_e32 v122, v168, v140
	v_mul_f32_e32 v123, v169, v140
	v_mul_f32_e32 v124, v170, v140
	v_mul_f32_e32 v125, v171, v140
	v_mul_f32_e32 v126, v172, v140
	v_mul_f32_e32 v127, v173, v140
	v_mul_f32_e32 v128, v174, v140
	v_mul_f32_e32 v129, v175, v140
	v_mul_f32_e32 v130, v176, v140
	v_mul_f32_e32 v131, v177, v140
	v_mul_f32_e32 v132, v178, v140
	v_mul_f32_e32 v133, v179, v140
	v_mul_f32_e32 v134, v180, v140
	v_mul_f32_e32 v135, v181, v140
	v_fma_f32 v120, v120, v88, v104
	v_fma_f32 v121, v121, v89, v105
	v_fma_f32 v122, v122, v90, v106
	v_fma_f32 v123, v123, v91, v107
	v_fma_f32 v124, v124, v92, v108
	v_fma_f32 v125, v125, v93, v109
	v_fma_f32 v126, v126, v94, v110
	v_fma_f32 v127, v127, v95, v111
	v_fma_f32 v128, v128, v96, v112
	v_fma_f32 v129, v129, v97, v113
	v_fma_f32 v130, v130, v98, v114
	v_fma_f32 v131, v131, v99, v115
	v_fma_f32 v132, v132, v100, v116
	v_fma_f32 v133, v133, v101, v117
	v_fma_f32 v134, v134, v102, v118
	v_fma_f32 v135, v135, v103, v119
	v_cvt_pk_bf16_f32 v156, v120, v121
	v_cvt_pk_bf16_f32 v157, v122, v123
	v_cvt_pk_bf16_f32 v158, v124, v125
	v_cvt_pk_bf16_f32 v159, v126, v127
	v_cvt_pk_bf16_f32 v160, v128, v129
	v_cvt_pk_bf16_f32 v161, v130, v131
	v_cvt_pk_bf16_f32 v162, v132, v133
	v_cvt_pk_bf16_f32 v163, v134, v135
	s_lshl_b32 vcc_lo, s19, 11
	s_add_u32 vcc_lo, vcc_lo, 0x2c00000
	s_add_u32 s100, s14, vcc_lo
	s_addc_u32 s101, s15, 0
	global_store_dwordx2 v137, v[156:157], s[100:101] offset:0
	global_store_dwordx2 v137, v[158:159], s[100:101] offset:512
	global_store_dwordx2 v137, v[160:161], s[100:101] offset:1024
	global_store_dwordx2 v137, v[162:163], s[100:101] offset:1536
	s_add_u32 s100, s20, 0x32000
	s_addc_u32 s101, s21, 0
	global_load_dwordx4 v[72:75], v136, s[100:101] offset:0
	global_load_dwordx4 v[76:79], v136, s[100:101] offset:1024
	global_load_dwordx4 v[80:83], v136, s[100:101] offset:2048
	global_load_dwordx4 v[84:87], v136, s[100:101] offset:3072
	s_load_dwordx2 s[98:99], s[4:5], 0x38
	s_waitcnt lgkmcnt(0)
	s_add_u32 s98, s98, 0x1000
	s_addc_u32 s99, s99, 0
	global_load_dwordx4 v[120:123], v136, s[98:99] offset:0
	global_load_dwordx4 v[124:127], v136, s[98:99] offset:1024
	global_load_dwordx4 v[128:131], v136, s[98:99] offset:2048
	global_load_dwordx4 v[132:135], v136, s[98:99] offset:3072
	s_add_u32 s100, s20, 0x33000
	s_addc_u32 s101, s21, 0
	global_load_dwordx4 v[104:107], v136, s[100:101] offset:0
	global_load_dwordx4 v[108:111], v136, s[100:101] offset:1024
	global_load_dwordx4 v[112:115], v136, s[100:101] offset:2048
	global_load_dwordx4 v[116:119], v136, s[100:101] offset:3072
	s_add_u32 s100, s100, 0x1000
	s_addc_u32 s101, s101, 0
	global_load_dwordx4 v[166:169], v136, s[100:101] offset:0
	global_load_dwordx4 v[170:173], v136, s[100:101] offset:1024
	global_load_dwordx4 v[174:177], v136, s[100:101] offset:2048
	global_load_dwordx4 v[178:181], v136, s[100:101] offset:3072
	s_load_dwordx2 s[98:99], s[4:5], 0x40
	s_waitcnt lgkmcnt(0)
	s_add_u32 s98, s98, 0x1000
	s_addc_u32 s99, s99, 0
	global_load_dwordx4 v[88:91], v136, s[98:99] offset:0
	global_load_dwordx4 v[92:95], v136, s[98:99] offset:1024
	global_load_dwordx4 v[96:99], v136, s[98:99] offset:2048
	global_load_dwordx4 v[100:103], v136, s[98:99] offset:3072
	s_waitcnt vmcnt(0)
; __device__ __forceinline__ void row_phase(const Params& P, int glayer, int layer, int xsrc, bool hasY, int gate_idx, const float* gpost,
;                           int xdst, bool doH, const float* gpre, int sh_idx, int nrows) {
;     ...
;             ss += yv[i].x * yv[i].x + yv[i].y * yv[i].y + yv[i].z * yv[i].z + yv[i].w * yv[i].w;
;           }
;           ss = wave_sum(ss);
;           const float rstd = __builtin_amdgcn_rsqf(ss * (1.f / 1024.f) + EPSF);
; #pragma unroll
;           for (int i = 0; i < 4; ++i) {
;             const int col = (i * 64 + lane) * 4;
;             const float4 gt = *reinterpret_cast<const float4*>(modg + gate_idx * 1024 + col);
;             const float4 gp = *reinterpret_cast<const float4*>(gpost + col);
;             xv[i].x += gt.x * (yv[i].x * rstd * gp.x); xv[i].y += gt.y * (yv[i].y * rstd * gp.y);
;             xv[i].z += gt.z * (yv[i].z * rstd * gp.z); xv[i].w += gt.w * (yv[i].w * rstd * gp.w);
;           }
;         }
;         if (xdst == 3 || (xdst == 1 && row >= N_X)) {
;           float* xout = (xdst == 3) ? P.out + (long)row * 1024 : P.xc + (long)(row - N_X) * 1024;
; #pragma unroll
;           for (int i = 0; i < 4; ++i) *reinterpret_cast<float4*>(xout + (i * 64 + lane) * 4) = xv[i];
;         } else if (xdst != 0) {
;           u16* xo = ((xdst == 1) ? resA : P.zf) + (long)row * 1024;
; #pragma unroll
;           for (int i = 0; i < 4; ++i) {
;             const unsigned b0 = f2bf(xv[i].x), b1 = f2bf(xv[i].y), b2 = f2bf(xv[i].z), b3 = f2bf(xv[i].w);
;             *reinterpret_cast<uint2*>(xo + (i * 64 + lane) * 4) = make_uint2(b0 | (b1 << 16), b2 | (b3 << 16));
;     ...
;             const float4 g = *reinterpret_cast<const float4*>(gpre + col);
;             const float4 sh = *reinterpret_cast<const float4*>(modp + sh_idx * 1024 + col);
;             const float4 sc = *reinterpret_cast<const float4*>(modp + (sh_idx + 1) * 1024 + col);
;             const unsigned h0 = f2bf(xv[i].x * rstd * g.x * (1.f + sc.x) + sh.x);
;             const unsigned h1 = f2bf(xv[i].y * rstd * g.y * (1.f + sc.y) + sh.y);
;             const unsigned h2 = f2bf(xv[i].z * rstd * g.z * (1.f + sc.z) + sh.z);
;             const unsigned h3 = f2bf(xv[i].w * rstd * g.w * (1.f + sc.w) + sh.w);
	v_mul_f32_e32 v72, v72, v120
	v_mul_f32_e32 v73, v73, v121
	v_mul_f32_e32 v74, v74, v122
	v_mul_f32_e32 v75, v75, v123
	v_mul_f32_e32 v76, v76, v124
	v_mul_f32_e32 v77, v77, v125
	v_mul_f32_e32 v78, v78, v126
	v_mul_f32_e32 v79, v79, v127
	v_mul_f32_e32 v80, v80, v128
	v_mul_f32_e32 v81, v81, v129
	v_mul_f32_e32 v82, v82, v130
	v_mul_f32_e32 v83, v83, v131
	v_mul_f32_e32 v84, v84, v132
	v_mul_f32_e32 v85, v85, v133
	v_mul_f32_e32 v86, v86, v134
	v_mul_f32_e32 v87, v87, v135
	v_fma_f32 v88, v88, v166, v88
	v_fma_f32 v89, v89, v167, v89
	v_fma_f32 v90, v90, v168, v90
	v_fma_f32 v91, v91, v169, v91
	v_fma_f32 v92, v92, v170, v92
	v_fma_f32 v93, v93, v171, v93
	v_fma_f32 v94, v94, v172, v94
	v_fma_f32 v95, v95, v173, v95
	v_fma_f32 v96, v96, v174, v96
	v_fma_f32 v97, v97, v175, v97
	v_fma_f32 v98, v98, v176, v98
	v_fma_f32 v99, v99, v177, v99
	v_fma_f32 v100, v100, v178, v100
	v_fma_f32 v101, v101, v179, v101
	v_fma_f32 v102, v102, v180, v102
	v_fma_f32 v103, v103, v181, v103
	s_lshl_b32 vcc_lo, s19, 11
	s_add_u32 vcc_lo, vcc_lo, 0x3c00000
	s_add_u32 s100, s12, vcc_lo
	s_addc_u32 s101, s13, 0
	global_load_dwordx2 v[174:175], v137, s[100:101] offset:0
	global_load_dwordx2 v[176:177], v137, s[100:101] offset:512
	global_load_dwordx2 v[178:179], v137, s[100:101] offset:1024
	global_load_dwordx2 v[180:181], v137, s[100:101] offset:1536
	s_lshl_b32 vcc_lo, s19, 11
	s_add_u32 vcc_lo, vcc_lo, 0x3c00000
	s_add_u32 s100, s14, vcc_lo
	s_addc_u32 s101, s15, 0
	global_load_dwordx2 v[182:183], v137, s[100:101] offset:0
	global_load_dwordx2 v[184:185], v137, s[100:101] offset:512
	global_load_dwordx2 v[186:187], v137, s[100:101] offset:1024
	global_load_dwordx2 v[188:189], v137, s[100:101] offset:1536
	v_lshlrev_b32_e32 v120, 16, v48
	v_and_b32_e32 v121, 0xffff0000, v48
	v_lshlrev_b32_e32 v122, 16, v49
	v_and_b32_e32 v123, 0xffff0000, v49
	v_lshlrev_b32_e32 v124, 16, v50
	v_and_b32_e32 v125, 0xffff0000, v50
	v_lshlrev_b32_e32 v126, 16, v51
	v_and_b32_e32 v127, 0xffff0000, v51
	v_lshlrev_b32_e32 v128, 16, v52
	v_and_b32_e32 v129, 0xffff0000, v52
	v_lshlrev_b32_e32 v130, 16, v53
	v_and_b32_e32 v131, 0xffff0000, v53
	v_lshlrev_b32_e32 v132, 16, v54
	v_and_b32_e32 v133, 0xffff0000, v54
	v_lshlrev_b32_e32 v134, 16, v55
	v_and_b32_e32 v135, 0xffff0000, v55
	v_mul_f32_e32 v138, v120, v120
	v_mul_f32_e32 v149, v121, v121
	v_mul_f32_e32 v150, v122, v122
	v_mul_f32_e32 v154, v123, v123
	v_fma_f32 v138, v124, v124, v138
	v_fma_f32 v149, v125, v125, v149
	v_fma_f32 v150, v126, v126, v150
	v_fma_f32 v154, v127, v127, v154
	v_fma_f32 v138, v128, v128, v138
	v_fma_f32 v149, v129, v129, v149
	v_fma_f32 v150, v130, v130, v150
	v_fma_f32 v154, v131, v131, v154
	v_fma_f32 v138, v132, v132, v138
	v_fma_f32 v149, v133, v133, v149
	v_fma_f32 v150, v134, v134, v150
	v_fma_f32 v154, v135, v135, v154
	v_add_f32_e32 v138, v138, v149
	v_add_f32_e32 v150, v150, v154
	v_add_f32_e32 v138, v138, v150
	s_nop 1
	v_add_f32_dpp v138, v138, v138 quad_perm:[1,0,3,2] row_mask:0xf bank_mask:0xf
	s_nop 1
	v_add_f32_dpp v138, v138, v138 quad_perm:[2,3,0,1] row_mask:0xf bank_mask:0xf
	s_nop 1
	v_add_f32_dpp v138, v138, v138 row_half_mirror row_mask:0xf bank_mask:0xf
	s_nop 1
	v_add_f32_dpp v138, v138, v138 row_mirror row_mask:0xf bank_mask:0xf
	v_mov_b32_e32 v139, v138
	s_nop 1
	v_permlane16_swap_b32_e32 v138, v139
	v_add_f32_e32 v138, v138, v139
	v_mov_b32_e32 v139, v138
	s_nop 1
	v_permlane32_swap_b32_e32 v138, v139
	v_add_f32_e32 v138, v138, v139
	v_mul_f32_e32 v138, 0x3a800000, v138
	v_add_f32_e32 v138, 0x358637bd, v138
	v_rsq_f32_e32 v140, v138
	v_lshlrev_b32_e32 v0, 16, v8
	v_and_b32_e32 v1, 0xffff0000, v8
	v_lshlrev_b32_e32 v2, 16, v9
	v_and_b32_e32 v3, 0xffff0000, v9
	v_lshlrev_b32_e32 v4, 16, v10
	v_and_b32_e32 v5, 0xffff0000, v10
	v_lshlrev_b32_e32 v6, 16, v11
	v_and_b32_e32 v7, 0xffff0000, v11
	v_lshlrev_b32_e32 v8, 16, v12
	v_and_b32_e32 v9, 0xffff0000, v12
	v_lshlrev_b32_e32 v10, 16, v13
	v_and_b32_e32 v11, 0xffff0000, v13
	v_lshlrev_b32_e32 v12, 16, v14
	v_and_b32_e32 v13, 0xffff0000, v14
	v_lshlrev_b32_e32 v14, 16, v15
	v_and_b32_e32 v15, 0xffff0000, v15
	s_nop 0
	v_mul_f32_e32 v120, v120, v140
	v_mul_f32_e32 v121, v121, v140
	v_mul_f32_e32 v122, v122, v140
	v_mul_f32_e32 v123, v123, v140
	v_mul_f32_e32 v124, v124, v140
	v_mul_f32_e32 v125, v125, v140
	v_mul_f32_e32 v126, v126, v140
	v_mul_f32_e32 v127, v127, v140
	v_mul_f32_e32 v128, v128, v140
	v_mul_f32_e32 v129, v129, v140
	v_mul_f32_e32 v130, v130, v140
	v_mul_f32_e32 v131, v131, v140
	v_mul_f32_e32 v132, v132, v140
	v_mul_f32_e32 v133, v133, v140
	v_mul_f32_e32 v134, v134, v140
	v_mul_f32_e32 v135, v135, v140
	v_fma_f32 v0, v120, v72, v0
	v_fma_f32 v1, v121, v73, v1
	v_fma_f32 v2, v122, v74, v2
	v_fma_f32 v3, v123, v75, v3
	v_fma_f32 v4, v124, v76, v4
	v_fma_f32 v5, v125, v77, v5
	v_fma_f32 v6, v126, v78, v6
	v_fma_f32 v7, v127, v79, v7
	v_fma_f32 v8, v128, v80, v8
	v_fma_f32 v9, v129, v81, v9
	v_fma_f32 v10, v130, v82, v10
	v_fma_f32 v11, v131, v83, v11
	v_fma_f32 v12, v132, v84, v12
	v_fma_f32 v13, v133, v85, v13
	v_fma_f32 v14, v134, v86, v14
	v_fma_f32 v15, v135, v87, v15
	v_cvt_pk_bf16_f32 v156, v0, v1
	v_cvt_pk_bf16_f32 v157, v2, v3
	v_cvt_pk_bf16_f32 v158, v4, v5
	v_cvt_pk_bf16_f32 v159, v6, v7
	v_cvt_pk_bf16_f32 v160, v8, v9
	v_cvt_pk_bf16_f32 v161, v10, v11
	v_cvt_pk_bf16_f32 v162, v12, v13
	v_cvt_pk_bf16_f32 v163, v14, v15
	s_lshl_b32 vcc_lo, s19, 11
	s_add_u32 vcc_lo, vcc_lo, 0x3000000
	s_add_u32 s100, s16, vcc_lo
	s_addc_u32 s101, s17, 0
	global_store_dwordx2 v137, v[156:157], s[100:101] offset:0
	global_store_dwordx2 v137, v[158:159], s[100:101] offset:512
	global_store_dwordx2 v137, v[160:161], s[100:101] offset:1024
; __device__ __forceinline__ void row_phase(const Params& P, int glayer, int layer, int xsrc, bool hasY, int gate_idx, const float* gpost,
;                           int xdst, bool doH, const float* gpre, int sh_idx, int nrows) {
;     ...
;           const float rstd = __builtin_amdgcn_rsqf(ss * (1.f / 1024.f) + EPSF);
; #pragma unroll
;           for (int i = 0; i < 4; ++i) {
;             const int col = (i * 64 + lane) * 4;
;             const float4 gt = *reinterpret_cast<const float4*>(modg + gate_idx * 1024 + col);
;             const float4 gp = *reinterpret_cast<const float4*>(gpost + col);
;             xv[i].x += gt.x * (yv[i].x * rstd * gp.x); xv[i].y += gt.y * (yv[i].y * rstd * gp.y);
;             xv[i].z += gt.z * (yv[i].z * rstd * gp.z); xv[i].w += gt.w * (yv[i].w * rstd * gp.w);
;           }
;         }
;         if (xdst == 3 || (xdst == 1 && row >= N_X)) {
;           float* xout = (xdst == 3) ? P.out + (long)row * 1024 : P.xc + (long)(row - N_X) * 1024;
; #pragma unroll
;           for (int i = 0; i < 4; ++i) *reinterpret_cast<float4*>(xout + (i * 64 + lane) * 4) = xv[i];
;         } else if (xdst != 0) {
;           u16* xo = ((xdst == 1) ? resA : P.zf) + (long)row * 1024;
; #pragma unroll
;           for (int i = 0; i < 4; ++i) {
;             const unsigned b0 = f2bf(xv[i].x), b1 = f2bf(xv[i].y), b2 = f2bf(xv[i].z), b3 = f2bf(xv[i].w);
;             *reinterpret_cast<uint2*>(xo + (i * 64 + lane) * 4) = make_uint2(b0 | (b1 << 16), b2 | (b3 << 16));
;           }
;         }
;         if (doH) {
;           float ss = 0.f;
; #pragma unroll
;           for (int i = 0; i < 4; ++i) ss += xv[i].x * xv[i].x + xv[i].y * xv[i].y + xv[i].z * xv[i].z + xv[i].w * xv[i].w;
;           ss = wave_sum(ss);
;           const float rstd = __builtin_amdgcn_rsqf(ss * (1.f / 1024.f) + EPSF);
;           u16* h = P.hy + (long)row * 1024;
; #pragma unroll
;           for (int i = 0; i < 4; ++i) {
;             const int col = (i * 64 + lane) * 4;
;             const float4 g = *reinterpret_cast<const float4*>(gpre + col);
;             const float4 sh = *reinterpret_cast<const float4*>(modp + sh_idx * 1024 + col);
;             const float4 sc = *reinterpret_cast<const float4*>(modp + (sh_idx + 1) * 1024 + col);
;             const unsigned h0 = f2bf(xv[i].x * rstd * g.x * (1.f + sc.x) + sh.x);
	global_store_dwordx2 v137, v[162:163], s[100:101] offset:1536
	v_mul_f32_e32 v138, v0, v0
	v_mul_f32_e32 v149, v1, v1
	v_mul_f32_e32 v150, v2, v2
	v_mul_f32_e32 v154, v3, v3
	v_fma_f32 v138, v4, v4, v138
	v_fma_f32 v149, v5, v5, v149
	v_fma_f32 v150, v6, v6, v150
	v_fma_f32 v154, v7, v7, v154
	v_fma_f32 v138, v8, v8, v138
	v_fma_f32 v149, v9, v9, v149
	v_fma_f32 v150, v10, v10, v150
	v_fma_f32 v154, v11, v11, v154
	v_fma_f32 v138, v12, v12, v138
	v_fma_f32 v149, v13, v13, v149
	v_fma_f32 v150, v14, v14, v150
	v_fma_f32 v154, v15, v15, v154
	v_add_f32_e32 v138, v138, v149
	v_add_f32_e32 v150, v150, v154
	v_add_f32_e32 v138, v138, v150
	s_nop 1
	v_add_f32_dpp v138, v138, v138 quad_perm:[1,0,3,2] row_mask:0xf bank_mask:0xf
	s_nop 1
	v_add_f32_dpp v138, v138, v138 quad_perm:[2,3,0,1] row_mask:0xf bank_mask:0xf
	s_nop 1
	v_add_f32_dpp v138, v138, v138 row_half_mirror row_mask:0xf bank_mask:0xf
	s_nop 1
	v_add_f32_dpp v138, v138, v138 row_mirror row_mask:0xf bank_mask:0xf
	v_mov_b32_e32 v139, v138
	s_nop 1
	v_permlane16_swap_b32_e32 v138, v139
	v_add_f32_e32 v138, v138, v139
	v_mov_b32_e32 v139, v138
	s_nop 1
	v_permlane32_swap_b32_e32 v138, v139
	v_add_f32_e32 v138, v138, v139
	v_mul_f32_e32 v138, 0x3a800000, v138
	v_add_f32_e32 v138, 0x358637bd, v138
	v_rsq_f32_e32 v140, v138
	s_nop 0
	v_mul_f32_e32 v120, v0, v140
	v_mul_f32_e32 v121, v1, v140
	v_mul_f32_e32 v122, v2, v140
	v_mul_f32_e32 v123, v3, v140
	v_mul_f32_e32 v124, v4, v140
	v_mul_f32_e32 v125, v5, v140
	v_mul_f32_e32 v126, v6, v140
	v_mul_f32_e32 v127, v7, v140
	v_mul_f32_e32 v128, v8, v140
	v_mul_f32_e32 v129, v9, v140
	v_mul_f32_e32 v130, v10, v140
	v_mul_f32_e32 v131, v11, v140
	v_mul_f32_e32 v132, v12, v140
	v_mul_f32_e32 v133, v13, v140
	v_mul_f32_e32 v134, v14, v140
	v_mul_f32_e32 v135, v15, v140
	v_fma_f32 v120, v120, v88, v104
	v_fma_f32 v121, v121, v89, v105
	v_fma_f32 v122, v122, v90, v106
	v_fma_f32 v123, v123, v91, v107
	v_fma_f32 v124, v124, v92, v108
	v_fma_f32 v125, v125, v93, v109
	v_fma_f32 v126, v126, v94, v110
	v_fma_f32 v127, v127, v95, v111
	v_fma_f32 v128, v128, v96, v112
	v_fma_f32 v129, v129, v97, v113
	v_fma_f32 v130, v130, v98, v114
	v_fma_f32 v131, v131, v99, v115
	v_fma_f32 v132, v132, v100, v116
	v_fma_f32 v133, v133, v101, v117
	v_fma_f32 v134, v134, v102, v118
	v_fma_f32 v135, v135, v103, v119
	v_cvt_pk_bf16_f32 v156, v120, v121
	v_cvt_pk_bf16_f32 v157, v122, v123
	v_cvt_pk_bf16_f32 v158, v124, v125
	v_cvt_pk_bf16_f32 v159, v126, v127
	v_cvt_pk_bf16_f32 v160, v128, v129
	v_cvt_pk_bf16_f32 v161, v130, v131
	v_cvt_pk_bf16_f32 v162, v132, v133
	v_cvt_pk_bf16_f32 v163, v134, v135
	s_lshl_b32 vcc_lo, s19, 11
	s_add_u32 vcc_lo, vcc_lo, 0x3000000
	s_add_u32 s100, s14, vcc_lo
	s_addc_u32 s101, s15, 0
	global_store_dwordx2 v137, v[156:157], s[100:101] offset:0
	global_store_dwordx2 v137, v[158:159], s[100:101] offset:512
	global_store_dwordx2 v137, v[160:161], s[100:101] offset:1024
	global_store_dwordx2 v137, v[162:163], s[100:101] offset:1536
	v_lshlrev_b32_e32 v120, 16, v56
	v_and_b32_e32 v121, 0xffff0000, v56
	v_lshlrev_b32_e32 v122, 16, v57
	v_and_b32_e32 v123, 0xffff0000, v57
	v_lshlrev_b32_e32 v124, 16, v58
	v_and_b32_e32 v125, 0xffff0000, v58
	v_lshlrev_b32_e32 v126, 16, v59
	v_and_b32_e32 v127, 0xffff0000, v59
	v_lshlrev_b32_e32 v128, 16, v60
	v_and_b32_e32 v129, 0xffff0000, v60
	v_lshlrev_b32_e32 v130, 16, v61
	v_and_b32_e32 v131, 0xffff0000, v61
	v_lshlrev_b32_e32 v132, 16, v62
	v_and_b32_e32 v133, 0xffff0000, v62
	v_lshlrev_b32_e32 v134, 16, v63
	v_and_b32_e32 v135, 0xffff0000, v63
	v_mul_f32_e32 v138, v120, v120
	v_mul_f32_e32 v149, v121, v121
	v_mul_f32_e32 v150, v122, v122
	v_mul_f32_e32 v154, v123, v123
	v_fma_f32 v138, v124, v124, v138
	v_fma_f32 v149, v125, v125, v149
	v_fma_f32 v150, v126, v126, v150
	v_fma_f32 v154, v127, v127, v154
	v_fma_f32 v138, v128, v128, v138
	v_fma_f32 v149, v129, v129, v149
	v_fma_f32 v150, v130, v130, v150
	v_fma_f32 v154, v131, v131, v154
	v_fma_f32 v138, v132, v132, v138
	v_fma_f32 v149, v133, v133, v149
	v_fma_f32 v150, v134, v134, v150
	v_fma_f32 v154, v135, v135, v154
	v_add_f32_e32 v138, v138, v149
	v_add_f32_e32 v150, v150, v154
	v_add_f32_e32 v138, v138, v150
	s_nop 1
	v_add_f32_dpp v138, v138, v138 quad_perm:[1,0,3,2] row_mask:0xf bank_mask:0xf
	s_nop 1
	v_add_f32_dpp v138, v138, v138 quad_perm:[2,3,0,1] row_mask:0xf bank_mask:0xf
	s_nop 1
	v_add_f32_dpp v138, v138, v138 row_half_mirror row_mask:0xf bank_mask:0xf
	s_nop 1
	v_add_f32_dpp v138, v138, v138 row_mirror row_mask:0xf bank_mask:0xf
	v_mov_b32_e32 v139, v138
	s_nop 1
	v_permlane16_swap_b32_e32 v138, v139
	v_add_f32_e32 v138, v138, v139
	v_mov_b32_e32 v139, v138
	s_nop 1
	v_permlane32_swap_b32_e32 v138, v139
	v_add_f32_e32 v138, v138, v139
	v_mul_f32_e32 v138, 0x3a800000, v138
	v_add_f32_e32 v138, 0x358637bd, v138
	v_rsq_f32_e32 v140, v138
	v_lshlrev_b32_e32 v16, 16, v24
	v_and_b32_e32 v17, 0xffff0000, v24
	v_lshlrev_b32_e32 v18, 16, v25
	v_and_b32_e32 v19, 0xffff0000, v25
	v_lshlrev_b32_e32 v20, 16, v26
	v_and_b32_e32 v21, 0xffff0000, v26
	v_lshlrev_b32_e32 v22, 16, v27
	v_and_b32_e32 v23, 0xffff0000, v27
	v_lshlrev_b32_e32 v24, 16, v28
	v_and_b32_e32 v25, 0xffff0000, v28
	v_lshlrev_b32_e32 v26, 16, v29
	v_and_b32_e32 v27, 0xffff0000, v29
	v_lshlrev_b32_e32 v28, 16, v30
	v_and_b32_e32 v29, 0xffff0000, v30
	v_lshlrev_b32_e32 v30, 16, v31
	v_and_b32_e32 v31, 0xffff0000, v31
	s_nop 0
	v_mul_f32_e32 v120, v120, v140
	v_mul_f32_e32 v121, v121, v140
	v_mul_f32_e32 v122, v122, v140
	v_mul_f32_e32 v123, v123, v140
	v_mul_f32_e32 v124, v124, v140
	v_mul_f32_e32 v125, v125, v140
	v_mul_f32_e32 v126, v126, v140
	v_mul_f32_e32 v127, v127, v140
; __device__ __forceinline__ void row_phase(const Params& P, int glayer, int layer, int xsrc, bool hasY, int gate_idx, const float* gpost,
;                           int xdst, bool doH, const float* gpre, int sh_idx, int nrows) {
;     ...
;             const float4 gt = *reinterpret_cast<const float4*>(modg + gate_idx * 1024 + col);
;             const float4 gp = *reinterpret_cast<const float4*>(gpost + col);
;             xv[i].x += gt.x * (yv[i].x * rstd * gp.x); xv[i].y += gt.y * (yv[i].y * rstd * gp.y);
;             xv[i].z += gt.z * (yv[i].z * rstd * gp.z); xv[i].w += gt.w * (yv[i].w * rstd * gp.w);
;           }
;         }
;         if (xdst == 3 || (xdst == 1 && row >= N_X)) {
;           float* xout = (xdst == 3) ? P.out + (long)row * 1024 : P.xc + (long)(row - N_X) * 1024;
; #pragma unroll
;           for (int i = 0; i < 4; ++i) *reinterpret_cast<float4*>(xout + (i * 64 + lane) * 4) = xv[i];
;         } else if (xdst != 0) {
;           u16* xo = ((xdst == 1) ? resA : P.zf) + (long)row * 1024;
; #pragma unroll
;           for (int i = 0; i < 4; ++i) {
;             const unsigned b0 = f2bf(xv[i].x), b1 = f2bf(xv[i].y), b2 = f2bf(xv[i].z), b3 = f2bf(xv[i].w);
;             *reinterpret_cast<uint2*>(xo + (i * 64 + lane) * 4) = make_uint2(b0 | (b1 << 16), b2 | (b3 << 16));
;           }
;         }
;         if (doH) {
;           float ss = 0.f;
; #pragma unroll
;           for (int i = 0; i < 4; ++i) ss += xv[i].x * xv[i].x + xv[i].y * xv[i].y + xv[i].z * xv[i].z + xv[i].w * xv[i].w;
;           ss = wave_sum(ss);
;           const float rstd = __builtin_amdgcn_rsqf(ss * (1.f / 1024.f) + EPSF);
;           u16* h = P.hy + (long)row * 1024;
; #pragma unroll
;           for (int i = 0; i < 4; ++i) {
;             const int col = (i * 64 + lane) * 4;
;             const float4 g = *reinterpret_cast<const float4*>(gpre + col);
;             const float4 sh = *reinterpret_cast<const float4*>(modp + sh_idx * 1024 + col);
;             const float4 sc = *reinterpret_cast<const float4*>(modp + (sh_idx + 1) * 1024 + col);
;             const unsigned h0 = f2bf(xv[i].x * rstd * g.x * (1.f + sc.x) + sh.x);
;             const unsigned h1 = f2bf(xv[i].y * rstd * g.y * (1.f + sc.y) + sh.y);
;             const unsigned h2 = f2bf(xv[i].z * rstd * g.z * (1.f + sc.z) + sh.z);
;             const unsigned h3 = f2bf(xv[i].w * rstd * g.w * (1.f + sc.w) + sh.w);
	v_mul_f32_e32 v128, v128, v140
	v_mul_f32_e32 v129, v129, v140
	v_mul_f32_e32 v130, v130, v140
	v_mul_f32_e32 v131, v131, v140
	v_mul_f32_e32 v132, v132, v140
	v_mul_f32_e32 v133, v133, v140
	v_mul_f32_e32 v134, v134, v140
	v_mul_f32_e32 v135, v135, v140
	v_fma_f32 v16, v120, v72, v16
	v_fma_f32 v17, v121, v73, v17
	v_fma_f32 v18, v122, v74, v18
	v_fma_f32 v19, v123, v75, v19
	v_fma_f32 v20, v124, v76, v20
	v_fma_f32 v21, v125, v77, v21
	v_fma_f32 v22, v126, v78, v22
	v_fma_f32 v23, v127, v79, v23
	v_fma_f32 v24, v128, v80, v24
	v_fma_f32 v25, v129, v81, v25
	v_fma_f32 v26, v130, v82, v26
	v_fma_f32 v27, v131, v83, v27
	v_fma_f32 v28, v132, v84, v28
	v_fma_f32 v29, v133, v85, v29
	v_fma_f32 v30, v134, v86, v30
	v_fma_f32 v31, v135, v87, v31
	v_cvt_pk_bf16_f32 v156, v16, v17
	v_cvt_pk_bf16_f32 v157, v18, v19
	v_cvt_pk_bf16_f32 v158, v20, v21
	v_cvt_pk_bf16_f32 v159, v22, v23
	v_cvt_pk_bf16_f32 v160, v24, v25
	v_cvt_pk_bf16_f32 v161, v26, v27
	v_cvt_pk_bf16_f32 v162, v28, v29
	v_cvt_pk_bf16_f32 v163, v30, v31
	s_lshl_b32 vcc_lo, s19, 11
	s_add_u32 vcc_lo, vcc_lo, 0x3400000
	s_add_u32 s100, s16, vcc_lo
	s_addc_u32 s101, s17, 0
	global_store_dwordx2 v137, v[156:157], s[100:101] offset:0
	global_store_dwordx2 v137, v[158:159], s[100:101] offset:512
	global_store_dwordx2 v137, v[160:161], s[100:101] offset:1024
	global_store_dwordx2 v137, v[162:163], s[100:101] offset:1536
	v_mul_f32_e32 v138, v16, v16
	v_mul_f32_e32 v149, v17, v17
	v_mul_f32_e32 v150, v18, v18
	v_mul_f32_e32 v154, v19, v19
	v_fma_f32 v138, v20, v20, v138
	v_fma_f32 v149, v21, v21, v149
	v_fma_f32 v150, v22, v22, v150
	v_fma_f32 v154, v23, v23, v154
	v_fma_f32 v138, v24, v24, v138
	v_fma_f32 v149, v25, v25, v149
	v_fma_f32 v150, v26, v26, v150
	v_fma_f32 v154, v27, v27, v154
	v_fma_f32 v138, v28, v28, v138
	v_fma_f32 v149, v29, v29, v149
	v_fma_f32 v150, v30, v30, v150
	v_fma_f32 v154, v31, v31, v154
	v_add_f32_e32 v138, v138, v149
	v_add_f32_e32 v150, v150, v154
	v_add_f32_e32 v138, v138, v150
	s_nop 1
	v_add_f32_dpp v138, v138, v138 quad_perm:[1,0,3,2] row_mask:0xf bank_mask:0xf
	s_nop 1
	v_add_f32_dpp v138, v138, v138 quad_perm:[2,3,0,1] row_mask:0xf bank_mask:0xf
	s_nop 1
	v_add_f32_dpp v138, v138, v138 row_half_mirror row_mask:0xf bank_mask:0xf
	s_nop 1
	v_add_f32_dpp v138, v138, v138 row_mirror row_mask:0xf bank_mask:0xf
	v_mov_b32_e32 v139, v138
	s_nop 1
	v_permlane16_swap_b32_e32 v138, v139
	v_add_f32_e32 v138, v138, v139
	v_mov_b32_e32 v139, v138
	s_nop 1
	v_permlane32_swap_b32_e32 v138, v139
	v_add_f32_e32 v138, v138, v139
	v_mul_f32_e32 v138, 0x3a800000, v138
	v_add_f32_e32 v138, 0x358637bd, v138
	v_rsq_f32_e32 v140, v138
	s_nop 0
	v_mul_f32_e32 v120, v16, v140
	v_mul_f32_e32 v121, v17, v140
	v_mul_f32_e32 v122, v18, v140
	v_mul_f32_e32 v123, v19, v140
	v_mul_f32_e32 v124, v20, v140
	v_mul_f32_e32 v125, v21, v140
	v_mul_f32_e32 v126, v22, v140
	v_mul_f32_e32 v127, v23, v140
	v_mul_f32_e32 v128, v24, v140
	v_mul_f32_e32 v129, v25, v140
	v_mul_f32_e32 v130, v26, v140
	v_mul_f32_e32 v131, v27, v140
	v_mul_f32_e32 v132, v28, v140
	v_mul_f32_e32 v133, v29, v140
	v_mul_f32_e32 v134, v30, v140
	v_mul_f32_e32 v135, v31, v140
	v_fma_f32 v120, v120, v88, v104
	v_fma_f32 v121, v121, v89, v105
	v_fma_f32 v122, v122, v90, v106
	v_fma_f32 v123, v123, v91, v107
	v_fma_f32 v124, v124, v92, v108
	v_fma_f32 v125, v125, v93, v109
	v_fma_f32 v126, v126, v94, v110
	v_fma_f32 v127, v127, v95, v111
	v_fma_f32 v128, v128, v96, v112
	v_fma_f32 v129, v129, v97, v113
	v_fma_f32 v130, v130, v98, v114
	v_fma_f32 v131, v131, v99, v115
	v_fma_f32 v132, v132, v100, v116
	v_fma_f32 v133, v133, v101, v117
	v_fma_f32 v134, v134, v102, v118
	v_fma_f32 v135, v135, v103, v119
	v_cvt_pk_bf16_f32 v156, v120, v121
	v_cvt_pk_bf16_f32 v157, v122, v123
	v_cvt_pk_bf16_f32 v158, v124, v125
	v_cvt_pk_bf16_f32 v159, v126, v127
	v_cvt_pk_bf16_f32 v160, v128, v129
	v_cvt_pk_bf16_f32 v161, v130, v131
	v_cvt_pk_bf16_f32 v162, v132, v133
	v_cvt_pk_bf16_f32 v163, v134, v135
	s_lshl_b32 vcc_lo, s19, 11
	s_add_u32 vcc_lo, vcc_lo, 0x3400000
	s_add_u32 s100, s14, vcc_lo
	s_addc_u32 s101, s15, 0
	global_store_dwordx2 v137, v[156:157], s[100:101] offset:0
	global_store_dwordx2 v137, v[158:159], s[100:101] offset:512
	global_store_dwordx2 v137, v[160:161], s[100:101] offset:1024
	global_store_dwordx2 v137, v[162:163], s[100:101] offset:1536
	v_lshlrev_b32_e32 v120, 16, v64
	v_and_b32_e32 v121, 0xffff0000, v64
	v_lshlrev_b32_e32 v122, 16, v65
	v_and_b32_e32 v123, 0xffff0000, v65
	v_lshlrev_b32_e32 v124, 16, v66
	v_and_b32_e32 v125, 0xffff0000, v66
	v_lshlrev_b32_e32 v126, 16, v67
	v_and_b32_e32 v127, 0xffff0000, v67
	v_lshlrev_b32_e32 v128, 16, v68
	v_and_b32_e32 v129, 0xffff0000, v68
	v_lshlrev_b32_e32 v130, 16, v69
	v_and_b32_e32 v131, 0xffff0000, v69
	v_lshlrev_b32_e32 v132, 16, v70
	v_and_b32_e32 v133, 0xffff0000, v70
	v_lshlrev_b32_e32 v134, 16, v71
	v_and_b32_e32 v135, 0xffff0000, v71
	v_mul_f32_e32 v138, v120, v120
	v_mul_f32_e32 v149, v121, v121
	v_mul_f32_e32 v150, v122, v122
	v_mul_f32_e32 v154, v123, v123
	v_fma_f32 v138, v124, v124, v138
	v_fma_f32 v149, v125, v125, v149
	v_fma_f32 v150, v126, v126, v150
	v_fma_f32 v154, v127, v127, v154
	v_fma_f32 v138, v128, v128, v138
	v_fma_f32 v149, v129, v129, v149
	v_fma_f32 v150, v130, v130, v150
	v_fma_f32 v154, v131, v131, v154
	v_fma_f32 v138, v132, v132, v138
	v_fma_f32 v149, v133, v133, v149
	v_fma_f32 v150, v134, v134, v150
	v_fma_f32 v154, v135, v135, v154
	v_add_f32_e32 v138, v138, v149
	v_add_f32_e32 v150, v150, v154
	v_add_f32_e32 v138, v138, v150
	s_nop 1
	v_add_f32_dpp v138, v138, v138 quad_perm:[1,0,3,2] row_mask:0xf bank_mask:0xf
	s_nop 1
; __device__ __forceinline__ void row_phase(const Params& P, int glayer, int layer, int xsrc, bool hasY, int gate_idx, const float* gpost,
;                           int xdst, bool doH, const float* gpre, int sh_idx, int nrows) {
;     ...
;           const float rstd = __builtin_amdgcn_rsqf(ss * (1.f / 1024.f) + EPSF);
; #pragma unroll
;           for (int i = 0; i < 4; ++i) {
;             const int col = (i * 64 + lane) * 4;
;             const float4 gt = *reinterpret_cast<const float4*>(modg + gate_idx * 1024 + col);
;             const float4 gp = *reinterpret_cast<const float4*>(gpost + col);
;             xv[i].x += gt.x * (yv[i].x * rstd * gp.x); xv[i].y += gt.y * (yv[i].y * rstd * gp.y);
;             xv[i].z += gt.z * (yv[i].z * rstd * gp.z); xv[i].w += gt.w * (yv[i].w * rstd * gp.w);
;           }
;         }
;         if (xdst == 3 || (xdst == 1 && row >= N_X)) {
;           float* xout = (xdst == 3) ? P.out + (long)row * 1024 : P.xc + (long)(row - N_X) * 1024;
; #pragma unroll
;           for (int i = 0; i < 4; ++i) *reinterpret_cast<float4*>(xout + (i * 64 + lane) * 4) = xv[i];
;         } else if (xdst != 0) {
;           u16* xo = ((xdst == 1) ? resA : P.zf) + (long)row * 1024;
; #pragma unroll
;           for (int i = 0; i < 4; ++i) {
;             const unsigned b0 = f2bf(xv[i].x), b1 = f2bf(xv[i].y), b2 = f2bf(xv[i].z), b3 = f2bf(xv[i].w);
;             *reinterpret_cast<uint2*>(xo + (i * 64 + lane) * 4) = make_uint2(b0 | (b1 << 16), b2 | (b3 << 16));
;           }
;         }
;         if (doH) {
;           float ss = 0.f;
; #pragma unroll
;           for (int i = 0; i < 4; ++i) ss += xv[i].x * xv[i].x + xv[i].y * xv[i].y + xv[i].z * xv[i].z + xv[i].w * xv[i].w;
;           ss = wave_sum(ss);
;           const float rstd = __builtin_amdgcn_rsqf(ss * (1.f / 1024.f) + EPSF);
;           u16* h = P.hy + (long)row * 1024;
; #pragma unroll
;           for (int i = 0; i < 4; ++i) {
;             const int col = (i * 64 + lane) * 4;
;             const float4 g = *reinterpret_cast<const float4*>(gpre + col);
;             const float4 sh = *reinterpret_cast<const float4*>(modp + sh_idx * 1024 + col);
;             const float4 sc = *reinterpret_cast<const float4*>(modp + (sh_idx + 1) * 1024 + col);
;             const unsigned h0 = f2bf(xv[i].x * rstd * g.x * (1.f + sc.x) + sh.x);
	v_add_f32_dpp v138, v138, v138 quad_perm:[2,3,0,1] row_mask:0xf bank_mask:0xf
	s_nop 1
	v_add_f32_dpp v138, v138, v138 row_half_mirror row_mask:0xf bank_mask:0xf
	s_nop 1
	v_add_f32_dpp v138, v138, v138 row_mirror row_mask:0xf bank_mask:0xf
	v_mov_b32_e32 v139, v138
	s_nop 1
	v_permlane16_swap_b32_e32 v138, v139
	v_add_f32_e32 v138, v138, v139
	v_mov_b32_e32 v139, v138
	s_nop 1
	v_permlane32_swap_b32_e32 v138, v139
	v_add_f32_e32 v138, v138, v139
	v_mul_f32_e32 v138, 0x3a800000, v138
	v_add_f32_e32 v138, 0x358637bd, v138
	v_rsq_f32_e32 v140, v138
	v_lshlrev_b32_e32 v32, 16, v40
	v_and_b32_e32 v33, 0xffff0000, v40
	v_lshlrev_b32_e32 v34, 16, v41
	v_and_b32_e32 v35, 0xffff0000, v41
	v_lshlrev_b32_e32 v36, 16, v42
	v_and_b32_e32 v37, 0xffff0000, v42
	v_lshlrev_b32_e32 v38, 16, v43
	v_and_b32_e32 v39, 0xffff0000, v43
	v_lshlrev_b32_e32 v40, 16, v44
	v_and_b32_e32 v41, 0xffff0000, v44
	v_lshlrev_b32_e32 v42, 16, v45
	v_and_b32_e32 v43, 0xffff0000, v45
	v_lshlrev_b32_e32 v44, 16, v46
	v_and_b32_e32 v45, 0xffff0000, v46
	v_lshlrev_b32_e32 v46, 16, v47
	v_and_b32_e32 v47, 0xffff0000, v47
	s_nop 0
	v_mul_f32_e32 v120, v120, v140
	v_mul_f32_e32 v121, v121, v140
	v_mul_f32_e32 v122, v122, v140
	v_mul_f32_e32 v123, v123, v140
	v_mul_f32_e32 v124, v124, v140
	v_mul_f32_e32 v125, v125, v140
	v_mul_f32_e32 v126, v126, v140
	v_mul_f32_e32 v127, v127, v140
	v_mul_f32_e32 v128, v128, v140
	v_mul_f32_e32 v129, v129, v140
	v_mul_f32_e32 v130, v130, v140
	v_mul_f32_e32 v131, v131, v140
	v_mul_f32_e32 v132, v132, v140
	v_mul_f32_e32 v133, v133, v140
	v_mul_f32_e32 v134, v134, v140
	v_mul_f32_e32 v135, v135, v140
	v_fma_f32 v32, v120, v72, v32
	v_fma_f32 v33, v121, v73, v33
	v_fma_f32 v34, v122, v74, v34
	v_fma_f32 v35, v123, v75, v35
	v_fma_f32 v36, v124, v76, v36
	v_fma_f32 v37, v125, v77, v37
	v_fma_f32 v38, v126, v78, v38
	v_fma_f32 v39, v127, v79, v39
	v_fma_f32 v40, v128, v80, v40
	v_fma_f32 v41, v129, v81, v41
	v_fma_f32 v42, v130, v82, v42
	v_fma_f32 v43, v131, v83, v43
	v_fma_f32 v44, v132, v84, v44
	v_fma_f32 v45, v133, v85, v45
	v_fma_f32 v46, v134, v86, v46
	v_fma_f32 v47, v135, v87, v47
	v_cvt_pk_bf16_f32 v156, v32, v33
	v_cvt_pk_bf16_f32 v157, v34, v35
	v_cvt_pk_bf16_f32 v158, v36, v37
	v_cvt_pk_bf16_f32 v159, v38, v39
	v_cvt_pk_bf16_f32 v160, v40, v41
	v_cvt_pk_bf16_f32 v161, v42, v43
	v_cvt_pk_bf16_f32 v162, v44, v45
	v_cvt_pk_bf16_f32 v163, v46, v47
	s_lshl_b32 vcc_lo, s19, 11
	s_add_u32 vcc_lo, vcc_lo, 0x3800000
	s_add_u32 s100, s16, vcc_lo
	s_addc_u32 s101, s17, 0
	global_store_dwordx2 v137, v[156:157], s[100:101] offset:0
	global_store_dwordx2 v137, v[158:159], s[100:101] offset:512
	global_store_dwordx2 v137, v[160:161], s[100:101] offset:1024
	global_store_dwordx2 v137, v[162:163], s[100:101] offset:1536
	v_mul_f32_e32 v138, v32, v32
	v_mul_f32_e32 v149, v33, v33
	v_mul_f32_e32 v150, v34, v34
	v_mul_f32_e32 v154, v35, v35
	v_fma_f32 v138, v36, v36, v138
	v_fma_f32 v149, v37, v37, v149
	v_fma_f32 v150, v38, v38, v150
	v_fma_f32 v154, v39, v39, v154
	v_fma_f32 v138, v40, v40, v138
	v_fma_f32 v149, v41, v41, v149
	v_fma_f32 v150, v42, v42, v150
	v_fma_f32 v154, v43, v43, v154
	v_fma_f32 v138, v44, v44, v138
	v_fma_f32 v149, v45, v45, v149
	v_fma_f32 v150, v46, v46, v150
	v_fma_f32 v154, v47, v47, v154
	v_add_f32_e32 v138, v138, v149
	v_add_f32_e32 v150, v150, v154
	v_add_f32_e32 v138, v138, v150
	s_nop 1
	v_add_f32_dpp v138, v138, v138 quad_perm:[1,0,3,2] row_mask:0xf bank_mask:0xf
	s_nop 1
	v_add_f32_dpp v138, v138, v138 quad_perm:[2,3,0,1] row_mask:0xf bank_mask:0xf
	s_nop 1
	v_add_f32_dpp v138, v138, v138 row_half_mirror row_mask:0xf bank_mask:0xf
	s_nop 1
	v_add_f32_dpp v138, v138, v138 row_mirror row_mask:0xf bank_mask:0xf
	v_mov_b32_e32 v139, v138
	s_nop 1
	v_permlane16_swap_b32_e32 v138, v139
	v_add_f32_e32 v138, v138, v139
	v_mov_b32_e32 v139, v138
	s_nop 1
	v_permlane32_swap_b32_e32 v138, v139
	v_add_f32_e32 v138, v138, v139
	v_mul_f32_e32 v138, 0x3a800000, v138
	v_add_f32_e32 v138, 0x358637bd, v138
	v_rsq_f32_e32 v140, v138
	s_nop 0
	v_mul_f32_e32 v120, v32, v140
	v_mul_f32_e32 v121, v33, v140
	v_mul_f32_e32 v122, v34, v140
	v_mul_f32_e32 v123, v35, v140
	v_mul_f32_e32 v124, v36, v140
	v_mul_f32_e32 v125, v37, v140
	v_mul_f32_e32 v126, v38, v140
	v_mul_f32_e32 v127, v39, v140
	v_mul_f32_e32 v128, v40, v140
	v_mul_f32_e32 v129, v41, v140
	v_mul_f32_e32 v130, v42, v140
	v_mul_f32_e32 v131, v43, v140
	v_mul_f32_e32 v132, v44, v140
	v_mul_f32_e32 v133, v45, v140
	v_mul_f32_e32 v134, v46, v140
	v_mul_f32_e32 v135, v47, v140
	v_fma_f32 v120, v120, v88, v104
	v_fma_f32 v121, v121, v89, v105
	v_fma_f32 v122, v122, v90, v106
	v_fma_f32 v123, v123, v91, v107
	v_fma_f32 v124, v124, v92, v108
	v_fma_f32 v125, v125, v93, v109
	v_fma_f32 v126, v126, v94, v110
	v_fma_f32 v127, v127, v95, v111
	v_fma_f32 v128, v128, v96, v112
	v_fma_f32 v129, v129, v97, v113
	v_fma_f32 v130, v130, v98, v114
	v_fma_f32 v131, v131, v99, v115
	v_fma_f32 v132, v132, v100, v116
	v_fma_f32 v133, v133, v101, v117
	v_fma_f32 v134, v134, v102, v118
	v_fma_f32 v135, v135, v103, v119
	v_cvt_pk_bf16_f32 v156, v120, v121
	v_cvt_pk_bf16_f32 v157, v122, v123
	v_cvt_pk_bf16_f32 v158, v124, v125
	v_cvt_pk_bf16_f32 v159, v126, v127
	v_cvt_pk_bf16_f32 v160, v128, v129
	v_cvt_pk_bf16_f32 v161, v130, v131
	v_cvt_pk_bf16_f32 v162, v132, v133
	v_cvt_pk_bf16_f32 v163, v134, v135
	s_lshl_b32 vcc_lo, s19, 11
	s_add_u32 vcc_lo, vcc_lo, 0x3800000
	s_add_u32 s100, s14, vcc_lo
	s_addc_u32 s101, s15, 0
	global_store_dwordx2 v137, v[156:157], s[100:101] offset:0
	global_store_dwordx2 v137, v[158:159], s[100:101] offset:512
	global_store_dwordx2 v137, v[160:161], s[100:101] offset:1024
	global_store_dwordx2 v137, v[162:163], s[100:101] offset:1536
	s_waitcnt vmcnt(24)
; __device__ __forceinline__ float bf2f(u16 h) { return __uint_as_float(((unsigned)h) << 16); }
; __device__ __forceinline__ void row_phase(const Params& P, int glayer, int layer, int xsrc, bool hasY, int gate_idx, const float* gpost,
;                           int xdst, bool doH, const float* gpre, int sh_idx, int nrows) {
;     ...
;         if (hasY) {
;           float4 yv[4];
;           float ss = 0.f;
; #pragma unroll
;           for (int i = 0; i < 4; ++i) {
;             const uint2 raw = yy[u][i];
;             yv[i].x = bf2f((u16)(raw.x & 0xffff)); yv[i].y = bf2f((u16)(raw.x >> 16));
;             yv[i].z = bf2f((u16)(raw.y & 0xffff)); yv[i].w = bf2f((u16)(raw.y >> 16));
;             ss += yv[i].x * yv[i].x + yv[i].y * yv[i].y + yv[i].z * yv[i].z + yv[i].w * yv[i].w;
;           }
;           ss = wave_sum(ss);
;           const float rstd = __builtin_amdgcn_rsqf(ss * (1.f / 1024.f) + EPSF);
; #pragma unroll
;           for (int i = 0; i < 4; ++i) {
;             const int col = (i * 64 + lane) * 4;
;             const float4 gt = *reinterpret_cast<const float4*>(modg + gate_idx * 1024 + col);
;             const float4 gp = *reinterpret_cast<const float4*>(gpost + col);
;             xv[i].x += gt.x * (yv[i].x * rstd * gp.x); xv[i].y += gt.y * (yv[i].y * rstd * gp.y);
;             xv[i].z += gt.z * (yv[i].z * rstd * gp.z); xv[i].w += gt.w * (yv[i].w * rstd * gp.w);
;           }
;         }
;         if (xdst == 3 || (xdst == 1 && row >= N_X)) {
;           float* xout = (xdst == 3) ? P.out + (long)row * 1024 : P.xc + (long)(row - N_X) * 1024;
; #pragma unroll
;           for (int i = 0; i < 4; ++i) *reinterpret_cast<float4*>(xout + (i * 64 + lane) * 4) = xv[i];
;         } else if (xdst != 0) {
;           u16* xo = ((xdst == 1) ? resA : P.zf) + (long)row * 1024;
; #pragma unroll
;           for (int i = 0; i < 4; ++i) {
;             const unsigned b0 = f2bf(xv[i].x), b1 = f2bf(xv[i].y), b2 = f2bf(xv[i].z), b3 = f2bf(xv[i].w);
;             *reinterpret_cast<uint2*>(xo + (i * 64 + lane) * 4) = make_uint2(b0 | (b1 << 16), b2 | (b3 << 16));
	v_lshlrev_b32_e32 v120, 16, v182
	v_and_b32_e32 v121, 0xffff0000, v182
	v_lshlrev_b32_e32 v122, 16, v183
	v_and_b32_e32 v123, 0xffff0000, v183
	v_lshlrev_b32_e32 v124, 16, v184
	v_and_b32_e32 v125, 0xffff0000, v184
	v_lshlrev_b32_e32 v126, 16, v185
	v_and_b32_e32 v127, 0xffff0000, v185
	v_lshlrev_b32_e32 v128, 16, v186
	v_and_b32_e32 v129, 0xffff0000, v186
	v_lshlrev_b32_e32 v130, 16, v187
	v_and_b32_e32 v131, 0xffff0000, v187
	v_lshlrev_b32_e32 v132, 16, v188
	v_and_b32_e32 v133, 0xffff0000, v188
	v_lshlrev_b32_e32 v134, 16, v189
	v_and_b32_e32 v135, 0xffff0000, v189
	v_mul_f32_e32 v138, v120, v120
	v_mul_f32_e32 v149, v121, v121
	v_mul_f32_e32 v150, v122, v122
	v_mul_f32_e32 v154, v123, v123
	v_fma_f32 v138, v124, v124, v138
	v_fma_f32 v149, v125, v125, v149
	v_fma_f32 v150, v126, v126, v150
	v_fma_f32 v154, v127, v127, v154
	v_fma_f32 v138, v128, v128, v138
	v_fma_f32 v149, v129, v129, v149
	v_fma_f32 v150, v130, v130, v150
	v_fma_f32 v154, v131, v131, v154
	v_fma_f32 v138, v132, v132, v138
	v_fma_f32 v149, v133, v133, v149
	v_fma_f32 v150, v134, v134, v150
	v_fma_f32 v154, v135, v135, v154
	v_add_f32_e32 v138, v138, v149
	v_add_f32_e32 v150, v150, v154
	v_add_f32_e32 v138, v138, v150
	s_nop 1
	v_add_f32_dpp v138, v138, v138 quad_perm:[1,0,3,2] row_mask:0xf bank_mask:0xf
	s_nop 1
	v_add_f32_dpp v138, v138, v138 quad_perm:[2,3,0,1] row_mask:0xf bank_mask:0xf
	s_nop 1
	v_add_f32_dpp v138, v138, v138 row_half_mirror row_mask:0xf bank_mask:0xf
	s_nop 1
	v_add_f32_dpp v138, v138, v138 row_mirror row_mask:0xf bank_mask:0xf
	v_mov_b32_e32 v139, v138
	s_nop 1
	v_permlane16_swap_b32_e32 v138, v139
	v_add_f32_e32 v138, v138, v139
	v_mov_b32_e32 v139, v138
	s_nop 1
	v_permlane32_swap_b32_e32 v138, v139
	v_add_f32_e32 v138, v138, v139
	v_mul_f32_e32 v138, 0x3a800000, v138
	v_add_f32_e32 v138, 0x358637bd, v138
	v_rsq_f32_e32 v140, v138
	v_lshlrev_b32_e32 v166, 16, v174
	v_and_b32_e32 v167, 0xffff0000, v174
	v_lshlrev_b32_e32 v168, 16, v175
	v_and_b32_e32 v169, 0xffff0000, v175
	v_lshlrev_b32_e32 v170, 16, v176
	v_and_b32_e32 v171, 0xffff0000, v176
	v_lshlrev_b32_e32 v172, 16, v177
	v_and_b32_e32 v173, 0xffff0000, v177
	v_lshlrev_b32_e32 v174, 16, v178
	v_and_b32_e32 v175, 0xffff0000, v178
	v_lshlrev_b32_e32 v176, 16, v179
	v_and_b32_e32 v177, 0xffff0000, v179
	v_lshlrev_b32_e32 v178, 16, v180
	v_and_b32_e32 v179, 0xffff0000, v180
	v_lshlrev_b32_e32 v180, 16, v181
	v_and_b32_e32 v181, 0xffff0000, v181
	s_nop 0
	v_mul_f32_e32 v120, v120, v140
	v_mul_f32_e32 v121, v121, v140
	v_mul_f32_e32 v122, v122, v140
	v_mul_f32_e32 v123, v123, v140
	v_mul_f32_e32 v124, v124, v140
	v_mul_f32_e32 v125, v125, v140
	v_mul_f32_e32 v126, v126, v140
	v_mul_f32_e32 v127, v127, v140
	v_mul_f32_e32 v128, v128, v140
	v_mul_f32_e32 v129, v129, v140
	v_mul_f32_e32 v130, v130, v140
	v_mul_f32_e32 v131, v131, v140
	v_mul_f32_e32 v132, v132, v140
	v_mul_f32_e32 v133, v133, v140
	v_mul_f32_e32 v134, v134, v140
	v_mul_f32_e32 v135, v135, v140
	v_fma_f32 v166, v120, v72, v166
	v_fma_f32 v167, v121, v73, v167
	v_fma_f32 v168, v122, v74, v168
	v_fma_f32 v169, v123, v75, v169
	v_fma_f32 v170, v124, v76, v170
	v_fma_f32 v171, v125, v77, v171
	v_fma_f32 v172, v126, v78, v172
	v_fma_f32 v173, v127, v79, v173
	v_fma_f32 v174, v128, v80, v174
	v_fma_f32 v175, v129, v81, v175
	v_fma_f32 v176, v130, v82, v176
	v_fma_f32 v177, v131, v83, v177
	v_fma_f32 v178, v132, v84, v178
	v_fma_f32 v179, v133, v85, v179
	v_fma_f32 v180, v134, v86, v180
	v_fma_f32 v181, v135, v87, v181
	v_cvt_pk_bf16_f32 v156, v166, v167
	v_cvt_pk_bf16_f32 v157, v168, v169
	v_cvt_pk_bf16_f32 v158, v170, v171
; __device__ __forceinline__ void row_phase(const Params& P, int glayer, int layer, int xsrc, bool hasY, int gate_idx, const float* gpost,
;                           int xdst, bool doH, const float* gpre, int sh_idx, int nrows) {
;     ...
;         if (xdst == 3 || (xdst == 1 && row >= N_X)) {
;           float* xout = (xdst == 3) ? P.out + (long)row * 1024 : P.xc + (long)(row - N_X) * 1024;
; #pragma unroll
;           for (int i = 0; i < 4; ++i) *reinterpret_cast<float4*>(xout + (i * 64 + lane) * 4) = xv[i];
;         } else if (xdst != 0) {
;           u16* xo = ((xdst == 1) ? resA : P.zf) + (long)row * 1024;
; #pragma unroll
;           for (int i = 0; i < 4; ++i) {
;             const unsigned b0 = f2bf(xv[i].x), b1 = f2bf(xv[i].y), b2 = f2bf(xv[i].z), b3 = f2bf(xv[i].w);
;             *reinterpret_cast<uint2*>(xo + (i * 64 + lane) * 4) = make_uint2(b0 | (b1 << 16), b2 | (b3 << 16));
;           }
;         }
;         if (doH) {
;           float ss = 0.f;
; #pragma unroll
;           for (int i = 0; i < 4; ++i) ss += xv[i].x * xv[i].x + xv[i].y * xv[i].y + xv[i].z * xv[i].z + xv[i].w * xv[i].w;
;           ss = wave_sum(ss);
;           const float rstd = __builtin_amdgcn_rsqf(ss * (1.f / 1024.f) + EPSF);
;           u16* h = P.hy + (long)row * 1024;
; #pragma unroll
;           for (int i = 0; i < 4; ++i) {
;             const int col = (i * 64 + lane) * 4;
;             const float4 g = *reinterpret_cast<const float4*>(gpre + col);
;             const float4 sh = *reinterpret_cast<const float4*>(modp + sh_idx * 1024 + col);
;             const float4 sc = *reinterpret_cast<const float4*>(modp + (sh_idx + 1) * 1024 + col);
;             const unsigned h0 = f2bf(xv[i].x * rstd * g.x * (1.f + sc.x) + sh.x);
;             const unsigned h1 = f2bf(xv[i].y * rstd * g.y * (1.f + sc.y) + sh.y);
;             const unsigned h2 = f2bf(xv[i].z * rstd * g.z * (1.f + sc.z) + sh.z);
;             const unsigned h3 = f2bf(xv[i].w * rstd * g.w * (1.f + sc.w) + sh.w);
;             *reinterpret_cast<uint2*>(h + col) = make_uint2(h0 | (h1 << 16), h2 | (h3 << 16));
;           }
	v_cvt_pk_bf16_f32 v159, v172, v173
	v_cvt_pk_bf16_f32 v160, v174, v175
	v_cvt_pk_bf16_f32 v161, v176, v177
	v_cvt_pk_bf16_f32 v162, v178, v179
	v_cvt_pk_bf16_f32 v163, v180, v181
	s_lshl_b32 vcc_lo, s19, 11
	s_add_u32 vcc_lo, vcc_lo, 0x3c00000
	s_add_u32 s100, s16, vcc_lo
	s_addc_u32 s101, s17, 0
	global_store_dwordx2 v137, v[156:157], s[100:101] offset:0
	global_store_dwordx2 v137, v[158:159], s[100:101] offset:512
	global_store_dwordx2 v137, v[160:161], s[100:101] offset:1024
	global_store_dwordx2 v137, v[162:163], s[100:101] offset:1536
	v_mul_f32_e32 v138, v166, v166
	v_mul_f32_e32 v149, v167, v167
	v_mul_f32_e32 v150, v168, v168
	v_mul_f32_e32 v154, v169, v169
	v_fma_f32 v138, v170, v170, v138
	v_fma_f32 v149, v171, v171, v149
	v_fma_f32 v150, v172, v172, v150
	v_fma_f32 v154, v173, v173, v154
	v_fma_f32 v138, v174, v174, v138
	v_fma_f32 v149, v175, v175, v149
	v_fma_f32 v150, v176, v176, v150
	v_fma_f32 v154, v177, v177, v154
	v_fma_f32 v138, v178, v178, v138
	v_fma_f32 v149, v179, v179, v149
	v_fma_f32 v150, v180, v180, v150
	v_fma_f32 v154, v181, v181, v154
	v_add_f32_e32 v138, v138, v149
	v_add_f32_e32 v150, v150, v154
	v_add_f32_e32 v138, v138, v150
	s_nop 1
	v_add_f32_dpp v138, v138, v138 quad_perm:[1,0,3,2] row_mask:0xf bank_mask:0xf
	s_nop 1
	v_add_f32_dpp v138, v138, v138 quad_perm:[2,3,0,1] row_mask:0xf bank_mask:0xf
	s_nop 1
	v_add_f32_dpp v138, v138, v138 row_half_mirror row_mask:0xf bank_mask:0xf
	s_nop 1
	v_add_f32_dpp v138, v138, v138 row_mirror row_mask:0xf bank_mask:0xf
	v_mov_b32_e32 v139, v138
	s_nop 1
	v_permlane16_swap_b32_e32 v138, v139
	v_add_f32_e32 v138, v138, v139
	v_mov_b32_e32 v139, v138
	s_nop 1
	v_permlane32_swap_b32_e32 v138, v139
	v_add_f32_e32 v138, v138, v139
	v_mul_f32_e32 v138, 0x3a800000, v138
	v_add_f32_e32 v138, 0x358637bd, v138
	v_rsq_f32_e32 v140, v138
	s_nop 0
	v_mul_f32_e32 v120, v166, v140
	v_mul_f32_e32 v121, v167, v140
	v_mul_f32_e32 v122, v168, v140
	v_mul_f32_e32 v123, v169, v140
	v_mul_f32_e32 v124, v170, v140
	v_mul_f32_e32 v125, v171, v140
	v_mul_f32_e32 v126, v172, v140
	v_mul_f32_e32 v127, v173, v140
	v_mul_f32_e32 v128, v174, v140
	v_mul_f32_e32 v129, v175, v140
	v_mul_f32_e32 v130, v176, v140
	v_mul_f32_e32 v131, v177, v140
	v_mul_f32_e32 v132, v178, v140
	v_mul_f32_e32 v133, v179, v140
	v_mul_f32_e32 v134, v180, v140
	v_mul_f32_e32 v135, v181, v140
	v_fma_f32 v120, v120, v88, v104
	v_fma_f32 v121, v121, v89, v105
	v_fma_f32 v122, v122, v90, v106
	v_fma_f32 v123, v123, v91, v107
	v_fma_f32 v124, v124, v92, v108
	v_fma_f32 v125, v125, v93, v109
	v_fma_f32 v126, v126, v94, v110
	v_fma_f32 v127, v127, v95, v111
	v_fma_f32 v128, v128, v96, v112
	v_fma_f32 v129, v129, v97, v113
	v_fma_f32 v130, v130, v98, v114
	v_fma_f32 v131, v131, v99, v115
	v_fma_f32 v132, v132, v100, v116
	v_fma_f32 v133, v133, v101, v117
	v_fma_f32 v134, v134, v102, v118
	v_fma_f32 v135, v135, v103, v119
	v_cvt_pk_bf16_f32 v156, v120, v121
	v_cvt_pk_bf16_f32 v157, v122, v123
	v_cvt_pk_bf16_f32 v158, v124, v125
	v_cvt_pk_bf16_f32 v159, v126, v127
	v_cvt_pk_bf16_f32 v160, v128, v129
	v_cvt_pk_bf16_f32 v161, v130, v131
	v_cvt_pk_bf16_f32 v162, v132, v133
	v_cvt_pk_bf16_f32 v163, v134, v135
	s_lshl_b32 vcc_lo, s19, 11
	s_add_u32 vcc_lo, vcc_lo, 0x3c00000
	s_add_u32 s100, s14, vcc_lo
	s_addc_u32 s101, s15, 0
	global_store_dwordx2 v137, v[156:157], s[100:101] offset:0
	global_store_dwordx2 v137, v[158:159], s[100:101] offset:512
	global_store_dwordx2 v137, v[160:161], s[100:101] offset:1024
	global_store_dwordx2 v137, v[162:163], s[100:101] offset:1536
	s_branch .LBB0_1678

; __device__ __forceinline__ void row_phase(const Params& P, int glayer, int layer, int xsrc, bool hasY, int gate_idx, const float* gpost,
;                           int xdst, bool doH, const float* gpre, int sh_idx, int nrows) {
;     ...
;       const int R = rb + u * stride;
;       if (R < nrows) {
;         if (xsrc != 0 && R < N_X) {
;           const u16* xs_ = ((xsrc == 1) ? resA : P.zf) + (long)R * 1024;
; #pragma unroll
;           for (int i = 0; i < 4; ++i) {
;             const uint2 t2 = *reinterpret_cast<const uint2*>(xs_ + (i * 64 + lane) * 4);
;             xr[u][i].x = t2.x; xr[u][i].y = t2.y;
;           }
;         } else {
;           const float* xin_;
;           if (xsrc == 0) xin_ = R < N_X ? P.x + (long)R * 1024 : P.ctx + (long)(R - N_X) * 1024;
;           else           xin_ = P.xc + (long)(R - N_X) * 1024;
; #pragma unroll
;           for (int i = 0; i < 4; ++i) xr[u][i] = *reinterpret_cast<const uint4*>(xin_ + (i * 64 + lane) * 4);
;         }
;         if (hasY) {
;           const u16* y_ = P.hy + (long)R * 1024;
; #pragma unroll
;           for (int i = 0; i < 4; ++i) yy[u][i] = *reinterpret_cast<const uint2*>(y_ + (i * 64 + lane) * 4);
;         }
;       }
;     }
; #pragma unroll
;     for (int u = 0; u < 4; ++u) {
;       const int row = rb + u * stride;
;       if (row < nrows) {
;         const int mi = row < N_X ? (row >> 13) : 4;
;         const float* modp = P.mod + (long)(layer * 5 + mi) * 6144;
;         const float* modg = P.mod + (long)(glayer * 5 + mi) * 6144;
;         float4 xv[4];
;         if (xsrc != 0 && row < N_X) {
; #pragma unroll
;           for (int i = 0; i < 4; ++i) {
;             const uint4 raw = xr[u][i];
;             xv[i].x = bf2f((u16)(raw.x & 0xffff)); xv[i].y = bf2f((u16)(raw.x >> 16));
;             xv[i].z = bf2f((u16)(raw.y & 0xffff)); xv[i].w = bf2f((u16)(raw.y >> 16));
;           }
;         } else {
; #pragma unroll
;           for (int i = 0; i < 4; ++i) {
;             xv[i].x = __uint_as_float(xr[u][i].x); xv[i].y = __uint_as_float(xr[u][i].y);
;             xv[i].z = __uint_as_float(xr[u][i].z); xv[i].w = __uint_as_float(xr[u][i].w);
;           }
;         }
;         if (hasY) {
;           float4 yv[4];
;           float ss = 0.f;
; #pragma unroll
;           for (int i = 0; i < 4; ++i) {
;             const uint2 raw = yy[u][i];
.LBB0_1946:
	s_cmp_gt_i32 s34, 17
	s_cselect_b64 s[0:1], -1, 0
	s_cmp_lt_i32 s35, 18
	s_cselect_b64 s[4:5], -1, 0
	s_or_b64 s[0:1], s[0:1], s[4:5]
	s_and_b64 vcc, exec, s[0:1]
	s_cbranch_vccnz .LBB0_2016
	s_waitcnt vmcnt(16)
	v_lshl_add_u32 v0, s2, 3, v204
	s_mov_b32 s18, 0x8000
	v_cmp_gt_i32_e32 vcc, s18, v0
	s_and_saveexec_b64 s[0:1], vcc
	s_cbranch_execz .LBB0_1962
	v_readlane_b32 s4, v252, 0
	v_readlane_b32 s5, v252, 1
	v_readfirstlane_b32 s19, v204
	s_nop 3
	s_sub_u32 s4, s4, 0x170
	s_subb_u32 s5, s5, 0
	s_load_dwordx2 s[12:13], s[4:5], 0x150
	s_load_dwordx2 s[14:15], s[4:5], 0x140
	s_load_dwordx2 s[16:17], s[4:5], 0xc8
	s_load_dwordx2 s[20:21], s[4:5], 0x100
	s_lshl_b32 s98, s2, 3
	s_add_u32 s19, s98, s19
	v_and_b32_e32 v136, 63, v152
	v_lshlrev_b32_e32 v137, 3, v136
	v_lshlrev_b32_e32 v136, 4, v136
	s_waitcnt lgkmcnt(0)
	s_lshl_b32 vcc_lo, s19, 11
	s_add_u32 s100, s12, vcc_lo
	s_addc_u32 s101, s13, 0
	global_load_dwordx2 v[8:9], v137, s[100:101] offset:0
	global_load_dwordx2 v[10:11], v137, s[100:101] offset:512
	global_load_dwordx2 v[12:13], v137, s[100:101] offset:1024
	global_load_dwordx2 v[14:15], v137, s[100:101] offset:1536
	s_lshl_b32 vcc_lo, s19, 11
	s_add_u32 s100, s14, vcc_lo
	s_addc_u32 s101, s15, 0
	global_load_dwordx2 v[48:49], v137, s[100:101] offset:0
	global_load_dwordx2 v[50:51], v137, s[100:101] offset:512
	global_load_dwordx2 v[52:53], v137, s[100:101] offset:1024
	global_load_dwordx2 v[54:55], v137, s[100:101] offset:1536
	s_lshl_b32 vcc_lo, s19, 11
	s_add_u32 vcc_lo, vcc_lo, 0x400000
	s_add_u32 s100, s12, vcc_lo
	s_addc_u32 s101, s13, 0
	global_load_dwordx2 v[24:25], v137, s[100:101] offset:0
	global_load_dwordx2 v[26:27], v137, s[100:101] offset:512
	global_load_dwordx2 v[28:29], v137, s[100:101] offset:1024
	global_load_dwordx2 v[30:31], v137, s[100:101] offset:1536
	s_lshl_b32 vcc_lo, s19, 11
	s_add_u32 vcc_lo, vcc_lo, 0x400000
	s_add_u32 s100, s14, vcc_lo
	s_addc_u32 s101, s15, 0
	global_load_dwordx2 v[56:57], v137, s[100:101] offset:0
	global_load_dwordx2 v[58:59], v137, s[100:101] offset:512
	global_load_dwordx2 v[60:61], v137, s[100:101] offset:1024
	global_load_dwordx2 v[62:63], v137, s[100:101] offset:1536
	s_lshl_b32 vcc_lo, s19, 11
	s_add_u32 vcc_lo, vcc_lo, 0x800000
	s_add_u32 s100, s12, vcc_lo
	s_addc_u32 s101, s13, 0
	global_load_dwordx2 v[40:41], v137, s[100:101] offset:0
	global_load_dwordx2 v[42:43], v137, s[100:101] offset:512
	global_load_dwordx2 v[44:45], v137, s[100:101] offset:1024
	global_load_dwordx2 v[46:47], v137, s[100:101] offset:1536
	s_lshl_b32 vcc_lo, s19, 11
	s_add_u32 vcc_lo, vcc_lo, 0x800000
	s_add_u32 s100, s14, vcc_lo
	s_addc_u32 s101, s15, 0
	global_load_dwordx2 v[64:65], v137, s[100:101] offset:0
	global_load_dwordx2 v[66:67], v137, s[100:101] offset:512
	global_load_dwordx2 v[68:69], v137, s[100:101] offset:1024
	global_load_dwordx2 v[70:71], v137, s[100:101] offset:1536
	s_add_u32 s100, s20, 0x23000
	s_addc_u32 s101, s21, 0
	global_load_dwordx4 v[72:75], v136, s[100:101] offset:0
	global_load_dwordx4 v[76:79], v136, s[100:101] offset:1024
	global_load_dwordx4 v[80:83], v136, s[100:101] offset:2048
	global_load_dwordx4 v[84:87], v136, s[100:101] offset:3072
	s_load_dwordx2 s[98:99], s[4:5], 0x48
	s_waitcnt lgkmcnt(0)
	s_add_u32 s98, s98, 0x1000
	s_addc_u32 s99, s99, 0
	global_load_dwordx4 v[120:123], v136, s[98:99] offset:0
	global_load_dwordx4 v[124:127], v136, s[98:99] offset:1024
	global_load_dwordx4 v[128:131], v136, s[98:99] offset:2048
	global_load_dwordx4 v[132:135], v136, s[98:99] offset:3072
	s_waitcnt vmcnt(0)
	v_mul_f32_e32 v72, v72, v120
	v_mul_f32_e32 v73, v73, v121
	v_mul_f32_e32 v74, v74, v122
	v_mul_f32_e32 v75, v75, v123
	v_mul_f32_e32 v76, v76, v124
	v_mul_f32_e32 v77, v77, v125
	v_mul_f32_e32 v78, v78, v126
	v_mul_f32_e32 v79, v79, v127
	v_mul_f32_e32 v80, v80, v128
	v_mul_f32_e32 v81, v81, v129
	v_mul_f32_e32 v82, v82, v130
	v_mul_f32_e32 v83, v83, v131
	v_mul_f32_e32 v84, v84, v132
	v_mul_f32_e32 v85, v85, v133
	v_mul_f32_e32 v86, v86, v134
	v_mul_f32_e32 v87, v87, v135
	s_lshl_b32 vcc_lo, s19, 11
	s_add_u32 vcc_lo, vcc_lo, 0xc00000
	s_add_u32 s100, s12, vcc_lo
	s_addc_u32 s101, s13, 0
	global_load_dwordx2 v[174:175], v137, s[100:101] offset:0
	global_load_dwordx2 v[176:177], v137, s[100:101] offset:512
	global_load_dwordx2 v[178:179], v137, s[100:101] offset:1024
	global_load_dwordx2 v[180:181], v137, s[100:101] offset:1536
	s_lshl_b32 vcc_lo, s19, 11
	s_add_u32 vcc_lo, vcc_lo, 0xc00000
	s_add_u32 s100, s14, vcc_lo
	s_addc_u32 s101, s15, 0
	global_load_dwordx2 v[182:183], v137, s[100:101] offset:0
	global_load_dwordx2 v[184:185], v137, s[100:101] offset:512
	global_load_dwordx2 v[186:187], v137, s[100:101] offset:1024
	global_load_dwordx2 v[188:189], v137, s[100:101] offset:1536
	v_lshlrev_b32_e32 v120, 16, v48
	v_and_b32_e32 v121, 0xffff0000, v48
	v_lshlrev_b32_e32 v122, 16, v49
	v_and_b32_e32 v123, 0xffff0000, v49
	v_lshlrev_b32_e32 v124, 16, v50
	v_and_b32_e32 v125, 0xffff0000, v50
	v_lshlrev_b32_e32 v126, 16, v51
	v_and_b32_e32 v127, 0xffff0000, v51
	v_lshlrev_b32_e32 v128, 16, v52
	v_and_b32_e32 v129, 0xffff0000, v52
	v_lshlrev_b32_e32 v130, 16, v53
	v_and_b32_e32 v131, 0xffff0000, v53
	v_lshlrev_b32_e32 v132, 16, v54
	v_and_b32_e32 v133, 0xffff0000, v54
	v_lshlrev_b32_e32 v134, 16, v55
	v_and_b32_e32 v135, 0xffff0000, v55
	v_mul_f32_e32 v138, v120, v120
	v_mul_f32_e32 v149, v121, v121
	v_mul_f32_e32 v150, v122, v122
	v_mul_f32_e32 v154, v123, v123
	v_fma_f32 v138, v124, v124, v138
	v_fma_f32 v149, v125, v125, v149
	v_fma_f32 v150, v126, v126, v150
	v_fma_f32 v154, v127, v127, v154
	v_fma_f32 v138, v128, v128, v138
	v_fma_f32 v149, v129, v129, v149
; __device__ __forceinline__ float bf2f(u16 h) { return __uint_as_float(((unsigned)h) << 16); }
; __device__ __forceinline__ void row_phase(const Params& P, int glayer, int layer, int xsrc, bool hasY, int gate_idx, const float* gpost,
;                           int xdst, bool doH, const float* gpre, int sh_idx, int nrows) {
;     ...
;         if (hasY) {
;           float4 yv[4];
;           float ss = 0.f;
; #pragma unroll
;           for (int i = 0; i < 4; ++i) {
;             const uint2 raw = yy[u][i];
;             yv[i].x = bf2f((u16)(raw.x & 0xffff)); yv[i].y = bf2f((u16)(raw.x >> 16));
;             yv[i].z = bf2f((u16)(raw.y & 0xffff)); yv[i].w = bf2f((u16)(raw.y >> 16));
;             ss += yv[i].x * yv[i].x + yv[i].y * yv[i].y + yv[i].z * yv[i].z + yv[i].w * yv[i].w;
;           }
;           ss = wave_sum(ss);
;           const float rstd = __builtin_amdgcn_rsqf(ss * (1.f / 1024.f) + EPSF);
; #pragma unroll
;           for (int i = 0; i < 4; ++i) {
;             const int col = (i * 64 + lane) * 4;
;             const float4 gt = *reinterpret_cast<const float4*>(modg + gate_idx * 1024 + col);
;             const float4 gp = *reinterpret_cast<const float4*>(gpost + col);
;             xv[i].x += gt.x * (yv[i].x * rstd * gp.x); xv[i].y += gt.y * (yv[i].y * rstd * gp.y);
;             xv[i].z += gt.z * (yv[i].z * rstd * gp.z); xv[i].w += gt.w * (yv[i].w * rstd * gp.w);
;           }
;         }
;         if (xdst == 3 || (xdst == 1 && row >= N_X)) {
;           float* xout = (xdst == 3) ? P.out + (long)row * 1024 : P.xc + (long)(row - N_X) * 1024;
; #pragma unroll
;           for (int i = 0; i < 4; ++i) *reinterpret_cast<float4*>(xout + (i * 64 + lane) * 4) = xv[i];
	v_fma_f32 v150, v130, v130, v150
	v_fma_f32 v154, v131, v131, v154
	v_fma_f32 v138, v132, v132, v138
	v_fma_f32 v149, v133, v133, v149
	v_fma_f32 v150, v134, v134, v150
	v_fma_f32 v154, v135, v135, v154
	v_add_f32_e32 v138, v138, v149
	v_add_f32_e32 v150, v150, v154
	v_add_f32_e32 v138, v138, v150
	s_nop 1
	v_add_f32_dpp v138, v138, v138 quad_perm:[1,0,3,2] row_mask:0xf bank_mask:0xf
	s_nop 1
	v_add_f32_dpp v138, v138, v138 quad_perm:[2,3,0,1] row_mask:0xf bank_mask:0xf
	s_nop 1
	v_add_f32_dpp v138, v138, v138 row_half_mirror row_mask:0xf bank_mask:0xf
	s_nop 1
	v_add_f32_dpp v138, v138, v138 row_mirror row_mask:0xf bank_mask:0xf
	v_mov_b32_e32 v139, v138
	s_nop 1
	v_permlane16_swap_b32_e32 v138, v139
	v_add_f32_e32 v138, v138, v139
	v_mov_b32_e32 v139, v138
	s_nop 1
	v_permlane32_swap_b32_e32 v138, v139
	v_add_f32_e32 v138, v138, v139
	v_mul_f32_e32 v138, 0x3a800000, v138
	v_add_f32_e32 v138, 0x358637bd, v138
	v_rsq_f32_e32 v140, v138
	v_lshlrev_b32_e32 v0, 16, v8
	v_and_b32_e32 v1, 0xffff0000, v8
	v_lshlrev_b32_e32 v2, 16, v9
	v_and_b32_e32 v3, 0xffff0000, v9
	v_lshlrev_b32_e32 v4, 16, v10
	v_and_b32_e32 v5, 0xffff0000, v10
	v_lshlrev_b32_e32 v6, 16, v11
	v_and_b32_e32 v7, 0xffff0000, v11
	v_lshlrev_b32_e32 v8, 16, v12
	v_and_b32_e32 v9, 0xffff0000, v12
	v_lshlrev_b32_e32 v10, 16, v13
	v_and_b32_e32 v11, 0xffff0000, v13
	v_lshlrev_b32_e32 v12, 16, v14
	v_and_b32_e32 v13, 0xffff0000, v14
	v_lshlrev_b32_e32 v14, 16, v15
	v_and_b32_e32 v15, 0xffff0000, v15
	s_nop 0
	v_mul_f32_e32 v120, v120, v140
	v_mul_f32_e32 v121, v121, v140
	v_mul_f32_e32 v122, v122, v140
	v_mul_f32_e32 v123, v123, v140
	v_mul_f32_e32 v124, v124, v140
	v_mul_f32_e32 v125, v125, v140
	v_mul_f32_e32 v126, v126, v140
	v_mul_f32_e32 v127, v127, v140
	v_mul_f32_e32 v128, v128, v140
	v_mul_f32_e32 v129, v129, v140
	v_mul_f32_e32 v130, v130, v140
	v_mul_f32_e32 v131, v131, v140
	v_mul_f32_e32 v132, v132, v140
	v_mul_f32_e32 v133, v133, v140
	v_mul_f32_e32 v134, v134, v140
	v_mul_f32_e32 v135, v135, v140
	v_fma_f32 v0, v120, v72, v0
	v_fma_f32 v1, v121, v73, v1
	v_fma_f32 v2, v122, v74, v2
	v_fma_f32 v3, v123, v75, v3
	v_fma_f32 v4, v124, v76, v4
	v_fma_f32 v5, v125, v77, v5
	v_fma_f32 v6, v126, v78, v6
	v_fma_f32 v7, v127, v79, v7
	v_fma_f32 v8, v128, v80, v8
	v_fma_f32 v9, v129, v81, v9
	v_fma_f32 v10, v130, v82, v10
	v_fma_f32 v11, v131, v83, v11
	v_fma_f32 v12, v132, v84, v12
	v_fma_f32 v13, v133, v85, v13
	v_fma_f32 v14, v134, v86, v14
	v_fma_f32 v15, v135, v87, v15
	s_lshl_b32 vcc_lo, s19, 12
	s_add_u32 s100, s16, vcc_lo
	s_addc_u32 s101, s17, 0
	global_store_dwordx4 v136, v[0:3], s[100:101] offset:0
	global_store_dwordx4 v136, v[4:7], s[100:101] offset:1024
	global_store_dwordx4 v136, v[8:11], s[100:101] offset:2048
	global_store_dwordx4 v136, v[12:15], s[100:101] offset:3072
	s_lshl_b32 vcc_lo, s19, 11
	s_add_u32 vcc_lo, vcc_lo, 0x1000000
	s_add_u32 s100, s12, vcc_lo
	s_addc_u32 s101, s13, 0
	global_load_dwordx2 v[8:9], v137, s[100:101] offset:0
	global_load_dwordx2 v[10:11], v137, s[100:101] offset:512
	global_load_dwordx2 v[12:13], v137, s[100:101] offset:1024
	global_load_dwordx2 v[14:15], v137, s[100:101] offset:1536
	s_lshl_b32 vcc_lo, s19, 11
	s_add_u32 vcc_lo, vcc_lo, 0x1000000
	s_add_u32 s100, s14, vcc_lo
	s_addc_u32 s101, s15, 0
	global_load_dwordx2 v[48:49], v137, s[100:101] offset:0
	global_load_dwordx2 v[50:51], v137, s[100:101] offset:512
	global_load_dwordx2 v[52:53], v137, s[100:101] offset:1024
	global_load_dwordx2 v[54:55], v137, s[100:101] offset:1536
	v_lshlrev_b32_e32 v120, 16, v56
	v_and_b32_e32 v121, 0xffff0000, v56
	v_lshlrev_b32_e32 v122, 16, v57
	v_and_b32_e32 v123, 0xffff0000, v57
	v_lshlrev_b32_e32 v124, 16, v58
	v_and_b32_e32 v125, 0xffff0000, v58
	v_lshlrev_b32_e32 v126, 16, v59
	v_and_b32_e32 v127, 0xffff0000, v59
	v_lshlrev_b32_e32 v128, 16, v60
	v_and_b32_e32 v129, 0xffff0000, v60
	v_lshlrev_b32_e32 v130, 16, v61
	v_and_b32_e32 v131, 0xffff0000, v61
	v_lshlrev_b32_e32 v132, 16, v62
	v_and_b32_e32 v133, 0xffff0000, v62
	v_lshlrev_b32_e32 v134, 16, v63
	v_and_b32_e32 v135, 0xffff0000, v63
	v_mul_f32_e32 v138, v120, v120
	v_mul_f32_e32 v149, v121, v121
	v_mul_f32_e32 v150, v122, v122
	v_mul_f32_e32 v154, v123, v123
	v_fma_f32 v138, v124, v124, v138
	v_fma_f32 v149, v125, v125, v149
	v_fma_f32 v150, v126, v126, v150
	v_fma_f32 v154, v127, v127, v154
	v_fma_f32 v138, v128, v128, v138
	v_fma_f32 v149, v129, v129, v149
	v_fma_f32 v150, v130, v130, v150
	v_fma_f32 v154, v131, v131, v154
	v_fma_f32 v138, v132, v132, v138
	v_fma_f32 v149, v133, v133, v149
	v_fma_f32 v150, v134, v134, v150
	v_fma_f32 v154, v135, v135, v154
	v_add_f32_e32 v138, v138, v149
	v_add_f32_e32 v150, v150, v154
	v_add_f32_e32 v138, v138, v150
	s_nop 1
	v_add_f32_dpp v138, v138, v138 quad_perm:[1,0,3,2] row_mask:0xf bank_mask:0xf
	s_nop 1
	v_add_f32_dpp v138, v138, v138 quad_perm:[2,3,0,1] row_mask:0xf bank_mask:0xf
	s_nop 1
	v_add_f32_dpp v138, v138, v138 row_half_mirror row_mask:0xf bank_mask:0xf
	s_nop 1
	v_add_f32_dpp v138, v138, v138 row_mirror row_mask:0xf bank_mask:0xf
	v_mov_b32_e32 v139, v138
	s_nop 1
	v_permlane16_swap_b32_e32 v138, v139
	v_add_f32_e32 v138, v138, v139
	v_mov_b32_e32 v139, v138
	s_nop 1
	v_permlane32_swap_b32_e32 v138, v139
	v_add_f32_e32 v138, v138, v139
	v_mul_f32_e32 v138, 0x3a800000, v138
	v_add_f32_e32 v138, 0x358637bd, v138
	v_rsq_f32_e32 v140, v138
	v_lshlrev_b32_e32 v16, 16, v24
	v_and_b32_e32 v17, 0xffff0000, v24
	v_lshlrev_b32_e32 v18, 16, v25
	v_and_b32_e32 v19, 0xffff0000, v25
	v_lshlrev_b32_e32 v20, 16, v26
	v_and_b32_e32 v21, 0xffff0000, v26
	v_lshlrev_b32_e32 v22, 16, v27
	v_and_b32_e32 v23, 0xffff0000, v27
	v_lshlrev_b32_e32 v24, 16, v28
; __device__ __forceinline__ float bf2f(u16 h) { return __uint_as_float(((unsigned)h) << 16); }
; __device__ __forceinline__ void row_phase(const Params& P, int glayer, int layer, int xsrc, bool hasY, int gate_idx, const float* gpost,
;                           int xdst, bool doH, const float* gpre, int sh_idx, int nrows) {
;     ...
;         if (hasY) {
;           float4 yv[4];
;           float ss = 0.f;
; #pragma unroll
;           for (int i = 0; i < 4; ++i) {
;             const uint2 raw = yy[u][i];
;             yv[i].x = bf2f((u16)(raw.x & 0xffff)); yv[i].y = bf2f((u16)(raw.x >> 16));
;             yv[i].z = bf2f((u16)(raw.y & 0xffff)); yv[i].w = bf2f((u16)(raw.y >> 16));
;             ss += yv[i].x * yv[i].x + yv[i].y * yv[i].y + yv[i].z * yv[i].z + yv[i].w * yv[i].w;
;           }
;           ss = wave_sum(ss);
;           const float rstd = __builtin_amdgcn_rsqf(ss * (1.f / 1024.f) + EPSF);
; #pragma unroll
;           for (int i = 0; i < 4; ++i) {
;             const int col = (i * 64 + lane) * 4;
;             const float4 gt = *reinterpret_cast<const float4*>(modg + gate_idx * 1024 + col);
;             const float4 gp = *reinterpret_cast<const float4*>(gpost + col);
;             xv[i].x += gt.x * (yv[i].x * rstd * gp.x); xv[i].y += gt.y * (yv[i].y * rstd * gp.y);
;             xv[i].z += gt.z * (yv[i].z * rstd * gp.z); xv[i].w += gt.w * (yv[i].w * rstd * gp.w);
;           }
;         }
;         if (xdst == 3 || (xdst == 1 && row >= N_X)) {
;           float* xout = (xdst == 3) ? P.out + (long)row * 1024 : P.xc + (long)(row - N_X) * 1024;
; #pragma unroll
;           for (int i = 0; i < 4; ++i) *reinterpret_cast<float4*>(xout + (i * 64 + lane) * 4) = xv[i];
	v_and_b32_e32 v25, 0xffff0000, v28
	v_lshlrev_b32_e32 v26, 16, v29
	v_and_b32_e32 v27, 0xffff0000, v29
	v_lshlrev_b32_e32 v28, 16, v30
	v_and_b32_e32 v29, 0xffff0000, v30
	v_lshlrev_b32_e32 v30, 16, v31
	v_and_b32_e32 v31, 0xffff0000, v31
	s_nop 0
	v_mul_f32_e32 v120, v120, v140
	v_mul_f32_e32 v121, v121, v140
	v_mul_f32_e32 v122, v122, v140
	v_mul_f32_e32 v123, v123, v140
	v_mul_f32_e32 v124, v124, v140
	v_mul_f32_e32 v125, v125, v140
	v_mul_f32_e32 v126, v126, v140
	v_mul_f32_e32 v127, v127, v140
	v_mul_f32_e32 v128, v128, v140
	v_mul_f32_e32 v129, v129, v140
	v_mul_f32_e32 v130, v130, v140
	v_mul_f32_e32 v131, v131, v140
	v_mul_f32_e32 v132, v132, v140
	v_mul_f32_e32 v133, v133, v140
	v_mul_f32_e32 v134, v134, v140
	v_mul_f32_e32 v135, v135, v140
	v_fma_f32 v16, v120, v72, v16
	v_fma_f32 v17, v121, v73, v17
	v_fma_f32 v18, v122, v74, v18
	v_fma_f32 v19, v123, v75, v19
	v_fma_f32 v20, v124, v76, v20
	v_fma_f32 v21, v125, v77, v21
	v_fma_f32 v22, v126, v78, v22
	v_fma_f32 v23, v127, v79, v23
	v_fma_f32 v24, v128, v80, v24
	v_fma_f32 v25, v129, v81, v25
	v_fma_f32 v26, v130, v82, v26
	v_fma_f32 v27, v131, v83, v27
	v_fma_f32 v28, v132, v84, v28
	v_fma_f32 v29, v133, v85, v29
	v_fma_f32 v30, v134, v86, v30
	v_fma_f32 v31, v135, v87, v31
	s_lshl_b32 vcc_lo, s19, 12
	s_add_u32 vcc_lo, vcc_lo, 0x800000
	s_add_u32 s100, s16, vcc_lo
	s_addc_u32 s101, s17, 0
	global_store_dwordx4 v136, v[16:19], s[100:101] offset:0
	global_store_dwordx4 v136, v[20:23], s[100:101] offset:1024
	global_store_dwordx4 v136, v[24:27], s[100:101] offset:2048
	global_store_dwordx4 v136, v[28:31], s[100:101] offset:3072
	s_lshl_b32 vcc_lo, s19, 11
	s_add_u32 vcc_lo, vcc_lo, 0x1400000
	s_add_u32 s100, s12, vcc_lo
	s_addc_u32 s101, s13, 0
	global_load_dwordx2 v[24:25], v137, s[100:101] offset:0
	global_load_dwordx2 v[26:27], v137, s[100:101] offset:512
	global_load_dwordx2 v[28:29], v137, s[100:101] offset:1024
	global_load_dwordx2 v[30:31], v137, s[100:101] offset:1536
	s_lshl_b32 vcc_lo, s19, 11
	s_add_u32 vcc_lo, vcc_lo, 0x1400000
	s_add_u32 s100, s14, vcc_lo
	s_addc_u32 s101, s15, 0
	global_load_dwordx2 v[56:57], v137, s[100:101] offset:0
	global_load_dwordx2 v[58:59], v137, s[100:101] offset:512
	global_load_dwordx2 v[60:61], v137, s[100:101] offset:1024
	global_load_dwordx2 v[62:63], v137, s[100:101] offset:1536
	v_lshlrev_b32_e32 v120, 16, v64
	v_and_b32_e32 v121, 0xffff0000, v64
	v_lshlrev_b32_e32 v122, 16, v65
	v_and_b32_e32 v123, 0xffff0000, v65
	v_lshlrev_b32_e32 v124, 16, v66
	v_and_b32_e32 v125, 0xffff0000, v66
	v_lshlrev_b32_e32 v126, 16, v67
	v_and_b32_e32 v127, 0xffff0000, v67
	v_lshlrev_b32_e32 v128, 16, v68
	v_and_b32_e32 v129, 0xffff0000, v68
	v_lshlrev_b32_e32 v130, 16, v69
	v_and_b32_e32 v131, 0xffff0000, v69
	v_lshlrev_b32_e32 v132, 16, v70
	v_and_b32_e32 v133, 0xffff0000, v70
	v_lshlrev_b32_e32 v134, 16, v71
	v_and_b32_e32 v135, 0xffff0000, v71
	v_mul_f32_e32 v138, v120, v120
	v_mul_f32_e32 v149, v121, v121
	v_mul_f32_e32 v150, v122, v122
	v_mul_f32_e32 v154, v123, v123
	v_fma_f32 v138, v124, v124, v138
	v_fma_f32 v149, v125, v125, v149
	v_fma_f32 v150, v126, v126, v150
	v_fma_f32 v154, v127, v127, v154
	v_fma_f32 v138, v128, v128, v138
	v_fma_f32 v149, v129, v129, v149
	v_fma_f32 v150, v130, v130, v150
	v_fma_f32 v154, v131, v131, v154
	v_fma_f32 v138, v132, v132, v138
	v_fma_f32 v149, v133, v133, v149
	v_fma_f32 v150, v134, v134, v150
	v_fma_f32 v154, v135, v135, v154
	v_add_f32_e32 v138, v138, v149
	v_add_f32_e32 v150, v150, v154
	v_add_f32_e32 v138, v138, v150
	s_nop 1
	v_add_f32_dpp v138, v138, v138 quad_perm:[1,0,3,2] row_mask:0xf bank_mask:0xf
	s_nop 1
	v_add_f32_dpp v138, v138, v138 quad_perm:[2,3,0,1] row_mask:0xf bank_mask:0xf
	s_nop 1
	v_add_f32_dpp v138, v138, v138 row_half_mirror row_mask:0xf bank_mask:0xf
	s_nop 1
	v_add_f32_dpp v138, v138, v138 row_mirror row_mask:0xf bank_mask:0xf
	v_mov_b32_e32 v139, v138
	s_nop 1
	v_permlane16_swap_b32_e32 v138, v139
	v_add_f32_e32 v138, v138, v139
	v_mov_b32_e32 v139, v138
	s_nop 1
	v_permlane32_swap_b32_e32 v138, v139
	v_add_f32_e32 v138, v138, v139
	v_mul_f32_e32 v138, 0x3a800000, v138
	v_add_f32_e32 v138, 0x358637bd, v138
	v_rsq_f32_e32 v140, v138
	v_lshlrev_b32_e32 v32, 16, v40
	v_and_b32_e32 v33, 0xffff0000, v40
	v_lshlrev_b32_e32 v34, 16, v41
	v_and_b32_e32 v35, 0xffff0000, v41
	v_lshlrev_b32_e32 v36, 16, v42
	v_and_b32_e32 v37, 0xffff0000, v42
	v_lshlrev_b32_e32 v38, 16, v43
	v_and_b32_e32 v39, 0xffff0000, v43
	v_lshlrev_b32_e32 v40, 16, v44
	v_and_b32_e32 v41, 0xffff0000, v44
	v_lshlrev_b32_e32 v42, 16, v45
	v_and_b32_e32 v43, 0xffff0000, v45
	v_lshlrev_b32_e32 v44, 16, v46
	v_and_b32_e32 v45, 0xffff0000, v46
	v_lshlrev_b32_e32 v46, 16, v47
	v_and_b32_e32 v47, 0xffff0000, v47
	s_nop 0
	v_mul_f32_e32 v120, v120, v140
	v_mul_f32_e32 v121, v121, v140
	v_mul_f32_e32 v122, v122, v140
	v_mul_f32_e32 v123, v123, v140
	v_mul_f32_e32 v124, v124, v140
	v_mul_f32_e32 v125, v125, v140
	v_mul_f32_e32 v126, v126, v140
	v_mul_f32_e32 v127, v127, v140
	v_mul_f32_e32 v128, v128, v140
	v_mul_f32_e32 v129, v129, v140
	v_mul_f32_e32 v130, v130, v140
	v_mul_f32_e32 v131, v131, v140
	v_mul_f32_e32 v132, v132, v140
	v_mul_f32_e32 v133, v133, v140
	v_mul_f32_e32 v134, v134, v140
	v_mul_f32_e32 v135, v135, v140
	v_fma_f32 v32, v120, v72, v32
	v_fma_f32 v33, v121, v73, v33
	v_fma_f32 v34, v122, v74, v34
	v_fma_f32 v35, v123, v75, v35
	v_fma_f32 v36, v124, v76, v36
	v_fma_f32 v37, v125, v77, v37
	v_fma_f32 v38, v126, v78, v38
	v_fma_f32 v39, v127, v79, v39
	v_fma_f32 v40, v128, v80, v40
	v_fma_f32 v41, v129, v81, v41
	v_fma_f32 v42, v130, v82, v42
	v_fma_f32 v43, v131, v83, v43
	v_fma_f32 v44, v132, v84, v44
	v_fma_f32 v45, v133, v85, v45
	v_fma_f32 v46, v134, v86, v46
	v_fma_f32 v47, v135, v87, v47
	s_lshl_b32 vcc_lo, s19, 12
	s_add_u32 vcc_lo, vcc_lo, 0x1000000
	s_add_u32 s100, s16, vcc_lo
	s_addc_u32 s101, s17, 0
	global_store_dwordx4 v136, v[32:35], s[100:101] offset:0
	global_store_dwordx4 v136, v[36:39], s[100:101] offset:1024
	global_store_dwordx4 v136, v[40:43], s[100:101] offset:2048
	global_store_dwordx4 v136, v[44:47], s[100:101] offset:3072
	s_lshl_b32 vcc_lo, s19, 11
	s_add_u32 vcc_lo, vcc_lo, 0x1800000
	s_add_u32 s100, s12, vcc_lo
	s_addc_u32 s101, s13, 0
	global_load_dwordx2 v[40:41], v137, s[100:101] offset:0
	global_load_dwordx2 v[42:43], v137, s[100:101] offset:512
	global_load_dwordx2 v[44:45], v137, s[100:101] offset:1024
	global_load_dwordx2 v[46:47], v137, s[100:101] offset:1536
	s_lshl_b32 vcc_lo, s19, 11
	s_add_u32 vcc_lo, vcc_lo, 0x1800000
	s_add_u32 s100, s14, vcc_lo
	s_addc_u32 s101, s15, 0
	global_load_dwordx2 v[64:65], v137, s[100:101] offset:0
	global_load_dwordx2 v[66:67], v137, s[100:101] offset:512
	global_load_dwordx2 v[68:69], v137, s[100:101] offset:1024
	global_load_dwordx2 v[70:71], v137, s[100:101] offset:1536
	s_waitcnt vmcnt(36)
; __device__ __forceinline__ float bf2f(u16 h) { return __uint_as_float(((unsigned)h) << 16); }
; __device__ __forceinline__ void row_phase(const Params& P, int glayer, int layer, int xsrc, bool hasY, int gate_idx, const float* gpost,
;                           int xdst, bool doH, const float* gpre, int sh_idx, int nrows) {
;     ...
;         if (hasY) {
;           float4 yv[4];
;           float ss = 0.f;
; #pragma unroll
;           for (int i = 0; i < 4; ++i) {
;             const uint2 raw = yy[u][i];
;             yv[i].x = bf2f((u16)(raw.x & 0xffff)); yv[i].y = bf2f((u16)(raw.x >> 16));
;             yv[i].z = bf2f((u16)(raw.y & 0xffff)); yv[i].w = bf2f((u16)(raw.y >> 16));
;             ss += yv[i].x * yv[i].x + yv[i].y * yv[i].y + yv[i].z * yv[i].z + yv[i].w * yv[i].w;
;           }
;           ss = wave_sum(ss);
;           const float rstd = __builtin_amdgcn_rsqf(ss * (1.f / 1024.f) + EPSF);
; #pragma unroll
;           for (int i = 0; i < 4; ++i) {
;             const int col = (i * 64 + lane) * 4;
;             const float4 gt = *reinterpret_cast<const float4*>(modg + gate_idx * 1024 + col);
;             const float4 gp = *reinterpret_cast<const float4*>(gpost + col);
;             xv[i].x += gt.x * (yv[i].x * rstd * gp.x); xv[i].y += gt.y * (yv[i].y * rstd * gp.y);
;             xv[i].z += gt.z * (yv[i].z * rstd * gp.z); xv[i].w += gt.w * (yv[i].w * rstd * gp.w);
;           }
;         }
;         if (xdst == 3 || (xdst == 1 && row >= N_X)) {
;           float* xout = (xdst == 3) ? P.out + (long)row * 1024 : P.xc + (long)(row - N_X) * 1024;
; #pragma unroll
;           for (int i = 0; i < 4; ++i) *reinterpret_cast<float4*>(xout + (i * 64 + lane) * 4) = xv[i];
	v_lshlrev_b32_e32 v120, 16, v182
	v_and_b32_e32 v121, 0xffff0000, v182
	v_lshlrev_b32_e32 v122, 16, v183
	v_and_b32_e32 v123, 0xffff0000, v183
	v_lshlrev_b32_e32 v124, 16, v184
	v_and_b32_e32 v125, 0xffff0000, v184
	v_lshlrev_b32_e32 v126, 16, v185
	v_and_b32_e32 v127, 0xffff0000, v185
	v_lshlrev_b32_e32 v128, 16, v186
	v_and_b32_e32 v129, 0xffff0000, v186
	v_lshlrev_b32_e32 v130, 16, v187
	v_and_b32_e32 v131, 0xffff0000, v187
	v_lshlrev_b32_e32 v132, 16, v188
	v_and_b32_e32 v133, 0xffff0000, v188
	v_lshlrev_b32_e32 v134, 16, v189
	v_and_b32_e32 v135, 0xffff0000, v189
	v_mul_f32_e32 v138, v120, v120
	v_mul_f32_e32 v149, v121, v121
	v_mul_f32_e32 v150, v122, v122
	v_mul_f32_e32 v154, v123, v123
	v_fma_f32 v138, v124, v124, v138
	v_fma_f32 v149, v125, v125, v149
	v_fma_f32 v150, v126, v126, v150
	v_fma_f32 v154, v127, v127, v154
	v_fma_f32 v138, v128, v128, v138
	v_fma_f32 v149, v129, v129, v149
	v_fma_f32 v150, v130, v130, v150
	v_fma_f32 v154, v131, v131, v154
	v_fma_f32 v138, v132, v132, v138
	v_fma_f32 v149, v133, v133, v149
	v_fma_f32 v150, v134, v134, v150
	v_fma_f32 v154, v135, v135, v154
	v_add_f32_e32 v138, v138, v149
	v_add_f32_e32 v150, v150, v154
	v_add_f32_e32 v138, v138, v150
	s_nop 1
	v_add_f32_dpp v138, v138, v138 quad_perm:[1,0,3,2] row_mask:0xf bank_mask:0xf
	s_nop 1
	v_add_f32_dpp v138, v138, v138 quad_perm:[2,3,0,1] row_mask:0xf bank_mask:0xf
	s_nop 1
	v_add_f32_dpp v138, v138, v138 row_half_mirror row_mask:0xf bank_mask:0xf
	s_nop 1
	v_add_f32_dpp v138, v138, v138 row_mirror row_mask:0xf bank_mask:0xf
	v_mov_b32_e32 v139, v138
	s_nop 1
	v_permlane16_swap_b32_e32 v138, v139
	v_add_f32_e32 v138, v138, v139
	v_mov_b32_e32 v139, v138
	s_nop 1
	v_permlane32_swap_b32_e32 v138, v139
	v_add_f32_e32 v138, v138, v139
	v_mul_f32_e32 v138, 0x3a800000, v138
	v_add_f32_e32 v138, 0x358637bd, v138
	v_rsq_f32_e32 v140, v138
	v_lshlrev_b32_e32 v166, 16, v174
	v_and_b32_e32 v167, 0xffff0000, v174
	v_lshlrev_b32_e32 v168, 16, v175
	v_and_b32_e32 v169, 0xffff0000, v175
	v_lshlrev_b32_e32 v170, 16, v176
	v_and_b32_e32 v171, 0xffff0000, v176
	v_lshlrev_b32_e32 v172, 16, v177
	v_and_b32_e32 v173, 0xffff0000, v177
	v_lshlrev_b32_e32 v174, 16, v178
	v_and_b32_e32 v175, 0xffff0000, v178
	v_lshlrev_b32_e32 v176, 16, v179
	v_and_b32_e32 v177, 0xffff0000, v179
	v_lshlrev_b32_e32 v178, 16, v180
	v_and_b32_e32 v179, 0xffff0000, v180
	v_lshlrev_b32_e32 v180, 16, v181
	v_and_b32_e32 v181, 0xffff0000, v181
	s_nop 0
	v_mul_f32_e32 v120, v120, v140
	v_mul_f32_e32 v121, v121, v140
	v_mul_f32_e32 v122, v122, v140
	v_mul_f32_e32 v123, v123, v140
	v_mul_f32_e32 v124, v124, v140
	v_mul_f32_e32 v125, v125, v140
	v_mul_f32_e32 v126, v126, v140
	v_mul_f32_e32 v127, v127, v140
	v_mul_f32_e32 v128, v128, v140
	v_mul_f32_e32 v129, v129, v140
	v_mul_f32_e32 v130, v130, v140
	v_mul_f32_e32 v131, v131, v140
	v_mul_f32_e32 v132, v132, v140
	v_mul_f32_e32 v133, v133, v140
	v_mul_f32_e32 v134, v134, v140
	v_mul_f32_e32 v135, v135, v140
	v_fma_f32 v166, v120, v72, v166
	v_fma_f32 v167, v121, v73, v167
	v_fma_f32 v168, v122, v74, v168
	v_fma_f32 v169, v123, v75, v169
	v_fma_f32 v170, v124, v76, v170
	v_fma_f32 v171, v125, v77, v171
	v_fma_f32 v172, v126, v78, v172
	v_fma_f32 v173, v127, v79, v173
	v_fma_f32 v174, v128, v80, v174
	v_fma_f32 v175, v129, v81, v175
	v_fma_f32 v176, v130, v82, v176
	v_fma_f32 v177, v131, v83, v177
	v_fma_f32 v178, v132, v84, v178
	v_fma_f32 v179, v133, v85, v179
	v_fma_f32 v180, v134, v86, v180
	v_fma_f32 v181, v135, v87, v181
	s_lshl_b32 vcc_lo, s19, 12
	s_add_u32 vcc_lo, vcc_lo, 0x1800000
	s_add_u32 s100, s16, vcc_lo
	s_addc_u32 s101, s17, 0
	global_store_dwordx4 v136, v[166:169], s[100:101] offset:0
	global_store_dwordx4 v136, v[170:173], s[100:101] offset:1024
	global_store_dwordx4 v136, v[174:177], s[100:101] offset:2048
	global_store_dwordx4 v136, v[178:181], s[100:101] offset:3072
	s_add_u32 s100, s20, 0x29000
	s_addc_u32 s101, s21, 0
	global_load_dwordx4 v[72:75], v136, s[100:101] offset:0
	global_load_dwordx4 v[76:79], v136, s[100:101] offset:1024
	global_load_dwordx4 v[80:83], v136, s[100:101] offset:2048
	global_load_dwordx4 v[84:87], v136, s[100:101] offset:3072
	s_load_dwordx2 s[98:99], s[4:5], 0x48
	s_waitcnt lgkmcnt(0)
	s_add_u32 s98, s98, 0x1000
	s_addc_u32 s99, s99, 0
	global_load_dwordx4 v[120:123], v136, s[98:99] offset:0
	global_load_dwordx4 v[124:127], v136, s[98:99] offset:1024
	global_load_dwordx4 v[128:131], v136, s[98:99] offset:2048
	global_load_dwordx4 v[132:135], v136, s[98:99] offset:3072
	s_waitcnt vmcnt(0)
; __device__ __forceinline__ float bf2f(u16 h) { return __uint_as_float(((unsigned)h) << 16); }
; __device__ __forceinline__ void row_phase(const Params& P, int glayer, int layer, int xsrc, bool hasY, int gate_idx, const float* gpost,
;                           int xdst, bool doH, const float* gpre, int sh_idx, int nrows) {
;     ...
;         if (hasY) {
;           float4 yv[4];
;           float ss = 0.f;
; #pragma unroll
;           for (int i = 0; i < 4; ++i) {
;             const uint2 raw = yy[u][i];
;             yv[i].x = bf2f((u16)(raw.x & 0xffff)); yv[i].y = bf2f((u16)(raw.x >> 16));
;             yv[i].z = bf2f((u16)(raw.y & 0xffff)); yv[i].w = bf2f((u16)(raw.y >> 16));
;             ss += yv[i].x * yv[i].x + yv[i].y * yv[i].y + yv[i].z * yv[i].z + yv[i].w * yv[i].w;
;           }
;           ss = wave_sum(ss);
;           const float rstd = __builtin_amdgcn_rsqf(ss * (1.f / 1024.f) + EPSF);
; #pragma unroll
;           for (int i = 0; i < 4; ++i) {
;             const int col = (i * 64 + lane) * 4;
;             const float4 gt = *reinterpret_cast<const float4*>(modg + gate_idx * 1024 + col);
;             const float4 gp = *reinterpret_cast<const float4*>(gpost + col);
;             xv[i].x += gt.x * (yv[i].x * rstd * gp.x); xv[i].y += gt.y * (yv[i].y * rstd * gp.y);
;             xv[i].z += gt.z * (yv[i].z * rstd * gp.z); xv[i].w += gt.w * (yv[i].w * rstd * gp.w);
;           }
;         }
;         if (xdst == 3 || (xdst == 1 && row >= N_X)) {
;           float* xout = (xdst == 3) ? P.out + (long)row * 1024 : P.xc + (long)(row - N_X) * 1024;
; #pragma unroll
;           for (int i = 0; i < 4; ++i) *reinterpret_cast<float4*>(xout + (i * 64 + lane) * 4) = xv[i];
	v_mul_f32_e32 v72, v72, v120
	v_mul_f32_e32 v73, v73, v121
	v_mul_f32_e32 v74, v74, v122
	v_mul_f32_e32 v75, v75, v123
	v_mul_f32_e32 v76, v76, v124
	v_mul_f32_e32 v77, v77, v125
	v_mul_f32_e32 v78, v78, v126
	v_mul_f32_e32 v79, v79, v127
	v_mul_f32_e32 v80, v80, v128
	v_mul_f32_e32 v81, v81, v129
	v_mul_f32_e32 v82, v82, v130
	v_mul_f32_e32 v83, v83, v131
	v_mul_f32_e32 v84, v84, v132
	v_mul_f32_e32 v85, v85, v133
	v_mul_f32_e32 v86, v86, v134
	v_mul_f32_e32 v87, v87, v135
	s_lshl_b32 vcc_lo, s19, 11
	s_add_u32 vcc_lo, vcc_lo, 0x1c00000
	s_add_u32 s100, s12, vcc_lo
	s_addc_u32 s101, s13, 0
	global_load_dwordx2 v[174:175], v137, s[100:101] offset:0
	global_load_dwordx2 v[176:177], v137, s[100:101] offset:512
	global_load_dwordx2 v[178:179], v137, s[100:101] offset:1024
	global_load_dwordx2 v[180:181], v137, s[100:101] offset:1536
	s_lshl_b32 vcc_lo, s19, 11
	s_add_u32 vcc_lo, vcc_lo, 0x1c00000
	s_add_u32 s100, s14, vcc_lo
	s_addc_u32 s101, s15, 0
	global_load_dwordx2 v[182:183], v137, s[100:101] offset:0
	global_load_dwordx2 v[184:185], v137, s[100:101] offset:512
	global_load_dwordx2 v[186:187], v137, s[100:101] offset:1024
	global_load_dwordx2 v[188:189], v137, s[100:101] offset:1536
	v_lshlrev_b32_e32 v120, 16, v48
	v_and_b32_e32 v121, 0xffff0000, v48
	v_lshlrev_b32_e32 v122, 16, v49
	v_and_b32_e32 v123, 0xffff0000, v49
	v_lshlrev_b32_e32 v124, 16, v50
	v_and_b32_e32 v125, 0xffff0000, v50
	v_lshlrev_b32_e32 v126, 16, v51
	v_and_b32_e32 v127, 0xffff0000, v51
	v_lshlrev_b32_e32 v128, 16, v52
	v_and_b32_e32 v129, 0xffff0000, v52
	v_lshlrev_b32_e32 v130, 16, v53
	v_and_b32_e32 v131, 0xffff0000, v53
	v_lshlrev_b32_e32 v132, 16, v54
	v_and_b32_e32 v133, 0xffff0000, v54
	v_lshlrev_b32_e32 v134, 16, v55
	v_and_b32_e32 v135, 0xffff0000, v55
	v_mul_f32_e32 v138, v120, v120
	v_mul_f32_e32 v149, v121, v121
	v_mul_f32_e32 v150, v122, v122
	v_mul_f32_e32 v154, v123, v123
	v_fma_f32 v138, v124, v124, v138
	v_fma_f32 v149, v125, v125, v149
	v_fma_f32 v150, v126, v126, v150
	v_fma_f32 v154, v127, v127, v154
	v_fma_f32 v138, v128, v128, v138
	v_fma_f32 v149, v129, v129, v149
	v_fma_f32 v150, v130, v130, v150
	v_fma_f32 v154, v131, v131, v154
	v_fma_f32 v138, v132, v132, v138
	v_fma_f32 v149, v133, v133, v149
	v_fma_f32 v150, v134, v134, v150
	v_fma_f32 v154, v135, v135, v154
	v_add_f32_e32 v138, v138, v149
	v_add_f32_e32 v150, v150, v154
	v_add_f32_e32 v138, v138, v150
	s_nop 1
	v_add_f32_dpp v138, v138, v138 quad_perm:[1,0,3,2] row_mask:0xf bank_mask:0xf
	s_nop 1
	v_add_f32_dpp v138, v138, v138 quad_perm:[2,3,0,1] row_mask:0xf bank_mask:0xf
	s_nop 1
	v_add_f32_dpp v138, v138, v138 row_half_mirror row_mask:0xf bank_mask:0xf
	s_nop 1
	v_add_f32_dpp v138, v138, v138 row_mirror row_mask:0xf bank_mask:0xf
	v_mov_b32_e32 v139, v138
	s_nop 1
	v_permlane16_swap_b32_e32 v138, v139
	v_add_f32_e32 v138, v138, v139
	v_mov_b32_e32 v139, v138
	s_nop 1
	v_permlane32_swap_b32_e32 v138, v139
	v_add_f32_e32 v138, v138, v139
	v_mul_f32_e32 v138, 0x3a800000, v138
	v_add_f32_e32 v138, 0x358637bd, v138
	v_rsq_f32_e32 v140, v138
	v_lshlrev_b32_e32 v0, 16, v8
	v_and_b32_e32 v1, 0xffff0000, v8
	v_lshlrev_b32_e32 v2, 16, v9
	v_and_b32_e32 v3, 0xffff0000, v9
	v_lshlrev_b32_e32 v4, 16, v10
	v_and_b32_e32 v5, 0xffff0000, v10
	v_lshlrev_b32_e32 v6, 16, v11
	v_and_b32_e32 v7, 0xffff0000, v11
	v_lshlrev_b32_e32 v8, 16, v12
	v_and_b32_e32 v9, 0xffff0000, v12
	v_lshlrev_b32_e32 v10, 16, v13
	v_and_b32_e32 v11, 0xffff0000, v13
	v_lshlrev_b32_e32 v12, 16, v14
	v_and_b32_e32 v13, 0xffff0000, v14
	v_lshlrev_b32_e32 v14, 16, v15
	v_and_b32_e32 v15, 0xffff0000, v15
	s_nop 0
	v_mul_f32_e32 v120, v120, v140
	v_mul_f32_e32 v121, v121, v140
	v_mul_f32_e32 v122, v122, v140
	v_mul_f32_e32 v123, v123, v140
	v_mul_f32_e32 v124, v124, v140
	v_mul_f32_e32 v125, v125, v140
	v_mul_f32_e32 v126, v126, v140
	v_mul_f32_e32 v127, v127, v140
	v_mul_f32_e32 v128, v128, v140
	v_mul_f32_e32 v129, v129, v140
	v_mul_f32_e32 v130, v130, v140
	v_mul_f32_e32 v131, v131, v140
	v_mul_f32_e32 v132, v132, v140
	v_mul_f32_e32 v133, v133, v140
	v_mul_f32_e32 v134, v134, v140
	v_mul_f32_e32 v135, v135, v140
	v_fma_f32 v0, v120, v72, v0
	v_fma_f32 v1, v121, v73, v1
	v_fma_f32 v2, v122, v74, v2
	v_fma_f32 v3, v123, v75, v3
	v_fma_f32 v4, v124, v76, v4
	v_fma_f32 v5, v125, v77, v5
	v_fma_f32 v6, v126, v78, v6
	v_fma_f32 v7, v127, v79, v7
	v_fma_f32 v8, v128, v80, v8
	v_fma_f32 v9, v129, v81, v9
	v_fma_f32 v10, v130, v82, v10
	v_fma_f32 v11, v131, v83, v11
	v_fma_f32 v12, v132, v84, v12
	v_fma_f32 v13, v133, v85, v13
	v_fma_f32 v14, v134, v86, v14
	v_fma_f32 v15, v135, v87, v15
	s_lshl_b32 vcc_lo, s19, 12
	s_add_u32 vcc_lo, vcc_lo, 0x2000000
	s_add_u32 s100, s16, vcc_lo
	s_addc_u32 s101, s17, 0
	global_store_dwordx4 v136, v[0:3], s[100:101] offset:0
	global_store_dwordx4 v136, v[4:7], s[100:101] offset:1024
	global_store_dwordx4 v136, v[8:11], s[100:101] offset:2048
	global_store_dwordx4 v136, v[12:15], s[100:101] offset:3072
	s_lshl_b32 vcc_lo, s19, 11
	s_add_u32 vcc_lo, vcc_lo, 0x2000000
	s_add_u32 s100, s12, vcc_lo
	s_addc_u32 s101, s13, 0
	global_load_dwordx2 v[8:9], v137, s[100:101] offset:0
	global_load_dwordx2 v[10:11], v137, s[100:101] offset:512
	global_load_dwordx2 v[12:13], v137, s[100:101] offset:1024
	global_load_dwordx2 v[14:15], v137, s[100:101] offset:1536
	s_lshl_b32 vcc_lo, s19, 11
	s_add_u32 vcc_lo, vcc_lo, 0x2000000
	s_add_u32 s100, s14, vcc_lo
	s_addc_u32 s101, s15, 0
	global_load_dwordx2 v[48:49], v137, s[100:101] offset:0
	global_load_dwordx2 v[50:51], v137, s[100:101] offset:512
	global_load_dwordx2 v[52:53], v137, s[100:101] offset:1024
	global_load_dwordx2 v[54:55], v137, s[100:101] offset:1536
; __device__ __forceinline__ float bf2f(u16 h) { return __uint_as_float(((unsigned)h) << 16); }
; __device__ __forceinline__ void row_phase(const Params& P, int glayer, int layer, int xsrc, bool hasY, int gate_idx, const float* gpost,
;                           int xdst, bool doH, const float* gpre, int sh_idx, int nrows) {
;     ...
;         if (hasY) {
;           float4 yv[4];
;           float ss = 0.f;
; #pragma unroll
;           for (int i = 0; i < 4; ++i) {
;             const uint2 raw = yy[u][i];
;             yv[i].x = bf2f((u16)(raw.x & 0xffff)); yv[i].y = bf2f((u16)(raw.x >> 16));
;             yv[i].z = bf2f((u16)(raw.y & 0xffff)); yv[i].w = bf2f((u16)(raw.y >> 16));
;             ss += yv[i].x * yv[i].x + yv[i].y * yv[i].y + yv[i].z * yv[i].z + yv[i].w * yv[i].w;
;           }
;           ss = wave_sum(ss);
;           const float rstd = __builtin_amdgcn_rsqf(ss * (1.f / 1024.f) + EPSF);
; #pragma unroll
;           for (int i = 0; i < 4; ++i) {
;             const int col = (i * 64 + lane) * 4;
;             const float4 gt = *reinterpret_cast<const float4*>(modg + gate_idx * 1024 + col);
;             const float4 gp = *reinterpret_cast<const float4*>(gpost + col);
;             xv[i].x += gt.x * (yv[i].x * rstd * gp.x); xv[i].y += gt.y * (yv[i].y * rstd * gp.y);
;             xv[i].z += gt.z * (yv[i].z * rstd * gp.z); xv[i].w += gt.w * (yv[i].w * rstd * gp.w);
;           }
;         }
;         if (xdst == 3 || (xdst == 1 && row >= N_X)) {
;           float* xout = (xdst == 3) ? P.out + (long)row * 1024 : P.xc + (long)(row - N_X) * 1024;
; #pragma unroll
;           for (int i = 0; i < 4; ++i) *reinterpret_cast<float4*>(xout + (i * 64 + lane) * 4) = xv[i];
	v_lshlrev_b32_e32 v120, 16, v56
	v_and_b32_e32 v121, 0xffff0000, v56
	v_lshlrev_b32_e32 v122, 16, v57
	v_and_b32_e32 v123, 0xffff0000, v57
	v_lshlrev_b32_e32 v124, 16, v58
	v_and_b32_e32 v125, 0xffff0000, v58
	v_lshlrev_b32_e32 v126, 16, v59
	v_and_b32_e32 v127, 0xffff0000, v59
	v_lshlrev_b32_e32 v128, 16, v60
	v_and_b32_e32 v129, 0xffff0000, v60
	v_lshlrev_b32_e32 v130, 16, v61
	v_and_b32_e32 v131, 0xffff0000, v61
	v_lshlrev_b32_e32 v132, 16, v62
	v_and_b32_e32 v133, 0xffff0000, v62
	v_lshlrev_b32_e32 v134, 16, v63
	v_and_b32_e32 v135, 0xffff0000, v63
	v_mul_f32_e32 v138, v120, v120
	v_mul_f32_e32 v149, v121, v121
	v_mul_f32_e32 v150, v122, v122
	v_mul_f32_e32 v154, v123, v123
	v_fma_f32 v138, v124, v124, v138
	v_fma_f32 v149, v125, v125, v149
	v_fma_f32 v150, v126, v126, v150
	v_fma_f32 v154, v127, v127, v154
	v_fma_f32 v138, v128, v128, v138
	v_fma_f32 v149, v129, v129, v149
	v_fma_f32 v150, v130, v130, v150
	v_fma_f32 v154, v131, v131, v154
	v_fma_f32 v138, v132, v132, v138
	v_fma_f32 v149, v133, v133, v149
	v_fma_f32 v150, v134, v134, v150
	v_fma_f32 v154, v135, v135, v154
	v_add_f32_e32 v138, v138, v149
	v_add_f32_e32 v150, v150, v154
	v_add_f32_e32 v138, v138, v150
	s_nop 1
	v_add_f32_dpp v138, v138, v138 quad_perm:[1,0,3,2] row_mask:0xf bank_mask:0xf
	s_nop 1
	v_add_f32_dpp v138, v138, v138 quad_perm:[2,3,0,1] row_mask:0xf bank_mask:0xf
	s_nop 1
	v_add_f32_dpp v138, v138, v138 row_half_mirror row_mask:0xf bank_mask:0xf
	s_nop 1
	v_add_f32_dpp v138, v138, v138 row_mirror row_mask:0xf bank_mask:0xf
	v_mov_b32_e32 v139, v138
	s_nop 1
	v_permlane16_swap_b32_e32 v138, v139
	v_add_f32_e32 v138, v138, v139
	v_mov_b32_e32 v139, v138
	s_nop 1
	v_permlane32_swap_b32_e32 v138, v139
	v_add_f32_e32 v138, v138, v139
	v_mul_f32_e32 v138, 0x3a800000, v138
	v_add_f32_e32 v138, 0x358637bd, v138
	v_rsq_f32_e32 v140, v138
	v_lshlrev_b32_e32 v16, 16, v24
	v_and_b32_e32 v17, 0xffff0000, v24
	v_lshlrev_b32_e32 v18, 16, v25
	v_and_b32_e32 v19, 0xffff0000, v25
	v_lshlrev_b32_e32 v20, 16, v26
	v_and_b32_e32 v21, 0xffff0000, v26
	v_lshlrev_b32_e32 v22, 16, v27
	v_and_b32_e32 v23, 0xffff0000, v27
	v_lshlrev_b32_e32 v24, 16, v28
	v_and_b32_e32 v25, 0xffff0000, v28
	v_lshlrev_b32_e32 v26, 16, v29
	v_and_b32_e32 v27, 0xffff0000, v29
	v_lshlrev_b32_e32 v28, 16, v30
	v_and_b32_e32 v29, 0xffff0000, v30
	v_lshlrev_b32_e32 v30, 16, v31
	v_and_b32_e32 v31, 0xffff0000, v31
	s_nop 0
	v_mul_f32_e32 v120, v120, v140
	v_mul_f32_e32 v121, v121, v140
	v_mul_f32_e32 v122, v122, v140
	v_mul_f32_e32 v123, v123, v140
	v_mul_f32_e32 v124, v124, v140
	v_mul_f32_e32 v125, v125, v140
	v_mul_f32_e32 v126, v126, v140
	v_mul_f32_e32 v127, v127, v140
	v_mul_f32_e32 v128, v128, v140
	v_mul_f32_e32 v129, v129, v140
	v_mul_f32_e32 v130, v130, v140
	v_mul_f32_e32 v131, v131, v140
	v_mul_f32_e32 v132, v132, v140
	v_mul_f32_e32 v133, v133, v140
	v_mul_f32_e32 v134, v134, v140
	v_mul_f32_e32 v135, v135, v140
	v_fma_f32 v16, v120, v72, v16
	v_fma_f32 v17, v121, v73, v17
	v_fma_f32 v18, v122, v74, v18
	v_fma_f32 v19, v123, v75, v19
	v_fma_f32 v20, v124, v76, v20
	v_fma_f32 v21, v125, v77, v21
	v_fma_f32 v22, v126, v78, v22
	v_fma_f32 v23, v127, v79, v23
	v_fma_f32 v24, v128, v80, v24
	v_fma_f32 v25, v129, v81, v25
	v_fma_f32 v26, v130, v82, v26
	v_fma_f32 v27, v131, v83, v27
	v_fma_f32 v28, v132, v84, v28
	v_fma_f32 v29, v133, v85, v29
	v_fma_f32 v30, v134, v86, v30
	v_fma_f32 v31, v135, v87, v31
	s_lshl_b32 vcc_lo, s19, 12
	s_add_u32 vcc_lo, vcc_lo, 0x2800000
	s_add_u32 s100, s16, vcc_lo
	s_addc_u32 s101, s17, 0
	global_store_dwordx4 v136, v[16:19], s[100:101] offset:0
	global_store_dwordx4 v136, v[20:23], s[100:101] offset:1024
	global_store_dwordx4 v136, v[24:27], s[100:101] offset:2048
	global_store_dwordx4 v136, v[28:31], s[100:101] offset:3072
	s_lshl_b32 vcc_lo, s19, 11
	s_add_u32 vcc_lo, vcc_lo, 0x2400000
	s_add_u32 s100, s12, vcc_lo
	s_addc_u32 s101, s13, 0
	global_load_dwordx2 v[24:25], v137, s[100:101] offset:0
	global_load_dwordx2 v[26:27], v137, s[100:101] offset:512
	global_load_dwordx2 v[28:29], v137, s[100:101] offset:1024
	global_load_dwordx2 v[30:31], v137, s[100:101] offset:1536
	s_lshl_b32 vcc_lo, s19, 11
	s_add_u32 vcc_lo, vcc_lo, 0x2400000
	s_add_u32 s100, s14, vcc_lo
	s_addc_u32 s101, s15, 0
	global_load_dwordx2 v[56:57], v137, s[100:101] offset:0
	global_load_dwordx2 v[58:59], v137, s[100:101] offset:512
	global_load_dwordx2 v[60:61], v137, s[100:101] offset:1024
	global_load_dwordx2 v[62:63], v137, s[100:101] offset:1536
	v_lshlrev_b32_e32 v120, 16, v64
	v_and_b32_e32 v121, 0xffff0000, v64
	v_lshlrev_b32_e32 v122, 16, v65
	v_and_b32_e32 v123, 0xffff0000, v65
	v_lshlrev_b32_e32 v124, 16, v66
	v_and_b32_e32 v125, 0xffff0000, v66
	v_lshlrev_b32_e32 v126, 16, v67
	v_and_b32_e32 v127, 0xffff0000, v67
	v_lshlrev_b32_e32 v128, 16, v68
	v_and_b32_e32 v129, 0xffff0000, v68
	v_lshlrev_b32_e32 v130, 16, v69
	v_and_b32_e32 v131, 0xffff0000, v69
	v_lshlrev_b32_e32 v132, 16, v70
	v_and_b32_e32 v133, 0xffff0000, v70
	v_lshlrev_b32_e32 v134, 16, v71
	v_and_b32_e32 v135, 0xffff0000, v71
	v_mul_f32_e32 v138, v120, v120
	v_mul_f32_e32 v149, v121, v121
	v_mul_f32_e32 v150, v122, v122
	v_mul_f32_e32 v154, v123, v123
	v_fma_f32 v138, v124, v124, v138
	v_fma_f32 v149, v125, v125, v149
	v_fma_f32 v150, v126, v126, v150
	v_fma_f32 v154, v127, v127, v154
	v_fma_f32 v138, v128, v128, v138
	v_fma_f32 v149, v129, v129, v149
	v_fma_f32 v150, v130, v130, v150
	v_fma_f32 v154, v131, v131, v154
	v_fma_f32 v138, v132, v132, v138
	v_fma_f32 v149, v133, v133, v149
	v_fma_f32 v150, v134, v134, v150
	v_fma_f32 v154, v135, v135, v154
	v_add_f32_e32 v138, v138, v149
	v_add_f32_e32 v150, v150, v154
; __device__ __forceinline__ float bf2f(u16 h) { return __uint_as_float(((unsigned)h) << 16); }
; __device__ __forceinline__ void row_phase(const Params& P, int glayer, int layer, int xsrc, bool hasY, int gate_idx, const float* gpost,
;                           int xdst, bool doH, const float* gpre, int sh_idx, int nrows) {
;     ...
;         if (hasY) {
;           float4 yv[4];
;           float ss = 0.f;
; #pragma unroll
;           for (int i = 0; i < 4; ++i) {
;             const uint2 raw = yy[u][i];
;             yv[i].x = bf2f((u16)(raw.x & 0xffff)); yv[i].y = bf2f((u16)(raw.x >> 16));
;             yv[i].z = bf2f((u16)(raw.y & 0xffff)); yv[i].w = bf2f((u16)(raw.y >> 16));
;             ss += yv[i].x * yv[i].x + yv[i].y * yv[i].y + yv[i].z * yv[i].z + yv[i].w * yv[i].w;
;           }
;           ss = wave_sum(ss);
;           const float rstd = __builtin_amdgcn_rsqf(ss * (1.f / 1024.f) + EPSF);
; #pragma unroll
;           for (int i = 0; i < 4; ++i) {
;             const int col = (i * 64 + lane) * 4;
;             const float4 gt = *reinterpret_cast<const float4*>(modg + gate_idx * 1024 + col);
;             const float4 gp = *reinterpret_cast<const float4*>(gpost + col);
;             xv[i].x += gt.x * (yv[i].x * rstd * gp.x); xv[i].y += gt.y * (yv[i].y * rstd * gp.y);
;             xv[i].z += gt.z * (yv[i].z * rstd * gp.z); xv[i].w += gt.w * (yv[i].w * rstd * gp.w);
;           }
;         }
;         if (xdst == 3 || (xdst == 1 && row >= N_X)) {
;           float* xout = (xdst == 3) ? P.out + (long)row * 1024 : P.xc + (long)(row - N_X) * 1024;
; #pragma unroll
;           for (int i = 0; i < 4; ++i) *reinterpret_cast<float4*>(xout + (i * 64 + lane) * 4) = xv[i];
	v_add_f32_e32 v138, v138, v150
	s_nop 1
	v_add_f32_dpp v138, v138, v138 quad_perm:[1,0,3,2] row_mask:0xf bank_mask:0xf
	s_nop 1
	v_add_f32_dpp v138, v138, v138 quad_perm:[2,3,0,1] row_mask:0xf bank_mask:0xf
	s_nop 1
	v_add_f32_dpp v138, v138, v138 row_half_mirror row_mask:0xf bank_mask:0xf
	s_nop 1
	v_add_f32_dpp v138, v138, v138 row_mirror row_mask:0xf bank_mask:0xf
	v_mov_b32_e32 v139, v138
	s_nop 1
	v_permlane16_swap_b32_e32 v138, v139
	v_add_f32_e32 v138, v138, v139
	v_mov_b32_e32 v139, v138
	s_nop 1
	v_permlane32_swap_b32_e32 v138, v139
	v_add_f32_e32 v138, v138, v139
	v_mul_f32_e32 v138, 0x3a800000, v138
	v_add_f32_e32 v138, 0x358637bd, v138
	v_rsq_f32_e32 v140, v138
	v_lshlrev_b32_e32 v32, 16, v40
	v_and_b32_e32 v33, 0xffff0000, v40
	v_lshlrev_b32_e32 v34, 16, v41
	v_and_b32_e32 v35, 0xffff0000, v41
	v_lshlrev_b32_e32 v36, 16, v42
	v_and_b32_e32 v37, 0xffff0000, v42
	v_lshlrev_b32_e32 v38, 16, v43
	v_and_b32_e32 v39, 0xffff0000, v43
	v_lshlrev_b32_e32 v40, 16, v44
	v_and_b32_e32 v41, 0xffff0000, v44
	v_lshlrev_b32_e32 v42, 16, v45
	v_and_b32_e32 v43, 0xffff0000, v45
	v_lshlrev_b32_e32 v44, 16, v46
	v_and_b32_e32 v45, 0xffff0000, v46
	v_lshlrev_b32_e32 v46, 16, v47
	v_and_b32_e32 v47, 0xffff0000, v47
	s_nop 0
	v_mul_f32_e32 v120, v120, v140
	v_mul_f32_e32 v121, v121, v140
	v_mul_f32_e32 v122, v122, v140
	v_mul_f32_e32 v123, v123, v140
	v_mul_f32_e32 v124, v124, v140
	v_mul_f32_e32 v125, v125, v140
	v_mul_f32_e32 v126, v126, v140
	v_mul_f32_e32 v127, v127, v140
	v_mul_f32_e32 v128, v128, v140
	v_mul_f32_e32 v129, v129, v140
	v_mul_f32_e32 v130, v130, v140
	v_mul_f32_e32 v131, v131, v140
	v_mul_f32_e32 v132, v132, v140
	v_mul_f32_e32 v133, v133, v140
	v_mul_f32_e32 v134, v134, v140
	v_mul_f32_e32 v135, v135, v140
	v_fma_f32 v32, v120, v72, v32
	v_fma_f32 v33, v121, v73, v33
	v_fma_f32 v34, v122, v74, v34
	v_fma_f32 v35, v123, v75, v35
	v_fma_f32 v36, v124, v76, v36
	v_fma_f32 v37, v125, v77, v37
	v_fma_f32 v38, v126, v78, v38
	v_fma_f32 v39, v127, v79, v39
	v_fma_f32 v40, v128, v80, v40
	v_fma_f32 v41, v129, v81, v41
	v_fma_f32 v42, v130, v82, v42
	v_fma_f32 v43, v131, v83, v43
	v_fma_f32 v44, v132, v84, v44
	v_fma_f32 v45, v133, v85, v45
	v_fma_f32 v46, v134, v86, v46
	v_fma_f32 v47, v135, v87, v47
	s_lshl_b32 vcc_lo, s19, 12
	s_add_u32 vcc_lo, vcc_lo, 0x3000000
	s_add_u32 s100, s16, vcc_lo
	s_addc_u32 s101, s17, 0
	global_store_dwordx4 v136, v[32:35], s[100:101] offset:0
	global_store_dwordx4 v136, v[36:39], s[100:101] offset:1024
	global_store_dwordx4 v136, v[40:43], s[100:101] offset:2048
	global_store_dwordx4 v136, v[44:47], s[100:101] offset:3072
	s_lshl_b32 vcc_lo, s19, 11
	s_add_u32 vcc_lo, vcc_lo, 0x2800000
	s_add_u32 s100, s12, vcc_lo
	s_addc_u32 s101, s13, 0
	global_load_dwordx2 v[40:41], v137, s[100:101] offset:0
	global_load_dwordx2 v[42:43], v137, s[100:101] offset:512
	global_load_dwordx2 v[44:45], v137, s[100:101] offset:1024
	global_load_dwordx2 v[46:47], v137, s[100:101] offset:1536
	s_lshl_b32 vcc_lo, s19, 11
	s_add_u32 vcc_lo, vcc_lo, 0x2800000
	s_add_u32 s100, s14, vcc_lo
	s_addc_u32 s101, s15, 0
	global_load_dwordx2 v[64:65], v137, s[100:101] offset:0
	global_load_dwordx2 v[66:67], v137, s[100:101] offset:512
	global_load_dwordx2 v[68:69], v137, s[100:101] offset:1024
	global_load_dwordx2 v[70:71], v137, s[100:101] offset:1536
	s_waitcnt vmcnt(36)
	v_lshlrev_b32_e32 v120, 16, v182
	v_and_b32_e32 v121, 0xffff0000, v182
	v_lshlrev_b32_e32 v122, 16, v183
	v_and_b32_e32 v123, 0xffff0000, v183
	v_lshlrev_b32_e32 v124, 16, v184
	v_and_b32_e32 v125, 0xffff0000, v184
	v_lshlrev_b32_e32 v126, 16, v185
	v_and_b32_e32 v127, 0xffff0000, v185
	v_lshlrev_b32_e32 v128, 16, v186
	v_and_b32_e32 v129, 0xffff0000, v186
	v_lshlrev_b32_e32 v130, 16, v187
	v_and_b32_e32 v131, 0xffff0000, v187
	v_lshlrev_b32_e32 v132, 16, v188
	v_and_b32_e32 v133, 0xffff0000, v188
	v_lshlrev_b32_e32 v134, 16, v189
	v_and_b32_e32 v135, 0xffff0000, v189
	v_mul_f32_e32 v138, v120, v120
	v_mul_f32_e32 v149, v121, v121
	v_mul_f32_e32 v150, v122, v122
	v_mul_f32_e32 v154, v123, v123
	v_fma_f32 v138, v124, v124, v138
	v_fma_f32 v149, v125, v125, v149
	v_fma_f32 v150, v126, v126, v150
	v_fma_f32 v154, v127, v127, v154
	v_fma_f32 v138, v128, v128, v138
	v_fma_f32 v149, v129, v129, v149
	v_fma_f32 v150, v130, v130, v150
	v_fma_f32 v154, v131, v131, v154
	v_fma_f32 v138, v132, v132, v138
	v_fma_f32 v149, v133, v133, v149
	v_fma_f32 v150, v134, v134, v150
	v_fma_f32 v154, v135, v135, v154
	v_add_f32_e32 v138, v138, v149
	v_add_f32_e32 v150, v150, v154
	v_add_f32_e32 v138, v138, v150
	s_nop 1
	v_add_f32_dpp v138, v138, v138 quad_perm:[1,0,3,2] row_mask:0xf bank_mask:0xf
	s_nop 1
	v_add_f32_dpp v138, v138, v138 quad_perm:[2,3,0,1] row_mask:0xf bank_mask:0xf
	s_nop 1
	v_add_f32_dpp v138, v138, v138 row_half_mirror row_mask:0xf bank_mask:0xf
	s_nop 1
	v_add_f32_dpp v138, v138, v138 row_mirror row_mask:0xf bank_mask:0xf
	v_mov_b32_e32 v139, v138
	s_nop 1
	v_permlane16_swap_b32_e32 v138, v139
	v_add_f32_e32 v138, v138, v139
	v_mov_b32_e32 v139, v138
	s_nop 1
	v_permlane32_swap_b32_e32 v138, v139
	v_add_f32_e32 v138, v138, v139
	v_mul_f32_e32 v138, 0x3a800000, v138
	v_add_f32_e32 v138, 0x358637bd, v138
	v_rsq_f32_e32 v140, v138
	v_lshlrev_b32_e32 v166, 16, v174
	v_and_b32_e32 v167, 0xffff0000, v174
	v_lshlrev_b32_e32 v168, 16, v175
	v_and_b32_e32 v169, 0xffff0000, v175
	v_lshlrev_b32_e32 v170, 16, v176
	v_and_b32_e32 v171, 0xffff0000, v176
	v_lshlrev_b32_e32 v172, 16, v177
	v_and_b32_e32 v173, 0xffff0000, v177
	v_lshlrev_b32_e32 v174, 16, v178
	v_and_b32_e32 v175, 0xffff0000, v178
	v_lshlrev_b32_e32 v176, 16, v179
	v_and_b32_e32 v177, 0xffff0000, v179
; __device__ __forceinline__ float bf2f(u16 h) { return __uint_as_float(((unsigned)h) << 16); }
; __device__ __forceinline__ void row_phase(const Params& P, int glayer, int layer, int xsrc, bool hasY, int gate_idx, const float* gpost,
;                           int xdst, bool doH, const float* gpre, int sh_idx, int nrows) {
;     ...
;         if (hasY) {
;           float4 yv[4];
;           float ss = 0.f;
; #pragma unroll
;           for (int i = 0; i < 4; ++i) {
;             const uint2 raw = yy[u][i];
;             yv[i].x = bf2f((u16)(raw.x & 0xffff)); yv[i].y = bf2f((u16)(raw.x >> 16));
;             yv[i].z = bf2f((u16)(raw.y & 0xffff)); yv[i].w = bf2f((u16)(raw.y >> 16));
;             ss += yv[i].x * yv[i].x + yv[i].y * yv[i].y + yv[i].z * yv[i].z + yv[i].w * yv[i].w;
;           }
;           ss = wave_sum(ss);
;           const float rstd = __builtin_amdgcn_rsqf(ss * (1.f / 1024.f) + EPSF);
; #pragma unroll
;           for (int i = 0; i < 4; ++i) {
;             const int col = (i * 64 + lane) * 4;
;             const float4 gt = *reinterpret_cast<const float4*>(modg + gate_idx * 1024 + col);
;             const float4 gp = *reinterpret_cast<const float4*>(gpost + col);
;             xv[i].x += gt.x * (yv[i].x * rstd * gp.x); xv[i].y += gt.y * (yv[i].y * rstd * gp.y);
;             xv[i].z += gt.z * (yv[i].z * rstd * gp.z); xv[i].w += gt.w * (yv[i].w * rstd * gp.w);
;           }
;         }
;         if (xdst == 3 || (xdst == 1 && row >= N_X)) {
;           float* xout = (xdst == 3) ? P.out + (long)row * 1024 : P.xc + (long)(row - N_X) * 1024;
; #pragma unroll
;           for (int i = 0; i < 4; ++i) *reinterpret_cast<float4*>(xout + (i * 64 + lane) * 4) = xv[i];
	v_lshlrev_b32_e32 v178, 16, v180
	v_and_b32_e32 v179, 0xffff0000, v180
	v_lshlrev_b32_e32 v180, 16, v181
	v_and_b32_e32 v181, 0xffff0000, v181
	s_nop 0
	v_mul_f32_e32 v120, v120, v140
	v_mul_f32_e32 v121, v121, v140
	v_mul_f32_e32 v122, v122, v140
	v_mul_f32_e32 v123, v123, v140
	v_mul_f32_e32 v124, v124, v140
	v_mul_f32_e32 v125, v125, v140
	v_mul_f32_e32 v126, v126, v140
	v_mul_f32_e32 v127, v127, v140
	v_mul_f32_e32 v128, v128, v140
	v_mul_f32_e32 v129, v129, v140
	v_mul_f32_e32 v130, v130, v140
	v_mul_f32_e32 v131, v131, v140
	v_mul_f32_e32 v132, v132, v140
	v_mul_f32_e32 v133, v133, v140
	v_mul_f32_e32 v134, v134, v140
	v_mul_f32_e32 v135, v135, v140
	v_fma_f32 v166, v120, v72, v166
	v_fma_f32 v167, v121, v73, v167
	v_fma_f32 v168, v122, v74, v168
	v_fma_f32 v169, v123, v75, v169
	v_fma_f32 v170, v124, v76, v170
	v_fma_f32 v171, v125, v77, v171
	v_fma_f32 v172, v126, v78, v172
	v_fma_f32 v173, v127, v79, v173
	v_fma_f32 v174, v128, v80, v174
	v_fma_f32 v175, v129, v81, v175
	v_fma_f32 v176, v130, v82, v176
	v_fma_f32 v177, v131, v83, v177
	v_fma_f32 v178, v132, v84, v178
	v_fma_f32 v179, v133, v85, v179
	v_fma_f32 v180, v134, v86, v180
	v_fma_f32 v181, v135, v87, v181
	s_lshl_b32 vcc_lo, s19, 12
	s_add_u32 vcc_lo, vcc_lo, 0x3800000
	s_add_u32 s100, s16, vcc_lo
	s_addc_u32 s101, s17, 0
	global_store_dwordx4 v136, v[166:169], s[100:101] offset:0
	global_store_dwordx4 v136, v[170:173], s[100:101] offset:1024
	global_store_dwordx4 v136, v[174:177], s[100:101] offset:2048
	global_store_dwordx4 v136, v[178:181], s[100:101] offset:3072
	s_add_u32 s100, s20, 0x2f000
	s_addc_u32 s101, s21, 0
	global_load_dwordx4 v[72:75], v136, s[100:101] offset:0
	global_load_dwordx4 v[76:79], v136, s[100:101] offset:1024
	global_load_dwordx4 v[80:83], v136, s[100:101] offset:2048
	global_load_dwordx4 v[84:87], v136, s[100:101] offset:3072
	s_load_dwordx2 s[98:99], s[4:5], 0x48
	s_waitcnt lgkmcnt(0)
	s_add_u32 s98, s98, 0x1000
	s_addc_u32 s99, s99, 0
	global_load_dwordx4 v[120:123], v136, s[98:99] offset:0
	global_load_dwordx4 v[124:127], v136, s[98:99] offset:1024
	global_load_dwordx4 v[128:131], v136, s[98:99] offset:2048
	global_load_dwordx4 v[132:135], v136, s[98:99] offset:3072
	s_waitcnt vmcnt(0)
	v_mul_f32_e32 v72, v72, v120
	v_mul_f32_e32 v73, v73, v121
	v_mul_f32_e32 v74, v74, v122
	v_mul_f32_e32 v75, v75, v123
	v_mul_f32_e32 v76, v76, v124
	v_mul_f32_e32 v77, v77, v125
	v_mul_f32_e32 v78, v78, v126
	v_mul_f32_e32 v79, v79, v127
	v_mul_f32_e32 v80, v80, v128
	v_mul_f32_e32 v81, v81, v129
	v_mul_f32_e32 v82, v82, v130
	v_mul_f32_e32 v83, v83, v131
	v_mul_f32_e32 v84, v84, v132
	v_mul_f32_e32 v85, v85, v133
	v_mul_f32_e32 v86, v86, v134
	v_mul_f32_e32 v87, v87, v135
	s_lshl_b32 vcc_lo, s19, 11
	s_add_u32 vcc_lo, vcc_lo, 0x2c00000
	s_add_u32 s100, s12, vcc_lo
	s_addc_u32 s101, s13, 0
	global_load_dwordx2 v[174:175], v137, s[100:101] offset:0
	global_load_dwordx2 v[176:177], v137, s[100:101] offset:512
	global_load_dwordx2 v[178:179], v137, s[100:101] offset:1024
	global_load_dwordx2 v[180:181], v137, s[100:101] offset:1536
	s_lshl_b32 vcc_lo, s19, 11
	s_add_u32 vcc_lo, vcc_lo, 0x2c00000
	s_add_u32 s100, s14, vcc_lo
	s_addc_u32 s101, s15, 0
	global_load_dwordx2 v[182:183], v137, s[100:101] offset:0
	global_load_dwordx2 v[184:185], v137, s[100:101] offset:512
	global_load_dwordx2 v[186:187], v137, s[100:101] offset:1024
	global_load_dwordx2 v[188:189], v137, s[100:101] offset:1536
	v_lshlrev_b32_e32 v120, 16, v48
	v_and_b32_e32 v121, 0xffff0000, v48
	v_lshlrev_b32_e32 v122, 16, v49
	v_and_b32_e32 v123, 0xffff0000, v49
	v_lshlrev_b32_e32 v124, 16, v50
	v_and_b32_e32 v125, 0xffff0000, v50
	v_lshlrev_b32_e32 v126, 16, v51
	v_and_b32_e32 v127, 0xffff0000, v51
	v_lshlrev_b32_e32 v128, 16, v52
	v_and_b32_e32 v129, 0xffff0000, v52
	v_lshlrev_b32_e32 v130, 16, v53
	v_and_b32_e32 v131, 0xffff0000, v53
	v_lshlrev_b32_e32 v132, 16, v54
	v_and_b32_e32 v133, 0xffff0000, v54
	v_lshlrev_b32_e32 v134, 16, v55
	v_and_b32_e32 v135, 0xffff0000, v55
	v_mul_f32_e32 v138, v120, v120
	v_mul_f32_e32 v149, v121, v121
	v_mul_f32_e32 v150, v122, v122
	v_mul_f32_e32 v154, v123, v123
	v_fma_f32 v138, v124, v124, v138
	v_fma_f32 v149, v125, v125, v149
	v_fma_f32 v150, v126, v126, v150
	v_fma_f32 v154, v127, v127, v154
	v_fma_f32 v138, v128, v128, v138
	v_fma_f32 v149, v129, v129, v149
	v_fma_f32 v150, v130, v130, v150
	v_fma_f32 v154, v131, v131, v154
	v_fma_f32 v138, v132, v132, v138
	v_fma_f32 v149, v133, v133, v149
	v_fma_f32 v150, v134, v134, v150
	v_fma_f32 v154, v135, v135, v154
	v_add_f32_e32 v138, v138, v149
	v_add_f32_e32 v150, v150, v154
	v_add_f32_e32 v138, v138, v150
	s_nop 1
	v_add_f32_dpp v138, v138, v138 quad_perm:[1,0,3,2] row_mask:0xf bank_mask:0xf
	s_nop 1
	v_add_f32_dpp v138, v138, v138 quad_perm:[2,3,0,1] row_mask:0xf bank_mask:0xf
	s_nop 1
	v_add_f32_dpp v138, v138, v138 row_half_mirror row_mask:0xf bank_mask:0xf
	s_nop 1
	v_add_f32_dpp v138, v138, v138 row_mirror row_mask:0xf bank_mask:0xf
	v_mov_b32_e32 v139, v138
	s_nop 1
	v_permlane16_swap_b32_e32 v138, v139
	v_add_f32_e32 v138, v138, v139
	v_mov_b32_e32 v139, v138
	s_nop 1
	v_permlane32_swap_b32_e32 v138, v139
	v_add_f32_e32 v138, v138, v139
	v_mul_f32_e32 v138, 0x3a800000, v138
	v_add_f32_e32 v138, 0x358637bd, v138
	v_rsq_f32_e32 v140, v138
	v_lshlrev_b32_e32 v0, 16, v8
	v_and_b32_e32 v1, 0xffff0000, v8
	v_lshlrev_b32_e32 v2, 16, v9
	v_and_b32_e32 v3, 0xffff0000, v9
	v_lshlrev_b32_e32 v4, 16, v10
	v_and_b32_e32 v5, 0xffff0000, v10
	v_lshlrev_b32_e32 v6, 16, v11
	v_and_b32_e32 v7, 0xffff0000, v11
	v_lshlrev_b32_e32 v8, 16, v12
	v_and_b32_e32 v9, 0xffff0000, v12
	v_lshlrev_b32_e32 v10, 16, v13
; __device__ __forceinline__ float bf2f(u16 h) { return __uint_as_float(((unsigned)h) << 16); }
; __device__ __forceinline__ void row_phase(const Params& P, int glayer, int layer, int xsrc, bool hasY, int gate_idx, const float* gpost,
;                           int xdst, bool doH, const float* gpre, int sh_idx, int nrows) {
;     ...
;         if (hasY) {
;           float4 yv[4];
;           float ss = 0.f;
; #pragma unroll
;           for (int i = 0; i < 4; ++i) {
;             const uint2 raw = yy[u][i];
;             yv[i].x = bf2f((u16)(raw.x & 0xffff)); yv[i].y = bf2f((u16)(raw.x >> 16));
;             yv[i].z = bf2f((u16)(raw.y & 0xffff)); yv[i].w = bf2f((u16)(raw.y >> 16));
;             ss += yv[i].x * yv[i].x + yv[i].y * yv[i].y + yv[i].z * yv[i].z + yv[i].w * yv[i].w;
;           }
;           ss = wave_sum(ss);
;           const float rstd = __builtin_amdgcn_rsqf(ss * (1.f / 1024.f) + EPSF);
; #pragma unroll
;           for (int i = 0; i < 4; ++i) {
;             const int col = (i * 64 + lane) * 4;
;             const float4 gt = *reinterpret_cast<const float4*>(modg + gate_idx * 1024 + col);
;             const float4 gp = *reinterpret_cast<const float4*>(gpost + col);
;             xv[i].x += gt.x * (yv[i].x * rstd * gp.x); xv[i].y += gt.y * (yv[i].y * rstd * gp.y);
;             xv[i].z += gt.z * (yv[i].z * rstd * gp.z); xv[i].w += gt.w * (yv[i].w * rstd * gp.w);
;           }
;         }
;         if (xdst == 3 || (xdst == 1 && row >= N_X)) {
;           float* xout = (xdst == 3) ? P.out + (long)row * 1024 : P.xc + (long)(row - N_X) * 1024;
; #pragma unroll
;           for (int i = 0; i < 4; ++i) *reinterpret_cast<float4*>(xout + (i * 64 + lane) * 4) = xv[i];
	v_and_b32_e32 v11, 0xffff0000, v13
	v_lshlrev_b32_e32 v12, 16, v14
	v_and_b32_e32 v13, 0xffff0000, v14
	v_lshlrev_b32_e32 v14, 16, v15
	v_and_b32_e32 v15, 0xffff0000, v15
	s_nop 0
	v_mul_f32_e32 v120, v120, v140
	v_mul_f32_e32 v121, v121, v140
	v_mul_f32_e32 v122, v122, v140
	v_mul_f32_e32 v123, v123, v140
	v_mul_f32_e32 v124, v124, v140
	v_mul_f32_e32 v125, v125, v140
	v_mul_f32_e32 v126, v126, v140
	v_mul_f32_e32 v127, v127, v140
	v_mul_f32_e32 v128, v128, v140
	v_mul_f32_e32 v129, v129, v140
	v_mul_f32_e32 v130, v130, v140
	v_mul_f32_e32 v131, v131, v140
	v_mul_f32_e32 v132, v132, v140
	v_mul_f32_e32 v133, v133, v140
	v_mul_f32_e32 v134, v134, v140
	v_mul_f32_e32 v135, v135, v140
	v_fma_f32 v0, v120, v72, v0
	v_fma_f32 v1, v121, v73, v1
	v_fma_f32 v2, v122, v74, v2
	v_fma_f32 v3, v123, v75, v3
	v_fma_f32 v4, v124, v76, v4
	v_fma_f32 v5, v125, v77, v5
	v_fma_f32 v6, v126, v78, v6
	v_fma_f32 v7, v127, v79, v7
	v_fma_f32 v8, v128, v80, v8
	v_fma_f32 v9, v129, v81, v9
	v_fma_f32 v10, v130, v82, v10
	v_fma_f32 v11, v131, v83, v11
	v_fma_f32 v12, v132, v84, v12
	v_fma_f32 v13, v133, v85, v13
	v_fma_f32 v14, v134, v86, v14
	v_fma_f32 v15, v135, v87, v15
	s_lshl_b32 vcc_lo, s19, 12
	s_add_u32 vcc_lo, vcc_lo, 0x4000000
	s_add_u32 s100, s16, vcc_lo
	s_addc_u32 s101, s17, 0
	global_store_dwordx4 v136, v[0:3], s[100:101] offset:0
	global_store_dwordx4 v136, v[4:7], s[100:101] offset:1024
	global_store_dwordx4 v136, v[8:11], s[100:101] offset:2048
	global_store_dwordx4 v136, v[12:15], s[100:101] offset:3072
	s_lshl_b32 vcc_lo, s19, 11
	s_add_u32 vcc_lo, vcc_lo, 0x3000000
	s_add_u32 s100, s12, vcc_lo
	s_addc_u32 s101, s13, 0
	global_load_dwordx2 v[8:9], v137, s[100:101] offset:0
	global_load_dwordx2 v[10:11], v137, s[100:101] offset:512
	global_load_dwordx2 v[12:13], v137, s[100:101] offset:1024
	global_load_dwordx2 v[14:15], v137, s[100:101] offset:1536
	s_lshl_b32 vcc_lo, s19, 11
	s_add_u32 vcc_lo, vcc_lo, 0x3000000
	s_add_u32 s100, s14, vcc_lo
	s_addc_u32 s101, s15, 0
	global_load_dwordx2 v[48:49], v137, s[100:101] offset:0
	global_load_dwordx2 v[50:51], v137, s[100:101] offset:512
	global_load_dwordx2 v[52:53], v137, s[100:101] offset:1024
	global_load_dwordx2 v[54:55], v137, s[100:101] offset:1536
	v_lshlrev_b32_e32 v120, 16, v56
	v_and_b32_e32 v121, 0xffff0000, v56
	v_lshlrev_b32_e32 v122, 16, v57
	v_and_b32_e32 v123, 0xffff0000, v57
	v_lshlrev_b32_e32 v124, 16, v58
	v_and_b32_e32 v125, 0xffff0000, v58
	v_lshlrev_b32_e32 v126, 16, v59
	v_and_b32_e32 v127, 0xffff0000, v59
	v_lshlrev_b32_e32 v128, 16, v60
	v_and_b32_e32 v129, 0xffff0000, v60
	v_lshlrev_b32_e32 v130, 16, v61
	v_and_b32_e32 v131, 0xffff0000, v61
	v_lshlrev_b32_e32 v132, 16, v62
	v_and_b32_e32 v133, 0xffff0000, v62
	v_lshlrev_b32_e32 v134, 16, v63
	v_and_b32_e32 v135, 0xffff0000, v63
	v_mul_f32_e32 v138, v120, v120
	v_mul_f32_e32 v149, v121, v121
	v_mul_f32_e32 v150, v122, v122
	v_mul_f32_e32 v154, v123, v123
	v_fma_f32 v138, v124, v124, v138
	v_fma_f32 v149, v125, v125, v149
	v_fma_f32 v150, v126, v126, v150
	v_fma_f32 v154, v127, v127, v154
	v_fma_f32 v138, v128, v128, v138
	v_fma_f32 v149, v129, v129, v149
	v_fma_f32 v150, v130, v130, v150
	v_fma_f32 v154, v131, v131, v154
	v_fma_f32 v138, v132, v132, v138
	v_fma_f32 v149, v133, v133, v149
	v_fma_f32 v150, v134, v134, v150
	v_fma_f32 v154, v135, v135, v154
	v_add_f32_e32 v138, v138, v149
	v_add_f32_e32 v150, v150, v154
	v_add_f32_e32 v138, v138, v150
	s_nop 1
	v_add_f32_dpp v138, v138, v138 quad_perm:[1,0,3,2] row_mask:0xf bank_mask:0xf
	s_nop 1
	v_add_f32_dpp v138, v138, v138 quad_perm:[2,3,0,1] row_mask:0xf bank_mask:0xf
	s_nop 1
	v_add_f32_dpp v138, v138, v138 row_half_mirror row_mask:0xf bank_mask:0xf
	s_nop 1
	v_add_f32_dpp v138, v138, v138 row_mirror row_mask:0xf bank_mask:0xf
	v_mov_b32_e32 v139, v138
	s_nop 1
	v_permlane16_swap_b32_e32 v138, v139
	v_add_f32_e32 v138, v138, v139
	v_mov_b32_e32 v139, v138
	s_nop 1
	v_permlane32_swap_b32_e32 v138, v139
	v_add_f32_e32 v138, v138, v139
	v_mul_f32_e32 v138, 0x3a800000, v138
	v_add_f32_e32 v138, 0x358637bd, v138
	v_rsq_f32_e32 v140, v138
	v_lshlrev_b32_e32 v16, 16, v24
	v_and_b32_e32 v17, 0xffff0000, v24
	v_lshlrev_b32_e32 v18, 16, v25
	v_and_b32_e32 v19, 0xffff0000, v25
	v_lshlrev_b32_e32 v20, 16, v26
	v_and_b32_e32 v21, 0xffff0000, v26
	v_lshlrev_b32_e32 v22, 16, v27
	v_and_b32_e32 v23, 0xffff0000, v27
	v_lshlrev_b32_e32 v24, 16, v28
	v_and_b32_e32 v25, 0xffff0000, v28
	v_lshlrev_b32_e32 v26, 16, v29
	v_and_b32_e32 v27, 0xffff0000, v29
	v_lshlrev_b32_e32 v28, 16, v30
	v_and_b32_e32 v29, 0xffff0000, v30
	v_lshlrev_b32_e32 v30, 16, v31
	v_and_b32_e32 v31, 0xffff0000, v31
	s_nop 0
	v_mul_f32_e32 v120, v120, v140
	v_mul_f32_e32 v121, v121, v140
	v_mul_f32_e32 v122, v122, v140
	v_mul_f32_e32 v123, v123, v140
	v_mul_f32_e32 v124, v124, v140
	v_mul_f32_e32 v125, v125, v140
	v_mul_f32_e32 v126, v126, v140
	v_mul_f32_e32 v127, v127, v140
	v_mul_f32_e32 v128, v128, v140
	v_mul_f32_e32 v129, v129, v140
	v_mul_f32_e32 v130, v130, v140
	v_mul_f32_e32 v131, v131, v140
	v_mul_f32_e32 v132, v132, v140
	v_mul_f32_e32 v133, v133, v140
	v_mul_f32_e32 v134, v134, v140
	v_mul_f32_e32 v135, v135, v140
	v_fma_f32 v16, v120, v72, v16
	v_fma_f32 v17, v121, v73, v17
	v_fma_f32 v18, v122, v74, v18
	v_fma_f32 v19, v123, v75, v19
	v_fma_f32 v20, v124, v76, v20
	v_fma_f32 v21, v125, v77, v21
	v_fma_f32 v22, v126, v78, v22
	v_fma_f32 v23, v127, v79, v23
	v_fma_f32 v24, v128, v80, v24
	v_fma_f32 v25, v129, v81, v25
	v_fma_f32 v26, v130, v82, v26
	v_fma_f32 v27, v131, v83, v27
	v_fma_f32 v28, v132, v84, v28
	v_fma_f32 v29, v133, v85, v29
	v_fma_f32 v30, v134, v86, v30
	v_fma_f32 v31, v135, v87, v31
; __device__ __forceinline__ float bf2f(u16 h) { return __uint_as_float(((unsigned)h) << 16); }
; __device__ __forceinline__ void row_phase(const Params& P, int glayer, int layer, int xsrc, bool hasY, int gate_idx, const float* gpost,
;                           int xdst, bool doH, const float* gpre, int sh_idx, int nrows) {
;     ...
;         if (hasY) {
;           float4 yv[4];
;           float ss = 0.f;
; #pragma unroll
;           for (int i = 0; i < 4; ++i) {
;             const uint2 raw = yy[u][i];
;             yv[i].x = bf2f((u16)(raw.x & 0xffff)); yv[i].y = bf2f((u16)(raw.x >> 16));
;             yv[i].z = bf2f((u16)(raw.y & 0xffff)); yv[i].w = bf2f((u16)(raw.y >> 16));
;             ss += yv[i].x * yv[i].x + yv[i].y * yv[i].y + yv[i].z * yv[i].z + yv[i].w * yv[i].w;
;           }
;           ss = wave_sum(ss);
;           const float rstd = __builtin_amdgcn_rsqf(ss * (1.f / 1024.f) + EPSF);
; #pragma unroll
;           for (int i = 0; i < 4; ++i) {
;             const int col = (i * 64 + lane) * 4;
;             const float4 gt = *reinterpret_cast<const float4*>(modg + gate_idx * 1024 + col);
;             const float4 gp = *reinterpret_cast<const float4*>(gpost + col);
;             xv[i].x += gt.x * (yv[i].x * rstd * gp.x); xv[i].y += gt.y * (yv[i].y * rstd * gp.y);
;             xv[i].z += gt.z * (yv[i].z * rstd * gp.z); xv[i].w += gt.w * (yv[i].w * rstd * gp.w);
;           }
;         }
;         if (xdst == 3 || (xdst == 1 && row >= N_X)) {
;           float* xout = (xdst == 3) ? P.out + (long)row * 1024 : P.xc + (long)(row - N_X) * 1024;
; #pragma unroll
;           for (int i = 0; i < 4; ++i) *reinterpret_cast<float4*>(xout + (i * 64 + lane) * 4) = xv[i];
	s_lshl_b32 vcc_lo, s19, 12
	s_add_u32 vcc_lo, vcc_lo, 0x4800000
	s_add_u32 s100, s16, vcc_lo
	s_addc_u32 s101, s17, 0
	global_store_dwordx4 v136, v[16:19], s[100:101] offset:0
	global_store_dwordx4 v136, v[20:23], s[100:101] offset:1024
	global_store_dwordx4 v136, v[24:27], s[100:101] offset:2048
	global_store_dwordx4 v136, v[28:31], s[100:101] offset:3072
	s_lshl_b32 vcc_lo, s19, 11
	s_add_u32 vcc_lo, vcc_lo, 0x3400000
	s_add_u32 s100, s12, vcc_lo
	s_addc_u32 s101, s13, 0
	global_load_dwordx2 v[24:25], v137, s[100:101] offset:0
	global_load_dwordx2 v[26:27], v137, s[100:101] offset:512
	global_load_dwordx2 v[28:29], v137, s[100:101] offset:1024
	global_load_dwordx2 v[30:31], v137, s[100:101] offset:1536
	s_lshl_b32 vcc_lo, s19, 11
	s_add_u32 vcc_lo, vcc_lo, 0x3400000
	s_add_u32 s100, s14, vcc_lo
	s_addc_u32 s101, s15, 0
	global_load_dwordx2 v[56:57], v137, s[100:101] offset:0
	global_load_dwordx2 v[58:59], v137, s[100:101] offset:512
	global_load_dwordx2 v[60:61], v137, s[100:101] offset:1024
	global_load_dwordx2 v[62:63], v137, s[100:101] offset:1536
	v_lshlrev_b32_e32 v120, 16, v64
	v_and_b32_e32 v121, 0xffff0000, v64
	v_lshlrev_b32_e32 v122, 16, v65
	v_and_b32_e32 v123, 0xffff0000, v65
	v_lshlrev_b32_e32 v124, 16, v66
	v_and_b32_e32 v125, 0xffff0000, v66
	v_lshlrev_b32_e32 v126, 16, v67
	v_and_b32_e32 v127, 0xffff0000, v67
	v_lshlrev_b32_e32 v128, 16, v68
	v_and_b32_e32 v129, 0xffff0000, v68
	v_lshlrev_b32_e32 v130, 16, v69
	v_and_b32_e32 v131, 0xffff0000, v69
	v_lshlrev_b32_e32 v132, 16, v70
	v_and_b32_e32 v133, 0xffff0000, v70
	v_lshlrev_b32_e32 v134, 16, v71
	v_and_b32_e32 v135, 0xffff0000, v71
	v_mul_f32_e32 v138, v120, v120
	v_mul_f32_e32 v149, v121, v121
	v_mul_f32_e32 v150, v122, v122
	v_mul_f32_e32 v154, v123, v123
	v_fma_f32 v138, v124, v124, v138
	v_fma_f32 v149, v125, v125, v149
	v_fma_f32 v150, v126, v126, v150
	v_fma_f32 v154, v127, v127, v154
	v_fma_f32 v138, v128, v128, v138
	v_fma_f32 v149, v129, v129, v149
	v_fma_f32 v150, v130, v130, v150
	v_fma_f32 v154, v131, v131, v154
	v_fma_f32 v138, v132, v132, v138
	v_fma_f32 v149, v133, v133, v149
	v_fma_f32 v150, v134, v134, v150
	v_fma_f32 v154, v135, v135, v154
	v_add_f32_e32 v138, v138, v149
	v_add_f32_e32 v150, v150, v154
	v_add_f32_e32 v138, v138, v150
	s_nop 1
	v_add_f32_dpp v138, v138, v138 quad_perm:[1,0,3,2] row_mask:0xf bank_mask:0xf
	s_nop 1
	v_add_f32_dpp v138, v138, v138 quad_perm:[2,3,0,1] row_mask:0xf bank_mask:0xf
	s_nop 1
	v_add_f32_dpp v138, v138, v138 row_half_mirror row_mask:0xf bank_mask:0xf
	s_nop 1
	v_add_f32_dpp v138, v138, v138 row_mirror row_mask:0xf bank_mask:0xf
	v_mov_b32_e32 v139, v138
	s_nop 1
	v_permlane16_swap_b32_e32 v138, v139
	v_add_f32_e32 v138, v138, v139
	v_mov_b32_e32 v139, v138
	s_nop 1
	v_permlane32_swap_b32_e32 v138, v139
	v_add_f32_e32 v138, v138, v139
	v_mul_f32_e32 v138, 0x3a800000, v138
	v_add_f32_e32 v138, 0x358637bd, v138
	v_rsq_f32_e32 v140, v138
	v_lshlrev_b32_e32 v32, 16, v40
	v_and_b32_e32 v33, 0xffff0000, v40
	v_lshlrev_b32_e32 v34, 16, v41
	v_and_b32_e32 v35, 0xffff0000, v41
	v_lshlrev_b32_e32 v36, 16, v42
	v_and_b32_e32 v37, 0xffff0000, v42
	v_lshlrev_b32_e32 v38, 16, v43
	v_and_b32_e32 v39, 0xffff0000, v43
	v_lshlrev_b32_e32 v40, 16, v44
	v_and_b32_e32 v41, 0xffff0000, v44
	v_lshlrev_b32_e32 v42, 16, v45
	v_and_b32_e32 v43, 0xffff0000, v45
	v_lshlrev_b32_e32 v44, 16, v46
	v_and_b32_e32 v45, 0xffff0000, v46
	v_lshlrev_b32_e32 v46, 16, v47
	v_and_b32_e32 v47, 0xffff0000, v47
	s_nop 0
	v_mul_f32_e32 v120, v120, v140
	v_mul_f32_e32 v121, v121, v140
	v_mul_f32_e32 v122, v122, v140
	v_mul_f32_e32 v123, v123, v140
	v_mul_f32_e32 v124, v124, v140
	v_mul_f32_e32 v125, v125, v140
	v_mul_f32_e32 v126, v126, v140
	v_mul_f32_e32 v127, v127, v140
	v_mul_f32_e32 v128, v128, v140
	v_mul_f32_e32 v129, v129, v140
	v_mul_f32_e32 v130, v130, v140
	v_mul_f32_e32 v131, v131, v140
	v_mul_f32_e32 v132, v132, v140
	v_mul_f32_e32 v133, v133, v140
	v_mul_f32_e32 v134, v134, v140
	v_mul_f32_e32 v135, v135, v140
	v_fma_f32 v32, v120, v72, v32
	v_fma_f32 v33, v121, v73, v33
	v_fma_f32 v34, v122, v74, v34
	v_fma_f32 v35, v123, v75, v35
	v_fma_f32 v36, v124, v76, v36
	v_fma_f32 v37, v125, v77, v37
	v_fma_f32 v38, v126, v78, v38
	v_fma_f32 v39, v127, v79, v39
	v_fma_f32 v40, v128, v80, v40
	v_fma_f32 v41, v129, v81, v41
	v_fma_f32 v42, v130, v82, v42
	v_fma_f32 v43, v131, v83, v43
	v_fma_f32 v44, v132, v84, v44
	v_fma_f32 v45, v133, v85, v45
	v_fma_f32 v46, v134, v86, v46
	v_fma_f32 v47, v135, v87, v47
	s_lshl_b32 vcc_lo, s19, 12
	s_add_u32 vcc_lo, vcc_lo, 0x5000000
	s_add_u32 s100, s16, vcc_lo
	s_addc_u32 s101, s17, 0
	global_store_dwordx4 v136, v[32:35], s[100:101] offset:0
	global_store_dwordx4 v136, v[36:39], s[100:101] offset:1024
	global_store_dwordx4 v136, v[40:43], s[100:101] offset:2048
	global_store_dwordx4 v136, v[44:47], s[100:101] offset:3072
	s_lshl_b32 vcc_lo, s19, 11
	s_add_u32 vcc_lo, vcc_lo, 0x3800000
	s_add_u32 s100, s12, vcc_lo
	s_addc_u32 s101, s13, 0
	global_load_dwordx2 v[40:41], v137, s[100:101] offset:0
	global_load_dwordx2 v[42:43], v137, s[100:101] offset:512
	global_load_dwordx2 v[44:45], v137, s[100:101] offset:1024
	global_load_dwordx2 v[46:47], v137, s[100:101] offset:1536
	s_lshl_b32 vcc_lo, s19, 11
	s_add_u32 vcc_lo, vcc_lo, 0x3800000
	s_add_u32 s100, s14, vcc_lo
	s_addc_u32 s101, s15, 0
	global_load_dwordx2 v[64:65], v137, s[100:101] offset:0
	global_load_dwordx2 v[66:67], v137, s[100:101] offset:512
	global_load_dwordx2 v[68:69], v137, s[100:101] offset:1024
	global_load_dwordx2 v[70:71], v137, s[100:101] offset:1536
	s_waitcnt vmcnt(36)
; __device__ __forceinline__ float bf2f(u16 h) { return __uint_as_float(((unsigned)h) << 16); }
; __device__ __forceinline__ void row_phase(const Params& P, int glayer, int layer, int xsrc, bool hasY, int gate_idx, const float* gpost,
;                           int xdst, bool doH, const float* gpre, int sh_idx, int nrows) {
;     ...
;         if (hasY) {
;           float4 yv[4];
;           float ss = 0.f;
; #pragma unroll
;           for (int i = 0; i < 4; ++i) {
;             const uint2 raw = yy[u][i];
;             yv[i].x = bf2f((u16)(raw.x & 0xffff)); yv[i].y = bf2f((u16)(raw.x >> 16));
;             yv[i].z = bf2f((u16)(raw.y & 0xffff)); yv[i].w = bf2f((u16)(raw.y >> 16));
;             ss += yv[i].x * yv[i].x + yv[i].y * yv[i].y + yv[i].z * yv[i].z + yv[i].w * yv[i].w;
;           }
;           ss = wave_sum(ss);
;           const float rstd = __builtin_amdgcn_rsqf(ss * (1.f / 1024.f) + EPSF);
; #pragma unroll
;           for (int i = 0; i < 4; ++i) {
;             const int col = (i * 64 + lane) * 4;
;             const float4 gt = *reinterpret_cast<const float4*>(modg + gate_idx * 1024 + col);
;             const float4 gp = *reinterpret_cast<const float4*>(gpost + col);
;             xv[i].x += gt.x * (yv[i].x * rstd * gp.x); xv[i].y += gt.y * (yv[i].y * rstd * gp.y);
;             xv[i].z += gt.z * (yv[i].z * rstd * gp.z); xv[i].w += gt.w * (yv[i].w * rstd * gp.w);
;           }
;         }
;         if (xdst == 3 || (xdst == 1 && row >= N_X)) {
;           float* xout = (xdst == 3) ? P.out + (long)row * 1024 : P.xc + (long)(row - N_X) * 1024;
; #pragma unroll
;           for (int i = 0; i < 4; ++i) *reinterpret_cast<float4*>(xout + (i * 64 + lane) * 4) = xv[i];
	v_lshlrev_b32_e32 v120, 16, v182
	v_and_b32_e32 v121, 0xffff0000, v182
	v_lshlrev_b32_e32 v122, 16, v183
	v_and_b32_e32 v123, 0xffff0000, v183
	v_lshlrev_b32_e32 v124, 16, v184
	v_and_b32_e32 v125, 0xffff0000, v184
	v_lshlrev_b32_e32 v126, 16, v185
	v_and_b32_e32 v127, 0xffff0000, v185
	v_lshlrev_b32_e32 v128, 16, v186
	v_and_b32_e32 v129, 0xffff0000, v186
	v_lshlrev_b32_e32 v130, 16, v187
	v_and_b32_e32 v131, 0xffff0000, v187
	v_lshlrev_b32_e32 v132, 16, v188
	v_and_b32_e32 v133, 0xffff0000, v188
	v_lshlrev_b32_e32 v134, 16, v189
	v_and_b32_e32 v135, 0xffff0000, v189
	v_mul_f32_e32 v138, v120, v120
	v_mul_f32_e32 v149, v121, v121
	v_mul_f32_e32 v150, v122, v122
	v_mul_f32_e32 v154, v123, v123
	v_fma_f32 v138, v124, v124, v138
	v_fma_f32 v149, v125, v125, v149
	v_fma_f32 v150, v126, v126, v150
	v_fma_f32 v154, v127, v127, v154
	v_fma_f32 v138, v128, v128, v138
	v_fma_f32 v149, v129, v129, v149
	v_fma_f32 v150, v130, v130, v150
	v_fma_f32 v154, v131, v131, v154
	v_fma_f32 v138, v132, v132, v138
	v_fma_f32 v149, v133, v133, v149
	v_fma_f32 v150, v134, v134, v150
	v_fma_f32 v154, v135, v135, v154
	v_add_f32_e32 v138, v138, v149
	v_add_f32_e32 v150, v150, v154
	v_add_f32_e32 v138, v138, v150
	s_nop 1
	v_add_f32_dpp v138, v138, v138 quad_perm:[1,0,3,2] row_mask:0xf bank_mask:0xf
	s_nop 1
	v_add_f32_dpp v138, v138, v138 quad_perm:[2,3,0,1] row_mask:0xf bank_mask:0xf
	s_nop 1
	v_add_f32_dpp v138, v138, v138 row_half_mirror row_mask:0xf bank_mask:0xf
	s_nop 1
	v_add_f32_dpp v138, v138, v138 row_mirror row_mask:0xf bank_mask:0xf
	v_mov_b32_e32 v139, v138
	s_nop 1
	v_permlane16_swap_b32_e32 v138, v139
	v_add_f32_e32 v138, v138, v139
	v_mov_b32_e32 v139, v138
	s_nop 1
	v_permlane32_swap_b32_e32 v138, v139
	v_add_f32_e32 v138, v138, v139
	v_mul_f32_e32 v138, 0x3a800000, v138
	v_add_f32_e32 v138, 0x358637bd, v138
	v_rsq_f32_e32 v140, v138
	v_lshlrev_b32_e32 v166, 16, v174
	v_and_b32_e32 v167, 0xffff0000, v174
	v_lshlrev_b32_e32 v168, 16, v175
	v_and_b32_e32 v169, 0xffff0000, v175
	v_lshlrev_b32_e32 v170, 16, v176
	v_and_b32_e32 v171, 0xffff0000, v176
	v_lshlrev_b32_e32 v172, 16, v177
	v_and_b32_e32 v173, 0xffff0000, v177
	v_lshlrev_b32_e32 v174, 16, v178
	v_and_b32_e32 v175, 0xffff0000, v178
	v_lshlrev_b32_e32 v176, 16, v179
	v_and_b32_e32 v177, 0xffff0000, v179
	v_lshlrev_b32_e32 v178, 16, v180
	v_and_b32_e32 v179, 0xffff0000, v180
	v_lshlrev_b32_e32 v180, 16, v181
	v_and_b32_e32 v181, 0xffff0000, v181
	s_nop 0
	v_mul_f32_e32 v120, v120, v140
	v_mul_f32_e32 v121, v121, v140
	v_mul_f32_e32 v122, v122, v140
	v_mul_f32_e32 v123, v123, v140
	v_mul_f32_e32 v124, v124, v140
	v_mul_f32_e32 v125, v125, v140
	v_mul_f32_e32 v126, v126, v140
	v_mul_f32_e32 v127, v127, v140
	v_mul_f32_e32 v128, v128, v140
	v_mul_f32_e32 v129, v129, v140
	v_mul_f32_e32 v130, v130, v140
	v_mul_f32_e32 v131, v131, v140
	v_mul_f32_e32 v132, v132, v140
	v_mul_f32_e32 v133, v133, v140
	v_mul_f32_e32 v134, v134, v140
	v_mul_f32_e32 v135, v135, v140
	v_fma_f32 v166, v120, v72, v166
	v_fma_f32 v167, v121, v73, v167
	v_fma_f32 v168, v122, v74, v168
	v_fma_f32 v169, v123, v75, v169
	v_fma_f32 v170, v124, v76, v170
	v_fma_f32 v171, v125, v77, v171
	v_fma_f32 v172, v126, v78, v172
	v_fma_f32 v173, v127, v79, v173
	v_fma_f32 v174, v128, v80, v174
	v_fma_f32 v175, v129, v81, v175
	v_fma_f32 v176, v130, v82, v176
	v_fma_f32 v177, v131, v83, v177
	v_fma_f32 v178, v132, v84, v178
	v_fma_f32 v179, v133, v85, v179
	v_fma_f32 v180, v134, v86, v180
	v_fma_f32 v181, v135, v87, v181
	s_lshl_b32 vcc_lo, s19, 12
	s_add_u32 vcc_lo, vcc_lo, 0x5800000
	s_add_u32 s100, s16, vcc_lo
	s_addc_u32 s101, s17, 0
	global_store_dwordx4 v136, v[166:169], s[100:101] offset:0
	global_store_dwordx4 v136, v[170:173], s[100:101] offset:1024
	global_store_dwordx4 v136, v[174:177], s[100:101] offset:2048
	global_store_dwordx4 v136, v[178:181], s[100:101] offset:3072
	s_add_u32 s100, s20, 0x35000
	s_addc_u32 s101, s21, 0
	global_load_dwordx4 v[72:75], v136, s[100:101] offset:0
	global_load_dwordx4 v[76:79], v136, s[100:101] offset:1024
	global_load_dwordx4 v[80:83], v136, s[100:101] offset:2048
	global_load_dwordx4 v[84:87], v136, s[100:101] offset:3072
	s_load_dwordx2 s[98:99], s[4:5], 0x48
	s_waitcnt lgkmcnt(0)
	s_add_u32 s98, s98, 0x1000
	s_addc_u32 s99, s99, 0
	global_load_dwordx4 v[120:123], v136, s[98:99] offset:0
	global_load_dwordx4 v[124:127], v136, s[98:99] offset:1024
	global_load_dwordx4 v[128:131], v136, s[98:99] offset:2048
	global_load_dwordx4 v[132:135], v136, s[98:99] offset:3072
	s_waitcnt vmcnt(0)
; __device__ __forceinline__ void row_phase(const Params& P, int glayer, int layer, int xsrc, bool hasY, int gate_idx, const float* gpost,
;                           int xdst, bool doH, const float* gpre, int sh_idx, int nrows) {
;     ...
;     for (int u = 0; u < 4; ++u) {
;       const int R = rb + u * stride;
;       if (R < nrows) {
;         if (xsrc != 0 && R < N_X) {
;           const u16* xs_ = ((xsrc == 1) ? resA : P.zf) + (long)R * 1024;
; #pragma unroll
;           for (int i = 0; i < 4; ++i) {
;             const uint2 t2 = *reinterpret_cast<const uint2*>(xs_ + (i * 64 + lane) * 4);
;             xr[u][i].x = t2.x; xr[u][i].y = t2.y;
;           }
;         } else {
;           const float* xin_;
;           if (xsrc == 0) xin_ = R < N_X ? P.x + (long)R * 1024 : P.ctx + (long)(R - N_X) * 1024;
;           else           xin_ = P.xc + (long)(R - N_X) * 1024;
; #pragma unroll
;           for (int i = 0; i < 4; ++i) xr[u][i] = *reinterpret_cast<const uint4*>(xin_ + (i * 64 + lane) * 4);
;         }
;     ...
;         if (hasY) {
;           float4 yv[4];
;           float ss = 0.f;
; #pragma unroll
;           for (int i = 0; i < 4; ++i) {
;             const uint2 raw = yy[u][i];
;             yv[i].x = bf2f((u16)(raw.x & 0xffff)); yv[i].y = bf2f((u16)(raw.x >> 16));
;             yv[i].z = bf2f((u16)(raw.y & 0xffff)); yv[i].w = bf2f((u16)(raw.y >> 16));
;             ss += yv[i].x * yv[i].x + yv[i].y * yv[i].y + yv[i].z * yv[i].z + yv[i].w * yv[i].w;
;           }
;           ss = wave_sum(ss);
;           const float rstd = __builtin_amdgcn_rsqf(ss * (1.f / 1024.f) + EPSF);
; #pragma unroll
;           for (int i = 0; i < 4; ++i) {
;             const int col = (i * 64 + lane) * 4;
;             const float4 gt = *reinterpret_cast<const float4*>(modg + gate_idx * 1024 + col);
;             const float4 gp = *reinterpret_cast<const float4*>(gpost + col);
;             xv[i].x += gt.x * (yv[i].x * rstd * gp.x); xv[i].y += gt.y * (yv[i].y * rstd * gp.y);
;             xv[i].z += gt.z * (yv[i].z * rstd * gp.z); xv[i].w += gt.w * (yv[i].w * rstd * gp.w);
;           }
;         }
;         if (xdst == 3 || (xdst == 1 && row >= N_X)) {
;           float* xout = (xdst == 3) ? P.out + (long)row * 1024 : P.xc + (long)(row - N_X) * 1024;
; #pragma unroll
;           for (int i = 0; i < 4; ++i) *reinterpret_cast<float4*>(xout + (i * 64 + lane) * 4) = xv[i];
	v_mul_f32_e32 v72, v72, v120
	v_mul_f32_e32 v73, v73, v121
	v_mul_f32_e32 v74, v74, v122
	v_mul_f32_e32 v75, v75, v123
	v_mul_f32_e32 v76, v76, v124
	v_mul_f32_e32 v77, v77, v125
	v_mul_f32_e32 v78, v78, v126
	v_mul_f32_e32 v79, v79, v127
	v_mul_f32_e32 v80, v80, v128
	v_mul_f32_e32 v81, v81, v129
	v_mul_f32_e32 v82, v82, v130
	v_mul_f32_e32 v83, v83, v131
	v_mul_f32_e32 v84, v84, v132
	v_mul_f32_e32 v85, v85, v133
	v_mul_f32_e32 v86, v86, v134
	v_mul_f32_e32 v87, v87, v135
	s_lshl_b32 vcc_lo, s19, 11
	s_add_u32 vcc_lo, vcc_lo, 0x3c00000
	s_add_u32 s100, s12, vcc_lo
	s_addc_u32 s101, s13, 0
	global_load_dwordx2 v[174:175], v137, s[100:101] offset:0
	global_load_dwordx2 v[176:177], v137, s[100:101] offset:512
	global_load_dwordx2 v[178:179], v137, s[100:101] offset:1024
	global_load_dwordx2 v[180:181], v137, s[100:101] offset:1536
	s_lshl_b32 vcc_lo, s19, 11
	s_add_u32 vcc_lo, vcc_lo, 0x3c00000
	s_add_u32 s100, s14, vcc_lo
	s_addc_u32 s101, s15, 0
	global_load_dwordx2 v[182:183], v137, s[100:101] offset:0
	global_load_dwordx2 v[184:185], v137, s[100:101] offset:512
	global_load_dwordx2 v[186:187], v137, s[100:101] offset:1024
	global_load_dwordx2 v[188:189], v137, s[100:101] offset:1536
	v_lshlrev_b32_e32 v120, 16, v48
	v_and_b32_e32 v121, 0xffff0000, v48
	v_lshlrev_b32_e32 v122, 16, v49
	v_and_b32_e32 v123, 0xffff0000, v49
	v_lshlrev_b32_e32 v124, 16, v50
	v_and_b32_e32 v125, 0xffff0000, v50
	v_lshlrev_b32_e32 v126, 16, v51
	v_and_b32_e32 v127, 0xffff0000, v51
	v_lshlrev_b32_e32 v128, 16, v52
	v_and_b32_e32 v129, 0xffff0000, v52
	v_lshlrev_b32_e32 v130, 16, v53
	v_and_b32_e32 v131, 0xffff0000, v53
	v_lshlrev_b32_e32 v132, 16, v54
	v_and_b32_e32 v133, 0xffff0000, v54
	v_lshlrev_b32_e32 v134, 16, v55
	v_and_b32_e32 v135, 0xffff0000, v55
	v_mul_f32_e32 v138, v120, v120
	v_mul_f32_e32 v149, v121, v121
	v_mul_f32_e32 v150, v122, v122
	v_mul_f32_e32 v154, v123, v123
	v_fma_f32 v138, v124, v124, v138
	v_fma_f32 v149, v125, v125, v149
	v_fma_f32 v150, v126, v126, v150
	v_fma_f32 v154, v127, v127, v154
	v_fma_f32 v138, v128, v128, v138
	v_fma_f32 v149, v129, v129, v149
	v_fma_f32 v150, v130, v130, v150
	v_fma_f32 v154, v131, v131, v154
	v_fma_f32 v138, v132, v132, v138
	v_fma_f32 v149, v133, v133, v149
	v_fma_f32 v150, v134, v134, v150
	v_fma_f32 v154, v135, v135, v154
	v_add_f32_e32 v138, v138, v149
	v_add_f32_e32 v150, v150, v154
	v_add_f32_e32 v138, v138, v150
	s_nop 1
	v_add_f32_dpp v138, v138, v138 quad_perm:[1,0,3,2] row_mask:0xf bank_mask:0xf
	s_nop 1
	v_add_f32_dpp v138, v138, v138 quad_perm:[2,3,0,1] row_mask:0xf bank_mask:0xf
	s_nop 1
	v_add_f32_dpp v138, v138, v138 row_half_mirror row_mask:0xf bank_mask:0xf
	s_nop 1
	v_add_f32_dpp v138, v138, v138 row_mirror row_mask:0xf bank_mask:0xf
	v_mov_b32_e32 v139, v138
	s_nop 1
	v_permlane16_swap_b32_e32 v138, v139
	v_add_f32_e32 v138, v138, v139
	v_mov_b32_e32 v139, v138
	s_nop 1
	v_permlane32_swap_b32_e32 v138, v139
	v_add_f32_e32 v138, v138, v139
	v_mul_f32_e32 v138, 0x3a800000, v138
	v_add_f32_e32 v138, 0x358637bd, v138
	v_rsq_f32_e32 v140, v138
	v_lshlrev_b32_e32 v0, 16, v8
	v_and_b32_e32 v1, 0xffff0000, v8
	v_lshlrev_b32_e32 v2, 16, v9
	v_and_b32_e32 v3, 0xffff0000, v9
	v_lshlrev_b32_e32 v4, 16, v10
	v_and_b32_e32 v5, 0xffff0000, v10
	v_lshlrev_b32_e32 v6, 16, v11
	v_and_b32_e32 v7, 0xffff0000, v11
	v_lshlrev_b32_e32 v8, 16, v12
	v_and_b32_e32 v9, 0xffff0000, v12
	v_lshlrev_b32_e32 v10, 16, v13
	v_and_b32_e32 v11, 0xffff0000, v13
	v_lshlrev_b32_e32 v12, 16, v14
	v_and_b32_e32 v13, 0xffff0000, v14
	v_lshlrev_b32_e32 v14, 16, v15
	v_and_b32_e32 v15, 0xffff0000, v15
	s_nop 0
	v_mul_f32_e32 v120, v120, v140
	v_mul_f32_e32 v121, v121, v140
	v_mul_f32_e32 v122, v122, v140
	v_mul_f32_e32 v123, v123, v140
	v_mul_f32_e32 v124, v124, v140
	v_mul_f32_e32 v125, v125, v140
	v_mul_f32_e32 v126, v126, v140
	v_mul_f32_e32 v127, v127, v140
	v_mul_f32_e32 v128, v128, v140
	v_mul_f32_e32 v129, v129, v140
	v_mul_f32_e32 v130, v130, v140
	v_mul_f32_e32 v131, v131, v140
	v_mul_f32_e32 v132, v132, v140
	v_mul_f32_e32 v133, v133, v140
	v_mul_f32_e32 v134, v134, v140
	v_mul_f32_e32 v135, v135, v140
	v_fma_f32 v0, v120, v72, v0
	v_fma_f32 v1, v121, v73, v1
	v_fma_f32 v2, v122, v74, v2
	v_fma_f32 v3, v123, v75, v3
	v_fma_f32 v4, v124, v76, v4
	v_fma_f32 v5, v125, v77, v5
	v_fma_f32 v6, v126, v78, v6
	v_fma_f32 v7, v127, v79, v7
	v_fma_f32 v8, v128, v80, v8
	v_fma_f32 v9, v129, v81, v9
	v_fma_f32 v10, v130, v82, v10
	v_fma_f32 v11, v131, v83, v11
	v_fma_f32 v12, v132, v84, v12
	v_fma_f32 v13, v133, v85, v13
	v_fma_f32 v14, v134, v86, v14
	v_fma_f32 v15, v135, v87, v15
	s_lshl_b32 vcc_lo, s19, 12
	s_add_u32 vcc_lo, vcc_lo, 0x6000000
	s_add_u32 s100, s16, vcc_lo
	s_addc_u32 s101, s17, 0
	global_store_dwordx4 v136, v[0:3], s[100:101] offset:0
	global_store_dwordx4 v136, v[4:7], s[100:101] offset:1024
	global_store_dwordx4 v136, v[8:11], s[100:101] offset:2048
	global_store_dwordx4 v136, v[12:15], s[100:101] offset:3072
	v_lshlrev_b32_e32 v120, 16, v56
	v_and_b32_e32 v121, 0xffff0000, v56
	v_lshlrev_b32_e32 v122, 16, v57
	v_and_b32_e32 v123, 0xffff0000, v57
	v_lshlrev_b32_e32 v124, 16, v58
	v_and_b32_e32 v125, 0xffff0000, v58
	v_lshlrev_b32_e32 v126, 16, v59
	v_and_b32_e32 v127, 0xffff0000, v59
	v_lshlrev_b32_e32 v128, 16, v60
	v_and_b32_e32 v129, 0xffff0000, v60
	v_lshlrev_b32_e32 v130, 16, v61
	v_and_b32_e32 v131, 0xffff0000, v61
	v_lshlrev_b32_e32 v132, 16, v62
	v_and_b32_e32 v133, 0xffff0000, v62
	v_lshlrev_b32_e32 v134, 16, v63
	v_and_b32_e32 v135, 0xffff0000, v63
	v_mul_f32_e32 v138, v120, v120
	v_mul_f32_e32 v149, v121, v121
	v_mul_f32_e32 v150, v122, v122
	v_mul_f32_e32 v154, v123, v123
	v_fma_f32 v138, v124, v124, v138
; __device__ __forceinline__ float bf2f(u16 h) { return __uint_as_float(((unsigned)h) << 16); }
; __device__ __forceinline__ void row_phase(const Params& P, int glayer, int layer, int xsrc, bool hasY, int gate_idx, const float* gpost,
;                           int xdst, bool doH, const float* gpre, int sh_idx, int nrows) {
;     ...
;         if (hasY) {
;           float4 yv[4];
;           float ss = 0.f;
; #pragma unroll
;           for (int i = 0; i < 4; ++i) {
;             const uint2 raw = yy[u][i];
;             yv[i].x = bf2f((u16)(raw.x & 0xffff)); yv[i].y = bf2f((u16)(raw.x >> 16));
;             yv[i].z = bf2f((u16)(raw.y & 0xffff)); yv[i].w = bf2f((u16)(raw.y >> 16));
;             ss += yv[i].x * yv[i].x + yv[i].y * yv[i].y + yv[i].z * yv[i].z + yv[i].w * yv[i].w;
;           }
;           ss = wave_sum(ss);
;           const float rstd = __builtin_amdgcn_rsqf(ss * (1.f / 1024.f) + EPSF);
; #pragma unroll
;           for (int i = 0; i < 4; ++i) {
;             const int col = (i * 64 + lane) * 4;
;             const float4 gt = *reinterpret_cast<const float4*>(modg + gate_idx * 1024 + col);
;             const float4 gp = *reinterpret_cast<const float4*>(gpost + col);
;             xv[i].x += gt.x * (yv[i].x * rstd * gp.x); xv[i].y += gt.y * (yv[i].y * rstd * gp.y);
;             xv[i].z += gt.z * (yv[i].z * rstd * gp.z); xv[i].w += gt.w * (yv[i].w * rstd * gp.w);
;           }
;         }
;         if (xdst == 3 || (xdst == 1 && row >= N_X)) {
;           float* xout = (xdst == 3) ? P.out + (long)row * 1024 : P.xc + (long)(row - N_X) * 1024;
; #pragma unroll
;           for (int i = 0; i < 4; ++i) *reinterpret_cast<float4*>(xout + (i * 64 + lane) * 4) = xv[i];
	v_fma_f32 v149, v125, v125, v149
	v_fma_f32 v150, v126, v126, v150
	v_fma_f32 v154, v127, v127, v154
	v_fma_f32 v138, v128, v128, v138
	v_fma_f32 v149, v129, v129, v149
	v_fma_f32 v150, v130, v130, v150
	v_fma_f32 v154, v131, v131, v154
	v_fma_f32 v138, v132, v132, v138
	v_fma_f32 v149, v133, v133, v149
	v_fma_f32 v150, v134, v134, v150
	v_fma_f32 v154, v135, v135, v154
	v_add_f32_e32 v138, v138, v149
	v_add_f32_e32 v150, v150, v154
	v_add_f32_e32 v138, v138, v150
	s_nop 1
	v_add_f32_dpp v138, v138, v138 quad_perm:[1,0,3,2] row_mask:0xf bank_mask:0xf
	s_nop 1
	v_add_f32_dpp v138, v138, v138 quad_perm:[2,3,0,1] row_mask:0xf bank_mask:0xf
	s_nop 1
	v_add_f32_dpp v138, v138, v138 row_half_mirror row_mask:0xf bank_mask:0xf
	s_nop 1
	v_add_f32_dpp v138, v138, v138 row_mirror row_mask:0xf bank_mask:0xf
	v_mov_b32_e32 v139, v138
	s_nop 1
	v_permlane16_swap_b32_e32 v138, v139
	v_add_f32_e32 v138, v138, v139
	v_mov_b32_e32 v139, v138
	s_nop 1
	v_permlane32_swap_b32_e32 v138, v139
	v_add_f32_e32 v138, v138, v139
	v_mul_f32_e32 v138, 0x3a800000, v138
	v_add_f32_e32 v138, 0x358637bd, v138
	v_rsq_f32_e32 v140, v138
	v_lshlrev_b32_e32 v16, 16, v24
	v_and_b32_e32 v17, 0xffff0000, v24
	v_lshlrev_b32_e32 v18, 16, v25
	v_and_b32_e32 v19, 0xffff0000, v25
	v_lshlrev_b32_e32 v20, 16, v26
	v_and_b32_e32 v21, 0xffff0000, v26
	v_lshlrev_b32_e32 v22, 16, v27
	v_and_b32_e32 v23, 0xffff0000, v27
	v_lshlrev_b32_e32 v24, 16, v28
	v_and_b32_e32 v25, 0xffff0000, v28
	v_lshlrev_b32_e32 v26, 16, v29
	v_and_b32_e32 v27, 0xffff0000, v29
	v_lshlrev_b32_e32 v28, 16, v30
	v_and_b32_e32 v29, 0xffff0000, v30
	v_lshlrev_b32_e32 v30, 16, v31
	v_and_b32_e32 v31, 0xffff0000, v31
	s_nop 0
	v_mul_f32_e32 v120, v120, v140
	v_mul_f32_e32 v121, v121, v140
	v_mul_f32_e32 v122, v122, v140
	v_mul_f32_e32 v123, v123, v140
	v_mul_f32_e32 v124, v124, v140
	v_mul_f32_e32 v125, v125, v140
	v_mul_f32_e32 v126, v126, v140
	v_mul_f32_e32 v127, v127, v140
	v_mul_f32_e32 v128, v128, v140
	v_mul_f32_e32 v129, v129, v140
	v_mul_f32_e32 v130, v130, v140
	v_mul_f32_e32 v131, v131, v140
	v_mul_f32_e32 v132, v132, v140
	v_mul_f32_e32 v133, v133, v140
	v_mul_f32_e32 v134, v134, v140
	v_mul_f32_e32 v135, v135, v140
	v_fma_f32 v16, v120, v72, v16
	v_fma_f32 v17, v121, v73, v17
	v_fma_f32 v18, v122, v74, v18
	v_fma_f32 v19, v123, v75, v19
	v_fma_f32 v20, v124, v76, v20
	v_fma_f32 v21, v125, v77, v21
	v_fma_f32 v22, v126, v78, v22
	v_fma_f32 v23, v127, v79, v23
	v_fma_f32 v24, v128, v80, v24
	v_fma_f32 v25, v129, v81, v25
	v_fma_f32 v26, v130, v82, v26
	v_fma_f32 v27, v131, v83, v27
	v_fma_f32 v28, v132, v84, v28
	v_fma_f32 v29, v133, v85, v29
	v_fma_f32 v30, v134, v86, v30
	v_fma_f32 v31, v135, v87, v31
	s_lshl_b32 vcc_lo, s19, 12
	s_add_u32 vcc_lo, vcc_lo, 0x6800000
	s_add_u32 s100, s16, vcc_lo
	s_addc_u32 s101, s17, 0
	global_store_dwordx4 v136, v[16:19], s[100:101] offset:0
	global_store_dwordx4 v136, v[20:23], s[100:101] offset:1024
	global_store_dwordx4 v136, v[24:27], s[100:101] offset:2048
	global_store_dwordx4 v136, v[28:31], s[100:101] offset:3072
	v_lshlrev_b32_e32 v120, 16, v64
	v_and_b32_e32 v121, 0xffff0000, v64
	v_lshlrev_b32_e32 v122, 16, v65
	v_and_b32_e32 v123, 0xffff0000, v65
	v_lshlrev_b32_e32 v124, 16, v66
	v_and_b32_e32 v125, 0xffff0000, v66
	v_lshlrev_b32_e32 v126, 16, v67
	v_and_b32_e32 v127, 0xffff0000, v67
	v_lshlrev_b32_e32 v128, 16, v68
	v_and_b32_e32 v129, 0xffff0000, v68
	v_lshlrev_b32_e32 v130, 16, v69
	v_and_b32_e32 v131, 0xffff0000, v69
	v_lshlrev_b32_e32 v132, 16, v70
	v_and_b32_e32 v133, 0xffff0000, v70
	v_lshlrev_b32_e32 v134, 16, v71
	v_and_b32_e32 v135, 0xffff0000, v71
	v_mul_f32_e32 v138, v120, v120
	v_mul_f32_e32 v149, v121, v121
	v_mul_f32_e32 v150, v122, v122
	v_mul_f32_e32 v154, v123, v123
	v_fma_f32 v138, v124, v124, v138
	v_fma_f32 v149, v125, v125, v149
	v_fma_f32 v150, v126, v126, v150
	v_fma_f32 v154, v127, v127, v154
	v_fma_f32 v138, v128, v128, v138
	v_fma_f32 v149, v129, v129, v149
	v_fma_f32 v150, v130, v130, v150
	v_fma_f32 v154, v131, v131, v154
	v_fma_f32 v138, v132, v132, v138
	v_fma_f32 v149, v133, v133, v149
	v_fma_f32 v150, v134, v134, v150
	v_fma_f32 v154, v135, v135, v154
	v_add_f32_e32 v138, v138, v149
	v_add_f32_e32 v150, v150, v154
	v_add_f32_e32 v138, v138, v150
	s_nop 1
	v_add_f32_dpp v138, v138, v138 quad_perm:[1,0,3,2] row_mask:0xf bank_mask:0xf
	s_nop 1
	v_add_f32_dpp v138, v138, v138 quad_perm:[2,3,0,1] row_mask:0xf bank_mask:0xf
	s_nop 1
	v_add_f32_dpp v138, v138, v138 row_half_mirror row_mask:0xf bank_mask:0xf
	s_nop 1
	v_add_f32_dpp v138, v138, v138 row_mirror row_mask:0xf bank_mask:0xf
	v_mov_b32_e32 v139, v138
	s_nop 1
	v_permlane16_swap_b32_e32 v138, v139
	v_add_f32_e32 v138, v138, v139
	v_mov_b32_e32 v139, v138
	s_nop 1
	v_permlane32_swap_b32_e32 v138, v139
	v_add_f32_e32 v138, v138, v139
	v_mul_f32_e32 v138, 0x3a800000, v138
	v_add_f32_e32 v138, 0x358637bd, v138
	v_rsq_f32_e32 v140, v138
	v_lshlrev_b32_e32 v32, 16, v40
	v_and_b32_e32 v33, 0xffff0000, v40
	v_lshlrev_b32_e32 v34, 16, v41
	v_and_b32_e32 v35, 0xffff0000, v41
	v_lshlrev_b32_e32 v36, 16, v42
	v_and_b32_e32 v37, 0xffff0000, v42
	v_lshlrev_b32_e32 v38, 16, v43
	v_and_b32_e32 v39, 0xffff0000, v43
	v_lshlrev_b32_e32 v40, 16, v44
	v_and_b32_e32 v41, 0xffff0000, v44
	v_lshlrev_b32_e32 v42, 16, v45
	v_and_b32_e32 v43, 0xffff0000, v45
	v_lshlrev_b32_e32 v44, 16, v46
	v_and_b32_e32 v45, 0xffff0000, v46
	v_lshlrev_b32_e32 v46, 16, v47
	v_and_b32_e32 v47, 0xffff0000, v47
	s_nop 0
	v_mul_f32_e32 v120, v120, v140
	v_mul_f32_e32 v121, v121, v140
	v_mul_f32_e32 v122, v122, v140
	v_mul_f32_e32 v123, v123, v140
	v_mul_f32_e32 v124, v124, v140
	v_mul_f32_e32 v125, v125, v140
	v_mul_f32_e32 v126, v126, v140
	v_mul_f32_e32 v127, v127, v140
	v_mul_f32_e32 v128, v128, v140
	v_mul_f32_e32 v129, v129, v140
	v_mul_f32_e32 v130, v130, v140
	v_mul_f32_e32 v131, v131, v140
	v_mul_f32_e32 v132, v132, v140
	v_mul_f32_e32 v133, v133, v140
	v_mul_f32_e32 v134, v134, v140
	v_mul_f32_e32 v135, v135, v140
	v_fma_f32 v32, v120, v72, v32
	v_fma_f32 v33, v121, v73, v33
	v_fma_f32 v34, v122, v74, v34
	v_fma_f32 v35, v123, v75, v35
	v_fma_f32 v36, v124, v76, v36
	v_fma_f32 v37, v125, v77, v37
	v_fma_f32 v38, v126, v78, v38
	v_fma_f32 v39, v127, v79, v39
	v_fma_f32 v40, v128, v80, v40
	v_fma_f32 v41, v129, v81, v41
	v_fma_f32 v42, v130, v82, v42
	v_fma_f32 v43, v131, v83, v43
	v_fma_f32 v44, v132, v84, v44
	v_fma_f32 v45, v133, v85, v45
	v_fma_f32 v46, v134, v86, v46
	v_fma_f32 v47, v135, v87, v47
	s_lshl_b32 vcc_lo, s19, 12
	s_add_u32 vcc_lo, vcc_lo, 0x7000000
	s_add_u32 s100, s16, vcc_lo
	s_addc_u32 s101, s17, 0
	global_store_dwordx4 v136, v[32:35], s[100:101] offset:0
	global_store_dwordx4 v136, v[36:39], s[100:101] offset:1024
	global_store_dwordx4 v136, v[40:43], s[100:101] offset:2048
	global_store_dwordx4 v136, v[44:47], s[100:101] offset:3072
	s_waitcnt vmcnt(12)
; __device__ __forceinline__ float bf2f(u16 h) { return __uint_as_float(((unsigned)h) << 16); }
; __device__ __forceinline__ void row_phase(const Params& P, int glayer, int layer, int xsrc, bool hasY, int gate_idx, const float* gpost,
;                           int xdst, bool doH, const float* gpre, int sh_idx, int nrows) {
;     ...
;         if (hasY) {
;           float4 yv[4];
;           float ss = 0.f;
; #pragma unroll
;           for (int i = 0; i < 4; ++i) {
;             const uint2 raw = yy[u][i];
;             yv[i].x = bf2f((u16)(raw.x & 0xffff)); yv[i].y = bf2f((u16)(raw.x >> 16));
;             yv[i].z = bf2f((u16)(raw.y & 0xffff)); yv[i].w = bf2f((u16)(raw.y >> 16));
;             ss += yv[i].x * yv[i].x + yv[i].y * yv[i].y + yv[i].z * yv[i].z + yv[i].w * yv[i].w;
;           }
;           ss = wave_sum(ss);
;           const float rstd = __builtin_amdgcn_rsqf(ss * (1.f / 1024.f) + EPSF);
; #pragma unroll
;           for (int i = 0; i < 4; ++i) {
;             const int col = (i * 64 + lane) * 4;
;             const float4 gt = *reinterpret_cast<const float4*>(modg + gate_idx * 1024 + col);
;             const float4 gp = *reinterpret_cast<const float4*>(gpost + col);
;             xv[i].x += gt.x * (yv[i].x * rstd * gp.x); xv[i].y += gt.y * (yv[i].y * rstd * gp.y);
;             xv[i].z += gt.z * (yv[i].z * rstd * gp.z); xv[i].w += gt.w * (yv[i].w * rstd * gp.w);
;           }
;         }
;         if (xdst == 3 || (xdst == 1 && row >= N_X)) {
;           float* xout = (xdst == 3) ? P.out + (long)row * 1024 : P.xc + (long)(row - N_X) * 1024;
; #pragma unroll
;           for (int i = 0; i < 4; ++i) *reinterpret_cast<float4*>(xout + (i * 64 + lane) * 4) = xv[i];
	v_lshlrev_b32_e32 v120, 16, v182
	v_and_b32_e32 v121, 0xffff0000, v182
	v_lshlrev_b32_e32 v122, 16, v183
	v_and_b32_e32 v123, 0xffff0000, v183
	v_lshlrev_b32_e32 v124, 16, v184
	v_and_b32_e32 v125, 0xffff0000, v184
	v_lshlrev_b32_e32 v126, 16, v185
	v_and_b32_e32 v127, 0xffff0000, v185
	v_lshlrev_b32_e32 v128, 16, v186
	v_and_b32_e32 v129, 0xffff0000, v186
	v_lshlrev_b32_e32 v130, 16, v187
	v_and_b32_e32 v131, 0xffff0000, v187
	v_lshlrev_b32_e32 v132, 16, v188
	v_and_b32_e32 v133, 0xffff0000, v188
	v_lshlrev_b32_e32 v134, 16, v189
	v_and_b32_e32 v135, 0xffff0000, v189
	v_mul_f32_e32 v138, v120, v120
	v_mul_f32_e32 v149, v121, v121
	v_mul_f32_e32 v150, v122, v122
	v_mul_f32_e32 v154, v123, v123
	v_fma_f32 v138, v124, v124, v138
	v_fma_f32 v149, v125, v125, v149
	v_fma_f32 v150, v126, v126, v150
	v_fma_f32 v154, v127, v127, v154
	v_fma_f32 v138, v128, v128, v138
	v_fma_f32 v149, v129, v129, v149
	v_fma_f32 v150, v130, v130, v150
	v_fma_f32 v154, v131, v131, v154
	v_fma_f32 v138, v132, v132, v138
	v_fma_f32 v149, v133, v133, v149
	v_fma_f32 v150, v134, v134, v150
	v_fma_f32 v154, v135, v135, v154
	v_add_f32_e32 v138, v138, v149
	v_add_f32_e32 v150, v150, v154
	v_add_f32_e32 v138, v138, v150
	s_nop 1
	v_add_f32_dpp v138, v138, v138 quad_perm:[1,0,3,2] row_mask:0xf bank_mask:0xf
	s_nop 1
	v_add_f32_dpp v138, v138, v138 quad_perm:[2,3,0,1] row_mask:0xf bank_mask:0xf
	s_nop 1
	v_add_f32_dpp v138, v138, v138 row_half_mirror row_mask:0xf bank_mask:0xf
	s_nop 1
	v_add_f32_dpp v138, v138, v138 row_mirror row_mask:0xf bank_mask:0xf
	v_mov_b32_e32 v139, v138
	s_nop 1
	v_permlane16_swap_b32_e32 v138, v139
	v_add_f32_e32 v138, v138, v139
	v_mov_b32_e32 v139, v138
	s_nop 1
	v_permlane32_swap_b32_e32 v138, v139
	v_add_f32_e32 v138, v138, v139
	v_mul_f32_e32 v138, 0x3a800000, v138
	v_add_f32_e32 v138, 0x358637bd, v138
	v_rsq_f32_e32 v140, v138
	v_lshlrev_b32_e32 v166, 16, v174
	v_and_b32_e32 v167, 0xffff0000, v174
	v_lshlrev_b32_e32 v168, 16, v175
	v_and_b32_e32 v169, 0xffff0000, v175
	v_lshlrev_b32_e32 v170, 16, v176
	v_and_b32_e32 v171, 0xffff0000, v176
	v_lshlrev_b32_e32 v172, 16, v177
	v_and_b32_e32 v173, 0xffff0000, v177
	v_lshlrev_b32_e32 v174, 16, v178
	v_and_b32_e32 v175, 0xffff0000, v178
	v_lshlrev_b32_e32 v176, 16, v179
	v_and_b32_e32 v177, 0xffff0000, v179
	v_lshlrev_b32_e32 v178, 16, v180
	v_and_b32_e32 v179, 0xffff0000, v180
	v_lshlrev_b32_e32 v180, 16, v181
	v_and_b32_e32 v181, 0xffff0000, v181
	s_nop 0
	v_mul_f32_e32 v120, v120, v140
	v_mul_f32_e32 v121, v121, v140
	v_mul_f32_e32 v122, v122, v140
	v_mul_f32_e32 v123, v123, v140
	v_mul_f32_e32 v124, v124, v140
	v_mul_f32_e32 v125, v125, v140
	v_mul_f32_e32 v126, v126, v140
	v_mul_f32_e32 v127, v127, v140
	v_mul_f32_e32 v128, v128, v140
	v_mul_f32_e32 v129, v129, v140
	v_mul_f32_e32 v130, v130, v140
	v_mul_f32_e32 v131, v131, v140
	v_mul_f32_e32 v132, v132, v140
	v_mul_f32_e32 v133, v133, v140
	v_mul_f32_e32 v134, v134, v140
	v_mul_f32_e32 v135, v135, v140
	v_fma_f32 v166, v120, v72, v166
	v_fma_f32 v167, v121, v73, v167
	v_fma_f32 v168, v122, v74, v168
	v_fma_f32 v169, v123, v75, v169
	v_fma_f32 v170, v124, v76, v170
	v_fma_f32 v171, v125, v77, v171
	v_fma_f32 v172, v126, v78, v172
	v_fma_f32 v173, v127, v79, v173
	v_fma_f32 v174, v128, v80, v174
	v_fma_f32 v175, v129, v81, v175
	v_fma_f32 v176, v130, v82, v176
	v_fma_f32 v177, v131, v83, v177
	v_fma_f32 v178, v132, v84, v178
	v_fma_f32 v179, v133, v85, v179
	v_fma_f32 v180, v134, v86, v180
	v_fma_f32 v181, v135, v87, v181
	s_lshl_b32 vcc_lo, s19, 12
	s_add_u32 vcc_lo, vcc_lo, 0x7800000
	s_add_u32 s100, s16, vcc_lo
	s_addc_u32 s101, s17, 0
	global_store_dwordx4 v136, v[166:169], s[100:101] offset:0
	global_store_dwordx4 v136, v[170:173], s[100:101] offset:1024
	global_store_dwordx4 v136, v[174:177], s[100:101] offset:2048
	global_store_dwordx4 v136, v[178:181], s[100:101] offset:3072
	s_branch .LBB0_1962
